# extended DPP-operand fusion (canonicalising copy in another register, full-overwrite DPP kills), redundant s_waitcnt removed, s_nop fillers removed
# baseline (speedup 1.0000x reference)
.LBB0_92:
	s_or_b64 exec, exec, s[0:1]
	s_waitcnt vmcnt(0)
	s_barrier
	s_and_saveexec_b64 s[0:1], s[4:5]
	s_xor_b64 s[0:1], exec, s[0:1]
	s_lshl_b32 s2, s60, 6
	s_mov_b32 s3, 0
	s_or_saveexec_b64 s[0:1], s[0:1]
	v_mov_b64_e32 v[0:1], s[2:3]
	s_xor_b64 exec, exec, s[0:1]
	s_cbranch_execz .LBB0_147
	s_add_i32 s2, 0, 0x13ff0
	v_mov_b32_e32 v0, s2
	s_waitcnt expcnt(0) lgkmcnt(0)
	ds_read_b32 v2, v0
	s_add_i32 s2, 0, 0x13ff4
	v_mov_b32_e32 v0, s2
	ds_read_b32 v0, v0
	s_waitcnt lgkmcnt(1)
	v_cmp_ne_u32_e32 vcc, 0, v2
	s_cbranch_vccnz .LBB0_110
	s_add_u32 s2, s92, 0x25467800
	s_addc_u32 s3, s93, 0
	s_add_u32 s4, s92, 0x25467a00
	s_addc_u32 s5, s93, 0
	s_add_u32 s6, s92, 0x25467b00
	s_addc_u32 s7, s93, 0
	s_add_u32 s8, s92, 0x25467c00
	s_addc_u32 s9, s93, 0
	s_add_u32 s10, s92, 0x25467d00
	s_addc_u32 s11, s93, 0
	s_add_u32 s12, s92, 0x25467e00
	s_addc_u32 s13, s93, 0
	s_add_u32 s14, s92, 0x25467f00
	s_addc_u32 s15, s93, 0
	s_add_u32 s34, s92, 0x25468000
	s_addc_u32 s35, s93, 0
	s_add_u32 s36, s92, 0x25468100
	s_addc_u32 s37, s93, 0
	s_add_u32 s38, s92, 0x25468200
	s_addc_u32 s39, s93, 0
	s_add_u32 s40, s92, 0x25468300
	s_addc_u32 s41, s93, 0
	s_add_u32 s42, s92, 0x25468400
	s_addc_u32 s43, s93, 0
	s_add_u32 s44, s92, 0x25468500
	s_addc_u32 s45, s93, 0
	s_add_u32 s46, s92, 0x25468600
	s_addc_u32 s47, s93, 0
	s_add_u32 s48, s92, 0x25468700
	s_addc_u32 s49, s93, 0
	s_add_u32 s50, s92, 0x25468800
	s_addc_u32 s51, s93, 0
	s_mul_i32 s33, s95, s61
	s_add_u32 s52, s92, 0x25468900
	s_mul_i32 s33, s33, s94
	s_addc_u32 s53, s93, 0
	s_mov_b32 s62, 1
	v_mov_b32_e32 v16, 0
	s_branch .LBB0_98

.LBB0_212:
	s_or_b64 exec, exec, s[0:1]
	s_waitcnt vmcnt(0)
	s_barrier
	s_mov_b64 s[0:1], exec
	v_readlane_b32 s2, v251, 0
	v_readlane_b32 s3, v251, 1
	s_and_b64 s[2:3], s[0:1], s[2:3]
	s_xor_b64 s[0:1], s[2:3], s[0:1]
	s_mov_b64 exec, s[2:3]
	s_cbranch_execz .LBB0_261
	v_readlane_b32 s2, v249, 49
	s_waitcnt expcnt(0) lgkmcnt(0)
	s_nop 0
	v_mov_b32_e32 v0, s2
	ds_read_b32 v2, v0
	v_readlane_b32 s2, v249, 50
	s_waitcnt lgkmcnt(0)
	v_cmp_ne_u32_e32 vcc, 0, v2
	v_mov_b32_e32 v0, s2
	ds_read_b32 v0, v0
	s_cbranch_vccnz .LBB0_228
	s_mov_b32 s4, 1
	s_branch .LBB0_216

.LBB0_268:
	s_add_u32 s4, s82, s40
	s_addc_u32 s7, s83, s41
	s_and_b64 s[10:11], s[12:13], exec
	s_cselect_b32 s10, s4, 0
	v_readlane_b32 s4, v251, 58
	s_cselect_b32 s11, s7, 0
	s_add_u32 s4, s4, s42
	v_readlane_b32 s7, v251, 59
	s_addc_u32 s7, s7, s43
	s_and_b64 s[40:41], s[12:13], exec
	s_cselect_b32 s41, s7, 0
	s_cselect_b32 s40, s4, 0
	v_lshl_add_u64 v[4:5], s[10:11], 0, v[0:1]
	v_lshl_add_u64 v[0:1], s[40:41], 0, v[0:1]
	v_lshl_add_u64 v[146:147], v[0:1], 0, v[96:97]
	v_lshrrev_b32_e32 v0, 1, v2
	v_and_b32_e32 v1, 31, v2
	v_and_or_b32 v1, v0, s81, v1
	v_lshrrev_b32_e32 v0, 2, v2
	v_and_b32_e32 v0, 8, v0
	v_lshl_add_u64 v[148:149], v[4:5], 0, v[96:97]
	v_mad_u64_u32 v[4:5], s[10:11], v1, s84, v[0:1]
	v_and_b32_e32 v1, 0x5f, v2
	v_mad_u32_u24 v0, v1, s84, v0
	v_lshl_add_u32 v176, v4, 1, 0
	v_lshl_add_u32 v96, v0, 1, 0
	v_add_u32_e32 v177, 0xd800, v175
	s_setprio 1
	ds_read_b128 v[212:215], v96 offset:36864
	ds_read_b128 v[216:219], v176
	ds_read_b128 v[220:223], v176 offset:4608
	ds_read_b128 v[224:227], v96 offset:36896
	ds_read_b128 v[228:231], v176 offset:32
	ds_read_b128 v[244:247], v176 offset:4640
	ds_read_b128 v[252:255], v96 offset:41472
	s_waitcnt lgkmcnt(5)
	v_mfma_f32_32x32x16_bf16 v[32:47], v[212:215], v[216:219], 0
	s_waitcnt lgkmcnt(4)
	v_mfma_f32_32x32x16_bf16 v[0:15], v[212:215], v[220:223], 0
	ds_read_b128 v[212:215], v96 offset:41504
	s_waitcnt lgkmcnt(3)
	v_mfma_f32_32x32x16_bf16 v[32:47], v[224:227], v[228:231], v[32:47]
	s_waitcnt lgkmcnt(2)
	v_mfma_f32_32x32x16_bf16 v[0:15], v[224:227], v[244:247], v[0:15]
	ds_read_b128 v[224:227], v96 offset:36928
	s_waitcnt lgkmcnt(2)
	v_mfma_f32_32x32x16_bf16 v[48:63], v[252:255], v[216:219], 0
	ds_read_b128 v[216:219], v176 offset:64
	v_mfma_f32_32x32x16_bf16 v[16:31], v[252:255], v[220:223], 0
	ds_read_b128 v[252:255], v176 offset:4672
	ds_read_b128 v[220:223], v96 offset:41536
	s_waitcnt lgkmcnt(4)
	v_mfma_f32_32x32x16_bf16 v[48:63], v[212:215], v[228:231], v[48:63]
	ds_read_b128 v[228:231], v96 offset:36960
	v_mfma_f32_32x32x16_bf16 v[16:31], v[212:215], v[244:247], v[16:31]
	ds_read_b128 v[212:215], v176 offset:96
	ds_read_b128 v[244:247], v176 offset:4704
	s_waitcnt lgkmcnt(5)
	v_mfma_f32_32x32x16_bf16 v[32:47], v[224:227], v[216:219], v[32:47]
	s_mov_b32 s4, 0x10000
	v_add_co_u32_e32 v154, vcc, s4, v152
	s_mov_b32 s7, 0x20000
	s_nop 0
	v_addc_co_u32_e32 v155, vcc, 0, v153, vcc
	v_add_co_u32_e32 v156, vcc, s7, v152
	s_mov_b32 s9, 0x30000
	s_nop 0
	s_waitcnt lgkmcnt(4)
	v_mfma_f32_32x32x16_bf16 v[0:15], v[224:227], v[252:255], v[0:15]
	ds_read_b128 v[224:227], v96 offset:41568
	v_addc_co_u32_e32 v157, vcc, 0, v153, vcc
	v_add_co_u32_e32 v158, vcc, s9, v152
	s_waitcnt vmcnt(11)
	ds_write_b128 v175, v[100:103] offset:18432
	s_waitcnt vmcnt(10)
	ds_write_b128 v175, v[104:107] offset:23040
	s_waitcnt lgkmcnt(6)
	v_mfma_f32_32x32x16_bf16 v[48:63], v[220:223], v[216:219], v[48:63]
	s_waitcnt vmcnt(9)
	ds_write_b128 v175, v[108:111] offset:27648
	s_waitcnt vmcnt(8)
	ds_write_b128 v175, v[112:115] offset:32256
	v_mfma_f32_32x32x16_bf16 v[16:31], v[220:223], v[252:255], v[16:31]
	s_waitcnt vmcnt(7)
	ds_write_b128 v175, v[116:119] offset:55296
	s_waitcnt vmcnt(6)
	ds_write_b128 v175, v[124:127] offset:59904
	s_waitcnt vmcnt(5)
	ds_write_b128 v175, v[120:123] offset:64512
	s_waitcnt lgkmcnt(9)
	v_mfma_f32_32x32x16_bf16 v[32:47], v[228:231], v[212:215], v[32:47]
	s_waitcnt vmcnt(4)
	ds_write_b128 v177, v[128:131] offset:13824
	v_addc_co_u32_e32 v159, vcc, 0, v153, vcc
	v_add_co_u32_e32 v160, vcc, s4, v150
	s_waitcnt lgkmcnt(9)
	v_mfma_f32_32x32x16_bf16 v[0:15], v[228:231], v[244:247], v[0:15]
	global_load_dwordx4 v[98:101], v[152:153], off offset:384
	global_load_dwordx4 v[102:105], v[154:155], off offset:384
	v_addc_co_u32_e32 v161, vcc, 0, v151, vcc
	v_add_co_u32_e32 v170, vcc, s7, v150
	global_load_dwordx4 v[106:109], v[156:157], off offset:384
	s_waitcnt lgkmcnt(8)
	v_mfma_f32_32x32x16_bf16 v[48:63], v[224:227], v[212:215], v[48:63]
	s_nop 0
	v_addc_co_u32_e32 v171, vcc, 0, v151, vcc
	v_add_co_u32_e32 v172, vcc, s9, v150
	global_load_dwordx4 v[110:113], v[158:159], off offset:384
	global_load_dwordx4 v[114:117], v[150:151], off offset:384
	v_mfma_f32_32x32x16_bf16 v[16:31], v[224:227], v[244:247], v[16:31]
	v_addc_co_u32_e32 v173, vcc, 0, v151, vcc
	global_load_dwordx4 v[118:121], v[160:161], off offset:384
	global_load_dwordx4 v[122:125], v[170:171], off offset:384
	global_load_dwordx4 v[130:133], v[172:173], off offset:384
	s_setprio 0
	s_waitcnt lgkmcnt(0)
	s_barrier
	s_setprio 1
	ds_read_b128 v[212:215], v96 offset:55296
	ds_read_b128 v[216:219], v176 offset:18432
	ds_read_b128 v[220:223], v176 offset:23040
	ds_read_b128 v[224:227], v96 offset:59904
	ds_read_b128 v[228:231], v96 offset:55328
	ds_read_b128 v[244:247], v176 offset:18464
	ds_read_b128 v[252:255], v176 offset:23072
	s_waitcnt lgkmcnt(5)
	v_mfma_f32_32x32x16_bf16 v[32:47], v[212:215], v[216:219], v[32:47]
	s_waitcnt lgkmcnt(4)
	v_mfma_f32_32x32x16_bf16 v[0:15], v[212:215], v[220:223], v[0:15]
	ds_read_b128 v[212:215], v96 offset:59936
	s_waitcnt lgkmcnt(4)
	v_mfma_f32_32x32x16_bf16 v[48:63], v[224:227], v[216:219], v[48:63]
	ds_read_b128 v[216:219], v96 offset:55360
	v_mfma_f32_32x32x16_bf16 v[16:31], v[224:227], v[220:223], v[16:31]
	ds_read_b128 v[224:227], v176 offset:18496
	ds_read_b128 v[220:223], v176 offset:23104
	s_waitcnt lgkmcnt(5)
	v_mfma_f32_32x32x16_bf16 v[32:47], v[228:231], v[244:247], v[32:47]
	s_waitcnt lgkmcnt(4)
	v_mfma_f32_32x32x16_bf16 v[0:15], v[228:231], v[252:255], v[0:15]
	ds_read_b128 v[228:231], v96 offset:59968
	s_waitcnt lgkmcnt(4)
	v_mfma_f32_32x32x16_bf16 v[48:63], v[212:215], v[244:247], v[48:63]
	ds_read_b128 v[244:247], v96 offset:55392
	v_mfma_f32_32x32x16_bf16 v[16:31], v[212:215], v[252:255], v[16:31]
	ds_read_b128 v[212:215], v176 offset:18528
	ds_read_b128 v[252:255], v176 offset:23136
	s_waitcnt lgkmcnt(5)
	v_mfma_f32_32x32x16_bf16 v[32:47], v[216:219], v[224:227], v[32:47]
	ds_write_b128 v175, v[64:67]
	global_load_dwordx4 v[64:67], v[152:153], off offset:512
	s_waitcnt lgkmcnt(5)
	v_mfma_f32_32x32x16_bf16 v[0:15], v[216:219], v[220:223], v[0:15]
	ds_read_b128 v[216:219], v96 offset:60000
	ds_write_b128 v175, v[68:71] offset:4608
	ds_write_b128 v175, v[72:75] offset:9216
	s_waitcnt lgkmcnt(7)
	v_mfma_f32_32x32x16_bf16 v[48:63], v[228:231], v[224:227], v[48:63]
	global_load_dwordx4 v[72:75], v[154:155], off offset:512
	ds_write_b128 v175, v[76:79] offset:13824
	v_mfma_f32_32x32x16_bf16 v[16:31], v[228:231], v[220:223], v[16:31]
	global_load_dwordx4 v[76:79], v[156:157], off offset:512
	s_waitcnt vmcnt(14)
	ds_write_b128 v175, v[80:83] offset:36864
	s_waitcnt lgkmcnt(7)
	v_mfma_f32_32x32x16_bf16 v[32:47], v[244:247], v[212:215], v[32:47]
	global_load_dwordx4 v[80:83], v[158:159], off offset:512
	global_load_dwordx4 v[126:129], v[150:151], off offset:512
	s_waitcnt lgkmcnt(6)
	v_mfma_f32_32x32x16_bf16 v[0:15], v[244:247], v[252:255], v[0:15]
	s_waitcnt vmcnt(15)
	ds_write_b128 v175, v[84:87] offset:41472
	global_load_dwordx4 v[134:137], v[160:161], off offset:512
	s_waitcnt lgkmcnt(5)
	v_mfma_f32_32x32x16_bf16 v[48:63], v[216:219], v[212:215], v[48:63]
	s_waitcnt vmcnt(15)
	ds_write_b128 v175, v[88:91] offset:46080
	global_load_dwordx4 v[138:141], v[170:171], off offset:512
	v_mfma_f32_32x32x16_bf16 v[16:31], v[216:219], v[252:255], v[16:31]
	s_waitcnt vmcnt(15)
	ds_write_b128 v175, v[92:95] offset:50688
	global_load_dwordx4 v[142:145], v[172:173], off offset:512
	s_setprio 0
	s_waitcnt lgkmcnt(0)
	s_barrier
	s_setprio 1
	ds_read_b128 v[212:215], v96 offset:36864
	ds_read_b128 v[216:219], v176
	ds_read_b128 v[220:223], v176 offset:4608
	ds_read_b128 v[224:227], v96 offset:41472
	ds_read_b128 v[228:231], v96 offset:36896
	ds_read_b128 v[244:247], v176 offset:32
	ds_read_b128 v[252:255], v176 offset:4640
	s_waitcnt lgkmcnt(5)
	v_mfma_f32_32x32x16_bf16 v[32:47], v[212:215], v[216:219], v[32:47]
	s_waitcnt lgkmcnt(4)
	v_mfma_f32_32x32x16_bf16 v[0:15], v[212:215], v[220:223], v[0:15]
	ds_read_b128 v[212:215], v96 offset:41504
	s_waitcnt lgkmcnt(4)
	v_mfma_f32_32x32x16_bf16 v[48:63], v[224:227], v[216:219], v[48:63]
	ds_read_b128 v[216:219], v96 offset:36928
	v_mfma_f32_32x32x16_bf16 v[16:31], v[224:227], v[220:223], v[16:31]
	ds_read_b128 v[224:227], v176 offset:64
	ds_read_b128 v[220:223], v176 offset:4672
	s_waitcnt lgkmcnt(5)
	v_mfma_f32_32x32x16_bf16 v[32:47], v[228:231], v[244:247], v[32:47]
	s_waitcnt lgkmcnt(4)
	v_mfma_f32_32x32x16_bf16 v[0:15], v[228:231], v[252:255], v[0:15]
	ds_read_b128 v[228:231], v96 offset:41536
	s_waitcnt lgkmcnt(4)
	v_mfma_f32_32x32x16_bf16 v[48:63], v[212:215], v[244:247], v[48:63]
	ds_read_b128 v[244:247], v96 offset:36960
	v_mfma_f32_32x32x16_bf16 v[16:31], v[212:215], v[252:255], v[16:31]
	ds_read_b128 v[212:215], v176 offset:96
	ds_read_b128 v[252:255], v176 offset:4704
	s_waitcnt lgkmcnt(5)
	v_mfma_f32_32x32x16_bf16 v[32:47], v[216:219], v[224:227], v[32:47]
	s_waitcnt vmcnt(15)
	ds_write_b128 v175, v[98:101] offset:18432
	global_load_dwordx4 v[68:71], v[152:153], off offset:640
	s_waitcnt lgkmcnt(5)
	v_mfma_f32_32x32x16_bf16 v[0:15], v[216:219], v[220:223], v[0:15]
	ds_read_b128 v[216:219], v96 offset:41568
	s_waitcnt vmcnt(15)
	ds_write_b128 v175, v[102:105] offset:23040
	global_load_dwordx4 v[84:87], v[154:155], off offset:640
	s_waitcnt lgkmcnt(6)
	v_mfma_f32_32x32x16_bf16 v[48:63], v[228:231], v[224:227], v[48:63]
	s_waitcnt vmcnt(15)
	ds_write_b128 v175, v[106:109] offset:27648
	global_load_dwordx4 v[88:91], v[156:157], off offset:640
	v_mfma_f32_32x32x16_bf16 v[16:31], v[228:231], v[220:223], v[16:31]
	s_waitcnt vmcnt(15)
	ds_write_b128 v175, v[110:113] offset:32256
	global_load_dwordx4 v[92:95], v[158:159], off offset:640
	s_waitcnt lgkmcnt(6)
	v_mfma_f32_32x32x16_bf16 v[32:47], v[244:247], v[212:215], v[32:47]
	s_waitcnt vmcnt(15)
	ds_write_b128 v175, v[114:117] offset:55296
	global_load_dwordx4 v[98:101], v[150:151], off offset:640
	s_waitcnt lgkmcnt(6)
	v_mfma_f32_32x32x16_bf16 v[0:15], v[244:247], v[252:255], v[0:15]
	s_waitcnt vmcnt(15)
	ds_write_b128 v175, v[118:121] offset:59904
	global_load_dwordx4 v[106:109], v[160:161], off offset:640
	s_waitcnt lgkmcnt(5)
	v_mfma_f32_32x32x16_bf16 v[48:63], v[216:219], v[212:215], v[48:63]
	s_waitcnt vmcnt(15)
	ds_write_b128 v175, v[122:125] offset:64512
	global_load_dwordx4 v[110:113], v[170:171], off offset:640
	v_mfma_f32_32x32x16_bf16 v[16:31], v[216:219], v[252:255], v[16:31]
	s_waitcnt vmcnt(15)
	ds_write_b128 v177, v[130:133] offset:13824
	global_load_dwordx4 v[114:117], v[172:173], off offset:640
	s_setprio 0
	s_waitcnt lgkmcnt(0)
	s_barrier
	s_setprio 1
	ds_read_b128 v[212:215], v96 offset:55296
	ds_read_b128 v[216:219], v176 offset:18432
	ds_read_b128 v[220:223], v176 offset:23040
	ds_read_b128 v[224:227], v96 offset:59904
	ds_read_b128 v[228:231], v96 offset:55328
	ds_read_b128 v[244:247], v176 offset:18464
	ds_read_b128 v[252:255], v176 offset:23072
	s_waitcnt lgkmcnt(5)
	v_mfma_f32_32x32x16_bf16 v[32:47], v[212:215], v[216:219], v[32:47]
	s_waitcnt lgkmcnt(4)
	v_mfma_f32_32x32x16_bf16 v[0:15], v[212:215], v[220:223], v[0:15]
	ds_read_b128 v[212:215], v96 offset:59936
	s_waitcnt lgkmcnt(4)
	v_mfma_f32_32x32x16_bf16 v[48:63], v[224:227], v[216:219], v[48:63]
	ds_read_b128 v[216:219], v96 offset:55360
	v_mfma_f32_32x32x16_bf16 v[16:31], v[224:227], v[220:223], v[16:31]
	ds_read_b128 v[224:227], v176 offset:18496
	ds_read_b128 v[220:223], v176 offset:23104
	s_waitcnt lgkmcnt(5)
	v_mfma_f32_32x32x16_bf16 v[32:47], v[228:231], v[244:247], v[32:47]
	s_waitcnt lgkmcnt(4)
	v_mfma_f32_32x32x16_bf16 v[0:15], v[228:231], v[252:255], v[0:15]
	ds_read_b128 v[228:231], v96 offset:59968
	s_waitcnt lgkmcnt(4)
	v_mfma_f32_32x32x16_bf16 v[48:63], v[212:215], v[244:247], v[48:63]
	ds_read_b128 v[244:247], v96 offset:55392
	v_mfma_f32_32x32x16_bf16 v[16:31], v[212:215], v[252:255], v[16:31]
	ds_read_b128 v[212:215], v176 offset:18528
	ds_read_b128 v[252:255], v176 offset:23136
	s_waitcnt lgkmcnt(5)
	v_mfma_f32_32x32x16_bf16 v[32:47], v[216:219], v[224:227], v[32:47]
	s_waitcnt vmcnt(15)
	ds_write_b128 v175, v[64:67]
	global_load_dwordx4 v[64:67], v[152:153], off offset:768
	s_waitcnt lgkmcnt(5)
	v_mfma_f32_32x32x16_bf16 v[0:15], v[216:219], v[220:223], v[0:15]
	ds_read_b128 v[216:219], v96 offset:60000
	s_waitcnt vmcnt(15)
	ds_write_b128 v175, v[72:75] offset:4608
	global_load_dwordx4 v[72:75], v[154:155], off offset:768
	s_waitcnt lgkmcnt(6)
	v_mfma_f32_32x32x16_bf16 v[48:63], v[228:231], v[224:227], v[48:63]
	s_waitcnt vmcnt(15)
	ds_write_b128 v175, v[76:79] offset:9216
	global_load_dwordx4 v[76:79], v[156:157], off offset:768
	v_mfma_f32_32x32x16_bf16 v[16:31], v[228:231], v[220:223], v[16:31]
	s_waitcnt vmcnt(15)
	ds_write_b128 v175, v[80:83] offset:13824
	global_load_dwordx4 v[80:83], v[158:159], off offset:768
	s_waitcnt lgkmcnt(6)
	v_mfma_f32_32x32x16_bf16 v[32:47], v[244:247], v[212:215], v[32:47]
	s_waitcnt vmcnt(15)
	ds_write_b128 v175, v[126:129] offset:36864
	global_load_dwordx4 v[102:105], v[150:151], off offset:768
	s_waitcnt lgkmcnt(6)
	v_mfma_f32_32x32x16_bf16 v[0:15], v[244:247], v[252:255], v[0:15]
	s_waitcnt vmcnt(15)
	ds_write_b128 v175, v[134:137] offset:41472
	global_load_dwordx4 v[118:121], v[160:161], off offset:768
	s_waitcnt lgkmcnt(5)
	v_mfma_f32_32x32x16_bf16 v[48:63], v[216:219], v[212:215], v[48:63]
	s_waitcnt vmcnt(15)
	ds_write_b128 v175, v[138:141] offset:46080
	global_load_dwordx4 v[122:125], v[170:171], off offset:768
	v_mfma_f32_32x32x16_bf16 v[16:31], v[216:219], v[252:255], v[16:31]
	s_waitcnt vmcnt(15)
	ds_write_b128 v175, v[142:145] offset:50688
	global_load_dwordx4 v[126:129], v[172:173], off offset:768
	s_setprio 0
	s_waitcnt lgkmcnt(0)
	s_barrier
	s_setprio 1
	ds_read_b128 v[212:215], v96 offset:36864
	ds_read_b128 v[216:219], v176
	ds_read_b128 v[220:223], v176 offset:4608
	ds_read_b128 v[224:227], v96 offset:41472
	ds_read_b128 v[228:231], v96 offset:36896
	ds_read_b128 v[244:247], v176 offset:32
	ds_read_b128 v[252:255], v176 offset:4640
	s_waitcnt lgkmcnt(5)
	v_mfma_f32_32x32x16_bf16 v[32:47], v[212:215], v[216:219], v[32:47]
	s_waitcnt lgkmcnt(4)
	v_mfma_f32_32x32x16_bf16 v[0:15], v[212:215], v[220:223], v[0:15]
	ds_read_b128 v[212:215], v96 offset:41504
	s_waitcnt lgkmcnt(4)
	v_mfma_f32_32x32x16_bf16 v[48:63], v[224:227], v[216:219], v[48:63]
	ds_read_b128 v[216:219], v96 offset:36928
	v_mfma_f32_32x32x16_bf16 v[16:31], v[224:227], v[220:223], v[16:31]
	ds_read_b128 v[224:227], v176 offset:64
	ds_read_b128 v[220:223], v176 offset:4672
	s_waitcnt lgkmcnt(5)
	v_mfma_f32_32x32x16_bf16 v[32:47], v[228:231], v[244:247], v[32:47]
	s_waitcnt lgkmcnt(4)
	v_mfma_f32_32x32x16_bf16 v[0:15], v[228:231], v[252:255], v[0:15]
	ds_read_b128 v[228:231], v96 offset:41536
	s_waitcnt lgkmcnt(4)
	v_mfma_f32_32x32x16_bf16 v[48:63], v[212:215], v[244:247], v[48:63]
	ds_read_b128 v[244:247], v96 offset:36960
	v_mfma_f32_32x32x16_bf16 v[16:31], v[212:215], v[252:255], v[16:31]
	ds_read_b128 v[212:215], v176 offset:96
	ds_read_b128 v[252:255], v176 offset:4704
	s_waitcnt lgkmcnt(5)
	v_mfma_f32_32x32x16_bf16 v[32:47], v[216:219], v[224:227], v[32:47]
	s_waitcnt vmcnt(15)
	ds_write_b128 v175, v[68:71] offset:18432
	global_load_dwordx4 v[68:71], v[152:153], off offset:896
	s_waitcnt lgkmcnt(5)
	v_mfma_f32_32x32x16_bf16 v[0:15], v[216:219], v[220:223], v[0:15]
	ds_read_b128 v[216:219], v96 offset:41568
	s_waitcnt vmcnt(15)
	ds_write_b128 v175, v[84:87] offset:23040
	global_load_dwordx4 v[84:87], v[154:155], off offset:896
	s_waitcnt lgkmcnt(6)
	v_mfma_f32_32x32x16_bf16 v[48:63], v[228:231], v[224:227], v[48:63]
	s_waitcnt vmcnt(15)
	ds_write_b128 v175, v[88:91] offset:27648
	global_load_dwordx4 v[88:91], v[156:157], off offset:896
	v_mfma_f32_32x32x16_bf16 v[16:31], v[228:231], v[220:223], v[16:31]
	s_waitcnt vmcnt(15)
	ds_write_b128 v175, v[92:95] offset:32256
	global_load_dwordx4 v[92:95], v[158:159], off offset:896
	s_waitcnt lgkmcnt(6)
	v_mfma_f32_32x32x16_bf16 v[32:47], v[244:247], v[212:215], v[32:47]
	s_waitcnt vmcnt(15)
	ds_write_b128 v175, v[98:101] offset:55296
	global_load_dwordx4 v[98:101], v[150:151], off offset:896
	s_waitcnt lgkmcnt(6)
	v_mfma_f32_32x32x16_bf16 v[0:15], v[244:247], v[252:255], v[0:15]
	s_waitcnt vmcnt(15)
	ds_write_b128 v175, v[106:109] offset:59904
	global_load_dwordx4 v[106:109], v[160:161], off offset:896
	s_waitcnt lgkmcnt(5)
	v_mfma_f32_32x32x16_bf16 v[48:63], v[216:219], v[212:215], v[48:63]
	s_waitcnt vmcnt(15)
	ds_write_b128 v175, v[110:113] offset:64512
	global_load_dwordx4 v[110:113], v[170:171], off offset:896
	v_mfma_f32_32x32x16_bf16 v[16:31], v[216:219], v[252:255], v[16:31]
	s_waitcnt vmcnt(15)
	ds_write_b128 v177, v[114:117] offset:13824
	global_load_dwordx4 v[114:117], v[172:173], off offset:896
	s_setprio 0
	s_waitcnt lgkmcnt(0)
	s_barrier
	s_setprio 1
	ds_read_b128 v[212:215], v96 offset:55296
	ds_read_b128 v[216:219], v176 offset:18432
	ds_read_b128 v[220:223], v176 offset:23040
	ds_read_b128 v[224:227], v96 offset:59904
	ds_read_b128 v[228:231], v96 offset:55328
	ds_read_b128 v[244:247], v176 offset:18464
	ds_read_b128 v[252:255], v176 offset:23072
	s_waitcnt lgkmcnt(5)
	v_mfma_f32_32x32x16_bf16 v[32:47], v[212:215], v[216:219], v[32:47]
	s_waitcnt lgkmcnt(4)
	v_mfma_f32_32x32x16_bf16 v[0:15], v[212:215], v[220:223], v[0:15]
	ds_read_b128 v[212:215], v96 offset:59936
	s_waitcnt lgkmcnt(4)
	v_mfma_f32_32x32x16_bf16 v[48:63], v[224:227], v[216:219], v[48:63]
	ds_read_b128 v[216:219], v96 offset:55360
	v_mfma_f32_32x32x16_bf16 v[16:31], v[224:227], v[220:223], v[16:31]
	ds_read_b128 v[224:227], v176 offset:18496
	ds_read_b128 v[220:223], v176 offset:23104
	s_waitcnt lgkmcnt(5)
	v_mfma_f32_32x32x16_bf16 v[32:47], v[228:231], v[244:247], v[32:47]
	s_waitcnt lgkmcnt(4)
	v_mfma_f32_32x32x16_bf16 v[0:15], v[228:231], v[252:255], v[0:15]
	ds_read_b128 v[228:231], v96 offset:59968
	s_waitcnt lgkmcnt(4)
	v_mfma_f32_32x32x16_bf16 v[48:63], v[212:215], v[244:247], v[48:63]
	ds_read_b128 v[244:247], v96 offset:55392
	v_mfma_f32_32x32x16_bf16 v[16:31], v[212:215], v[252:255], v[16:31]
	ds_read_b128 v[212:215], v176 offset:18528
	ds_read_b128 v[252:255], v176 offset:23136
	s_waitcnt lgkmcnt(5)
	v_mfma_f32_32x32x16_bf16 v[32:47], v[216:219], v[224:227], v[32:47]
	s_waitcnt vmcnt(15)
	ds_write_b128 v175, v[64:67]
	global_load_dwordx4 v[64:67], v[152:153], off offset:1024
	s_waitcnt lgkmcnt(5)
	v_mfma_f32_32x32x16_bf16 v[0:15], v[216:219], v[220:223], v[0:15]
	ds_read_b128 v[216:219], v96 offset:60000
	s_waitcnt vmcnt(15)
	ds_write_b128 v175, v[72:75] offset:4608
	global_load_dwordx4 v[72:75], v[154:155], off offset:1024
	s_waitcnt lgkmcnt(6)
	v_mfma_f32_32x32x16_bf16 v[48:63], v[228:231], v[224:227], v[48:63]
	s_waitcnt vmcnt(15)
	ds_write_b128 v175, v[76:79] offset:9216
	global_load_dwordx4 v[76:79], v[156:157], off offset:1024
	v_mfma_f32_32x32x16_bf16 v[16:31], v[228:231], v[220:223], v[16:31]
	s_waitcnt vmcnt(15)
	ds_write_b128 v175, v[80:83] offset:13824
	global_load_dwordx4 v[80:83], v[158:159], off offset:1024
	s_waitcnt lgkmcnt(6)
	v_mfma_f32_32x32x16_bf16 v[32:47], v[244:247], v[212:215], v[32:47]
	s_waitcnt vmcnt(15)
	ds_write_b128 v175, v[102:105] offset:36864
	global_load_dwordx4 v[102:105], v[150:151], off offset:1024
	s_waitcnt lgkmcnt(6)
	v_mfma_f32_32x32x16_bf16 v[0:15], v[244:247], v[252:255], v[0:15]
	s_waitcnt vmcnt(15)
	ds_write_b128 v175, v[118:121] offset:41472
	global_load_dwordx4 v[118:121], v[160:161], off offset:1024
	s_waitcnt lgkmcnt(5)
	v_mfma_f32_32x32x16_bf16 v[48:63], v[216:219], v[212:215], v[48:63]
	s_waitcnt vmcnt(15)
	ds_write_b128 v175, v[122:125] offset:46080
	global_load_dwordx4 v[122:125], v[170:171], off offset:1024
	v_mfma_f32_32x32x16_bf16 v[16:31], v[216:219], v[252:255], v[16:31]
	s_waitcnt vmcnt(15)
	ds_write_b128 v175, v[126:129] offset:50688
	global_load_dwordx4 v[126:129], v[172:173], off offset:1024
	s_setprio 0
	s_waitcnt lgkmcnt(0)
	s_barrier
	s_setprio 1
	ds_read_b128 v[212:215], v96 offset:36864
	ds_read_b128 v[216:219], v176
	ds_read_b128 v[220:223], v176 offset:4608
	ds_read_b128 v[224:227], v96 offset:41472
	ds_read_b128 v[228:231], v96 offset:36896
	ds_read_b128 v[244:247], v176 offset:32
	ds_read_b128 v[252:255], v176 offset:4640
	s_waitcnt lgkmcnt(5)
	v_mfma_f32_32x32x16_bf16 v[32:47], v[212:215], v[216:219], v[32:47]
	s_waitcnt lgkmcnt(4)
	v_mfma_f32_32x32x16_bf16 v[0:15], v[212:215], v[220:223], v[0:15]
	ds_read_b128 v[212:215], v96 offset:41504
	s_waitcnt lgkmcnt(4)
	v_mfma_f32_32x32x16_bf16 v[48:63], v[224:227], v[216:219], v[48:63]
	ds_read_b128 v[216:219], v96 offset:36928
	v_mfma_f32_32x32x16_bf16 v[16:31], v[224:227], v[220:223], v[16:31]
	ds_read_b128 v[224:227], v176 offset:64
	ds_read_b128 v[220:223], v176 offset:4672
	s_waitcnt lgkmcnt(5)
	v_mfma_f32_32x32x16_bf16 v[32:47], v[228:231], v[244:247], v[32:47]
	s_waitcnt lgkmcnt(4)
	v_mfma_f32_32x32x16_bf16 v[0:15], v[228:231], v[252:255], v[0:15]
	ds_read_b128 v[228:231], v96 offset:41536
	s_waitcnt lgkmcnt(4)
	v_mfma_f32_32x32x16_bf16 v[48:63], v[212:215], v[244:247], v[48:63]
	ds_read_b128 v[244:247], v96 offset:36960
	v_mfma_f32_32x32x16_bf16 v[16:31], v[212:215], v[252:255], v[16:31]
	ds_read_b128 v[212:215], v176 offset:96
	ds_read_b128 v[252:255], v176 offset:4704
	s_waitcnt lgkmcnt(5)
	v_mfma_f32_32x32x16_bf16 v[32:47], v[216:219], v[224:227], v[32:47]
	s_waitcnt vmcnt(15)
	ds_write_b128 v175, v[68:71] offset:18432
	global_load_dwordx4 v[68:71], v[152:153], off offset:1152
	s_waitcnt lgkmcnt(5)
	v_mfma_f32_32x32x16_bf16 v[0:15], v[216:219], v[220:223], v[0:15]
	ds_read_b128 v[216:219], v96 offset:41568
	s_waitcnt vmcnt(15)
	ds_write_b128 v175, v[84:87] offset:23040
	global_load_dwordx4 v[84:87], v[154:155], off offset:1152
	s_waitcnt lgkmcnt(6)
	v_mfma_f32_32x32x16_bf16 v[48:63], v[228:231], v[224:227], v[48:63]
	s_waitcnt vmcnt(15)
	ds_write_b128 v175, v[88:91] offset:27648
	global_load_dwordx4 v[88:91], v[156:157], off offset:1152
	v_mfma_f32_32x32x16_bf16 v[16:31], v[228:231], v[220:223], v[16:31]
	s_waitcnt vmcnt(15)
	ds_write_b128 v175, v[92:95] offset:32256
	global_load_dwordx4 v[92:95], v[158:159], off offset:1152
	s_waitcnt lgkmcnt(6)
	v_mfma_f32_32x32x16_bf16 v[32:47], v[244:247], v[212:215], v[32:47]
	s_waitcnt vmcnt(15)
	ds_write_b128 v175, v[98:101] offset:55296
	global_load_dwordx4 v[98:101], v[150:151], off offset:1152
	s_waitcnt lgkmcnt(6)
	v_mfma_f32_32x32x16_bf16 v[0:15], v[244:247], v[252:255], v[0:15]
	s_waitcnt vmcnt(15)
	ds_write_b128 v175, v[106:109] offset:59904
	global_load_dwordx4 v[106:109], v[160:161], off offset:1152
	s_waitcnt lgkmcnt(5)
	v_mfma_f32_32x32x16_bf16 v[48:63], v[216:219], v[212:215], v[48:63]
	s_waitcnt vmcnt(15)
	ds_write_b128 v175, v[110:113] offset:64512
	global_load_dwordx4 v[110:113], v[170:171], off offset:1152
	v_mfma_f32_32x32x16_bf16 v[16:31], v[216:219], v[252:255], v[16:31]
	s_waitcnt vmcnt(15)
	ds_write_b128 v177, v[114:117] offset:13824
	global_load_dwordx4 v[114:117], v[172:173], off offset:1152
	s_setprio 0
	s_waitcnt lgkmcnt(0)
	s_barrier
	s_setprio 1
	ds_read_b128 v[212:215], v96 offset:55296
	ds_read_b128 v[216:219], v176 offset:18432
	ds_read_b128 v[220:223], v176 offset:23040
	ds_read_b128 v[224:227], v96 offset:59904
	ds_read_b128 v[228:231], v96 offset:55328
	ds_read_b128 v[244:247], v176 offset:18464
	ds_read_b128 v[252:255], v176 offset:23072
	s_waitcnt lgkmcnt(5)
	v_mfma_f32_32x32x16_bf16 v[32:47], v[212:215], v[216:219], v[32:47]
	s_waitcnt lgkmcnt(4)
	v_mfma_f32_32x32x16_bf16 v[0:15], v[212:215], v[220:223], v[0:15]
	ds_read_b128 v[212:215], v96 offset:59936
	s_waitcnt lgkmcnt(4)
	v_mfma_f32_32x32x16_bf16 v[48:63], v[224:227], v[216:219], v[48:63]
	ds_read_b128 v[216:219], v96 offset:55360
	v_mfma_f32_32x32x16_bf16 v[16:31], v[224:227], v[220:223], v[16:31]
	ds_read_b128 v[224:227], v176 offset:18496
	ds_read_b128 v[220:223], v176 offset:23104
	s_waitcnt lgkmcnt(5)
	v_mfma_f32_32x32x16_bf16 v[32:47], v[228:231], v[244:247], v[32:47]
	s_waitcnt lgkmcnt(4)
	v_mfma_f32_32x32x16_bf16 v[0:15], v[228:231], v[252:255], v[0:15]
	ds_read_b128 v[228:231], v96 offset:59968
	s_waitcnt lgkmcnt(4)
	v_mfma_f32_32x32x16_bf16 v[48:63], v[212:215], v[244:247], v[48:63]
	ds_read_b128 v[244:247], v96 offset:55392
	v_mfma_f32_32x32x16_bf16 v[16:31], v[212:215], v[252:255], v[16:31]
	ds_read_b128 v[212:215], v176 offset:18528
	ds_read_b128 v[252:255], v176 offset:23136
	s_waitcnt lgkmcnt(5)
	v_mfma_f32_32x32x16_bf16 v[32:47], v[216:219], v[224:227], v[32:47]
	s_waitcnt vmcnt(15)
	ds_write_b128 v175, v[64:67]
	global_load_dwordx4 v[64:67], v[152:153], off offset:1280
	s_waitcnt lgkmcnt(5)
	v_mfma_f32_32x32x16_bf16 v[0:15], v[216:219], v[220:223], v[0:15]
	ds_read_b128 v[216:219], v96 offset:60000
	s_waitcnt vmcnt(15)
	ds_write_b128 v175, v[72:75] offset:4608
	global_load_dwordx4 v[72:75], v[154:155], off offset:1280
	s_waitcnt lgkmcnt(6)
	v_mfma_f32_32x32x16_bf16 v[48:63], v[228:231], v[224:227], v[48:63]
	s_waitcnt vmcnt(15)
	ds_write_b128 v175, v[76:79] offset:9216
	global_load_dwordx4 v[76:79], v[156:157], off offset:1280
	v_mfma_f32_32x32x16_bf16 v[16:31], v[228:231], v[220:223], v[16:31]
	s_waitcnt vmcnt(15)
	ds_write_b128 v175, v[80:83] offset:13824
	global_load_dwordx4 v[80:83], v[158:159], off offset:1280
	s_waitcnt lgkmcnt(6)
	v_mfma_f32_32x32x16_bf16 v[32:47], v[244:247], v[212:215], v[32:47]
	s_waitcnt vmcnt(15)
	ds_write_b128 v175, v[102:105] offset:36864
	global_load_dwordx4 v[102:105], v[150:151], off offset:1280
	s_waitcnt lgkmcnt(6)
	v_mfma_f32_32x32x16_bf16 v[0:15], v[244:247], v[252:255], v[0:15]
	s_waitcnt vmcnt(15)
	ds_write_b128 v175, v[118:121] offset:41472
	global_load_dwordx4 v[118:121], v[160:161], off offset:1280
	s_waitcnt lgkmcnt(5)
	v_mfma_f32_32x32x16_bf16 v[48:63], v[216:219], v[212:215], v[48:63]
	s_waitcnt vmcnt(15)
	ds_write_b128 v175, v[122:125] offset:46080
	global_load_dwordx4 v[122:125], v[170:171], off offset:1280
	v_mfma_f32_32x32x16_bf16 v[16:31], v[216:219], v[252:255], v[16:31]
	s_waitcnt vmcnt(15)
	ds_write_b128 v175, v[126:129] offset:50688
	global_load_dwordx4 v[126:129], v[172:173], off offset:1280
	s_setprio 0
	s_waitcnt lgkmcnt(0)
	s_barrier
	s_setprio 1
	ds_read_b128 v[212:215], v96 offset:36864
	ds_read_b128 v[216:219], v176
	ds_read_b128 v[220:223], v176 offset:4608
	ds_read_b128 v[224:227], v96 offset:41472
	ds_read_b128 v[228:231], v96 offset:36896
	ds_read_b128 v[244:247], v176 offset:32
	ds_read_b128 v[252:255], v176 offset:4640
	s_waitcnt lgkmcnt(5)
	v_mfma_f32_32x32x16_bf16 v[32:47], v[212:215], v[216:219], v[32:47]
	s_waitcnt lgkmcnt(4)
	v_mfma_f32_32x32x16_bf16 v[0:15], v[212:215], v[220:223], v[0:15]
	ds_read_b128 v[212:215], v96 offset:41504
	s_waitcnt lgkmcnt(4)
	v_mfma_f32_32x32x16_bf16 v[48:63], v[224:227], v[216:219], v[48:63]
	ds_read_b128 v[216:219], v96 offset:36928
	v_mfma_f32_32x32x16_bf16 v[16:31], v[224:227], v[220:223], v[16:31]
	ds_read_b128 v[224:227], v176 offset:64
	ds_read_b128 v[220:223], v176 offset:4672
	s_waitcnt lgkmcnt(5)
	v_mfma_f32_32x32x16_bf16 v[32:47], v[228:231], v[244:247], v[32:47]
	s_waitcnt lgkmcnt(4)
	v_mfma_f32_32x32x16_bf16 v[0:15], v[228:231], v[252:255], v[0:15]
	ds_read_b128 v[228:231], v96 offset:41536
	s_waitcnt lgkmcnt(4)
	v_mfma_f32_32x32x16_bf16 v[48:63], v[212:215], v[244:247], v[48:63]
	ds_read_b128 v[244:247], v96 offset:36960
	v_mfma_f32_32x32x16_bf16 v[16:31], v[212:215], v[252:255], v[16:31]
	ds_read_b128 v[212:215], v176 offset:96
	ds_read_b128 v[252:255], v176 offset:4704
	s_waitcnt lgkmcnt(5)
	v_mfma_f32_32x32x16_bf16 v[32:47], v[216:219], v[224:227], v[32:47]
	s_waitcnt vmcnt(15)
	ds_write_b128 v175, v[68:71] offset:18432
	global_load_dwordx4 v[68:71], v[152:153], off offset:1408
	s_waitcnt lgkmcnt(5)
	v_mfma_f32_32x32x16_bf16 v[0:15], v[216:219], v[220:223], v[0:15]
	ds_read_b128 v[216:219], v96 offset:41568
	s_waitcnt vmcnt(15)
	ds_write_b128 v175, v[84:87] offset:23040
	global_load_dwordx4 v[84:87], v[154:155], off offset:1408
	s_waitcnt lgkmcnt(6)
	v_mfma_f32_32x32x16_bf16 v[48:63], v[228:231], v[224:227], v[48:63]
	s_waitcnt vmcnt(15)
	ds_write_b128 v175, v[88:91] offset:27648
	global_load_dwordx4 v[88:91], v[156:157], off offset:1408
	v_mfma_f32_32x32x16_bf16 v[16:31], v[228:231], v[220:223], v[16:31]
	s_waitcnt vmcnt(15)
	ds_write_b128 v175, v[92:95] offset:32256
	global_load_dwordx4 v[92:95], v[158:159], off offset:1408
	s_waitcnt lgkmcnt(6)
	v_mfma_f32_32x32x16_bf16 v[32:47], v[244:247], v[212:215], v[32:47]
	s_waitcnt vmcnt(15)
	ds_write_b128 v175, v[98:101] offset:55296
	global_load_dwordx4 v[98:101], v[150:151], off offset:1408
	s_waitcnt lgkmcnt(6)
	v_mfma_f32_32x32x16_bf16 v[0:15], v[244:247], v[252:255], v[0:15]
	s_waitcnt vmcnt(15)
	ds_write_b128 v175, v[106:109] offset:59904
	global_load_dwordx4 v[106:109], v[160:161], off offset:1408
	s_waitcnt lgkmcnt(5)
	v_mfma_f32_32x32x16_bf16 v[48:63], v[216:219], v[212:215], v[48:63]
	s_waitcnt vmcnt(15)
	ds_write_b128 v175, v[110:113] offset:64512
	global_load_dwordx4 v[110:113], v[170:171], off offset:1408
	v_mfma_f32_32x32x16_bf16 v[16:31], v[216:219], v[252:255], v[16:31]
	s_waitcnt vmcnt(15)
	ds_write_b128 v177, v[114:117] offset:13824
	global_load_dwordx4 v[130:133], v[172:173], off offset:1408
	s_setprio 0
	s_waitcnt lgkmcnt(0)
	s_barrier
	s_setprio 1
	ds_read_b128 v[212:215], v96 offset:55296
	ds_read_b128 v[216:219], v176 offset:18432
	ds_read_b128 v[220:223], v176 offset:23040
	ds_read_b128 v[224:227], v96 offset:59904
	ds_read_b128 v[228:231], v96 offset:55328
	ds_read_b128 v[244:247], v176 offset:18464
	ds_read_b128 v[252:255], v176 offset:23072
	s_waitcnt lgkmcnt(5)
	v_mfma_f32_32x32x16_bf16 v[32:47], v[212:215], v[216:219], v[32:47]
	s_waitcnt lgkmcnt(4)
	v_mfma_f32_32x32x16_bf16 v[0:15], v[212:215], v[220:223], v[0:15]
	ds_read_b128 v[212:215], v96 offset:59936
	s_waitcnt lgkmcnt(4)
	v_mfma_f32_32x32x16_bf16 v[48:63], v[224:227], v[216:219], v[48:63]
	ds_read_b128 v[216:219], v96 offset:55360
	v_mfma_f32_32x32x16_bf16 v[16:31], v[224:227], v[220:223], v[16:31]
	ds_read_b128 v[224:227], v176 offset:18496
	ds_read_b128 v[220:223], v176 offset:23104
	s_waitcnt lgkmcnt(5)
	v_mfma_f32_32x32x16_bf16 v[32:47], v[228:231], v[244:247], v[32:47]
	s_waitcnt lgkmcnt(4)
	v_mfma_f32_32x32x16_bf16 v[0:15], v[228:231], v[252:255], v[0:15]
	ds_read_b128 v[228:231], v96 offset:59968
	s_waitcnt lgkmcnt(4)
	v_mfma_f32_32x32x16_bf16 v[48:63], v[212:215], v[244:247], v[48:63]
	ds_read_b128 v[244:247], v96 offset:55392
	v_mfma_f32_32x32x16_bf16 v[16:31], v[212:215], v[252:255], v[16:31]
	ds_read_b128 v[212:215], v176 offset:18528
	ds_read_b128 v[252:255], v176 offset:23136
	s_waitcnt lgkmcnt(5)
	v_mfma_f32_32x32x16_bf16 v[32:47], v[216:219], v[224:227], v[32:47]
	s_waitcnt vmcnt(15)
	ds_write_b128 v175, v[64:67]
	global_load_dwordx4 v[64:67], v[152:153], off offset:1536
	s_waitcnt lgkmcnt(5)
	v_mfma_f32_32x32x16_bf16 v[0:15], v[216:219], v[220:223], v[0:15]
	ds_read_b128 v[216:219], v96 offset:60000
	s_waitcnt vmcnt(15)
	ds_write_b128 v175, v[72:75] offset:4608
	global_load_dwordx4 v[72:75], v[154:155], off offset:1536
	s_waitcnt lgkmcnt(6)
	v_mfma_f32_32x32x16_bf16 v[48:63], v[228:231], v[224:227], v[48:63]
	s_waitcnt vmcnt(15)
	ds_write_b128 v175, v[76:79] offset:9216
	global_load_dwordx4 v[76:79], v[156:157], off offset:1536
	v_mfma_f32_32x32x16_bf16 v[16:31], v[228:231], v[220:223], v[16:31]
	s_waitcnt vmcnt(15)
	ds_write_b128 v175, v[80:83] offset:13824
	global_load_dwordx4 v[80:83], v[158:159], off offset:1536
	s_waitcnt lgkmcnt(6)
	v_mfma_f32_32x32x16_bf16 v[32:47], v[244:247], v[212:215], v[32:47]
	s_waitcnt vmcnt(15)
	ds_write_b128 v175, v[102:105] offset:36864
	global_load_dwordx4 v[114:117], v[150:151], off offset:1536
	s_waitcnt lgkmcnt(6)
	v_mfma_f32_32x32x16_bf16 v[0:15], v[244:247], v[252:255], v[0:15]
	s_waitcnt vmcnt(15)
	ds_write_b128 v175, v[118:121] offset:41472
	s_waitcnt vmcnt(14)
	ds_write_b128 v175, v[122:125] offset:46080
	s_waitcnt lgkmcnt(6)
	v_mfma_f32_32x32x16_bf16 v[48:63], v[216:219], v[212:215], v[48:63]
	global_load_dwordx4 v[122:125], v[160:161], off offset:1536
	s_waitcnt vmcnt(14)
	ds_write_b128 v175, v[126:129] offset:50688
	v_mfma_f32_32x32x16_bf16 v[16:31], v[216:219], v[252:255], v[16:31]
	global_load_dwordx4 v[126:129], v[170:171], off offset:1536
	global_load_dwordx4 v[134:137], v[172:173], off offset:1536
	s_setprio 0
	s_waitcnt lgkmcnt(0)
	s_barrier
	s_setprio 1
	ds_read_b128 v[212:215], v96 offset:36864
	ds_read_b128 v[216:219], v176
	ds_read_b128 v[220:223], v176 offset:4608
	ds_read_b128 v[224:227], v96 offset:41472
	ds_read_b128 v[228:231], v96 offset:36896
	ds_read_b128 v[244:247], v176 offset:32
	ds_read_b128 v[252:255], v176 offset:4640
	s_waitcnt lgkmcnt(5)
	v_mfma_f32_32x32x16_bf16 v[32:47], v[212:215], v[216:219], v[32:47]
	s_waitcnt lgkmcnt(4)
	v_mfma_f32_32x32x16_bf16 v[0:15], v[212:215], v[220:223], v[0:15]
	ds_read_b128 v[212:215], v96 offset:41504
	s_waitcnt lgkmcnt(4)
	v_mfma_f32_32x32x16_bf16 v[48:63], v[224:227], v[216:219], v[48:63]
	ds_read_b128 v[216:219], v96 offset:36928
	v_mfma_f32_32x32x16_bf16 v[16:31], v[224:227], v[220:223], v[16:31]
	ds_read_b128 v[224:227], v176 offset:64
	ds_read_b128 v[220:223], v176 offset:4672
	s_waitcnt lgkmcnt(5)
	v_mfma_f32_32x32x16_bf16 v[32:47], v[228:231], v[244:247], v[32:47]
	s_waitcnt lgkmcnt(4)
	v_mfma_f32_32x32x16_bf16 v[0:15], v[228:231], v[252:255], v[0:15]
	ds_read_b128 v[228:231], v96 offset:41536
	s_waitcnt lgkmcnt(4)
	v_mfma_f32_32x32x16_bf16 v[48:63], v[212:215], v[244:247], v[48:63]
	ds_read_b128 v[244:247], v96 offset:36960
	v_mfma_f32_32x32x16_bf16 v[16:31], v[212:215], v[252:255], v[16:31]
	ds_read_b128 v[212:215], v176 offset:96
	ds_read_b128 v[252:255], v176 offset:4704
	s_waitcnt lgkmcnt(5)
	v_mfma_f32_32x32x16_bf16 v[32:47], v[216:219], v[224:227], v[32:47]
	s_waitcnt vmcnt(15)
	ds_write_b128 v175, v[68:71] offset:18432
	s_waitcnt vmcnt(14)
	ds_write_b128 v175, v[84:87] offset:23040
	s_waitcnt lgkmcnt(6)
	v_mfma_f32_32x32x16_bf16 v[0:15], v[216:219], v[220:223], v[0:15]
	ds_read_b128 v[216:219], v96 offset:41568
	s_waitcnt vmcnt(13)
	ds_write_b128 v175, v[88:91] offset:27648
	s_waitcnt vmcnt(12)
	ds_write_b128 v175, v[92:95] offset:32256
	s_waitcnt lgkmcnt(8)
	v_mfma_f32_32x32x16_bf16 v[48:63], v[228:231], v[224:227], v[48:63]
	s_waitcnt vmcnt(11)
	ds_write_b128 v175, v[98:101] offset:55296
	v_mfma_f32_32x32x16_bf16 v[16:31], v[228:231], v[220:223], v[16:31]
	global_load_dwordx4 v[98:101], v[152:153], off offset:1664
	global_load_dwordx4 v[102:105], v[154:155], off offset:1664
	s_waitcnt vmcnt(12)
	ds_write_b128 v175, v[106:109] offset:59904
	s_waitcnt lgkmcnt(8)
	v_mfma_f32_32x32x16_bf16 v[32:47], v[244:247], v[212:215], v[32:47]
	global_load_dwordx4 v[106:109], v[156:157], off offset:1664
	s_waitcnt vmcnt(12)
	ds_write_b128 v175, v[110:113] offset:64512
	s_waitcnt lgkmcnt(8)
	v_mfma_f32_32x32x16_bf16 v[0:15], v[244:247], v[252:255], v[0:15]
	global_load_dwordx4 v[110:113], v[158:159], off offset:1664
	global_load_dwordx4 v[118:121], v[150:151], off offset:1664
	s_waitcnt lgkmcnt(5)
	v_mfma_f32_32x32x16_bf16 v[48:63], v[216:219], v[212:215], v[48:63]
	s_waitcnt vmcnt(13)
	ds_write_b128 v177, v[130:133] offset:13824
	global_load_dwordx4 v[130:133], v[160:161], off offset:1664
	v_mfma_f32_32x32x16_bf16 v[16:31], v[216:219], v[252:255], v[16:31]
	global_load_dwordx4 v[138:141], v[170:171], off offset:1664
	global_load_dwordx4 v[142:145], v[172:173], off offset:1664
	s_setprio 0
	s_waitcnt lgkmcnt(0)
	s_barrier
	s_setprio 1
	ds_read_b128 v[212:215], v96 offset:55296
	ds_read_b128 v[216:219], v176 offset:18432
	ds_read_b128 v[220:223], v176 offset:23040
	ds_read_b128 v[224:227], v96 offset:59904
	ds_read_b128 v[228:231], v96 offset:55328
	ds_read_b128 v[244:247], v176 offset:18464
	ds_read_b128 v[252:255], v176 offset:23072
	s_waitcnt lgkmcnt(5)
	v_mfma_f32_32x32x16_bf16 v[32:47], v[212:215], v[216:219], v[32:47]
	s_waitcnt lgkmcnt(4)
	v_mfma_f32_32x32x16_bf16 v[0:15], v[212:215], v[220:223], v[0:15]
	ds_read_b128 v[212:215], v96 offset:59936
	s_waitcnt lgkmcnt(4)
	v_mfma_f32_32x32x16_bf16 v[48:63], v[224:227], v[216:219], v[48:63]
	ds_read_b128 v[216:219], v96 offset:55360
	v_mfma_f32_32x32x16_bf16 v[16:31], v[224:227], v[220:223], v[16:31]
	ds_read_b128 v[224:227], v176 offset:18496
	ds_read_b128 v[220:223], v176 offset:23104
	s_waitcnt lgkmcnt(5)
	v_mfma_f32_32x32x16_bf16 v[32:47], v[228:231], v[244:247], v[32:47]
	s_waitcnt lgkmcnt(4)
	v_mfma_f32_32x32x16_bf16 v[0:15], v[228:231], v[252:255], v[0:15]
	ds_read_b128 v[228:231], v96 offset:59968
	s_waitcnt lgkmcnt(4)
	v_mfma_f32_32x32x16_bf16 v[48:63], v[212:215], v[244:247], v[48:63]
	ds_read_b128 v[244:247], v96 offset:55392
	v_mfma_f32_32x32x16_bf16 v[16:31], v[212:215], v[252:255], v[16:31]
	ds_read_b128 v[212:215], v176 offset:18528
	ds_read_b128 v[252:255], v176 offset:23136
	s_waitcnt lgkmcnt(5)
	v_mfma_f32_32x32x16_bf16 v[32:47], v[216:219], v[224:227], v[32:47]
	s_waitcnt vmcnt(15)
	ds_write_b128 v175, v[64:67]
	global_load_dwordx4 v[64:67], v[152:153], off offset:1792
	s_waitcnt lgkmcnt(5)
	v_mfma_f32_32x32x16_bf16 v[0:15], v[216:219], v[220:223], v[0:15]
	ds_read_b128 v[216:219], v96 offset:60000
	s_waitcnt vmcnt(15)
	ds_write_b128 v175, v[72:75] offset:4608
	global_load_dwordx4 v[68:71], v[154:155], off offset:1792
	s_waitcnt lgkmcnt(6)
	v_mfma_f32_32x32x16_bf16 v[48:63], v[228:231], v[224:227], v[48:63]
	s_waitcnt vmcnt(15)
	ds_write_b128 v175, v[76:79] offset:9216
	global_load_dwordx4 v[72:75], v[156:157], off offset:1792
	v_mfma_f32_32x32x16_bf16 v[16:31], v[228:231], v[220:223], v[16:31]
	s_waitcnt vmcnt(15)
	ds_write_b128 v175, v[80:83] offset:13824
	global_load_dwordx4 v[76:79], v[158:159], off offset:1792
	s_waitcnt lgkmcnt(6)
	v_mfma_f32_32x32x16_bf16 v[32:47], v[244:247], v[212:215], v[32:47]
	s_waitcnt vmcnt(15)
	ds_write_b128 v175, v[114:117] offset:36864
	global_load_dwordx4 v[80:83], v[150:151], off offset:1792
	s_waitcnt lgkmcnt(6)
	v_mfma_f32_32x32x16_bf16 v[0:15], v[244:247], v[252:255], v[0:15]
	s_waitcnt vmcnt(15)
	ds_write_b128 v175, v[122:125] offset:41472
	global_load_dwordx4 v[84:87], v[160:161], off offset:1792
	s_waitcnt lgkmcnt(5)
	v_mfma_f32_32x32x16_bf16 v[48:63], v[216:219], v[212:215], v[48:63]
	s_waitcnt vmcnt(15)
	ds_write_b128 v175, v[126:129] offset:46080
	global_load_dwordx4 v[88:91], v[170:171], off offset:1792
	v_mfma_f32_32x32x16_bf16 v[16:31], v[216:219], v[252:255], v[16:31]
	s_waitcnt vmcnt(15)
	ds_write_b128 v175, v[134:137] offset:50688
	global_load_dwordx4 v[92:95], v[172:173], off offset:1792
	s_setprio 0
	s_waitcnt lgkmcnt(0)
	s_barrier
	s_setprio 1
	ds_read_b128 v[212:215], v96 offset:36864
	ds_read_b128 v[216:219], v176
	ds_read_b128 v[220:223], v176 offset:4608
	ds_read_b128 v[224:227], v96 offset:41472
	ds_read_b128 v[228:231], v96 offset:36896
	ds_read_b128 v[244:247], v176 offset:32
	ds_read_b128 v[252:255], v176 offset:4640
	s_waitcnt lgkmcnt(5)
	v_mfma_f32_32x32x16_bf16 v[32:47], v[212:215], v[216:219], v[32:47]
	s_waitcnt lgkmcnt(4)
	v_mfma_f32_32x32x16_bf16 v[0:15], v[212:215], v[220:223], v[0:15]
	ds_read_b128 v[212:215], v96 offset:41504
	s_waitcnt lgkmcnt(4)
	v_mfma_f32_32x32x16_bf16 v[48:63], v[224:227], v[216:219], v[48:63]
	ds_read_b128 v[216:219], v96 offset:36928
	v_mfma_f32_32x32x16_bf16 v[16:31], v[224:227], v[220:223], v[16:31]
	ds_read_b128 v[224:227], v176 offset:64
	ds_read_b128 v[220:223], v176 offset:4672
	s_waitcnt lgkmcnt(5)
	v_mfma_f32_32x32x16_bf16 v[32:47], v[228:231], v[244:247], v[32:47]
	s_waitcnt lgkmcnt(4)
	v_mfma_f32_32x32x16_bf16 v[0:15], v[228:231], v[252:255], v[0:15]
	ds_read_b128 v[228:231], v96 offset:41536
	s_waitcnt lgkmcnt(4)
	v_mfma_f32_32x32x16_bf16 v[48:63], v[212:215], v[244:247], v[48:63]
	ds_read_b128 v[244:247], v96 offset:36960
	v_mfma_f32_32x32x16_bf16 v[16:31], v[212:215], v[252:255], v[16:31]
	ds_read_b128 v[212:215], v176 offset:96
	ds_read_b128 v[252:255], v176 offset:4704
	s_waitcnt lgkmcnt(5)
	v_mfma_f32_32x32x16_bf16 v[32:47], v[216:219], v[224:227], v[32:47]
	s_waitcnt vmcnt(15)
	ds_write_b128 v175, v[98:101] offset:18432
	s_waitcnt vmcnt(14)
	ds_write_b128 v175, v[102:105] offset:23040
	s_waitcnt lgkmcnt(6)
	v_mfma_f32_32x32x16_bf16 v[0:15], v[216:219], v[220:223], v[0:15]
	ds_read_b128 v[216:219], v96 offset:41568
	global_load_dwordx4 v[100:103], v[152:153], off offset:1920
	s_waitcnt vmcnt(14)
	ds_write_b128 v175, v[106:109] offset:27648
	s_waitcnt lgkmcnt(7)
	v_mfma_f32_32x32x16_bf16 v[48:63], v[228:231], v[224:227], v[48:63]
	global_load_dwordx4 v[104:107], v[154:155], off offset:1920
	s_waitcnt vmcnt(14)
	ds_write_b128 v175, v[110:113] offset:32256
	v_mfma_f32_32x32x16_bf16 v[16:31], v[228:231], v[220:223], v[16:31]
	global_load_dwordx4 v[108:111], v[156:157], off offset:1920
	global_load_dwordx4 v[112:115], v[158:159], off offset:1920
	s_waitcnt lgkmcnt(6)
	v_mfma_f32_32x32x16_bf16 v[32:47], v[244:247], v[212:215], v[32:47]
	s_waitcnt vmcnt(15)
	ds_write_b128 v175, v[118:121] offset:55296
	global_load_dwordx4 v[116:119], v[150:151], off offset:1920
	s_waitcnt lgkmcnt(6)
	v_mfma_f32_32x32x16_bf16 v[0:15], v[244:247], v[252:255], v[0:15]
	s_waitcnt vmcnt(15)
	ds_write_b128 v175, v[130:133] offset:59904
	global_load_dwordx4 v[124:127], v[160:161], off offset:1920
	s_waitcnt lgkmcnt(4)
	v_mfma_f32_32x32x16_bf16 v[48:63], v[216:219], v[212:215], v[48:63]
	s_waitcnt vmcnt(15)
	ds_write_b128 v175, v[138:141] offset:64512
	global_load_dwordx4 v[120:123], v[170:171], off offset:1920
	v_mfma_f32_32x32x16_bf16 v[16:31], v[216:219], v[252:255], v[16:31]
	s_waitcnt vmcnt(15)
	ds_write_b128 v177, v[142:145] offset:13824
	global_load_dwordx4 v[128:131], v[172:173], off offset:1920
	s_setprio 0
	s_waitcnt lgkmcnt(0)
	s_barrier
	s_setprio 1
	ds_read_b128 v[212:215], v96 offset:55296
	ds_read_b128 v[216:219], v176 offset:18432
	ds_read_b128 v[220:223], v176 offset:23040
	ds_read_b128 v[224:227], v96 offset:59904
	ds_read_b128 v[228:231], v96 offset:55328
	ds_read_b128 v[244:247], v176 offset:18464
	ds_read_b128 v[252:255], v176 offset:23072
	s_waitcnt lgkmcnt(5)
	v_mfma_f32_32x32x16_bf16 v[32:47], v[212:215], v[216:219], v[32:47]
	s_waitcnt lgkmcnt(4)
	v_mfma_f32_32x32x16_bf16 v[0:15], v[212:215], v[220:223], v[0:15]
	ds_read_b128 v[212:215], v96 offset:59936
	s_waitcnt lgkmcnt(4)
	v_mfma_f32_32x32x16_bf16 v[48:63], v[224:227], v[216:219], v[48:63]
	ds_read_b128 v[216:219], v96 offset:55360
	v_mfma_f32_32x32x16_bf16 v[16:31], v[224:227], v[220:223], v[16:31]
	ds_read_b128 v[224:227], v176 offset:18496
	ds_read_b128 v[220:223], v176 offset:23104
	s_waitcnt lgkmcnt(5)
	v_mfma_f32_32x32x16_bf16 v[32:47], v[228:231], v[244:247], v[32:47]
	s_waitcnt lgkmcnt(4)
	v_mfma_f32_32x32x16_bf16 v[0:15], v[228:231], v[252:255], v[0:15]
	ds_read_b128 v[228:231], v96 offset:59968
	s_waitcnt lgkmcnt(4)
	v_mfma_f32_32x32x16_bf16 v[48:63], v[212:215], v[244:247], v[48:63]
	ds_read_b128 v[244:247], v96 offset:55392
	v_mfma_f32_32x32x16_bf16 v[16:31], v[212:215], v[252:255], v[16:31]
	ds_read_b128 v[212:215], v176 offset:18528
	ds_read_b128 v[252:255], v176 offset:23136
	s_waitcnt lgkmcnt(5)
	v_mfma_f32_32x32x16_bf16 v[32:47], v[216:219], v[224:227], v[32:47]
	s_waitcnt lgkmcnt(4)
	v_mfma_f32_32x32x16_bf16 v[0:15], v[216:219], v[220:223], v[0:15]
	ds_read_b128 v[216:219], v96 offset:60000
	s_waitcnt lgkmcnt(4)
	v_mfma_f32_32x32x16_bf16 v[48:63], v[228:231], v[224:227], v[48:63]
	v_mfma_f32_32x32x16_bf16 v[16:31], v[228:231], v[220:223], v[16:31]
	s_waitcnt lgkmcnt(2)
	v_mfma_f32_32x32x16_bf16 v[32:47], v[244:247], v[212:215], v[32:47]
	s_waitcnt lgkmcnt(1)
	v_mfma_f32_32x32x16_bf16 v[0:15], v[244:247], v[252:255], v[0:15]
	s_waitcnt lgkmcnt(0)
	v_mfma_f32_32x32x16_bf16 v[48:63], v[216:219], v[212:215], v[48:63]
	v_mfma_f32_32x32x16_bf16 v[16:31], v[216:219], v[252:255], v[16:31]
	s_setprio 0
	v_cndmask_b32_e64 v98, 0, 1, s[12:13]
	v_cmp_ne_u32_e64 s[40:41], 1, v98
	s_andn2_b64 vcc, exec, s[12:13]
	s_waitcnt vmcnt(15)
	ds_write_b128 v175, v[64:67]
	s_waitcnt vmcnt(14)
	ds_write_b128 v175, v[68:71] offset:4608
	s_waitcnt vmcnt(13)
	ds_write_b128 v175, v[72:75] offset:9216
	s_waitcnt vmcnt(12)
	ds_write_b128 v175, v[76:79] offset:13824
	s_waitcnt vmcnt(11)
	ds_write_b128 v175, v[80:83] offset:36864
	s_waitcnt vmcnt(10)
	ds_write_b128 v175, v[84:87] offset:41472
	s_waitcnt vmcnt(9)
	ds_write_b128 v175, v[88:91] offset:46080
	s_waitcnt vmcnt(8)
	ds_write_b128 v175, v[92:95] offset:50688
	s_cbranch_vccnz .LBB0_270
	v_add_co_u32_e32 v68, vcc, 0x10000, v148
	global_load_dwordx4 v[64:67], v[148:149], off
	s_nop 0
	v_addc_co_u32_e32 v69, vcc, 0, v149, vcc
	v_add_co_u32_e32 v72, vcc, 0x20000, v148
	s_nop 1
	v_addc_co_u32_e32 v73, vcc, 0, v149, vcc
	v_add_co_u32_e32 v76, vcc, 0x30000, v148
	global_load_dwordx4 v[68:71], v[68:69], off
	global_load_dwordx4 v[72:75], v[72:73], off
	v_addc_co_u32_e32 v77, vcc, 0, v149, vcc
	v_add_co_u32_e32 v84, vcc, 0x10000, v146
	global_load_dwordx4 v[76:79], v[76:77], off
	s_nop 0
	global_load_dwordx4 v[80:83], v[146:147], off
	v_addc_co_u32_e32 v85, vcc, 0, v147, vcc
	v_add_co_u32_e32 v88, vcc, 0x20000, v146
	s_nop 1
	v_addc_co_u32_e32 v89, vcc, 0, v147, vcc
	v_add_co_u32_e32 v92, vcc, 0x30000, v146
	global_load_dwordx4 v[84:87], v[84:85], off
	s_nop 0
	global_load_dwordx4 v[88:91], v[88:89], off
	v_addc_co_u32_e32 v93, vcc, 0, v147, vcc
	global_load_dwordx4 v[92:95], v[92:93], off

.LBB0_274:
	s_waitcnt vmcnt(0)
	s_barrier
	s_mov_b64 s[0:1], exec
	v_readlane_b32 s2, v251, 0
	v_readlane_b32 s3, v251, 1
	s_and_b64 s[2:3], s[0:1], s[2:3]
	s_xor_b64 s[0:1], s[2:3], s[0:1]
	s_mov_b64 exec, s[2:3]
	s_cbranch_execz .LBB0_323
	v_readlane_b32 s2, v249, 49
	s_waitcnt expcnt(0) lgkmcnt(0)
	s_nop 0
	v_mov_b32_e32 v0, s2
	ds_read_b32 v2, v0
	v_readlane_b32 s2, v249, 50
	s_waitcnt lgkmcnt(0)
	v_cmp_ne_u32_e32 vcc, 0, v2
	v_mov_b32_e32 v0, s2
	ds_read_b32 v0, v0
	s_cbranch_vccnz .LBB0_290
	s_mov_b32 s4, 1
	s_branch .LBB0_278

.LBB0_340:
	s_waitcnt vmcnt(0)
	s_barrier
	s_mov_b64 s[0:1], exec
	v_readlane_b32 s2, v251, 0
	v_readlane_b32 s3, v251, 1
	s_and_b64 s[2:3], s[0:1], s[2:3]
	s_mov_b64 exec, s[2:3]
	s_cbranch_execz .LBB0_388
	v_readlane_b32 s2, v249, 49
	s_waitcnt expcnt(0) lgkmcnt(0)
	s_nop 0
	v_mov_b32_e32 v0, s2
	ds_read_b32 v2, v0
	v_readlane_b32 s2, v249, 50
	s_waitcnt lgkmcnt(0)
	v_cmp_ne_u32_e32 vcc, 0, v2
	v_mov_b32_e32 v0, s2
	ds_read_b32 v0, v0
	s_cbranch_vccnz .LBB0_356
	s_mov_b32 s4, 1
	s_branch .LBB0_344

.LBB0_472:
	s_ashr_i32 s47, s46, 31
	s_lshl_b64 s[40:41], s[46:47], 18
	s_add_u32 s3, s82, s40
	s_addc_u32 s7, s83, s41
	s_and_b64 s[40:41], s[12:13], exec
	s_cselect_b32 s41, s7, 0
	s_cselect_b32 s40, s3, 0
	s_ashr_i32 s45, s44, 31
	s_lshl_b64 s[42:43], s[44:45], 18
	v_readlane_b32 s14, v251, 56
	v_readlane_b32 s15, v251, 57
	s_add_u32 s3, s14, s42
	s_addc_u32 s7, s15, s43
	s_and_b64 s[42:43], s[12:13], exec
	s_cselect_b32 s43, s7, 0
	s_cselect_b32 s42, s3, 0
	v_lshl_add_u64 v[4:5], s[40:41], 0, v[0:1]
	v_lshl_add_u64 v[0:1], s[42:43], 0, v[0:1]
	v_lshl_add_u64 v[146:147], v[0:1], 0, v[96:97]
	v_lshrrev_b32_e32 v0, 1, v2
	v_and_b32_e32 v1, 31, v2
	v_and_or_b32 v1, v0, s81, v1
	v_lshrrev_b32_e32 v0, 2, v2
	v_and_b32_e32 v0, 8, v0
	v_lshl_add_u64 v[148:149], v[4:5], 0, v[96:97]
	v_mad_u64_u32 v[4:5], s[40:41], v1, s84, v[0:1]
	v_and_b32_e32 v1, 0x5f, v2
	v_mad_u32_u24 v0, v1, s84, v0
	v_lshl_add_u32 v178, v4, 1, 0
	v_lshl_add_u32 v96, v0, 1, 0
	v_add_u32_e32 v179, 0xd800, v177
	s_setprio 1
	ds_read_b128 v[212:215], v96 offset:36864
	ds_read_b128 v[216:219], v178
	ds_read_b128 v[220:223], v178 offset:4608
	ds_read_b128 v[224:227], v96 offset:36896
	ds_read_b128 v[228:231], v178 offset:32
	ds_read_b128 v[244:247], v178 offset:4640
	ds_read_b128 v[252:255], v96 offset:41472
	s_waitcnt lgkmcnt(5)
	v_mfma_f32_32x32x16_bf16 v[48:63], v[212:215], v[216:219], 0
	s_waitcnt lgkmcnt(4)
	v_mfma_f32_32x32x16_bf16 v[32:47], v[212:215], v[220:223], 0
	ds_read_b128 v[212:215], v96 offset:41504
	s_waitcnt lgkmcnt(3)
	v_mfma_f32_32x32x16_bf16 v[48:63], v[224:227], v[228:231], v[48:63]
	s_waitcnt lgkmcnt(2)
	v_mfma_f32_32x32x16_bf16 v[32:47], v[224:227], v[244:247], v[32:47]
	ds_read_b128 v[224:227], v96 offset:36928
	s_waitcnt lgkmcnt(2)
	v_mfma_f32_32x32x16_bf16 v[16:31], v[252:255], v[216:219], 0
	ds_read_b128 v[216:219], v178 offset:64
	v_mfma_f32_32x32x16_bf16 v[0:15], v[252:255], v[220:223], 0
	ds_read_b128 v[252:255], v178 offset:4672
	ds_read_b128 v[220:223], v96 offset:41536
	s_waitcnt lgkmcnt(4)
	v_mfma_f32_32x32x16_bf16 v[16:31], v[212:215], v[228:231], v[16:31]
	ds_read_b128 v[228:231], v96 offset:36960
	v_mfma_f32_32x32x16_bf16 v[0:15], v[212:215], v[244:247], v[0:15]
	ds_read_b128 v[212:215], v178 offset:96
	ds_read_b128 v[244:247], v178 offset:4704
	s_waitcnt lgkmcnt(5)
	v_mfma_f32_32x32x16_bf16 v[48:63], v[224:227], v[216:219], v[48:63]
	s_mov_b32 s3, 0x10000
	v_add_co_u32_e32 v154, vcc, s3, v152
	s_mov_b32 s7, 0x20000
	s_nop 0
	v_addc_co_u32_e32 v155, vcc, 0, v153, vcc
	v_add_co_u32_e32 v156, vcc, s7, v152
	s_mov_b32 s8, 0x30000
	s_nop 0
	s_waitcnt lgkmcnt(4)
	v_mfma_f32_32x32x16_bf16 v[32:47], v[224:227], v[252:255], v[32:47]
	ds_read_b128 v[224:227], v96 offset:41568
	v_addc_co_u32_e32 v157, vcc, 0, v153, vcc
	v_add_co_u32_e32 v158, vcc, s8, v152
	s_waitcnt vmcnt(7)
	ds_write_b128 v177, v[100:103] offset:18432
	s_waitcnt vmcnt(6)
	ds_write_b128 v177, v[104:107] offset:23040
	s_waitcnt lgkmcnt(6)
	v_mfma_f32_32x32x16_bf16 v[16:31], v[220:223], v[216:219], v[16:31]
	s_waitcnt vmcnt(5)
	ds_write_b128 v177, v[108:111] offset:27648
	s_waitcnt vmcnt(4)
	ds_write_b128 v177, v[112:115] offset:32256
	v_mfma_f32_32x32x16_bf16 v[0:15], v[220:223], v[252:255], v[0:15]
	s_waitcnt vmcnt(3)
	ds_write_b128 v177, v[116:119] offset:55296
	s_waitcnt vmcnt(2)
	ds_write_b128 v177, v[120:123] offset:59904
	s_waitcnt vmcnt(1)
	ds_write_b128 v177, v[128:131] offset:64512
	s_waitcnt lgkmcnt(9)
	v_mfma_f32_32x32x16_bf16 v[48:63], v[228:231], v[212:215], v[48:63]
	s_waitcnt vmcnt(0)
	ds_write_b128 v179, v[124:127] offset:13824
	v_addc_co_u32_e32 v159, vcc, 0, v153, vcc
	v_add_co_u32_e32 v160, vcc, s3, v150
	s_waitcnt lgkmcnt(9)
	v_mfma_f32_32x32x16_bf16 v[32:47], v[228:231], v[244:247], v[32:47]
	global_load_dwordx4 v[98:101], v[152:153], off offset:384
	global_load_dwordx4 v[102:105], v[154:155], off offset:384
	v_addc_co_u32_e32 v161, vcc, 0, v151, vcc
	v_add_co_u32_e32 v170, vcc, s7, v150
	global_load_dwordx4 v[106:109], v[156:157], off offset:384
	s_waitcnt lgkmcnt(8)
	v_mfma_f32_32x32x16_bf16 v[16:31], v[224:227], v[212:215], v[16:31]
	s_nop 0
	v_addc_co_u32_e32 v171, vcc, 0, v151, vcc
	v_add_co_u32_e32 v172, vcc, s8, v150
	global_load_dwordx4 v[110:113], v[158:159], off offset:384
	global_load_dwordx4 v[114:117], v[150:151], off offset:384
	v_mfma_f32_32x32x16_bf16 v[0:15], v[224:227], v[244:247], v[0:15]
	v_addc_co_u32_e32 v173, vcc, 0, v151, vcc
	global_load_dwordx4 v[118:121], v[160:161], off offset:384
	global_load_dwordx4 v[122:125], v[170:171], off offset:384
	global_load_dwordx4 v[130:133], v[172:173], off offset:384
	s_setprio 0
	s_waitcnt lgkmcnt(0)
	s_barrier
	s_setprio 1
	ds_read_b128 v[212:215], v96 offset:55296
	ds_read_b128 v[216:219], v178 offset:18432
	ds_read_b128 v[220:223], v178 offset:23040
	ds_read_b128 v[224:227], v96 offset:59904
	ds_read_b128 v[228:231], v96 offset:55328
	ds_read_b128 v[244:247], v178 offset:18464
	ds_read_b128 v[252:255], v178 offset:23072
	s_waitcnt lgkmcnt(5)
	v_mfma_f32_32x32x16_bf16 v[48:63], v[212:215], v[216:219], v[48:63]
	s_waitcnt lgkmcnt(4)
	v_mfma_f32_32x32x16_bf16 v[32:47], v[212:215], v[220:223], v[32:47]
	ds_read_b128 v[212:215], v96 offset:59936
	s_waitcnt lgkmcnt(4)
	v_mfma_f32_32x32x16_bf16 v[16:31], v[224:227], v[216:219], v[16:31]
	ds_read_b128 v[216:219], v96 offset:55360
	v_mfma_f32_32x32x16_bf16 v[0:15], v[224:227], v[220:223], v[0:15]
	ds_read_b128 v[224:227], v178 offset:18496
	ds_read_b128 v[220:223], v178 offset:23104
	s_waitcnt lgkmcnt(5)
	v_mfma_f32_32x32x16_bf16 v[48:63], v[228:231], v[244:247], v[48:63]
	s_waitcnt lgkmcnt(4)
	v_mfma_f32_32x32x16_bf16 v[32:47], v[228:231], v[252:255], v[32:47]
	ds_read_b128 v[228:231], v96 offset:59968
	s_waitcnt lgkmcnt(4)
	v_mfma_f32_32x32x16_bf16 v[16:31], v[212:215], v[244:247], v[16:31]
	ds_read_b128 v[244:247], v96 offset:55392
	v_mfma_f32_32x32x16_bf16 v[0:15], v[212:215], v[252:255], v[0:15]
	ds_read_b128 v[212:215], v178 offset:18528
	ds_read_b128 v[252:255], v178 offset:23136
	s_waitcnt lgkmcnt(5)
	v_mfma_f32_32x32x16_bf16 v[48:63], v[216:219], v[224:227], v[48:63]
	ds_write_b128 v177, v[64:67]
	global_load_dwordx4 v[64:67], v[152:153], off offset:512
	s_waitcnt lgkmcnt(5)
	v_mfma_f32_32x32x16_bf16 v[32:47], v[216:219], v[220:223], v[32:47]
	ds_read_b128 v[216:219], v96 offset:60000
	ds_write_b128 v177, v[68:71] offset:4608
	ds_write_b128 v177, v[72:75] offset:9216
	s_waitcnt lgkmcnt(7)
	v_mfma_f32_32x32x16_bf16 v[16:31], v[228:231], v[224:227], v[16:31]
	global_load_dwordx4 v[72:75], v[154:155], off offset:512
	ds_write_b128 v177, v[76:79] offset:13824
	v_mfma_f32_32x32x16_bf16 v[0:15], v[228:231], v[220:223], v[0:15]
	global_load_dwordx4 v[76:79], v[156:157], off offset:512
	ds_write_b128 v177, v[80:83] offset:36864
	s_waitcnt lgkmcnt(7)
	v_mfma_f32_32x32x16_bf16 v[48:63], v[244:247], v[212:215], v[48:63]
	global_load_dwordx4 v[80:83], v[158:159], off offset:512
	global_load_dwordx4 v[126:129], v[150:151], off offset:512
	s_waitcnt lgkmcnt(6)
	v_mfma_f32_32x32x16_bf16 v[32:47], v[244:247], v[252:255], v[32:47]
	ds_write_b128 v177, v[84:87] offset:41472
	global_load_dwordx4 v[134:137], v[160:161], off offset:512
	s_waitcnt lgkmcnt(5)
	v_mfma_f32_32x32x16_bf16 v[16:31], v[216:219], v[212:215], v[16:31]
	ds_write_b128 v177, v[88:91] offset:46080
	global_load_dwordx4 v[138:141], v[170:171], off offset:512
	v_mfma_f32_32x32x16_bf16 v[0:15], v[216:219], v[252:255], v[0:15]
	ds_write_b128 v177, v[92:95] offset:50688
	global_load_dwordx4 v[142:145], v[172:173], off offset:512
	s_setprio 0
	s_waitcnt lgkmcnt(0)
	s_barrier
	s_setprio 1
	ds_read_b128 v[212:215], v96 offset:36864
	ds_read_b128 v[216:219], v178
	ds_read_b128 v[220:223], v178 offset:4608
	ds_read_b128 v[224:227], v96 offset:41472
	ds_read_b128 v[228:231], v96 offset:36896
	ds_read_b128 v[244:247], v178 offset:32
	ds_read_b128 v[252:255], v178 offset:4640
	s_waitcnt lgkmcnt(5)
	v_mfma_f32_32x32x16_bf16 v[48:63], v[212:215], v[216:219], v[48:63]
	s_waitcnt lgkmcnt(4)
	v_mfma_f32_32x32x16_bf16 v[32:47], v[212:215], v[220:223], v[32:47]
	ds_read_b128 v[212:215], v96 offset:41504
	s_waitcnt lgkmcnt(4)
	v_mfma_f32_32x32x16_bf16 v[16:31], v[224:227], v[216:219], v[16:31]
	ds_read_b128 v[216:219], v96 offset:36928
	v_mfma_f32_32x32x16_bf16 v[0:15], v[224:227], v[220:223], v[0:15]
	ds_read_b128 v[224:227], v178 offset:64
	ds_read_b128 v[220:223], v178 offset:4672
	s_waitcnt lgkmcnt(5)
	v_mfma_f32_32x32x16_bf16 v[48:63], v[228:231], v[244:247], v[48:63]
	s_waitcnt lgkmcnt(4)
	v_mfma_f32_32x32x16_bf16 v[32:47], v[228:231], v[252:255], v[32:47]
	ds_read_b128 v[228:231], v96 offset:41536
	s_waitcnt lgkmcnt(4)
	v_mfma_f32_32x32x16_bf16 v[16:31], v[212:215], v[244:247], v[16:31]
	ds_read_b128 v[244:247], v96 offset:36960
	v_mfma_f32_32x32x16_bf16 v[0:15], v[212:215], v[252:255], v[0:15]
	ds_read_b128 v[212:215], v178 offset:96
	ds_read_b128 v[252:255], v178 offset:4704
	s_waitcnt lgkmcnt(5)
	v_mfma_f32_32x32x16_bf16 v[48:63], v[216:219], v[224:227], v[48:63]
	s_waitcnt vmcnt(15)
	ds_write_b128 v177, v[98:101] offset:18432
	global_load_dwordx4 v[68:71], v[152:153], off offset:640
	s_waitcnt lgkmcnt(5)
	v_mfma_f32_32x32x16_bf16 v[32:47], v[216:219], v[220:223], v[32:47]
	ds_read_b128 v[216:219], v96 offset:41568
	s_waitcnt vmcnt(15)
	ds_write_b128 v177, v[102:105] offset:23040
	global_load_dwordx4 v[84:87], v[154:155], off offset:640
	s_waitcnt lgkmcnt(6)
	v_mfma_f32_32x32x16_bf16 v[16:31], v[228:231], v[224:227], v[16:31]
	s_waitcnt vmcnt(15)
	ds_write_b128 v177, v[106:109] offset:27648
	global_load_dwordx4 v[88:91], v[156:157], off offset:640
	v_mfma_f32_32x32x16_bf16 v[0:15], v[228:231], v[220:223], v[0:15]
	s_waitcnt vmcnt(15)
	ds_write_b128 v177, v[110:113] offset:32256
	global_load_dwordx4 v[92:95], v[158:159], off offset:640
	s_waitcnt lgkmcnt(6)
	v_mfma_f32_32x32x16_bf16 v[48:63], v[244:247], v[212:215], v[48:63]
	s_waitcnt vmcnt(15)
	ds_write_b128 v177, v[114:117] offset:55296
	global_load_dwordx4 v[98:101], v[150:151], off offset:640
	s_waitcnt lgkmcnt(6)
	v_mfma_f32_32x32x16_bf16 v[32:47], v[244:247], v[252:255], v[32:47]
	s_waitcnt vmcnt(15)
	ds_write_b128 v177, v[118:121] offset:59904
	global_load_dwordx4 v[106:109], v[160:161], off offset:640
	s_waitcnt lgkmcnt(5)
	v_mfma_f32_32x32x16_bf16 v[16:31], v[216:219], v[212:215], v[16:31]
	s_waitcnt vmcnt(15)
	ds_write_b128 v177, v[122:125] offset:64512
	global_load_dwordx4 v[110:113], v[170:171], off offset:640
	v_mfma_f32_32x32x16_bf16 v[0:15], v[216:219], v[252:255], v[0:15]
	s_waitcnt vmcnt(15)
	ds_write_b128 v179, v[130:133] offset:13824
	global_load_dwordx4 v[114:117], v[172:173], off offset:640
	s_setprio 0
	s_waitcnt lgkmcnt(0)
	s_barrier
	s_setprio 1
	ds_read_b128 v[212:215], v96 offset:55296
	ds_read_b128 v[216:219], v178 offset:18432
	ds_read_b128 v[220:223], v178 offset:23040
	ds_read_b128 v[224:227], v96 offset:59904
	ds_read_b128 v[228:231], v96 offset:55328
	ds_read_b128 v[244:247], v178 offset:18464
	ds_read_b128 v[252:255], v178 offset:23072
	s_waitcnt lgkmcnt(5)
	v_mfma_f32_32x32x16_bf16 v[48:63], v[212:215], v[216:219], v[48:63]
	s_waitcnt lgkmcnt(4)
	v_mfma_f32_32x32x16_bf16 v[32:47], v[212:215], v[220:223], v[32:47]
	ds_read_b128 v[212:215], v96 offset:59936
	s_waitcnt lgkmcnt(4)
	v_mfma_f32_32x32x16_bf16 v[16:31], v[224:227], v[216:219], v[16:31]
	ds_read_b128 v[216:219], v96 offset:55360
	v_mfma_f32_32x32x16_bf16 v[0:15], v[224:227], v[220:223], v[0:15]
	ds_read_b128 v[224:227], v178 offset:18496
	ds_read_b128 v[220:223], v178 offset:23104
	s_waitcnt lgkmcnt(5)
	v_mfma_f32_32x32x16_bf16 v[48:63], v[228:231], v[244:247], v[48:63]
	s_waitcnt lgkmcnt(4)
	v_mfma_f32_32x32x16_bf16 v[32:47], v[228:231], v[252:255], v[32:47]
	ds_read_b128 v[228:231], v96 offset:59968
	s_waitcnt lgkmcnt(4)
	v_mfma_f32_32x32x16_bf16 v[16:31], v[212:215], v[244:247], v[16:31]
	ds_read_b128 v[244:247], v96 offset:55392
	v_mfma_f32_32x32x16_bf16 v[0:15], v[212:215], v[252:255], v[0:15]
	ds_read_b128 v[212:215], v178 offset:18528
	ds_read_b128 v[252:255], v178 offset:23136
	s_waitcnt lgkmcnt(5)
	v_mfma_f32_32x32x16_bf16 v[48:63], v[216:219], v[224:227], v[48:63]
	s_waitcnt vmcnt(15)
	ds_write_b128 v177, v[64:67]
	global_load_dwordx4 v[64:67], v[152:153], off offset:768
	s_waitcnt lgkmcnt(5)
	v_mfma_f32_32x32x16_bf16 v[32:47], v[216:219], v[220:223], v[32:47]
	ds_read_b128 v[216:219], v96 offset:60000
	s_waitcnt vmcnt(15)
	ds_write_b128 v177, v[72:75] offset:4608
	global_load_dwordx4 v[72:75], v[154:155], off offset:768
	s_waitcnt lgkmcnt(6)
	v_mfma_f32_32x32x16_bf16 v[16:31], v[228:231], v[224:227], v[16:31]
	s_waitcnt vmcnt(15)
	ds_write_b128 v177, v[76:79] offset:9216
	global_load_dwordx4 v[76:79], v[156:157], off offset:768
	v_mfma_f32_32x32x16_bf16 v[0:15], v[228:231], v[220:223], v[0:15]
	s_waitcnt vmcnt(15)
	ds_write_b128 v177, v[80:83] offset:13824
	global_load_dwordx4 v[80:83], v[158:159], off offset:768
	s_waitcnt lgkmcnt(6)
	v_mfma_f32_32x32x16_bf16 v[48:63], v[244:247], v[212:215], v[48:63]
	s_waitcnt vmcnt(15)
	ds_write_b128 v177, v[126:129] offset:36864
	global_load_dwordx4 v[102:105], v[150:151], off offset:768
	s_waitcnt lgkmcnt(6)
	v_mfma_f32_32x32x16_bf16 v[32:47], v[244:247], v[252:255], v[32:47]
	s_waitcnt vmcnt(15)
	ds_write_b128 v177, v[134:137] offset:41472
	global_load_dwordx4 v[118:121], v[160:161], off offset:768
	s_waitcnt lgkmcnt(5)
	v_mfma_f32_32x32x16_bf16 v[16:31], v[216:219], v[212:215], v[16:31]
	s_waitcnt vmcnt(15)
	ds_write_b128 v177, v[138:141] offset:46080
	global_load_dwordx4 v[122:125], v[170:171], off offset:768
	v_mfma_f32_32x32x16_bf16 v[0:15], v[216:219], v[252:255], v[0:15]
	s_waitcnt vmcnt(15)
	ds_write_b128 v177, v[142:145] offset:50688
	global_load_dwordx4 v[126:129], v[172:173], off offset:768
	s_setprio 0
	s_waitcnt lgkmcnt(0)
	s_barrier
	s_setprio 1
	ds_read_b128 v[212:215], v96 offset:36864
	ds_read_b128 v[216:219], v178
	ds_read_b128 v[220:223], v178 offset:4608
	ds_read_b128 v[224:227], v96 offset:41472
	ds_read_b128 v[228:231], v96 offset:36896
	ds_read_b128 v[244:247], v178 offset:32
	ds_read_b128 v[252:255], v178 offset:4640
	s_waitcnt lgkmcnt(5)
	v_mfma_f32_32x32x16_bf16 v[48:63], v[212:215], v[216:219], v[48:63]
	s_waitcnt lgkmcnt(4)
	v_mfma_f32_32x32x16_bf16 v[32:47], v[212:215], v[220:223], v[32:47]
	ds_read_b128 v[212:215], v96 offset:41504
	s_waitcnt lgkmcnt(4)
	v_mfma_f32_32x32x16_bf16 v[16:31], v[224:227], v[216:219], v[16:31]
	ds_read_b128 v[216:219], v96 offset:36928
	v_mfma_f32_32x32x16_bf16 v[0:15], v[224:227], v[220:223], v[0:15]
	ds_read_b128 v[224:227], v178 offset:64
	ds_read_b128 v[220:223], v178 offset:4672
	s_waitcnt lgkmcnt(5)
	v_mfma_f32_32x32x16_bf16 v[48:63], v[228:231], v[244:247], v[48:63]
	s_waitcnt lgkmcnt(4)
	v_mfma_f32_32x32x16_bf16 v[32:47], v[228:231], v[252:255], v[32:47]
	ds_read_b128 v[228:231], v96 offset:41536
	s_waitcnt lgkmcnt(4)
	v_mfma_f32_32x32x16_bf16 v[16:31], v[212:215], v[244:247], v[16:31]
	ds_read_b128 v[244:247], v96 offset:36960
	v_mfma_f32_32x32x16_bf16 v[0:15], v[212:215], v[252:255], v[0:15]
	ds_read_b128 v[212:215], v178 offset:96
	ds_read_b128 v[252:255], v178 offset:4704
	s_waitcnt lgkmcnt(5)
	v_mfma_f32_32x32x16_bf16 v[48:63], v[216:219], v[224:227], v[48:63]
	s_waitcnt vmcnt(15)
	ds_write_b128 v177, v[68:71] offset:18432
	global_load_dwordx4 v[68:71], v[152:153], off offset:896
	s_waitcnt lgkmcnt(5)
	v_mfma_f32_32x32x16_bf16 v[32:47], v[216:219], v[220:223], v[32:47]
	ds_read_b128 v[216:219], v96 offset:41568
	s_waitcnt vmcnt(15)
	ds_write_b128 v177, v[84:87] offset:23040
	global_load_dwordx4 v[84:87], v[154:155], off offset:896
	s_waitcnt lgkmcnt(6)
	v_mfma_f32_32x32x16_bf16 v[16:31], v[228:231], v[224:227], v[16:31]
	s_waitcnt vmcnt(15)
	ds_write_b128 v177, v[88:91] offset:27648
	global_load_dwordx4 v[88:91], v[156:157], off offset:896
	v_mfma_f32_32x32x16_bf16 v[0:15], v[228:231], v[220:223], v[0:15]
	s_waitcnt vmcnt(15)
	ds_write_b128 v177, v[92:95] offset:32256
	global_load_dwordx4 v[92:95], v[158:159], off offset:896
	s_waitcnt lgkmcnt(6)
	v_mfma_f32_32x32x16_bf16 v[48:63], v[244:247], v[212:215], v[48:63]
	s_waitcnt vmcnt(15)
	ds_write_b128 v177, v[98:101] offset:55296
	global_load_dwordx4 v[98:101], v[150:151], off offset:896
	s_waitcnt lgkmcnt(6)
	v_mfma_f32_32x32x16_bf16 v[32:47], v[244:247], v[252:255], v[32:47]
	s_waitcnt vmcnt(15)
	ds_write_b128 v177, v[106:109] offset:59904
	global_load_dwordx4 v[106:109], v[160:161], off offset:896
	s_waitcnt lgkmcnt(5)
	v_mfma_f32_32x32x16_bf16 v[16:31], v[216:219], v[212:215], v[16:31]
	s_waitcnt vmcnt(15)
	ds_write_b128 v177, v[110:113] offset:64512
	global_load_dwordx4 v[110:113], v[170:171], off offset:896
	v_mfma_f32_32x32x16_bf16 v[0:15], v[216:219], v[252:255], v[0:15]
	s_waitcnt vmcnt(15)
	ds_write_b128 v179, v[114:117] offset:13824
	global_load_dwordx4 v[114:117], v[172:173], off offset:896
	s_setprio 0
	s_waitcnt lgkmcnt(0)
	s_barrier
	s_setprio 1
	ds_read_b128 v[212:215], v96 offset:55296
	ds_read_b128 v[216:219], v178 offset:18432
	ds_read_b128 v[220:223], v178 offset:23040
	ds_read_b128 v[224:227], v96 offset:59904
	ds_read_b128 v[228:231], v96 offset:55328
	ds_read_b128 v[244:247], v178 offset:18464
	ds_read_b128 v[252:255], v178 offset:23072
	s_waitcnt lgkmcnt(5)
	v_mfma_f32_32x32x16_bf16 v[48:63], v[212:215], v[216:219], v[48:63]
	s_waitcnt lgkmcnt(4)
	v_mfma_f32_32x32x16_bf16 v[32:47], v[212:215], v[220:223], v[32:47]
	ds_read_b128 v[212:215], v96 offset:59936
	s_waitcnt lgkmcnt(4)
	v_mfma_f32_32x32x16_bf16 v[16:31], v[224:227], v[216:219], v[16:31]
	ds_read_b128 v[216:219], v96 offset:55360
	v_mfma_f32_32x32x16_bf16 v[0:15], v[224:227], v[220:223], v[0:15]
	ds_read_b128 v[224:227], v178 offset:18496
	ds_read_b128 v[220:223], v178 offset:23104
	s_waitcnt lgkmcnt(5)
	v_mfma_f32_32x32x16_bf16 v[48:63], v[228:231], v[244:247], v[48:63]
	s_waitcnt lgkmcnt(4)
	v_mfma_f32_32x32x16_bf16 v[32:47], v[228:231], v[252:255], v[32:47]
	ds_read_b128 v[228:231], v96 offset:59968
	s_waitcnt lgkmcnt(4)
	v_mfma_f32_32x32x16_bf16 v[16:31], v[212:215], v[244:247], v[16:31]
	ds_read_b128 v[244:247], v96 offset:55392
	v_mfma_f32_32x32x16_bf16 v[0:15], v[212:215], v[252:255], v[0:15]
	ds_read_b128 v[212:215], v178 offset:18528
	ds_read_b128 v[252:255], v178 offset:23136
	s_waitcnt lgkmcnt(5)
	v_mfma_f32_32x32x16_bf16 v[48:63], v[216:219], v[224:227], v[48:63]
	s_waitcnt vmcnt(15)
	ds_write_b128 v177, v[64:67]
	global_load_dwordx4 v[64:67], v[152:153], off offset:1024
	s_waitcnt lgkmcnt(5)
	v_mfma_f32_32x32x16_bf16 v[32:47], v[216:219], v[220:223], v[32:47]
	ds_read_b128 v[216:219], v96 offset:60000
	s_waitcnt vmcnt(15)
	ds_write_b128 v177, v[72:75] offset:4608
	global_load_dwordx4 v[72:75], v[154:155], off offset:1024
	s_waitcnt lgkmcnt(6)
	v_mfma_f32_32x32x16_bf16 v[16:31], v[228:231], v[224:227], v[16:31]
	s_waitcnt vmcnt(15)
	ds_write_b128 v177, v[76:79] offset:9216
	global_load_dwordx4 v[76:79], v[156:157], off offset:1024
	v_mfma_f32_32x32x16_bf16 v[0:15], v[228:231], v[220:223], v[0:15]
	s_waitcnt vmcnt(15)
	ds_write_b128 v177, v[80:83] offset:13824
	global_load_dwordx4 v[80:83], v[158:159], off offset:1024
	s_waitcnt lgkmcnt(6)
	v_mfma_f32_32x32x16_bf16 v[48:63], v[244:247], v[212:215], v[48:63]
	s_waitcnt vmcnt(15)
	ds_write_b128 v177, v[102:105] offset:36864
	global_load_dwordx4 v[102:105], v[150:151], off offset:1024
	s_waitcnt lgkmcnt(6)
	v_mfma_f32_32x32x16_bf16 v[32:47], v[244:247], v[252:255], v[32:47]
	s_waitcnt vmcnt(15)
	ds_write_b128 v177, v[118:121] offset:41472
	global_load_dwordx4 v[118:121], v[160:161], off offset:1024
	s_waitcnt lgkmcnt(5)
	v_mfma_f32_32x32x16_bf16 v[16:31], v[216:219], v[212:215], v[16:31]
	s_waitcnt vmcnt(15)
	ds_write_b128 v177, v[122:125] offset:46080
	global_load_dwordx4 v[122:125], v[170:171], off offset:1024
	v_mfma_f32_32x32x16_bf16 v[0:15], v[216:219], v[252:255], v[0:15]
	s_waitcnt vmcnt(15)
	ds_write_b128 v177, v[126:129] offset:50688
	global_load_dwordx4 v[126:129], v[172:173], off offset:1024
	s_setprio 0
	s_waitcnt lgkmcnt(0)
	s_barrier
	s_setprio 1
	ds_read_b128 v[212:215], v96 offset:36864
	ds_read_b128 v[216:219], v178
	ds_read_b128 v[220:223], v178 offset:4608
	ds_read_b128 v[224:227], v96 offset:41472
	ds_read_b128 v[228:231], v96 offset:36896
	ds_read_b128 v[244:247], v178 offset:32
	ds_read_b128 v[252:255], v178 offset:4640
	s_waitcnt lgkmcnt(5)
	v_mfma_f32_32x32x16_bf16 v[48:63], v[212:215], v[216:219], v[48:63]
	s_waitcnt lgkmcnt(4)
	v_mfma_f32_32x32x16_bf16 v[32:47], v[212:215], v[220:223], v[32:47]
	ds_read_b128 v[212:215], v96 offset:41504
	s_waitcnt lgkmcnt(4)
	v_mfma_f32_32x32x16_bf16 v[16:31], v[224:227], v[216:219], v[16:31]
	ds_read_b128 v[216:219], v96 offset:36928
	v_mfma_f32_32x32x16_bf16 v[0:15], v[224:227], v[220:223], v[0:15]
	ds_read_b128 v[224:227], v178 offset:64
	ds_read_b128 v[220:223], v178 offset:4672
	s_waitcnt lgkmcnt(5)
	v_mfma_f32_32x32x16_bf16 v[48:63], v[228:231], v[244:247], v[48:63]
	s_waitcnt lgkmcnt(4)
	v_mfma_f32_32x32x16_bf16 v[32:47], v[228:231], v[252:255], v[32:47]
	ds_read_b128 v[228:231], v96 offset:41536
	s_waitcnt lgkmcnt(4)
	v_mfma_f32_32x32x16_bf16 v[16:31], v[212:215], v[244:247], v[16:31]
	ds_read_b128 v[244:247], v96 offset:36960
	v_mfma_f32_32x32x16_bf16 v[0:15], v[212:215], v[252:255], v[0:15]
	ds_read_b128 v[212:215], v178 offset:96
	ds_read_b128 v[252:255], v178 offset:4704
	s_waitcnt lgkmcnt(5)
	v_mfma_f32_32x32x16_bf16 v[48:63], v[216:219], v[224:227], v[48:63]
	s_waitcnt vmcnt(15)
	ds_write_b128 v177, v[68:71] offset:18432
	global_load_dwordx4 v[68:71], v[152:153], off offset:1152
	s_waitcnt lgkmcnt(5)
	v_mfma_f32_32x32x16_bf16 v[32:47], v[216:219], v[220:223], v[32:47]
	ds_read_b128 v[216:219], v96 offset:41568
	s_waitcnt vmcnt(15)
	ds_write_b128 v177, v[84:87] offset:23040
	global_load_dwordx4 v[84:87], v[154:155], off offset:1152
	s_waitcnt lgkmcnt(6)
	v_mfma_f32_32x32x16_bf16 v[16:31], v[228:231], v[224:227], v[16:31]
	s_waitcnt vmcnt(15)
	ds_write_b128 v177, v[88:91] offset:27648
	global_load_dwordx4 v[88:91], v[156:157], off offset:1152
	v_mfma_f32_32x32x16_bf16 v[0:15], v[228:231], v[220:223], v[0:15]
	s_waitcnt vmcnt(15)
	ds_write_b128 v177, v[92:95] offset:32256
	global_load_dwordx4 v[92:95], v[158:159], off offset:1152
	s_waitcnt lgkmcnt(6)
	v_mfma_f32_32x32x16_bf16 v[48:63], v[244:247], v[212:215], v[48:63]
	s_waitcnt vmcnt(15)
	ds_write_b128 v177, v[98:101] offset:55296
	global_load_dwordx4 v[98:101], v[150:151], off offset:1152
	s_waitcnt lgkmcnt(6)
	v_mfma_f32_32x32x16_bf16 v[32:47], v[244:247], v[252:255], v[32:47]
	s_waitcnt vmcnt(15)
	ds_write_b128 v177, v[106:109] offset:59904
	global_load_dwordx4 v[106:109], v[160:161], off offset:1152
	s_waitcnt lgkmcnt(5)
	v_mfma_f32_32x32x16_bf16 v[16:31], v[216:219], v[212:215], v[16:31]
	s_waitcnt vmcnt(15)
	ds_write_b128 v177, v[110:113] offset:64512
	global_load_dwordx4 v[110:113], v[170:171], off offset:1152
	v_mfma_f32_32x32x16_bf16 v[0:15], v[216:219], v[252:255], v[0:15]
	s_waitcnt vmcnt(15)
	ds_write_b128 v179, v[114:117] offset:13824
	global_load_dwordx4 v[114:117], v[172:173], off offset:1152
	s_setprio 0
	s_waitcnt lgkmcnt(0)
	s_barrier
	s_setprio 1
	ds_read_b128 v[212:215], v96 offset:55296
	ds_read_b128 v[216:219], v178 offset:18432
	ds_read_b128 v[220:223], v178 offset:23040
	ds_read_b128 v[224:227], v96 offset:59904
	ds_read_b128 v[228:231], v96 offset:55328
	ds_read_b128 v[244:247], v178 offset:18464
	ds_read_b128 v[252:255], v178 offset:23072
	s_waitcnt lgkmcnt(5)
	v_mfma_f32_32x32x16_bf16 v[48:63], v[212:215], v[216:219], v[48:63]
	s_waitcnt lgkmcnt(4)
	v_mfma_f32_32x32x16_bf16 v[32:47], v[212:215], v[220:223], v[32:47]
	ds_read_b128 v[212:215], v96 offset:59936
	s_waitcnt lgkmcnt(4)
	v_mfma_f32_32x32x16_bf16 v[16:31], v[224:227], v[216:219], v[16:31]
	ds_read_b128 v[216:219], v96 offset:55360
	v_mfma_f32_32x32x16_bf16 v[0:15], v[224:227], v[220:223], v[0:15]
	ds_read_b128 v[224:227], v178 offset:18496
	ds_read_b128 v[220:223], v178 offset:23104
	s_waitcnt lgkmcnt(5)
	v_mfma_f32_32x32x16_bf16 v[48:63], v[228:231], v[244:247], v[48:63]
	s_waitcnt lgkmcnt(4)
	v_mfma_f32_32x32x16_bf16 v[32:47], v[228:231], v[252:255], v[32:47]
	ds_read_b128 v[228:231], v96 offset:59968
	s_waitcnt lgkmcnt(4)
	v_mfma_f32_32x32x16_bf16 v[16:31], v[212:215], v[244:247], v[16:31]
	ds_read_b128 v[244:247], v96 offset:55392
	v_mfma_f32_32x32x16_bf16 v[0:15], v[212:215], v[252:255], v[0:15]
	ds_read_b128 v[212:215], v178 offset:18528
	ds_read_b128 v[252:255], v178 offset:23136
	s_waitcnt lgkmcnt(5)
	v_mfma_f32_32x32x16_bf16 v[48:63], v[216:219], v[224:227], v[48:63]
	s_waitcnt vmcnt(15)
	ds_write_b128 v177, v[64:67]
	global_load_dwordx4 v[64:67], v[152:153], off offset:1280
	s_waitcnt lgkmcnt(5)
	v_mfma_f32_32x32x16_bf16 v[32:47], v[216:219], v[220:223], v[32:47]
	ds_read_b128 v[216:219], v96 offset:60000
	s_waitcnt vmcnt(15)
	ds_write_b128 v177, v[72:75] offset:4608
	global_load_dwordx4 v[72:75], v[154:155], off offset:1280
	s_waitcnt lgkmcnt(6)
	v_mfma_f32_32x32x16_bf16 v[16:31], v[228:231], v[224:227], v[16:31]
	s_waitcnt vmcnt(15)
	ds_write_b128 v177, v[76:79] offset:9216
	global_load_dwordx4 v[76:79], v[156:157], off offset:1280
	v_mfma_f32_32x32x16_bf16 v[0:15], v[228:231], v[220:223], v[0:15]
	s_waitcnt vmcnt(15)
	ds_write_b128 v177, v[80:83] offset:13824
	global_load_dwordx4 v[80:83], v[158:159], off offset:1280
	s_waitcnt lgkmcnt(6)
	v_mfma_f32_32x32x16_bf16 v[48:63], v[244:247], v[212:215], v[48:63]
	s_waitcnt vmcnt(15)
	ds_write_b128 v177, v[102:105] offset:36864
	global_load_dwordx4 v[102:105], v[150:151], off offset:1280
	s_waitcnt lgkmcnt(6)
	v_mfma_f32_32x32x16_bf16 v[32:47], v[244:247], v[252:255], v[32:47]
	s_waitcnt vmcnt(15)
	ds_write_b128 v177, v[118:121] offset:41472
	global_load_dwordx4 v[118:121], v[160:161], off offset:1280
	s_waitcnt lgkmcnt(5)
	v_mfma_f32_32x32x16_bf16 v[16:31], v[216:219], v[212:215], v[16:31]
	s_waitcnt vmcnt(15)
	ds_write_b128 v177, v[122:125] offset:46080
	global_load_dwordx4 v[122:125], v[170:171], off offset:1280
	v_mfma_f32_32x32x16_bf16 v[0:15], v[216:219], v[252:255], v[0:15]
	s_waitcnt vmcnt(15)
	ds_write_b128 v177, v[126:129] offset:50688
	global_load_dwordx4 v[126:129], v[172:173], off offset:1280
	s_setprio 0
	s_waitcnt lgkmcnt(0)
	s_barrier
	s_setprio 1
	ds_read_b128 v[212:215], v96 offset:36864
	ds_read_b128 v[216:219], v178
	ds_read_b128 v[220:223], v178 offset:4608
	ds_read_b128 v[224:227], v96 offset:41472
	ds_read_b128 v[228:231], v96 offset:36896
	ds_read_b128 v[244:247], v178 offset:32
	ds_read_b128 v[252:255], v178 offset:4640
	s_waitcnt lgkmcnt(5)
	v_mfma_f32_32x32x16_bf16 v[48:63], v[212:215], v[216:219], v[48:63]
	s_waitcnt lgkmcnt(4)
	v_mfma_f32_32x32x16_bf16 v[32:47], v[212:215], v[220:223], v[32:47]
	ds_read_b128 v[212:215], v96 offset:41504
	s_waitcnt lgkmcnt(4)
	v_mfma_f32_32x32x16_bf16 v[16:31], v[224:227], v[216:219], v[16:31]
	ds_read_b128 v[216:219], v96 offset:36928
	v_mfma_f32_32x32x16_bf16 v[0:15], v[224:227], v[220:223], v[0:15]
	ds_read_b128 v[224:227], v178 offset:64
	ds_read_b128 v[220:223], v178 offset:4672
	s_waitcnt lgkmcnt(5)
	v_mfma_f32_32x32x16_bf16 v[48:63], v[228:231], v[244:247], v[48:63]
	s_waitcnt lgkmcnt(4)
	v_mfma_f32_32x32x16_bf16 v[32:47], v[228:231], v[252:255], v[32:47]
	ds_read_b128 v[228:231], v96 offset:41536
	s_waitcnt lgkmcnt(4)
	v_mfma_f32_32x32x16_bf16 v[16:31], v[212:215], v[244:247], v[16:31]
	ds_read_b128 v[244:247], v96 offset:36960
	v_mfma_f32_32x32x16_bf16 v[0:15], v[212:215], v[252:255], v[0:15]
	ds_read_b128 v[212:215], v178 offset:96
	ds_read_b128 v[252:255], v178 offset:4704
	s_waitcnt lgkmcnt(5)
	v_mfma_f32_32x32x16_bf16 v[48:63], v[216:219], v[224:227], v[48:63]
	s_waitcnt vmcnt(15)
	ds_write_b128 v177, v[68:71] offset:18432
	global_load_dwordx4 v[68:71], v[152:153], off offset:1408
	s_waitcnt lgkmcnt(5)
	v_mfma_f32_32x32x16_bf16 v[32:47], v[216:219], v[220:223], v[32:47]
	ds_read_b128 v[216:219], v96 offset:41568
	s_waitcnt vmcnt(15)
	ds_write_b128 v177, v[84:87] offset:23040
	global_load_dwordx4 v[84:87], v[154:155], off offset:1408
	s_waitcnt lgkmcnt(6)
	v_mfma_f32_32x32x16_bf16 v[16:31], v[228:231], v[224:227], v[16:31]
	s_waitcnt vmcnt(15)
	ds_write_b128 v177, v[88:91] offset:27648
	global_load_dwordx4 v[88:91], v[156:157], off offset:1408
	v_mfma_f32_32x32x16_bf16 v[0:15], v[228:231], v[220:223], v[0:15]
	s_waitcnt vmcnt(15)
	ds_write_b128 v177, v[92:95] offset:32256
	global_load_dwordx4 v[92:95], v[158:159], off offset:1408
	s_waitcnt lgkmcnt(6)
	v_mfma_f32_32x32x16_bf16 v[48:63], v[244:247], v[212:215], v[48:63]
	s_waitcnt vmcnt(15)
	ds_write_b128 v177, v[98:101] offset:55296
	global_load_dwordx4 v[98:101], v[150:151], off offset:1408
	s_waitcnt lgkmcnt(6)
	v_mfma_f32_32x32x16_bf16 v[32:47], v[244:247], v[252:255], v[32:47]
	s_waitcnt vmcnt(15)
	ds_write_b128 v177, v[106:109] offset:59904
	global_load_dwordx4 v[106:109], v[160:161], off offset:1408
	s_waitcnt lgkmcnt(5)
	v_mfma_f32_32x32x16_bf16 v[16:31], v[216:219], v[212:215], v[16:31]
	s_waitcnt vmcnt(15)
	ds_write_b128 v177, v[110:113] offset:64512
	global_load_dwordx4 v[110:113], v[170:171], off offset:1408
	v_mfma_f32_32x32x16_bf16 v[0:15], v[216:219], v[252:255], v[0:15]
	s_waitcnt vmcnt(15)
	ds_write_b128 v179, v[114:117] offset:13824
	global_load_dwordx4 v[130:133], v[172:173], off offset:1408
	s_setprio 0
	s_waitcnt lgkmcnt(0)
	s_barrier
	s_setprio 1
	ds_read_b128 v[212:215], v96 offset:55296
	ds_read_b128 v[216:219], v178 offset:18432
	ds_read_b128 v[220:223], v178 offset:23040
	ds_read_b128 v[224:227], v96 offset:59904
	ds_read_b128 v[228:231], v96 offset:55328
	ds_read_b128 v[244:247], v178 offset:18464
	ds_read_b128 v[252:255], v178 offset:23072
	s_waitcnt lgkmcnt(5)
	v_mfma_f32_32x32x16_bf16 v[48:63], v[212:215], v[216:219], v[48:63]
	s_waitcnt lgkmcnt(4)
	v_mfma_f32_32x32x16_bf16 v[32:47], v[212:215], v[220:223], v[32:47]
	ds_read_b128 v[212:215], v96 offset:59936
	s_waitcnt lgkmcnt(4)
	v_mfma_f32_32x32x16_bf16 v[16:31], v[224:227], v[216:219], v[16:31]
	ds_read_b128 v[216:219], v96 offset:55360
	v_mfma_f32_32x32x16_bf16 v[0:15], v[224:227], v[220:223], v[0:15]
	ds_read_b128 v[224:227], v178 offset:18496
	ds_read_b128 v[220:223], v178 offset:23104
	s_waitcnt lgkmcnt(5)
	v_mfma_f32_32x32x16_bf16 v[48:63], v[228:231], v[244:247], v[48:63]
	s_waitcnt lgkmcnt(4)
	v_mfma_f32_32x32x16_bf16 v[32:47], v[228:231], v[252:255], v[32:47]
	ds_read_b128 v[228:231], v96 offset:59968
	s_waitcnt lgkmcnt(4)
	v_mfma_f32_32x32x16_bf16 v[16:31], v[212:215], v[244:247], v[16:31]
	ds_read_b128 v[244:247], v96 offset:55392
	v_mfma_f32_32x32x16_bf16 v[0:15], v[212:215], v[252:255], v[0:15]
	ds_read_b128 v[212:215], v178 offset:18528
	ds_read_b128 v[252:255], v178 offset:23136
	s_waitcnt lgkmcnt(5)
	v_mfma_f32_32x32x16_bf16 v[48:63], v[216:219], v[224:227], v[48:63]
	s_waitcnt vmcnt(15)
	ds_write_b128 v177, v[64:67]
	global_load_dwordx4 v[64:67], v[152:153], off offset:1536
	s_waitcnt lgkmcnt(5)
	v_mfma_f32_32x32x16_bf16 v[32:47], v[216:219], v[220:223], v[32:47]
	ds_read_b128 v[216:219], v96 offset:60000
	s_waitcnt vmcnt(15)
	ds_write_b128 v177, v[72:75] offset:4608
	global_load_dwordx4 v[72:75], v[154:155], off offset:1536
	s_waitcnt lgkmcnt(6)
	v_mfma_f32_32x32x16_bf16 v[16:31], v[228:231], v[224:227], v[16:31]
	s_waitcnt vmcnt(15)
	ds_write_b128 v177, v[76:79] offset:9216
	global_load_dwordx4 v[76:79], v[156:157], off offset:1536
	v_mfma_f32_32x32x16_bf16 v[0:15], v[228:231], v[220:223], v[0:15]
	s_waitcnt vmcnt(15)
	ds_write_b128 v177, v[80:83] offset:13824
	global_load_dwordx4 v[80:83], v[158:159], off offset:1536
	s_waitcnt lgkmcnt(6)
	v_mfma_f32_32x32x16_bf16 v[48:63], v[244:247], v[212:215], v[48:63]
	s_waitcnt vmcnt(15)
	ds_write_b128 v177, v[102:105] offset:36864
	global_load_dwordx4 v[114:117], v[150:151], off offset:1536
	s_waitcnt lgkmcnt(6)
	v_mfma_f32_32x32x16_bf16 v[32:47], v[244:247], v[252:255], v[32:47]
	s_waitcnt vmcnt(15)
	ds_write_b128 v177, v[118:121] offset:41472
	s_waitcnt vmcnt(14)
	ds_write_b128 v177, v[122:125] offset:46080
	s_waitcnt lgkmcnt(6)
	v_mfma_f32_32x32x16_bf16 v[16:31], v[216:219], v[212:215], v[16:31]
	global_load_dwordx4 v[122:125], v[160:161], off offset:1536
	s_waitcnt vmcnt(14)
	ds_write_b128 v177, v[126:129] offset:50688
	v_mfma_f32_32x32x16_bf16 v[0:15], v[216:219], v[252:255], v[0:15]
	global_load_dwordx4 v[126:129], v[170:171], off offset:1536
	global_load_dwordx4 v[134:137], v[172:173], off offset:1536
	s_setprio 0
	s_waitcnt lgkmcnt(0)
	s_barrier
	s_setprio 1
	ds_read_b128 v[212:215], v96 offset:36864
	ds_read_b128 v[216:219], v178
	ds_read_b128 v[220:223], v178 offset:4608
	ds_read_b128 v[224:227], v96 offset:41472
	ds_read_b128 v[228:231], v96 offset:36896
	ds_read_b128 v[244:247], v178 offset:32
	ds_read_b128 v[252:255], v178 offset:4640
	s_waitcnt lgkmcnt(5)
	v_mfma_f32_32x32x16_bf16 v[48:63], v[212:215], v[216:219], v[48:63]
	s_waitcnt lgkmcnt(4)
	v_mfma_f32_32x32x16_bf16 v[32:47], v[212:215], v[220:223], v[32:47]
	ds_read_b128 v[212:215], v96 offset:41504
	s_waitcnt lgkmcnt(4)
	v_mfma_f32_32x32x16_bf16 v[16:31], v[224:227], v[216:219], v[16:31]
	ds_read_b128 v[216:219], v96 offset:36928
	v_mfma_f32_32x32x16_bf16 v[0:15], v[224:227], v[220:223], v[0:15]
	ds_read_b128 v[224:227], v178 offset:64
	ds_read_b128 v[220:223], v178 offset:4672
	s_waitcnt lgkmcnt(5)
	v_mfma_f32_32x32x16_bf16 v[48:63], v[228:231], v[244:247], v[48:63]
	s_waitcnt lgkmcnt(4)
	v_mfma_f32_32x32x16_bf16 v[32:47], v[228:231], v[252:255], v[32:47]
	ds_read_b128 v[228:231], v96 offset:41536
	s_waitcnt lgkmcnt(4)
	v_mfma_f32_32x32x16_bf16 v[16:31], v[212:215], v[244:247], v[16:31]
	ds_read_b128 v[244:247], v96 offset:36960
	v_mfma_f32_32x32x16_bf16 v[0:15], v[212:215], v[252:255], v[0:15]
	ds_read_b128 v[212:215], v178 offset:96
	ds_read_b128 v[252:255], v178 offset:4704
	s_waitcnt lgkmcnt(5)
	v_mfma_f32_32x32x16_bf16 v[48:63], v[216:219], v[224:227], v[48:63]
	s_waitcnt vmcnt(15)
	ds_write_b128 v177, v[68:71] offset:18432
	s_waitcnt vmcnt(14)
	ds_write_b128 v177, v[84:87] offset:23040
	s_waitcnt lgkmcnt(6)
	v_mfma_f32_32x32x16_bf16 v[32:47], v[216:219], v[220:223], v[32:47]
	ds_read_b128 v[216:219], v96 offset:41568
	s_waitcnt vmcnt(13)
	ds_write_b128 v177, v[88:91] offset:27648
	s_waitcnt vmcnt(12)
	ds_write_b128 v177, v[92:95] offset:32256
	s_waitcnt lgkmcnt(8)
	v_mfma_f32_32x32x16_bf16 v[16:31], v[228:231], v[224:227], v[16:31]
	s_waitcnt vmcnt(11)
	ds_write_b128 v177, v[98:101] offset:55296
	v_mfma_f32_32x32x16_bf16 v[0:15], v[228:231], v[220:223], v[0:15]
	global_load_dwordx4 v[98:101], v[152:153], off offset:1664
	global_load_dwordx4 v[102:105], v[154:155], off offset:1664
	s_waitcnt vmcnt(12)
	ds_write_b128 v177, v[106:109] offset:59904
	s_waitcnt lgkmcnt(8)
	v_mfma_f32_32x32x16_bf16 v[48:63], v[244:247], v[212:215], v[48:63]
	global_load_dwordx4 v[106:109], v[156:157], off offset:1664
	s_waitcnt vmcnt(12)
	ds_write_b128 v177, v[110:113] offset:64512
	s_waitcnt lgkmcnt(8)
	v_mfma_f32_32x32x16_bf16 v[32:47], v[244:247], v[252:255], v[32:47]
	global_load_dwordx4 v[110:113], v[158:159], off offset:1664
	global_load_dwordx4 v[118:121], v[150:151], off offset:1664
	s_waitcnt lgkmcnt(5)
	v_mfma_f32_32x32x16_bf16 v[16:31], v[216:219], v[212:215], v[16:31]
	s_waitcnt vmcnt(13)
	ds_write_b128 v179, v[130:133] offset:13824
	global_load_dwordx4 v[130:133], v[160:161], off offset:1664
	v_mfma_f32_32x32x16_bf16 v[0:15], v[216:219], v[252:255], v[0:15]
	global_load_dwordx4 v[138:141], v[170:171], off offset:1664
	global_load_dwordx4 v[142:145], v[172:173], off offset:1664
	s_setprio 0
	s_waitcnt lgkmcnt(0)
	s_barrier
	s_setprio 1
	ds_read_b128 v[212:215], v96 offset:55296
	ds_read_b128 v[216:219], v178 offset:18432
	ds_read_b128 v[220:223], v178 offset:23040
	ds_read_b128 v[224:227], v96 offset:59904
	ds_read_b128 v[228:231], v96 offset:55328
	ds_read_b128 v[244:247], v178 offset:18464
	ds_read_b128 v[252:255], v178 offset:23072
	s_waitcnt lgkmcnt(5)
	v_mfma_f32_32x32x16_bf16 v[48:63], v[212:215], v[216:219], v[48:63]
	s_waitcnt lgkmcnt(4)
	v_mfma_f32_32x32x16_bf16 v[32:47], v[212:215], v[220:223], v[32:47]
	ds_read_b128 v[212:215], v96 offset:59936
	s_waitcnt lgkmcnt(4)
	v_mfma_f32_32x32x16_bf16 v[16:31], v[224:227], v[216:219], v[16:31]
	ds_read_b128 v[216:219], v96 offset:55360
	v_mfma_f32_32x32x16_bf16 v[0:15], v[224:227], v[220:223], v[0:15]
	ds_read_b128 v[224:227], v178 offset:18496
	ds_read_b128 v[220:223], v178 offset:23104
	s_waitcnt lgkmcnt(5)
	v_mfma_f32_32x32x16_bf16 v[48:63], v[228:231], v[244:247], v[48:63]
	s_waitcnt lgkmcnt(4)
	v_mfma_f32_32x32x16_bf16 v[32:47], v[228:231], v[252:255], v[32:47]
	ds_read_b128 v[228:231], v96 offset:59968
	s_waitcnt lgkmcnt(4)
	v_mfma_f32_32x32x16_bf16 v[16:31], v[212:215], v[244:247], v[16:31]
	ds_read_b128 v[244:247], v96 offset:55392
	v_mfma_f32_32x32x16_bf16 v[0:15], v[212:215], v[252:255], v[0:15]
	ds_read_b128 v[212:215], v178 offset:18528
	ds_read_b128 v[252:255], v178 offset:23136
	s_waitcnt lgkmcnt(5)
	v_mfma_f32_32x32x16_bf16 v[48:63], v[216:219], v[224:227], v[48:63]
	s_waitcnt vmcnt(15)
	ds_write_b128 v177, v[64:67]
	global_load_dwordx4 v[64:67], v[152:153], off offset:1792
	s_waitcnt lgkmcnt(5)
	v_mfma_f32_32x32x16_bf16 v[32:47], v[216:219], v[220:223], v[32:47]
	ds_read_b128 v[216:219], v96 offset:60000
	s_waitcnt vmcnt(15)
	ds_write_b128 v177, v[72:75] offset:4608
	global_load_dwordx4 v[68:71], v[154:155], off offset:1792
	s_waitcnt lgkmcnt(6)
	v_mfma_f32_32x32x16_bf16 v[16:31], v[228:231], v[224:227], v[16:31]
	s_waitcnt vmcnt(15)
	ds_write_b128 v177, v[76:79] offset:9216
	global_load_dwordx4 v[72:75], v[156:157], off offset:1792
	v_mfma_f32_32x32x16_bf16 v[0:15], v[228:231], v[220:223], v[0:15]
	s_waitcnt vmcnt(15)
	ds_write_b128 v177, v[80:83] offset:13824
	global_load_dwordx4 v[76:79], v[158:159], off offset:1792
	s_waitcnt lgkmcnt(6)
	v_mfma_f32_32x32x16_bf16 v[48:63], v[244:247], v[212:215], v[48:63]
	s_waitcnt vmcnt(15)
	ds_write_b128 v177, v[114:117] offset:36864
	global_load_dwordx4 v[80:83], v[150:151], off offset:1792
	s_waitcnt lgkmcnt(6)
	v_mfma_f32_32x32x16_bf16 v[32:47], v[244:247], v[252:255], v[32:47]
	s_waitcnt vmcnt(15)
	ds_write_b128 v177, v[122:125] offset:41472
	global_load_dwordx4 v[84:87], v[160:161], off offset:1792
	s_waitcnt lgkmcnt(5)
	v_mfma_f32_32x32x16_bf16 v[16:31], v[216:219], v[212:215], v[16:31]
	s_waitcnt vmcnt(15)
	ds_write_b128 v177, v[126:129] offset:46080
	global_load_dwordx4 v[88:91], v[170:171], off offset:1792
	v_mfma_f32_32x32x16_bf16 v[0:15], v[216:219], v[252:255], v[0:15]
	s_waitcnt vmcnt(15)
	ds_write_b128 v177, v[134:137] offset:50688
	global_load_dwordx4 v[92:95], v[172:173], off offset:1792
	s_setprio 0
	s_waitcnt lgkmcnt(0)
	s_barrier
	s_setprio 1
	ds_read_b128 v[212:215], v96 offset:36864
	ds_read_b128 v[216:219], v178
	ds_read_b128 v[220:223], v178 offset:4608
	ds_read_b128 v[224:227], v96 offset:41472
	ds_read_b128 v[228:231], v96 offset:36896
	ds_read_b128 v[244:247], v178 offset:32
	ds_read_b128 v[252:255], v178 offset:4640
	s_waitcnt lgkmcnt(5)
	v_mfma_f32_32x32x16_bf16 v[48:63], v[212:215], v[216:219], v[48:63]
	s_waitcnt lgkmcnt(4)
	v_mfma_f32_32x32x16_bf16 v[32:47], v[212:215], v[220:223], v[32:47]
	ds_read_b128 v[212:215], v96 offset:41504
	s_waitcnt lgkmcnt(4)
	v_mfma_f32_32x32x16_bf16 v[16:31], v[224:227], v[216:219], v[16:31]
	ds_read_b128 v[216:219], v96 offset:36928
	v_mfma_f32_32x32x16_bf16 v[0:15], v[224:227], v[220:223], v[0:15]
	ds_read_b128 v[224:227], v178 offset:64
	ds_read_b128 v[220:223], v178 offset:4672
	s_waitcnt lgkmcnt(5)
	v_mfma_f32_32x32x16_bf16 v[48:63], v[228:231], v[244:247], v[48:63]
	s_waitcnt lgkmcnt(4)
	v_mfma_f32_32x32x16_bf16 v[32:47], v[228:231], v[252:255], v[32:47]
	ds_read_b128 v[228:231], v96 offset:41536
	s_waitcnt lgkmcnt(4)
	v_mfma_f32_32x32x16_bf16 v[16:31], v[212:215], v[244:247], v[16:31]
	ds_read_b128 v[244:247], v96 offset:36960
	v_mfma_f32_32x32x16_bf16 v[0:15], v[212:215], v[252:255], v[0:15]
	ds_read_b128 v[212:215], v178 offset:96
	ds_read_b128 v[252:255], v178 offset:4704
	s_waitcnt lgkmcnt(5)
	v_mfma_f32_32x32x16_bf16 v[48:63], v[216:219], v[224:227], v[48:63]
	s_waitcnt vmcnt(15)
	ds_write_b128 v177, v[98:101] offset:18432
	s_waitcnt vmcnt(14)
	ds_write_b128 v177, v[102:105] offset:23040
	s_waitcnt lgkmcnt(6)
	v_mfma_f32_32x32x16_bf16 v[32:47], v[216:219], v[220:223], v[32:47]
	ds_read_b128 v[216:219], v96 offset:41568
	global_load_dwordx4 v[100:103], v[152:153], off offset:1920
	s_waitcnt vmcnt(14)
	ds_write_b128 v177, v[106:109] offset:27648
	s_waitcnt lgkmcnt(7)
	v_mfma_f32_32x32x16_bf16 v[16:31], v[228:231], v[224:227], v[16:31]
	global_load_dwordx4 v[104:107], v[154:155], off offset:1920
	s_waitcnt vmcnt(14)
	ds_write_b128 v177, v[110:113] offset:32256
	v_mfma_f32_32x32x16_bf16 v[0:15], v[228:231], v[220:223], v[0:15]
	global_load_dwordx4 v[108:111], v[156:157], off offset:1920
	global_load_dwordx4 v[112:115], v[158:159], off offset:1920
	s_waitcnt lgkmcnt(6)
	v_mfma_f32_32x32x16_bf16 v[48:63], v[244:247], v[212:215], v[48:63]
	s_waitcnt vmcnt(15)
	ds_write_b128 v177, v[118:121] offset:55296
	global_load_dwordx4 v[116:119], v[150:151], off offset:1920
	s_waitcnt lgkmcnt(6)
	v_mfma_f32_32x32x16_bf16 v[32:47], v[244:247], v[252:255], v[32:47]
	s_waitcnt vmcnt(15)
	ds_write_b128 v177, v[130:133] offset:59904
	global_load_dwordx4 v[120:123], v[160:161], off offset:1920
	s_waitcnt lgkmcnt(4)
	v_mfma_f32_32x32x16_bf16 v[16:31], v[216:219], v[212:215], v[16:31]
	s_waitcnt vmcnt(15)
	ds_write_b128 v177, v[138:141] offset:64512
	global_load_dwordx4 v[128:131], v[170:171], off offset:1920
	v_mfma_f32_32x32x16_bf16 v[0:15], v[216:219], v[252:255], v[0:15]
	s_waitcnt vmcnt(15)
	ds_write_b128 v179, v[142:145] offset:13824
	global_load_dwordx4 v[124:127], v[172:173], off offset:1920
	s_setprio 0
	s_waitcnt lgkmcnt(0)
	s_barrier
	s_setprio 1
	ds_read_b128 v[212:215], v96 offset:55296
	ds_read_b128 v[216:219], v178 offset:18432
	ds_read_b128 v[220:223], v178 offset:23040
	ds_read_b128 v[224:227], v96 offset:59904
	ds_read_b128 v[228:231], v96 offset:55328
	ds_read_b128 v[244:247], v178 offset:18464
	ds_read_b128 v[252:255], v178 offset:23072
	s_waitcnt lgkmcnt(5)
	v_mfma_f32_32x32x16_bf16 v[48:63], v[212:215], v[216:219], v[48:63]
	s_waitcnt lgkmcnt(4)
	v_mfma_f32_32x32x16_bf16 v[32:47], v[212:215], v[220:223], v[32:47]
	ds_read_b128 v[212:215], v96 offset:59936
	s_waitcnt lgkmcnt(4)
	v_mfma_f32_32x32x16_bf16 v[16:31], v[224:227], v[216:219], v[16:31]
	ds_read_b128 v[216:219], v96 offset:55360
	v_mfma_f32_32x32x16_bf16 v[0:15], v[224:227], v[220:223], v[0:15]
	ds_read_b128 v[224:227], v178 offset:18496
	ds_read_b128 v[220:223], v178 offset:23104
	s_waitcnt lgkmcnt(5)
	v_mfma_f32_32x32x16_bf16 v[48:63], v[228:231], v[244:247], v[48:63]
	s_waitcnt lgkmcnt(4)
	v_mfma_f32_32x32x16_bf16 v[32:47], v[228:231], v[252:255], v[32:47]
	ds_read_b128 v[228:231], v96 offset:59968
	s_waitcnt lgkmcnt(4)
	v_mfma_f32_32x32x16_bf16 v[16:31], v[212:215], v[244:247], v[16:31]
	ds_read_b128 v[244:247], v96 offset:55392
	v_mfma_f32_32x32x16_bf16 v[0:15], v[212:215], v[252:255], v[0:15]
	ds_read_b128 v[212:215], v178 offset:18528
	ds_read_b128 v[252:255], v178 offset:23136
	s_waitcnt lgkmcnt(5)
	v_mfma_f32_32x32x16_bf16 v[48:63], v[216:219], v[224:227], v[48:63]
	s_waitcnt lgkmcnt(4)
	v_mfma_f32_32x32x16_bf16 v[32:47], v[216:219], v[220:223], v[32:47]
	ds_read_b128 v[216:219], v96 offset:60000
	s_waitcnt lgkmcnt(4)
	v_mfma_f32_32x32x16_bf16 v[16:31], v[228:231], v[224:227], v[16:31]
	v_mfma_f32_32x32x16_bf16 v[0:15], v[228:231], v[220:223], v[0:15]
	s_waitcnt lgkmcnt(2)
	v_mfma_f32_32x32x16_bf16 v[48:63], v[244:247], v[212:215], v[48:63]
	s_waitcnt lgkmcnt(1)
	v_mfma_f32_32x32x16_bf16 v[32:47], v[244:247], v[252:255], v[32:47]
	s_waitcnt lgkmcnt(0)
	v_mfma_f32_32x32x16_bf16 v[16:31], v[216:219], v[212:215], v[16:31]
	v_mfma_f32_32x32x16_bf16 v[0:15], v[216:219], v[252:255], v[0:15]
	s_setprio 0
	v_cndmask_b32_e64 v98, 0, 1, s[12:13]
	v_cmp_ne_u32_e64 s[40:41], 1, v98
	s_andn2_b64 vcc, exec, s[12:13]
	s_waitcnt vmcnt(15)
	ds_write_b128 v177, v[64:67]
	s_waitcnt vmcnt(14)
	ds_write_b128 v177, v[68:71] offset:4608
	s_waitcnt vmcnt(13)
	ds_write_b128 v177, v[72:75] offset:9216
	s_waitcnt vmcnt(12)
	ds_write_b128 v177, v[76:79] offset:13824
	s_waitcnt vmcnt(11)
	ds_write_b128 v177, v[80:83] offset:36864
	s_waitcnt vmcnt(10)
	ds_write_b128 v177, v[84:87] offset:41472
	s_waitcnt vmcnt(9)
	ds_write_b128 v177, v[88:91] offset:46080
	s_waitcnt vmcnt(8)
	ds_write_b128 v177, v[92:95] offset:50688
	s_cbranch_vccnz .LBB0_474
	v_add_co_u32_e32 v68, vcc, 0x10000, v148
	global_load_dwordx4 v[64:67], v[148:149], off
	s_nop 0
	v_addc_co_u32_e32 v69, vcc, 0, v149, vcc
	v_add_co_u32_e32 v72, vcc, 0x20000, v148
	s_nop 1
	v_addc_co_u32_e32 v73, vcc, 0, v149, vcc
	v_add_co_u32_e32 v76, vcc, 0x30000, v148
	global_load_dwordx4 v[68:71], v[68:69], off
	global_load_dwordx4 v[72:75], v[72:73], off
	v_addc_co_u32_e32 v77, vcc, 0, v149, vcc
	v_add_co_u32_e32 v84, vcc, 0x10000, v146
	global_load_dwordx4 v[76:79], v[76:77], off
	s_nop 0
	global_load_dwordx4 v[80:83], v[146:147], off
	v_addc_co_u32_e32 v85, vcc, 0, v147, vcc
	v_add_co_u32_e32 v88, vcc, 0x20000, v146
	s_nop 1
	v_addc_co_u32_e32 v89, vcc, 0, v147, vcc
	v_add_co_u32_e32 v92, vcc, 0x30000, v146
	global_load_dwordx4 v[84:87], v[84:85], off
	s_nop 0
	global_load_dwordx4 v[88:91], v[88:89], off
	v_addc_co_u32_e32 v93, vcc, 0, v147, vcc
	global_load_dwordx4 v[92:95], v[92:93], off

.LBB0_580:
	v_add_u32_e32 v68, v67, v65
	ds_read_b128 v[72:75], v67 offset:18432
	ds_read_b128 v[76:79], v68
	s_add_i32 s0, s0, 32
	s_cmp_lt_u32 s0, 48
	s_waitcnt lgkmcnt(0)
	v_mfma_f32_32x32x16_bf16 v[48:63], v[76:79], v[72:75], v[48:63]
	ds_read_b128 v[72:75], v67 offset:23040
	s_waitcnt lgkmcnt(0)
	v_mfma_f32_32x32x16_bf16 v[16:31], v[76:79], v[72:75], v[16:31]
	ds_read_b128 v[72:75], v67 offset:27648
	s_waitcnt lgkmcnt(0)
	v_mfma_f32_32x32x16_bf16 v[32:47], v[76:79], v[72:75], v[32:47]
	ds_read_b128 v[72:75], v67 offset:32256
	ds_read_b128 v[80:83], v67 offset:18464
	s_waitcnt lgkmcnt(1)
	v_mfma_f32_32x32x16_bf16 v[0:15], v[76:79], v[72:75], v[0:15]
	ds_read_b128 v[72:75], v68 offset:32
	ds_read_b128 v[76:79], v67 offset:23072
	s_waitcnt lgkmcnt(0)
	v_mfma_f32_32x32x16_bf16 v[16:31], v[72:75], v[76:79], v[16:31]
	ds_read_b128 v[76:79], v67 offset:27680
	s_waitcnt lgkmcnt(0)
	v_mfma_f32_32x32x16_bf16 v[32:47], v[72:75], v[76:79], v[32:47]
	ds_read_b128 v[76:79], v67 offset:32288
	v_add_u32_e32 v67, 64, v67
	v_mfma_f32_32x32x16_bf16 v[48:63], v[72:75], v[80:83], v[48:63]
	s_waitcnt lgkmcnt(0)
	v_mfma_f32_32x32x16_bf16 v[0:15], v[72:75], v[76:79], v[0:15]
	s_cbranch_scc1 .LBB0_580
	s_lshl_b32 s0, s39, 9
	s_or_b32 s6, s0, s3
	v_or_b32_e32 v96, s6, v71
	v_readlane_b32 s8, v251, 20
	v_lshlrev_b32_e32 v67, 11, v64
	v_lshlrev_b64 v[64:65], 2, v[96:97]
	v_readlane_b32 s10, v251, 22
	v_readlane_b32 s11, v251, 23
	s_barrier
	s_nop 0
	v_lshl_add_u64 v[68:69], s[10:11], 0, v[64:65]
	v_readlane_b32 s100, v251, 16
	v_readlane_b32 s101, v251, 17
	s_nop 1
	v_lshl_add_u64 v[220:221], s[100:101], 0, v[64:65]
	v_readlane_b32 s100, v251, 20
	v_readlane_b32 s101, v251, 21
	s_nop 1
	v_lshl_add_u64 v[222:223], s[100:101], 0, v[64:65]
	global_load_dword v224, v[220:221], off
	global_load_dword v225, v[222:223], off
	global_load_dword v226, v[68:69], off offset:128
	global_load_dword v227, v[222:223], off offset:128
	global_load_dword v228, v[220:221], off offset:128
	global_load_dword v68, v[68:69], off
	s_mov_b32 s7, 0x3f2aaaab
	s_mov_b32 s39, 0x3f317218
	v_readlane_b32 s12, v251, 24
	v_readlane_b32 s13, v251, 25
	v_readlane_b32 s14, v251, 26
	v_readlane_b32 s15, v251, 27
	v_readlane_b32 s16, v251, 28
	v_readlane_b32 s17, v251, 29
	v_readlane_b32 s18, v251, 30
	v_readlane_b32 s19, v251, 31
	v_readlane_b32 s20, v251, 32
	v_readlane_b32 s21, v251, 33
	v_readlane_b32 s22, v251, 34
	v_readlane_b32 s23, v251, 35
	v_readlane_b32 s12, v251, 4
	v_readlane_b32 s24, v251, 16
	v_readlane_b32 s25, v251, 17
	v_readlane_b32 s9, v251, 21
	s_mov_b32 s40, 0x7f800000
	s_mov_b32 s41, 0x33800000
	v_readlane_b32 s15, v251, 7
	s_mov_b32 s15, 0x43000000
	v_readlane_b32 s16, v251, 8
	s_mov_b32 s16, 0x42b17217
	v_readlane_b32 s17, v251, 9
	s_mov_b32 s17, 0xf800000
	v_readlane_b32 s18, v251, 10
	s_mov_b32 s18, 0xc1880000
	v_add_u32_e32 v96, s6, v71
	s_cmp_eq_u32 s38, 0
	s_mov_b32 s4, 0
	v_readlane_b32 s13, v251, 5
	v_readlane_b32 s14, v251, 6
	v_readlane_b32 s19, v251, 11
	v_readlane_b32 s20, v251, 12
	v_readlane_b32 s21, v251, 13
	v_readlane_b32 s22, v251, 14
	v_readlane_b32 s23, v251, 15
	v_readlane_b32 s26, v251, 18
	v_readlane_b32 s27, v251, 19
	s_waitcnt vmcnt(0)
	v_mul_f32_e32 v68, 0xbfb8aa3b, v68
	v_exp_f32_e32 v70, v68
	s_nop 0
	v_add_f32_e32 v72, 1.0, v70
	v_add_f32_e32 v68, -1.0, v72
	v_sub_f32_e32 v69, v68, v72
	v_add_f32_e32 v69, 1.0, v69
	v_sub_f32_e32 v68, v70, v68
	v_add_f32_e32 v73, v68, v69
	v_frexp_mant_f32_e32 v68, v72
	v_cmp_gt_f32_e32 vcc, s7, v68
	v_cvt_f64_f32_e32 v[68:69], v72
	v_frexp_exp_i32_f64_e32 v68, v[68:69]
	v_subbrev_co_u32_e32 v78, vcc, 0, v68, vcc
	v_sub_u32_e32 v68, 0, v78
	v_ldexp_f32 v69, v72, v68
	v_add_f32_e32 v72, -1.0, v69
	v_add_f32_e32 v74, 1.0, v69
	v_ldexp_f32 v68, v73, v68
	v_add_f32_e32 v73, 1.0, v72
	v_add_f32_e32 v75, -1.0, v74
	v_sub_f32_e32 v73, v69, v73
	v_sub_f32_e32 v69, v69, v75
	v_add_f32_e32 v73, v68, v73
	v_add_f32_e32 v68, v68, v69
	v_add_f32_e32 v79, v74, v68
	v_rcp_f32_e32 v81, v79
	v_sub_f32_e32 v69, v79, v74
	v_sub_f32_e32 v80, v68, v69
	v_add_f32_e32 v69, v72, v73
	v_mul_f32_e32 v83, v69, v81
	v_sub_f32_e32 v68, v69, v72
	v_mul_f32_e32 v72, v79, v83
	v_fma_f32 v74, v83, v79, -v72
	v_fmac_f32_e32 v74, v83, v80
	v_sub_f32_e32 v82, v73, v68
	v_add_f32_e32 v68, v72, v74
	v_sub_f32_e32 v73, v69, v68
	v_pk_add_f32 v[76:77], v[68:69], v[72:73] neg_lo:[0,1] neg_hi:[0,1]
	v_mov_b32_e32 v75, v68
	v_pk_add_f32 v[68:69], v[76:77], v[74:75] neg_lo:[0,1] neg_hi:[0,1]
	v_cmp_neq_f32_e32 vcc, s40, v70
	v_add_f32_e32 v69, v82, v69
	v_add_f32_e32 v68, v68, v69
	v_add_f32_e32 v69, v73, v68
	v_mul_f32_e32 v82, v81, v69
	v_mul_f32_e32 v72, v79, v82
	v_fma_f32 v74, v82, v79, -v72
	v_fmac_f32_e32 v74, v82, v80
	v_sub_f32_e32 v73, v73, v69
	v_add_f32_e32 v79, v68, v73
	v_add_f32_e32 v68, v72, v74
	v_sub_f32_e32 v73, v69, v68
	v_pk_add_f32 v[76:77], v[68:69], v[72:73] neg_lo:[0,1] neg_hi:[0,1]
	v_mov_b32_e32 v75, v68
	v_pk_add_f32 v[68:69], v[76:77], v[74:75] neg_lo:[0,1] neg_hi:[0,1]
	v_add_f32_e32 v69, v79, v69
	v_add_f32_e32 v68, v68, v69
	v_add_f32_e32 v69, v83, v82
	v_add_f32_e32 v68, v73, v68
	v_sub_f32_e32 v72, v69, v83
	v_mul_f32_e32 v68, v81, v68
	v_sub_f32_e32 v72, v82, v72
	v_add_f32_e32 v72, v72, v68
	v_add_f32_e32 v74, v69, v72
	v_mul_f32_e32 v75, v74, v74
	v_fmamk_f32 v68, v75, 0x3e9b6dac, v191
	v_fmaak_f32 v169, v75, v68, 0x3f2aaada
	v_cvt_f32_i32_e32 v68, v78
	v_sub_f32_e32 v69, v74, v69
	v_sub_f32_e32 v69, v72, v69
	v_ldexp_f32 v76, v69, 1
	v_mul_f32_e32 v69, v74, v75
	v_ldexp_f32 v73, v74, 1
	v_pk_mul_f32 v[74:75], v[68:69], v[168:169]
	v_fma_f32 v72, v68, s39, -v74
	v_fmac_f32_e32 v72, 0xb102e308, v68
	v_pk_add_f32 v[68:69], v[74:75], v[72:73]
	v_sub_f32_e32 v73, v69, v73
	v_sub_f32_e32 v73, v75, v73
	v_add_f32_e32 v77, v76, v73
	v_mov_b32_e32 v76, v74
	v_pk_add_f32 v[74:75], v[68:69], v[74:75] neg_lo:[0,1] neg_hi:[0,1]
	v_pk_add_f32 v[78:79], v[68:69], v[76:77]
	v_mov_b32_e32 v73, v68
	v_mov_b32_e32 v75, v79
	v_pk_add_f32 v[80:81], v[72:73], v[74:75] neg_lo:[0,1] neg_hi:[0,1]
	v_pk_add_f32 v[72:73], v[72:73], v[74:75]
	v_mov_b32_e32 v76, v77
	v_pk_add_f32 v[74:75], v[72:73], v[68:69] op_sel:[1,0] op_sel_hi:[0,1] neg_lo:[0,1] neg_hi:[0,1]
	v_pk_add_f32 v[82:83], v[78:79], v[74:75] op_sel_hi:[1,0] neg_lo:[0,1] neg_hi:[0,1]
	v_mov_b32_e32 v78, v79
	v_mov_b32_e32 v79, v73
	v_pk_mov_b32 v[74:75], v[68:69], v[74:75] op_sel:[1,0]
	v_mov_b32_e32 v77, v68
	v_pk_add_f32 v[74:75], v[78:79], v[74:75] neg_lo:[0,1] neg_hi:[0,1]
	v_mov_b32_e32 v82, v80
	v_pk_add_f32 v[68:69], v[76:77], v[74:75] neg_lo:[0,1] neg_hi:[0,1]
	v_mov_b32_e32 v81, v73
	v_pk_add_f32 v[74:75], v[82:83], v[68:69]
	v_pk_add_f32 v[76:77], v[74:75], v[74:75] op_sel:[0,1] op_sel_hi:[1,0]
	v_pk_add_f32 v[72:73], v[72:73], v[76:77] op_sel:[1,0] op_sel_hi:[0,1]
	v_mov_b32_e32 v75, v72
	v_pk_add_f32 v[78:79], v[74:75], v[80:81] neg_lo:[0,1] neg_hi:[0,1]
	v_mov_b32_e32 v69, v76
	v_sub_f32_e32 v73, v74, v78
	v_pk_add_f32 v[68:69], v[68:69], v[78:79] neg_lo:[0,1] neg_hi:[0,1]
	v_sub_f32_e32 v73, v80, v73
	v_add_f32_e32 v68, v68, v73
	v_add_f32_e32 v68, v68, v69
	v_add_f32_e32 v68, v72, v68
	v_lshl_add_u64 v[72:73], s[24:25], 0, v[64:65]
	v_mov_b32_e32 v74, v224
	v_lshl_add_u64 v[64:65], s[8:9], 0, v[64:65]
	v_mov_b32_e32 v73, v225
	v_cndmask_b32_e32 v68, v199, v68, vcc
	v_cmp_ngt_f32_e32 vcc, -1.0, v70
	v_add_f32_e32 v48, v48, v74
	v_mul_f32_e32 v48, 0xbfb8aa3b, v48
	v_exp_f32_e32 v48, v48
	v_cndmask_b32_e32 v68, v200, v68, vcc
	v_cmp_neq_f32_e32 vcc, -1.0, v70
	v_add_f32_e32 v32, v32, v73
	v_add_f32_e32 v48, 1.0, v48
	v_rcp_f32_e32 v48, v48
	v_cndmask_b32_e32 v68, v201, v68, vcc
	v_cmp_lt_f32_e64 vcc, |v70|, s41
	v_mul_f32_e32 v32, 0xbfb8aa3b, v32
	v_exp_f32_e32 v32, v32
	v_cndmask_b32_e32 v68, v68, v70, vcc
	v_mul_f32_e32 v72, 0xc1000000, v68
	v_mul_f32_e32 v48, v48, v72
	v_mul_f32_e32 v64, 0x3fb8aa3b, v48
	v_add_f32_e32 v48, v48, v48
	v_exp_f32_e32 v68, v64
	v_mul_f32_e32 v64, 0x3fb8aa3b, v48
	v_rndne_f32_e32 v64, v64
	v_fmamk_f32 v65, v64, 0xbf317218, v48
	v_fmac_f32_e32 v65, 0x3102e308, v64
	v_fmamk_f32 v69, v65, 0x395133b1, v192
	v_cmp_eq_f32_e32 vcc, s15, v64
	v_cvt_i32_f32_e32 v64, v64
	v_fmaak_f32 v69, v65, v69, 0x3c0887f9
	v_fmaak_f32 v69, v65, v69, 0x3d2aaa81
	v_fmaak_f32 v69, v65, v69, 0x3e2aaaab
	v_fma_f32 v69, v65, v69, 0.5
	v_ldexp_f32 v64, 1.0, v64
	v_mul_f32_e32 v69, v65, v69
	v_cndmask_b32_e32 v64, v64, v202, vcc
	v_fmac_f32_e32 v65, v65, v69
	v_add_f32_e32 v69, -1.0, v64
	v_fmac_f32_e32 v69, v64, v65
	v_add_f32_e32 v64, v69, v69
	v_cndmask_b32_e32 v64, v69, v64, vcc
	v_cmp_nlt_f32_e32 vcc, s16, v48
	v_add_f32_e32 v32, 1.0, v32
	v_rcp_f32_e32 v32, v32
	v_cndmask_b32_e64 v64, v201, -v64, vcc
	v_cmp_gt_f32_e32 vcc, s17, v64
	v_mul_f32_e32 v65, 0x4f800000, v64
	v_add_f32_e32 v33, v33, v73
	v_cndmask_b32_e32 v64, v64, v65, vcc
	v_sqrt_f32_e32 v65, v64
	v_mul_f32_e32 v33, 0xbfb8aa3b, v33
	v_exp_f32_e32 v33, v33
	v_add_f32_e32 v34, v34, v73
	v_add_u32_e32 v69, -1, v65
	v_fma_f32 v70, -v69, v65, v64
	v_cmp_ge_f32_e64 s[0:1], 0, v70
	v_add_u32_e32 v70, 1, v65
	v_add_f32_e32 v33, 1.0, v33
	v_cndmask_b32_e64 v69, v65, v69, s[0:1]
	v_fma_f32 v65, -v70, v65, v64
	v_cmp_lt_f32_e64 s[0:1], 0, v65
	v_rcp_f32_e32 v33, v33
	v_mul_f32_e32 v34, 0xbfb8aa3b, v34
	v_cndmask_b32_e64 v65, v69, v70, s[0:1]
	v_mul_f32_e32 v69, 0x37800000, v65
	v_cndmask_b32_e32 v65, v65, v69, vcc
	v_cmp_class_f32_e32 vcc, v64, v193
	v_exp_f32_e32 v34, v34
	s_nop 0
	v_cndmask_b32_e32 v64, v65, v64, vcc
	v_cmp_ngt_f32_e32 vcc, s18, v48
	v_add_f32_e32 v34, 1.0, v34
	v_rcp_f32_e32 v34, v34
	v_cndmask_b32_e32 v48, 1.0, v64, vcc
	v_mul_f32_e32 v48, v32, v48
	v_and_b32_e32 v32, 0x100, v66
	v_or3_b32 v32, v67, v71, v32
	v_lshl_add_u32 v70, v32, 2, 0
	v_add_u32_e32 v32, 0x9000, v70
	ds_read2_b32 v[64:65], v32 offset1:32
	s_waitcnt lgkmcnt(0)
	v_mul_f32_e32 v48, v64, v48
	ds_write_b32 v70, v68
	ds_write_b32 v70, v48 offset:36864
	v_add_f32_e32 v48, v49, v74
	v_mul_f32_e32 v48, 0xbfb8aa3b, v48
	v_exp_f32_e32 v48, v48
	s_nop 0
	v_add_f32_e32 v48, 1.0, v48
	v_rcp_f32_e32 v48, v48
	s_nop 0
	v_mul_f32_e32 v48, v48, v72
	v_mul_f32_e32 v49, 0x3fb8aa3b, v48
	v_add_f32_e32 v48, v48, v48
	v_exp_f32_e32 v64, v49
	v_mul_f32_e32 v49, 0x3fb8aa3b, v48
	v_rndne_f32_e32 v49, v49
	v_fmamk_f32 v66, v49, 0xbf317218, v48
	v_fmac_f32_e32 v66, 0x3102e308, v49
	v_fmamk_f32 v67, v66, 0x395133b1, v192
	v_cmp_eq_f32_e32 vcc, s15, v49
	v_cvt_i32_f32_e32 v49, v49
	v_fmaak_f32 v67, v66, v67, 0x3c0887f9
	v_fmaak_f32 v67, v66, v67, 0x3d2aaa81
	v_fmaak_f32 v67, v66, v67, 0x3e2aaaab
	v_fma_f32 v67, v66, v67, 0.5
	v_ldexp_f32 v49, 1.0, v49
	v_mul_f32_e32 v67, v66, v67
	v_cndmask_b32_e32 v49, v49, v202, vcc
	v_fmac_f32_e32 v66, v66, v67
	v_add_f32_e32 v67, -1.0, v49
	v_fmac_f32_e32 v67, v49, v66
	v_add_f32_e32 v49, v67, v67
	v_cndmask_b32_e32 v49, v67, v49, vcc
	v_cmp_nlt_f32_e32 vcc, s16, v48
	s_nop 1
	v_cndmask_b32_e64 v49, v201, -v49, vcc
	v_cmp_gt_f32_e32 vcc, s17, v49
	v_mul_f32_e32 v66, 0x4f800000, v49
	s_nop 0
	v_cndmask_b32_e32 v49, v49, v66, vcc
	v_sqrt_f32_e32 v66, v49
	s_nop 0
	v_add_u32_e32 v67, -1, v66
	v_fma_f32 v68, -v67, v66, v49
	v_cmp_ge_f32_e64 s[0:1], 0, v68
	v_add_u32_e32 v68, 1, v66
	s_nop 0
	v_cndmask_b32_e64 v67, v66, v67, s[0:1]
	v_fma_f32 v66, -v68, v66, v49
	v_cmp_lt_f32_e64 s[0:1], 0, v66
	s_nop 1
	v_cndmask_b32_e64 v66, v67, v68, s[0:1]
	v_mul_f32_e32 v67, 0x37800000, v66
	v_cndmask_b32_e32 v66, v66, v67, vcc
	v_cmp_class_f32_e32 vcc, v49, v193
	s_nop 1
	v_cndmask_b32_e32 v49, v66, v49, vcc
	v_cmp_ngt_f32_e32 vcc, s18, v48
	s_nop 1
	v_cndmask_b32_e32 v48, 1.0, v49, vcc
	v_mul_f32_e32 v33, v33, v48
	ds_read2_b32 v[48:49], v32 offset0:64 offset1:96
	s_waitcnt lgkmcnt(0)
	v_mul_f32_e32 v33, v48, v33
	ds_write_b32 v70, v64 offset:256
	ds_write_b32 v70, v33 offset:37120
	v_add_f32_e32 v33, v50, v74
	v_mul_f32_e32 v33, 0xbfb8aa3b, v33
	v_exp_f32_e32 v33, v33
	s_nop 0
	v_add_f32_e32 v33, 1.0, v33
	v_rcp_f32_e32 v33, v33
	s_nop 0
	v_mul_f32_e32 v33, v33, v72
	v_mul_f32_e32 v48, 0x3fb8aa3b, v33
	v_add_f32_e32 v33, v33, v33
	v_mul_f32_e32 v50, 0x3fb8aa3b, v33
	v_rndne_f32_e32 v50, v50
	v_fmamk_f32 v64, v50, 0xbf317218, v33
	v_fmac_f32_e32 v64, 0x3102e308, v50
	v_fmamk_f32 v66, v64, 0x395133b1, v192
	v_cmp_eq_f32_e32 vcc, s15, v50
	v_cvt_i32_f32_e32 v50, v50
	v_fmaak_f32 v66, v64, v66, 0x3c0887f9
	v_fmaak_f32 v66, v64, v66, 0x3d2aaa81
	v_fmaak_f32 v66, v64, v66, 0x3e2aaaab
	v_fma_f32 v66, v64, v66, 0.5
	v_ldexp_f32 v50, 1.0, v50
	v_mul_f32_e32 v66, v64, v66
	v_cndmask_b32_e32 v50, v50, v202, vcc
	v_fmac_f32_e32 v64, v64, v66
	v_add_f32_e32 v66, -1.0, v50
	v_fmac_f32_e32 v66, v50, v64
	v_add_f32_e32 v50, v66, v66
	v_cndmask_b32_e32 v50, v66, v50, vcc
	v_cmp_nlt_f32_e32 vcc, s16, v33
	v_exp_f32_e32 v48, v48
	s_nop 0
	v_cndmask_b32_e64 v50, v201, -v50, vcc
	v_cmp_gt_f32_e32 vcc, s17, v50
	v_mul_f32_e32 v64, 0x4f800000, v50
	s_nop 0
	v_cndmask_b32_e32 v50, v50, v64, vcc
	v_sqrt_f32_e32 v64, v50
	s_nop 0
	v_add_u32_e32 v66, -1, v64
	v_fma_f32 v67, -v66, v64, v50
	v_cmp_ge_f32_e64 s[0:1], 0, v67
	v_add_u32_e32 v67, 1, v64
	s_nop 0
	v_cndmask_b32_e64 v66, v64, v66, s[0:1]
	v_fma_f32 v64, -v67, v64, v50
	v_cmp_lt_f32_e64 s[0:1], 0, v64
	s_nop 1
	v_cndmask_b32_e64 v64, v66, v67, s[0:1]
	v_mul_f32_e32 v66, 0x37800000, v64
	v_cndmask_b32_e32 v64, v64, v66, vcc
	ds_read2_b32 v[66:67], v32 offset0:128 offset1:160
	v_cmp_class_f32_e32 vcc, v50, v193
	s_nop 1
	v_cndmask_b32_e32 v50, v64, v50, vcc
	v_cmp_ngt_f32_e32 vcc, s18, v33
	s_nop 1
	v_cndmask_b32_e32 v33, 1.0, v50, vcc
	v_mul_f32_e32 v33, v34, v33
	s_waitcnt lgkmcnt(0)
	v_mul_f32_e32 v33, v66, v33
	ds_write_b32 v70, v48 offset:512
	ds_write_b32 v70, v33 offset:37376
	v_add_f32_e32 v33, v51, v74
	v_mul_f32_e32 v33, 0xbfb8aa3b, v33
	v_exp_f32_e32 v33, v33
	v_add_f32_e32 v34, v35, v73
	v_mul_f32_e32 v34, 0xbfb8aa3b, v34
	v_exp_f32_e32 v34, v34
	v_add_f32_e32 v33, 1.0, v33
	v_rcp_f32_e32 v33, v33
	v_add_f32_e32 v34, 1.0, v34
	v_rcp_f32_e32 v34, v34
	v_mul_f32_e32 v33, v33, v72
	v_mul_f32_e32 v35, 0x3fb8aa3b, v33
	v_add_f32_e32 v33, v33, v33
	v_mul_f32_e32 v48, 0x3fb8aa3b, v33
	v_rndne_f32_e32 v48, v48
	v_fmamk_f32 v50, v48, 0xbf317218, v33
	v_fmac_f32_e32 v50, 0x3102e308, v48
	v_fmamk_f32 v51, v50, 0x395133b1, v192
	v_cmp_eq_f32_e32 vcc, s15, v48
	v_cvt_i32_f32_e32 v48, v48
	v_fmaak_f32 v51, v50, v51, 0x3c0887f9
	v_fmaak_f32 v51, v50, v51, 0x3d2aaa81
	v_fmaak_f32 v51, v50, v51, 0x3e2aaaab
	v_fma_f32 v51, v50, v51, 0.5
	v_ldexp_f32 v48, 1.0, v48
	v_mul_f32_e32 v51, v50, v51
	v_cndmask_b32_e32 v48, v48, v202, vcc
	v_fmac_f32_e32 v50, v50, v51
	v_add_f32_e32 v51, -1.0, v48
	v_fmac_f32_e32 v51, v48, v50
	v_add_f32_e32 v48, v51, v51
	v_cndmask_b32_e32 v48, v51, v48, vcc
	v_cmp_nlt_f32_e32 vcc, s16, v33
	v_exp_f32_e32 v35, v35
	s_nop 0
	v_cndmask_b32_e64 v48, v201, -v48, vcc
	v_cmp_gt_f32_e32 vcc, s17, v48
	v_mul_f32_e32 v50, 0x4f800000, v48
	s_nop 0
	v_cndmask_b32_e32 v48, v48, v50, vcc
	v_sqrt_f32_e32 v50, v48
	s_nop 0
	v_add_u32_e32 v51, -1, v50
	v_fma_f32 v64, -v51, v50, v48
	v_cmp_ge_f32_e64 s[0:1], 0, v64
	v_add_u32_e32 v64, 1, v50
	s_nop 0
	v_cndmask_b32_e64 v51, v50, v51, s[0:1]
	v_fma_f32 v50, -v64, v50, v48
	v_cmp_lt_f32_e64 s[0:1], 0, v50
	s_nop 1
	v_cndmask_b32_e64 v50, v51, v64, s[0:1]
	v_mul_f32_e32 v51, 0x37800000, v50
	v_cndmask_b32_e32 v50, v50, v51, vcc
	v_cmp_class_f32_e32 vcc, v48, v193
	s_nop 1
	v_cndmask_b32_e32 v48, v50, v48, vcc
	ds_read2_b32 v[50:51], v32 offset0:192 offset1:224
	v_cmp_ngt_f32_e32 vcc, s18, v33
	s_nop 1
	v_cndmask_b32_e32 v33, 1.0, v48, vcc
	v_mul_f32_e32 v33, v34, v33
	s_waitcnt lgkmcnt(0)
	v_mul_f32_e32 v32, v50, v33
	ds_write_b32 v70, v35 offset:768
	ds_write_b32 v70, v32 offset:37632
	v_add_f32_e32 v32, v52, v74
	v_mul_f32_e32 v32, 0xbfb8aa3b, v32
	v_exp_f32_e32 v32, v32
	v_add_f32_e32 v33, v36, v73
	v_mul_f32_e32 v33, 0xbfb8aa3b, v33
	v_exp_f32_e32 v33, v33
	v_add_f32_e32 v32, 1.0, v32
	v_rcp_f32_e32 v32, v32
	v_add_f32_e32 v33, 1.0, v33
	v_rcp_f32_e32 v33, v33
	v_mul_f32_e32 v32, v32, v72
	v_mul_f32_e32 v34, 0x3fb8aa3b, v32
	v_add_f32_e32 v32, v32, v32
	v_mul_f32_e32 v35, 0x3fb8aa3b, v32
	v_rndne_f32_e32 v35, v35
	v_fmamk_f32 v36, v35, 0xbf317218, v32
	v_fmac_f32_e32 v36, 0x3102e308, v35
	v_fmamk_f32 v48, v36, 0x395133b1, v192
	v_cmp_eq_f32_e32 vcc, s15, v35
	v_cvt_i32_f32_e32 v35, v35
	v_fmaak_f32 v48, v36, v48, 0x3c0887f9
	v_fmaak_f32 v48, v36, v48, 0x3d2aaa81
	v_fmaak_f32 v48, v36, v48, 0x3e2aaaab
	v_fma_f32 v48, v36, v48, 0.5
	v_ldexp_f32 v35, 1.0, v35
	v_mul_f32_e32 v48, v36, v48
	v_cndmask_b32_e32 v35, v35, v202, vcc
	v_fmac_f32_e32 v36, v36, v48
	v_add_f32_e32 v48, -1.0, v35
	v_fmac_f32_e32 v48, v35, v36
	v_add_f32_e32 v35, v48, v48
	v_cndmask_b32_e32 v35, v48, v35, vcc
	v_cmp_nlt_f32_e32 vcc, s16, v32
	v_exp_f32_e32 v34, v34
	s_nop 0
	v_cndmask_b32_e64 v35, v201, -v35, vcc
	v_cmp_gt_f32_e32 vcc, s17, v35
	v_mul_f32_e32 v36, 0x4f800000, v35
	s_nop 0
	v_cndmask_b32_e32 v35, v35, v36, vcc
	v_sqrt_f32_e32 v36, v35
	s_nop 0
	v_add_u32_e32 v48, -1, v36
	v_fma_f32 v50, -v48, v36, v35
	v_cmp_ge_f32_e64 s[0:1], 0, v50
	v_add_u32_e32 v50, 1, v36
	s_nop 0
	v_cndmask_b32_e64 v48, v36, v48, s[0:1]
	v_fma_f32 v36, -v50, v36, v35
	v_cmp_lt_f32_e64 s[0:1], 0, v36
	s_nop 1
	v_cndmask_b32_e64 v36, v48, v50, s[0:1]
	v_mul_f32_e32 v48, 0x37800000, v36
	v_cndmask_b32_e32 v36, v36, v48, vcc
	v_cmp_class_f32_e32 vcc, v35, v193
	s_nop 1
	v_cndmask_b32_e32 v35, v36, v35, vcc
	v_cmp_ngt_f32_e32 vcc, s18, v32
	s_nop 1
	v_cndmask_b32_e32 v32, 1.0, v35, vcc
	v_mul_f32_e32 v33, v33, v32
	v_add_u32_e32 v32, 0x9800, v70
	ds_read2_b32 v[68:69], v32 offset1:32
	s_waitcnt lgkmcnt(0)
	v_mul_f32_e32 v33, v68, v33
	ds_write_b32 v70, v34 offset:2048
	ds_write_b32 v70, v33 offset:38912
	v_add_f32_e32 v33, v53, v74
	v_mul_f32_e32 v33, 0xbfb8aa3b, v33
	v_exp_f32_e32 v33, v33
	v_add_f32_e32 v34, v37, v73
	v_mul_f32_e32 v34, 0xbfb8aa3b, v34
	v_exp_f32_e32 v34, v34
	v_add_f32_e32 v33, 1.0, v33
	v_rcp_f32_e32 v33, v33
	v_add_f32_e32 v34, 1.0, v34
	v_rcp_f32_e32 v34, v34
	v_mul_f32_e32 v33, v33, v72
	v_mul_f32_e32 v35, 0x3fb8aa3b, v33
	v_add_f32_e32 v33, v33, v33
	v_mul_f32_e32 v36, 0x3fb8aa3b, v33
	v_rndne_f32_e32 v36, v36
	v_fmamk_f32 v37, v36, 0xbf317218, v33
	v_fmac_f32_e32 v37, 0x3102e308, v36
	v_fmamk_f32 v48, v37, 0x395133b1, v192
	v_cmp_eq_f32_e32 vcc, s15, v36
	v_cvt_i32_f32_e32 v36, v36
	v_fmaak_f32 v48, v37, v48, 0x3c0887f9
	v_fmaak_f32 v48, v37, v48, 0x3d2aaa81
	v_fmaak_f32 v48, v37, v48, 0x3e2aaaab
	v_fma_f32 v48, v37, v48, 0.5
	v_ldexp_f32 v36, 1.0, v36
	v_mul_f32_e32 v48, v37, v48
	v_cndmask_b32_e32 v36, v36, v202, vcc
	v_fmac_f32_e32 v37, v37, v48
	v_add_f32_e32 v48, -1.0, v36
	v_fmac_f32_e32 v48, v36, v37
	v_add_f32_e32 v36, v48, v48
	v_cndmask_b32_e32 v36, v48, v36, vcc
	v_cmp_nlt_f32_e32 vcc, s16, v33
	v_exp_f32_e32 v35, v35
	s_nop 0
	v_cndmask_b32_e64 v36, v201, -v36, vcc
	v_cmp_gt_f32_e32 vcc, s17, v36
	v_mul_f32_e32 v37, 0x4f800000, v36
	s_nop 0
	v_cndmask_b32_e32 v36, v36, v37, vcc
	v_sqrt_f32_e32 v37, v36
	s_nop 0
	v_add_u32_e32 v48, -1, v37
	v_fma_f32 v50, -v48, v37, v36
	v_cmp_ge_f32_e64 s[0:1], 0, v50
	v_add_u32_e32 v50, 1, v37
	s_nop 0
	v_cndmask_b32_e64 v48, v37, v48, s[0:1]
	v_fma_f32 v37, -v50, v37, v36
	v_cmp_lt_f32_e64 s[0:1], 0, v37
	s_nop 1
	v_cndmask_b32_e64 v37, v48, v50, s[0:1]
	v_mul_f32_e32 v48, 0x37800000, v37
	v_cndmask_b32_e32 v37, v37, v48, vcc
	v_cmp_class_f32_e32 vcc, v36, v193
	s_nop 1
	v_cndmask_b32_e32 v36, v37, v36, vcc
	v_cmp_ngt_f32_e32 vcc, s18, v33
	s_nop 1
	v_cndmask_b32_e32 v33, 1.0, v36, vcc
	ds_read2_b32 v[36:37], v32 offset0:64 offset1:96
	v_mul_f32_e32 v33, v34, v33
	v_add_f32_e32 v34, v38, v73
	v_mul_f32_e32 v34, 0xbfb8aa3b, v34
	v_exp_f32_e32 v34, v34
	s_waitcnt lgkmcnt(0)
	v_mul_f32_e32 v33, v36, v33
	ds_write_b32 v70, v35 offset:2304
	ds_write_b32 v70, v33 offset:39168
	v_add_f32_e32 v33, v54, v74
	v_mul_f32_e32 v33, 0xbfb8aa3b, v33
	v_exp_f32_e32 v33, v33
	v_add_f32_e32 v34, 1.0, v34
	v_rcp_f32_e32 v34, v34
	ds_read2_b32 v[52:53], v32 offset0:128 offset1:160
	v_add_f32_e32 v33, 1.0, v33
	v_rcp_f32_e32 v33, v33
	s_nop 0
	v_mul_f32_e32 v33, v33, v72
	v_mul_f32_e32 v35, 0x3fb8aa3b, v33
	v_add_f32_e32 v33, v33, v33
	v_mul_f32_e32 v36, 0x3fb8aa3b, v33
	v_rndne_f32_e32 v36, v36
	v_fmamk_f32 v38, v36, 0xbf317218, v33
	v_fmac_f32_e32 v38, 0x3102e308, v36
	v_fmamk_f32 v48, v38, 0x395133b1, v192
	v_cmp_eq_f32_e32 vcc, s15, v36
	v_cvt_i32_f32_e32 v36, v36
	v_fmaak_f32 v48, v38, v48, 0x3c0887f9
	v_fmaak_f32 v48, v38, v48, 0x3d2aaa81
	v_fmaak_f32 v48, v38, v48, 0x3e2aaaab
	v_fma_f32 v48, v38, v48, 0.5
	v_ldexp_f32 v36, 1.0, v36
	v_mul_f32_e32 v48, v38, v48
	v_cndmask_b32_e32 v36, v36, v202, vcc
	v_fmac_f32_e32 v38, v38, v48
	v_add_f32_e32 v48, -1.0, v36
	v_fmac_f32_e32 v48, v36, v38
	v_add_f32_e32 v36, v48, v48
	v_cndmask_b32_e32 v36, v48, v36, vcc
	v_cmp_nlt_f32_e32 vcc, s16, v33
	v_exp_f32_e32 v35, v35
	s_nop 0
	v_cndmask_b32_e64 v36, v201, -v36, vcc
	v_cmp_gt_f32_e32 vcc, s17, v36
	v_mul_f32_e32 v38, 0x4f800000, v36
	s_nop 0
	v_cndmask_b32_e32 v36, v36, v38, vcc
	v_sqrt_f32_e32 v38, v36
	s_nop 0
	v_add_u32_e32 v48, -1, v38
	v_fma_f32 v50, -v48, v38, v36
	v_cmp_ge_f32_e64 s[0:1], 0, v50
	v_add_u32_e32 v50, 1, v38
	s_nop 0
	v_cndmask_b32_e64 v48, v38, v48, s[0:1]
	v_fma_f32 v38, -v50, v38, v36
	v_cmp_lt_f32_e64 s[0:1], 0, v38
	s_nop 1
	v_cndmask_b32_e64 v38, v48, v50, s[0:1]
	v_mul_f32_e32 v48, 0x37800000, v38
	v_cndmask_b32_e32 v38, v38, v48, vcc
	v_cmp_class_f32_e32 vcc, v36, v193
	s_nop 1
	v_cndmask_b32_e32 v36, v38, v36, vcc
	v_cmp_ngt_f32_e32 vcc, s18, v33
	s_nop 1
	v_cndmask_b32_e32 v33, 1.0, v36, vcc
	v_mul_f32_e32 v33, v34, v33
	s_waitcnt lgkmcnt(0)
	v_mul_f32_e32 v33, v52, v33
	ds_write_b32 v70, v35 offset:2560
	ds_write_b32 v70, v33 offset:39424
	v_add_f32_e32 v33, v55, v74
	v_mul_f32_e32 v33, 0xbfb8aa3b, v33
	v_exp_f32_e32 v33, v33
	v_add_f32_e32 v34, v39, v73
	v_mul_f32_e32 v34, 0xbfb8aa3b, v34
	v_exp_f32_e32 v34, v34
	v_add_f32_e32 v33, 1.0, v33
	v_rcp_f32_e32 v33, v33
	v_add_f32_e32 v34, 1.0, v34
	v_rcp_f32_e32 v34, v34
	v_mul_f32_e32 v33, v33, v72
	v_mul_f32_e32 v35, 0x3fb8aa3b, v33
	v_add_f32_e32 v33, v33, v33
	v_mul_f32_e32 v36, 0x3fb8aa3b, v33
	v_rndne_f32_e32 v36, v36
	v_fmamk_f32 v38, v36, 0xbf317218, v33
	v_fmac_f32_e32 v38, 0x3102e308, v36
	v_fmamk_f32 v39, v38, 0x395133b1, v192
	v_cmp_eq_f32_e32 vcc, s15, v36
	v_cvt_i32_f32_e32 v36, v36
	v_fmaak_f32 v39, v38, v39, 0x3c0887f9
	v_fmaak_f32 v39, v38, v39, 0x3d2aaa81
	v_fmaak_f32 v39, v38, v39, 0x3e2aaaab
	v_fma_f32 v39, v38, v39, 0.5
	v_ldexp_f32 v36, 1.0, v36
	v_mul_f32_e32 v39, v38, v39
	v_cndmask_b32_e32 v36, v36, v202, vcc
	v_fmac_f32_e32 v38, v38, v39
	v_add_f32_e32 v39, -1.0, v36
	v_fmac_f32_e32 v39, v36, v38
	v_add_f32_e32 v36, v39, v39
	v_cndmask_b32_e32 v36, v39, v36, vcc
	v_cmp_nlt_f32_e32 vcc, s16, v33
	v_exp_f32_e32 v35, v35
	s_nop 0
	v_cndmask_b32_e64 v36, v201, -v36, vcc
	v_cmp_gt_f32_e32 vcc, s17, v36
	v_mul_f32_e32 v38, 0x4f800000, v36
	s_nop 0
	v_cndmask_b32_e32 v36, v36, v38, vcc
	v_sqrt_f32_e32 v38, v36
	s_nop 0
	v_add_u32_e32 v39, -1, v38
	v_fma_f32 v48, -v39, v38, v36
	v_cmp_ge_f32_e64 s[0:1], 0, v48
	v_add_u32_e32 v48, 1, v38
	s_nop 0
	v_cndmask_b32_e64 v39, v38, v39, s[0:1]
	v_fma_f32 v38, -v48, v38, v36
	v_cmp_lt_f32_e64 s[0:1], 0, v38
	s_nop 1
	v_cndmask_b32_e64 v38, v39, v48, s[0:1]
	v_mul_f32_e32 v39, 0x37800000, v38
	v_cndmask_b32_e32 v38, v38, v39, vcc
	v_cmp_class_f32_e32 vcc, v36, v193
	s_nop 1
	v_cndmask_b32_e32 v36, v38, v36, vcc
	ds_read2_b32 v[38:39], v32 offset0:192 offset1:224
	v_cmp_ngt_f32_e32 vcc, s18, v33
	s_nop 1
	v_cndmask_b32_e32 v33, 1.0, v36, vcc
	v_mul_f32_e32 v33, v34, v33
	s_waitcnt lgkmcnt(0)
	v_mul_f32_e32 v32, v38, v33
	ds_write_b32 v70, v35 offset:2816
	ds_write_b32 v70, v32 offset:39680
	v_add_f32_e32 v32, v56, v74
	v_mul_f32_e32 v32, 0xbfb8aa3b, v32
	v_exp_f32_e32 v32, v32
	v_add_f32_e32 v33, v40, v73
	v_mul_f32_e32 v33, 0xbfb8aa3b, v33
	v_exp_f32_e32 v33, v33
	v_add_f32_e32 v32, 1.0, v32
	v_rcp_f32_e32 v32, v32
	v_add_f32_e32 v33, 1.0, v33
	v_rcp_f32_e32 v33, v33
	v_mul_f32_e32 v32, v32, v72
	v_mul_f32_e32 v34, 0x3fb8aa3b, v32
	v_add_f32_e32 v32, v32, v32
	v_mul_f32_e32 v35, 0x3fb8aa3b, v32
	v_rndne_f32_e32 v35, v35
	v_fmamk_f32 v36, v35, 0xbf317218, v32
	v_fmac_f32_e32 v36, 0x3102e308, v35
	v_fmamk_f32 v38, v36, 0x395133b1, v192
	v_cmp_eq_f32_e32 vcc, s15, v35
	v_cvt_i32_f32_e32 v35, v35
	v_fmaak_f32 v38, v36, v38, 0x3c0887f9
	v_fmaak_f32 v38, v36, v38, 0x3d2aaa81
	v_fmaak_f32 v38, v36, v38, 0x3e2aaaab
	v_fma_f32 v38, v36, v38, 0.5
	v_ldexp_f32 v35, 1.0, v35
	v_mul_f32_e32 v38, v36, v38
	v_cndmask_b32_e32 v35, v35, v202, vcc
	v_fmac_f32_e32 v36, v36, v38
	v_add_f32_e32 v38, -1.0, v35
	v_fmac_f32_e32 v38, v35, v36
	v_add_f32_e32 v35, v38, v38
	v_cndmask_b32_e32 v35, v38, v35, vcc
	v_cmp_nlt_f32_e32 vcc, s16, v32
	v_exp_f32_e32 v34, v34
	s_nop 0
	v_cndmask_b32_e64 v35, v201, -v35, vcc
	v_cmp_gt_f32_e32 vcc, s17, v35
	v_mul_f32_e32 v36, 0x4f800000, v35
	s_nop 0
	v_cndmask_b32_e32 v35, v35, v36, vcc
	v_sqrt_f32_e32 v36, v35
	s_nop 0
	v_add_u32_e32 v38, -1, v36
	v_fma_f32 v40, -v38, v36, v35
	v_cmp_ge_f32_e64 s[0:1], 0, v40
	v_add_u32_e32 v40, 1, v36
	s_nop 0
	v_cndmask_b32_e64 v38, v36, v38, s[0:1]
	v_fma_f32 v36, -v40, v36, v35
	v_cmp_lt_f32_e64 s[0:1], 0, v36
	s_nop 1
	v_cndmask_b32_e64 v36, v38, v40, s[0:1]
	v_mul_f32_e32 v38, 0x37800000, v36
	v_cndmask_b32_e32 v36, v36, v38, vcc
	v_cmp_class_f32_e32 vcc, v35, v193
	s_nop 1
	v_cndmask_b32_e32 v35, v36, v35, vcc
	v_cmp_ngt_f32_e32 vcc, s18, v32
	s_nop 1
	v_cndmask_b32_e32 v32, 1.0, v35, vcc
	v_mul_f32_e32 v33, v33, v32
	v_add_u32_e32 v32, 0xa000, v70
	ds_read2_b32 v[54:55], v32 offset1:32
	s_waitcnt lgkmcnt(0)
	v_mul_f32_e32 v33, v54, v33
	ds_write_b32 v70, v34 offset:4096
	ds_write_b32 v70, v33 offset:40960
	v_add_f32_e32 v33, v57, v74
	v_mul_f32_e32 v33, 0xbfb8aa3b, v33
	v_exp_f32_e32 v33, v33
	v_add_f32_e32 v34, v41, v73
	v_mul_f32_e32 v34, 0xbfb8aa3b, v34
	v_exp_f32_e32 v34, v34
	v_add_f32_e32 v33, 1.0, v33
	v_rcp_f32_e32 v33, v33
	v_add_f32_e32 v34, 1.0, v34
	v_rcp_f32_e32 v34, v34
	v_mul_f32_e32 v33, v33, v72
	v_mul_f32_e32 v35, 0x3fb8aa3b, v33
	v_add_f32_e32 v33, v33, v33
	v_mul_f32_e32 v36, 0x3fb8aa3b, v33
	v_rndne_f32_e32 v36, v36
	v_fmamk_f32 v38, v36, 0xbf317218, v33
	v_fmac_f32_e32 v38, 0x3102e308, v36
	v_fmamk_f32 v40, v38, 0x395133b1, v192
	v_cmp_eq_f32_e32 vcc, s15, v36
	v_cvt_i32_f32_e32 v36, v36
	v_fmaak_f32 v40, v38, v40, 0x3c0887f9
	v_fmaak_f32 v40, v38, v40, 0x3d2aaa81
	v_fmaak_f32 v40, v38, v40, 0x3e2aaaab
	v_fma_f32 v40, v38, v40, 0.5
	v_ldexp_f32 v36, 1.0, v36
	v_mul_f32_e32 v40, v38, v40
	v_cndmask_b32_e32 v36, v36, v202, vcc
	v_fmac_f32_e32 v38, v38, v40
	v_add_f32_e32 v40, -1.0, v36
	v_fmac_f32_e32 v40, v36, v38
	v_add_f32_e32 v36, v40, v40
	v_cndmask_b32_e32 v36, v40, v36, vcc
	v_cmp_nlt_f32_e32 vcc, s16, v33
	v_exp_f32_e32 v35, v35
	s_nop 0
	v_cndmask_b32_e64 v36, v201, -v36, vcc
	v_cmp_gt_f32_e32 vcc, s17, v36
	v_mul_f32_e32 v38, 0x4f800000, v36
	s_nop 0
	v_cndmask_b32_e32 v36, v36, v38, vcc
	v_sqrt_f32_e32 v38, v36
	s_nop 0
	v_add_u32_e32 v40, -1, v38
	v_fma_f32 v41, -v40, v38, v36
	v_cmp_ge_f32_e64 s[0:1], 0, v41
	v_add_u32_e32 v41, 1, v38
	s_nop 0
	v_cndmask_b32_e64 v40, v38, v40, s[0:1]
	v_fma_f32 v38, -v41, v38, v36
	v_cmp_lt_f32_e64 s[0:1], 0, v38
	s_nop 1
	v_cndmask_b32_e64 v38, v40, v41, s[0:1]
	v_mul_f32_e32 v40, 0x37800000, v38
	v_cndmask_b32_e32 v38, v38, v40, vcc
	ds_read2_b32 v[40:41], v32 offset0:64 offset1:96
	v_cmp_class_f32_e32 vcc, v36, v193
	s_nop 1
	v_cndmask_b32_e32 v36, v38, v36, vcc
	v_cmp_ngt_f32_e32 vcc, s18, v33
	s_nop 1
	v_cndmask_b32_e32 v33, 1.0, v36, vcc
	v_mul_f32_e32 v33, v34, v33
	s_waitcnt lgkmcnt(0)
	v_mul_f32_e32 v33, v40, v33
	ds_write_b32 v70, v35 offset:4352
	ds_write_b32 v70, v33 offset:41216
	v_add_f32_e32 v33, v58, v74
	v_mul_f32_e32 v33, 0xbfb8aa3b, v33
	v_exp_f32_e32 v33, v33
	v_add_f32_e32 v34, v42, v73
	v_mul_f32_e32 v34, 0xbfb8aa3b, v34
	v_exp_f32_e32 v34, v34
	v_add_f32_e32 v33, 1.0, v33
	v_rcp_f32_e32 v33, v33
	ds_read2_b32 v[56:57], v32 offset0:128 offset1:160
	v_add_f32_e32 v34, 1.0, v34
	v_rcp_f32_e32 v34, v34
	v_mul_f32_e32 v33, v33, v72
	v_mul_f32_e32 v35, 0x3fb8aa3b, v33
	v_add_f32_e32 v33, v33, v33
	v_mul_f32_e32 v36, 0x3fb8aa3b, v33
	v_rndne_f32_e32 v36, v36
	v_fmamk_f32 v38, v36, 0xbf317218, v33
	v_fmac_f32_e32 v38, 0x3102e308, v36
	v_fmamk_f32 v40, v38, 0x395133b1, v192
	v_cmp_eq_f32_e32 vcc, s15, v36
	v_cvt_i32_f32_e32 v36, v36
	v_fmaak_f32 v40, v38, v40, 0x3c0887f9
	v_fmaak_f32 v40, v38, v40, 0x3d2aaa81
	v_fmaak_f32 v40, v38, v40, 0x3e2aaaab
	v_fma_f32 v40, v38, v40, 0.5
	v_ldexp_f32 v36, 1.0, v36
	v_mul_f32_e32 v40, v38, v40
	v_cndmask_b32_e32 v36, v36, v202, vcc
	v_fmac_f32_e32 v38, v38, v40
	v_add_f32_e32 v40, -1.0, v36
	v_fmac_f32_e32 v40, v36, v38
	v_add_f32_e32 v36, v40, v40
	v_cndmask_b32_e32 v36, v40, v36, vcc
	v_cmp_nlt_f32_e32 vcc, s16, v33
	v_exp_f32_e32 v35, v35
	s_nop 0
	v_cndmask_b32_e64 v36, v201, -v36, vcc
	v_cmp_gt_f32_e32 vcc, s17, v36
	v_mul_f32_e32 v38, 0x4f800000, v36
	s_nop 0
	v_cndmask_b32_e32 v36, v36, v38, vcc
	v_sqrt_f32_e32 v38, v36
	s_nop 0
	v_add_u32_e32 v40, -1, v38
	v_fma_f32 v42, -v40, v38, v36
	v_cmp_ge_f32_e64 s[0:1], 0, v42
	v_add_u32_e32 v42, 1, v38
	s_nop 0
	v_cndmask_b32_e64 v40, v38, v40, s[0:1]
	v_fma_f32 v38, -v42, v38, v36
	v_cmp_lt_f32_e64 s[0:1], 0, v38
	s_nop 1
	v_cndmask_b32_e64 v38, v40, v42, s[0:1]
	v_mul_f32_e32 v40, 0x37800000, v38
	v_cndmask_b32_e32 v38, v38, v40, vcc
	v_cmp_class_f32_e32 vcc, v36, v193
	s_nop 1
	v_cndmask_b32_e32 v36, v38, v36, vcc
	v_cmp_ngt_f32_e32 vcc, s18, v33
	s_nop 1
	v_cndmask_b32_e32 v33, 1.0, v36, vcc
	v_mul_f32_e32 v33, v34, v33
	s_waitcnt lgkmcnt(0)
	v_mul_f32_e32 v33, v56, v33
	ds_write_b32 v70, v35 offset:4608
	ds_write_b32 v70, v33 offset:41472
	v_add_f32_e32 v33, v59, v74
	v_mul_f32_e32 v33, 0xbfb8aa3b, v33
	v_exp_f32_e32 v33, v33
	v_add_f32_e32 v34, v43, v73
	v_mul_f32_e32 v34, 0xbfb8aa3b, v34
	v_exp_f32_e32 v34, v34
	v_add_f32_e32 v33, 1.0, v33
	v_rcp_f32_e32 v33, v33
	v_add_f32_e32 v34, 1.0, v34
	v_rcp_f32_e32 v34, v34
	v_mul_f32_e32 v33, v33, v72
	v_mul_f32_e32 v35, 0x3fb8aa3b, v33
	v_add_f32_e32 v33, v33, v33
	v_mul_f32_e32 v36, 0x3fb8aa3b, v33
	v_rndne_f32_e32 v36, v36
	v_fmamk_f32 v38, v36, 0xbf317218, v33
	v_fmac_f32_e32 v38, 0x3102e308, v36
	v_fmamk_f32 v40, v38, 0x395133b1, v192
	v_cmp_eq_f32_e32 vcc, s15, v36
	v_cvt_i32_f32_e32 v36, v36
	v_fmaak_f32 v40, v38, v40, 0x3c0887f9
	v_fmaak_f32 v40, v38, v40, 0x3d2aaa81
	v_fmaak_f32 v40, v38, v40, 0x3e2aaaab
	v_fma_f32 v40, v38, v40, 0.5
	v_ldexp_f32 v36, 1.0, v36
	v_mul_f32_e32 v40, v38, v40
	v_cndmask_b32_e32 v36, v36, v202, vcc
	v_fmac_f32_e32 v38, v38, v40
	v_add_f32_e32 v40, -1.0, v36
	v_fmac_f32_e32 v40, v36, v38
	v_add_f32_e32 v36, v40, v40
	v_cndmask_b32_e32 v36, v40, v36, vcc
	v_cmp_nlt_f32_e32 vcc, s16, v33
	v_exp_f32_e32 v35, v35
	s_nop 0
	v_cndmask_b32_e64 v36, v201, -v36, vcc
	v_cmp_gt_f32_e32 vcc, s17, v36
	v_mul_f32_e32 v38, 0x4f800000, v36
	s_nop 0
	v_cndmask_b32_e32 v36, v36, v38, vcc
	v_sqrt_f32_e32 v38, v36
	s_nop 0
	v_add_u32_e32 v40, -1, v38
	v_fma_f32 v42, -v40, v38, v36
	v_cmp_ge_f32_e64 s[0:1], 0, v42
	v_add_u32_e32 v42, 1, v38
	s_nop 0
	v_cndmask_b32_e64 v40, v38, v40, s[0:1]
	v_fma_f32 v38, -v42, v38, v36
	v_cmp_lt_f32_e64 s[0:1], 0, v38
	s_nop 1
	v_cndmask_b32_e64 v38, v40, v42, s[0:1]
	v_mul_f32_e32 v40, 0x37800000, v38
	ds_read2_b32 v[42:43], v32 offset0:192 offset1:224
	v_cndmask_b32_e32 v38, v38, v40, vcc
	v_cmp_class_f32_e32 vcc, v36, v193
	s_nop 1
	v_cndmask_b32_e32 v36, v38, v36, vcc
	v_cmp_ngt_f32_e32 vcc, s18, v33
	s_nop 1
	v_cndmask_b32_e32 v33, 1.0, v36, vcc
	v_mul_f32_e32 v33, v34, v33
	s_waitcnt lgkmcnt(0)
	v_mul_f32_e32 v32, v42, v33
	ds_write_b32 v70, v35 offset:4864
	ds_write_b32 v70, v32 offset:41728
	v_add_f32_e32 v32, v60, v74
	v_mul_f32_e32 v32, 0xbfb8aa3b, v32
	v_exp_f32_e32 v32, v32
	v_add_f32_e32 v33, v44, v73
	v_mul_f32_e32 v33, 0xbfb8aa3b, v33
	v_exp_f32_e32 v33, v33
	v_add_f32_e32 v32, 1.0, v32
	v_rcp_f32_e32 v32, v32
	v_add_f32_e32 v33, 1.0, v33
	v_rcp_f32_e32 v33, v33
	v_mul_f32_e32 v32, v32, v72
	v_mul_f32_e32 v34, 0x3fb8aa3b, v32
	v_add_f32_e32 v32, v32, v32
	v_mul_f32_e32 v35, 0x3fb8aa3b, v32
	v_rndne_f32_e32 v35, v35
	v_fmamk_f32 v36, v35, 0xbf317218, v32
	v_fmac_f32_e32 v36, 0x3102e308, v35
	v_fmamk_f32 v38, v36, 0x395133b1, v192
	v_cmp_eq_f32_e32 vcc, s15, v35
	v_cvt_i32_f32_e32 v35, v35
	v_fmaak_f32 v38, v36, v38, 0x3c0887f9
	v_fmaak_f32 v38, v36, v38, 0x3d2aaa81
	v_fmaak_f32 v38, v36, v38, 0x3e2aaaab
	v_fma_f32 v38, v36, v38, 0.5
	v_ldexp_f32 v35, 1.0, v35
	v_mul_f32_e32 v38, v36, v38
	v_cndmask_b32_e32 v35, v35, v202, vcc
	v_fmac_f32_e32 v36, v36, v38
	v_add_f32_e32 v38, -1.0, v35
	v_fmac_f32_e32 v38, v35, v36
	v_add_f32_e32 v35, v38, v38
	v_cndmask_b32_e32 v35, v38, v35, vcc
	v_cmp_nlt_f32_e32 vcc, s16, v32
	v_exp_f32_e32 v34, v34
	s_nop 0
	v_cndmask_b32_e64 v35, v201, -v35, vcc
	v_cmp_gt_f32_e32 vcc, s17, v35
	v_mul_f32_e32 v36, 0x4f800000, v35
	s_nop 0
	v_cndmask_b32_e32 v35, v35, v36, vcc
	v_sqrt_f32_e32 v36, v35
	s_nop 0
	v_add_u32_e32 v38, -1, v36
	v_fma_f32 v40, -v38, v36, v35
	v_cmp_ge_f32_e64 s[0:1], 0, v40
	v_add_u32_e32 v40, 1, v36
	s_nop 0
	v_cndmask_b32_e64 v38, v36, v38, s[0:1]
	v_fma_f32 v36, -v40, v36, v35
	v_cmp_lt_f32_e64 s[0:1], 0, v36
	s_nop 1
	v_cndmask_b32_e64 v36, v38, v40, s[0:1]
	v_mul_f32_e32 v38, 0x37800000, v36
	v_cndmask_b32_e32 v36, v36, v38, vcc
	v_cmp_class_f32_e32 vcc, v35, v193
	s_nop 1
	v_cndmask_b32_e32 v35, v36, v35, vcc
	v_cmp_ngt_f32_e32 vcc, s18, v32
	s_nop 1
	v_cndmask_b32_e32 v32, 1.0, v35, vcc
	v_mul_f32_e32 v32, v33, v32
	v_add_u32_e32 v33, 0xa800, v70
	ds_read2_b32 v[58:59], v33 offset1:32
	s_waitcnt lgkmcnt(0)
	v_mul_f32_e32 v32, v58, v32
	ds_write_b32 v70, v34 offset:6144
	ds_write_b32 v70, v32 offset:43008
	v_add_f32_e32 v32, v61, v74
	v_mul_f32_e32 v32, 0xbfb8aa3b, v32
	v_exp_f32_e32 v32, v32
	v_add_f32_e32 v34, v45, v73
	v_mul_f32_e32 v34, 0xbfb8aa3b, v34
	v_exp_f32_e32 v34, v34
	v_add_f32_e32 v32, 1.0, v32
	v_rcp_f32_e32 v32, v32
	ds_read2_b32 v[44:45], v33 offset0:64 offset1:96
	v_add_f32_e32 v34, 1.0, v34
	v_rcp_f32_e32 v34, v34
	v_mul_f32_e32 v32, v32, v72
	v_mul_f32_e32 v35, 0x3fb8aa3b, v32
	v_add_f32_e32 v32, v32, v32
	v_mul_f32_e32 v36, 0x3fb8aa3b, v32
	v_rndne_f32_e32 v36, v36
	v_fmamk_f32 v38, v36, 0xbf317218, v32
	v_fmac_f32_e32 v38, 0x3102e308, v36
	v_fmamk_f32 v40, v38, 0x395133b1, v192
	v_cmp_eq_f32_e32 vcc, s15, v36
	v_cvt_i32_f32_e32 v36, v36
	v_fmaak_f32 v40, v38, v40, 0x3c0887f9
	v_fmaak_f32 v40, v38, v40, 0x3d2aaa81
	v_fmaak_f32 v40, v38, v40, 0x3e2aaaab
	v_fma_f32 v40, v38, v40, 0.5
	v_ldexp_f32 v36, 1.0, v36
	v_mul_f32_e32 v40, v38, v40
	v_cndmask_b32_e32 v36, v36, v202, vcc
	v_fmac_f32_e32 v38, v38, v40
	v_add_f32_e32 v40, -1.0, v36
	v_fmac_f32_e32 v40, v36, v38
	v_add_f32_e32 v36, v40, v40
	v_cndmask_b32_e32 v36, v40, v36, vcc
	v_cmp_nlt_f32_e32 vcc, s16, v32
	v_exp_f32_e32 v35, v35
	s_nop 0
	v_cndmask_b32_e64 v36, v201, -v36, vcc
	v_cmp_gt_f32_e32 vcc, s17, v36
	v_mul_f32_e32 v38, 0x4f800000, v36
	s_nop 0
	v_cndmask_b32_e32 v36, v36, v38, vcc
	v_sqrt_f32_e32 v38, v36
	s_nop 0
	v_add_u32_e32 v40, -1, v38
	v_fma_f32 v42, -v40, v38, v36
	v_cmp_ge_f32_e64 s[0:1], 0, v42
	v_add_u32_e32 v42, 1, v38
	s_nop 0
	v_cndmask_b32_e64 v40, v38, v40, s[0:1]
	v_fma_f32 v38, -v42, v38, v36
	v_cmp_lt_f32_e64 s[0:1], 0, v38
	s_nop 1
	v_cndmask_b32_e64 v38, v40, v42, s[0:1]
	v_mul_f32_e32 v40, 0x37800000, v38
	v_cndmask_b32_e32 v38, v38, v40, vcc
	v_cmp_class_f32_e32 vcc, v36, v193
	s_nop 1
	v_cndmask_b32_e32 v36, v38, v36, vcc
	v_cmp_ngt_f32_e32 vcc, s18, v32
	s_nop 1
	v_cndmask_b32_e32 v32, 1.0, v36, vcc
	v_mul_f32_e32 v32, v34, v32
	s_waitcnt lgkmcnt(0)
	v_mul_f32_e32 v32, v44, v32
	ds_write_b32 v70, v35 offset:6400
	ds_write_b32 v70, v32 offset:43264
	v_add_f32_e32 v32, v62, v74
	v_mul_f32_e32 v32, 0xbfb8aa3b, v32
	v_exp_f32_e32 v32, v32
	v_add_f32_e32 v34, v46, v73
	v_mul_f32_e32 v34, 0xbfb8aa3b, v34
	v_exp_f32_e32 v34, v34
	v_add_f32_e32 v32, 1.0, v32
	v_rcp_f32_e32 v32, v32
	v_add_f32_e32 v34, 1.0, v34
	v_rcp_f32_e32 v34, v34
	v_mul_f32_e32 v32, v32, v72
	v_mul_f32_e32 v35, 0x3fb8aa3b, v32
	v_add_f32_e32 v32, v32, v32
	v_exp_f32_e32 v36, v35
	v_mul_f32_e32 v35, 0x3fb8aa3b, v32
	v_rndne_f32_e32 v35, v35
	v_fmamk_f32 v38, v35, 0xbf317218, v32
	v_fmac_f32_e32 v38, 0x3102e308, v35
	v_fmamk_f32 v40, v38, 0x395133b1, v192
	v_cmp_eq_f32_e32 vcc, s15, v35
	v_cvt_i32_f32_e32 v35, v35
	v_fmaak_f32 v40, v38, v40, 0x3c0887f9
	v_fmaak_f32 v40, v38, v40, 0x3d2aaa81
	v_fmaak_f32 v40, v38, v40, 0x3e2aaaab
	v_fma_f32 v40, v38, v40, 0.5
	v_ldexp_f32 v35, 1.0, v35
	v_mul_f32_e32 v40, v38, v40
	v_cndmask_b32_e32 v35, v35, v202, vcc
	v_fmac_f32_e32 v38, v38, v40
	v_add_f32_e32 v40, -1.0, v35
	v_fmac_f32_e32 v40, v35, v38
	v_add_f32_e32 v35, v40, v40
	v_cndmask_b32_e32 v35, v40, v35, vcc
	v_cmp_nlt_f32_e32 vcc, s16, v32
	s_nop 1
	v_cndmask_b32_e64 v35, v201, -v35, vcc
	v_cmp_gt_f32_e32 vcc, s17, v35
	v_mul_f32_e32 v38, 0x4f800000, v35
	s_nop 0
	v_cndmask_b32_e32 v35, v35, v38, vcc
	v_sqrt_f32_e32 v38, v35
	s_nop 0
	v_add_u32_e32 v40, -1, v38
	v_fma_f32 v42, -v40, v38, v35
	v_cmp_ge_f32_e64 s[0:1], 0, v42
	v_add_u32_e32 v42, 1, v38
	s_nop 0
	v_cndmask_b32_e64 v40, v38, v40, s[0:1]
	v_fma_f32 v38, -v42, v38, v35
	v_cmp_lt_f32_e64 s[0:1], 0, v38
	s_nop 1
	v_cndmask_b32_e64 v38, v40, v42, s[0:1]
	v_mul_f32_e32 v40, 0x37800000, v38
	v_cndmask_b32_e32 v38, v38, v40, vcc
	v_cmp_class_f32_e32 vcc, v35, v193
	s_nop 1
	v_cndmask_b32_e32 v35, v38, v35, vcc
	v_cmp_ngt_f32_e32 vcc, s18, v32
	s_nop 1
	v_cndmask_b32_e32 v32, 1.0, v35, vcc
	v_mul_f32_e32 v32, v34, v32
	ds_read2_b32 v[34:35], v33 offset0:128 offset1:160
	s_waitcnt lgkmcnt(0)
	v_mul_f32_e32 v32, v34, v32
	ds_write_b32 v70, v36 offset:6656
	ds_write_b32 v70, v32 offset:43520
	v_add_f32_e32 v32, v63, v74
	v_mul_f32_e32 v32, 0xbfb8aa3b, v32
	v_exp_f32_e32 v32, v32
	v_add_f32_e32 v34, v47, v73
	v_mul_f32_e32 v34, 0xbfb8aa3b, v34
	v_exp_f32_e32 v34, v34
	v_add_f32_e32 v32, 1.0, v32
	v_rcp_f32_e32 v32, v32
	v_lshlrev_b64 v[46:47], 2, v[96:97]
	v_add_f32_e32 v34, 1.0, v34
	v_rcp_f32_e32 v36, v34
	v_mul_f32_e32 v32, v32, v72
	v_mul_f32_e32 v34, 0x3fb8aa3b, v32
	v_add_f32_e32 v32, v32, v32
	v_mul_f32_e32 v38, 0x3fb8aa3b, v32
	v_rndne_f32_e32 v38, v38
	v_fmamk_f32 v40, v38, 0xbf317218, v32
	v_fmac_f32_e32 v40, 0x3102e308, v38
	v_fmamk_f32 v42, v40, 0x395133b1, v192
	v_cmp_eq_f32_e32 vcc, s15, v38
	v_cvt_i32_f32_e32 v38, v38
	v_fmaak_f32 v42, v40, v42, 0x3c0887f9
	v_fmaak_f32 v42, v40, v42, 0x3d2aaa81
	v_fmaak_f32 v42, v40, v42, 0x3e2aaaab
	v_fma_f32 v42, v40, v42, 0.5
	v_ldexp_f32 v38, 1.0, v38
	v_mul_f32_e32 v42, v40, v42
	v_cndmask_b32_e32 v38, v38, v202, vcc
	v_fmac_f32_e32 v40, v40, v42
	v_add_f32_e32 v42, -1.0, v38
	v_fmac_f32_e32 v42, v38, v40
	v_add_f32_e32 v38, v42, v42
	v_cndmask_b32_e32 v38, v42, v38, vcc
	v_cmp_nlt_f32_e32 vcc, s16, v32
	v_lshl_add_u64 v[60:61], s[10:11], 0, v[46:47]
	v_exp_f32_e32 v34, v34
	v_cndmask_b32_e64 v38, v201, -v38, vcc
	v_cmp_gt_f32_e32 vcc, s17, v38
	v_mul_f32_e32 v40, 0x4f800000, v38
	s_nop 0
	v_cndmask_b32_e32 v38, v38, v40, vcc
	v_sqrt_f32_e32 v40, v38
	s_nop 0
	v_add_u32_e32 v42, -1, v40
	v_fma_f32 v44, -v42, v40, v38
	v_cmp_ge_f32_e64 s[0:1], 0, v44
	v_add_u32_e32 v44, 1, v40
	s_nop 0
	v_cndmask_b32_e64 v42, v40, v42, s[0:1]
	v_fma_f32 v40, -v44, v40, v38
	v_cmp_lt_f32_e64 s[0:1], 0, v40
	s_nop 1
	v_cndmask_b32_e64 v40, v42, v44, s[0:1]
	v_mul_f32_e32 v42, 0x37800000, v40
	v_cndmask_b32_e32 v40, v40, v42, vcc
	v_cmp_class_f32_e32 vcc, v38, v193
	s_nop 1
	v_cndmask_b32_e32 v38, v40, v38, vcc
	v_cmp_ngt_f32_e32 vcc, s18, v32
	s_nop 1
	v_cndmask_b32_e32 v32, 1.0, v38, vcc
	v_mul_f32_e32 v36, v36, v32
	ds_read2_b32 v[32:33], v33 offset0:192 offset1:224
	s_waitcnt lgkmcnt(0)
	v_mul_f32_e32 v32, v32, v36
	ds_write_b32 v70, v32 offset:43776
	v_mov_b32_e32 v32, v226
	v_mul_f32_e32 v32, 0xbfb8aa3b, v32
	v_exp_f32_e32 v32, v32
	s_nop 0
	v_add_f32_e32 v36, 1.0, v32
	v_add_f32_e32 v38, -1.0, v36
	v_sub_f32_e32 v40, v38, v36
	v_add_f32_e32 v40, 1.0, v40
	v_sub_f32_e32 v38, v32, v38
	v_add_f32_e32 v38, v38, v40
	v_frexp_mant_f32_e32 v40, v36
	v_cvt_f64_f32_e32 v[60:61], v36
	v_cmp_gt_f32_e32 vcc, s7, v40
	v_frexp_exp_i32_f64_e32 v40, v[60:61]
	s_nop 0
	v_subbrev_co_u32_e32 v40, vcc, 0, v40, vcc
	v_sub_u32_e32 v42, 0, v40
	v_ldexp_f32 v36, v36, v42
	v_ldexp_f32 v38, v38, v42
	v_add_f32_e32 v42, -1.0, v36
	v_add_f32_e32 v48, 1.0, v36
	v_add_f32_e32 v44, 1.0, v42
	v_add_f32_e32 v50, -1.0, v48
	v_sub_f32_e32 v44, v36, v44
	v_sub_f32_e32 v36, v36, v50
	v_add_f32_e32 v36, v38, v36
	v_add_f32_e32 v44, v38, v44
	v_add_f32_e32 v38, v48, v36
	v_sub_f32_e32 v48, v38, v48
	v_sub_f32_e32 v36, v36, v48
	v_rcp_f32_e32 v48, v38
	v_add_f32_e32 v61, v42, v44
	v_sub_f32_e32 v42, v61, v42
	v_sub_f32_e32 v42, v44, v42
	v_mul_f32_e32 v44, v61, v48
	v_mul_f32_e32 v62, v38, v44
	v_fma_f32 v72, v44, v38, -v62
	v_fmac_f32_e32 v72, v44, v36
	v_add_f32_e32 v60, v62, v72
	v_sub_f32_e32 v63, v61, v60
	v_pk_add_f32 v[74:75], v[60:61], v[62:63] neg_lo:[0,1] neg_hi:[0,1]
	v_mov_b32_e32 v73, v60
	v_pk_add_f32 v[60:61], v[74:75], v[72:73] neg_lo:[0,1] neg_hi:[0,1]
	v_cmp_neq_f32_e32 vcc, s40, v32
	v_add_f32_e32 v42, v42, v61
	v_add_f32_e32 v42, v60, v42
	v_add_f32_e32 v61, v63, v42
	v_mul_f32_e32 v50, v48, v61
	v_mul_f32_e32 v62, v38, v50
	v_fma_f32 v72, v50, v38, -v62
	v_fmac_f32_e32 v72, v50, v36
	v_add_f32_e32 v60, v62, v72
	v_sub_f32_e32 v36, v63, v61
	v_sub_f32_e32 v63, v61, v60
	v_pk_add_f32 v[74:75], v[60:61], v[62:63] neg_lo:[0,1] neg_hi:[0,1]
	v_mov_b32_e32 v73, v60
	v_add_f32_e32 v36, v42, v36
	v_pk_add_f32 v[60:61], v[74:75], v[72:73] neg_lo:[0,1] neg_hi:[0,1]
	v_add_f32_e32 v38, v44, v50
	v_add_f32_e32 v36, v36, v61
	v_add_f32_e32 v36, v60, v36
	v_add_f32_e32 v36, v63, v36
	v_sub_f32_e32 v42, v38, v44
	v_mul_f32_e32 v36, v48, v36
	v_sub_f32_e32 v42, v50, v42
	v_add_f32_e32 v36, v42, v36
	v_add_f32_e32 v42, v38, v36
	v_cvt_f32_i32_e32 v60, v40
	v_mul_f32_e32 v44, v42, v42
	v_fmamk_f32 v48, v44, 0x3e9b6dac, v191
	v_fmaak_f32 v169, v44, v48, 0x3f2aaada
	v_mul_f32_e32 v61, v42, v44
	v_pk_mul_f32 v[72:73], v[60:61], v[168:169]
	v_ldexp_f32 v63, v42, 1
	v_fma_f32 v62, v60, s39, -v72
	v_fmac_f32_e32 v62, 0xb102e308, v60
	v_sub_f32_e32 v38, v42, v38
	v_pk_add_f32 v[60:61], v[72:73], v[62:63]
	v_sub_f32_e32 v36, v36, v38
	v_sub_f32_e32 v38, v61, v63
	v_ldexp_f32 v36, v36, 1
	v_sub_f32_e32 v38, v73, v38
	v_add_f32_e32 v75, v36, v38
	v_mov_b32_e32 v74, v72
	v_pk_add_f32 v[72:73], v[60:61], v[72:73] neg_lo:[0,1] neg_hi:[0,1]
	v_pk_add_f32 v[76:77], v[60:61], v[74:75]
	v_mov_b32_e32 v63, v60
	v_mov_b32_e32 v73, v77
	v_pk_add_f32 v[78:79], v[62:63], v[72:73] neg_lo:[0,1] neg_hi:[0,1]
	v_pk_add_f32 v[62:63], v[62:63], v[72:73]
	v_mov_b32_e32 v74, v75
	v_pk_add_f32 v[72:73], v[62:63], v[60:61] op_sel:[1,0] op_sel_hi:[0,1] neg_lo:[0,1] neg_hi:[0,1]
	v_pk_add_f32 v[80:81], v[76:77], v[72:73] op_sel_hi:[1,0] neg_lo:[0,1] neg_hi:[0,1]
	v_mov_b32_e32 v76, v77
	v_mov_b32_e32 v77, v63
	v_pk_mov_b32 v[72:73], v[60:61], v[72:73] op_sel:[1,0]
	v_mov_b32_e32 v75, v60
	v_pk_add_f32 v[72:73], v[76:77], v[72:73] neg_lo:[0,1] neg_hi:[0,1]
	v_mov_b32_e32 v80, v78
	v_pk_add_f32 v[60:61], v[74:75], v[72:73] neg_lo:[0,1] neg_hi:[0,1]
	v_mov_b32_e32 v79, v63
	v_pk_add_f32 v[72:73], v[80:81], v[60:61]
	v_pk_add_f32 v[74:75], v[72:73], v[72:73] op_sel:[0,1] op_sel_hi:[1,0]
	v_pk_add_f32 v[62:63], v[62:63], v[74:75] op_sel:[1,0] op_sel_hi:[0,1]
	v_mov_b32_e32 v73, v62
	v_pk_add_f32 v[76:77], v[72:73], v[78:79] neg_lo:[0,1] neg_hi:[0,1]
	v_mov_b32_e32 v61, v74
	v_sub_f32_e32 v36, v72, v76
	v_pk_add_f32 v[60:61], v[60:61], v[76:77] neg_lo:[0,1] neg_hi:[0,1]
	v_sub_f32_e32 v36, v78, v36
	v_add_f32_e32 v36, v60, v36
	v_add_f32_e32 v36, v36, v61
	v_add_f32_e32 v36, v62, v36
	v_cndmask_b32_e32 v36, v199, v36, vcc
	v_cmp_ngt_f32_e32 vcc, -1.0, v32
	v_lshl_add_u64 v[60:61], s[24:25], 0, v[46:47]
	v_lshl_add_u64 v[46:47], s[8:9], 0, v[46:47]
	v_cndmask_b32_e32 v36, v200, v36, vcc
	v_cmp_neq_f32_e32 vcc, -1.0, v32
	v_mov_b32_e32 v38, v227
	v_add_f32_e32 v0, v0, v38
	v_cndmask_b32_e32 v36, v201, v36, vcc
	v_cmp_lt_f32_e64 vcc, |v32|, s41
	v_mul_f32_e32 v0, 0xbfb8aa3b, v0
	v_exp_f32_e32 v0, v0
	v_cndmask_b32_e32 v32, v36, v32, vcc
	v_mov_b32_e32 v36, v228
	v_mul_f32_e32 v32, 0xc1000000, v32
	v_add_f32_e32 v0, 1.0, v0
	v_rcp_f32_e32 v0, v0
	v_add_f32_e32 v1, v1, v38
	v_mul_f32_e32 v1, 0xbfb8aa3b, v1
	v_exp_f32_e32 v1, v1
	v_add_f32_e32 v16, v16, v36
	v_mul_f32_e32 v16, 0xbfb8aa3b, v16
	v_exp_f32_e32 v16, v16
	v_add_f32_e32 v1, 1.0, v1
	v_rcp_f32_e32 v1, v1
	v_add_f32_e32 v16, 1.0, v16
	v_rcp_f32_e32 v16, v16
	s_nop 0
	v_mul_f32_e32 v16, v16, v32
	v_mul_f32_e32 v40, 0x3fb8aa3b, v16
	v_add_f32_e32 v16, v16, v16
	v_mul_f32_e32 v42, 0x3fb8aa3b, v16
	v_rndne_f32_e32 v42, v42
	v_fmamk_f32 v44, v42, 0xbf317218, v16
	v_fmac_f32_e32 v44, 0x3102e308, v42
	v_fmamk_f32 v46, v44, 0x395133b1, v192
	v_cmp_eq_f32_e32 vcc, s15, v42
	v_cvt_i32_f32_e32 v42, v42
	v_fmaak_f32 v46, v44, v46, 0x3c0887f9
	v_fmaak_f32 v46, v44, v46, 0x3d2aaa81
	v_fmaak_f32 v46, v44, v46, 0x3e2aaaab
	v_fma_f32 v46, v44, v46, 0.5
	v_ldexp_f32 v42, 1.0, v42
	v_mul_f32_e32 v46, v44, v46
	v_cndmask_b32_e32 v42, v42, v202, vcc
	v_fmac_f32_e32 v44, v44, v46
	v_add_f32_e32 v46, -1.0, v42
	v_fmac_f32_e32 v46, v42, v44
	v_add_f32_e32 v42, v46, v46
	v_cndmask_b32_e32 v42, v46, v42, vcc
	v_cmp_nlt_f32_e32 vcc, s16, v16
	v_exp_f32_e32 v40, v40
	s_nop 0
	v_cndmask_b32_e64 v42, v201, -v42, vcc
	v_cmp_gt_f32_e32 vcc, s17, v42
	v_mul_f32_e32 v44, 0x4f800000, v42
	s_nop 0
	v_cndmask_b32_e32 v42, v42, v44, vcc
	v_sqrt_f32_e32 v44, v42
	s_nop 0
	v_add_u32_e32 v46, -1, v44
	v_fma_f32 v47, -v46, v44, v42
	v_cmp_ge_f32_e64 s[0:1], 0, v47
	v_add_u32_e32 v47, 1, v44
	s_nop 0
	v_cndmask_b32_e64 v46, v44, v46, s[0:1]
	v_fma_f32 v44, -v47, v44, v42
	v_cmp_lt_f32_e64 s[0:1], 0, v44
	s_nop 1
	v_cndmask_b32_e64 v44, v46, v47, s[0:1]
	v_mul_f32_e32 v46, 0x37800000, v44
	v_cndmask_b32_e32 v44, v44, v46, vcc
	v_cmp_class_f32_e32 vcc, v42, v193
	s_nop 1
	v_cndmask_b32_e32 v42, v44, v42, vcc
	v_cmp_ngt_f32_e32 vcc, s18, v16
	s_nop 1
	v_cndmask_b32_e32 v16, 1.0, v42, vcc
	v_mul_f32_e32 v0, v0, v16
	v_mul_f32_e32 v0, v65, v0
	ds_write_b32 v70, v40 offset:128
	ds_write_b32 v70, v0 offset:36992
	v_add_f32_e32 v0, v17, v36
	v_mul_f32_e32 v0, 0xbfb8aa3b, v0
	v_exp_f32_e32 v0, v0
	s_nop 0
	v_add_f32_e32 v0, 1.0, v0
	v_rcp_f32_e32 v0, v0
	s_nop 0
	v_mul_f32_e32 v0, v0, v32
	v_mul_f32_e32 v16, 0x3fb8aa3b, v0
	v_add_f32_e32 v0, v0, v0
	v_mul_f32_e32 v17, 0x3fb8aa3b, v0
	v_rndne_f32_e32 v17, v17
	v_fmamk_f32 v40, v17, 0xbf317218, v0
	v_fmac_f32_e32 v40, 0x3102e308, v17
	v_fmamk_f32 v42, v40, 0x395133b1, v192
	v_cmp_eq_f32_e32 vcc, s15, v17
	v_cvt_i32_f32_e32 v17, v17
	v_fmaak_f32 v42, v40, v42, 0x3c0887f9
	v_fmaak_f32 v42, v40, v42, 0x3d2aaa81
	v_fmaak_f32 v42, v40, v42, 0x3e2aaaab
	v_fma_f32 v42, v40, v42, 0.5
	v_ldexp_f32 v17, 1.0, v17
	v_mul_f32_e32 v42, v40, v42
	v_cndmask_b32_e32 v17, v17, v202, vcc
	v_fmac_f32_e32 v40, v40, v42
	v_add_f32_e32 v42, -1.0, v17
	v_fmac_f32_e32 v42, v17, v40
	v_add_f32_e32 v17, v42, v42
	v_cndmask_b32_e32 v17, v42, v17, vcc
	v_cmp_nlt_f32_e32 vcc, s16, v0
	v_exp_f32_e32 v16, v16
	s_nop 0
	v_cndmask_b32_e64 v17, v201, -v17, vcc
	v_cmp_gt_f32_e32 vcc, s17, v17
	v_mul_f32_e32 v40, 0x4f800000, v17
	s_nop 0
	v_cndmask_b32_e32 v17, v17, v40, vcc
	v_sqrt_f32_e32 v40, v17
	s_nop 0
	v_add_u32_e32 v42, -1, v40
	v_fma_f32 v44, -v42, v40, v17
	v_cmp_ge_f32_e64 s[0:1], 0, v44
	v_add_u32_e32 v44, 1, v40
	s_nop 0
	v_cndmask_b32_e64 v42, v40, v42, s[0:1]
	v_fma_f32 v40, -v44, v40, v17
	v_cmp_lt_f32_e64 s[0:1], 0, v40
	s_nop 1
	v_cndmask_b32_e64 v40, v42, v44, s[0:1]
	v_mul_f32_e32 v42, 0x37800000, v40
	v_cndmask_b32_e32 v40, v40, v42, vcc
	v_cmp_class_f32_e32 vcc, v17, v193
	s_nop 1
	v_cndmask_b32_e32 v17, v40, v17, vcc
	v_cmp_ngt_f32_e32 vcc, s18, v0
	s_nop 1
	v_cndmask_b32_e32 v0, 1.0, v17, vcc
	v_mul_f32_e32 v0, v1, v0
	v_mul_f32_e32 v0, v49, v0
	ds_write_b32 v70, v16 offset:384
	ds_write_b32 v70, v0 offset:37248
	v_add_f32_e32 v0, v18, v36
	v_mul_f32_e32 v0, 0xbfb8aa3b, v0
	v_exp_f32_e32 v0, v0
	v_add_f32_e32 v1, v2, v38
	v_mul_f32_e32 v1, 0xbfb8aa3b, v1
	v_exp_f32_e32 v1, v1
	v_add_f32_e32 v0, 1.0, v0
	v_rcp_f32_e32 v0, v0
	v_add_f32_e32 v1, 1.0, v1
	v_rcp_f32_e32 v1, v1
	v_mul_f32_e32 v0, v0, v32
	v_mul_f32_e32 v2, 0x3fb8aa3b, v0
	v_add_f32_e32 v0, v0, v0
	v_mul_f32_e32 v16, 0x3fb8aa3b, v0
	v_rndne_f32_e32 v16, v16
	v_fmamk_f32 v17, v16, 0xbf317218, v0
	v_fmac_f32_e32 v17, 0x3102e308, v16
	v_fmamk_f32 v18, v17, 0x395133b1, v192
	v_cmp_eq_f32_e32 vcc, s15, v16
	v_cvt_i32_f32_e32 v16, v16
	v_fmaak_f32 v18, v17, v18, 0x3c0887f9
	v_fmaak_f32 v18, v17, v18, 0x3d2aaa81
	v_fmaak_f32 v18, v17, v18, 0x3e2aaaab
	v_fma_f32 v18, v17, v18, 0.5
	v_ldexp_f32 v16, 1.0, v16
	v_mul_f32_e32 v18, v17, v18
	v_cndmask_b32_e32 v16, v16, v202, vcc
	v_fmac_f32_e32 v17, v17, v18
	v_add_f32_e32 v18, -1.0, v16
	v_fmac_f32_e32 v18, v16, v17
	v_add_f32_e32 v16, v18, v18
	v_cndmask_b32_e32 v16, v18, v16, vcc
	v_cmp_nlt_f32_e32 vcc, s16, v0
	v_exp_f32_e32 v2, v2
	s_nop 0
	v_cndmask_b32_e64 v16, v201, -v16, vcc
	v_cmp_gt_f32_e32 vcc, s17, v16
	v_mul_f32_e32 v17, 0x4f800000, v16
	s_nop 0
	v_cndmask_b32_e32 v16, v16, v17, vcc
	v_sqrt_f32_e32 v17, v16
	s_nop 0
	v_add_u32_e32 v18, -1, v17
	v_fma_f32 v40, -v18, v17, v16
	v_cmp_ge_f32_e64 s[0:1], 0, v40
	v_add_u32_e32 v40, 1, v17
	s_nop 0
	v_cndmask_b32_e64 v18, v17, v18, s[0:1]
	v_fma_f32 v17, -v40, v17, v16
	v_cmp_lt_f32_e64 s[0:1], 0, v17
	s_nop 1
	v_cndmask_b32_e64 v17, v18, v40, s[0:1]
	v_mul_f32_e32 v18, 0x37800000, v17
	v_cndmask_b32_e32 v17, v17, v18, vcc
	v_cmp_class_f32_e32 vcc, v16, v193
	s_nop 1
	v_cndmask_b32_e32 v16, v17, v16, vcc
	v_cmp_ngt_f32_e32 vcc, s18, v0
	s_nop 1
	v_cndmask_b32_e32 v0, 1.0, v16, vcc
	v_mul_f32_e32 v0, v1, v0
	v_mul_f32_e32 v0, v67, v0
	ds_write_b32 v70, v2 offset:640
	ds_write_b32 v70, v0 offset:37504
	v_add_f32_e32 v0, v19, v36
	v_mul_f32_e32 v0, 0xbfb8aa3b, v0
	v_exp_f32_e32 v0, v0
	v_add_f32_e32 v1, v3, v38
	v_mul_f32_e32 v1, 0xbfb8aa3b, v1
	v_exp_f32_e32 v1, v1
	v_add_f32_e32 v0, 1.0, v0
	v_rcp_f32_e32 v0, v0
	v_add_f32_e32 v1, 1.0, v1
	v_rcp_f32_e32 v1, v1
	v_mul_f32_e32 v0, v0, v32
	v_mul_f32_e32 v2, 0x3fb8aa3b, v0
	v_add_f32_e32 v0, v0, v0
	v_mul_f32_e32 v3, 0x3fb8aa3b, v0
	v_rndne_f32_e32 v3, v3
	v_fmamk_f32 v16, v3, 0xbf317218, v0
	v_fmac_f32_e32 v16, 0x3102e308, v3
	v_fmamk_f32 v17, v16, 0x395133b1, v192
	v_cmp_eq_f32_e32 vcc, s15, v3
	v_cvt_i32_f32_e32 v3, v3
	v_fmaak_f32 v17, v16, v17, 0x3c0887f9
	v_fmaak_f32 v17, v16, v17, 0x3d2aaa81
	v_fmaak_f32 v17, v16, v17, 0x3e2aaaab
	v_fma_f32 v17, v16, v17, 0.5
	v_ldexp_f32 v3, 1.0, v3
	v_mul_f32_e32 v17, v16, v17
	v_cndmask_b32_e32 v3, v3, v202, vcc
	v_fmac_f32_e32 v16, v16, v17
	v_add_f32_e32 v17, -1.0, v3
	v_fmac_f32_e32 v17, v3, v16
	v_add_f32_e32 v3, v17, v17
	v_cndmask_b32_e32 v3, v17, v3, vcc
	v_cmp_nlt_f32_e32 vcc, s16, v0
	v_exp_f32_e32 v2, v2
	s_nop 0
	v_cndmask_b32_e64 v3, v201, -v3, vcc
	v_cmp_gt_f32_e32 vcc, s17, v3
	v_mul_f32_e32 v16, 0x4f800000, v3
	s_nop 0
	v_cndmask_b32_e32 v3, v3, v16, vcc
	v_sqrt_f32_e32 v16, v3
	s_nop 0
	v_add_u32_e32 v17, -1, v16
	v_fma_f32 v18, -v17, v16, v3
	v_cmp_ge_f32_e64 s[0:1], 0, v18
	v_add_u32_e32 v18, 1, v16
	s_nop 0
	v_cndmask_b32_e64 v17, v16, v17, s[0:1]
	v_fma_f32 v16, -v18, v16, v3
	v_cmp_lt_f32_e64 s[0:1], 0, v16
	s_nop 1
	v_cndmask_b32_e64 v16, v17, v18, s[0:1]
	v_mul_f32_e32 v17, 0x37800000, v16
	v_cndmask_b32_e32 v16, v16, v17, vcc
	v_cmp_class_f32_e32 vcc, v3, v193
	s_nop 1
	v_cndmask_b32_e32 v3, v16, v3, vcc
	v_cmp_ngt_f32_e32 vcc, s18, v0
	s_nop 1
	v_cndmask_b32_e32 v0, 1.0, v3, vcc
	v_mul_f32_e32 v0, v1, v0
	v_mul_f32_e32 v0, v51, v0
	ds_write_b32 v70, v2 offset:896
	ds_write_b32 v70, v0 offset:37760
	v_add_f32_e32 v0, v20, v36
	v_mul_f32_e32 v0, 0xbfb8aa3b, v0
	v_exp_f32_e32 v0, v0
	v_add_f32_e32 v1, v4, v38
	v_mul_f32_e32 v1, 0xbfb8aa3b, v1
	v_exp_f32_e32 v1, v1
	v_add_f32_e32 v0, 1.0, v0
	v_rcp_f32_e32 v0, v0
	v_add_f32_e32 v1, 1.0, v1
	v_rcp_f32_e32 v1, v1
	v_mul_f32_e32 v0, v0, v32
	v_mul_f32_e32 v2, 0x3fb8aa3b, v0
	v_add_f32_e32 v0, v0, v0
	v_mul_f32_e32 v3, 0x3fb8aa3b, v0
	v_rndne_f32_e32 v3, v3
	v_fmamk_f32 v4, v3, 0xbf317218, v0
	v_fmac_f32_e32 v4, 0x3102e308, v3
	v_fmamk_f32 v16, v4, 0x395133b1, v192
	v_cmp_eq_f32_e32 vcc, s15, v3
	v_cvt_i32_f32_e32 v3, v3
	v_fmaak_f32 v16, v4, v16, 0x3c0887f9
	v_fmaak_f32 v16, v4, v16, 0x3d2aaa81
	v_fmaak_f32 v16, v4, v16, 0x3e2aaaab
	v_fma_f32 v16, v4, v16, 0.5
	v_ldexp_f32 v3, 1.0, v3
	v_mul_f32_e32 v16, v4, v16
	v_cndmask_b32_e32 v3, v3, v202, vcc
	v_fmac_f32_e32 v4, v4, v16
	v_add_f32_e32 v16, -1.0, v3
	v_fmac_f32_e32 v16, v3, v4
	v_add_f32_e32 v3, v16, v16
	v_cndmask_b32_e32 v3, v16, v3, vcc
	v_cmp_nlt_f32_e32 vcc, s16, v0
	v_exp_f32_e32 v2, v2
	s_nop 0
	v_cndmask_b32_e64 v3, v201, -v3, vcc
	v_cmp_gt_f32_e32 vcc, s17, v3
	v_mul_f32_e32 v4, 0x4f800000, v3
	s_nop 0
	v_cndmask_b32_e32 v3, v3, v4, vcc
	v_sqrt_f32_e32 v4, v3
	s_nop 0
	v_add_u32_e32 v16, -1, v4
	v_fma_f32 v17, -v16, v4, v3
	v_cmp_ge_f32_e64 s[0:1], 0, v17
	v_add_u32_e32 v17, 1, v4
	s_nop 0
	v_cndmask_b32_e64 v16, v4, v16, s[0:1]
	v_fma_f32 v4, -v17, v4, v3
	v_cmp_lt_f32_e64 s[0:1], 0, v4
	s_nop 1
	v_cndmask_b32_e64 v4, v16, v17, s[0:1]
	v_mul_f32_e32 v16, 0x37800000, v4
	v_cndmask_b32_e32 v4, v4, v16, vcc
	v_cmp_class_f32_e32 vcc, v3, v193
	s_nop 1
	v_cndmask_b32_e32 v3, v4, v3, vcc
	v_cmp_ngt_f32_e32 vcc, s18, v0
	s_nop 1
	v_cndmask_b32_e32 v0, 1.0, v3, vcc
	v_mul_f32_e32 v0, v1, v0
	v_mul_f32_e32 v0, v69, v0
	ds_write_b32 v70, v2 offset:2176
	ds_write_b32 v70, v0 offset:39040
	v_add_f32_e32 v0, v21, v36
	v_mul_f32_e32 v0, 0xbfb8aa3b, v0
	v_exp_f32_e32 v0, v0
	v_add_f32_e32 v1, v5, v38
	v_mul_f32_e32 v1, 0xbfb8aa3b, v1
	v_exp_f32_e32 v1, v1
	v_add_f32_e32 v0, 1.0, v0
	v_rcp_f32_e32 v0, v0
	v_add_f32_e32 v1, 1.0, v1
	v_rcp_f32_e32 v1, v1
	v_mul_f32_e32 v0, v0, v32
	v_mul_f32_e32 v2, 0x3fb8aa3b, v0
	v_add_f32_e32 v0, v0, v0
	v_mul_f32_e32 v3, 0x3fb8aa3b, v0
	v_rndne_f32_e32 v3, v3
	v_fmamk_f32 v4, v3, 0xbf317218, v0
	v_fmac_f32_e32 v4, 0x3102e308, v3
	v_fmamk_f32 v5, v4, 0x395133b1, v192
	v_cmp_eq_f32_e32 vcc, s15, v3
	v_cvt_i32_f32_e32 v3, v3
	v_fmaak_f32 v5, v4, v5, 0x3c0887f9
	v_fmaak_f32 v5, v4, v5, 0x3d2aaa81
	v_fmaak_f32 v5, v4, v5, 0x3e2aaaab
	v_fma_f32 v5, v4, v5, 0.5
	v_ldexp_f32 v3, 1.0, v3
	v_mul_f32_e32 v5, v4, v5
	v_cndmask_b32_e32 v3, v3, v202, vcc
	v_fmac_f32_e32 v4, v4, v5
	v_add_f32_e32 v5, -1.0, v3
	v_fmac_f32_e32 v5, v3, v4
	v_add_f32_e32 v3, v5, v5
	v_cndmask_b32_e32 v3, v5, v3, vcc
	v_cmp_nlt_f32_e32 vcc, s16, v0
	v_exp_f32_e32 v2, v2
	s_nop 0
	v_cndmask_b32_e64 v3, v201, -v3, vcc
	v_cmp_gt_f32_e32 vcc, s17, v3
	v_mul_f32_e32 v4, 0x4f800000, v3
	s_nop 0
	v_cndmask_b32_e32 v3, v3, v4, vcc
	v_sqrt_f32_e32 v4, v3
	s_nop 0
	v_add_u32_e32 v5, -1, v4
	v_fma_f32 v16, -v5, v4, v3
	v_cmp_ge_f32_e64 s[0:1], 0, v16
	v_add_u32_e32 v16, 1, v4
	s_nop 0
	v_cndmask_b32_e64 v5, v4, v5, s[0:1]
	v_fma_f32 v4, -v16, v4, v3
	v_cmp_lt_f32_e64 s[0:1], 0, v4
	s_nop 1
	v_cndmask_b32_e64 v4, v5, v16, s[0:1]
	v_mul_f32_e32 v5, 0x37800000, v4
	v_cndmask_b32_e32 v4, v4, v5, vcc
	v_cmp_class_f32_e32 vcc, v3, v193
	s_nop 1
	v_cndmask_b32_e32 v3, v4, v3, vcc
	v_cmp_ngt_f32_e32 vcc, s18, v0
	s_nop 1
	v_cndmask_b32_e32 v0, 1.0, v3, vcc
	v_mul_f32_e32 v0, v1, v0
	v_mul_f32_e32 v0, v37, v0
	ds_write_b32 v70, v2 offset:2432
	ds_write_b32 v70, v0 offset:39296
	v_add_f32_e32 v0, v22, v36
	v_mul_f32_e32 v0, 0xbfb8aa3b, v0
	v_exp_f32_e32 v0, v0
	v_add_f32_e32 v1, v6, v38
	v_mul_f32_e32 v1, 0xbfb8aa3b, v1
	v_exp_f32_e32 v1, v1
	v_add_f32_e32 v0, 1.0, v0
	v_rcp_f32_e32 v0, v0
	v_add_f32_e32 v1, 1.0, v1
	v_rcp_f32_e32 v1, v1
	v_mul_f32_e32 v0, v0, v32
	v_mul_f32_e32 v2, 0x3fb8aa3b, v0
	v_add_f32_e32 v0, v0, v0
	v_mul_f32_e32 v3, 0x3fb8aa3b, v0
	v_rndne_f32_e32 v3, v3
	v_fmamk_f32 v4, v3, 0xbf317218, v0
	v_fmac_f32_e32 v4, 0x3102e308, v3
	v_fmamk_f32 v5, v4, 0x395133b1, v192
	v_cmp_eq_f32_e32 vcc, s15, v3
	v_cvt_i32_f32_e32 v3, v3
	v_fmaak_f32 v5, v4, v5, 0x3c0887f9
	v_fmaak_f32 v5, v4, v5, 0x3d2aaa81
	v_fmaak_f32 v5, v4, v5, 0x3e2aaaab
	v_fma_f32 v5, v4, v5, 0.5
	v_ldexp_f32 v3, 1.0, v3
	v_mul_f32_e32 v5, v4, v5
	v_cndmask_b32_e32 v3, v3, v202, vcc
	v_fmac_f32_e32 v4, v4, v5
	v_add_f32_e32 v5, -1.0, v3
	v_fmac_f32_e32 v5, v3, v4
	v_add_f32_e32 v3, v5, v5
	v_cndmask_b32_e32 v3, v5, v3, vcc
	v_cmp_nlt_f32_e32 vcc, s16, v0
	v_exp_f32_e32 v2, v2
	s_nop 0
	v_cndmask_b32_e64 v3, v201, -v3, vcc
	v_cmp_gt_f32_e32 vcc, s17, v3
	v_mul_f32_e32 v4, 0x4f800000, v3
	s_nop 0
	v_cndmask_b32_e32 v3, v3, v4, vcc
	v_sqrt_f32_e32 v4, v3
	s_nop 0
	v_add_u32_e32 v5, -1, v4
	v_fma_f32 v6, -v5, v4, v3
	v_cmp_ge_f32_e64 s[0:1], 0, v6
	v_add_u32_e32 v6, 1, v4
	s_nop 0
	v_cndmask_b32_e64 v5, v4, v5, s[0:1]
	v_fma_f32 v4, -v6, v4, v3
	v_cmp_lt_f32_e64 s[0:1], 0, v4
	s_nop 1
	v_cndmask_b32_e64 v4, v5, v6, s[0:1]
	v_mul_f32_e32 v5, 0x37800000, v4
	v_cndmask_b32_e32 v4, v4, v5, vcc
	v_cmp_class_f32_e32 vcc, v3, v193
	s_nop 1
	v_cndmask_b32_e32 v3, v4, v3, vcc
	v_cmp_ngt_f32_e32 vcc, s18, v0
	s_nop 1
	v_cndmask_b32_e32 v0, 1.0, v3, vcc
	v_mul_f32_e32 v0, v1, v0
	v_mul_f32_e32 v0, v53, v0
	ds_write_b32 v70, v2 offset:2688
	ds_write_b32 v70, v0 offset:39552
	v_add_f32_e32 v0, v23, v36
	v_mul_f32_e32 v0, 0xbfb8aa3b, v0
	v_exp_f32_e32 v0, v0
	v_add_f32_e32 v1, v7, v38
	v_mul_f32_e32 v1, 0xbfb8aa3b, v1
	v_exp_f32_e32 v1, v1
	v_add_f32_e32 v0, 1.0, v0
	v_rcp_f32_e32 v0, v0
	v_add_f32_e32 v1, 1.0, v1
	v_rcp_f32_e32 v1, v1
	v_mul_f32_e32 v0, v0, v32
	v_mul_f32_e32 v2, 0x3fb8aa3b, v0
	v_add_f32_e32 v0, v0, v0
	v_mul_f32_e32 v3, 0x3fb8aa3b, v0
	v_rndne_f32_e32 v3, v3
	v_fmamk_f32 v4, v3, 0xbf317218, v0
	v_fmac_f32_e32 v4, 0x3102e308, v3
	v_fmamk_f32 v5, v4, 0x395133b1, v192
	v_cmp_eq_f32_e32 vcc, s15, v3
	v_cvt_i32_f32_e32 v3, v3
	v_fmaak_f32 v5, v4, v5, 0x3c0887f9
	v_fmaak_f32 v5, v4, v5, 0x3d2aaa81
	v_fmaak_f32 v5, v4, v5, 0x3e2aaaab
	v_fma_f32 v5, v4, v5, 0.5
	v_ldexp_f32 v3, 1.0, v3
	v_mul_f32_e32 v5, v4, v5
	v_cndmask_b32_e32 v3, v3, v202, vcc
	v_fmac_f32_e32 v4, v4, v5
	v_add_f32_e32 v5, -1.0, v3
	v_fmac_f32_e32 v5, v3, v4
	v_add_f32_e32 v3, v5, v5
	v_cndmask_b32_e32 v3, v5, v3, vcc
	v_cmp_nlt_f32_e32 vcc, s16, v0
	v_exp_f32_e32 v2, v2
	s_nop 0
	v_cndmask_b32_e64 v3, v201, -v3, vcc
	v_cmp_gt_f32_e32 vcc, s17, v3
	v_mul_f32_e32 v4, 0x4f800000, v3
	s_nop 0
	v_cndmask_b32_e32 v3, v3, v4, vcc
	v_sqrt_f32_e32 v4, v3
	s_nop 0
	v_add_u32_e32 v5, -1, v4
	v_fma_f32 v6, -v5, v4, v3
	v_cmp_ge_f32_e64 s[0:1], 0, v6
	v_add_u32_e32 v6, 1, v4
	s_nop 0
	v_cndmask_b32_e64 v5, v4, v5, s[0:1]
	v_fma_f32 v4, -v6, v4, v3
	v_cmp_lt_f32_e64 s[0:1], 0, v4
	s_nop 1
	v_cndmask_b32_e64 v4, v5, v6, s[0:1]
	v_mul_f32_e32 v5, 0x37800000, v4
	v_cndmask_b32_e32 v4, v4, v5, vcc
	v_cmp_class_f32_e32 vcc, v3, v193
	s_nop 1
	v_cndmask_b32_e32 v3, v4, v3, vcc
	v_cmp_ngt_f32_e32 vcc, s18, v0
	s_nop 1
	v_cndmask_b32_e32 v0, 1.0, v3, vcc
	v_mul_f32_e32 v0, v1, v0
	v_mul_f32_e32 v0, v39, v0
	ds_write_b32 v70, v2 offset:2944
	ds_write_b32 v70, v0 offset:39808
	v_add_f32_e32 v0, v24, v36
	v_mul_f32_e32 v0, 0xbfb8aa3b, v0
	v_exp_f32_e32 v0, v0
	v_add_f32_e32 v1, v8, v38
	v_mul_f32_e32 v1, 0xbfb8aa3b, v1
	v_exp_f32_e32 v1, v1
	v_add_f32_e32 v0, 1.0, v0
	v_rcp_f32_e32 v0, v0
	v_add_f32_e32 v1, 1.0, v1
	v_rcp_f32_e32 v1, v1
	v_mul_f32_e32 v0, v0, v32
	v_mul_f32_e32 v2, 0x3fb8aa3b, v0
	v_add_f32_e32 v0, v0, v0
	v_mul_f32_e32 v3, 0x3fb8aa3b, v0
	v_rndne_f32_e32 v3, v3
	v_fmamk_f32 v4, v3, 0xbf317218, v0
	v_fmac_f32_e32 v4, 0x3102e308, v3
	v_fmamk_f32 v5, v4, 0x395133b1, v192
	v_cmp_eq_f32_e32 vcc, s15, v3
	v_cvt_i32_f32_e32 v3, v3
	v_fmaak_f32 v5, v4, v5, 0x3c0887f9
	v_fmaak_f32 v5, v4, v5, 0x3d2aaa81
	v_fmaak_f32 v5, v4, v5, 0x3e2aaaab
	v_fma_f32 v5, v4, v5, 0.5
	v_ldexp_f32 v3, 1.0, v3
	v_mul_f32_e32 v5, v4, v5
	v_cndmask_b32_e32 v3, v3, v202, vcc
	v_fmac_f32_e32 v4, v4, v5
	v_add_f32_e32 v5, -1.0, v3
	v_fmac_f32_e32 v5, v3, v4
	v_add_f32_e32 v3, v5, v5
	v_cndmask_b32_e32 v3, v5, v3, vcc
	v_cmp_nlt_f32_e32 vcc, s16, v0
	v_exp_f32_e32 v2, v2
	s_nop 0
	v_cndmask_b32_e64 v3, v201, -v3, vcc
	v_cmp_gt_f32_e32 vcc, s17, v3
	v_mul_f32_e32 v4, 0x4f800000, v3
	s_nop 0
	v_cndmask_b32_e32 v3, v3, v4, vcc
	v_sqrt_f32_e32 v4, v3
	s_nop 0
	v_add_u32_e32 v5, -1, v4
	v_fma_f32 v6, -v5, v4, v3
	v_cmp_ge_f32_e64 s[0:1], 0, v6
	v_add_u32_e32 v6, 1, v4
	s_nop 0
	v_cndmask_b32_e64 v5, v4, v5, s[0:1]
	v_fma_f32 v4, -v6, v4, v3
	v_cmp_lt_f32_e64 s[0:1], 0, v4
	s_nop 1
	v_cndmask_b32_e64 v4, v5, v6, s[0:1]
	v_mul_f32_e32 v5, 0x37800000, v4
	v_cndmask_b32_e32 v4, v4, v5, vcc
	v_cmp_class_f32_e32 vcc, v3, v193
	s_nop 1
	v_cndmask_b32_e32 v3, v4, v3, vcc
	v_cmp_ngt_f32_e32 vcc, s18, v0
	s_nop 1
	v_cndmask_b32_e32 v0, 1.0, v3, vcc
	v_mul_f32_e32 v0, v1, v0
	v_mul_f32_e32 v0, v55, v0
	ds_write_b32 v70, v2 offset:4224
	ds_write_b32 v70, v0 offset:41088
	v_add_f32_e32 v0, v25, v36
	v_mul_f32_e32 v0, 0xbfb8aa3b, v0
	v_exp_f32_e32 v0, v0
	v_add_f32_e32 v1, v9, v38
	v_mul_f32_e32 v1, 0xbfb8aa3b, v1
	v_exp_f32_e32 v1, v1
	v_add_f32_e32 v0, 1.0, v0
	v_rcp_f32_e32 v0, v0
	v_add_f32_e32 v1, 1.0, v1
	v_rcp_f32_e32 v1, v1
	v_mul_f32_e32 v0, v0, v32
	v_mul_f32_e32 v2, 0x3fb8aa3b, v0
	v_add_f32_e32 v0, v0, v0
	v_mul_f32_e32 v3, 0x3fb8aa3b, v0
	v_rndne_f32_e32 v3, v3
	v_fmamk_f32 v4, v3, 0xbf317218, v0
	v_fmac_f32_e32 v4, 0x3102e308, v3
	v_fmamk_f32 v5, v4, 0x395133b1, v192
	v_cmp_eq_f32_e32 vcc, s15, v3
	v_cvt_i32_f32_e32 v3, v3
	v_fmaak_f32 v5, v4, v5, 0x3c0887f9
	v_fmaak_f32 v5, v4, v5, 0x3d2aaa81
	v_fmaak_f32 v5, v4, v5, 0x3e2aaaab
	v_fma_f32 v5, v4, v5, 0.5
	v_ldexp_f32 v3, 1.0, v3
	v_mul_f32_e32 v5, v4, v5
	v_cndmask_b32_e32 v3, v3, v202, vcc
	v_fmac_f32_e32 v4, v4, v5
	v_add_f32_e32 v5, -1.0, v3
	v_fmac_f32_e32 v5, v3, v4
	v_add_f32_e32 v3, v5, v5
	v_cndmask_b32_e32 v3, v5, v3, vcc
	v_cmp_nlt_f32_e32 vcc, s16, v0
	v_exp_f32_e32 v2, v2
	s_nop 0
	v_cndmask_b32_e64 v3, v201, -v3, vcc
	v_cmp_gt_f32_e32 vcc, s17, v3
	v_mul_f32_e32 v4, 0x4f800000, v3
	s_nop 0
	v_cndmask_b32_e32 v3, v3, v4, vcc
	v_sqrt_f32_e32 v4, v3
	s_nop 0
	v_add_u32_e32 v5, -1, v4
	v_fma_f32 v6, -v5, v4, v3
	v_cmp_ge_f32_e64 s[0:1], 0, v6
	v_add_u32_e32 v6, 1, v4
	s_nop 0
	v_cndmask_b32_e64 v5, v4, v5, s[0:1]
	v_fma_f32 v4, -v6, v4, v3
	v_cmp_lt_f32_e64 s[0:1], 0, v4
	s_nop 1
	v_cndmask_b32_e64 v4, v5, v6, s[0:1]
	v_mul_f32_e32 v5, 0x37800000, v4
	v_cndmask_b32_e32 v4, v4, v5, vcc
	v_cmp_class_f32_e32 vcc, v3, v193
	s_nop 1
	v_cndmask_b32_e32 v3, v4, v3, vcc
	v_cmp_ngt_f32_e32 vcc, s18, v0
	s_nop 1
	v_cndmask_b32_e32 v0, 1.0, v3, vcc
	v_mul_f32_e32 v0, v1, v0
	v_mul_f32_e32 v0, v41, v0
	ds_write_b32 v70, v2 offset:4480
	ds_write_b32 v70, v0 offset:41344
	v_add_f32_e32 v0, v26, v36
	v_mul_f32_e32 v0, 0xbfb8aa3b, v0
	v_exp_f32_e32 v0, v0
	v_add_f32_e32 v1, v10, v38
	v_mul_f32_e32 v1, 0xbfb8aa3b, v1
	v_exp_f32_e32 v1, v1
	v_add_f32_e32 v0, 1.0, v0
	v_rcp_f32_e32 v0, v0
	v_add_f32_e32 v1, 1.0, v1
	v_rcp_f32_e32 v1, v1
	v_mul_f32_e32 v0, v0, v32
	v_mul_f32_e32 v2, 0x3fb8aa3b, v0
	v_add_f32_e32 v0, v0, v0
	v_mul_f32_e32 v3, 0x3fb8aa3b, v0
	v_rndne_f32_e32 v3, v3
	v_fmamk_f32 v4, v3, 0xbf317218, v0
	v_fmac_f32_e32 v4, 0x3102e308, v3
	v_fmamk_f32 v5, v4, 0x395133b1, v192
	v_cmp_eq_f32_e32 vcc, s15, v3
	v_cvt_i32_f32_e32 v3, v3
	v_fmaak_f32 v5, v4, v5, 0x3c0887f9
	v_fmaak_f32 v5, v4, v5, 0x3d2aaa81
	v_fmaak_f32 v5, v4, v5, 0x3e2aaaab
	v_fma_f32 v5, v4, v5, 0.5
	v_ldexp_f32 v3, 1.0, v3
	v_mul_f32_e32 v5, v4, v5
	v_cndmask_b32_e32 v3, v3, v202, vcc
	v_fmac_f32_e32 v4, v4, v5
	v_add_f32_e32 v5, -1.0, v3
	v_fmac_f32_e32 v5, v3, v4
	v_add_f32_e32 v3, v5, v5
	v_cndmask_b32_e32 v3, v5, v3, vcc
	v_cmp_nlt_f32_e32 vcc, s16, v0
	v_exp_f32_e32 v2, v2
	s_nop 0
	v_cndmask_b32_e64 v3, v201, -v3, vcc
	v_cmp_gt_f32_e32 vcc, s17, v3
	v_mul_f32_e32 v4, 0x4f800000, v3
	s_nop 0
	v_cndmask_b32_e32 v3, v3, v4, vcc
	v_sqrt_f32_e32 v4, v3
	s_nop 0
	v_add_u32_e32 v5, -1, v4
	v_fma_f32 v6, -v5, v4, v3
	v_cmp_ge_f32_e64 s[0:1], 0, v6
	v_add_u32_e32 v6, 1, v4
	s_nop 0
	v_cndmask_b32_e64 v5, v4, v5, s[0:1]
	v_fma_f32 v4, -v6, v4, v3
	v_cmp_lt_f32_e64 s[0:1], 0, v4
	s_nop 1
	v_cndmask_b32_e64 v4, v5, v6, s[0:1]
	v_mul_f32_e32 v5, 0x37800000, v4
	v_cndmask_b32_e32 v4, v4, v5, vcc
	v_cmp_class_f32_e32 vcc, v3, v193
	s_nop 1
	v_cndmask_b32_e32 v3, v4, v3, vcc
	v_cmp_ngt_f32_e32 vcc, s18, v0
	s_nop 1
	v_cndmask_b32_e32 v0, 1.0, v3, vcc
	v_mul_f32_e32 v0, v1, v0
	v_mul_f32_e32 v0, v57, v0
	ds_write_b32 v70, v2 offset:4736
	ds_write_b32 v70, v0 offset:41600
	v_add_f32_e32 v0, v27, v36
	v_mul_f32_e32 v0, 0xbfb8aa3b, v0
	v_exp_f32_e32 v0, v0
	v_add_f32_e32 v1, v11, v38
	v_mul_f32_e32 v1, 0xbfb8aa3b, v1
	v_exp_f32_e32 v1, v1
	v_add_f32_e32 v0, 1.0, v0
	v_rcp_f32_e32 v0, v0
	v_add_f32_e32 v1, 1.0, v1
	v_rcp_f32_e32 v1, v1
	v_mul_f32_e32 v0, v0, v32
	v_mul_f32_e32 v2, 0x3fb8aa3b, v0
	v_add_f32_e32 v0, v0, v0
	v_mul_f32_e32 v3, 0x3fb8aa3b, v0
	v_rndne_f32_e32 v3, v3
	v_fmamk_f32 v4, v3, 0xbf317218, v0
	v_fmac_f32_e32 v4, 0x3102e308, v3
	v_fmamk_f32 v5, v4, 0x395133b1, v192
	v_cmp_eq_f32_e32 vcc, s15, v3
	v_cvt_i32_f32_e32 v3, v3
	v_fmaak_f32 v5, v4, v5, 0x3c0887f9
	v_fmaak_f32 v5, v4, v5, 0x3d2aaa81
	v_fmaak_f32 v5, v4, v5, 0x3e2aaaab
	v_fma_f32 v5, v4, v5, 0.5
	v_ldexp_f32 v3, 1.0, v3
	v_mul_f32_e32 v5, v4, v5
	v_cndmask_b32_e32 v3, v3, v202, vcc
	v_fmac_f32_e32 v4, v4, v5
	v_add_f32_e32 v5, -1.0, v3
	v_fmac_f32_e32 v5, v3, v4
	v_add_f32_e32 v3, v5, v5
	v_cndmask_b32_e32 v3, v5, v3, vcc
	v_cmp_nlt_f32_e32 vcc, s16, v0
	v_exp_f32_e32 v2, v2
	s_nop 0
	v_cndmask_b32_e64 v3, v201, -v3, vcc
	v_cmp_gt_f32_e32 vcc, s17, v3
	v_mul_f32_e32 v4, 0x4f800000, v3
	s_nop 0
	v_cndmask_b32_e32 v3, v3, v4, vcc
	v_sqrt_f32_e32 v4, v3
	s_nop 0
	v_add_u32_e32 v5, -1, v4
	v_fma_f32 v6, -v5, v4, v3
	v_cmp_ge_f32_e64 s[0:1], 0, v6
	v_add_u32_e32 v6, 1, v4
	s_nop 0
	v_cndmask_b32_e64 v5, v4, v5, s[0:1]
	v_fma_f32 v4, -v6, v4, v3
	v_cmp_lt_f32_e64 s[0:1], 0, v4
	s_nop 1
	v_cndmask_b32_e64 v4, v5, v6, s[0:1]
	v_mul_f32_e32 v5, 0x37800000, v4
	v_cndmask_b32_e32 v4, v4, v5, vcc
	v_cmp_class_f32_e32 vcc, v3, v193
	s_nop 1
	v_cndmask_b32_e32 v3, v4, v3, vcc
	v_cmp_ngt_f32_e32 vcc, s18, v0
	s_nop 1
	v_cndmask_b32_e32 v0, 1.0, v3, vcc
	v_mul_f32_e32 v0, v1, v0
	v_mul_f32_e32 v0, v43, v0
	ds_write_b32 v70, v2 offset:4992
	ds_write_b32 v70, v0 offset:41856
	v_add_f32_e32 v0, v28, v36
	v_mul_f32_e32 v0, 0xbfb8aa3b, v0
	v_exp_f32_e32 v0, v0
	v_add_f32_e32 v1, v12, v38
	v_mul_f32_e32 v1, 0xbfb8aa3b, v1
	v_exp_f32_e32 v1, v1
	v_add_f32_e32 v0, 1.0, v0
	v_rcp_f32_e32 v0, v0
	v_add_f32_e32 v1, 1.0, v1
	v_rcp_f32_e32 v1, v1
	v_mul_f32_e32 v0, v0, v32
	v_mul_f32_e32 v2, 0x3fb8aa3b, v0
	v_add_f32_e32 v0, v0, v0
	v_mul_f32_e32 v3, 0x3fb8aa3b, v0
	v_rndne_f32_e32 v3, v3
	v_fmamk_f32 v4, v3, 0xbf317218, v0
	v_fmac_f32_e32 v4, 0x3102e308, v3
	v_fmamk_f32 v5, v4, 0x395133b1, v192
	v_cmp_eq_f32_e32 vcc, s15, v3
	v_cvt_i32_f32_e32 v3, v3
	v_fmaak_f32 v5, v4, v5, 0x3c0887f9
	v_fmaak_f32 v5, v4, v5, 0x3d2aaa81
	v_fmaak_f32 v5, v4, v5, 0x3e2aaaab
	v_fma_f32 v5, v4, v5, 0.5
	v_ldexp_f32 v3, 1.0, v3
	v_mul_f32_e32 v5, v4, v5
	v_cndmask_b32_e32 v3, v3, v202, vcc
	v_fmac_f32_e32 v4, v4, v5
	v_add_f32_e32 v5, -1.0, v3
	v_fmac_f32_e32 v5, v3, v4
	v_add_f32_e32 v3, v5, v5
	v_cndmask_b32_e32 v3, v5, v3, vcc
	v_cmp_nlt_f32_e32 vcc, s16, v0
	v_exp_f32_e32 v2, v2
	s_nop 0
	v_cndmask_b32_e64 v3, v201, -v3, vcc
	v_cmp_gt_f32_e32 vcc, s17, v3
	v_mul_f32_e32 v4, 0x4f800000, v3
	s_nop 0
	v_cndmask_b32_e32 v3, v3, v4, vcc
	v_sqrt_f32_e32 v4, v3
	s_nop 0
	v_add_u32_e32 v5, -1, v4
	v_fma_f32 v6, -v5, v4, v3
	v_cmp_ge_f32_e64 s[0:1], 0, v6
	v_add_u32_e32 v6, 1, v4
	s_nop 0
	v_cndmask_b32_e64 v5, v4, v5, s[0:1]
	v_fma_f32 v4, -v6, v4, v3
	v_cmp_lt_f32_e64 s[0:1], 0, v4
	s_nop 1
	v_cndmask_b32_e64 v4, v5, v6, s[0:1]
	v_mul_f32_e32 v5, 0x37800000, v4
	v_cndmask_b32_e32 v4, v4, v5, vcc
	v_cmp_class_f32_e32 vcc, v3, v193
	s_nop 1
	v_cndmask_b32_e32 v3, v4, v3, vcc
	v_cmp_ngt_f32_e32 vcc, s18, v0
	s_nop 1
	v_cndmask_b32_e32 v0, 1.0, v3, vcc
	v_mul_f32_e32 v0, v1, v0
	v_mul_f32_e32 v0, v59, v0
	ds_write_b32 v70, v2 offset:6272
	ds_write_b32 v70, v0 offset:43136
	v_add_f32_e32 v0, v29, v36
	v_mul_f32_e32 v0, 0xbfb8aa3b, v0
	v_exp_f32_e32 v0, v0
	v_add_f32_e32 v1, v13, v38
	v_mul_f32_e32 v1, 0xbfb8aa3b, v1
	v_exp_f32_e32 v1, v1
	v_add_f32_e32 v0, 1.0, v0
	v_rcp_f32_e32 v0, v0
	v_add_f32_e32 v1, 1.0, v1
	v_rcp_f32_e32 v1, v1
	v_mul_f32_e32 v0, v0, v32
	v_mul_f32_e32 v2, 0x3fb8aa3b, v0
	v_add_f32_e32 v0, v0, v0
	v_mul_f32_e32 v3, 0x3fb8aa3b, v0
	v_rndne_f32_e32 v3, v3
	v_fmamk_f32 v4, v3, 0xbf317218, v0
	v_fmac_f32_e32 v4, 0x3102e308, v3
	v_fmamk_f32 v5, v4, 0x395133b1, v192
	v_cmp_eq_f32_e32 vcc, s15, v3
	v_cvt_i32_f32_e32 v3, v3
	v_fmaak_f32 v5, v4, v5, 0x3c0887f9
	v_fmaak_f32 v5, v4, v5, 0x3d2aaa81
	v_fmaak_f32 v5, v4, v5, 0x3e2aaaab
	v_fma_f32 v5, v4, v5, 0.5
	v_ldexp_f32 v3, 1.0, v3
	v_mul_f32_e32 v5, v4, v5
	v_cndmask_b32_e32 v3, v3, v202, vcc
	v_fmac_f32_e32 v4, v4, v5
	v_add_f32_e32 v5, -1.0, v3
	v_fmac_f32_e32 v5, v3, v4
	v_add_f32_e32 v3, v5, v5
	v_cndmask_b32_e32 v3, v5, v3, vcc
	v_cmp_nlt_f32_e32 vcc, s16, v0
	v_exp_f32_e32 v2, v2
	s_nop 0
	v_cndmask_b32_e64 v3, v201, -v3, vcc
	v_cmp_gt_f32_e32 vcc, s17, v3
	v_mul_f32_e32 v4, 0x4f800000, v3
	s_nop 0
	v_cndmask_b32_e32 v3, v3, v4, vcc
	v_sqrt_f32_e32 v4, v3
	s_nop 0
	v_add_u32_e32 v5, -1, v4
	v_fma_f32 v6, -v5, v4, v3
	v_cmp_ge_f32_e64 s[0:1], 0, v6
	v_add_u32_e32 v6, 1, v4
	s_nop 0
	v_cndmask_b32_e64 v5, v4, v5, s[0:1]
	v_fma_f32 v4, -v6, v4, v3
	v_cmp_lt_f32_e64 s[0:1], 0, v4
	s_nop 1
	v_cndmask_b32_e64 v4, v5, v6, s[0:1]
	v_mul_f32_e32 v5, 0x37800000, v4
	v_cndmask_b32_e32 v4, v4, v5, vcc
	v_cmp_class_f32_e32 vcc, v3, v193
	s_nop 1
	v_cndmask_b32_e32 v3, v4, v3, vcc
	v_cmp_ngt_f32_e32 vcc, s18, v0
	s_nop 1
	v_cndmask_b32_e32 v0, 1.0, v3, vcc
	v_mul_f32_e32 v0, v1, v0
	v_mul_f32_e32 v0, v45, v0
	ds_write_b32 v70, v2 offset:6528
	ds_write_b32 v70, v0 offset:43392
	v_add_f32_e32 v0, v30, v36
	v_mul_f32_e32 v0, 0xbfb8aa3b, v0
	v_exp_f32_e32 v0, v0
	v_add_f32_e32 v1, v14, v38
	v_mul_f32_e32 v1, 0xbfb8aa3b, v1
	v_exp_f32_e32 v1, v1
	v_add_f32_e32 v0, 1.0, v0
	v_rcp_f32_e32 v0, v0
	v_add_f32_e32 v1, 1.0, v1
	v_rcp_f32_e32 v1, v1
	v_mul_f32_e32 v0, v0, v32
	v_mul_f32_e32 v2, 0x3fb8aa3b, v0
	v_add_f32_e32 v0, v0, v0
	v_mul_f32_e32 v3, 0x3fb8aa3b, v0
	v_rndne_f32_e32 v3, v3
	v_fmamk_f32 v4, v3, 0xbf317218, v0
	v_fmac_f32_e32 v4, 0x3102e308, v3
	v_fmamk_f32 v5, v4, 0x395133b1, v192
	v_cmp_eq_f32_e32 vcc, s15, v3
	v_cvt_i32_f32_e32 v3, v3
	v_fmaak_f32 v5, v4, v5, 0x3c0887f9
	v_fmaak_f32 v5, v4, v5, 0x3d2aaa81
	v_fmaak_f32 v5, v4, v5, 0x3e2aaaab
	v_fma_f32 v5, v4, v5, 0.5
	v_ldexp_f32 v3, 1.0, v3
	v_mul_f32_e32 v5, v4, v5
	v_cndmask_b32_e32 v3, v3, v202, vcc
	v_fmac_f32_e32 v4, v4, v5
	v_add_f32_e32 v5, -1.0, v3
	v_fmac_f32_e32 v5, v3, v4
	v_add_f32_e32 v3, v5, v5
	v_cndmask_b32_e32 v3, v5, v3, vcc
	v_cmp_nlt_f32_e32 vcc, s16, v0
	v_exp_f32_e32 v2, v2
	s_nop 0
	v_cndmask_b32_e64 v3, v201, -v3, vcc
	v_cmp_gt_f32_e32 vcc, s17, v3
	v_mul_f32_e32 v4, 0x4f800000, v3
	s_nop 0
	v_cndmask_b32_e32 v3, v3, v4, vcc
	v_sqrt_f32_e32 v4, v3
	s_nop 0
	v_add_u32_e32 v5, -1, v4
	v_fma_f32 v6, -v5, v4, v3
	v_cmp_ge_f32_e64 s[0:1], 0, v6
	v_add_u32_e32 v6, 1, v4
	s_nop 0
	v_cndmask_b32_e64 v5, v4, v5, s[0:1]
	v_fma_f32 v4, -v6, v4, v3
	v_cmp_lt_f32_e64 s[0:1], 0, v4
	s_nop 1
	v_cndmask_b32_e64 v4, v5, v6, s[0:1]
	v_mul_f32_e32 v5, 0x37800000, v4
	v_cndmask_b32_e32 v4, v4, v5, vcc
	v_cmp_class_f32_e32 vcc, v3, v193
	s_nop 1
	v_cndmask_b32_e32 v3, v4, v3, vcc
	v_cmp_ngt_f32_e32 vcc, s18, v0
	s_nop 1
	v_cndmask_b32_e32 v0, 1.0, v3, vcc
	v_mul_f32_e32 v0, v1, v0
	v_mul_f32_e32 v0, v35, v0
	v_add_u32_e32 v1, 0x1800, v70
	ds_write2_b32 v1, v2, v34 offset0:160 offset1:192
	ds_write_b32 v70, v0 offset:43648
	v_add_f32_e32 v0, v31, v36
	v_mul_f32_e32 v0, 0xbfb8aa3b, v0
	v_exp_f32_e32 v0, v0
	v_add_f32_e32 v1, v15, v38
	v_mul_f32_e32 v1, 0xbfb8aa3b, v1
	v_exp_f32_e32 v1, v1
	v_add_f32_e32 v0, 1.0, v0
	v_rcp_f32_e32 v0, v0
	v_add_f32_e32 v1, 1.0, v1
	v_rcp_f32_e32 v1, v1
	v_mul_f32_e32 v0, v0, v32
	v_mul_f32_e32 v2, 0x3fb8aa3b, v0
	v_add_f32_e32 v0, v0, v0
	v_mul_f32_e32 v3, 0x3fb8aa3b, v0
	v_rndne_f32_e32 v3, v3
	v_fmamk_f32 v4, v3, 0xbf317218, v0
	v_fmac_f32_e32 v4, 0x3102e308, v3
	v_fmamk_f32 v5, v4, 0x395133b1, v192
	v_cmp_eq_f32_e32 vcc, s15, v3
	v_cvt_i32_f32_e32 v3, v3
	v_fmaak_f32 v5, v4, v5, 0x3c0887f9
	v_fmaak_f32 v5, v4, v5, 0x3d2aaa81
	v_fmaak_f32 v5, v4, v5, 0x3e2aaaab
	v_fma_f32 v5, v4, v5, 0.5
	v_ldexp_f32 v3, 1.0, v3
	v_mul_f32_e32 v5, v4, v5
	v_cndmask_b32_e32 v3, v3, v202, vcc
	v_fmac_f32_e32 v4, v4, v5
	v_add_f32_e32 v5, -1.0, v3
	v_fmac_f32_e32 v5, v3, v4
	v_add_f32_e32 v3, v5, v5
	v_cndmask_b32_e32 v3, v5, v3, vcc
	v_cmp_nlt_f32_e32 vcc, s16, v0
	v_exp_f32_e32 v2, v2
	s_nop 0
	v_cndmask_b32_e64 v3, v201, -v3, vcc
	v_cmp_gt_f32_e32 vcc, s17, v3
	v_mul_f32_e32 v4, 0x4f800000, v3
	s_nop 0
	v_cndmask_b32_e32 v3, v3, v4, vcc
	v_sqrt_f32_e32 v4, v3
	s_nop 0
	v_add_u32_e32 v5, -1, v4
	v_fma_f32 v6, -v5, v4, v3
	v_cmp_ge_f32_e64 s[0:1], 0, v6
	v_add_u32_e32 v6, 1, v4
	s_nop 0
	v_cndmask_b32_e64 v5, v4, v5, s[0:1]
	v_fma_f32 v4, -v6, v4, v3
	v_cmp_lt_f32_e64 s[0:1], 0, v4
	s_nop 1
	v_cndmask_b32_e64 v4, v5, v6, s[0:1]
	v_mul_f32_e32 v5, 0x37800000, v4
	v_cndmask_b32_e32 v4, v4, v5, vcc
	v_cmp_class_f32_e32 vcc, v3, v193
	v_mov_b32_e32 v6, 1.0
	s_mov_b32 s0, 24
	v_cndmask_b32_e32 v3, v4, v3, vcc
	v_cmp_ngt_f32_e32 vcc, s18, v0
	s_nop 1
	v_cndmask_b32_e32 v0, 1.0, v3, vcc
	v_mul_f32_e32 v0, v1, v0
	v_mul_f32_e32 v0, v33, v0
	ds_write_b32 v70, v2 offset:7040
	ds_write_b32 v70, v0 offset:43904
	v_mov_b32_e32 v2, v162
	s_waitcnt lgkmcnt(0)
	s_barrier
	s_cselect_b64 vcc, -1, 0
	v_and_b32_e32 v3, 63, v2
	v_ashrrev_i32_e32 v4, 6, v2
	v_lshl_or_b32 v5, v4, 11, v3
	v_mov_b32_e32 v1, 0

.LBB0_634:
	v_and_b32_e32 v12, 0x7e, v1
	v_ashrrev_i32_e32 v13, 3, v0
	v_mul_u32_u24_e32 v96, 0x3600, v12
	v_and_b32_e32 v10, -8, v13
	v_lshl_add_u64 v[2:3], s[6:7], 0, v[96:97]
	v_ashrrev_i32_e32 v11, 31, v10
	v_lshl_add_u64 v[6:7], v[10:11], 1, v[2:3]
	global_load_dwordx4 v[2:5], v[6:7], off offset:3072
	v_add_co_u32_e32 v6, vcc, s8, v6
	v_lshl_add_u32 v12, v12, 1, 0
	s_nop 0
	v_addc_co_u32_e32 v7, vcc, 0, v7, vcc
	s_waitcnt lgkmcnt(8)
	global_load_dwordx4 v[6:9], v[6:7], off offset:512
	v_add_u32_e32 v16, 0x100, v0
	v_add_u32_e32 v17, 0x200, v1
	v_and_b32_e32 v28, 0x7e, v17
	v_ashrrev_i32_e32 v29, 3, v16
	v_mul_u32_u24_e32 v96, 0x3600, v28
	v_and_b32_e32 v26, -8, v29
	v_lshl_add_u64 v[18:19], s[6:7], 0, v[96:97]
	v_ashrrev_i32_e32 v27, 31, v26
	v_lshl_add_u64 v[22:23], v[26:27], 1, v[18:19]
	global_load_dwordx4 v[18:21], v[22:23], off offset:3072
	v_add_co_u32_e32 v22, vcc, s8, v22
	v_lshl_add_u32 v28, v28, 1, 0
	s_nop 0
	v_addc_co_u32_e32 v23, vcc, 0, v23, vcc
	global_load_dwordx4 v[22:25], v[22:23], off offset:512
	v_add_u32_e32 v32, 0x200, v0
	v_add_u32_e32 v33, 0x400, v1
	v_and_b32_e32 v44, 0x7e, v33
	v_ashrrev_i32_e32 v45, 3, v32
	v_mul_u32_u24_e32 v96, 0x3600, v44
	v_and_b32_e32 v42, -8, v45
	v_lshl_add_u64 v[34:35], s[6:7], 0, v[96:97]
	v_ashrrev_i32_e32 v43, 31, v42
	v_lshl_add_u64 v[38:39], v[42:43], 1, v[34:35]
	global_load_dwordx4 v[34:37], v[38:39], off offset:3072
	v_add_co_u32_e32 v38, vcc, s8, v38
	v_lshl_add_u32 v44, v44, 1, 0
	s_nop 0
	v_addc_co_u32_e32 v39, vcc, 0, v39, vcc
	global_load_dwordx4 v[38:41], v[38:39], off offset:512
	v_add_u32_e32 v48, 0x300, v0
	v_add_u32_e32 v49, 0x600, v1
	v_and_b32_e32 v60, 0x7e, v49
	v_ashrrev_i32_e32 v61, 3, v48
	v_mul_u32_u24_e32 v96, 0x3600, v60
	v_and_b32_e32 v58, -8, v61
	v_lshl_add_u64 v[50:51], s[6:7], 0, v[96:97]
	v_ashrrev_i32_e32 v59, 31, v58
	v_lshl_add_u64 v[54:55], v[58:59], 1, v[50:51]
	global_load_dwordx4 v[50:53], v[54:55], off offset:3072
	v_add_co_u32_e32 v54, vcc, s8, v54
	v_lshl_add_u32 v60, v60, 1, 0
	s_nop 0
	v_addc_co_u32_e32 v55, vcc, 0, v55, vcc
	global_load_dwordx4 v[54:57], v[54:55], off offset:512
	s_waitcnt vmcnt(7)
	v_and_b32_e32 v11, 0xffff, v2
	v_lshrrev_b32_e32 v2, 16, v2
	s_waitcnt vmcnt(6)
	v_lshl_or_b32 v14, v6, 16, v11
	v_mad_u64_u32 v[10:11], s[38:39], v10, s87, v[12:13]
	v_and_or_b32 v2, v6, s79, v2
	v_add_u32_e32 v6, 0x8800, v10
	ds_write2_b32 v6, v14, v2 offset1:68
	v_and_b32_e32 v2, 0xffff, v3
	v_lshrrev_b32_e32 v3, 16, v3
	v_lshl_or_b32 v2, v7, 16, v2
	v_and_or_b32 v3, v7, s79, v3
	ds_write2_b32 v6, v2, v3 offset0:136 offset1:204
	v_and_b32_e32 v2, 0xffff, v4
	v_lshrrev_b32_e32 v3, 16, v4
	v_lshl_or_b32 v2, v8, 16, v2
	v_and_or_b32 v3, v8, s79, v3
	v_add_u32_e32 v4, 0x8c00, v10
	ds_write2_b32 v4, v2, v3 offset0:16 offset1:84
	v_and_b32_e32 v2, 0xffff, v5
	v_lshl_or_b32 v2, v9, 16, v2
	ds_write_b32 v10, v2 offset:36448
	v_lshrrev_b32_e32 v2, 16, v5
	v_and_or_b32 v4, v9, s79, v2
	v_or_b32_e32 v2, 7, v13
	v_mad_u64_u32 v[2:3], s[38:39], v2, s87, v[12:13]
	ds_write_b32 v2, v4 offset:34816
	s_waitcnt vmcnt(5)
	v_and_b32_e32 v27, 0xffff, v18
	v_lshrrev_b32_e32 v18, 16, v18
	s_waitcnt vmcnt(4)
	v_lshl_or_b32 v30, v22, 16, v27
	v_mad_u64_u32 v[26:27], s[38:39], v26, s87, v[28:29]
	v_and_or_b32 v18, v22, s79, v18
	v_add_u32_e32 v22, 0x8800, v26
	ds_write2_b32 v22, v30, v18 offset1:68
	v_and_b32_e32 v18, 0xffff, v19
	v_lshrrev_b32_e32 v19, 16, v19
	v_lshl_or_b32 v18, v23, 16, v18
	v_and_or_b32 v19, v23, s79, v19
	ds_write2_b32 v22, v18, v19 offset0:136 offset1:204
	v_and_b32_e32 v18, 0xffff, v20
	v_lshrrev_b32_e32 v19, 16, v20
	v_lshl_or_b32 v18, v24, 16, v18
	v_and_or_b32 v19, v24, s79, v19
	v_add_u32_e32 v20, 0x8c00, v26
	ds_write2_b32 v20, v18, v19 offset0:16 offset1:84
	v_and_b32_e32 v18, 0xffff, v21
	v_lshl_or_b32 v18, v25, 16, v18
	ds_write_b32 v26, v18 offset:36448
	v_lshrrev_b32_e32 v18, 16, v21
	v_and_or_b32 v20, v25, s79, v18
	v_or_b32_e32 v18, 7, v29
	v_mad_u64_u32 v[18:19], s[38:39], v18, s87, v[28:29]
	ds_write_b32 v18, v20 offset:34816
	s_waitcnt vmcnt(3)
	v_and_b32_e32 v43, 0xffff, v34
	v_lshrrev_b32_e32 v34, 16, v34
	s_waitcnt vmcnt(2)
	v_lshl_or_b32 v46, v38, 16, v43
	v_mad_u64_u32 v[42:43], s[38:39], v42, s87, v[44:45]
	v_and_or_b32 v34, v38, s79, v34
	v_add_u32_e32 v38, 0x8800, v42
	ds_write2_b32 v38, v46, v34 offset1:68
	v_and_b32_e32 v34, 0xffff, v35
	v_lshrrev_b32_e32 v35, 16, v35
	v_lshl_or_b32 v34, v39, 16, v34
	v_and_or_b32 v35, v39, s79, v35
	ds_write2_b32 v38, v34, v35 offset0:136 offset1:204
	v_and_b32_e32 v34, 0xffff, v36
	v_lshrrev_b32_e32 v35, 16, v36
	v_lshl_or_b32 v34, v40, 16, v34
	v_and_or_b32 v35, v40, s79, v35
	v_add_u32_e32 v36, 0x8c00, v42
	ds_write2_b32 v36, v34, v35 offset0:16 offset1:84
	v_and_b32_e32 v34, 0xffff, v37
	v_lshl_or_b32 v34, v41, 16, v34
	ds_write_b32 v42, v34 offset:36448
	v_lshrrev_b32_e32 v34, 16, v37
	v_and_or_b32 v36, v41, s79, v34
	v_or_b32_e32 v34, 7, v45
	v_mad_u64_u32 v[34:35], s[38:39], v34, s87, v[44:45]
	ds_write_b32 v34, v36 offset:34816
	s_waitcnt vmcnt(1)
	v_and_b32_e32 v59, 0xffff, v50
	v_lshrrev_b32_e32 v50, 16, v50
	s_waitcnt vmcnt(0)
	v_lshl_or_b32 v62, v54, 16, v59
	v_mad_u64_u32 v[58:59], s[38:39], v58, s87, v[60:61]
	v_and_or_b32 v50, v54, s79, v50
	v_add_u32_e32 v54, 0x8800, v58
	ds_write2_b32 v54, v62, v50 offset1:68
	v_and_b32_e32 v50, 0xffff, v51
	v_lshrrev_b32_e32 v51, 16, v51
	v_lshl_or_b32 v50, v55, 16, v50
	v_and_or_b32 v51, v55, s79, v51
	ds_write2_b32 v54, v50, v51 offset0:136 offset1:204
	v_and_b32_e32 v50, 0xffff, v52
	v_lshrrev_b32_e32 v51, 16, v52
	v_lshl_or_b32 v50, v56, 16, v50
	v_and_or_b32 v51, v56, s79, v51
	v_add_u32_e32 v52, 0x8c00, v58
	ds_write2_b32 v52, v50, v51 offset0:16 offset1:84
	v_and_b32_e32 v50, 0xffff, v53
	v_lshl_or_b32 v50, v57, 16, v50
	ds_write_b32 v58, v50 offset:36448
	v_lshrrev_b32_e32 v50, 16, v53
	v_and_or_b32 v52, v57, s79, v50
	v_or_b32_e32 v50, 7, v61
	v_mad_u64_u32 v[50:51], s[38:39], v50, s87, v[60:61]
	ds_write_b32 v50, v52 offset:34816
	s_mov_b64 s[12:13], exec

.LBB0_636:
	s_waitcnt vmcnt(3)
	v_add_u32_e32 v82, v69, v67
	ds_read_b128 v[70:73], v69 offset:34816
	ds_read_b128 v[74:77], v82
	s_add_i32 s0, s0, 32
	s_cmpk_lt_u32 s0, 0x70
	s_waitcnt lgkmcnt(0)
	v_mfma_f32_32x32x16_bf16 v[48:63], v[74:77], v[70:73], v[48:63]
	ds_read_b128 v[70:73], v69 offset:43520
	s_waitcnt lgkmcnt(0)
	v_mfma_f32_32x32x16_bf16 v[32:47], v[74:77], v[70:73], v[32:47]
	ds_read_b128 v[70:73], v69 offset:52224
	s_waitcnt lgkmcnt(0)
	v_mfma_f32_32x32x16_bf16 v[16:31], v[74:77], v[70:73], v[16:31]
	ds_read_b128 v[70:73], v69 offset:60928
	ds_read_b128 v[78:81], v69 offset:34848
	s_waitcnt lgkmcnt(1)
	v_mfma_f32_32x32x16_bf16 v[0:15], v[74:77], v[70:73], v[0:15]
	ds_read_b128 v[70:73], v82 offset:32
	ds_read_b128 v[74:77], v69 offset:43552
	s_waitcnt lgkmcnt(0)
	v_mfma_f32_32x32x16_bf16 v[32:47], v[70:73], v[74:77], v[32:47]
	ds_read_b128 v[74:77], v69 offset:52256
	s_waitcnt lgkmcnt(0)
	v_mfma_f32_32x32x16_bf16 v[16:31], v[70:73], v[74:77], v[16:31]
	ds_read_b128 v[74:77], v69 offset:60960
	v_add_u32_e32 v69, 64, v69
	v_mfma_f32_32x32x16_bf16 v[48:63], v[70:73], v[78:81], v[48:63]
	s_waitcnt lgkmcnt(0)
	v_mfma_f32_32x32x16_bf16 v[0:15], v[70:73], v[74:77], v[0:15]
	s_cbranch_scc1 .LBB0_636
	v_lshrrev_b32_e32 v67, 3, v65
	s_ashr_i32 s3, s2, 31
	v_and_or_b32 v66, v67, 4, v66
	s_lshl_b64 s[0:1], s[2:3], 16
	v_lshlrev_b32_e32 v69, 7, v66
	s_add_u32 s0, s56, s0
	v_or_b32_e32 v66, v69, v68
	s_addc_u32 s1, s57, s1
	v_ashrrev_i32_e32 v67, 31, v66
	v_mul_f32_e32 v48, 0x3db504f3, v48
	v_lshl_add_u64 v[70:71], v[66:67], 2, s[0:1]
	v_ashrrev_i32_e32 v67, 31, v69
	global_store_dword v[70:71], v48, off
	v_mul_f32_e32 v70, 0x3db504f3, v49
	v_lshl_add_u64 v[48:49], v[66:67], 2, s[0:1]
	v_mul_f32_e32 v50, 0x3db504f3, v50
	global_store_dword v[48:49], v70, off offset:512
	global_store_dword v[48:49], v50, off offset:1024
	v_mul_f32_e32 v50, 0x3db504f3, v51
	v_or_b32_e32 v70, 0x400, v69
	global_store_dword v[48:49], v50, off offset:1536
	v_or_b32_e32 v50, v70, v68
	v_ashrrev_i32_e32 v51, 31, v50
	v_mul_f32_e32 v52, 0x3db504f3, v52
	v_lshl_add_u64 v[50:51], v[50:51], 2, s[0:1]
	global_store_dword v[50:51], v52, off
	v_mul_f32_e32 v52, 0x3db504f3, v53
	v_or_b32_e32 v53, 0x480, v69
	v_or_b32_e32 v50, v53, v68
	v_ashrrev_i32_e32 v51, 31, v50
	v_lshl_add_u64 v[50:51], v[50:51], 2, s[0:1]
	global_store_dword v[50:51], v52, off
	v_mul_f32_e32 v52, 0x3db504f3, v54
	v_or_b32_e32 v54, 0x500, v69
	v_or_b32_e32 v50, v54, v68
	v_ashrrev_i32_e32 v51, 31, v50
	v_lshl_add_u64 v[50:51], v[50:51], 2, s[0:1]
	global_store_dword v[50:51], v52, off
	v_mul_f32_e32 v52, 0x3db504f3, v55
	v_or_b32_e32 v55, 0x580, v69
	v_or_b32_e32 v50, v55, v68
	v_ashrrev_i32_e32 v51, 31, v50
	v_lshl_add_u64 v[50:51], v[50:51], 2, s[0:1]
	global_store_dword v[50:51], v52, off
	v_mul_f32_e32 v52, 0x3db504f3, v56
	v_or_b32_e32 v56, 0x800, v69
	v_or_b32_e32 v50, v56, v68
	v_ashrrev_i32_e32 v51, 31, v50
	v_lshl_add_u64 v[50:51], v[50:51], 2, s[0:1]
	global_store_dword v[50:51], v52, off
	v_mul_f32_e32 v52, 0x3db504f3, v57
	v_or_b32_e32 v57, 0x880, v69
	v_or_b32_e32 v50, v57, v68
	v_ashrrev_i32_e32 v51, 31, v50
	v_lshl_add_u64 v[50:51], v[50:51], 2, s[0:1]
	global_store_dword v[50:51], v52, off
	v_mul_f32_e32 v52, 0x3db504f3, v58
	v_or_b32_e32 v58, 0x900, v69
	v_or_b32_e32 v50, v58, v68
	v_ashrrev_i32_e32 v51, 31, v50
	v_lshl_add_u64 v[50:51], v[50:51], 2, s[0:1]
	global_store_dword v[50:51], v52, off
	v_mul_f32_e32 v52, 0x3db504f3, v59
	v_or_b32_e32 v59, 0x980, v69
	v_or_b32_e32 v50, v59, v68
	v_ashrrev_i32_e32 v51, 31, v50
	v_lshl_add_u64 v[50:51], v[50:51], 2, s[0:1]
	global_store_dword v[50:51], v52, off
	v_mul_f32_e32 v52, 0x3db504f3, v60
	v_or_b32_e32 v60, 0xc00, v69
	v_or_b32_e32 v50, v60, v68
	v_ashrrev_i32_e32 v51, 31, v50
	v_lshl_add_u64 v[50:51], v[50:51], 2, s[0:1]
	global_store_dword v[50:51], v52, off
	v_mul_f32_e32 v52, 0x3db504f3, v61
	v_or_b32_e32 v61, 0xc80, v69
	v_or_b32_e32 v50, v61, v68
	v_ashrrev_i32_e32 v51, 31, v50
	v_lshl_add_u64 v[50:51], v[50:51], 2, s[0:1]
	global_store_dword v[50:51], v52, off
	v_mul_f32_e32 v52, 0x3db504f3, v62
	v_or_b32_e32 v62, 0xd00, v69
	v_or_b32_e32 v50, v62, v68
	v_ashrrev_i32_e32 v51, 31, v50
	v_lshl_add_u64 v[50:51], v[50:51], 2, s[0:1]
	global_store_dword v[50:51], v52, off
	v_mul_f32_e32 v52, 0x3db504f3, v63
	v_or_b32_e32 v63, 0xd80, v69
	v_or_b32_e32 v50, v63, v68
	v_ashrrev_i32_e32 v51, 31, v50
	v_lshl_add_u64 v[50:51], v[50:51], 2, s[0:1]
	global_store_dword v[50:51], v52, off
	v_or_b32_e32 v50, 32, v68
	v_mul_f32_e32 v32, 0x3db504f3, v32
	v_or_b32_e32 v66, v69, v50
	global_store_dword v[48:49], v32, off offset:128
	v_mul_f32_e32 v51, 0x3db504f3, v33
	v_lshl_add_u64 v[32:33], v[66:67], 2, s[0:1]
	v_mul_f32_e32 v34, 0x3db504f3, v34
	global_store_dword v[32:33], v34, off offset:1024
	v_mul_f32_e32 v34, 0x3db504f3, v35
	global_store_dword v[32:33], v51, off offset:512
	global_store_dword v[32:33], v34, off offset:1536
	v_or_b32_e32 v32, v70, v50
	v_ashrrev_i32_e32 v33, 31, v32
	v_mul_f32_e32 v34, 0x3db504f3, v36
	v_lshl_add_u64 v[32:33], v[32:33], 2, s[0:1]
	global_store_dword v[32:33], v34, off
	v_or_b32_e32 v32, v53, v50
	v_ashrrev_i32_e32 v33, 31, v32
	v_mul_f32_e32 v34, 0x3db504f3, v37
	v_lshl_add_u64 v[32:33], v[32:33], 2, s[0:1]
	global_store_dword v[32:33], v34, off
	v_or_b32_e32 v32, v54, v50
	v_ashrrev_i32_e32 v33, 31, v32
	v_mul_f32_e32 v34, 0x3db504f3, v38
	v_lshl_add_u64 v[32:33], v[32:33], 2, s[0:1]
	global_store_dword v[32:33], v34, off
	v_or_b32_e32 v32, v55, v50
	v_ashrrev_i32_e32 v33, 31, v32
	v_mul_f32_e32 v34, 0x3db504f3, v39
	v_lshl_add_u64 v[32:33], v[32:33], 2, s[0:1]
	global_store_dword v[32:33], v34, off
	v_or_b32_e32 v32, v56, v50
	v_ashrrev_i32_e32 v33, 31, v32
	v_mul_f32_e32 v34, 0x3db504f3, v40
	v_lshl_add_u64 v[32:33], v[32:33], 2, s[0:1]
	global_store_dword v[32:33], v34, off
	v_or_b32_e32 v32, v57, v50
	v_ashrrev_i32_e32 v33, 31, v32
	v_mul_f32_e32 v34, 0x3db504f3, v41
	v_lshl_add_u64 v[32:33], v[32:33], 2, s[0:1]
	global_store_dword v[32:33], v34, off
	v_or_b32_e32 v32, v58, v50
	v_ashrrev_i32_e32 v33, 31, v32
	v_mul_f32_e32 v34, 0x3db504f3, v42
	v_lshl_add_u64 v[32:33], v[32:33], 2, s[0:1]
	global_store_dword v[32:33], v34, off
	v_or_b32_e32 v32, v59, v50
	v_ashrrev_i32_e32 v33, 31, v32
	v_mul_f32_e32 v34, 0x3db504f3, v43
	v_lshl_add_u64 v[32:33], v[32:33], 2, s[0:1]
	global_store_dword v[32:33], v34, off
	v_or_b32_e32 v32, v60, v50
	v_ashrrev_i32_e32 v33, 31, v32
	v_mul_f32_e32 v34, 0x3db504f3, v44
	v_lshl_add_u64 v[32:33], v[32:33], 2, s[0:1]
	global_store_dword v[32:33], v34, off
	v_or_b32_e32 v32, v61, v50
	v_ashrrev_i32_e32 v33, 31, v32
	v_mul_f32_e32 v34, 0x3db504f3, v45
	v_lshl_add_u64 v[32:33], v[32:33], 2, s[0:1]
	global_store_dword v[32:33], v34, off
	v_or_b32_e32 v32, v62, v50
	v_ashrrev_i32_e32 v33, 31, v32
	v_mul_f32_e32 v34, 0x3db504f3, v46
	v_lshl_add_u64 v[32:33], v[32:33], 2, s[0:1]
	global_store_dword v[32:33], v34, off
	v_or_b32_e32 v32, v63, v50
	v_ashrrev_i32_e32 v33, 31, v32
	v_mul_f32_e32 v34, 0x3db504f3, v47
	v_lshl_add_u64 v[32:33], v[32:33], 2, s[0:1]
	global_store_dword v[32:33], v34, off
	v_or_b32_e32 v32, 64, v68
	v_mul_f32_e32 v16, 0x3db504f3, v16
	v_or_b32_e32 v66, v69, v32
	global_store_dword v[48:49], v16, off offset:256
	v_mul_f32_e32 v33, 0x3db504f3, v17
	v_lshl_add_u64 v[16:17], v[66:67], 2, s[0:1]
	v_mul_f32_e32 v18, 0x3db504f3, v18
	global_store_dword v[16:17], v18, off offset:1024
	v_mul_f32_e32 v18, 0x3db504f3, v19
	global_store_dword v[16:17], v33, off offset:512
	global_store_dword v[16:17], v18, off offset:1536
	v_or_b32_e32 v16, v70, v32
	v_ashrrev_i32_e32 v17, 31, v16
	v_mul_f32_e32 v18, 0x3db504f3, v20
	v_lshl_add_u64 v[16:17], v[16:17], 2, s[0:1]
	global_store_dword v[16:17], v18, off
	v_or_b32_e32 v16, v53, v32
	v_ashrrev_i32_e32 v17, 31, v16
	v_mul_f32_e32 v18, 0x3db504f3, v21
	v_lshl_add_u64 v[16:17], v[16:17], 2, s[0:1]
	global_store_dword v[16:17], v18, off
	v_or_b32_e32 v16, v54, v32
	v_ashrrev_i32_e32 v17, 31, v16
	v_mul_f32_e32 v18, 0x3db504f3, v22
	v_lshl_add_u64 v[16:17], v[16:17], 2, s[0:1]
	global_store_dword v[16:17], v18, off
	v_or_b32_e32 v16, v55, v32
	v_ashrrev_i32_e32 v17, 31, v16
	v_mul_f32_e32 v18, 0x3db504f3, v23
	v_lshl_add_u64 v[16:17], v[16:17], 2, s[0:1]
	global_store_dword v[16:17], v18, off
	v_or_b32_e32 v16, v56, v32
	v_ashrrev_i32_e32 v17, 31, v16
	v_mul_f32_e32 v18, 0x3db504f3, v24
	v_lshl_add_u64 v[16:17], v[16:17], 2, s[0:1]
	global_store_dword v[16:17], v18, off
	v_or_b32_e32 v16, v57, v32
	v_ashrrev_i32_e32 v17, 31, v16
	v_mul_f32_e32 v18, 0x3db504f3, v25
	v_lshl_add_u64 v[16:17], v[16:17], 2, s[0:1]
	global_store_dword v[16:17], v18, off
	v_or_b32_e32 v16, v58, v32
	v_ashrrev_i32_e32 v17, 31, v16
	v_mul_f32_e32 v18, 0x3db504f3, v26
	v_lshl_add_u64 v[16:17], v[16:17], 2, s[0:1]
	global_store_dword v[16:17], v18, off
	v_or_b32_e32 v16, v59, v32
	v_ashrrev_i32_e32 v17, 31, v16
	v_mul_f32_e32 v18, 0x3db504f3, v27
	v_lshl_add_u64 v[16:17], v[16:17], 2, s[0:1]
	global_store_dword v[16:17], v18, off
	v_or_b32_e32 v16, v60, v32
	v_ashrrev_i32_e32 v17, 31, v16
	v_mul_f32_e32 v18, 0x3db504f3, v28
	v_lshl_add_u64 v[16:17], v[16:17], 2, s[0:1]
	global_store_dword v[16:17], v18, off
	v_or_b32_e32 v16, v61, v32
	v_ashrrev_i32_e32 v17, 31, v16
	v_mul_f32_e32 v18, 0x3db504f3, v29
	v_lshl_add_u64 v[16:17], v[16:17], 2, s[0:1]
	global_store_dword v[16:17], v18, off
	v_or_b32_e32 v16, v62, v32
	v_ashrrev_i32_e32 v17, 31, v16
	v_mul_f32_e32 v18, 0x3db504f3, v30
	v_lshl_add_u64 v[16:17], v[16:17], 2, s[0:1]
	global_store_dword v[16:17], v18, off
	v_or_b32_e32 v16, v63, v32
	v_ashrrev_i32_e32 v17, 31, v16
	v_mul_f32_e32 v18, 0x3db504f3, v31
	v_lshl_add_u64 v[16:17], v[16:17], 2, s[0:1]
	global_store_dword v[16:17], v18, off
	v_or_b32_e32 v16, 0x60, v68
	v_mul_f32_e32 v0, 0x3db504f3, v0
	v_or_b32_e32 v66, v69, v16
	global_store_dword v[48:49], v0, off offset:384
	v_mul_f32_e32 v17, 0x3db504f3, v1
	v_lshl_add_u64 v[0:1], v[66:67], 2, s[0:1]
	v_mul_f32_e32 v2, 0x3db504f3, v2
	global_store_dword v[0:1], v2, off offset:1024
	v_mul_f32_e32 v2, 0x3db504f3, v3
	global_store_dword v[0:1], v17, off offset:512
	global_store_dword v[0:1], v2, off offset:1536
	v_or_b32_e32 v0, v70, v16
	v_ashrrev_i32_e32 v1, 31, v0
	v_mul_f32_e32 v2, 0x3db504f3, v4
	v_lshl_add_u64 v[0:1], v[0:1], 2, s[0:1]
	global_store_dword v[0:1], v2, off
	v_or_b32_e32 v0, v53, v16
	v_ashrrev_i32_e32 v1, 31, v0
	v_mul_f32_e32 v2, 0x3db504f3, v5
	v_lshl_add_u64 v[0:1], v[0:1], 2, s[0:1]
	global_store_dword v[0:1], v2, off
	v_or_b32_e32 v0, v54, v16
	v_ashrrev_i32_e32 v1, 31, v0
	v_mul_f32_e32 v2, 0x3db504f3, v6
	v_lshl_add_u64 v[0:1], v[0:1], 2, s[0:1]
	global_store_dword v[0:1], v2, off
	v_or_b32_e32 v0, v55, v16
	v_ashrrev_i32_e32 v1, 31, v0
	v_mul_f32_e32 v2, 0x3db504f3, v7
	v_lshl_add_u64 v[0:1], v[0:1], 2, s[0:1]
	global_store_dword v[0:1], v2, off
	v_or_b32_e32 v0, v56, v16
	v_ashrrev_i32_e32 v1, 31, v0
	v_mul_f32_e32 v2, 0x3db504f3, v8
	v_lshl_add_u64 v[0:1], v[0:1], 2, s[0:1]
	global_store_dword v[0:1], v2, off
	v_or_b32_e32 v0, v57, v16
	v_ashrrev_i32_e32 v1, 31, v0
	v_mul_f32_e32 v2, 0x3db504f3, v9
	v_lshl_add_u64 v[0:1], v[0:1], 2, s[0:1]
	global_store_dword v[0:1], v2, off
	v_or_b32_e32 v0, v58, v16
	v_ashrrev_i32_e32 v1, 31, v0
	v_mul_f32_e32 v2, 0x3db504f3, v10
	v_lshl_add_u64 v[0:1], v[0:1], 2, s[0:1]
	global_store_dword v[0:1], v2, off
	v_or_b32_e32 v0, v59, v16
	v_ashrrev_i32_e32 v1, 31, v0
	v_mul_f32_e32 v2, 0x3db504f3, v11
	v_lshl_add_u64 v[0:1], v[0:1], 2, s[0:1]
	global_store_dword v[0:1], v2, off
	v_or_b32_e32 v0, v60, v16
	v_ashrrev_i32_e32 v1, 31, v0
	v_mul_f32_e32 v2, 0x3db504f3, v12
	v_lshl_add_u64 v[0:1], v[0:1], 2, s[0:1]
	global_store_dword v[0:1], v2, off
	v_or_b32_e32 v0, v61, v16
	v_ashrrev_i32_e32 v1, 31, v0
	v_mul_f32_e32 v2, 0x3db504f3, v13
	v_lshl_add_u64 v[0:1], v[0:1], 2, s[0:1]
	global_store_dword v[0:1], v2, off
	v_or_b32_e32 v0, v62, v16
	v_ashrrev_i32_e32 v1, 31, v0
	v_mul_f32_e32 v2, 0x3db504f3, v14
	v_lshl_add_u64 v[0:1], v[0:1], 2, s[0:1]
	global_store_dword v[0:1], v2, off
	v_or_b32_e32 v0, v63, v16
	v_ashrrev_i32_e32 v1, 31, v0
	v_mul_f32_e32 v2, 0x3db504f3, v15
	v_lshl_add_u64 v[0:1], v[0:1], 2, s[0:1]
	v_and_b32_e32 v4, 1, v65
	global_store_dword v[0:1], v2, off
	v_mul_lo_u32 v0, v64, s87
	v_lshlrev_b32_e32 v1, 7, v4
	v_add3_u32 v7, 0, v0, v1
	v_lshl_add_u32 v6, v4, 8, 0
	ds_read_b128 v[8:11], v7 offset:34816
	ds_read_b128 v[12:15], v7 offset:34832
	ds_read_b128 v[16:19], v7 offset:34848
	ds_read_b128 v[0:3], v7 offset:34864
	v_add_u32_e32 v6, 0x11600, v6
	ds_read_b128 v[20:23], v6
	ds_read_b128 v[24:27], v6 offset:16
	ds_read_b128 v[28:31], v6 offset:32
	ds_read_b128 v[32:35], v6 offset:48
	s_waitcnt lgkmcnt(7)
	v_lshlrev_b32_e32 v5, 16, v8
	s_waitcnt lgkmcnt(3)
	v_fma_f32 v5, v20, v5, 0
	v_and_b32_e32 v8, 0xffff0000, v8
	v_fmac_f32_e32 v5, v21, v8
	v_lshlrev_b32_e32 v8, 16, v9
	v_fmac_f32_e32 v5, v22, v8
	v_and_b32_e32 v8, 0xffff0000, v9
	v_fmac_f32_e32 v5, v23, v8
	v_lshlrev_b32_e32 v8, 16, v10
	s_waitcnt lgkmcnt(2)
	v_fmac_f32_e32 v5, v24, v8
	v_and_b32_e32 v8, 0xffff0000, v10
	v_fmac_f32_e32 v5, v25, v8
	v_lshlrev_b32_e32 v8, 16, v11
	v_fmac_f32_e32 v5, v26, v8
	v_and_b32_e32 v8, 0xffff0000, v11
	v_fmac_f32_e32 v5, v27, v8
	v_lshlrev_b32_e32 v8, 16, v12
	s_waitcnt lgkmcnt(1)
	v_fmac_f32_e32 v5, v28, v8
	v_and_b32_e32 v8, 0xffff0000, v12
	v_fmac_f32_e32 v5, v29, v8
	v_lshlrev_b32_e32 v8, 16, v13
	v_fmac_f32_e32 v5, v30, v8
	v_and_b32_e32 v8, 0xffff0000, v13
	v_fmac_f32_e32 v5, v31, v8
	v_lshlrev_b32_e32 v8, 16, v14
	s_waitcnt lgkmcnt(0)
	v_fmac_f32_e32 v5, v32, v8
	v_and_b32_e32 v8, 0xffff0000, v14
	v_fmac_f32_e32 v5, v33, v8
	v_lshlrev_b32_e32 v8, 16, v15
	v_fmac_f32_e32 v5, v34, v8
	v_and_b32_e32 v8, 0xffff0000, v15
	v_fmac_f32_e32 v5, v35, v8
	ds_read_b128 v[8:11], v6 offset:64
	v_lshlrev_b32_e32 v12, 16, v16
	s_waitcnt lgkmcnt(0)
	v_fmac_f32_e32 v5, v8, v12
	v_and_b32_e32 v8, 0xffff0000, v16
	v_fmac_f32_e32 v5, v9, v8
	v_lshlrev_b32_e32 v8, 16, v17
	v_fmac_f32_e32 v5, v10, v8
	v_and_b32_e32 v8, 0xffff0000, v17
	v_fmac_f32_e32 v5, v11, v8
	ds_read_b128 v[8:11], v6 offset:80
	v_lshlrev_b32_e32 v12, 16, v18
	s_waitcnt lgkmcnt(0)
	v_fmac_f32_e32 v5, v8, v12
	v_and_b32_e32 v8, 0xffff0000, v18
	v_fmac_f32_e32 v5, v9, v8
	v_lshlrev_b32_e32 v8, 16, v19
	v_fmac_f32_e32 v5, v10, v8
	v_and_b32_e32 v8, 0xffff0000, v19
	v_fmac_f32_e32 v5, v11, v8
	ds_read_b128 v[8:11], v6 offset:96
	v_lshlrev_b32_e32 v12, 16, v0
	v_and_b32_e32 v0, 0xffff0000, v0
	s_waitcnt lgkmcnt(0)
	v_fmac_f32_e32 v5, v8, v12
	v_fmac_f32_e32 v5, v9, v0
	v_lshlrev_b32_e32 v0, 16, v1
	v_fmac_f32_e32 v5, v10, v0
	v_and_b32_e32 v0, 0xffff0000, v1
	v_fmac_f32_e32 v5, v11, v0
	ds_read_b128 v[8:11], v6 offset:112
	v_lshlrev_b32_e32 v0, 16, v2
	s_waitcnt lgkmcnt(0)
	v_fmac_f32_e32 v5, v8, v0
	v_and_b32_e32 v0, 0xffff0000, v2
	v_fmac_f32_e32 v5, v9, v0
	v_lshlrev_b32_e32 v0, 16, v3
	v_fmac_f32_e32 v5, v10, v0
	v_and_b32_e32 v0, 0xffff0000, v3
	v_fmac_f32_e32 v5, v11, v0
	ds_read_b128 v[0:3], v7 offset:34880
	ds_read_b128 v[8:11], v6 offset:128
	s_waitcnt lgkmcnt(1)
	v_lshlrev_b32_e32 v12, 16, v0
	s_waitcnt lgkmcnt(0)
	v_fmac_f32_e32 v5, v8, v12
	v_and_b32_e32 v0, 0xffff0000, v0
	v_fmac_f32_e32 v5, v9, v0
	v_lshlrev_b32_e32 v0, 16, v1
	v_fmac_f32_e32 v5, v10, v0
	v_and_b32_e32 v0, 0xffff0000, v1
	v_fmac_f32_e32 v5, v11, v0
	ds_read_b128 v[8:11], v6 offset:144
	v_lshlrev_b32_e32 v0, 16, v2
	s_waitcnt lgkmcnt(0)
	v_fmac_f32_e32 v5, v8, v0
	v_and_b32_e32 v0, 0xffff0000, v2
	v_fmac_f32_e32 v5, v9, v0
	v_lshlrev_b32_e32 v0, 16, v3
	v_fmac_f32_e32 v5, v10, v0
	v_and_b32_e32 v0, 0xffff0000, v3
	v_fmac_f32_e32 v5, v11, v0
	ds_read_b128 v[0:3], v7 offset:34896
	ds_read_b128 v[8:11], v6 offset:160
	s_waitcnt lgkmcnt(1)
	v_lshlrev_b32_e32 v12, 16, v0
	s_waitcnt lgkmcnt(0)
	v_fmac_f32_e32 v5, v8, v12
	v_and_b32_e32 v0, 0xffff0000, v0
	v_fmac_f32_e32 v5, v9, v0
	v_lshlrev_b32_e32 v0, 16, v1
	v_fmac_f32_e32 v5, v10, v0
	v_and_b32_e32 v0, 0xffff0000, v1
	v_fmac_f32_e32 v5, v11, v0
	ds_read_b128 v[8:11], v6 offset:176
	v_lshlrev_b32_e32 v0, 16, v2
	s_waitcnt lgkmcnt(0)
	v_fmac_f32_e32 v5, v8, v0
	v_and_b32_e32 v0, 0xffff0000, v2
	v_fmac_f32_e32 v5, v9, v0
	v_lshlrev_b32_e32 v0, 16, v3
	v_fmac_f32_e32 v5, v10, v0
	v_and_b32_e32 v0, 0xffff0000, v3
	v_fmac_f32_e32 v5, v11, v0
	ds_read_b128 v[0:3], v7 offset:34912
	ds_read_b128 v[8:11], v6 offset:192
	s_waitcnt lgkmcnt(1)
	v_lshlrev_b32_e32 v12, 16, v0
	s_waitcnt lgkmcnt(0)
	v_fmac_f32_e32 v5, v8, v12
	v_and_b32_e32 v0, 0xffff0000, v0
	v_fmac_f32_e32 v5, v9, v0
	v_lshlrev_b32_e32 v0, 16, v1
	v_fmac_f32_e32 v5, v10, v0
	v_and_b32_e32 v0, 0xffff0000, v1
	v_fmac_f32_e32 v5, v11, v0
	ds_read_b128 v[8:11], v6 offset:208
	v_lshlrev_b32_e32 v0, 16, v2
	s_waitcnt lgkmcnt(0)
	v_fmac_f32_e32 v5, v8, v0
	v_and_b32_e32 v0, 0xffff0000, v2
	v_fmac_f32_e32 v5, v9, v0
	v_lshlrev_b32_e32 v0, 16, v3
	v_fmac_f32_e32 v5, v10, v0
	v_and_b32_e32 v0, 0xffff0000, v3
	v_fmac_f32_e32 v5, v11, v0
	ds_read_b128 v[0:3], v7 offset:34928
	ds_read_b128 v[8:11], v6 offset:224
	s_waitcnt lgkmcnt(1)
	v_lshlrev_b32_e32 v7, 16, v0
	s_waitcnt lgkmcnt(0)
	v_fmac_f32_e32 v5, v8, v7
	v_and_b32_e32 v0, 0xffff0000, v0
	v_fmac_f32_e32 v5, v9, v0
	ds_read_b128 v[6:9], v6 offset:240
	v_lshlrev_b32_e32 v0, 16, v1
	v_fmac_f32_e32 v5, v10, v0
	v_and_b32_e32 v0, 0xffff0000, v1
	v_fmac_f32_e32 v5, v11, v0
	v_lshlrev_b32_e32 v0, 16, v2
	s_waitcnt lgkmcnt(0)
	v_fmac_f32_e32 v5, v6, v0
	v_and_b32_e32 v0, 0xffff0000, v2
	v_fmac_f32_e32 v5, v7, v0
	v_lshlrev_b32_e32 v0, 16, v3
	v_fmac_f32_e32 v5, v8, v0
	v_and_b32_e32 v0, 0xffff0000, v3
	v_fmac_f32_e32 v5, v9, v0
	v_mbcnt_hi_u32_b32 v0, -1, v195
	v_and_b32_e32 v2, 64, v0
	v_xor_b32_e32 v1, 1, v0
	v_add_u32_e32 v2, 64, v2
	v_cmp_lt_i32_e32 vcc, v1, v2
	s_nop 1
	v_cndmask_b32_e32 v0, v0, v1, vcc
	v_lshlrev_b32_e32 v0, 2, v0
	v_mov_b32_dpp v0, v5 quad_perm:[1,0,3,2] row_mask:0xf bank_mask:0xf
	v_cmp_eq_u32_e32 vcc, 0, v4
	s_and_saveexec_b64 s[0:1], vcc
	s_cbranch_execz .LBB0_535
	s_lshl_b64 s[6:7], s[2:3], 9
	v_readlane_b32 s8, v249, 21
	v_readlane_b32 s9, v249, 22
	s_add_u32 s6, s8, s6
	s_addc_u32 s7, s9, s7
	v_ashrrev_i32_e32 v65, 31, v64
	v_add_f32_e32 v0, v5, v0
	v_lshl_add_u64 v[2:3], v[64:65], 2, s[6:7]
	v_mul_f32_e32 v0, 0x3db504f3, v0
	global_store_dword v[2:3], v0, off
	s_branch .LBB0_535

.LBB0_640:
	s_waitcnt vmcnt(0)
	s_waitcnt lgkmcnt(0)
	s_barrier
	s_mov_b64 s[0:1], exec
	v_readlane_b32 s2, v251, 0
	v_readlane_b32 s3, v251, 1
	s_and_b64 s[2:3], s[0:1], s[2:3]
	s_mov_b64 exec, s[2:3]
	s_cbranch_execz .LBB0_688
	v_readlane_b32 s2, v249, 49
	s_waitcnt expcnt(0)
	s_nop 0
	v_mov_b32_e32 v0, s2
	ds_read_b32 v2, v0
	v_readlane_b32 s2, v249, 50
	s_waitcnt lgkmcnt(0)
	v_cmp_ne_u32_e32 vcc, 0, v2
	v_mov_b32_e32 v0, s2
	ds_read_b32 v0, v0
	s_cbranch_vccnz .LBB0_656
	s_mov_b32 s4, 1
	s_branch .LBB0_644

.LBB0_717:
	s_or_b64 exec, exec, s[6:7]
	ds_write_b128 v70, v[52:55]
	ds_write_b128 v70, v[56:59] offset:4608
	ds_write_b128 v70, v[60:63] offset:9216
	ds_write_b128 v70, v[64:67] offset:13824
	s_waitcnt lgkmcnt(0)
	s_barrier
	ds_read_b128 v[32:35], v158
	ds_read_b128 v[36:39], v158 offset:4608
	s_waitcnt lgkmcnt(1)
	v_mfma_f32_32x32x16_bf16 v[80:95], v[98:101], v[32:35], 0
	s_waitcnt lgkmcnt(0)
	v_mfma_f32_32x32x16_bf16 v[48:63], v[98:101], v[36:39], 0
	ds_read_b128 v[32:35], v158 offset:9216
	ds_read_b128 v[36:39], v158 offset:13824
	s_waitcnt lgkmcnt(1)
	v_mfma_f32_32x32x16_bf16 v[64:79], v[98:101], v[32:35], 0
	s_waitcnt lgkmcnt(0)
	v_mfma_f32_32x32x16_bf16 v[32:47], v[98:101], v[36:39], 0
	ds_read_b128 v[148:151], v158 offset:32
	s_waitcnt lgkmcnt(0)
	v_mfma_f32_32x32x16_bf16 v[80:95], v[102:105], v[148:151], v[80:95]
	ds_read_b128 v[148:151], v158 offset:4640
	s_waitcnt lgkmcnt(0)
	v_mfma_f32_32x32x16_bf16 v[48:63], v[102:105], v[148:151], v[48:63]
	ds_read_b128 v[148:151], v158 offset:9248
	s_waitcnt lgkmcnt(0)
	v_mfma_f32_32x32x16_bf16 v[64:79], v[102:105], v[148:151], v[64:79]
	ds_read_b128 v[148:151], v158 offset:13856
	s_waitcnt lgkmcnt(0)
	v_mfma_f32_32x32x16_bf16 v[32:47], v[102:105], v[148:151], v[32:47]
	ds_read_b128 v[148:151], v158 offset:64
	s_waitcnt lgkmcnt(0)
	v_mfma_f32_32x32x16_bf16 v[80:95], v[106:109], v[148:151], v[80:95]
	ds_read_b128 v[148:151], v158 offset:4672
	s_waitcnt lgkmcnt(0)
	v_mfma_f32_32x32x16_bf16 v[48:63], v[106:109], v[148:151], v[48:63]
	ds_read_b128 v[148:151], v158 offset:9280
	s_waitcnt lgkmcnt(0)
	v_mfma_f32_32x32x16_bf16 v[64:79], v[106:109], v[148:151], v[64:79]
	ds_read_b128 v[148:151], v158 offset:13888
	s_waitcnt lgkmcnt(0)
	v_mfma_f32_32x32x16_bf16 v[32:47], v[106:109], v[148:151], v[32:47]
	ds_read_b128 v[148:151], v158 offset:96
	s_waitcnt lgkmcnt(0)
	v_mfma_f32_32x32x16_bf16 v[80:95], v[110:113], v[148:151], v[80:95]
	ds_read_b128 v[148:151], v158 offset:4704
	s_waitcnt lgkmcnt(0)
	v_mfma_f32_32x32x16_bf16 v[48:63], v[110:113], v[148:151], v[48:63]
	ds_read_b128 v[148:151], v158 offset:9312
	s_waitcnt lgkmcnt(0)
	v_mfma_f32_32x32x16_bf16 v[64:79], v[110:113], v[148:151], v[64:79]
	ds_read_b128 v[148:151], v158 offset:13920
	s_waitcnt lgkmcnt(0)
	v_mfma_f32_32x32x16_bf16 v[32:47], v[110:113], v[148:151], v[32:47]
	s_cmp_eq_u32 s53, 1
	s_cbranch_scc1 .Latt_nm
	s_cmp_gt_u32 s53, 2
	s_cbranch_scc1 .Latt_nm
	s_add_i32 s6, s53, s49
	v_mbcnt_hi_u32_b32 v148, -1, v195
	v_lshl_add_u32 v96, s6, 7, v183
	v_and_b32_e32 v147, 64, v148
	v_add_u32_e32 v149, 64, v147
	v_sub_u32_e32 v147, v96, v159
	v_cmp_gt_u32_e32 vcc, s58, v147
	s_or_b64 vcc, s[2:3], vcc
	v_add_u32_e32 v150, 32, v147
	v_cndmask_b32_e32 v80, v204, v80, vcc
	v_cmp_gt_u32_e32 vcc, s58, v150
	s_or_b64 vcc, s[2:3], vcc
	v_add_u32_e32 v151, 64, v147
	v_cndmask_b32_e32 v48, v204, v48, vcc
	v_cmp_gt_u32_e32 vcc, s58, v151
	s_or_b64 vcc, s[2:3], vcc
	v_add_u32_e32 v147, 0x60, v147
	v_cndmask_b32_e32 v64, v204, v64, vcc
	v_cmp_gt_u32_e32 vcc, s58, v147
	s_or_b64 vcc, s[2:3], vcc
	v_xor_b32_e32 v147, 16, v148
	v_cndmask_b32_e32 v32, v204, v32, vcc
	v_cmp_lt_i32_e32 vcc, v147, v149
	v_max3_f32 v150, v80, s59, v48
	v_max3_f32 v150, v150, v64, v32
	v_cndmask_b32_e32 v147, v148, v147, vcc
	v_lshlrev_b32_e32 v147, 2, v147
	v_mov_b32_e32 v151, v150
	v_mov_b32_e32 v255, v150
	s_nop 1
	v_permlane16_swap_b32_e32 v151, v255
	v_add_u32_e32 v187, 0x8800, v186
	v_add_u32_e32 v215, 0x9000, v186
	v_max_f32_e32 v150, v151, v255
	v_xor_b32_e32 v151, 8, v148
	v_cmp_lt_i32_e32 vcc, v151, v149
	s_nop 1
	v_cndmask_b32_e32 v151, v148, v151, vcc
	v_lshlrev_b32_e32 v208, 2, v151
	v_max_f32_dpp v150, v150, v150 row_ror:8 row_mask:0xf bank_mask:0xf
	v_xor_b32_e32 v151, 4, v148
	v_cmp_lt_i32_e32 vcc, v151, v149
	s_nop 1
	v_cndmask_b32_e32 v151, v148, v151, vcc
	v_lshlrev_b32_e32 v209, 2, v151
	v_mov_b32_dpp v151, v150 row_shl:4 row_mask:0xf bank_mask:0x5
	v_mov_b32_dpp v151, v150 row_shr:4 row_mask:0xf bank_mask:0xa
	v_max_f32_e32 v150, v150, v151
	v_xor_b32_e32 v151, 2, v148
	v_cmp_lt_i32_e32 vcc, v151, v149
	s_nop 1
	v_cndmask_b32_e32 v151, v148, v151, vcc
	v_lshlrev_b32_e32 v210, 2, v151
	v_max_f32_dpp v150, v150, v150 quad_perm:[2,3,0,1] row_mask:0xf bank_mask:0xf
	v_xor_b32_e32 v151, 1, v148
	v_cmp_lt_i32_e32 vcc, v151, v149
	v_sub_u32_e32 v149, v96, v161
	s_nop 0
	v_cndmask_b32_e32 v148, v148, v151, vcc
	v_cmp_gt_u32_e32 vcc, s58, v149
	s_or_b64 vcc, s[2:3], vcc
	v_lshlrev_b32_e32 v211, 2, v148
	v_cndmask_b32_e32 v151, v204, v81, vcc
	v_add_u32_e32 v81, 32, v149
	v_cmp_gt_u32_e32 vcc, s58, v81
	s_or_b64 vcc, s[2:3], vcc
	v_add_u32_e32 v81, 64, v149
	v_cndmask_b32_e32 v152, v204, v49, vcc
	v_cmp_gt_u32_e32 vcc, s58, v81
	s_or_b64 vcc, s[2:3], vcc
	v_max3_f32 v49, v151, s59, v152
	v_cndmask_b32_e32 v153, v204, v65, vcc
	v_add_u32_e32 v65, 0x60, v149
	v_cmp_gt_u32_e32 vcc, s58, v65
	s_or_b64 vcc, s[2:3], vcc
	v_mov_b32_dpp v148, v150 quad_perm:[1,0,3,2] row_mask:0xf bank_mask:0xf
	v_cndmask_b32_e32 v154, v204, v33, vcc
	v_max3_f32 v33, v49, v153, v154
	v_mov_b32_e32 v49, v33
	v_mov_b32_e32 v255, v33
	s_nop 1
	v_permlane16_swap_b32_e32 v49, v255
	v_max3_f32 v207, v130, v150, v148
	v_sub_f32_e32 v48, v48, v207
	v_mul_f32_e32 v48, 0x3fb8aa3b, v48
	v_max_f32_e32 v49, v49, v255
	v_sub_f32_e32 v33, v80, v207
	v_sub_f32_e32 v32, v32, v207
	v_mul_f32_e32 v32, 0x3fb8aa3b, v32
	v_sub_f32_e32 v130, v130, v207
	v_max_f32_dpp v65, v49, v49 row_ror:8 row_mask:0xf bank_mask:0xf
	s_nop 1
	v_mov_b32_dpp v80, v65 row_shl:4 row_mask:0xf bank_mask:0x5
	v_mov_b32_dpp v80, v65 row_shr:4 row_mask:0xf bank_mask:0xa
	v_exp_f32_e32 v49, v48
	v_sub_f32_e32 v48, v64, v207
	v_mul_f32_e32 v48, 0x3fb8aa3b, v48
	v_exp_f32_e32 v81, v48
	v_max_f32_e32 v64, v80, v80
	v_max_f32_e32 v64, v65, v64
	v_exp_f32_e32 v65, v32
	v_mul_f32_e32 v33, 0x3fb8aa3b, v33
	v_exp_f32_e32 v33, v33
	v_max_f32_dpp v32, v64, v64 quad_perm:[2,3,0,1] row_mask:0xf bank_mask:0xf
	s_nop 1
	v_mov_b32_dpp v48, v32 quad_perm:[1,0,3,2] row_mask:0xf bank_mask:0xf
	v_mul_f32_e32 v64, 0x3fb8aa3b, v130
	v_exp_f32_e32 v130, v64
	v_cvt_pk_bf16_f32 v148, v33, v49
	v_cvt_pk_bf16_f32 v149, v81, v65
	v_max3_f32 v206, v131, v32, v48
	v_sub_u32_e32 v32, v96, v169
	v_cmp_gt_u32_e32 vcc, s58, v32
	s_or_b64 vcc, s[2:3], vcc
	v_add_u32_e32 v48, 32, v32
	v_cndmask_b32_e32 v82, v204, v82, vcc
	v_cmp_gt_u32_e32 vcc, s58, v48
	s_or_b64 vcc, s[2:3], vcc
	v_add_u32_e32 v64, 64, v32
	v_cndmask_b32_e32 v50, v204, v50, vcc
	v_cmp_gt_u32_e32 vcc, s58, v64
	s_or_b64 vcc, s[2:3], vcc
	v_add_u32_e32 v32, 0x60, v32
	v_cndmask_b32_e32 v66, v204, v66, vcc
	v_cmp_gt_u32_e32 vcc, s58, v32
	s_or_b64 vcc, s[2:3], vcc
	v_max3_f32 v48, v82, s59, v50
	v_cndmask_b32_e32 v34, v204, v34, vcc
	v_max3_f32 v48, v48, v66, v34
	v_mov_b32_e32 v64, v48
	v_mov_b32_e32 v255, v48
	s_nop 1
	v_permlane16_swap_b32_e32 v64, v255
	v_sub_f32_e32 v32, v151, v206
	v_sub_f32_e32 v80, v152, v206
	v_mul_f32_e32 v32, 0x3fb8aa3b, v32
	v_exp_f32_e32 v32, v32
	v_max_f32_e32 v64, v64, v255
	v_mul_f32_e32 v48, 0x3fb8aa3b, v80
	v_sub_f32_e32 v80, v153, v206
	v_mul_f32_e32 v80, 0x3fb8aa3b, v80
	v_exp_f32_e32 v48, v48
	v_max_f32_dpp v150, v64, v64 row_ror:8 row_mask:0xf bank_mask:0xf
	v_sub_f32_e32 v64, v154, v206
	v_sub_u32_e32 v154, v96, v170
	v_cmp_gt_u32_e32 vcc, s58, v154
	s_or_b64 vcc, s[2:3], vcc
	v_mov_b32_dpp v151, v150 row_shl:4 row_mask:0xf bank_mask:0x5
	v_mov_b32_dpp v151, v150 row_shr:4 row_mask:0xf bank_mask:0xa
	v_cndmask_b32_e32 v155, v204, v83, vcc
	v_add_u32_e32 v83, 32, v154
	v_cmp_gt_u32_e32 vcc, s58, v83
	s_or_b64 vcc, s[2:3], vcc
	v_add_u32_e32 v83, 64, v154
	v_cndmask_b32_e32 v156, v204, v51, vcc
	v_cmp_gt_u32_e32 vcc, s58, v83
	s_or_b64 vcc, s[2:3], vcc
	v_max3_f32 v51, v155, s59, v156
	v_cndmask_b32_e32 v160, v204, v67, vcc
	v_add_u32_e32 v67, 0x60, v154
	v_cmp_gt_u32_e32 vcc, s58, v67
	s_or_b64 vcc, s[2:3], vcc
	v_max_f32_e32 v151, v151, v151
	v_cndmask_b32_e32 v154, v204, v35, vcc
	v_max3_f32 v35, v51, v160, v154
	v_max_f32_e32 v152, v150, v151
	v_mov_b32_e32 v51, v35
	v_mov_b32_e32 v255, v35
	s_nop 1
	v_permlane16_swap_b32_e32 v51, v255
	v_mov_b32_dpp v153, v152 quad_perm:[2,3,0,1] row_mask:0xf bank_mask:0xf
	v_mul_f32_e32 v64, 0x3fb8aa3b, v64
	v_exp_f32_e32 v80, v80
	v_exp_f32_e32 v64, v64
	v_max_f32_e32 v153, v153, v153
	v_max_f32_e32 v51, v51, v255
	v_max_f32_e32 v152, v152, v153
	s_nop 1
	v_mov_b32_dpp v153, v152 quad_perm:[1,0,3,2] row_mask:0xf bank_mask:0xf
	v_cvt_pk_bf16_f32 v150, v32, v48
	v_cvt_pk_bf16_f32 v151, v80, v64
	ds_write2_b64 v187, v[148:149], v[150:151] offset0:128 offset1:162
	v_max3_f32 v189, v132, v152, v153
	v_max_f32_dpp v67, v51, v51 row_ror:8 row_mask:0xf bank_mask:0xf
	v_sub_f32_e32 v35, v82, v189
	s_nop 1
	v_mov_b32_dpp v82, v67 row_shl:4 row_mask:0xf bank_mask:0x5
	v_mov_b32_dpp v82, v67 row_shr:4 row_mask:0xf bank_mask:0xa
	v_sub_f32_e32 v50, v50, v189
	v_mul_f32_e32 v50, 0x3fb8aa3b, v50
	v_exp_f32_e32 v51, v50
	v_sub_f32_e32 v50, v66, v189
	s_waitcnt lgkmcnt(0)
	v_max_f32_e32 v66, v82, v82
	v_max_f32_e32 v66, v67, v66
	v_sub_f32_e32 v34, v34, v189
	v_mul_f32_e32 v34, 0x3fb8aa3b, v34
	v_exp_f32_e32 v67, v34
	v_mul_f32_e32 v50, 0x3fb8aa3b, v50
	v_max_f32_dpp v34, v66, v66 quad_perm:[2,3,0,1] row_mask:0xf bank_mask:0xf
	v_exp_f32_e32 v83, v50
	s_nop 1
	v_mov_b32_dpp v50, v34 quad_perm:[1,0,3,2] row_mask:0xf bank_mask:0xf
	v_sub_f32_e32 v132, v132, v189
	v_mul_f32_e32 v66, 0x3fb8aa3b, v132
	v_exp_f32_e32 v132, v66
	v_mul_f32_e32 v35, 0x3fb8aa3b, v35
	v_max3_f32 v188, v133, v34, v50
	v_sub_u32_e32 v34, v96, v171
	v_cmp_gt_u32_e32 vcc, s58, v34
	s_or_b64 vcc, s[2:3], vcc
	v_add_u32_e32 v50, 32, v34
	v_cndmask_b32_e32 v84, v204, v84, vcc
	v_cmp_gt_u32_e32 vcc, s58, v50
	s_or_b64 vcc, s[2:3], vcc
	v_add_u32_e32 v66, 64, v34
	v_cndmask_b32_e32 v52, v204, v52, vcc
	v_cmp_gt_u32_e32 vcc, s58, v66
	s_or_b64 vcc, s[2:3], vcc
	v_add_u32_e32 v34, 0x60, v34
	v_cndmask_b32_e32 v68, v204, v68, vcc
	v_cmp_gt_u32_e32 vcc, s58, v34
	s_or_b64 vcc, s[2:3], vcc
	v_max3_f32 v50, v84, s59, v52
	v_cndmask_b32_e32 v150, v204, v36, vcc
	v_max3_f32 v34, v50, v68, v150
	v_mov_b32_e32 v36, v34
	v_mov_b32_e32 v255, v34
	s_nop 1
	v_permlane16_swap_b32_e32 v36, v255
	v_sub_f32_e32 v151, v154, v188
	v_sub_f32_e32 v50, v133, v188
	v_mul_f32_e32 v133, 0x3fb8aa3b, v50
	v_sub_f32_e32 v50, v155, v188
	v_max_f32_e32 v36, v36, v255
	s_nop 1
	v_mov_b32_dpp v66, v36 row_ror:8 row_mask:0xf bank_mask:0xf
	v_mul_f32_e32 v50, 0x3fb8aa3b, v50
	v_exp_f32_e32 v34, v50
	v_sub_f32_e32 v50, v156, v188
	v_sub_f32_e32 v82, v160, v188
	v_max_f32_e32 v66, v66, v66
	v_max_f32_e32 v36, v36, v66
	s_nop 1
	v_mov_b32_dpp v66, v36 row_shl:4 row_mask:0xf bank_mask:0x5
	v_mov_b32_dpp v66, v36 row_shr:4 row_mask:0xf bank_mask:0xa
	v_mul_f32_e32 v50, 0x3fb8aa3b, v50
	v_mul_f32_e32 v82, 0x3fb8aa3b, v82
	v_exp_f32_e32 v35, v35
	v_exp_f32_e32 v50, v50
	v_max_f32_e32 v66, v66, v66
	v_max_f32_e32 v152, v36, v66
	s_nop 1
	v_mov_b32_dpp v153, v152 quad_perm:[2,3,0,1] row_mask:0xf bank_mask:0xf
	v_mul_f32_e32 v36, 0x3fb8aa3b, v151
	v_exp_f32_e32 v82, v82
	v_exp_f32_e32 v66, v36
	v_cvt_pk_bf16_f32 v148, v35, v51
	v_max_f32_e32 v151, v153, v153
	v_sub_u32_e32 v153, v96, v172
	v_cmp_gt_u32_e32 vcc, s58, v153
	s_or_b64 vcc, s[2:3], vcc
	v_cvt_pk_bf16_f32 v149, v83, v67
	v_cndmask_b32_e32 v154, v204, v85, vcc
	v_add_u32_e32 v85, 32, v153
	v_cmp_gt_u32_e32 vcc, s58, v85
	s_or_b64 vcc, s[2:3], vcc
	v_add_u32_e32 v85, 64, v153
	v_cndmask_b32_e32 v155, v204, v53, vcc
	v_cmp_gt_u32_e32 vcc, s58, v85
	s_or_b64 vcc, s[2:3], vcc
	v_max3_f32 v53, v154, s59, v155
	v_cndmask_b32_e32 v156, v204, v69, vcc
	v_add_u32_e32 v69, 0x60, v153
	v_cmp_gt_u32_e32 vcc, s58, v69
	s_or_b64 vcc, s[2:3], vcc
	v_cvt_pk_bf16_f32 v36, v34, v50
	v_cndmask_b32_e32 v153, v204, v37, vcc
	v_max3_f32 v53, v53, v156, v153
	v_mov_b32_e32 v69, v53
	v_mov_b32_e32 v255, v53
	s_nop 1
	v_permlane16_swap_b32_e32 v69, v255
	s_nop 1
	v_mov_b32_dpp v69, v255 quad_perm:[0,1,2,3] row_mask:0x5 bank_mask:0xf
	v_cvt_pk_bf16_f32 v37, v82, v66
	ds_write2_b64 v187, v[148:149], v[36:37] offset0:196 offset1:230
	v_max_f32_e32 v151, v152, v151
	s_nop 1
	v_mov_b32_dpp v152, v151 quad_perm:[1,0,3,2] row_mask:0xf bank_mask:0xf
	v_max_f32_e32 v37, v69, v69
	v_max_f32_e32 v53, v53, v37
	v_sub_f32_e32 v131, v131, v206
	s_waitcnt lgkmcnt(0)
	v_max3_f32 v187, v134, v151, v152
	v_sub_f32_e32 v37, v84, v187
	v_sub_f32_e32 v52, v52, v187
	v_max_f32_dpp v69, v53, v53 row_ror:8 row_mask:0xf bank_mask:0xf
	s_nop 1
	v_mov_b32_dpp v84, v69 row_shl:4 row_mask:0xf bank_mask:0x5
	v_mov_b32_dpp v84, v69 row_shr:4 row_mask:0xf bank_mask:0xa
	v_mul_f32_e32 v52, 0x3fb8aa3b, v52
	v_exp_f32_e32 v53, v52
	v_sub_f32_e32 v52, v68, v187
	v_mul_f32_e32 v52, 0x3fb8aa3b, v52
	v_max_f32_e32 v68, v84, v84
	v_max_f32_e32 v68, v69, v68
	v_exp_f32_e32 v85, v52
	v_sub_f32_e32 v52, v150, v187
	v_mul_f32_e32 v52, 0x3fb8aa3b, v52
	v_exp_f32_e32 v69, v52
	s_nop 0
	v_max_f32_dpp v52, v68, v68 quad_perm:[2,3,0,1] row_mask:0xf bank_mask:0xf
	s_nop 1
	v_mov_b32_dpp v68, v52 quad_perm:[1,0,3,2] row_mask:0xf bank_mask:0xf
	v_sub_f32_e32 v36, v134, v187
	v_mul_f32_e32 v36, 0x3fb8aa3b, v36
	v_exp_f32_e32 v134, v36
	v_sub_u32_e32 v36, v96, v173
	v_cmp_gt_u32_e32 vcc, s58, v36
	v_max3_f32 v160, v135, v52, v68
	s_or_b64 vcc, s[2:3], vcc
	v_add_u32_e32 v52, 32, v36
	v_cndmask_b32_e32 v86, v204, v86, vcc
	v_cmp_gt_u32_e32 vcc, s58, v52
	s_or_b64 vcc, s[2:3], vcc
	v_add_u32_e32 v68, 64, v36
	v_cndmask_b32_e32 v54, v204, v54, vcc
	v_cmp_gt_u32_e32 vcc, s58, v68
	s_or_b64 vcc, s[2:3], vcc
	v_add_u32_e32 v36, 0x60, v36
	v_cndmask_b32_e32 v70, v204, v70, vcc
	v_cmp_gt_u32_e32 vcc, s58, v36
	s_or_b64 vcc, s[2:3], vcc
	v_max3_f32 v52, v86, s59, v54
	v_cndmask_b32_e32 v38, v204, v38, vcc
	v_max3_f32 v52, v52, v70, v38
	v_mov_b32_e32 v68, v52
	v_mov_b32_e32 v255, v52
	s_nop 1
	v_permlane16_swap_b32_e32 v68, v255
	v_sub_f32_e32 v36, v154, v160
	v_sub_u32_e32 v154, v96, v174
	v_cmp_gt_u32_e32 vcc, s58, v154
	s_or_b64 vcc, s[2:3], vcc
	v_max_f32_e32 v68, v68, v255
	v_cndmask_b32_e32 v212, v204, v87, vcc
	v_add_u32_e32 v87, 32, v154
	v_cmp_gt_u32_e32 vcc, s58, v87
	s_or_b64 vcc, s[2:3], vcc
	v_add_u32_e32 v87, 64, v154
	v_max_f32_dpp v150, v68, v68 row_ror:8 row_mask:0xf bank_mask:0xf
	v_cndmask_b32_e32 v213, v204, v55, vcc
	v_cmp_gt_u32_e32 vcc, s58, v87
	v_mov_b32_dpp v151, v150 row_shl:4 row_mask:0xf bank_mask:0x5
	v_mov_b32_dpp v151, v150 row_shr:4 row_mask:0xf bank_mask:0xa
	s_or_b64 vcc, s[2:3], vcc
	v_cndmask_b32_e32 v214, v204, v71, vcc
	v_add_u32_e32 v71, 0x60, v154
	v_cmp_gt_u32_e32 vcc, s58, v71
	s_or_b64 vcc, s[2:3], vcc
	v_max3_f32 v55, v212, s59, v213
	v_cndmask_b32_e32 v154, v204, v39, vcc
	v_max_f32_e32 v151, v151, v151
	v_max3_f32 v39, v55, v214, v154
	v_max_f32_e32 v152, v150, v151
	v_mov_b32_e32 v55, v39
	v_mov_b32_e32 v255, v39
	s_nop 1
	v_permlane16_swap_b32_e32 v55, v255
	v_sub_f32_e32 v68, v153, v160
	v_mov_b32_dpp v153, v152 quad_perm:[2,3,0,1] row_mask:0xf bank_mask:0xf
	v_sub_f32_e32 v84, v155, v160
	v_mul_f32_e32 v52, 0x3fb8aa3b, v84
	v_max_f32_e32 v55, v55, v255
	v_max_f32_e32 v153, v153, v153
	v_max_f32_e32 v152, v152, v153
	s_nop 0
	s_nop 1
	v_mov_b32_dpp v153, v152 quad_perm:[1,0,3,2] row_mask:0xf bank_mask:0xf
	v_sub_f32_e32 v84, v156, v160
	v_mul_f32_e32 v37, 0x3fb8aa3b, v37
	v_mul_f32_e32 v36, 0x3fb8aa3b, v36
	v_max3_f32 v156, v136, v152, v153
	v_max_f32_dpp v71, v55, v55 row_ror:8 row_mask:0xf bank_mask:0xf
	v_sub_f32_e32 v39, v86, v156
	s_nop 1
	v_mov_b32_dpp v86, v71 row_shl:4 row_mask:0xf bank_mask:0x5
	v_mov_b32_dpp v86, v71 row_shr:4 row_mask:0xf bank_mask:0xa
	v_sub_f32_e32 v54, v54, v156
	v_mul_f32_e32 v54, 0x3fb8aa3b, v54
	v_exp_f32_e32 v55, v54
	v_sub_f32_e32 v54, v70, v156
	v_max_f32_e32 v70, v86, v86
	v_max_f32_e32 v70, v71, v70
	v_sub_f32_e32 v38, v38, v156
	v_mul_f32_e32 v38, 0x3fb8aa3b, v38
	v_exp_f32_e32 v71, v38
	v_mul_f32_e32 v54, 0x3fb8aa3b, v54
	v_max_f32_dpp v38, v70, v70 quad_perm:[2,3,0,1] row_mask:0xf bank_mask:0xf
	v_exp_f32_e32 v87, v54
	s_nop 1
	v_mov_b32_dpp v54, v38 quad_perm:[1,0,3,2] row_mask:0xf bank_mask:0xf
	v_sub_f32_e32 v136, v136, v156
	v_mul_f32_e32 v84, 0x3fb8aa3b, v84
	v_mul_f32_e32 v68, 0x3fb8aa3b, v68
	v_mul_f32_e32 v70, 0x3fb8aa3b, v136
	v_max3_f32 v155, v137, v38, v54
	v_sub_u32_e32 v38, v96, v175
	v_cmp_gt_u32_e32 vcc, s58, v38
	s_or_b64 vcc, s[2:3], vcc
	v_add_u32_e32 v54, 32, v38
	v_cndmask_b32_e32 v88, v204, v88, vcc
	v_cmp_gt_u32_e32 vcc, s58, v54
	v_exp_f32_e32 v37, v37
	v_exp_f32_e32 v36, v36
	v_exp_f32_e32 v52, v52
	v_exp_f32_e32 v84, v84
	v_exp_f32_e32 v68, v68
	v_exp_f32_e32 v136, v70
	s_or_b64 vcc, s[2:3], vcc
	v_add_u32_e32 v70, 64, v38
	v_cndmask_b32_e32 v56, v204, v56, vcc
	v_cmp_gt_u32_e32 vcc, s58, v70
	s_or_b64 vcc, s[2:3], vcc
	v_add_u32_e32 v38, 0x60, v38
	v_cndmask_b32_e32 v72, v204, v72, vcc
	v_cmp_gt_u32_e32 vcc, s58, v38
	v_cvt_pk_bf16_f32 v148, v37, v53
	v_cvt_pk_bf16_f32 v149, v85, v69
	v_cvt_pk_bf16_f32 v150, v36, v52
	v_cvt_pk_bf16_f32 v151, v84, v68
	s_or_b64 vcc, s[2:3], vcc
	ds_write2_b64 v215, v[148:149], v[150:151] offset0:144 offset1:178
	v_max3_f32 v54, v88, s59, v56
	v_cndmask_b32_e32 v150, v204, v40, vcc
	v_max3_f32 v38, v54, v72, v150
	v_mov_b32_e32 v40, v38
	v_mov_b32_e32 v255, v38
	s_nop 1
	v_permlane16_swap_b32_e32 v40, v255
	v_sub_f32_e32 v151, v154, v155
	v_sub_f32_e32 v54, v137, v155
	v_mul_f32_e32 v137, 0x3fb8aa3b, v54
	v_sub_f32_e32 v54, v212, v155
	s_waitcnt lgkmcnt(0)
	v_max_f32_e32 v40, v40, v255
	s_nop 1
	v_mov_b32_dpp v70, v40 row_ror:8 row_mask:0xf bank_mask:0xf
	v_mul_f32_e32 v54, 0x3fb8aa3b, v54
	v_exp_f32_e32 v38, v54
	v_sub_f32_e32 v54, v213, v155
	v_sub_f32_e32 v86, v214, v155
	v_max_f32_e32 v70, v70, v70
	v_max_f32_e32 v40, v40, v70
	s_nop 1
	v_mov_b32_dpp v70, v40 row_shl:4 row_mask:0xf bank_mask:0x5
	v_mov_b32_dpp v70, v40 row_shr:4 row_mask:0xf bank_mask:0xa
	v_mul_f32_e32 v39, 0x3fb8aa3b, v39
	v_mul_f32_e32 v54, 0x3fb8aa3b, v54
	v_mul_f32_e32 v86, 0x3fb8aa3b, v86
	v_exp_f32_e32 v39, v39
	v_max_f32_e32 v70, v70, v70
	v_max_f32_e32 v152, v40, v70
	s_nop 1
	v_mov_b32_dpp v153, v152 quad_perm:[2,3,0,1] row_mask:0xf bank_mask:0xf
	v_mul_f32_e32 v40, 0x3fb8aa3b, v151
	v_exp_f32_e32 v54, v54
	v_exp_f32_e32 v86, v86
	v_exp_f32_e32 v70, v40
	v_max_f32_e32 v151, v153, v153
	v_sub_u32_e32 v153, v96, v176
	v_cmp_gt_u32_e32 vcc, s58, v153
	s_or_b64 vcc, s[2:3], vcc
	v_cvt_pk_bf16_f32 v148, v39, v55
	v_cndmask_b32_e32 v212, v204, v89, vcc
	v_add_u32_e32 v89, 32, v153
	v_cmp_gt_u32_e32 vcc, s58, v89
	s_or_b64 vcc, s[2:3], vcc
	v_add_u32_e32 v89, 64, v153
	v_cndmask_b32_e32 v213, v204, v57, vcc
	v_cmp_gt_u32_e32 vcc, s58, v89
	s_or_b64 vcc, s[2:3], vcc
	v_max3_f32 v57, v212, s59, v213
	v_cndmask_b32_e32 v214, v204, v73, vcc
	v_add_u32_e32 v73, 0x60, v153
	v_cmp_gt_u32_e32 vcc, s58, v73
	s_or_b64 vcc, s[2:3], vcc
	v_cvt_pk_bf16_f32 v149, v87, v71
	v_cndmask_b32_e32 v216, v204, v41, vcc
	v_max3_f32 v57, v57, v214, v216
	v_mov_b32_e32 v73, v57
	v_mov_b32_e32 v255, v57
	s_nop 1
	v_permlane16_swap_b32_e32 v73, v255
	s_nop 1
	v_mov_b32_dpp v73, v255 quad_perm:[0,1,2,3] row_mask:0x5 bank_mask:0xf
	v_cvt_pk_bf16_f32 v40, v38, v54
	v_cvt_pk_bf16_f32 v41, v86, v70
	ds_write2_b64 v215, v[148:149], v[40:41] offset0:212 offset1:246
	v_max_f32_e32 v151, v152, v151
	v_max_f32_e32 v41, v73, v73
	v_max_f32_e32 v57, v57, v41
	v_mov_b32_dpp v152, v151 quad_perm:[1,0,3,2] row_mask:0xf bank_mask:0xf
	v_sub_f32_e32 v135, v135, v160
	v_mul_f32_e32 v131, 0x3fb8aa3b, v131
	v_mul_f32_e32 v135, 0x3fb8aa3b, v135
	s_waitcnt lgkmcnt(0)
	v_max3_f32 v154, v138, v151, v152
	v_max_f32_dpp v73, v57, v57 row_ror:8 row_mask:0xf bank_mask:0xf
	v_sub_f32_e32 v41, v88, v154
	s_nop 1
	v_mov_b32_dpp v88, v73 row_shl:4 row_mask:0xf bank_mask:0x5
	v_mov_b32_dpp v88, v73 row_shr:4 row_mask:0xf bank_mask:0xa
	v_sub_f32_e32 v56, v56, v154
	v_mul_f32_e32 v56, 0x3fb8aa3b, v56
	v_exp_f32_e32 v57, v56
	v_sub_f32_e32 v56, v72, v154
	v_max_f32_e32 v72, v88, v88
	v_max_f32_e32 v72, v73, v72
	v_mul_f32_e32 v56, 0x3fb8aa3b, v56
	v_exp_f32_e32 v89, v56
	v_sub_f32_e32 v56, v150, v154
	v_mul_f32_e32 v56, 0x3fb8aa3b, v56
	v_exp_f32_e32 v73, v56
	s_nop 0
	v_max_f32_dpp v56, v72, v72 quad_perm:[2,3,0,1] row_mask:0xf bank_mask:0xf
	s_nop 1
	v_mov_b32_dpp v72, v56 quad_perm:[1,0,3,2] row_mask:0xf bank_mask:0xf
	v_sub_f32_e32 v40, v138, v154
	v_mul_f32_e32 v40, 0x3fb8aa3b, v40
	v_exp_f32_e32 v138, v40
	v_sub_u32_e32 v40, v96, v177
	v_cmp_gt_u32_e32 vcc, s58, v40
	v_max3_f32 v153, v139, v56, v72
	s_or_b64 vcc, s[2:3], vcc
	v_add_u32_e32 v56, 32, v40
	v_cndmask_b32_e32 v90, v204, v90, vcc
	v_cmp_gt_u32_e32 vcc, s58, v56
	s_or_b64 vcc, s[2:3], vcc
	v_add_u32_e32 v72, 64, v40
	v_cndmask_b32_e32 v58, v204, v58, vcc
	v_cmp_gt_u32_e32 vcc, s58, v72
	s_or_b64 vcc, s[2:3], vcc
	v_add_u32_e32 v40, 0x60, v40
	v_cndmask_b32_e32 v74, v204, v74, vcc
	v_cmp_gt_u32_e32 vcc, s58, v40
	s_or_b64 vcc, s[2:3], vcc
	v_max3_f32 v56, v90, s59, v58
	v_cndmask_b32_e32 v42, v204, v42, vcc
	v_max3_f32 v56, v56, v74, v42
	v_mov_b32_e32 v72, v56
	v_mov_b32_e32 v255, v56
	s_nop 1
	v_permlane16_swap_b32_e32 v72, v255
	v_sub_f32_e32 v88, v213, v153
	v_sub_u32_e32 v213, v96, v178
	v_cmp_gt_u32_e32 vcc, s58, v213
	s_or_b64 vcc, s[2:3], vcc
	v_max_f32_e32 v72, v72, v255
	v_mul_f32_e32 v56, 0x3fb8aa3b, v88
	v_sub_f32_e32 v88, v214, v153
	v_cndmask_b32_e32 v214, v204, v91, vcc
	v_add_u32_e32 v91, 32, v213
	v_cmp_gt_u32_e32 vcc, s58, v91
	s_or_b64 vcc, s[2:3], vcc
	v_add_u32_e32 v91, 64, v213
	v_max_f32_dpp v150, v72, v72 row_ror:8 row_mask:0xf bank_mask:0xf
	v_cndmask_b32_e32 v215, v204, v59, vcc
	v_cmp_gt_u32_e32 vcc, s58, v91
	v_mov_b32_dpp v151, v150 row_shl:4 row_mask:0xf bank_mask:0x5
	v_mov_b32_dpp v151, v150 row_shr:4 row_mask:0xf bank_mask:0xa
	s_or_b64 vcc, s[2:3], vcc
	v_sub_f32_e32 v72, v216, v153
	v_cndmask_b32_e32 v216, v204, v75, vcc
	v_add_u32_e32 v75, 0x60, v213
	v_cmp_gt_u32_e32 vcc, s58, v75
	s_or_b64 vcc, s[2:3], vcc
	v_max3_f32 v59, v214, s59, v215
	v_cndmask_b32_e32 v213, v204, v43, vcc
	v_max_f32_e32 v151, v151, v151
	v_max3_f32 v43, v59, v216, v213
	v_sub_f32_e32 v40, v212, v153
	v_max_f32_e32 v152, v150, v151
	v_mov_b32_e32 v59, v43
	v_mov_b32_e32 v255, v43
	s_nop 1
	v_permlane16_swap_b32_e32 v59, v255
	v_mul_f32_e32 v41, 0x3fb8aa3b, v41
	v_mul_f32_e32 v40, 0x3fb8aa3b, v40
	v_mul_f32_e32 v88, 0x3fb8aa3b, v88
	v_mul_f32_e32 v72, 0x3fb8aa3b, v72
	v_mov_b32_dpp v212, v152 quad_perm:[2,3,0,1] row_mask:0xf bank_mask:0xf
	v_exp_f32_e32 v41, v41
	v_exp_f32_e32 v40, v40
	v_exp_f32_e32 v56, v56
	v_exp_f32_e32 v88, v88
	v_exp_f32_e32 v72, v72
	v_cvt_pk_bf16_f32 v148, v41, v57
	v_cvt_pk_bf16_f32 v149, v89, v73
	v_cvt_pk_bf16_f32 v150, v40, v56
	v_cvt_pk_bf16_f32 v151, v88, v72
	v_max_f32_e32 v212, v212, v212
	v_add_u32_e32 v75, 0x9800, v186
	v_max_f32_e32 v59, v59, v255
	v_max_f32_e32 v152, v152, v212
	ds_write2_b64 v75, v[148:149], v[150:151] offset0:160 offset1:194
	s_nop 0
	v_mov_b32_dpp v212, v152 quad_perm:[1,0,3,2] row_mask:0xf bank_mask:0xf
	v_sub_f32_e32 v139, v139, v153
	v_mul_f32_e32 v139, 0x3fb8aa3b, v139
	v_exp_f32_e32 v131, v131
	s_waitcnt lgkmcnt(0)
	v_max3_f32 v152, v140, v152, v212
	v_max_f32_dpp v75, v59, v59 row_ror:8 row_mask:0xf bank_mask:0xf
	v_sub_f32_e32 v43, v90, v152
	s_nop 1
	v_mov_b32_dpp v90, v75 row_shl:4 row_mask:0xf bank_mask:0x5
	v_mov_b32_dpp v90, v75 row_shr:4 row_mask:0xf bank_mask:0xa
	v_sub_f32_e32 v58, v58, v152
	v_mul_f32_e32 v58, 0x3fb8aa3b, v58
	v_exp_f32_e32 v59, v58
	v_sub_f32_e32 v58, v74, v152
	v_max_f32_e32 v74, v90, v90
	v_max_f32_e32 v74, v75, v74
	v_sub_f32_e32 v42, v42, v152
	v_mul_f32_e32 v42, 0x3fb8aa3b, v42
	v_exp_f32_e32 v75, v42
	v_mul_f32_e32 v58, 0x3fb8aa3b, v58
	v_max_f32_dpp v42, v74, v74 quad_perm:[2,3,0,1] row_mask:0xf bank_mask:0xf
	v_exp_f32_e32 v91, v58
	s_nop 1
	v_mov_b32_dpp v58, v42 quad_perm:[1,0,3,2] row_mask:0xf bank_mask:0xf
	v_sub_f32_e32 v140, v140, v152
	v_mul_f32_e32 v74, 0x3fb8aa3b, v140
	v_exp_f32_e32 v140, v74
	v_mul_f32_e32 v43, 0x3fb8aa3b, v43
	v_max3_f32 v151, v141, v42, v58
	v_sub_u32_e32 v42, v96, v179
	v_cmp_gt_u32_e32 vcc, s58, v42
	s_or_b64 vcc, s[2:3], vcc
	v_add_u32_e32 v58, 32, v42
	v_cndmask_b32_e32 v92, v204, v92, vcc
	v_cmp_gt_u32_e32 vcc, s58, v58
	s_or_b64 vcc, s[2:3], vcc
	v_add_u32_e32 v74, 64, v42
	v_cndmask_b32_e32 v60, v204, v60, vcc
	v_cmp_gt_u32_e32 vcc, s58, v74
	s_or_b64 vcc, s[2:3], vcc
	v_add_u32_e32 v42, 0x60, v42
	v_cndmask_b32_e32 v76, v204, v76, vcc
	v_cmp_gt_u32_e32 vcc, s58, v42
	s_or_b64 vcc, s[2:3], vcc
	v_max3_f32 v58, v92, s59, v60
	v_cndmask_b32_e32 v44, v204, v44, vcc
	v_max3_f32 v58, v58, v76, v44
	v_mov_b32_e32 v74, v58
	v_mov_b32_e32 v255, v58
	s_nop 1
	v_permlane16_swap_b32_e32 v74, v255
	v_sub_f32_e32 v90, v215, v151
	v_sub_u32_e32 v215, v96, v180
	v_cmp_gt_u32_e32 vcc, s58, v215
	s_or_b64 vcc, s[2:3], vcc
	v_max_f32_e32 v74, v74, v255
	v_mul_f32_e32 v58, 0x3fb8aa3b, v90
	v_sub_f32_e32 v90, v216, v151
	v_cndmask_b32_e32 v216, v204, v93, vcc
	v_add_u32_e32 v93, 32, v215
	v_cmp_gt_u32_e32 vcc, s58, v93
	s_or_b64 vcc, s[2:3], vcc
	v_add_u32_e32 v93, 64, v215
	v_max_f32_dpp v150, v74, v74 row_ror:8 row_mask:0xf bank_mask:0xf
	v_cndmask_b32_e32 v217, v204, v61, vcc
	v_cmp_gt_u32_e32 vcc, s58, v93
	v_mov_b32_dpp v212, v150 row_shl:4 row_mask:0xf bank_mask:0x5
	v_mov_b32_dpp v212, v150 row_shr:4 row_mask:0xf bank_mask:0xa
	s_or_b64 vcc, s[2:3], vcc
	v_cndmask_b32_e32 v218, v204, v77, vcc
	v_add_u32_e32 v77, 0x60, v215
	v_cmp_gt_u32_e32 vcc, s58, v77
	s_or_b64 vcc, s[2:3], vcc
	v_max3_f32 v61, v216, s59, v217
	v_cndmask_b32_e32 v215, v204, v45, vcc
	v_max_f32_e32 v212, v212, v212
	v_max3_f32 v45, v61, v218, v215
	v_sub_f32_e32 v42, v214, v151
	v_sub_f32_e32 v74, v213, v151
	v_max_f32_e32 v150, v150, v212
	v_mov_b32_e32 v61, v45
	v_mov_b32_e32 v255, v45
	s_nop 1
	v_permlane16_swap_b32_e32 v61, v255
	v_mul_f32_e32 v42, 0x3fb8aa3b, v42
	v_mul_f32_e32 v90, 0x3fb8aa3b, v90
	v_mul_f32_e32 v74, 0x3fb8aa3b, v74
	v_mov_b32_dpp v214, v150 quad_perm:[2,3,0,1] row_mask:0xf bank_mask:0xf
	v_exp_f32_e32 v43, v43
	v_exp_f32_e32 v42, v42
	v_exp_f32_e32 v58, v58
	v_exp_f32_e32 v90, v90
	v_exp_f32_e32 v74, v74
	v_cvt_pk_bf16_f32 v148, v43, v59
	v_cvt_pk_bf16_f32 v149, v91, v75
	v_cvt_pk_bf16_f32 v212, v42, v58
	v_cvt_pk_bf16_f32 v213, v90, v74
	v_max_f32_e32 v214, v214, v214
	v_add_u32_e32 v77, 0x9c00, v186
	v_max_f32_e32 v61, v61, v255
	v_max_f32_e32 v150, v150, v214
	ds_write2_b64 v77, v[148:149], v[212:213] offset0:100 offset1:134
	s_nop 0
	v_mov_b32_dpp v214, v150 quad_perm:[1,0,3,2] row_mask:0xf bank_mask:0xf
	v_sub_f32_e32 v141, v141, v151
	v_mul_f32_e32 v141, 0x3fb8aa3b, v141
	v_exp_f32_e32 v133, v133
	s_waitcnt lgkmcnt(0)
	v_max3_f32 v150, v142, v150, v214
	v_max_f32_dpp v77, v61, v61 row_ror:8 row_mask:0xf bank_mask:0xf
	v_sub_f32_e32 v45, v92, v150
	s_nop 1
	v_mov_b32_dpp v92, v77 row_shl:4 row_mask:0xf bank_mask:0x5
	v_mov_b32_dpp v92, v77 row_shr:4 row_mask:0xf bank_mask:0xa
	v_sub_f32_e32 v60, v60, v150
	v_mul_f32_e32 v60, 0x3fb8aa3b, v60
	v_exp_f32_e32 v61, v60
	v_sub_f32_e32 v60, v76, v150
	v_max_f32_e32 v76, v92, v92
	v_max_f32_e32 v76, v77, v76
	v_sub_f32_e32 v44, v44, v150
	v_mul_f32_e32 v44, 0x3fb8aa3b, v44
	v_exp_f32_e32 v77, v44
	v_mul_f32_e32 v60, 0x3fb8aa3b, v60
	v_max_f32_dpp v44, v76, v76 quad_perm:[2,3,0,1] row_mask:0xf bank_mask:0xf
	v_exp_f32_e32 v93, v60
	s_nop 1
	v_mov_b32_dpp v60, v44 quad_perm:[1,0,3,2] row_mask:0xf bank_mask:0xf
	v_sub_f32_e32 v142, v142, v150
	v_mul_f32_e32 v76, 0x3fb8aa3b, v142
	v_exp_f32_e32 v142, v76
	v_mul_f32_e32 v45, 0x3fb8aa3b, v45
	v_max3_f32 v149, v143, v44, v60
	v_sub_u32_e32 v44, v96, v181
	v_cmp_gt_u32_e32 vcc, s58, v44
	s_or_b64 vcc, s[2:3], vcc
	v_add_u32_e32 v60, 32, v44
	v_cndmask_b32_e32 v94, v204, v94, vcc
	v_cmp_gt_u32_e32 vcc, s58, v60
	s_or_b64 vcc, s[2:3], vcc
	v_add_u32_e32 v76, 64, v44
	v_cndmask_b32_e32 v62, v204, v62, vcc
	v_cmp_gt_u32_e32 vcc, s58, v76
	s_or_b64 vcc, s[2:3], vcc
	v_add_u32_e32 v44, 0x60, v44
	v_cndmask_b32_e32 v78, v204, v78, vcc
	v_cmp_gt_u32_e32 vcc, s58, v44
	s_or_b64 vcc, s[2:3], vcc
	v_max3_f32 v60, v94, s59, v62
	v_cndmask_b32_e32 v46, v204, v46, vcc
	v_max3_f32 v60, v60, v78, v46
	v_mov_b32_e32 v76, v60
	v_mov_b32_e32 v255, v60
	s_nop 1
	v_permlane16_swap_b32_e32 v76, v255
	v_sub_u32_e32 v96, v96, v182
	v_cmp_gt_u32_e32 vcc, s58, v96
	s_or_b64 vcc, s[2:3], vcc
	v_sub_f32_e32 v92, v217, v149
	v_max_f32_e32 v76, v76, v255
	v_cndmask_b32_e32 v217, v204, v95, vcc
	v_add_u32_e32 v95, 32, v96
	v_cmp_gt_u32_e32 vcc, s58, v95
	s_or_b64 vcc, s[2:3], vcc
	v_add_u32_e32 v95, 64, v96
	v_mul_f32_e32 v60, 0x3fb8aa3b, v92
	v_sub_f32_e32 v92, v218, v149
	v_max_f32_dpp v148, v76, v76 row_ror:8 row_mask:0xf bank_mask:0xf
	v_cndmask_b32_e32 v218, v204, v63, vcc
	v_cmp_gt_u32_e32 vcc, s58, v95
	v_mov_b32_dpp v214, v148 row_shl:4 row_mask:0xf bank_mask:0x5
	v_mov_b32_dpp v214, v148 row_shr:4 row_mask:0xf bank_mask:0xa
	s_or_b64 vcc, s[2:3], vcc
	v_cndmask_b32_e32 v219, v204, v79, vcc
	v_add_u32_e32 v79, 0x60, v96
	v_cmp_gt_u32_e32 vcc, s58, v79
	s_or_b64 vcc, s[2:3], vcc
	v_max3_f32 v63, v217, s59, v218
	v_cndmask_b32_e32 v96, v204, v47, vcc
	v_max_f32_e32 v214, v214, v214
	v_max3_f32 v47, v63, v219, v96
	v_sub_f32_e32 v44, v216, v149
	v_sub_f32_e32 v76, v215, v149
	v_max_f32_e32 v148, v148, v214
	v_mov_b32_e32 v63, v47
	v_mov_b32_e32 v255, v47
	s_nop 1
	v_permlane16_swap_b32_e32 v63, v255
	v_mul_f32_e32 v44, 0x3fb8aa3b, v44
	v_mul_f32_e32 v92, 0x3fb8aa3b, v92
	v_mul_f32_e32 v76, 0x3fb8aa3b, v76
	v_mov_b32_dpp v216, v148 quad_perm:[2,3,0,1] row_mask:0xf bank_mask:0xf
	v_exp_f32_e32 v45, v45
	v_exp_f32_e32 v44, v44
	v_exp_f32_e32 v60, v60
	v_exp_f32_e32 v92, v92
	v_exp_f32_e32 v76, v76
	v_cvt_pk_bf16_f32 v212, v45, v61
	v_cvt_pk_bf16_f32 v213, v93, v77
	v_cvt_pk_bf16_f32 v214, v44, v60
	v_cvt_pk_bf16_f32 v215, v92, v76
	v_max_f32_e32 v216, v216, v216
	v_add_u32_e32 v79, 0xa000, v186
	v_max_f32_e32 v63, v63, v255
	v_max_f32_e32 v148, v148, v216
	ds_write2_b64 v79, v[212:213], v[214:215] offset0:176 offset1:210
	s_nop 0
	v_mov_b32_dpp v216, v148 quad_perm:[1,0,3,2] row_mask:0xf bank_mask:0xf
	v_sub_f32_e32 v143, v143, v149
	v_mul_f32_e32 v143, 0x3fb8aa3b, v143
	v_exp_f32_e32 v135, v135
	s_waitcnt lgkmcnt(0)
	v_max3_f32 v148, v144, v148, v216
	v_max_f32_dpp v79, v63, v63 row_ror:8 row_mask:0xf bank_mask:0xf
	v_sub_f32_e32 v47, v94, v148
	s_nop 1
	v_mov_b32_dpp v94, v79 row_shl:4 row_mask:0xf bank_mask:0x5
	v_mov_b32_dpp v94, v79 row_shr:4 row_mask:0xf bank_mask:0xa
	v_sub_f32_e32 v62, v62, v148
	v_mul_f32_e32 v62, 0x3fb8aa3b, v62
	v_exp_f32_e32 v63, v62
	v_sub_f32_e32 v62, v78, v148
	v_max_f32_e32 v78, v94, v94
	v_max_f32_e32 v78, v79, v78
	v_sub_f32_e32 v46, v46, v148
	v_mul_f32_e32 v46, 0x3fb8aa3b, v46
	v_exp_f32_e32 v79, v46
	v_mul_f32_e32 v62, 0x3fb8aa3b, v62
	v_max_f32_dpp v46, v78, v78 quad_perm:[2,3,0,1] row_mask:0xf bank_mask:0xf
	v_exp_f32_e32 v95, v62
	s_nop 1
	v_mov_b32_dpp v62, v46 quad_perm:[1,0,3,2] row_mask:0xf bank_mask:0xf
	v_sub_f32_e32 v144, v144, v148
	v_mul_f32_e32 v78, 0x3fb8aa3b, v144
	v_exp_f32_e32 v144, v78
	v_mul_f32_e32 v47, 0x3fb8aa3b, v47
	v_max3_f32 v147, v145, v46, v62
	v_sub_f32_e32 v78, v219, v147
	v_mul_f32_e32 v78, 0x3fb8aa3b, v78
	v_sub_f32_e32 v46, v217, v147
	v_sub_f32_e32 v62, v218, v147
	v_exp_f32_e32 v94, v78
	v_sub_f32_e32 v78, v96, v147
	v_sub_f32_e32 v145, v145, v147
	v_mul_f32_e32 v46, 0x3fb8aa3b, v46
	v_mul_f32_e32 v62, 0x3fb8aa3b, v62
	v_mul_f32_e32 v78, 0x3fb8aa3b, v78
	v_exp_f32_e32 v47, v47
	v_exp_f32_e32 v46, v46
	v_exp_f32_e32 v62, v62
	v_exp_f32_e32 v78, v78
	v_mul_f32_e32 v96, 0x3fb8aa3b, v145
	v_exp_f32_e32 v137, v137
	v_exp_f32_e32 v139, v139
	v_exp_f32_e32 v141, v141
	v_exp_f32_e32 v143, v143
	v_exp_f32_e32 v145, v96
	v_cvt_pk_bf16_f32 v208, v47, v63
	v_cvt_pk_bf16_f32 v209, v95, v79
	v_cvt_pk_bf16_f32 v210, v46, v62
	v_cvt_pk_bf16_f32 v211, v94, v78
	v_add_u32_e32 v96, 0xa400, v186
	ds_write2_b64 v96, v[208:209], v[210:211] offset0:116 offset1:150
	v_pk_mul_f32 v[14:15], v[14:15], v[144:145]
	v_pk_mul_f32 v[12:13], v[12:13], v[142:143]
	v_pk_mul_f32 v[10:11], v[10:11], v[140:141]
	v_pk_mul_f32 v[8:9], v[8:9], v[138:139]
	v_pk_mul_f32 v[6:7], v[6:7], v[136:137]
	v_pk_mul_f32 v[4:5], v[4:5], v[134:135]
	v_pk_mul_f32 v[2:3], v[2:3], v[132:133]
	v_pk_mul_f32 v[0:1], v[0:1], v[130:131]
	v_pk_mul_f32 v[30:31], v[30:31], v[144:145]
	v_pk_mul_f32 v[28:29], v[28:29], v[142:143]
	v_pk_mul_f32 v[26:27], v[26:27], v[140:141]
	v_pk_mul_f32 v[24:25], v[24:25], v[138:139]
	v_pk_mul_f32 v[22:23], v[22:23], v[136:137]
	v_pk_mul_f32 v[20:21], v[20:21], v[134:135]
	v_pk_mul_f32 v[18:19], v[18:19], v[132:133]
	v_pk_mul_f32 v[16:17], v[16:17], v[130:131]
	s_mov_b32 s2, -16
	v_mov_b32_e32 v96, v185
	v_mov_b32_e32 v208, v184

.Latt_nm:
	s_nop 7
	s_nop 7
	s_nop 7
	s_add_i32 s6, s53, s49
	v_mbcnt_hi_u32_b32 v148, -1, v195
	v_lshl_add_u32 v96, s6, 7, v183
	v_and_b32_e32 v147, 64, v148
	v_add_u32_e32 v149, 64, v147
	v_xor_b32_e32 v147, 16, v148
	v_cmp_lt_i32_e32 vcc, v147, v149
	v_max3_f32 v150, v80, s59, v48
	v_max3_f32 v150, v150, v64, v32
	v_mov_b32_e32 v151, v150
	v_mov_b32_e32 v255, v150
	s_nop 1
	v_permlane16_swap_b32_e32 v151, v255
	v_add_u32_e32 v187, 0x8800, v186
	v_add_u32_e32 v215, 0x9000, v186
	v_max_f32_e32 v150, v151, v255
	v_xor_b32_e32 v151, 8, v148
	v_cmp_lt_i32_e32 vcc, v151, v149
	s_nop 1
	v_cndmask_b32_e32 v151, v148, v151, vcc
	v_max_f32_dpp v150, v150, v150 row_ror:8 row_mask:0xf bank_mask:0xf
	v_xor_b32_e32 v151, 4, v148
	v_cmp_lt_i32_e32 vcc, v151, v149
	s_nop 1
	v_cndmask_b32_e32 v151, v148, v151, vcc
	s_nop 1
	v_mov_b32_dpp v151, v150 row_shl:4 row_mask:0xf bank_mask:0x5
	s_nop 1
	v_mov_b32_dpp v151, v150 row_shr:4 row_mask:0xf bank_mask:0xa
	v_max_f32_e32 v150, v150, v151
	v_xor_b32_e32 v151, 2, v148
	v_cmp_lt_i32_e32 vcc, v151, v149
	s_nop 1
	v_cndmask_b32_e32 v151, v148, v151, vcc
	v_max_f32_dpp v150, v150, v150 quad_perm:[2,3,0,1] row_mask:0xf bank_mask:0xf
	v_xor_b32_e32 v151, 1, v148
	v_cmp_lt_i32_e32 vcc, v151, v149
	v_sub_u32_e32 v149, v96, v161
	s_nop 0
	v_cndmask_b32_e32 v148, v148, v151, vcc
	v_mov_b32_e32 v151, v81
	v_mov_b32_e32 v152, v49
	v_max3_f32 v49, v151, s59, v152
	v_mov_b32_e32 v153, v65
	v_add_u32_e32 v65, 0x60, v149
	v_mov_b32_dpp v148, v150 quad_perm:[1,0,3,2] row_mask:0xf bank_mask:0xf
	v_mov_b32_e32 v154, v33
	v_max3_f32 v33, v49, v153, v154
	v_mov_b32_e32 v49, v33
	v_mov_b32_e32 v255, v33
	s_nop 1
	v_permlane16_swap_b32_e32 v49, v255
	v_max3_f32 v207, v130, v150, v148
	v_sub_f32_e32 v48, v48, v207
	v_mul_f32_e32 v48, 0x3fb8aa3b, v48
	v_max_f32_e32 v49, v49, v255
	v_sub_f32_e32 v33, v80, v207
	v_sub_f32_e32 v32, v32, v207
	v_mul_f32_e32 v32, 0x3fb8aa3b, v32
	v_sub_f32_e32 v130, v130, v207
	v_max_f32_dpp v65, v49, v49 row_ror:8 row_mask:0xf bank_mask:0xf
	s_nop 1
	v_mov_b32_dpp v80, v65 row_shl:4 row_mask:0xf bank_mask:0x5
	s_nop 1
	v_mov_b32_dpp v80, v65 row_shr:4 row_mask:0xf bank_mask:0xa
	v_exp_f32_e32 v49, v48
	v_sub_f32_e32 v48, v64, v207
	v_mul_f32_e32 v48, 0x3fb8aa3b, v48
	v_exp_f32_e32 v81, v48
	v_max_f32_e32 v64, v80, v80
	v_max_f32_e32 v64, v65, v64
	v_exp_f32_e32 v65, v32
	v_mul_f32_e32 v33, 0x3fb8aa3b, v33
	v_exp_f32_e32 v33, v33
	v_max_f32_dpp v32, v64, v64 quad_perm:[2,3,0,1] row_mask:0xf bank_mask:0xf
	s_nop 1
	v_mov_b32_dpp v48, v32 quad_perm:[1,0,3,2] row_mask:0xf bank_mask:0xf
	v_mul_f32_e32 v64, 0x3fb8aa3b, v130
	v_exp_f32_e32 v130, v64
	v_cvt_pk_bf16_f32 v148, v33, v49
	v_cvt_pk_bf16_f32 v149, v81, v65
	v_max3_f32 v206, v131, v32, v48
	v_max3_f32 v48, v82, s59, v50
	v_max3_f32 v48, v48, v66, v34
	v_mov_b32_e32 v64, v48
	v_mov_b32_e32 v255, v48
	s_nop 1
	v_permlane16_swap_b32_e32 v64, v255
	v_sub_f32_e32 v32, v151, v206
	v_sub_f32_e32 v80, v152, v206
	v_mul_f32_e32 v32, 0x3fb8aa3b, v32
	v_exp_f32_e32 v32, v32
	v_max_f32_e32 v64, v64, v255
	v_mul_f32_e32 v48, 0x3fb8aa3b, v80
	v_sub_f32_e32 v80, v153, v206
	v_mul_f32_e32 v80, 0x3fb8aa3b, v80
	v_exp_f32_e32 v48, v48
	v_max_f32_dpp v150, v64, v64 row_ror:8 row_mask:0xf bank_mask:0xf
	v_sub_f32_e32 v64, v154, v206
	v_sub_u32_e32 v154, v96, v170
	v_mov_b32_dpp v151, v150 row_shl:4 row_mask:0xf bank_mask:0x5
	s_nop 1
	v_mov_b32_dpp v151, v150 row_shr:4 row_mask:0xf bank_mask:0xa
	v_mov_b32_e32 v155, v83
	v_mov_b32_e32 v156, v51
	v_max3_f32 v51, v155, s59, v156
	v_mov_b32_e32 v160, v67
	v_add_u32_e32 v67, 0x60, v154
	v_max_f32_e32 v151, v151, v151
	v_mov_b32_e32 v154, v35
	v_max3_f32 v35, v51, v160, v154
	v_max_f32_e32 v152, v150, v151
	v_mov_b32_e32 v51, v35
	v_mov_b32_e32 v255, v35
	s_nop 1
	v_permlane16_swap_b32_e32 v51, v255
	v_mov_b32_dpp v153, v152 quad_perm:[2,3,0,1] row_mask:0xf bank_mask:0xf
	v_mul_f32_e32 v64, 0x3fb8aa3b, v64
	v_exp_f32_e32 v80, v80
	v_exp_f32_e32 v64, v64
	v_max_f32_e32 v153, v153, v153
	v_max_f32_e32 v51, v51, v255
	v_max_f32_e32 v152, v152, v153
	s_nop 1
	v_mov_b32_dpp v153, v152 quad_perm:[1,0,3,2] row_mask:0xf bank_mask:0xf
	v_cvt_pk_bf16_f32 v150, v32, v48
	v_cvt_pk_bf16_f32 v151, v80, v64
	ds_write2_b64 v187, v[148:149], v[150:151] offset0:128 offset1:162
	v_max3_f32 v189, v132, v152, v153
	v_max_f32_dpp v67, v51, v51 row_ror:8 row_mask:0xf bank_mask:0xf
	v_sub_f32_e32 v35, v82, v189
	s_nop 1
	v_mov_b32_dpp v82, v67 row_shl:4 row_mask:0xf bank_mask:0x5
	s_nop 1
	v_mov_b32_dpp v82, v67 row_shr:4 row_mask:0xf bank_mask:0xa
	v_sub_f32_e32 v50, v50, v189
	v_mul_f32_e32 v50, 0x3fb8aa3b, v50
	v_exp_f32_e32 v51, v50
	v_sub_f32_e32 v50, v66, v189
	s_waitcnt lgkmcnt(0)
	v_max_f32_e32 v66, v82, v82
	v_max_f32_e32 v66, v67, v66
	v_sub_f32_e32 v34, v34, v189
	v_mul_f32_e32 v34, 0x3fb8aa3b, v34
	v_exp_f32_e32 v67, v34
	v_mul_f32_e32 v50, 0x3fb8aa3b, v50
	v_max_f32_dpp v34, v66, v66 quad_perm:[2,3,0,1] row_mask:0xf bank_mask:0xf
	v_exp_f32_e32 v83, v50
	s_nop 1
	v_mov_b32_dpp v50, v34 quad_perm:[1,0,3,2] row_mask:0xf bank_mask:0xf
	v_sub_f32_e32 v132, v132, v189
	v_mul_f32_e32 v66, 0x3fb8aa3b, v132
	v_exp_f32_e32 v132, v66
	v_mul_f32_e32 v35, 0x3fb8aa3b, v35
	v_max3_f32 v188, v133, v34, v50
	v_sub_u32_e32 v34, v96, v171
	v_add_u32_e32 v66, 64, v34
	v_max3_f32 v50, v84, s59, v52
	v_mov_b32_e32 v150, v36
	v_max3_f32 v34, v50, v68, v150
	v_mov_b32_e32 v36, v34
	v_mov_b32_e32 v255, v34
	s_nop 1
	v_permlane16_swap_b32_e32 v36, v255
	v_sub_f32_e32 v151, v154, v188
	v_sub_f32_e32 v50, v133, v188
	v_mul_f32_e32 v133, 0x3fb8aa3b, v50
	v_sub_f32_e32 v50, v155, v188
	v_max_f32_e32 v36, v36, v255
	s_nop 1
	v_mov_b32_dpp v66, v36 row_ror:8 row_mask:0xf bank_mask:0xf
	v_mul_f32_e32 v50, 0x3fb8aa3b, v50
	v_exp_f32_e32 v34, v50
	v_sub_f32_e32 v50, v156, v188
	v_sub_f32_e32 v82, v160, v188
	v_max_f32_e32 v66, v66, v66
	v_max_f32_e32 v36, v36, v66
	s_nop 1
	v_mov_b32_dpp v66, v36 row_shl:4 row_mask:0xf bank_mask:0x5
	s_nop 1
	v_mov_b32_dpp v66, v36 row_shr:4 row_mask:0xf bank_mask:0xa
	v_mul_f32_e32 v50, 0x3fb8aa3b, v50
	v_mul_f32_e32 v82, 0x3fb8aa3b, v82
	v_exp_f32_e32 v35, v35
	v_exp_f32_e32 v50, v50
	v_max_f32_e32 v66, v66, v66
	v_max_f32_e32 v152, v36, v66
	s_nop 1
	v_mov_b32_dpp v153, v152 quad_perm:[2,3,0,1] row_mask:0xf bank_mask:0xf
	v_mul_f32_e32 v36, 0x3fb8aa3b, v151
	v_exp_f32_e32 v82, v82
	v_exp_f32_e32 v66, v36
	v_cvt_pk_bf16_f32 v148, v35, v51
	v_max_f32_e32 v151, v153, v153
	v_cvt_pk_bf16_f32 v149, v83, v67
	v_mov_b32_e32 v154, v85
	v_mov_b32_e32 v155, v53
	v_max3_f32 v53, v154, s59, v155
	v_mov_b32_e32 v156, v69
	v_cvt_pk_bf16_f32 v36, v34, v50
	v_mov_b32_e32 v153, v37
	v_max3_f32 v53, v53, v156, v153
	v_mov_b32_e32 v69, v53
	v_mov_b32_e32 v255, v53
	s_nop 1
	v_permlane16_swap_b32_e32 v69, v255
	s_nop 1
	v_mov_b32_dpp v69, v255 quad_perm:[0,1,2,3] row_mask:0x5 bank_mask:0xf
	v_cvt_pk_bf16_f32 v37, v82, v66
	ds_write2_b64 v187, v[148:149], v[36:37] offset0:196 offset1:230
	v_max_f32_e32 v151, v152, v151
	s_nop 1
	v_mov_b32_dpp v152, v151 quad_perm:[1,0,3,2] row_mask:0xf bank_mask:0xf
	v_max_f32_e32 v37, v69, v69
	v_max_f32_e32 v53, v53, v37
	v_sub_f32_e32 v131, v131, v206
	s_waitcnt lgkmcnt(0)
	v_max3_f32 v187, v134, v151, v152
	v_sub_f32_e32 v37, v84, v187
	v_sub_f32_e32 v52, v52, v187
	v_max_f32_dpp v69, v53, v53 row_ror:8 row_mask:0xf bank_mask:0xf
	s_nop 1
	v_mov_b32_dpp v84, v69 row_shl:4 row_mask:0xf bank_mask:0x5
	s_nop 1
	v_mov_b32_dpp v84, v69 row_shr:4 row_mask:0xf bank_mask:0xa
	v_mul_f32_e32 v52, 0x3fb8aa3b, v52
	v_exp_f32_e32 v53, v52
	v_sub_f32_e32 v52, v68, v187
	v_mul_f32_e32 v52, 0x3fb8aa3b, v52
	v_max_f32_e32 v68, v84, v84
	v_max_f32_e32 v68, v69, v68
	v_exp_f32_e32 v85, v52
	v_sub_f32_e32 v52, v150, v187
	v_mul_f32_e32 v52, 0x3fb8aa3b, v52
	v_exp_f32_e32 v69, v52
	s_nop 0
	v_max_f32_dpp v52, v68, v68 quad_perm:[2,3,0,1] row_mask:0xf bank_mask:0xf
	s_nop 1
	v_mov_b32_dpp v68, v52 quad_perm:[1,0,3,2] row_mask:0xf bank_mask:0xf
	v_sub_f32_e32 v36, v134, v187
	v_mul_f32_e32 v36, 0x3fb8aa3b, v36
	v_exp_f32_e32 v134, v36
	v_max3_f32 v160, v135, v52, v68
	v_max3_f32 v52, v86, s59, v54
	v_max3_f32 v52, v52, v70, v38
	v_mov_b32_e32 v68, v52
	v_mov_b32_e32 v255, v52
	s_nop 1
	v_permlane16_swap_b32_e32 v68, v255
	v_sub_f32_e32 v36, v154, v160
	v_sub_u32_e32 v154, v96, v174
	v_max_f32_e32 v68, v68, v255
	s_nop 1
	v_mov_b32_e32 v212, v87
	v_max_f32_dpp v150, v68, v68 row_ror:8 row_mask:0xf bank_mask:0xf
	v_mov_b32_e32 v213, v55
	s_nop 0
	v_mov_b32_dpp v151, v150 row_shl:4 row_mask:0xf bank_mask:0x5
	s_nop 1
	v_mov_b32_dpp v151, v150 row_shr:4 row_mask:0xf bank_mask:0xa
	v_mov_b32_e32 v214, v71
	v_add_u32_e32 v71, 0x60, v154
	v_max3_f32 v55, v212, s59, v213
	v_mov_b32_e32 v154, v39
	v_max_f32_e32 v151, v151, v151
	v_max3_f32 v39, v55, v214, v154
	v_max_f32_e32 v152, v150, v151
	v_mov_b32_e32 v55, v39
	v_mov_b32_e32 v255, v39
	s_nop 1
	v_permlane16_swap_b32_e32 v55, v255
	v_sub_f32_e32 v68, v153, v160
	v_mov_b32_dpp v153, v152 quad_perm:[2,3,0,1] row_mask:0xf bank_mask:0xf
	v_sub_f32_e32 v84, v155, v160
	v_mul_f32_e32 v52, 0x3fb8aa3b, v84
	v_max_f32_e32 v55, v55, v255
	v_max_f32_e32 v153, v153, v153
	v_max_f32_e32 v152, v152, v153
	s_nop 0
	s_nop 1
	v_mov_b32_dpp v153, v152 quad_perm:[1,0,3,2] row_mask:0xf bank_mask:0xf
	v_sub_f32_e32 v84, v156, v160
	v_mul_f32_e32 v37, 0x3fb8aa3b, v37
	v_mul_f32_e32 v36, 0x3fb8aa3b, v36
	v_max3_f32 v156, v136, v152, v153
	v_max_f32_dpp v71, v55, v55 row_ror:8 row_mask:0xf bank_mask:0xf
	v_sub_f32_e32 v39, v86, v156
	s_nop 1
	v_mov_b32_dpp v86, v71 row_shl:4 row_mask:0xf bank_mask:0x5
	s_nop 1
	v_mov_b32_dpp v86, v71 row_shr:4 row_mask:0xf bank_mask:0xa
	v_sub_f32_e32 v54, v54, v156
	v_mul_f32_e32 v54, 0x3fb8aa3b, v54
	v_exp_f32_e32 v55, v54
	v_sub_f32_e32 v54, v70, v156
	v_max_f32_e32 v70, v86, v86
	v_max_f32_e32 v70, v71, v70
	v_sub_f32_e32 v38, v38, v156
	v_mul_f32_e32 v38, 0x3fb8aa3b, v38
	v_exp_f32_e32 v71, v38
	v_mul_f32_e32 v54, 0x3fb8aa3b, v54
	v_max_f32_dpp v38, v70, v70 quad_perm:[2,3,0,1] row_mask:0xf bank_mask:0xf
	v_exp_f32_e32 v87, v54
	s_nop 1
	v_mov_b32_dpp v54, v38 quad_perm:[1,0,3,2] row_mask:0xf bank_mask:0xf
	v_sub_f32_e32 v136, v136, v156
	v_mul_f32_e32 v84, 0x3fb8aa3b, v84
	v_mul_f32_e32 v68, 0x3fb8aa3b, v68
	v_mul_f32_e32 v70, 0x3fb8aa3b, v136
	v_max3_f32 v155, v137, v38, v54
	v_sub_u32_e32 v38, v96, v175
	v_exp_f32_e32 v37, v37
	v_exp_f32_e32 v36, v36
	v_exp_f32_e32 v52, v52
	v_exp_f32_e32 v84, v84
	v_exp_f32_e32 v68, v68
	v_exp_f32_e32 v136, v70
	v_add_u32_e32 v70, 64, v38
	v_cvt_pk_bf16_f32 v148, v37, v53
	v_cvt_pk_bf16_f32 v149, v85, v69
	v_cvt_pk_bf16_f32 v150, v36, v52
	v_cvt_pk_bf16_f32 v151, v84, v68
	ds_write2_b64 v215, v[148:149], v[150:151] offset0:144 offset1:178
	v_max3_f32 v54, v88, s59, v56
	v_mov_b32_e32 v150, v40
	v_max3_f32 v38, v54, v72, v150
	v_mov_b32_e32 v40, v38
	v_mov_b32_e32 v255, v38
	s_nop 1
	v_permlane16_swap_b32_e32 v40, v255
	v_sub_f32_e32 v151, v154, v155
	v_sub_f32_e32 v54, v137, v155
	v_mul_f32_e32 v137, 0x3fb8aa3b, v54
	v_sub_f32_e32 v54, v212, v155
	s_waitcnt lgkmcnt(0)
	v_max_f32_e32 v40, v40, v255
	s_nop 1
	v_mov_b32_dpp v70, v40 row_ror:8 row_mask:0xf bank_mask:0xf
	v_mul_f32_e32 v54, 0x3fb8aa3b, v54
	v_exp_f32_e32 v38, v54
	v_sub_f32_e32 v54, v213, v155
	v_sub_f32_e32 v86, v214, v155
	v_max_f32_e32 v70, v70, v70
	v_max_f32_e32 v40, v40, v70
	s_nop 1
	v_mov_b32_dpp v70, v40 row_shl:4 row_mask:0xf bank_mask:0x5
	s_nop 1
	v_mov_b32_dpp v70, v40 row_shr:4 row_mask:0xf bank_mask:0xa
	v_mul_f32_e32 v39, 0x3fb8aa3b, v39
	v_mul_f32_e32 v54, 0x3fb8aa3b, v54
	v_mul_f32_e32 v86, 0x3fb8aa3b, v86
	v_exp_f32_e32 v39, v39
	v_max_f32_e32 v70, v70, v70
	v_max_f32_e32 v152, v40, v70
	v_mul_f32_e32 v40, 0x3fb8aa3b, v151
	v_exp_f32_e32 v54, v54
	v_exp_f32_e32 v86, v86
	v_exp_f32_e32 v70, v40
	v_cvt_pk_bf16_f32 v148, v39, v55
	v_mov_b32_e32 v212, v89
	v_mov_b32_e32 v213, v57
	v_max3_f32 v57, v212, s59, v213
	v_mov_b32_e32 v214, v73
	v_cvt_pk_bf16_f32 v149, v87, v71
	v_mov_b32_e32 v216, v41
	v_max3_f32 v57, v57, v214, v216
	v_mov_b32_e32 v73, v57
	v_mov_b32_e32 v255, v57
	s_nop 1
	v_permlane16_swap_b32_e32 v73, v255
	s_nop 1
	v_mov_b32_dpp v73, v255 quad_perm:[0,1,2,3] row_mask:0x5 bank_mask:0xf
	v_cvt_pk_bf16_f32 v40, v38, v54
	v_cvt_pk_bf16_f32 v41, v86, v70
	ds_write2_b64 v215, v[148:149], v[40:41] offset0:212 offset1:246
	v_max_f32_dpp v151, v152, v152 quad_perm:[2,3,0,1] row_mask:0xf bank_mask:0xf
	v_max_f32_e32 v41, v73, v73
	v_max_f32_e32 v57, v57, v41
	v_mov_b32_dpp v152, v151 quad_perm:[1,0,3,2] row_mask:0xf bank_mask:0xf
	v_sub_f32_e32 v135, v135, v160
	v_mul_f32_e32 v131, 0x3fb8aa3b, v131
	v_mul_f32_e32 v135, 0x3fb8aa3b, v135
	s_waitcnt lgkmcnt(0)
	v_max3_f32 v154, v138, v151, v152
	v_max_f32_dpp v73, v57, v57 row_ror:8 row_mask:0xf bank_mask:0xf
	v_sub_f32_e32 v41, v88, v154
	s_nop 1
	v_mov_b32_dpp v88, v73 row_shl:4 row_mask:0xf bank_mask:0x5
	s_nop 1
	v_mov_b32_dpp v88, v73 row_shr:4 row_mask:0xf bank_mask:0xa
	v_sub_f32_e32 v56, v56, v154
	v_mul_f32_e32 v56, 0x3fb8aa3b, v56
	v_exp_f32_e32 v57, v56
	v_sub_f32_e32 v56, v72, v154
	v_max_f32_e32 v72, v88, v88
	v_max_f32_e32 v72, v73, v72
	v_mul_f32_e32 v56, 0x3fb8aa3b, v56
	v_exp_f32_e32 v89, v56
	v_sub_f32_e32 v56, v150, v154
	v_mul_f32_e32 v56, 0x3fb8aa3b, v56
	v_exp_f32_e32 v73, v56
	s_nop 0
	v_max_f32_dpp v56, v72, v72 quad_perm:[2,3,0,1] row_mask:0xf bank_mask:0xf
	s_nop 1
	v_mov_b32_dpp v72, v56 quad_perm:[1,0,3,2] row_mask:0xf bank_mask:0xf
	v_sub_f32_e32 v40, v138, v154
	v_mul_f32_e32 v40, 0x3fb8aa3b, v40
	v_exp_f32_e32 v138, v40
	v_max3_f32 v153, v139, v56, v72
	v_max3_f32 v56, v90, s59, v58
	v_max3_f32 v56, v56, v74, v42
	v_mov_b32_e32 v72, v56
	v_mov_b32_e32 v255, v56
	s_nop 1
	v_permlane16_swap_b32_e32 v72, v255
	v_sub_f32_e32 v88, v213, v153
	v_max_f32_e32 v72, v72, v255
	v_mul_f32_e32 v56, 0x3fb8aa3b, v88
	v_sub_f32_e32 v88, v214, v153
	v_mov_b32_e32 v214, v91
	v_max_f32_dpp v150, v72, v72 row_ror:8 row_mask:0xf bank_mask:0xf
	v_mov_b32_e32 v215, v59
	s_nop 0
	v_mov_b32_dpp v151, v150 row_shl:4 row_mask:0xf bank_mask:0x5
	s_nop 1
	v_mov_b32_dpp v151, v150 row_shr:4 row_mask:0xf bank_mask:0xa
	v_sub_f32_e32 v72, v216, v153
	v_mov_b32_e32 v216, v75
	v_max3_f32 v59, v214, s59, v215
	v_mov_b32_e32 v213, v43
	v_max_f32_e32 v151, v151, v151
	v_max3_f32 v43, v59, v216, v213
	v_sub_f32_e32 v40, v212, v153
	v_max_f32_e32 v152, v150, v151
	v_mov_b32_e32 v59, v43
	v_mov_b32_e32 v255, v43
	s_nop 1
	v_permlane16_swap_b32_e32 v59, v255
	v_mul_f32_e32 v41, 0x3fb8aa3b, v41
	v_mul_f32_e32 v40, 0x3fb8aa3b, v40
	v_mul_f32_e32 v88, 0x3fb8aa3b, v88
	v_mul_f32_e32 v72, 0x3fb8aa3b, v72
	v_mov_b32_dpp v212, v152 quad_perm:[2,3,0,1] row_mask:0xf bank_mask:0xf
	v_exp_f32_e32 v41, v41
	v_exp_f32_e32 v40, v40
	v_exp_f32_e32 v56, v56
	v_exp_f32_e32 v88, v88
	v_exp_f32_e32 v72, v72
	v_cvt_pk_bf16_f32 v148, v41, v57
	v_cvt_pk_bf16_f32 v149, v89, v73
	v_cvt_pk_bf16_f32 v150, v40, v56
	v_cvt_pk_bf16_f32 v151, v88, v72
	v_max_f32_e32 v212, v212, v212
	v_add_u32_e32 v75, 0x9800, v186
	v_max_f32_e32 v59, v59, v255
	v_max_f32_e32 v152, v152, v212
	ds_write2_b64 v75, v[148:149], v[150:151] offset0:160 offset1:194
	s_nop 0
	v_mov_b32_dpp v212, v152 quad_perm:[1,0,3,2] row_mask:0xf bank_mask:0xf
	v_sub_f32_e32 v139, v139, v153
	v_mul_f32_e32 v139, 0x3fb8aa3b, v139
	v_exp_f32_e32 v131, v131
	s_waitcnt lgkmcnt(0)
	v_max3_f32 v152, v140, v152, v212
	v_max_f32_dpp v75, v59, v59 row_ror:8 row_mask:0xf bank_mask:0xf
	v_sub_f32_e32 v43, v90, v152
	s_nop 1
	v_mov_b32_dpp v90, v75 row_shl:4 row_mask:0xf bank_mask:0x5
	s_nop 1
	v_mov_b32_dpp v90, v75 row_shr:4 row_mask:0xf bank_mask:0xa
	v_sub_f32_e32 v58, v58, v152
	v_mul_f32_e32 v58, 0x3fb8aa3b, v58
	v_exp_f32_e32 v59, v58
	v_sub_f32_e32 v58, v74, v152
	v_max_f32_e32 v74, v90, v90
	v_max_f32_e32 v74, v75, v74
	v_sub_f32_e32 v42, v42, v152
	v_mul_f32_e32 v42, 0x3fb8aa3b, v42
	v_exp_f32_e32 v75, v42
	v_mul_f32_e32 v58, 0x3fb8aa3b, v58
	v_max_f32_dpp v42, v74, v74 quad_perm:[2,3,0,1] row_mask:0xf bank_mask:0xf
	v_exp_f32_e32 v91, v58
	s_nop 1
	v_mov_b32_dpp v58, v42 quad_perm:[1,0,3,2] row_mask:0xf bank_mask:0xf
	v_sub_f32_e32 v140, v140, v152
	v_mul_f32_e32 v74, 0x3fb8aa3b, v140
	v_exp_f32_e32 v140, v74
	v_mul_f32_e32 v43, 0x3fb8aa3b, v43
	v_max3_f32 v151, v141, v42, v58
	v_max3_f32 v58, v92, s59, v60
	v_max3_f32 v58, v58, v76, v44
	v_mov_b32_e32 v74, v58
	v_mov_b32_e32 v255, v58
	s_nop 1
	v_permlane16_swap_b32_e32 v74, v255
	v_sub_f32_e32 v90, v215, v151
	v_max_f32_e32 v74, v74, v255
	v_mul_f32_e32 v58, 0x3fb8aa3b, v90
	v_sub_f32_e32 v90, v216, v151
	v_mov_b32_e32 v216, v93
	v_max_f32_dpp v150, v74, v74 row_ror:8 row_mask:0xf bank_mask:0xf
	v_mov_b32_e32 v217, v61
	s_nop 0
	v_mov_b32_dpp v212, v150 row_shl:4 row_mask:0xf bank_mask:0x5
	s_nop 1
	v_mov_b32_dpp v212, v150 row_shr:4 row_mask:0xf bank_mask:0xa
	v_mov_b32_e32 v218, v77
	v_max3_f32 v61, v216, s59, v217
	v_mov_b32_e32 v215, v45
	v_max_f32_e32 v212, v212, v212
	v_max3_f32 v45, v61, v218, v215
	v_sub_f32_e32 v42, v214, v151
	v_sub_f32_e32 v74, v213, v151
	v_max_f32_e32 v150, v150, v212
	v_mov_b32_e32 v61, v45
	v_mov_b32_e32 v255, v45
	s_nop 1
	v_permlane16_swap_b32_e32 v61, v255
	v_mul_f32_e32 v42, 0x3fb8aa3b, v42
	v_mul_f32_e32 v90, 0x3fb8aa3b, v90
	v_mul_f32_e32 v74, 0x3fb8aa3b, v74
	v_mov_b32_dpp v214, v150 quad_perm:[2,3,0,1] row_mask:0xf bank_mask:0xf
	v_exp_f32_e32 v43, v43
	v_exp_f32_e32 v42, v42
	v_exp_f32_e32 v58, v58
	v_exp_f32_e32 v90, v90
	v_exp_f32_e32 v74, v74
	v_cvt_pk_bf16_f32 v148, v43, v59
	v_cvt_pk_bf16_f32 v149, v91, v75
	v_cvt_pk_bf16_f32 v212, v42, v58
	v_cvt_pk_bf16_f32 v213, v90, v74
	v_max_f32_e32 v214, v214, v214
	v_add_u32_e32 v77, 0x9c00, v186
	v_max_f32_e32 v61, v61, v255
	v_max_f32_e32 v150, v150, v214
	ds_write2_b64 v77, v[148:149], v[212:213] offset0:100 offset1:134
	s_nop 0
	v_mov_b32_dpp v214, v150 quad_perm:[1,0,3,2] row_mask:0xf bank_mask:0xf
	v_sub_f32_e32 v141, v141, v151
	v_mul_f32_e32 v141, 0x3fb8aa3b, v141
	v_exp_f32_e32 v133, v133
	s_waitcnt lgkmcnt(0)
	v_max3_f32 v150, v142, v150, v214
	v_max_f32_dpp v77, v61, v61 row_ror:8 row_mask:0xf bank_mask:0xf
	v_sub_f32_e32 v45, v92, v150
	s_nop 1
	v_mov_b32_dpp v92, v77 row_shl:4 row_mask:0xf bank_mask:0x5
	s_nop 1
	v_mov_b32_dpp v92, v77 row_shr:4 row_mask:0xf bank_mask:0xa
	v_sub_f32_e32 v60, v60, v150
	v_mul_f32_e32 v60, 0x3fb8aa3b, v60
	v_exp_f32_e32 v61, v60
	v_sub_f32_e32 v60, v76, v150
	v_max_f32_e32 v76, v92, v92
	v_max_f32_e32 v76, v77, v76
	v_sub_f32_e32 v44, v44, v150
	v_mul_f32_e32 v44, 0x3fb8aa3b, v44
	v_exp_f32_e32 v77, v44
	v_mul_f32_e32 v60, 0x3fb8aa3b, v60
	v_max_f32_dpp v44, v76, v76 quad_perm:[2,3,0,1] row_mask:0xf bank_mask:0xf
	v_exp_f32_e32 v93, v60
	s_nop 1
	v_mov_b32_dpp v60, v44 quad_perm:[1,0,3,2] row_mask:0xf bank_mask:0xf
	v_sub_f32_e32 v142, v142, v150
	v_mul_f32_e32 v76, 0x3fb8aa3b, v142
	v_exp_f32_e32 v142, v76
	v_mul_f32_e32 v45, 0x3fb8aa3b, v45
	v_max3_f32 v149, v143, v44, v60
	v_max3_f32 v60, v94, s59, v62
	v_max3_f32 v60, v60, v78, v46
	v_mov_b32_e32 v76, v60
	v_mov_b32_e32 v255, v60
	s_nop 1
	v_permlane16_swap_b32_e32 v76, v255
	v_sub_f32_e32 v92, v217, v149
	v_max_f32_e32 v76, v76, v255
	v_mov_b32_e32 v217, v95
	v_mul_f32_e32 v60, 0x3fb8aa3b, v92
	v_sub_f32_e32 v92, v218, v149
	v_max_f32_dpp v148, v76, v76 row_ror:8 row_mask:0xf bank_mask:0xf
	v_mov_b32_e32 v218, v63
	s_nop 0
	v_mov_b32_dpp v214, v148 row_shl:4 row_mask:0xf bank_mask:0x5
	s_nop 1
	v_mov_b32_dpp v214, v148 row_shr:4 row_mask:0xf bank_mask:0xa
	v_mov_b32_e32 v219, v79
	v_max3_f32 v63, v217, s59, v218
	v_mov_b32_e32 v96, v47
	v_max_f32_e32 v214, v214, v214
	v_max3_f32 v47, v63, v219, v96
	v_sub_f32_e32 v44, v216, v149
	v_sub_f32_e32 v76, v215, v149
	v_max_f32_e32 v148, v148, v214
	v_mov_b32_e32 v63, v47
	v_mov_b32_e32 v255, v47
	s_nop 1
	v_permlane16_swap_b32_e32 v63, v255
	v_mul_f32_e32 v44, 0x3fb8aa3b, v44
	v_mul_f32_e32 v92, 0x3fb8aa3b, v92
	v_mul_f32_e32 v76, 0x3fb8aa3b, v76
	v_mov_b32_dpp v216, v148 quad_perm:[2,3,0,1] row_mask:0xf bank_mask:0xf
	v_exp_f32_e32 v45, v45
	v_exp_f32_e32 v44, v44
	v_exp_f32_e32 v60, v60
	v_exp_f32_e32 v92, v92
	v_exp_f32_e32 v76, v76
	v_cvt_pk_bf16_f32 v212, v45, v61
	v_cvt_pk_bf16_f32 v213, v93, v77
	v_cvt_pk_bf16_f32 v214, v44, v60
	v_cvt_pk_bf16_f32 v215, v92, v76
	v_max_f32_e32 v216, v216, v216
	v_add_u32_e32 v79, 0xa000, v186
	v_max_f32_e32 v63, v63, v255
	v_max_f32_e32 v148, v148, v216
	ds_write2_b64 v79, v[212:213], v[214:215] offset0:176 offset1:210
	s_nop 0
	v_mov_b32_dpp v216, v148 quad_perm:[1,0,3,2] row_mask:0xf bank_mask:0xf
	v_sub_f32_e32 v143, v143, v149
	v_mul_f32_e32 v143, 0x3fb8aa3b, v143
	v_exp_f32_e32 v135, v135
	s_waitcnt lgkmcnt(0)
	v_max3_f32 v148, v144, v148, v216
	v_max_f32_dpp v79, v63, v63 row_ror:8 row_mask:0xf bank_mask:0xf
	v_sub_f32_e32 v47, v94, v148
	s_nop 1
	v_mov_b32_dpp v94, v79 row_shl:4 row_mask:0xf bank_mask:0x5
	s_nop 1
	v_mov_b32_dpp v94, v79 row_shr:4 row_mask:0xf bank_mask:0xa
	v_sub_f32_e32 v62, v62, v148
	v_mul_f32_e32 v62, 0x3fb8aa3b, v62
	v_exp_f32_e32 v63, v62
	v_sub_f32_e32 v62, v78, v148
	v_max_f32_e32 v78, v94, v94
	v_max_f32_e32 v78, v79, v78
	v_sub_f32_e32 v46, v46, v148
	v_mul_f32_e32 v46, 0x3fb8aa3b, v46
	v_exp_f32_e32 v79, v46
	v_mul_f32_e32 v62, 0x3fb8aa3b, v62
	v_max_f32_dpp v46, v78, v78 quad_perm:[2,3,0,1] row_mask:0xf bank_mask:0xf
	v_exp_f32_e32 v95, v62
	s_nop 1
	v_mov_b32_dpp v62, v46 quad_perm:[1,0,3,2] row_mask:0xf bank_mask:0xf
	v_sub_f32_e32 v144, v144, v148
	v_mul_f32_e32 v78, 0x3fb8aa3b, v144
	v_exp_f32_e32 v144, v78
	v_mul_f32_e32 v47, 0x3fb8aa3b, v47
	v_max3_f32 v147, v145, v46, v62
	v_sub_f32_e32 v78, v219, v147
	v_mul_f32_e32 v78, 0x3fb8aa3b, v78
	v_sub_f32_e32 v46, v217, v147
	v_sub_f32_e32 v62, v218, v147
	v_exp_f32_e32 v94, v78
	v_sub_f32_e32 v78, v96, v147
	v_sub_f32_e32 v145, v145, v147
	v_mul_f32_e32 v46, 0x3fb8aa3b, v46
	v_mul_f32_e32 v62, 0x3fb8aa3b, v62
	v_mul_f32_e32 v78, 0x3fb8aa3b, v78
	v_exp_f32_e32 v47, v47
	v_exp_f32_e32 v46, v46
	v_exp_f32_e32 v62, v62
	v_exp_f32_e32 v78, v78
	v_mul_f32_e32 v96, 0x3fb8aa3b, v145
	v_exp_f32_e32 v137, v137
	v_exp_f32_e32 v139, v139
	v_exp_f32_e32 v141, v141
	v_exp_f32_e32 v143, v143
	v_exp_f32_e32 v145, v96
	v_cvt_pk_bf16_f32 v208, v47, v63
	v_cvt_pk_bf16_f32 v209, v95, v79
	v_cvt_pk_bf16_f32 v210, v46, v62
	v_cvt_pk_bf16_f32 v211, v94, v78
	v_add_u32_e32 v96, 0xa400, v186
	ds_write2_b64 v96, v[208:209], v[210:211] offset0:116 offset1:150
	v_pk_mul_f32 v[14:15], v[14:15], v[144:145]
	v_pk_mul_f32 v[12:13], v[12:13], v[142:143]
	v_pk_mul_f32 v[10:11], v[10:11], v[140:141]
	v_pk_mul_f32 v[8:9], v[8:9], v[138:139]
	v_pk_mul_f32 v[6:7], v[6:7], v[136:137]
	v_pk_mul_f32 v[4:5], v[4:5], v[134:135]
	v_pk_mul_f32 v[2:3], v[2:3], v[132:133]
	v_pk_mul_f32 v[0:1], v[0:1], v[130:131]
	v_pk_mul_f32 v[30:31], v[30:31], v[144:145]
	v_pk_mul_f32 v[28:29], v[28:29], v[142:143]
	v_pk_mul_f32 v[26:27], v[26:27], v[140:141]
	v_pk_mul_f32 v[24:25], v[24:25], v[138:139]
	v_pk_mul_f32 v[22:23], v[22:23], v[136:137]
	v_pk_mul_f32 v[20:21], v[20:21], v[134:135]
	v_pk_mul_f32 v[18:19], v[18:19], v[132:133]
	v_pk_mul_f32 v[16:17], v[16:17], v[130:131]
	s_mov_b32 s2, -16
	v_mov_b32_e32 v96, v185
	v_mov_b32_e32 v208, v184
	s_branch .Latt_join

.LBB0_763:
	s_waitcnt vmcnt(0)
	s_barrier
	s_mov_b64 s[0:1], exec
	v_readlane_b32 s2, v251, 0
	v_readlane_b32 s3, v251, 1
	s_and_b64 s[2:3], s[0:1], s[2:3]
	s_mov_b64 exec, s[2:3]
	s_branch .LBB0_811
	v_readlane_b32 s2, v249, 49
	s_waitcnt expcnt(0) lgkmcnt(0)
	s_nop 0
	v_mov_b32_e32 v0, s2
	ds_read_b32 v2, v0
	v_readlane_b32 s2, v249, 50
	s_waitcnt lgkmcnt(0)
	v_cmp_ne_u32_e32 vcc, 0, v2
	v_mov_b32_e32 v0, s2
	ds_read_b32 v0, v0
	s_cbranch_vccnz .LBB0_779
	s_mov_b32 s4, 1
	s_branch .LBB0_767

.LBB0_859:
	v_add_u32_e32 v67, v65, v64
	ds_read_b128 v[76:79], v65 offset:18432
	ds_read_b128 v[80:83], v67
	s_add_i32 s0, s0, 32
	s_cmp_lt_u32 s0, 48
	s_waitcnt lgkmcnt(0)
	v_mfma_f32_32x32x16_bf16 v[48:63], v[80:83], v[76:79], v[48:63]
	ds_read_b128 v[76:79], v65 offset:23040
	s_waitcnt lgkmcnt(0)
	v_mfma_f32_32x32x16_bf16 v[16:31], v[80:83], v[76:79], v[16:31]
	ds_read_b128 v[76:79], v65 offset:27648
	s_waitcnt lgkmcnt(0)
	v_mfma_f32_32x32x16_bf16 v[32:47], v[80:83], v[76:79], v[32:47]
	ds_read_b128 v[76:79], v65 offset:32256
	ds_read_b128 v[84:87], v65 offset:18464
	s_waitcnt lgkmcnt(1)
	v_mfma_f32_32x32x16_bf16 v[0:15], v[80:83], v[76:79], v[0:15]
	ds_read_b128 v[76:79], v67 offset:32
	ds_read_b128 v[80:83], v65 offset:23072
	s_waitcnt lgkmcnt(0)
	v_mfma_f32_32x32x16_bf16 v[16:31], v[76:79], v[80:83], v[16:31]
	ds_read_b128 v[80:83], v65 offset:27680
	s_waitcnt lgkmcnt(0)
	v_mfma_f32_32x32x16_bf16 v[32:47], v[76:79], v[80:83], v[32:47]
	ds_read_b128 v[80:83], v65 offset:32288
	v_add_u32_e32 v65, 64, v65
	v_mfma_f32_32x32x16_bf16 v[48:63], v[76:79], v[84:87], v[48:63]
	s_waitcnt lgkmcnt(0)
	v_mfma_f32_32x32x16_bf16 v[0:15], v[76:79], v[80:83], v[0:15]
	s_cbranch_scc1 .LBB0_859
	v_and_b32_e32 v141, 63, v72
	v_or_b32_e32 v140, s13, v141
	v_readlane_b32 s0, v249, 15
	v_lshlrev_b32_e32 v96, 3, v140
	v_readlane_b32 s1, v249, 16
	v_readlane_b32 s16, v251, 20
	v_lshlrev_b32_e32 v69, 11, v66
	v_lshl_add_u64 v[64:65], s[0:1], 0, v[96:97]
	v_readlane_b32 s0, v248, 25
	s_or_b32 s3, s13, s0
	v_or_b32_e32 v96, s3, v74
	v_lshlrev_b64 v[66:67], 2, v[96:97]
	v_readlane_b32 s18, v251, 22
	v_readlane_b32 s19, v251, 23
	s_barrier
	s_nop 0
	v_lshl_add_u64 v[70:71], s[18:19], 0, v[66:67]
	v_readlane_b32 s100, v251, 16
	v_readlane_b32 s101, v251, 17
	s_nop 1
	v_lshl_add_u64 v[220:221], s[100:101], 0, v[66:67]
	v_readlane_b32 s100, v251, 20
	v_readlane_b32 s101, v251, 21
	s_nop 1
	v_lshl_add_u64 v[222:223], s[100:101], 0, v[66:67]
	global_load_dword v224, v[220:221], off
	global_load_dword v225, v[222:223], off
	global_load_dword v226, v[70:71], off offset:128
	global_load_dword v227, v[222:223], off offset:128
	global_load_dword v228, v[220:221], off offset:128
	global_load_dword v70, v[70:71], off
	s_mov_b32 s4, 0x3f2aaaab
	s_mov_b32 s8, 0x3f317218
	v_readlane_b32 s40, v251, 4
	v_readlane_b32 s52, v251, 16
	v_readlane_b32 s53, v251, 17
	v_readlane_b32 s17, v251, 21
	s_mov_b32 s9, 0x7f800000
	s_mov_b32 s10, 0x33800000
	v_readlane_b32 s20, v251, 24
	s_mov_b32 s20, 0x43000000
	v_readlane_b32 s21, v251, 25
	s_mov_b32 s21, 0x42b17217
	v_readlane_b32 s22, v251, 26
	s_mov_b32 s22, 0xf800000
	v_readlane_b32 s23, v251, 27
	s_mov_b32 s23, 0xc1880000
	v_add_u32_e32 v96, s3, v74
	s_mov_b32 s2, 0
	s_cmp_eq_u32 s12, 0
	v_readlane_b32 s24, v251, 28
	v_readlane_b32 s25, v251, 29
	v_readlane_b32 s26, v251, 30
	v_readlane_b32 s27, v251, 31
	v_readlane_b32 s28, v251, 32
	v_readlane_b32 s29, v251, 33
	v_readlane_b32 s30, v251, 34
	v_readlane_b32 s31, v251, 35
	v_readlane_b32 s41, v251, 5
	v_readlane_b32 s42, v251, 6
	v_readlane_b32 s43, v251, 7
	v_readlane_b32 s44, v251, 8
	v_readlane_b32 s45, v251, 9
	v_readlane_b32 s46, v251, 10
	v_readlane_b32 s47, v251, 11
	v_readlane_b32 s48, v251, 12
	v_readlane_b32 s49, v251, 13
	v_readlane_b32 s50, v251, 14
	v_readlane_b32 s51, v251, 15
	v_readlane_b32 s54, v251, 18
	v_readlane_b32 s55, v251, 19
	s_waitcnt vmcnt(0)
	v_mul_f32_e32 v70, 0xbfb8aa3b, v70
	v_exp_f32_e32 v73, v70
	s_nop 0
	v_add_f32_e32 v75, 1.0, v73
	v_add_f32_e32 v70, -1.0, v75
	v_sub_f32_e32 v71, v70, v75
	v_add_f32_e32 v71, 1.0, v71
	v_sub_f32_e32 v70, v73, v70
	v_add_f32_e32 v76, v70, v71
	v_frexp_mant_f32_e32 v70, v75
	v_cmp_gt_f32_e32 vcc, s4, v70
	v_cvt_f64_f32_e32 v[70:71], v75
	v_frexp_exp_i32_f64_e32 v70, v[70:71]
	v_subbrev_co_u32_e32 v82, vcc, 0, v70, vcc
	v_sub_u32_e32 v70, 0, v82
	v_ldexp_f32 v71, v75, v70
	v_add_f32_e32 v75, -1.0, v71
	v_add_f32_e32 v77, 1.0, v71
	v_ldexp_f32 v70, v76, v70
	v_add_f32_e32 v76, 1.0, v75
	v_add_f32_e32 v78, -1.0, v77
	v_sub_f32_e32 v76, v71, v76
	v_sub_f32_e32 v71, v71, v78
	v_add_f32_e32 v76, v70, v76
	v_add_f32_e32 v70, v70, v71
	v_add_f32_e32 v83, v77, v70
	v_rcp_f32_e32 v85, v83
	v_sub_f32_e32 v71, v83, v77
	v_sub_f32_e32 v84, v70, v71
	v_add_f32_e32 v71, v75, v76
	v_sub_f32_e32 v70, v71, v75
	v_mul_f32_e32 v86, v71, v85
	v_sub_f32_e32 v75, v76, v70
	v_mul_f32_e32 v76, v83, v86
	v_fma_f32 v78, v86, v83, -v76
	v_fmac_f32_e32 v78, v86, v84
	v_add_f32_e32 v70, v76, v78
	v_sub_f32_e32 v77, v71, v70
	v_pk_add_f32 v[80:81], v[70:71], v[76:77] neg_lo:[0,1] neg_hi:[0,1]
	v_mov_b32_e32 v79, v70
	v_pk_add_f32 v[70:71], v[80:81], v[78:79] neg_lo:[0,1] neg_hi:[0,1]
	v_cmp_neq_f32_e32 vcc, s9, v73
	v_add_f32_e32 v71, v75, v71
	v_add_f32_e32 v70, v70, v71
	v_add_f32_e32 v71, v77, v70
	v_mul_f32_e32 v75, v85, v71
	v_mul_f32_e32 v76, v83, v75
	v_fma_f32 v78, v75, v83, -v76
	v_fmac_f32_e32 v78, v75, v84
	v_sub_f32_e32 v77, v77, v71
	v_add_f32_e32 v83, v70, v77
	v_add_f32_e32 v70, v76, v78
	v_sub_f32_e32 v77, v71, v70
	v_pk_add_f32 v[80:81], v[70:71], v[76:77] neg_lo:[0,1] neg_hi:[0,1]
	v_mov_b32_e32 v79, v70
	v_pk_add_f32 v[70:71], v[80:81], v[78:79] neg_lo:[0,1] neg_hi:[0,1]
	v_add_f32_e32 v71, v83, v71
	v_add_f32_e32 v70, v70, v71
	v_add_f32_e32 v71, v86, v75
	v_add_f32_e32 v70, v77, v70
	v_sub_f32_e32 v76, v71, v86
	v_mul_f32_e32 v70, v85, v70
	v_sub_f32_e32 v75, v75, v76
	v_add_f32_e32 v75, v75, v70
	v_add_f32_e32 v76, v71, v75
	v_mul_f32_e32 v78, v76, v76
	v_fmamk_f32 v70, v78, 0x3e9b6dac, v191
	v_fmaak_f32 v169, v78, v70, 0x3f2aaada
	v_cvt_f32_i32_e32 v70, v82
	v_sub_f32_e32 v71, v76, v71
	v_sub_f32_e32 v71, v75, v71
	v_ldexp_f32 v75, v71, 1
	v_mul_f32_e32 v71, v76, v78
	v_pk_mul_f32 v[78:79], v[70:71], v[168:169]
	v_ldexp_f32 v77, v76, 1
	v_fma_f32 v76, v70, s8, -v78
	v_fmac_f32_e32 v76, 0xb102e308, v70
	v_pk_add_f32 v[70:71], v[78:79], v[76:77]
	v_mov_b32_e32 v80, v78
	v_sub_f32_e32 v77, v71, v77
	v_sub_f32_e32 v77, v79, v77
	v_add_f32_e32 v81, v75, v77
	v_pk_add_f32 v[78:79], v[70:71], v[78:79] neg_lo:[0,1] neg_hi:[0,1]
	v_pk_add_f32 v[82:83], v[70:71], v[80:81]
	v_mov_b32_e32 v77, v70
	v_mov_b32_e32 v79, v83
	v_pk_add_f32 v[84:85], v[76:77], v[78:79] neg_lo:[0,1] neg_hi:[0,1]
	v_pk_add_f32 v[76:77], v[76:77], v[78:79]
	v_mov_b32_e32 v80, v81
	v_pk_add_f32 v[78:79], v[76:77], v[70:71] op_sel:[1,0] op_sel_hi:[0,1] neg_lo:[0,1] neg_hi:[0,1]
	v_pk_add_f32 v[86:87], v[82:83], v[78:79] op_sel_hi:[1,0] neg_lo:[0,1] neg_hi:[0,1]
	v_mov_b32_e32 v82, v83
	v_mov_b32_e32 v83, v77
	v_pk_mov_b32 v[78:79], v[70:71], v[78:79] op_sel:[1,0]
	v_mov_b32_e32 v81, v70
	v_pk_add_f32 v[78:79], v[82:83], v[78:79] neg_lo:[0,1] neg_hi:[0,1]
	v_mov_b32_e32 v86, v84
	v_pk_add_f32 v[70:71], v[80:81], v[78:79] neg_lo:[0,1] neg_hi:[0,1]
	v_mov_b32_e32 v85, v77
	v_pk_add_f32 v[78:79], v[86:87], v[70:71]
	v_pk_add_f32 v[80:81], v[78:79], v[78:79] op_sel:[0,1] op_sel_hi:[1,0]
	v_pk_add_f32 v[76:77], v[76:77], v[80:81] op_sel:[1,0] op_sel_hi:[0,1]
	v_mov_b32_e32 v79, v76
	v_pk_add_f32 v[82:83], v[78:79], v[84:85] neg_lo:[0,1] neg_hi:[0,1]
	v_mov_b32_e32 v71, v80
	v_sub_f32_e32 v75, v78, v82
	v_pk_add_f32 v[70:71], v[70:71], v[82:83] neg_lo:[0,1] neg_hi:[0,1]
	v_sub_f32_e32 v75, v84, v75
	v_add_f32_e32 v70, v70, v75
	v_add_f32_e32 v70, v70, v71
	v_add_f32_e32 v70, v76, v70
	v_lshl_add_u64 v[76:77], s[52:53], 0, v[66:67]
	v_mov_b32_e32 v77, v224
	v_lshl_add_u64 v[66:67], s[16:17], 0, v[66:67]
	v_mov_b32_e32 v76, v225
	v_cndmask_b32_e32 v70, v199, v70, vcc
	v_cmp_ngt_f32_e32 vcc, -1.0, v73
	v_add_f32_e32 v48, v48, v77
	v_mul_f32_e32 v48, 0xbfb8aa3b, v48
	v_exp_f32_e32 v48, v48
	v_cndmask_b32_e32 v70, v200, v70, vcc
	v_cmp_neq_f32_e32 vcc, -1.0, v73
	v_add_f32_e32 v32, v32, v76
	v_add_f32_e32 v48, 1.0, v48
	v_rcp_f32_e32 v48, v48
	v_cndmask_b32_e32 v70, v201, v70, vcc
	v_cmp_lt_f32_e64 vcc, |v73|, s10
	v_mul_f32_e32 v32, 0xbfb8aa3b, v32
	v_exp_f32_e32 v32, v32
	v_cndmask_b32_e32 v70, v70, v73, vcc
	v_mul_f32_e32 v75, 0xc1000000, v70
	v_mul_f32_e32 v48, v48, v75
	v_mul_f32_e32 v66, 0x3fb8aa3b, v48
	v_add_f32_e32 v48, v48, v48
	v_exp_f32_e32 v70, v66
	v_mul_f32_e32 v66, 0x3fb8aa3b, v48
	v_rndne_f32_e32 v66, v66
	v_fmamk_f32 v67, v66, 0xbf317218, v48
	v_fmac_f32_e32 v67, 0x3102e308, v66
	v_fmamk_f32 v71, v67, 0x395133b1, v192
	v_cmp_eq_f32_e32 vcc, s20, v66
	v_cvt_i32_f32_e32 v66, v66
	v_fmaak_f32 v71, v67, v71, 0x3c0887f9
	v_fmaak_f32 v71, v67, v71, 0x3d2aaa81
	v_fmaak_f32 v71, v67, v71, 0x3e2aaaab
	v_fma_f32 v71, v67, v71, 0.5
	v_ldexp_f32 v66, 1.0, v66
	v_mul_f32_e32 v71, v67, v71
	v_cndmask_b32_e32 v66, v66, v202, vcc
	v_fmac_f32_e32 v67, v67, v71
	v_add_f32_e32 v71, -1.0, v66
	v_fmac_f32_e32 v71, v66, v67
	v_add_f32_e32 v66, v71, v71
	v_cndmask_b32_e32 v66, v71, v66, vcc
	v_cmp_nlt_f32_e32 vcc, s21, v48
	v_add_f32_e32 v32, 1.0, v32
	v_rcp_f32_e32 v32, v32
	v_cndmask_b32_e64 v66, v201, -v66, vcc
	v_cmp_gt_f32_e32 vcc, s22, v66
	v_mul_f32_e32 v67, 0x4f800000, v66
	v_add_f32_e32 v33, v33, v76
	v_cndmask_b32_e32 v66, v66, v67, vcc
	v_sqrt_f32_e32 v67, v66
	v_mul_f32_e32 v33, 0xbfb8aa3b, v33
	v_exp_f32_e32 v33, v33
	v_add_f32_e32 v34, v34, v76
	v_add_u32_e32 v71, -1, v67
	v_fma_f32 v73, -v71, v67, v66
	v_cmp_ge_f32_e64 s[0:1], 0, v73
	v_add_u32_e32 v73, 1, v67
	v_add_f32_e32 v33, 1.0, v33
	v_cndmask_b32_e64 v71, v67, v71, s[0:1]
	v_fma_f32 v67, -v73, v67, v66
	v_cmp_lt_f32_e64 s[0:1], 0, v67
	v_rcp_f32_e32 v33, v33
	v_mul_f32_e32 v34, 0xbfb8aa3b, v34
	v_cndmask_b32_e64 v67, v71, v73, s[0:1]
	v_mul_f32_e32 v71, 0x37800000, v67
	v_cndmask_b32_e32 v67, v67, v71, vcc
	v_cmp_class_f32_e32 vcc, v66, v193
	v_exp_f32_e32 v34, v34
	s_nop 0
	v_cndmask_b32_e32 v66, v67, v66, vcc
	v_cmp_ngt_f32_e32 vcc, s23, v48
	v_add_f32_e32 v34, 1.0, v34
	v_rcp_f32_e32 v34, v34
	v_cndmask_b32_e32 v48, 1.0, v66, vcc
	v_mul_f32_e32 v48, v32, v48
	v_and_b32_e32 v32, 0x100, v68
	v_or3_b32 v32, v69, v74, v32
	v_lshl_add_u32 v73, v32, 2, 0
	v_add_u32_e32 v32, 0x9000, v73
	ds_read2_b32 v[66:67], v32 offset1:32
	s_waitcnt lgkmcnt(0)
	v_mul_f32_e32 v48, v66, v48
	ds_write_b32 v73, v70
	ds_write_b32 v73, v48 offset:36864
	v_add_f32_e32 v48, v49, v77
	v_mul_f32_e32 v48, 0xbfb8aa3b, v48
	v_exp_f32_e32 v48, v48
	s_nop 0
	v_add_f32_e32 v48, 1.0, v48
	v_rcp_f32_e32 v48, v48
	s_nop 0
	v_mul_f32_e32 v48, v48, v75
	v_mul_f32_e32 v49, 0x3fb8aa3b, v48
	v_add_f32_e32 v48, v48, v48
	v_exp_f32_e32 v66, v49
	v_mul_f32_e32 v49, 0x3fb8aa3b, v48
	v_rndne_f32_e32 v49, v49
	v_fmamk_f32 v68, v49, 0xbf317218, v48
	v_fmac_f32_e32 v68, 0x3102e308, v49
	v_fmamk_f32 v69, v68, 0x395133b1, v192
	v_cmp_eq_f32_e32 vcc, s20, v49
	v_cvt_i32_f32_e32 v49, v49
	v_fmaak_f32 v69, v68, v69, 0x3c0887f9
	v_fmaak_f32 v69, v68, v69, 0x3d2aaa81
	v_fmaak_f32 v69, v68, v69, 0x3e2aaaab
	v_fma_f32 v69, v68, v69, 0.5
	v_ldexp_f32 v49, 1.0, v49
	v_mul_f32_e32 v69, v68, v69
	v_cndmask_b32_e32 v49, v49, v202, vcc
	v_fmac_f32_e32 v68, v68, v69
	v_add_f32_e32 v69, -1.0, v49
	v_fmac_f32_e32 v69, v49, v68
	v_add_f32_e32 v49, v69, v69
	v_cndmask_b32_e32 v49, v69, v49, vcc
	v_cmp_nlt_f32_e32 vcc, s21, v48
	s_nop 1
	v_cndmask_b32_e64 v49, v201, -v49, vcc
	v_cmp_gt_f32_e32 vcc, s22, v49
	v_mul_f32_e32 v68, 0x4f800000, v49
	s_nop 0
	v_cndmask_b32_e32 v49, v49, v68, vcc
	v_sqrt_f32_e32 v68, v49
	s_nop 0
	v_add_u32_e32 v69, -1, v68
	v_fma_f32 v70, -v69, v68, v49
	v_cmp_ge_f32_e64 s[0:1], 0, v70
	v_add_u32_e32 v70, 1, v68
	s_nop 0
	v_cndmask_b32_e64 v69, v68, v69, s[0:1]
	v_fma_f32 v68, -v70, v68, v49
	v_cmp_lt_f32_e64 s[0:1], 0, v68
	s_nop 1
	v_cndmask_b32_e64 v68, v69, v70, s[0:1]
	v_mul_f32_e32 v69, 0x37800000, v68
	v_cndmask_b32_e32 v68, v68, v69, vcc
	v_cmp_class_f32_e32 vcc, v49, v193
	s_nop 1
	v_cndmask_b32_e32 v49, v68, v49, vcc
	v_cmp_ngt_f32_e32 vcc, s23, v48
	s_nop 1
	v_cndmask_b32_e32 v48, 1.0, v49, vcc
	v_mul_f32_e32 v33, v33, v48
	ds_read2_b32 v[48:49], v32 offset0:64 offset1:96
	s_waitcnt lgkmcnt(0)
	v_mul_f32_e32 v33, v48, v33
	ds_write_b32 v73, v66 offset:256
	ds_write_b32 v73, v33 offset:37120
	v_add_f32_e32 v33, v50, v77
	v_mul_f32_e32 v33, 0xbfb8aa3b, v33
	v_exp_f32_e32 v33, v33
	s_nop 0
	v_add_f32_e32 v33, 1.0, v33
	v_rcp_f32_e32 v33, v33
	s_nop 0
	v_mul_f32_e32 v33, v33, v75
	v_mul_f32_e32 v48, 0x3fb8aa3b, v33
	v_add_f32_e32 v33, v33, v33
	v_mul_f32_e32 v50, 0x3fb8aa3b, v33
	v_rndne_f32_e32 v50, v50
	v_fmamk_f32 v66, v50, 0xbf317218, v33
	v_fmac_f32_e32 v66, 0x3102e308, v50
	v_fmamk_f32 v68, v66, 0x395133b1, v192
	v_cmp_eq_f32_e32 vcc, s20, v50
	v_cvt_i32_f32_e32 v50, v50
	v_fmaak_f32 v68, v66, v68, 0x3c0887f9
	v_fmaak_f32 v68, v66, v68, 0x3d2aaa81
	v_fmaak_f32 v68, v66, v68, 0x3e2aaaab
	v_fma_f32 v68, v66, v68, 0.5
	v_ldexp_f32 v50, 1.0, v50
	v_mul_f32_e32 v68, v66, v68
	v_cndmask_b32_e32 v50, v50, v202, vcc
	v_fmac_f32_e32 v66, v66, v68
	v_add_f32_e32 v68, -1.0, v50
	v_fmac_f32_e32 v68, v50, v66
	v_add_f32_e32 v50, v68, v68
	v_cndmask_b32_e32 v50, v68, v50, vcc
	v_cmp_nlt_f32_e32 vcc, s21, v33
	v_exp_f32_e32 v48, v48
	s_nop 0
	v_cndmask_b32_e64 v50, v201, -v50, vcc
	v_cmp_gt_f32_e32 vcc, s22, v50
	v_mul_f32_e32 v66, 0x4f800000, v50
	s_nop 0
	v_cndmask_b32_e32 v50, v50, v66, vcc
	v_sqrt_f32_e32 v66, v50
	s_nop 0
	v_add_u32_e32 v68, -1, v66
	v_fma_f32 v69, -v68, v66, v50
	v_cmp_ge_f32_e64 s[0:1], 0, v69
	v_add_u32_e32 v69, 1, v66
	s_nop 0
	v_cndmask_b32_e64 v68, v66, v68, s[0:1]
	v_fma_f32 v66, -v69, v66, v50
	v_cmp_lt_f32_e64 s[0:1], 0, v66
	s_nop 1
	v_cndmask_b32_e64 v66, v68, v69, s[0:1]
	v_mul_f32_e32 v68, 0x37800000, v66
	v_cndmask_b32_e32 v66, v66, v68, vcc
	ds_read2_b32 v[68:69], v32 offset0:128 offset1:160
	v_cmp_class_f32_e32 vcc, v50, v193
	s_nop 1
	v_cndmask_b32_e32 v50, v66, v50, vcc
	v_cmp_ngt_f32_e32 vcc, s23, v33
	s_nop 1
	v_cndmask_b32_e32 v33, 1.0, v50, vcc
	v_mul_f32_e32 v33, v34, v33
	s_waitcnt lgkmcnt(0)
	v_mul_f32_e32 v33, v68, v33
	ds_write_b32 v73, v48 offset:512
	ds_write_b32 v73, v33 offset:37376
	v_add_f32_e32 v33, v51, v77
	v_mul_f32_e32 v33, 0xbfb8aa3b, v33
	v_exp_f32_e32 v33, v33
	v_add_f32_e32 v34, v35, v76
	v_mul_f32_e32 v34, 0xbfb8aa3b, v34
	v_exp_f32_e32 v34, v34
	v_add_f32_e32 v33, 1.0, v33
	v_rcp_f32_e32 v33, v33
	v_add_f32_e32 v34, 1.0, v34
	v_rcp_f32_e32 v34, v34
	v_mul_f32_e32 v33, v33, v75
	v_mul_f32_e32 v35, 0x3fb8aa3b, v33
	v_add_f32_e32 v33, v33, v33
	v_mul_f32_e32 v48, 0x3fb8aa3b, v33
	v_rndne_f32_e32 v48, v48
	v_fmamk_f32 v50, v48, 0xbf317218, v33
	v_fmac_f32_e32 v50, 0x3102e308, v48
	v_fmamk_f32 v51, v50, 0x395133b1, v192
	v_cmp_eq_f32_e32 vcc, s20, v48
	v_cvt_i32_f32_e32 v48, v48
	v_fmaak_f32 v51, v50, v51, 0x3c0887f9
	v_fmaak_f32 v51, v50, v51, 0x3d2aaa81
	v_fmaak_f32 v51, v50, v51, 0x3e2aaaab
	v_fma_f32 v51, v50, v51, 0.5
	v_ldexp_f32 v48, 1.0, v48
	v_mul_f32_e32 v51, v50, v51
	v_cndmask_b32_e32 v48, v48, v202, vcc
	v_fmac_f32_e32 v50, v50, v51
	v_add_f32_e32 v51, -1.0, v48
	v_fmac_f32_e32 v51, v48, v50
	v_add_f32_e32 v48, v51, v51
	v_cndmask_b32_e32 v48, v51, v48, vcc
	v_cmp_nlt_f32_e32 vcc, s21, v33
	v_exp_f32_e32 v35, v35
	s_nop 0
	v_cndmask_b32_e64 v48, v201, -v48, vcc
	v_cmp_gt_f32_e32 vcc, s22, v48
	v_mul_f32_e32 v50, 0x4f800000, v48
	s_nop 0
	v_cndmask_b32_e32 v48, v48, v50, vcc
	v_sqrt_f32_e32 v50, v48
	s_nop 0
	v_add_u32_e32 v51, -1, v50
	v_fma_f32 v66, -v51, v50, v48
	v_cmp_ge_f32_e64 s[0:1], 0, v66
	v_add_u32_e32 v66, 1, v50
	s_nop 0
	v_cndmask_b32_e64 v51, v50, v51, s[0:1]
	v_fma_f32 v50, -v66, v50, v48
	v_cmp_lt_f32_e64 s[0:1], 0, v50
	s_nop 1
	v_cndmask_b32_e64 v50, v51, v66, s[0:1]
	v_mul_f32_e32 v51, 0x37800000, v50
	v_cndmask_b32_e32 v50, v50, v51, vcc
	v_cmp_class_f32_e32 vcc, v48, v193
	s_nop 1
	v_cndmask_b32_e32 v48, v50, v48, vcc
	ds_read2_b32 v[50:51], v32 offset0:192 offset1:224
	v_cmp_ngt_f32_e32 vcc, s23, v33
	s_nop 1
	v_cndmask_b32_e32 v33, 1.0, v48, vcc
	v_mul_f32_e32 v33, v34, v33
	s_waitcnt lgkmcnt(0)
	v_mul_f32_e32 v32, v50, v33
	ds_write_b32 v73, v35 offset:768
	ds_write_b32 v73, v32 offset:37632
	v_add_f32_e32 v32, v52, v77
	v_mul_f32_e32 v32, 0xbfb8aa3b, v32
	v_exp_f32_e32 v32, v32
	v_add_f32_e32 v33, v36, v76
	v_mul_f32_e32 v33, 0xbfb8aa3b, v33
	v_exp_f32_e32 v33, v33
	v_add_f32_e32 v32, 1.0, v32
	v_rcp_f32_e32 v32, v32
	v_add_f32_e32 v33, 1.0, v33
	v_rcp_f32_e32 v33, v33
	v_mul_f32_e32 v32, v32, v75
	v_mul_f32_e32 v34, 0x3fb8aa3b, v32
	v_add_f32_e32 v32, v32, v32
	v_mul_f32_e32 v35, 0x3fb8aa3b, v32
	v_rndne_f32_e32 v35, v35
	v_fmamk_f32 v36, v35, 0xbf317218, v32
	v_fmac_f32_e32 v36, 0x3102e308, v35
	v_fmamk_f32 v48, v36, 0x395133b1, v192
	v_cmp_eq_f32_e32 vcc, s20, v35
	v_cvt_i32_f32_e32 v35, v35
	v_fmaak_f32 v48, v36, v48, 0x3c0887f9
	v_fmaak_f32 v48, v36, v48, 0x3d2aaa81
	v_fmaak_f32 v48, v36, v48, 0x3e2aaaab
	v_fma_f32 v48, v36, v48, 0.5
	v_ldexp_f32 v35, 1.0, v35
	v_mul_f32_e32 v48, v36, v48
	v_cndmask_b32_e32 v35, v35, v202, vcc
	v_fmac_f32_e32 v36, v36, v48
	v_add_f32_e32 v48, -1.0, v35
	v_fmac_f32_e32 v48, v35, v36
	v_add_f32_e32 v35, v48, v48
	v_cndmask_b32_e32 v35, v48, v35, vcc
	v_cmp_nlt_f32_e32 vcc, s21, v32
	v_exp_f32_e32 v34, v34
	s_nop 0
	v_cndmask_b32_e64 v35, v201, -v35, vcc
	v_cmp_gt_f32_e32 vcc, s22, v35
	v_mul_f32_e32 v36, 0x4f800000, v35
	s_nop 0
	v_cndmask_b32_e32 v35, v35, v36, vcc
	v_sqrt_f32_e32 v36, v35
	s_nop 0
	v_add_u32_e32 v48, -1, v36
	v_fma_f32 v50, -v48, v36, v35
	v_cmp_ge_f32_e64 s[0:1], 0, v50
	v_add_u32_e32 v50, 1, v36
	s_nop 0
	v_cndmask_b32_e64 v48, v36, v48, s[0:1]
	v_fma_f32 v36, -v50, v36, v35
	v_cmp_lt_f32_e64 s[0:1], 0, v36
	s_nop 1
	v_cndmask_b32_e64 v36, v48, v50, s[0:1]
	v_mul_f32_e32 v48, 0x37800000, v36
	v_cndmask_b32_e32 v36, v36, v48, vcc
	v_cmp_class_f32_e32 vcc, v35, v193
	s_nop 1
	v_cndmask_b32_e32 v35, v36, v35, vcc
	v_cmp_ngt_f32_e32 vcc, s23, v32
	s_nop 1
	v_cndmask_b32_e32 v32, 1.0, v35, vcc
	v_mul_f32_e32 v33, v33, v32
	v_add_u32_e32 v32, 0x9800, v73
	ds_read2_b32 v[70:71], v32 offset1:32
	s_waitcnt lgkmcnt(0)
	v_mul_f32_e32 v33, v70, v33
	ds_write_b32 v73, v34 offset:2048
	ds_write_b32 v73, v33 offset:38912
	v_add_f32_e32 v33, v53, v77
	v_mul_f32_e32 v33, 0xbfb8aa3b, v33
	v_exp_f32_e32 v33, v33
	v_add_f32_e32 v34, v37, v76
	v_mul_f32_e32 v34, 0xbfb8aa3b, v34
	v_exp_f32_e32 v34, v34
	v_add_f32_e32 v33, 1.0, v33
	v_rcp_f32_e32 v33, v33
	v_add_f32_e32 v34, 1.0, v34
	v_rcp_f32_e32 v34, v34
	v_mul_f32_e32 v33, v33, v75
	v_mul_f32_e32 v35, 0x3fb8aa3b, v33
	v_add_f32_e32 v33, v33, v33
	v_mul_f32_e32 v36, 0x3fb8aa3b, v33
	v_rndne_f32_e32 v36, v36
	v_fmamk_f32 v37, v36, 0xbf317218, v33
	v_fmac_f32_e32 v37, 0x3102e308, v36
	v_fmamk_f32 v48, v37, 0x395133b1, v192
	v_cmp_eq_f32_e32 vcc, s20, v36
	v_cvt_i32_f32_e32 v36, v36
	v_fmaak_f32 v48, v37, v48, 0x3c0887f9
	v_fmaak_f32 v48, v37, v48, 0x3d2aaa81
	v_fmaak_f32 v48, v37, v48, 0x3e2aaaab
	v_fma_f32 v48, v37, v48, 0.5
	v_ldexp_f32 v36, 1.0, v36
	v_mul_f32_e32 v48, v37, v48
	v_cndmask_b32_e32 v36, v36, v202, vcc
	v_fmac_f32_e32 v37, v37, v48
	v_add_f32_e32 v48, -1.0, v36
	v_fmac_f32_e32 v48, v36, v37
	v_add_f32_e32 v36, v48, v48
	v_cndmask_b32_e32 v36, v48, v36, vcc
	v_cmp_nlt_f32_e32 vcc, s21, v33
	v_exp_f32_e32 v35, v35
	s_nop 0
	v_cndmask_b32_e64 v36, v201, -v36, vcc
	v_cmp_gt_f32_e32 vcc, s22, v36
	v_mul_f32_e32 v37, 0x4f800000, v36
	s_nop 0
	v_cndmask_b32_e32 v36, v36, v37, vcc
	v_sqrt_f32_e32 v37, v36
	s_nop 0
	v_add_u32_e32 v48, -1, v37
	v_fma_f32 v50, -v48, v37, v36
	v_cmp_ge_f32_e64 s[0:1], 0, v50
	v_add_u32_e32 v50, 1, v37
	s_nop 0
	v_cndmask_b32_e64 v48, v37, v48, s[0:1]
	v_fma_f32 v37, -v50, v37, v36
	v_cmp_lt_f32_e64 s[0:1], 0, v37
	s_nop 1
	v_cndmask_b32_e64 v37, v48, v50, s[0:1]
	v_mul_f32_e32 v48, 0x37800000, v37
	v_cndmask_b32_e32 v37, v37, v48, vcc
	v_cmp_class_f32_e32 vcc, v36, v193
	s_nop 1
	v_cndmask_b32_e32 v36, v37, v36, vcc
	v_cmp_ngt_f32_e32 vcc, s23, v33
	s_nop 1
	v_cndmask_b32_e32 v33, 1.0, v36, vcc
	ds_read2_b32 v[36:37], v32 offset0:64 offset1:96
	v_mul_f32_e32 v33, v34, v33
	v_add_f32_e32 v34, v38, v76
	v_mul_f32_e32 v34, 0xbfb8aa3b, v34
	v_exp_f32_e32 v34, v34
	s_waitcnt lgkmcnt(0)
	v_mul_f32_e32 v33, v36, v33
	ds_write_b32 v73, v35 offset:2304
	ds_write_b32 v73, v33 offset:39168
	v_add_f32_e32 v33, v54, v77
	v_mul_f32_e32 v33, 0xbfb8aa3b, v33
	v_exp_f32_e32 v33, v33
	v_add_f32_e32 v34, 1.0, v34
	v_rcp_f32_e32 v34, v34
	ds_read2_b32 v[52:53], v32 offset0:128 offset1:160
	v_add_f32_e32 v33, 1.0, v33
	v_rcp_f32_e32 v33, v33
	s_nop 0
	v_mul_f32_e32 v33, v33, v75
	v_mul_f32_e32 v35, 0x3fb8aa3b, v33
	v_add_f32_e32 v33, v33, v33
	v_mul_f32_e32 v36, 0x3fb8aa3b, v33
	v_rndne_f32_e32 v36, v36
	v_fmamk_f32 v38, v36, 0xbf317218, v33
	v_fmac_f32_e32 v38, 0x3102e308, v36
	v_fmamk_f32 v48, v38, 0x395133b1, v192
	v_cmp_eq_f32_e32 vcc, s20, v36
	v_cvt_i32_f32_e32 v36, v36
	v_fmaak_f32 v48, v38, v48, 0x3c0887f9
	v_fmaak_f32 v48, v38, v48, 0x3d2aaa81
	v_fmaak_f32 v48, v38, v48, 0x3e2aaaab
	v_fma_f32 v48, v38, v48, 0.5
	v_ldexp_f32 v36, 1.0, v36
	v_mul_f32_e32 v48, v38, v48
	v_cndmask_b32_e32 v36, v36, v202, vcc
	v_fmac_f32_e32 v38, v38, v48
	v_add_f32_e32 v48, -1.0, v36
	v_fmac_f32_e32 v48, v36, v38
	v_add_f32_e32 v36, v48, v48
	v_cndmask_b32_e32 v36, v48, v36, vcc
	v_cmp_nlt_f32_e32 vcc, s21, v33
	v_exp_f32_e32 v35, v35
	s_nop 0
	v_cndmask_b32_e64 v36, v201, -v36, vcc
	v_cmp_gt_f32_e32 vcc, s22, v36
	v_mul_f32_e32 v38, 0x4f800000, v36
	s_nop 0
	v_cndmask_b32_e32 v36, v36, v38, vcc
	v_sqrt_f32_e32 v38, v36
	s_nop 0
	v_add_u32_e32 v48, -1, v38
	v_fma_f32 v50, -v48, v38, v36
	v_cmp_ge_f32_e64 s[0:1], 0, v50
	v_add_u32_e32 v50, 1, v38
	s_nop 0
	v_cndmask_b32_e64 v48, v38, v48, s[0:1]
	v_fma_f32 v38, -v50, v38, v36
	v_cmp_lt_f32_e64 s[0:1], 0, v38
	s_nop 1
	v_cndmask_b32_e64 v38, v48, v50, s[0:1]
	v_mul_f32_e32 v48, 0x37800000, v38
	v_cndmask_b32_e32 v38, v38, v48, vcc
	v_cmp_class_f32_e32 vcc, v36, v193
	s_nop 1
	v_cndmask_b32_e32 v36, v38, v36, vcc
	v_cmp_ngt_f32_e32 vcc, s23, v33
	s_nop 1
	v_cndmask_b32_e32 v33, 1.0, v36, vcc
	v_mul_f32_e32 v33, v34, v33
	s_waitcnt lgkmcnt(0)
	v_mul_f32_e32 v33, v52, v33
	ds_write_b32 v73, v35 offset:2560
	ds_write_b32 v73, v33 offset:39424
	v_add_f32_e32 v33, v55, v77
	v_mul_f32_e32 v33, 0xbfb8aa3b, v33
	v_exp_f32_e32 v33, v33
	v_add_f32_e32 v34, v39, v76
	v_mul_f32_e32 v34, 0xbfb8aa3b, v34
	v_exp_f32_e32 v34, v34
	v_add_f32_e32 v33, 1.0, v33
	v_rcp_f32_e32 v33, v33
	v_add_f32_e32 v34, 1.0, v34
	v_rcp_f32_e32 v34, v34
	v_mul_f32_e32 v33, v33, v75
	v_mul_f32_e32 v35, 0x3fb8aa3b, v33
	v_add_f32_e32 v33, v33, v33
	v_mul_f32_e32 v36, 0x3fb8aa3b, v33
	v_rndne_f32_e32 v36, v36
	v_fmamk_f32 v38, v36, 0xbf317218, v33
	v_fmac_f32_e32 v38, 0x3102e308, v36
	v_fmamk_f32 v39, v38, 0x395133b1, v192
	v_cmp_eq_f32_e32 vcc, s20, v36
	v_cvt_i32_f32_e32 v36, v36
	v_fmaak_f32 v39, v38, v39, 0x3c0887f9
	v_fmaak_f32 v39, v38, v39, 0x3d2aaa81
	v_fmaak_f32 v39, v38, v39, 0x3e2aaaab
	v_fma_f32 v39, v38, v39, 0.5
	v_ldexp_f32 v36, 1.0, v36
	v_mul_f32_e32 v39, v38, v39
	v_cndmask_b32_e32 v36, v36, v202, vcc
	v_fmac_f32_e32 v38, v38, v39
	v_add_f32_e32 v39, -1.0, v36
	v_fmac_f32_e32 v39, v36, v38
	v_add_f32_e32 v36, v39, v39
	v_cndmask_b32_e32 v36, v39, v36, vcc
	v_cmp_nlt_f32_e32 vcc, s21, v33
	v_exp_f32_e32 v35, v35
	s_nop 0
	v_cndmask_b32_e64 v36, v201, -v36, vcc
	v_cmp_gt_f32_e32 vcc, s22, v36
	v_mul_f32_e32 v38, 0x4f800000, v36
	s_nop 0
	v_cndmask_b32_e32 v36, v36, v38, vcc
	v_sqrt_f32_e32 v38, v36
	s_nop 0
	v_add_u32_e32 v39, -1, v38
	v_fma_f32 v48, -v39, v38, v36
	v_cmp_ge_f32_e64 s[0:1], 0, v48
	v_add_u32_e32 v48, 1, v38
	s_nop 0
	v_cndmask_b32_e64 v39, v38, v39, s[0:1]
	v_fma_f32 v38, -v48, v38, v36
	v_cmp_lt_f32_e64 s[0:1], 0, v38
	s_nop 1
	v_cndmask_b32_e64 v38, v39, v48, s[0:1]
	v_mul_f32_e32 v39, 0x37800000, v38
	v_cndmask_b32_e32 v38, v38, v39, vcc
	v_cmp_class_f32_e32 vcc, v36, v193
	s_nop 1
	v_cndmask_b32_e32 v36, v38, v36, vcc
	ds_read2_b32 v[38:39], v32 offset0:192 offset1:224
	v_cmp_ngt_f32_e32 vcc, s23, v33
	s_nop 1
	v_cndmask_b32_e32 v33, 1.0, v36, vcc
	v_mul_f32_e32 v33, v34, v33
	s_waitcnt lgkmcnt(0)
	v_mul_f32_e32 v32, v38, v33
	ds_write_b32 v73, v35 offset:2816
	ds_write_b32 v73, v32 offset:39680
	v_add_f32_e32 v32, v56, v77
	v_mul_f32_e32 v32, 0xbfb8aa3b, v32
	v_exp_f32_e32 v32, v32
	v_add_f32_e32 v33, v40, v76
	v_mul_f32_e32 v33, 0xbfb8aa3b, v33
	v_exp_f32_e32 v33, v33
	v_add_f32_e32 v32, 1.0, v32
	v_rcp_f32_e32 v32, v32
	v_add_f32_e32 v33, 1.0, v33
	v_rcp_f32_e32 v33, v33
	v_mul_f32_e32 v32, v32, v75
	v_mul_f32_e32 v34, 0x3fb8aa3b, v32
	v_add_f32_e32 v32, v32, v32
	v_mul_f32_e32 v35, 0x3fb8aa3b, v32
	v_rndne_f32_e32 v35, v35
	v_fmamk_f32 v36, v35, 0xbf317218, v32
	v_fmac_f32_e32 v36, 0x3102e308, v35
	v_fmamk_f32 v38, v36, 0x395133b1, v192
	v_cmp_eq_f32_e32 vcc, s20, v35
	v_cvt_i32_f32_e32 v35, v35
	v_fmaak_f32 v38, v36, v38, 0x3c0887f9
	v_fmaak_f32 v38, v36, v38, 0x3d2aaa81
	v_fmaak_f32 v38, v36, v38, 0x3e2aaaab
	v_fma_f32 v38, v36, v38, 0.5
	v_ldexp_f32 v35, 1.0, v35
	v_mul_f32_e32 v38, v36, v38
	v_cndmask_b32_e32 v35, v35, v202, vcc
	v_fmac_f32_e32 v36, v36, v38
	v_add_f32_e32 v38, -1.0, v35
	v_fmac_f32_e32 v38, v35, v36
	v_add_f32_e32 v35, v38, v38
	v_cndmask_b32_e32 v35, v38, v35, vcc
	v_cmp_nlt_f32_e32 vcc, s21, v32
	v_exp_f32_e32 v34, v34
	s_nop 0
	v_cndmask_b32_e64 v35, v201, -v35, vcc
	v_cmp_gt_f32_e32 vcc, s22, v35
	v_mul_f32_e32 v36, 0x4f800000, v35
	s_nop 0
	v_cndmask_b32_e32 v35, v35, v36, vcc
	v_sqrt_f32_e32 v36, v35
	s_nop 0
	v_add_u32_e32 v38, -1, v36
	v_fma_f32 v40, -v38, v36, v35
	v_cmp_ge_f32_e64 s[0:1], 0, v40
	v_add_u32_e32 v40, 1, v36
	s_nop 0
	v_cndmask_b32_e64 v38, v36, v38, s[0:1]
	v_fma_f32 v36, -v40, v36, v35
	v_cmp_lt_f32_e64 s[0:1], 0, v36
	s_nop 1
	v_cndmask_b32_e64 v36, v38, v40, s[0:1]
	v_mul_f32_e32 v38, 0x37800000, v36
	v_cndmask_b32_e32 v36, v36, v38, vcc
	v_cmp_class_f32_e32 vcc, v35, v193
	s_nop 1
	v_cndmask_b32_e32 v35, v36, v35, vcc
	v_cmp_ngt_f32_e32 vcc, s23, v32
	s_nop 1
	v_cndmask_b32_e32 v32, 1.0, v35, vcc
	v_mul_f32_e32 v33, v33, v32
	v_add_u32_e32 v32, 0xa000, v73
	ds_read2_b32 v[54:55], v32 offset1:32
	s_waitcnt lgkmcnt(0)
	v_mul_f32_e32 v33, v54, v33
	ds_write_b32 v73, v34 offset:4096
	ds_write_b32 v73, v33 offset:40960
	v_add_f32_e32 v33, v57, v77
	v_mul_f32_e32 v33, 0xbfb8aa3b, v33
	v_exp_f32_e32 v33, v33
	v_add_f32_e32 v34, v41, v76
	v_mul_f32_e32 v34, 0xbfb8aa3b, v34
	v_exp_f32_e32 v34, v34
	v_add_f32_e32 v33, 1.0, v33
	v_rcp_f32_e32 v33, v33
	v_add_f32_e32 v34, 1.0, v34
	v_rcp_f32_e32 v34, v34
	v_mul_f32_e32 v33, v33, v75
	v_mul_f32_e32 v35, 0x3fb8aa3b, v33
	v_add_f32_e32 v33, v33, v33
	v_mul_f32_e32 v36, 0x3fb8aa3b, v33
	v_rndne_f32_e32 v36, v36
	v_fmamk_f32 v38, v36, 0xbf317218, v33
	v_fmac_f32_e32 v38, 0x3102e308, v36
	v_fmamk_f32 v40, v38, 0x395133b1, v192
	v_cmp_eq_f32_e32 vcc, s20, v36
	v_cvt_i32_f32_e32 v36, v36
	v_fmaak_f32 v40, v38, v40, 0x3c0887f9
	v_fmaak_f32 v40, v38, v40, 0x3d2aaa81
	v_fmaak_f32 v40, v38, v40, 0x3e2aaaab
	v_fma_f32 v40, v38, v40, 0.5
	v_ldexp_f32 v36, 1.0, v36
	v_mul_f32_e32 v40, v38, v40
	v_cndmask_b32_e32 v36, v36, v202, vcc
	v_fmac_f32_e32 v38, v38, v40
	v_add_f32_e32 v40, -1.0, v36
	v_fmac_f32_e32 v40, v36, v38
	v_add_f32_e32 v36, v40, v40
	v_cndmask_b32_e32 v36, v40, v36, vcc
	v_cmp_nlt_f32_e32 vcc, s21, v33
	v_exp_f32_e32 v35, v35
	s_nop 0
	v_cndmask_b32_e64 v36, v201, -v36, vcc
	v_cmp_gt_f32_e32 vcc, s22, v36
	v_mul_f32_e32 v38, 0x4f800000, v36
	s_nop 0
	v_cndmask_b32_e32 v36, v36, v38, vcc
	v_sqrt_f32_e32 v38, v36
	s_nop 0
	v_add_u32_e32 v40, -1, v38
	v_fma_f32 v41, -v40, v38, v36
	v_cmp_ge_f32_e64 s[0:1], 0, v41
	v_add_u32_e32 v41, 1, v38
	s_nop 0
	v_cndmask_b32_e64 v40, v38, v40, s[0:1]
	v_fma_f32 v38, -v41, v38, v36
	v_cmp_lt_f32_e64 s[0:1], 0, v38
	s_nop 1
	v_cndmask_b32_e64 v38, v40, v41, s[0:1]
	v_mul_f32_e32 v40, 0x37800000, v38
	v_cndmask_b32_e32 v38, v38, v40, vcc
	ds_read2_b32 v[40:41], v32 offset0:64 offset1:96
	v_cmp_class_f32_e32 vcc, v36, v193
	s_nop 1
	v_cndmask_b32_e32 v36, v38, v36, vcc
	v_cmp_ngt_f32_e32 vcc, s23, v33
	s_nop 1
	v_cndmask_b32_e32 v33, 1.0, v36, vcc
	v_mul_f32_e32 v33, v34, v33
	s_waitcnt lgkmcnt(0)
	v_mul_f32_e32 v33, v40, v33
	ds_write_b32 v73, v35 offset:4352
	ds_write_b32 v73, v33 offset:41216
	v_add_f32_e32 v33, v58, v77
	v_mul_f32_e32 v33, 0xbfb8aa3b, v33
	v_exp_f32_e32 v33, v33
	v_add_f32_e32 v34, v42, v76
	v_mul_f32_e32 v34, 0xbfb8aa3b, v34
	v_exp_f32_e32 v34, v34
	v_add_f32_e32 v33, 1.0, v33
	v_rcp_f32_e32 v33, v33
	ds_read2_b32 v[56:57], v32 offset0:128 offset1:160
	v_add_f32_e32 v34, 1.0, v34
	v_rcp_f32_e32 v34, v34
	v_mul_f32_e32 v33, v33, v75
	v_mul_f32_e32 v35, 0x3fb8aa3b, v33
	v_add_f32_e32 v33, v33, v33
	v_mul_f32_e32 v36, 0x3fb8aa3b, v33
	v_rndne_f32_e32 v36, v36
	v_fmamk_f32 v38, v36, 0xbf317218, v33
	v_fmac_f32_e32 v38, 0x3102e308, v36
	v_fmamk_f32 v40, v38, 0x395133b1, v192
	v_cmp_eq_f32_e32 vcc, s20, v36
	v_cvt_i32_f32_e32 v36, v36
	v_fmaak_f32 v40, v38, v40, 0x3c0887f9
	v_fmaak_f32 v40, v38, v40, 0x3d2aaa81
	v_fmaak_f32 v40, v38, v40, 0x3e2aaaab
	v_fma_f32 v40, v38, v40, 0.5
	v_ldexp_f32 v36, 1.0, v36
	v_mul_f32_e32 v40, v38, v40
	v_cndmask_b32_e32 v36, v36, v202, vcc
	v_fmac_f32_e32 v38, v38, v40
	v_add_f32_e32 v40, -1.0, v36
	v_fmac_f32_e32 v40, v36, v38
	v_add_f32_e32 v36, v40, v40
	v_cndmask_b32_e32 v36, v40, v36, vcc
	v_cmp_nlt_f32_e32 vcc, s21, v33
	v_exp_f32_e32 v35, v35
	s_nop 0
	v_cndmask_b32_e64 v36, v201, -v36, vcc
	v_cmp_gt_f32_e32 vcc, s22, v36
	v_mul_f32_e32 v38, 0x4f800000, v36
	s_nop 0
	v_cndmask_b32_e32 v36, v36, v38, vcc
	v_sqrt_f32_e32 v38, v36
	s_nop 0
	v_add_u32_e32 v40, -1, v38
	v_fma_f32 v42, -v40, v38, v36
	v_cmp_ge_f32_e64 s[0:1], 0, v42
	v_add_u32_e32 v42, 1, v38
	s_nop 0
	v_cndmask_b32_e64 v40, v38, v40, s[0:1]
	v_fma_f32 v38, -v42, v38, v36
	v_cmp_lt_f32_e64 s[0:1], 0, v38
	s_nop 1
	v_cndmask_b32_e64 v38, v40, v42, s[0:1]
	v_mul_f32_e32 v40, 0x37800000, v38
	v_cndmask_b32_e32 v38, v38, v40, vcc
	v_cmp_class_f32_e32 vcc, v36, v193
	s_nop 1
	v_cndmask_b32_e32 v36, v38, v36, vcc
	v_cmp_ngt_f32_e32 vcc, s23, v33
	s_nop 1
	v_cndmask_b32_e32 v33, 1.0, v36, vcc
	v_mul_f32_e32 v33, v34, v33
	s_waitcnt lgkmcnt(0)
	v_mul_f32_e32 v33, v56, v33
	ds_write_b32 v73, v35 offset:4608
	ds_write_b32 v73, v33 offset:41472
	v_add_f32_e32 v33, v59, v77
	v_mul_f32_e32 v33, 0xbfb8aa3b, v33
	v_exp_f32_e32 v33, v33
	v_add_f32_e32 v34, v43, v76
	v_mul_f32_e32 v34, 0xbfb8aa3b, v34
	v_exp_f32_e32 v34, v34
	v_add_f32_e32 v33, 1.0, v33
	v_rcp_f32_e32 v33, v33
	v_add_f32_e32 v34, 1.0, v34
	v_rcp_f32_e32 v34, v34
	v_mul_f32_e32 v33, v33, v75
	v_mul_f32_e32 v35, 0x3fb8aa3b, v33
	v_add_f32_e32 v33, v33, v33
	v_mul_f32_e32 v36, 0x3fb8aa3b, v33
	v_rndne_f32_e32 v36, v36
	v_fmamk_f32 v38, v36, 0xbf317218, v33
	v_fmac_f32_e32 v38, 0x3102e308, v36
	v_fmamk_f32 v40, v38, 0x395133b1, v192
	v_cmp_eq_f32_e32 vcc, s20, v36
	v_cvt_i32_f32_e32 v36, v36
	v_fmaak_f32 v40, v38, v40, 0x3c0887f9
	v_fmaak_f32 v40, v38, v40, 0x3d2aaa81
	v_fmaak_f32 v40, v38, v40, 0x3e2aaaab
	v_fma_f32 v40, v38, v40, 0.5
	v_ldexp_f32 v36, 1.0, v36
	v_mul_f32_e32 v40, v38, v40
	v_cndmask_b32_e32 v36, v36, v202, vcc
	v_fmac_f32_e32 v38, v38, v40
	v_add_f32_e32 v40, -1.0, v36
	v_fmac_f32_e32 v40, v36, v38
	v_add_f32_e32 v36, v40, v40
	v_cndmask_b32_e32 v36, v40, v36, vcc
	v_cmp_nlt_f32_e32 vcc, s21, v33
	v_exp_f32_e32 v35, v35
	s_nop 0
	v_cndmask_b32_e64 v36, v201, -v36, vcc
	v_cmp_gt_f32_e32 vcc, s22, v36
	v_mul_f32_e32 v38, 0x4f800000, v36
	s_nop 0
	v_cndmask_b32_e32 v36, v36, v38, vcc
	v_sqrt_f32_e32 v38, v36
	s_nop 0
	v_add_u32_e32 v40, -1, v38
	v_fma_f32 v42, -v40, v38, v36
	v_cmp_ge_f32_e64 s[0:1], 0, v42
	v_add_u32_e32 v42, 1, v38
	s_nop 0
	v_cndmask_b32_e64 v40, v38, v40, s[0:1]
	v_fma_f32 v38, -v42, v38, v36
	v_cmp_lt_f32_e64 s[0:1], 0, v38
	s_nop 1
	v_cndmask_b32_e64 v38, v40, v42, s[0:1]
	v_mul_f32_e32 v40, 0x37800000, v38
	ds_read2_b32 v[42:43], v32 offset0:192 offset1:224
	v_cndmask_b32_e32 v38, v38, v40, vcc
	v_cmp_class_f32_e32 vcc, v36, v193
	s_nop 1
	v_cndmask_b32_e32 v36, v38, v36, vcc
	v_cmp_ngt_f32_e32 vcc, s23, v33
	s_nop 1
	v_cndmask_b32_e32 v33, 1.0, v36, vcc
	v_mul_f32_e32 v33, v34, v33
	s_waitcnt lgkmcnt(0)
	v_mul_f32_e32 v32, v42, v33
	ds_write_b32 v73, v35 offset:4864
	ds_write_b32 v73, v32 offset:41728
	v_add_f32_e32 v32, v60, v77
	v_mul_f32_e32 v32, 0xbfb8aa3b, v32
	v_exp_f32_e32 v32, v32
	v_add_f32_e32 v33, v44, v76
	v_mul_f32_e32 v33, 0xbfb8aa3b, v33
	v_exp_f32_e32 v33, v33
	v_add_f32_e32 v32, 1.0, v32
	v_rcp_f32_e32 v32, v32
	v_add_f32_e32 v33, 1.0, v33
	v_rcp_f32_e32 v33, v33
	v_mul_f32_e32 v32, v32, v75
	v_mul_f32_e32 v34, 0x3fb8aa3b, v32
	v_add_f32_e32 v32, v32, v32
	v_mul_f32_e32 v35, 0x3fb8aa3b, v32
	v_rndne_f32_e32 v35, v35
	v_fmamk_f32 v36, v35, 0xbf317218, v32
	v_fmac_f32_e32 v36, 0x3102e308, v35
	v_fmamk_f32 v38, v36, 0x395133b1, v192
	v_cmp_eq_f32_e32 vcc, s20, v35
	v_cvt_i32_f32_e32 v35, v35
	v_fmaak_f32 v38, v36, v38, 0x3c0887f9
	v_fmaak_f32 v38, v36, v38, 0x3d2aaa81
	v_fmaak_f32 v38, v36, v38, 0x3e2aaaab
	v_fma_f32 v38, v36, v38, 0.5
	v_ldexp_f32 v35, 1.0, v35
	v_mul_f32_e32 v38, v36, v38
	v_cndmask_b32_e32 v35, v35, v202, vcc
	v_fmac_f32_e32 v36, v36, v38
	v_add_f32_e32 v38, -1.0, v35
	v_fmac_f32_e32 v38, v35, v36
	v_add_f32_e32 v35, v38, v38
	v_cndmask_b32_e32 v35, v38, v35, vcc
	v_cmp_nlt_f32_e32 vcc, s21, v32
	v_exp_f32_e32 v34, v34
	s_nop 0
	v_cndmask_b32_e64 v35, v201, -v35, vcc
	v_cmp_gt_f32_e32 vcc, s22, v35
	v_mul_f32_e32 v36, 0x4f800000, v35
	s_nop 0
	v_cndmask_b32_e32 v35, v35, v36, vcc
	v_sqrt_f32_e32 v36, v35
	s_nop 0
	v_add_u32_e32 v38, -1, v36
	v_fma_f32 v40, -v38, v36, v35
	v_cmp_ge_f32_e64 s[0:1], 0, v40
	v_add_u32_e32 v40, 1, v36
	s_nop 0
	v_cndmask_b32_e64 v38, v36, v38, s[0:1]
	v_fma_f32 v36, -v40, v36, v35
	v_cmp_lt_f32_e64 s[0:1], 0, v36
	s_nop 1
	v_cndmask_b32_e64 v36, v38, v40, s[0:1]
	v_mul_f32_e32 v38, 0x37800000, v36
	v_cndmask_b32_e32 v36, v36, v38, vcc
	v_cmp_class_f32_e32 vcc, v35, v193
	s_nop 1
	v_cndmask_b32_e32 v35, v36, v35, vcc
	v_cmp_ngt_f32_e32 vcc, s23, v32
	s_nop 1
	v_cndmask_b32_e32 v32, 1.0, v35, vcc
	v_mul_f32_e32 v32, v33, v32
	v_add_u32_e32 v33, 0xa800, v73
	ds_read2_b32 v[58:59], v33 offset1:32
	s_waitcnt lgkmcnt(0)
	v_mul_f32_e32 v32, v58, v32
	ds_write_b32 v73, v34 offset:6144
	ds_write_b32 v73, v32 offset:43008
	v_add_f32_e32 v32, v61, v77
	v_mul_f32_e32 v32, 0xbfb8aa3b, v32
	v_exp_f32_e32 v32, v32
	v_add_f32_e32 v34, v45, v76
	v_mul_f32_e32 v34, 0xbfb8aa3b, v34
	v_exp_f32_e32 v34, v34
	v_add_f32_e32 v32, 1.0, v32
	v_rcp_f32_e32 v32, v32
	ds_read2_b32 v[44:45], v33 offset0:64 offset1:96
	v_add_f32_e32 v34, 1.0, v34
	v_rcp_f32_e32 v34, v34
	v_mul_f32_e32 v32, v32, v75
	v_mul_f32_e32 v35, 0x3fb8aa3b, v32
	v_add_f32_e32 v32, v32, v32
	v_mul_f32_e32 v36, 0x3fb8aa3b, v32
	v_rndne_f32_e32 v36, v36
	v_fmamk_f32 v38, v36, 0xbf317218, v32
	v_fmac_f32_e32 v38, 0x3102e308, v36
	v_fmamk_f32 v40, v38, 0x395133b1, v192
	v_cmp_eq_f32_e32 vcc, s20, v36
	v_cvt_i32_f32_e32 v36, v36
	v_fmaak_f32 v40, v38, v40, 0x3c0887f9
	v_fmaak_f32 v40, v38, v40, 0x3d2aaa81
	v_fmaak_f32 v40, v38, v40, 0x3e2aaaab
	v_fma_f32 v40, v38, v40, 0.5
	v_ldexp_f32 v36, 1.0, v36
	v_mul_f32_e32 v40, v38, v40
	v_cndmask_b32_e32 v36, v36, v202, vcc
	v_fmac_f32_e32 v38, v38, v40
	v_add_f32_e32 v40, -1.0, v36
	v_fmac_f32_e32 v40, v36, v38
	v_add_f32_e32 v36, v40, v40
	v_cndmask_b32_e32 v36, v40, v36, vcc
	v_cmp_nlt_f32_e32 vcc, s21, v32
	v_exp_f32_e32 v35, v35
	s_nop 0
	v_cndmask_b32_e64 v36, v201, -v36, vcc
	v_cmp_gt_f32_e32 vcc, s22, v36
	v_mul_f32_e32 v38, 0x4f800000, v36
	s_nop 0
	v_cndmask_b32_e32 v36, v36, v38, vcc
	v_sqrt_f32_e32 v38, v36
	s_nop 0
	v_add_u32_e32 v40, -1, v38
	v_fma_f32 v42, -v40, v38, v36
	v_cmp_ge_f32_e64 s[0:1], 0, v42
	v_add_u32_e32 v42, 1, v38
	s_nop 0
	v_cndmask_b32_e64 v40, v38, v40, s[0:1]
	v_fma_f32 v38, -v42, v38, v36
	v_cmp_lt_f32_e64 s[0:1], 0, v38
	s_nop 1
	v_cndmask_b32_e64 v38, v40, v42, s[0:1]
	v_mul_f32_e32 v40, 0x37800000, v38
	v_cndmask_b32_e32 v38, v38, v40, vcc
	v_cmp_class_f32_e32 vcc, v36, v193
	s_nop 1
	v_cndmask_b32_e32 v36, v38, v36, vcc
	v_cmp_ngt_f32_e32 vcc, s23, v32
	s_nop 1
	v_cndmask_b32_e32 v32, 1.0, v36, vcc
	v_mul_f32_e32 v32, v34, v32
	s_waitcnt lgkmcnt(0)
	v_mul_f32_e32 v32, v44, v32
	ds_write_b32 v73, v35 offset:6400
	ds_write_b32 v73, v32 offset:43264
	v_add_f32_e32 v32, v62, v77
	v_mul_f32_e32 v32, 0xbfb8aa3b, v32
	v_exp_f32_e32 v32, v32
	v_add_f32_e32 v34, v46, v76
	v_mul_f32_e32 v34, 0xbfb8aa3b, v34
	v_exp_f32_e32 v34, v34
	v_add_f32_e32 v32, 1.0, v32
	v_rcp_f32_e32 v32, v32
	v_add_f32_e32 v34, 1.0, v34
	v_rcp_f32_e32 v34, v34
	v_mul_f32_e32 v32, v32, v75
	v_mul_f32_e32 v35, 0x3fb8aa3b, v32
	v_add_f32_e32 v32, v32, v32
	v_exp_f32_e32 v36, v35
	v_mul_f32_e32 v35, 0x3fb8aa3b, v32
	v_rndne_f32_e32 v35, v35
	v_fmamk_f32 v38, v35, 0xbf317218, v32
	v_fmac_f32_e32 v38, 0x3102e308, v35
	v_fmamk_f32 v40, v38, 0x395133b1, v192
	v_cmp_eq_f32_e32 vcc, s20, v35
	v_cvt_i32_f32_e32 v35, v35
	v_fmaak_f32 v40, v38, v40, 0x3c0887f9
	v_fmaak_f32 v40, v38, v40, 0x3d2aaa81
	v_fmaak_f32 v40, v38, v40, 0x3e2aaaab
	v_fma_f32 v40, v38, v40, 0.5
	v_ldexp_f32 v35, 1.0, v35
	v_mul_f32_e32 v40, v38, v40
	v_cndmask_b32_e32 v35, v35, v202, vcc
	v_fmac_f32_e32 v38, v38, v40
	v_add_f32_e32 v40, -1.0, v35
	v_fmac_f32_e32 v40, v35, v38
	v_add_f32_e32 v35, v40, v40
	v_cndmask_b32_e32 v35, v40, v35, vcc
	v_cmp_nlt_f32_e32 vcc, s21, v32
	s_nop 1
	v_cndmask_b32_e64 v35, v201, -v35, vcc
	v_cmp_gt_f32_e32 vcc, s22, v35
	v_mul_f32_e32 v38, 0x4f800000, v35
	s_nop 0
	v_cndmask_b32_e32 v35, v35, v38, vcc
	v_sqrt_f32_e32 v38, v35
	s_nop 0
	v_add_u32_e32 v40, -1, v38
	v_fma_f32 v42, -v40, v38, v35
	v_cmp_ge_f32_e64 s[0:1], 0, v42
	v_add_u32_e32 v42, 1, v38
	s_nop 0
	v_cndmask_b32_e64 v40, v38, v40, s[0:1]
	v_fma_f32 v38, -v42, v38, v35
	v_cmp_lt_f32_e64 s[0:1], 0, v38
	s_nop 1
	v_cndmask_b32_e64 v38, v40, v42, s[0:1]
	v_mul_f32_e32 v40, 0x37800000, v38
	v_cndmask_b32_e32 v38, v38, v40, vcc
	v_cmp_class_f32_e32 vcc, v35, v193
	s_nop 1
	v_cndmask_b32_e32 v35, v38, v35, vcc
	v_cmp_ngt_f32_e32 vcc, s23, v32
	s_nop 1
	v_cndmask_b32_e32 v32, 1.0, v35, vcc
	v_mul_f32_e32 v32, v34, v32
	ds_read2_b32 v[34:35], v33 offset0:128 offset1:160
	s_waitcnt lgkmcnt(0)
	v_mul_f32_e32 v32, v34, v32
	ds_write_b32 v73, v36 offset:6656
	ds_write_b32 v73, v32 offset:43520
	v_add_f32_e32 v32, v63, v77
	v_mul_f32_e32 v32, 0xbfb8aa3b, v32
	v_exp_f32_e32 v32, v32
	v_add_f32_e32 v34, v47, v76
	v_mul_f32_e32 v34, 0xbfb8aa3b, v34
	v_exp_f32_e32 v34, v34
	v_add_f32_e32 v32, 1.0, v32
	v_rcp_f32_e32 v32, v32
	v_lshlrev_b64 v[46:47], 2, v[96:97]
	v_add_f32_e32 v34, 1.0, v34
	v_rcp_f32_e32 v36, v34
	v_mul_f32_e32 v32, v32, v75
	v_mul_f32_e32 v34, 0x3fb8aa3b, v32
	v_add_f32_e32 v32, v32, v32
	v_mul_f32_e32 v38, 0x3fb8aa3b, v32
	v_rndne_f32_e32 v38, v38
	v_fmamk_f32 v40, v38, 0xbf317218, v32
	v_fmac_f32_e32 v40, 0x3102e308, v38
	v_fmamk_f32 v42, v40, 0x395133b1, v192
	v_cmp_eq_f32_e32 vcc, s20, v38
	v_cvt_i32_f32_e32 v38, v38
	v_fmaak_f32 v42, v40, v42, 0x3c0887f9
	v_fmaak_f32 v42, v40, v42, 0x3d2aaa81
	v_fmaak_f32 v42, v40, v42, 0x3e2aaaab
	v_fma_f32 v42, v40, v42, 0.5
	v_ldexp_f32 v38, 1.0, v38
	v_mul_f32_e32 v42, v40, v42
	v_cndmask_b32_e32 v38, v38, v202, vcc
	v_fmac_f32_e32 v40, v40, v42
	v_add_f32_e32 v42, -1.0, v38
	v_fmac_f32_e32 v42, v38, v40
	v_add_f32_e32 v38, v42, v42
	v_cndmask_b32_e32 v38, v42, v38, vcc
	v_cmp_nlt_f32_e32 vcc, s21, v32
	v_lshl_add_u64 v[60:61], s[18:19], 0, v[46:47]
	v_exp_f32_e32 v34, v34
	v_cndmask_b32_e64 v38, v201, -v38, vcc
	v_cmp_gt_f32_e32 vcc, s22, v38
	v_mul_f32_e32 v40, 0x4f800000, v38
	s_nop 0
	v_cndmask_b32_e32 v38, v38, v40, vcc
	v_sqrt_f32_e32 v40, v38
	s_nop 0
	v_add_u32_e32 v42, -1, v40
	v_fma_f32 v44, -v42, v40, v38
	v_cmp_ge_f32_e64 s[0:1], 0, v44
	v_add_u32_e32 v44, 1, v40
	s_nop 0
	v_cndmask_b32_e64 v42, v40, v42, s[0:1]
	v_fma_f32 v40, -v44, v40, v38
	v_cmp_lt_f32_e64 s[0:1], 0, v40
	s_nop 1
	v_cndmask_b32_e64 v40, v42, v44, s[0:1]
	v_mul_f32_e32 v42, 0x37800000, v40
	v_cndmask_b32_e32 v40, v40, v42, vcc
	v_cmp_class_f32_e32 vcc, v38, v193
	s_nop 1
	v_cndmask_b32_e32 v38, v40, v38, vcc
	v_cmp_ngt_f32_e32 vcc, s23, v32
	s_nop 1
	v_cndmask_b32_e32 v32, 1.0, v38, vcc
	v_mul_f32_e32 v36, v36, v32
	ds_read2_b32 v[32:33], v33 offset0:192 offset1:224
	s_waitcnt lgkmcnt(0)
	v_mul_f32_e32 v32, v32, v36
	ds_write_b32 v73, v32 offset:43776
	v_mov_b32_e32 v32, v226
	v_mul_f32_e32 v32, 0xbfb8aa3b, v32
	v_exp_f32_e32 v32, v32
	s_nop 0
	v_add_f32_e32 v36, 1.0, v32
	v_add_f32_e32 v38, -1.0, v36
	v_sub_f32_e32 v40, v38, v36
	v_add_f32_e32 v40, 1.0, v40
	v_sub_f32_e32 v38, v32, v38
	v_add_f32_e32 v38, v38, v40
	v_frexp_mant_f32_e32 v40, v36
	v_cvt_f64_f32_e32 v[60:61], v36
	v_cmp_gt_f32_e32 vcc, s4, v40
	v_frexp_exp_i32_f64_e32 v40, v[60:61]
	s_mul_i32 s4, s11, 0x24000
	v_subbrev_co_u32_e32 v40, vcc, 0, v40, vcc
	v_sub_u32_e32 v42, 0, v40
	v_ldexp_f32 v36, v36, v42
	v_ldexp_f32 v38, v38, v42
	v_add_f32_e32 v42, -1.0, v36
	v_add_f32_e32 v48, 1.0, v36
	v_add_f32_e32 v44, 1.0, v42
	v_add_f32_e32 v50, -1.0, v48
	v_sub_f32_e32 v44, v36, v44
	v_sub_f32_e32 v36, v36, v50
	v_add_f32_e32 v36, v38, v36
	v_add_f32_e32 v44, v38, v44
	v_add_f32_e32 v38, v48, v36
	v_sub_f32_e32 v48, v38, v48
	v_sub_f32_e32 v36, v36, v48
	v_rcp_f32_e32 v48, v38
	v_add_f32_e32 v61, v42, v44
	v_sub_f32_e32 v42, v61, v42
	v_sub_f32_e32 v42, v44, v42
	v_mul_f32_e32 v44, v61, v48
	v_mul_f32_e32 v62, v38, v44
	v_fma_f32 v74, v44, v38, -v62
	v_fmac_f32_e32 v74, v44, v36
	v_add_f32_e32 v60, v62, v74
	v_sub_f32_e32 v63, v61, v60
	v_pk_add_f32 v[76:77], v[60:61], v[62:63] neg_lo:[0,1] neg_hi:[0,1]
	v_mov_b32_e32 v75, v60
	v_pk_add_f32 v[60:61], v[76:77], v[74:75] neg_lo:[0,1] neg_hi:[0,1]
	v_cmp_neq_f32_e32 vcc, s9, v32
	v_add_f32_e32 v42, v42, v61
	v_add_f32_e32 v42, v60, v42
	v_add_f32_e32 v61, v63, v42
	v_mul_f32_e32 v50, v48, v61
	v_mul_f32_e32 v62, v38, v50
	v_fma_f32 v74, v50, v38, -v62
	v_fmac_f32_e32 v74, v50, v36
	v_add_f32_e32 v60, v62, v74
	v_sub_f32_e32 v36, v63, v61
	v_sub_f32_e32 v63, v61, v60
	v_pk_add_f32 v[76:77], v[60:61], v[62:63] neg_lo:[0,1] neg_hi:[0,1]
	v_mov_b32_e32 v75, v60
	v_add_f32_e32 v36, v42, v36
	v_pk_add_f32 v[60:61], v[76:77], v[74:75] neg_lo:[0,1] neg_hi:[0,1]
	v_add_f32_e32 v38, v44, v50
	v_add_f32_e32 v36, v36, v61
	v_add_f32_e32 v36, v60, v36
	v_add_f32_e32 v36, v63, v36
	v_sub_f32_e32 v42, v38, v44
	v_mul_f32_e32 v36, v48, v36
	v_sub_f32_e32 v42, v50, v42
	v_add_f32_e32 v36, v42, v36
	v_add_f32_e32 v42, v38, v36
	v_cvt_f32_i32_e32 v60, v40
	v_mul_f32_e32 v44, v42, v42
	v_fmamk_f32 v48, v44, 0x3e9b6dac, v191
	v_fmaak_f32 v169, v44, v48, 0x3f2aaada
	v_mul_f32_e32 v61, v42, v44
	v_pk_mul_f32 v[74:75], v[60:61], v[168:169]
	v_ldexp_f32 v63, v42, 1
	v_fma_f32 v62, v60, s8, -v74
	v_fmac_f32_e32 v62, 0xb102e308, v60
	v_sub_f32_e32 v38, v42, v38
	v_pk_add_f32 v[60:61], v[74:75], v[62:63]
	v_sub_f32_e32 v36, v36, v38
	v_sub_f32_e32 v38, v61, v63
	v_ldexp_f32 v36, v36, 1
	v_sub_f32_e32 v38, v75, v38
	v_add_f32_e32 v77, v36, v38
	v_mov_b32_e32 v76, v74
	v_pk_add_f32 v[74:75], v[60:61], v[74:75] neg_lo:[0,1] neg_hi:[0,1]
	v_pk_add_f32 v[78:79], v[60:61], v[76:77]
	v_mov_b32_e32 v63, v60
	v_mov_b32_e32 v75, v79
	v_pk_add_f32 v[80:81], v[62:63], v[74:75] neg_lo:[0,1] neg_hi:[0,1]
	v_pk_add_f32 v[62:63], v[62:63], v[74:75]
	v_mov_b32_e32 v76, v77
	v_pk_add_f32 v[74:75], v[62:63], v[60:61] op_sel:[1,0] op_sel_hi:[0,1] neg_lo:[0,1] neg_hi:[0,1]
	v_pk_add_f32 v[82:83], v[78:79], v[74:75] op_sel_hi:[1,0] neg_lo:[0,1] neg_hi:[0,1]
	v_mov_b32_e32 v78, v79
	v_mov_b32_e32 v79, v63
	v_pk_mov_b32 v[74:75], v[60:61], v[74:75] op_sel:[1,0]
	v_mov_b32_e32 v77, v60
	v_pk_add_f32 v[74:75], v[78:79], v[74:75] neg_lo:[0,1] neg_hi:[0,1]
	v_mov_b32_e32 v82, v80
	v_pk_add_f32 v[60:61], v[76:77], v[74:75] neg_lo:[0,1] neg_hi:[0,1]
	v_mov_b32_e32 v81, v63
	v_pk_add_f32 v[74:75], v[82:83], v[60:61]
	v_pk_add_f32 v[76:77], v[74:75], v[74:75] op_sel:[0,1] op_sel_hi:[1,0]
	v_pk_add_f32 v[62:63], v[62:63], v[76:77] op_sel:[1,0] op_sel_hi:[0,1]
	v_mov_b32_e32 v75, v62
	v_pk_add_f32 v[78:79], v[74:75], v[80:81] neg_lo:[0,1] neg_hi:[0,1]
	v_mov_b32_e32 v61, v76
	v_sub_f32_e32 v36, v74, v78
	v_pk_add_f32 v[60:61], v[60:61], v[78:79] neg_lo:[0,1] neg_hi:[0,1]
	v_sub_f32_e32 v36, v80, v36
	v_add_f32_e32 v36, v60, v36
	v_add_f32_e32 v36, v36, v61
	v_add_f32_e32 v36, v62, v36
	v_cndmask_b32_e32 v36, v199, v36, vcc
	v_cmp_ngt_f32_e32 vcc, -1.0, v32
	v_lshl_add_u64 v[60:61], s[52:53], 0, v[46:47]
	v_lshl_add_u64 v[46:47], s[16:17], 0, v[46:47]
	v_cndmask_b32_e32 v36, v200, v36, vcc
	v_cmp_neq_f32_e32 vcc, -1.0, v32
	v_mov_b32_e32 v38, v227
	v_add_f32_e32 v0, v0, v38
	v_cndmask_b32_e32 v36, v201, v36, vcc
	v_cmp_lt_f32_e64 vcc, |v32|, s10
	v_mul_f32_e32 v0, 0xbfb8aa3b, v0
	v_exp_f32_e32 v0, v0
	v_cndmask_b32_e32 v32, v36, v32, vcc
	v_mov_b32_e32 v36, v228
	v_mul_f32_e32 v32, 0xc1000000, v32
	v_add_f32_e32 v0, 1.0, v0
	v_rcp_f32_e32 v0, v0
	v_add_f32_e32 v1, v1, v38
	v_mul_f32_e32 v1, 0xbfb8aa3b, v1
	v_exp_f32_e32 v1, v1
	v_add_f32_e32 v16, v16, v36
	v_mul_f32_e32 v16, 0xbfb8aa3b, v16
	v_exp_f32_e32 v16, v16
	v_add_f32_e32 v1, 1.0, v1
	v_rcp_f32_e32 v1, v1
	v_add_f32_e32 v16, 1.0, v16
	v_rcp_f32_e32 v16, v16
	s_nop 0
	v_mul_f32_e32 v16, v16, v32
	v_mul_f32_e32 v40, 0x3fb8aa3b, v16
	v_add_f32_e32 v16, v16, v16
	v_mul_f32_e32 v42, 0x3fb8aa3b, v16
	v_rndne_f32_e32 v42, v42
	v_fmamk_f32 v44, v42, 0xbf317218, v16
	v_fmac_f32_e32 v44, 0x3102e308, v42
	v_fmamk_f32 v46, v44, 0x395133b1, v192
	v_cmp_eq_f32_e32 vcc, s20, v42
	v_cvt_i32_f32_e32 v42, v42
	v_fmaak_f32 v46, v44, v46, 0x3c0887f9
	v_fmaak_f32 v46, v44, v46, 0x3d2aaa81
	v_fmaak_f32 v46, v44, v46, 0x3e2aaaab
	v_fma_f32 v46, v44, v46, 0.5
	v_ldexp_f32 v42, 1.0, v42
	v_mul_f32_e32 v46, v44, v46
	v_cndmask_b32_e32 v42, v42, v202, vcc
	v_fmac_f32_e32 v44, v44, v46
	v_add_f32_e32 v46, -1.0, v42
	v_fmac_f32_e32 v46, v42, v44
	v_add_f32_e32 v42, v46, v46
	v_cndmask_b32_e32 v42, v46, v42, vcc
	v_cmp_nlt_f32_e32 vcc, s21, v16
	v_exp_f32_e32 v40, v40
	s_nop 0
	v_cndmask_b32_e64 v42, v201, -v42, vcc
	v_cmp_gt_f32_e32 vcc, s22, v42
	v_mul_f32_e32 v44, 0x4f800000, v42
	s_nop 0
	v_cndmask_b32_e32 v42, v42, v44, vcc
	v_sqrt_f32_e32 v44, v42
	s_nop 0
	v_add_u32_e32 v46, -1, v44
	v_fma_f32 v47, -v46, v44, v42
	v_cmp_ge_f32_e64 s[0:1], 0, v47
	v_add_u32_e32 v47, 1, v44
	s_nop 0
	v_cndmask_b32_e64 v46, v44, v46, s[0:1]
	v_fma_f32 v44, -v47, v44, v42
	v_cmp_lt_f32_e64 s[0:1], 0, v44
	s_nop 1
	v_cndmask_b32_e64 v44, v46, v47, s[0:1]
	v_mul_f32_e32 v46, 0x37800000, v44
	v_cndmask_b32_e32 v44, v44, v46, vcc
	v_cmp_class_f32_e32 vcc, v42, v193
	s_nop 1
	v_cndmask_b32_e32 v42, v44, v42, vcc
	v_cmp_ngt_f32_e32 vcc, s23, v16
	s_nop 1
	v_cndmask_b32_e32 v16, 1.0, v42, vcc
	v_mul_f32_e32 v0, v0, v16
	v_mul_f32_e32 v0, v67, v0
	ds_write_b32 v73, v40 offset:128
	ds_write_b32 v73, v0 offset:36992
	v_add_f32_e32 v0, v17, v36
	v_mul_f32_e32 v0, 0xbfb8aa3b, v0
	v_exp_f32_e32 v0, v0
	s_nop 0
	v_add_f32_e32 v0, 1.0, v0
	v_rcp_f32_e32 v0, v0
	s_nop 0
	v_mul_f32_e32 v0, v0, v32
	v_mul_f32_e32 v16, 0x3fb8aa3b, v0
	v_add_f32_e32 v0, v0, v0
	v_mul_f32_e32 v17, 0x3fb8aa3b, v0
	v_rndne_f32_e32 v17, v17
	v_fmamk_f32 v40, v17, 0xbf317218, v0
	v_fmac_f32_e32 v40, 0x3102e308, v17
	v_fmamk_f32 v42, v40, 0x395133b1, v192
	v_cmp_eq_f32_e32 vcc, s20, v17
	v_cvt_i32_f32_e32 v17, v17
	v_fmaak_f32 v42, v40, v42, 0x3c0887f9
	v_fmaak_f32 v42, v40, v42, 0x3d2aaa81
	v_fmaak_f32 v42, v40, v42, 0x3e2aaaab
	v_fma_f32 v42, v40, v42, 0.5
	v_ldexp_f32 v17, 1.0, v17
	v_mul_f32_e32 v42, v40, v42
	v_cndmask_b32_e32 v17, v17, v202, vcc
	v_fmac_f32_e32 v40, v40, v42
	v_add_f32_e32 v42, -1.0, v17
	v_fmac_f32_e32 v42, v17, v40
	v_add_f32_e32 v17, v42, v42
	v_cndmask_b32_e32 v17, v42, v17, vcc
	v_cmp_nlt_f32_e32 vcc, s21, v0
	v_exp_f32_e32 v16, v16
	s_nop 0
	v_cndmask_b32_e64 v17, v201, -v17, vcc
	v_cmp_gt_f32_e32 vcc, s22, v17
	v_mul_f32_e32 v40, 0x4f800000, v17
	s_nop 0
	v_cndmask_b32_e32 v17, v17, v40, vcc
	v_sqrt_f32_e32 v40, v17
	s_nop 0
	v_add_u32_e32 v42, -1, v40
	v_fma_f32 v44, -v42, v40, v17
	v_cmp_ge_f32_e64 s[0:1], 0, v44
	v_add_u32_e32 v44, 1, v40
	s_nop 0
	v_cndmask_b32_e64 v42, v40, v42, s[0:1]
	v_fma_f32 v40, -v44, v40, v17
	v_cmp_lt_f32_e64 s[0:1], 0, v40
	s_nop 1
	v_cndmask_b32_e64 v40, v42, v44, s[0:1]
	v_mul_f32_e32 v42, 0x37800000, v40
	v_cndmask_b32_e32 v40, v40, v42, vcc
	v_cmp_class_f32_e32 vcc, v17, v193
	s_nop 1
	v_cndmask_b32_e32 v17, v40, v17, vcc
	v_cmp_ngt_f32_e32 vcc, s23, v0
	s_nop 1
	v_cndmask_b32_e32 v0, 1.0, v17, vcc
	v_mul_f32_e32 v0, v1, v0
	v_mul_f32_e32 v0, v49, v0
	ds_write_b32 v73, v16 offset:384
	ds_write_b32 v73, v0 offset:37248
	v_add_f32_e32 v0, v18, v36
	v_mul_f32_e32 v0, 0xbfb8aa3b, v0
	v_exp_f32_e32 v0, v0
	v_add_f32_e32 v1, v2, v38
	v_mul_f32_e32 v1, 0xbfb8aa3b, v1
	v_exp_f32_e32 v1, v1
	v_add_f32_e32 v0, 1.0, v0
	v_rcp_f32_e32 v0, v0
	v_add_f32_e32 v1, 1.0, v1
	v_rcp_f32_e32 v1, v1
	v_mul_f32_e32 v0, v0, v32
	v_mul_f32_e32 v2, 0x3fb8aa3b, v0
	v_add_f32_e32 v0, v0, v0
	v_mul_f32_e32 v16, 0x3fb8aa3b, v0
	v_rndne_f32_e32 v16, v16
	v_fmamk_f32 v17, v16, 0xbf317218, v0
	v_fmac_f32_e32 v17, 0x3102e308, v16
	v_fmamk_f32 v18, v17, 0x395133b1, v192
	v_cmp_eq_f32_e32 vcc, s20, v16
	v_cvt_i32_f32_e32 v16, v16
	v_fmaak_f32 v18, v17, v18, 0x3c0887f9
	v_fmaak_f32 v18, v17, v18, 0x3d2aaa81
	v_fmaak_f32 v18, v17, v18, 0x3e2aaaab
	v_fma_f32 v18, v17, v18, 0.5
	v_ldexp_f32 v16, 1.0, v16
	v_mul_f32_e32 v18, v17, v18
	v_cndmask_b32_e32 v16, v16, v202, vcc
	v_fmac_f32_e32 v17, v17, v18
	v_add_f32_e32 v18, -1.0, v16
	v_fmac_f32_e32 v18, v16, v17
	v_add_f32_e32 v16, v18, v18
	v_cndmask_b32_e32 v16, v18, v16, vcc
	v_cmp_nlt_f32_e32 vcc, s21, v0
	v_exp_f32_e32 v2, v2
	s_nop 0
	v_cndmask_b32_e64 v16, v201, -v16, vcc
	v_cmp_gt_f32_e32 vcc, s22, v16
	v_mul_f32_e32 v17, 0x4f800000, v16
	s_nop 0
	v_cndmask_b32_e32 v16, v16, v17, vcc
	v_sqrt_f32_e32 v17, v16
	s_nop 0
	v_add_u32_e32 v18, -1, v17
	v_fma_f32 v40, -v18, v17, v16
	v_cmp_ge_f32_e64 s[0:1], 0, v40
	v_add_u32_e32 v40, 1, v17
	s_nop 0
	v_cndmask_b32_e64 v18, v17, v18, s[0:1]
	v_fma_f32 v17, -v40, v17, v16
	v_cmp_lt_f32_e64 s[0:1], 0, v17
	s_nop 1
	v_cndmask_b32_e64 v17, v18, v40, s[0:1]
	v_mul_f32_e32 v18, 0x37800000, v17
	v_cndmask_b32_e32 v17, v17, v18, vcc
	v_cmp_class_f32_e32 vcc, v16, v193
	s_nop 1
	v_cndmask_b32_e32 v16, v17, v16, vcc
	v_cmp_ngt_f32_e32 vcc, s23, v0
	s_nop 1
	v_cndmask_b32_e32 v0, 1.0, v16, vcc
	v_mul_f32_e32 v0, v1, v0
	v_mul_f32_e32 v0, v69, v0
	ds_write_b32 v73, v2 offset:640
	ds_write_b32 v73, v0 offset:37504
	v_add_f32_e32 v0, v19, v36
	v_mul_f32_e32 v0, 0xbfb8aa3b, v0
	v_exp_f32_e32 v0, v0
	v_add_f32_e32 v1, v3, v38
	v_mul_f32_e32 v1, 0xbfb8aa3b, v1
	v_exp_f32_e32 v1, v1
	v_add_f32_e32 v0, 1.0, v0
	v_rcp_f32_e32 v0, v0
	v_add_f32_e32 v1, 1.0, v1
	v_rcp_f32_e32 v1, v1
	v_mul_f32_e32 v0, v0, v32
	v_mul_f32_e32 v2, 0x3fb8aa3b, v0
	v_add_f32_e32 v0, v0, v0
	v_mul_f32_e32 v3, 0x3fb8aa3b, v0
	v_rndne_f32_e32 v3, v3
	v_fmamk_f32 v16, v3, 0xbf317218, v0
	v_fmac_f32_e32 v16, 0x3102e308, v3
	v_fmamk_f32 v17, v16, 0x395133b1, v192
	v_cmp_eq_f32_e32 vcc, s20, v3
	v_cvt_i32_f32_e32 v3, v3
	v_fmaak_f32 v17, v16, v17, 0x3c0887f9
	v_fmaak_f32 v17, v16, v17, 0x3d2aaa81
	v_fmaak_f32 v17, v16, v17, 0x3e2aaaab
	v_fma_f32 v17, v16, v17, 0.5
	v_ldexp_f32 v3, 1.0, v3
	v_mul_f32_e32 v17, v16, v17
	v_cndmask_b32_e32 v3, v3, v202, vcc
	v_fmac_f32_e32 v16, v16, v17
	v_add_f32_e32 v17, -1.0, v3
	v_fmac_f32_e32 v17, v3, v16
	v_add_f32_e32 v3, v17, v17
	v_cndmask_b32_e32 v3, v17, v3, vcc
	v_cmp_nlt_f32_e32 vcc, s21, v0
	v_exp_f32_e32 v2, v2
	s_nop 0
	v_cndmask_b32_e64 v3, v201, -v3, vcc
	v_cmp_gt_f32_e32 vcc, s22, v3
	v_mul_f32_e32 v16, 0x4f800000, v3
	s_nop 0
	v_cndmask_b32_e32 v3, v3, v16, vcc
	v_sqrt_f32_e32 v16, v3
	s_nop 0
	v_add_u32_e32 v17, -1, v16
	v_fma_f32 v18, -v17, v16, v3
	v_cmp_ge_f32_e64 s[0:1], 0, v18
	v_add_u32_e32 v18, 1, v16
	s_nop 0
	v_cndmask_b32_e64 v17, v16, v17, s[0:1]
	v_fma_f32 v16, -v18, v16, v3
	v_cmp_lt_f32_e64 s[0:1], 0, v16
	s_nop 1
	v_cndmask_b32_e64 v16, v17, v18, s[0:1]
	v_mul_f32_e32 v17, 0x37800000, v16
	v_cndmask_b32_e32 v16, v16, v17, vcc
	v_cmp_class_f32_e32 vcc, v3, v193
	s_nop 1
	v_cndmask_b32_e32 v3, v16, v3, vcc
	v_cmp_ngt_f32_e32 vcc, s23, v0
	s_nop 1
	v_cndmask_b32_e32 v0, 1.0, v3, vcc
	v_mul_f32_e32 v0, v1, v0
	v_mul_f32_e32 v0, v51, v0
	ds_write_b32 v73, v2 offset:896
	ds_write_b32 v73, v0 offset:37760
	v_add_f32_e32 v0, v20, v36
	v_mul_f32_e32 v0, 0xbfb8aa3b, v0
	v_exp_f32_e32 v0, v0
	v_add_f32_e32 v1, v4, v38
	v_mul_f32_e32 v1, 0xbfb8aa3b, v1
	v_exp_f32_e32 v1, v1
	v_add_f32_e32 v0, 1.0, v0
	v_rcp_f32_e32 v0, v0
	v_add_f32_e32 v1, 1.0, v1
	v_rcp_f32_e32 v1, v1
	v_mul_f32_e32 v0, v0, v32
	v_mul_f32_e32 v2, 0x3fb8aa3b, v0
	v_add_f32_e32 v0, v0, v0
	v_mul_f32_e32 v3, 0x3fb8aa3b, v0
	v_rndne_f32_e32 v3, v3
	v_fmamk_f32 v4, v3, 0xbf317218, v0
	v_fmac_f32_e32 v4, 0x3102e308, v3
	v_fmamk_f32 v16, v4, 0x395133b1, v192
	v_cmp_eq_f32_e32 vcc, s20, v3
	v_cvt_i32_f32_e32 v3, v3
	v_fmaak_f32 v16, v4, v16, 0x3c0887f9
	v_fmaak_f32 v16, v4, v16, 0x3d2aaa81
	v_fmaak_f32 v16, v4, v16, 0x3e2aaaab
	v_fma_f32 v16, v4, v16, 0.5
	v_ldexp_f32 v3, 1.0, v3
	v_mul_f32_e32 v16, v4, v16
	v_cndmask_b32_e32 v3, v3, v202, vcc
	v_fmac_f32_e32 v4, v4, v16
	v_add_f32_e32 v16, -1.0, v3
	v_fmac_f32_e32 v16, v3, v4
	v_add_f32_e32 v3, v16, v16
	v_cndmask_b32_e32 v3, v16, v3, vcc
	v_cmp_nlt_f32_e32 vcc, s21, v0
	v_exp_f32_e32 v2, v2
	s_nop 0
	v_cndmask_b32_e64 v3, v201, -v3, vcc
	v_cmp_gt_f32_e32 vcc, s22, v3
	v_mul_f32_e32 v4, 0x4f800000, v3
	s_nop 0
	v_cndmask_b32_e32 v3, v3, v4, vcc
	v_sqrt_f32_e32 v4, v3
	s_nop 0
	v_add_u32_e32 v16, -1, v4
	v_fma_f32 v17, -v16, v4, v3
	v_cmp_ge_f32_e64 s[0:1], 0, v17
	v_add_u32_e32 v17, 1, v4
	s_nop 0
	v_cndmask_b32_e64 v16, v4, v16, s[0:1]
	v_fma_f32 v4, -v17, v4, v3
	v_cmp_lt_f32_e64 s[0:1], 0, v4
	s_nop 1
	v_cndmask_b32_e64 v4, v16, v17, s[0:1]
	v_mul_f32_e32 v16, 0x37800000, v4
	v_cndmask_b32_e32 v4, v4, v16, vcc
	v_cmp_class_f32_e32 vcc, v3, v193
	s_nop 1
	v_cndmask_b32_e32 v3, v4, v3, vcc
	v_cmp_ngt_f32_e32 vcc, s23, v0
	s_nop 1
	v_cndmask_b32_e32 v0, 1.0, v3, vcc
	v_mul_f32_e32 v0, v1, v0
	v_mul_f32_e32 v0, v71, v0
	ds_write_b32 v73, v2 offset:2176
	ds_write_b32 v73, v0 offset:39040
	v_add_f32_e32 v0, v21, v36
	v_mul_f32_e32 v0, 0xbfb8aa3b, v0
	v_exp_f32_e32 v0, v0
	v_add_f32_e32 v1, v5, v38
	v_mul_f32_e32 v1, 0xbfb8aa3b, v1
	v_exp_f32_e32 v1, v1
	v_add_f32_e32 v0, 1.0, v0
	v_rcp_f32_e32 v0, v0
	v_add_f32_e32 v1, 1.0, v1
	v_rcp_f32_e32 v1, v1
	v_mul_f32_e32 v0, v0, v32
	v_mul_f32_e32 v2, 0x3fb8aa3b, v0
	v_add_f32_e32 v0, v0, v0
	v_mul_f32_e32 v3, 0x3fb8aa3b, v0
	v_rndne_f32_e32 v3, v3
	v_fmamk_f32 v4, v3, 0xbf317218, v0
	v_fmac_f32_e32 v4, 0x3102e308, v3
	v_fmamk_f32 v5, v4, 0x395133b1, v192
	v_cmp_eq_f32_e32 vcc, s20, v3
	v_cvt_i32_f32_e32 v3, v3
	v_fmaak_f32 v5, v4, v5, 0x3c0887f9
	v_fmaak_f32 v5, v4, v5, 0x3d2aaa81
	v_fmaak_f32 v5, v4, v5, 0x3e2aaaab
	v_fma_f32 v5, v4, v5, 0.5
	v_ldexp_f32 v3, 1.0, v3
	v_mul_f32_e32 v5, v4, v5
	v_cndmask_b32_e32 v3, v3, v202, vcc
	v_fmac_f32_e32 v4, v4, v5
	v_add_f32_e32 v5, -1.0, v3
	v_fmac_f32_e32 v5, v3, v4
	v_add_f32_e32 v3, v5, v5
	v_cndmask_b32_e32 v3, v5, v3, vcc
	v_cmp_nlt_f32_e32 vcc, s21, v0
	v_exp_f32_e32 v2, v2
	s_nop 0
	v_cndmask_b32_e64 v3, v201, -v3, vcc
	v_cmp_gt_f32_e32 vcc, s22, v3
	v_mul_f32_e32 v4, 0x4f800000, v3
	s_nop 0
	v_cndmask_b32_e32 v3, v3, v4, vcc
	v_sqrt_f32_e32 v4, v3
	s_nop 0
	v_add_u32_e32 v5, -1, v4
	v_fma_f32 v16, -v5, v4, v3
	v_cmp_ge_f32_e64 s[0:1], 0, v16
	v_add_u32_e32 v16, 1, v4
	s_nop 0
	v_cndmask_b32_e64 v5, v4, v5, s[0:1]
	v_fma_f32 v4, -v16, v4, v3
	v_cmp_lt_f32_e64 s[0:1], 0, v4
	s_nop 1
	v_cndmask_b32_e64 v4, v5, v16, s[0:1]
	v_mul_f32_e32 v5, 0x37800000, v4
	v_cndmask_b32_e32 v4, v4, v5, vcc
	v_cmp_class_f32_e32 vcc, v3, v193
	s_nop 1
	v_cndmask_b32_e32 v3, v4, v3, vcc
	v_cmp_ngt_f32_e32 vcc, s23, v0
	s_nop 1
	v_cndmask_b32_e32 v0, 1.0, v3, vcc
	v_mul_f32_e32 v0, v1, v0
	v_mul_f32_e32 v0, v37, v0
	ds_write_b32 v73, v2 offset:2432
	ds_write_b32 v73, v0 offset:39296
	v_add_f32_e32 v0, v22, v36
	v_mul_f32_e32 v0, 0xbfb8aa3b, v0
	v_exp_f32_e32 v0, v0
	v_add_f32_e32 v1, v6, v38
	v_mul_f32_e32 v1, 0xbfb8aa3b, v1
	v_exp_f32_e32 v1, v1
	v_add_f32_e32 v0, 1.0, v0
	v_rcp_f32_e32 v0, v0
	v_add_f32_e32 v1, 1.0, v1
	v_rcp_f32_e32 v1, v1
	v_mul_f32_e32 v0, v0, v32
	v_mul_f32_e32 v2, 0x3fb8aa3b, v0
	v_add_f32_e32 v0, v0, v0
	v_mul_f32_e32 v3, 0x3fb8aa3b, v0
	v_rndne_f32_e32 v3, v3
	v_fmamk_f32 v4, v3, 0xbf317218, v0
	v_fmac_f32_e32 v4, 0x3102e308, v3
	v_fmamk_f32 v5, v4, 0x395133b1, v192
	v_cmp_eq_f32_e32 vcc, s20, v3
	v_cvt_i32_f32_e32 v3, v3
	v_fmaak_f32 v5, v4, v5, 0x3c0887f9
	v_fmaak_f32 v5, v4, v5, 0x3d2aaa81
	v_fmaak_f32 v5, v4, v5, 0x3e2aaaab
	v_fma_f32 v5, v4, v5, 0.5
	v_ldexp_f32 v3, 1.0, v3
	v_mul_f32_e32 v5, v4, v5
	v_cndmask_b32_e32 v3, v3, v202, vcc
	v_fmac_f32_e32 v4, v4, v5
	v_add_f32_e32 v5, -1.0, v3
	v_fmac_f32_e32 v5, v3, v4
	v_add_f32_e32 v3, v5, v5
	v_cndmask_b32_e32 v3, v5, v3, vcc
	v_cmp_nlt_f32_e32 vcc, s21, v0
	v_exp_f32_e32 v2, v2
	s_nop 0
	v_cndmask_b32_e64 v3, v201, -v3, vcc
	v_cmp_gt_f32_e32 vcc, s22, v3
	v_mul_f32_e32 v4, 0x4f800000, v3
	s_nop 0
	v_cndmask_b32_e32 v3, v3, v4, vcc
	v_sqrt_f32_e32 v4, v3
	s_nop 0
	v_add_u32_e32 v5, -1, v4
	v_fma_f32 v6, -v5, v4, v3
	v_cmp_ge_f32_e64 s[0:1], 0, v6
	v_add_u32_e32 v6, 1, v4
	s_nop 0
	v_cndmask_b32_e64 v5, v4, v5, s[0:1]
	v_fma_f32 v4, -v6, v4, v3
	v_cmp_lt_f32_e64 s[0:1], 0, v4
	s_nop 1
	v_cndmask_b32_e64 v4, v5, v6, s[0:1]
	v_mul_f32_e32 v5, 0x37800000, v4
	v_cndmask_b32_e32 v4, v4, v5, vcc
	v_cmp_class_f32_e32 vcc, v3, v193
	s_nop 1
	v_cndmask_b32_e32 v3, v4, v3, vcc
	v_cmp_ngt_f32_e32 vcc, s23, v0
	s_nop 1
	v_cndmask_b32_e32 v0, 1.0, v3, vcc
	v_mul_f32_e32 v0, v1, v0
	v_mul_f32_e32 v0, v53, v0
	ds_write_b32 v73, v2 offset:2688
	ds_write_b32 v73, v0 offset:39552
	v_add_f32_e32 v0, v23, v36
	v_mul_f32_e32 v0, 0xbfb8aa3b, v0
	v_exp_f32_e32 v0, v0
	v_add_f32_e32 v1, v7, v38
	v_mul_f32_e32 v1, 0xbfb8aa3b, v1
	v_exp_f32_e32 v1, v1
	v_add_f32_e32 v0, 1.0, v0
	v_rcp_f32_e32 v0, v0
	v_add_f32_e32 v1, 1.0, v1
	v_rcp_f32_e32 v1, v1
	v_mul_f32_e32 v0, v0, v32
	v_mul_f32_e32 v2, 0x3fb8aa3b, v0
	v_add_f32_e32 v0, v0, v0
	v_mul_f32_e32 v3, 0x3fb8aa3b, v0
	v_rndne_f32_e32 v3, v3
	v_fmamk_f32 v4, v3, 0xbf317218, v0
	v_fmac_f32_e32 v4, 0x3102e308, v3
	v_fmamk_f32 v5, v4, 0x395133b1, v192
	v_cmp_eq_f32_e32 vcc, s20, v3
	v_cvt_i32_f32_e32 v3, v3
	v_fmaak_f32 v5, v4, v5, 0x3c0887f9
	v_fmaak_f32 v5, v4, v5, 0x3d2aaa81
	v_fmaak_f32 v5, v4, v5, 0x3e2aaaab
	v_fma_f32 v5, v4, v5, 0.5
	v_ldexp_f32 v3, 1.0, v3
	v_mul_f32_e32 v5, v4, v5
	v_cndmask_b32_e32 v3, v3, v202, vcc
	v_fmac_f32_e32 v4, v4, v5
	v_add_f32_e32 v5, -1.0, v3
	v_fmac_f32_e32 v5, v3, v4
	v_add_f32_e32 v3, v5, v5
	v_cndmask_b32_e32 v3, v5, v3, vcc
	v_cmp_nlt_f32_e32 vcc, s21, v0
	v_exp_f32_e32 v2, v2
	s_nop 0
	v_cndmask_b32_e64 v3, v201, -v3, vcc
	v_cmp_gt_f32_e32 vcc, s22, v3
	v_mul_f32_e32 v4, 0x4f800000, v3
	s_nop 0
	v_cndmask_b32_e32 v3, v3, v4, vcc
	v_sqrt_f32_e32 v4, v3
	s_nop 0
	v_add_u32_e32 v5, -1, v4
	v_fma_f32 v6, -v5, v4, v3
	v_cmp_ge_f32_e64 s[0:1], 0, v6
	v_add_u32_e32 v6, 1, v4
	s_nop 0
	v_cndmask_b32_e64 v5, v4, v5, s[0:1]
	v_fma_f32 v4, -v6, v4, v3
	v_cmp_lt_f32_e64 s[0:1], 0, v4
	s_nop 1
	v_cndmask_b32_e64 v4, v5, v6, s[0:1]
	v_mul_f32_e32 v5, 0x37800000, v4
	v_cndmask_b32_e32 v4, v4, v5, vcc
	v_cmp_class_f32_e32 vcc, v3, v193
	s_nop 1
	v_cndmask_b32_e32 v3, v4, v3, vcc
	v_cmp_ngt_f32_e32 vcc, s23, v0
	s_nop 1
	v_cndmask_b32_e32 v0, 1.0, v3, vcc
	v_mul_f32_e32 v0, v1, v0
	v_mul_f32_e32 v0, v39, v0
	ds_write_b32 v73, v2 offset:2944
	ds_write_b32 v73, v0 offset:39808
	v_add_f32_e32 v0, v24, v36
	v_mul_f32_e32 v0, 0xbfb8aa3b, v0
	v_exp_f32_e32 v0, v0
	v_add_f32_e32 v1, v8, v38
	v_mul_f32_e32 v1, 0xbfb8aa3b, v1
	v_exp_f32_e32 v1, v1
	v_add_f32_e32 v0, 1.0, v0
	v_rcp_f32_e32 v0, v0
	v_add_f32_e32 v1, 1.0, v1
	v_rcp_f32_e32 v1, v1
	v_mul_f32_e32 v0, v0, v32
	v_mul_f32_e32 v2, 0x3fb8aa3b, v0
	v_add_f32_e32 v0, v0, v0
	v_mul_f32_e32 v3, 0x3fb8aa3b, v0
	v_rndne_f32_e32 v3, v3
	v_fmamk_f32 v4, v3, 0xbf317218, v0
	v_fmac_f32_e32 v4, 0x3102e308, v3
	v_fmamk_f32 v5, v4, 0x395133b1, v192
	v_cmp_eq_f32_e32 vcc, s20, v3
	v_cvt_i32_f32_e32 v3, v3
	v_fmaak_f32 v5, v4, v5, 0x3c0887f9
	v_fmaak_f32 v5, v4, v5, 0x3d2aaa81
	v_fmaak_f32 v5, v4, v5, 0x3e2aaaab
	v_fma_f32 v5, v4, v5, 0.5
	v_ldexp_f32 v3, 1.0, v3
	v_mul_f32_e32 v5, v4, v5
	v_cndmask_b32_e32 v3, v3, v202, vcc
	v_fmac_f32_e32 v4, v4, v5
	v_add_f32_e32 v5, -1.0, v3
	v_fmac_f32_e32 v5, v3, v4
	v_add_f32_e32 v3, v5, v5
	v_cndmask_b32_e32 v3, v5, v3, vcc
	v_cmp_nlt_f32_e32 vcc, s21, v0
	v_exp_f32_e32 v2, v2
	s_nop 0
	v_cndmask_b32_e64 v3, v201, -v3, vcc
	v_cmp_gt_f32_e32 vcc, s22, v3
	v_mul_f32_e32 v4, 0x4f800000, v3
	s_nop 0
	v_cndmask_b32_e32 v3, v3, v4, vcc
	v_sqrt_f32_e32 v4, v3
	s_nop 0
	v_add_u32_e32 v5, -1, v4
	v_fma_f32 v6, -v5, v4, v3
	v_cmp_ge_f32_e64 s[0:1], 0, v6
	v_add_u32_e32 v6, 1, v4
	s_nop 0
	v_cndmask_b32_e64 v5, v4, v5, s[0:1]
	v_fma_f32 v4, -v6, v4, v3
	v_cmp_lt_f32_e64 s[0:1], 0, v4
	s_nop 1
	v_cndmask_b32_e64 v4, v5, v6, s[0:1]
	v_mul_f32_e32 v5, 0x37800000, v4
	v_cndmask_b32_e32 v4, v4, v5, vcc
	v_cmp_class_f32_e32 vcc, v3, v193
	s_nop 1
	v_cndmask_b32_e32 v3, v4, v3, vcc
	v_cmp_ngt_f32_e32 vcc, s23, v0
	s_nop 1
	v_cndmask_b32_e32 v0, 1.0, v3, vcc
	v_mul_f32_e32 v0, v1, v0
	v_mul_f32_e32 v0, v55, v0
	ds_write_b32 v73, v2 offset:4224
	ds_write_b32 v73, v0 offset:41088
	v_add_f32_e32 v0, v25, v36
	v_mul_f32_e32 v0, 0xbfb8aa3b, v0
	v_exp_f32_e32 v0, v0
	v_add_f32_e32 v1, v9, v38
	v_mul_f32_e32 v1, 0xbfb8aa3b, v1
	v_exp_f32_e32 v1, v1
	v_add_f32_e32 v0, 1.0, v0
	v_rcp_f32_e32 v0, v0
	v_add_f32_e32 v1, 1.0, v1
	v_rcp_f32_e32 v1, v1
	v_mul_f32_e32 v0, v0, v32
	v_mul_f32_e32 v2, 0x3fb8aa3b, v0
	v_add_f32_e32 v0, v0, v0
	v_mul_f32_e32 v3, 0x3fb8aa3b, v0
	v_rndne_f32_e32 v3, v3
	v_fmamk_f32 v4, v3, 0xbf317218, v0
	v_fmac_f32_e32 v4, 0x3102e308, v3
	v_fmamk_f32 v5, v4, 0x395133b1, v192
	v_cmp_eq_f32_e32 vcc, s20, v3
	v_cvt_i32_f32_e32 v3, v3
	v_fmaak_f32 v5, v4, v5, 0x3c0887f9
	v_fmaak_f32 v5, v4, v5, 0x3d2aaa81
	v_fmaak_f32 v5, v4, v5, 0x3e2aaaab
	v_fma_f32 v5, v4, v5, 0.5
	v_ldexp_f32 v3, 1.0, v3
	v_mul_f32_e32 v5, v4, v5
	v_cndmask_b32_e32 v3, v3, v202, vcc
	v_fmac_f32_e32 v4, v4, v5
	v_add_f32_e32 v5, -1.0, v3
	v_fmac_f32_e32 v5, v3, v4
	v_add_f32_e32 v3, v5, v5
	v_cndmask_b32_e32 v3, v5, v3, vcc
	v_cmp_nlt_f32_e32 vcc, s21, v0
	v_exp_f32_e32 v2, v2
	s_nop 0
	v_cndmask_b32_e64 v3, v201, -v3, vcc
	v_cmp_gt_f32_e32 vcc, s22, v3
	v_mul_f32_e32 v4, 0x4f800000, v3
	s_nop 0
	v_cndmask_b32_e32 v3, v3, v4, vcc
	v_sqrt_f32_e32 v4, v3
	s_nop 0
	v_add_u32_e32 v5, -1, v4
	v_fma_f32 v6, -v5, v4, v3
	v_cmp_ge_f32_e64 s[0:1], 0, v6
	v_add_u32_e32 v6, 1, v4
	s_nop 0
	v_cndmask_b32_e64 v5, v4, v5, s[0:1]
	v_fma_f32 v4, -v6, v4, v3
	v_cmp_lt_f32_e64 s[0:1], 0, v4
	s_nop 1
	v_cndmask_b32_e64 v4, v5, v6, s[0:1]
	v_mul_f32_e32 v5, 0x37800000, v4
	v_cndmask_b32_e32 v4, v4, v5, vcc
	v_cmp_class_f32_e32 vcc, v3, v193
	s_nop 1
	v_cndmask_b32_e32 v3, v4, v3, vcc
	v_cmp_ngt_f32_e32 vcc, s23, v0
	s_nop 1
	v_cndmask_b32_e32 v0, 1.0, v3, vcc
	v_mul_f32_e32 v0, v1, v0
	v_mul_f32_e32 v0, v41, v0
	ds_write_b32 v73, v2 offset:4480
	ds_write_b32 v73, v0 offset:41344
	v_add_f32_e32 v0, v26, v36
	v_mul_f32_e32 v0, 0xbfb8aa3b, v0
	v_exp_f32_e32 v0, v0
	v_add_f32_e32 v1, v10, v38
	v_mul_f32_e32 v1, 0xbfb8aa3b, v1
	v_exp_f32_e32 v1, v1
	v_add_f32_e32 v0, 1.0, v0
	v_rcp_f32_e32 v0, v0
	v_add_f32_e32 v1, 1.0, v1
	v_rcp_f32_e32 v1, v1
	v_mul_f32_e32 v0, v0, v32
	v_mul_f32_e32 v2, 0x3fb8aa3b, v0
	v_add_f32_e32 v0, v0, v0
	v_mul_f32_e32 v3, 0x3fb8aa3b, v0
	v_rndne_f32_e32 v3, v3
	v_fmamk_f32 v4, v3, 0xbf317218, v0
	v_fmac_f32_e32 v4, 0x3102e308, v3
	v_fmamk_f32 v5, v4, 0x395133b1, v192
	v_cmp_eq_f32_e32 vcc, s20, v3
	v_cvt_i32_f32_e32 v3, v3
	v_fmaak_f32 v5, v4, v5, 0x3c0887f9
	v_fmaak_f32 v5, v4, v5, 0x3d2aaa81
	v_fmaak_f32 v5, v4, v5, 0x3e2aaaab
	v_fma_f32 v5, v4, v5, 0.5
	v_ldexp_f32 v3, 1.0, v3
	v_mul_f32_e32 v5, v4, v5
	v_cndmask_b32_e32 v3, v3, v202, vcc
	v_fmac_f32_e32 v4, v4, v5
	v_add_f32_e32 v5, -1.0, v3
	v_fmac_f32_e32 v5, v3, v4
	v_add_f32_e32 v3, v5, v5
	v_cndmask_b32_e32 v3, v5, v3, vcc
	v_cmp_nlt_f32_e32 vcc, s21, v0
	v_exp_f32_e32 v2, v2
	s_nop 0
	v_cndmask_b32_e64 v3, v201, -v3, vcc
	v_cmp_gt_f32_e32 vcc, s22, v3
	v_mul_f32_e32 v4, 0x4f800000, v3
	s_nop 0
	v_cndmask_b32_e32 v3, v3, v4, vcc
	v_sqrt_f32_e32 v4, v3
	s_nop 0
	v_add_u32_e32 v5, -1, v4
	v_fma_f32 v6, -v5, v4, v3
	v_cmp_ge_f32_e64 s[0:1], 0, v6
	v_add_u32_e32 v6, 1, v4
	s_nop 0
	v_cndmask_b32_e64 v5, v4, v5, s[0:1]
	v_fma_f32 v4, -v6, v4, v3
	v_cmp_lt_f32_e64 s[0:1], 0, v4
	s_nop 1
	v_cndmask_b32_e64 v4, v5, v6, s[0:1]
	v_mul_f32_e32 v5, 0x37800000, v4
	v_cndmask_b32_e32 v4, v4, v5, vcc
	v_cmp_class_f32_e32 vcc, v3, v193
	s_nop 1
	v_cndmask_b32_e32 v3, v4, v3, vcc
	v_cmp_ngt_f32_e32 vcc, s23, v0
	s_nop 1
	v_cndmask_b32_e32 v0, 1.0, v3, vcc
	v_mul_f32_e32 v0, v1, v0
	v_mul_f32_e32 v0, v57, v0
	ds_write_b32 v73, v2 offset:4736
	ds_write_b32 v73, v0 offset:41600
	v_add_f32_e32 v0, v27, v36
	v_mul_f32_e32 v0, 0xbfb8aa3b, v0
	v_exp_f32_e32 v0, v0
	v_add_f32_e32 v1, v11, v38
	v_mul_f32_e32 v1, 0xbfb8aa3b, v1
	v_exp_f32_e32 v1, v1
	v_add_f32_e32 v0, 1.0, v0
	v_rcp_f32_e32 v0, v0
	v_add_f32_e32 v1, 1.0, v1
	v_rcp_f32_e32 v1, v1
	v_mul_f32_e32 v0, v0, v32
	v_mul_f32_e32 v2, 0x3fb8aa3b, v0
	v_add_f32_e32 v0, v0, v0
	v_mul_f32_e32 v3, 0x3fb8aa3b, v0
	v_rndne_f32_e32 v3, v3
	v_fmamk_f32 v4, v3, 0xbf317218, v0
	v_fmac_f32_e32 v4, 0x3102e308, v3
	v_fmamk_f32 v5, v4, 0x395133b1, v192
	v_cmp_eq_f32_e32 vcc, s20, v3
	v_cvt_i32_f32_e32 v3, v3
	v_fmaak_f32 v5, v4, v5, 0x3c0887f9
	v_fmaak_f32 v5, v4, v5, 0x3d2aaa81
	v_fmaak_f32 v5, v4, v5, 0x3e2aaaab
	v_fma_f32 v5, v4, v5, 0.5
	v_ldexp_f32 v3, 1.0, v3
	v_mul_f32_e32 v5, v4, v5
	v_cndmask_b32_e32 v3, v3, v202, vcc
	v_fmac_f32_e32 v4, v4, v5
	v_add_f32_e32 v5, -1.0, v3
	v_fmac_f32_e32 v5, v3, v4
	v_add_f32_e32 v3, v5, v5
	v_cndmask_b32_e32 v3, v5, v3, vcc
	v_cmp_nlt_f32_e32 vcc, s21, v0
	v_exp_f32_e32 v2, v2
	s_nop 0
	v_cndmask_b32_e64 v3, v201, -v3, vcc
	v_cmp_gt_f32_e32 vcc, s22, v3
	v_mul_f32_e32 v4, 0x4f800000, v3
	s_nop 0
	v_cndmask_b32_e32 v3, v3, v4, vcc
	v_sqrt_f32_e32 v4, v3
	s_nop 0
	v_add_u32_e32 v5, -1, v4
	v_fma_f32 v6, -v5, v4, v3
	v_cmp_ge_f32_e64 s[0:1], 0, v6
	v_add_u32_e32 v6, 1, v4
	s_nop 0
	v_cndmask_b32_e64 v5, v4, v5, s[0:1]
	v_fma_f32 v4, -v6, v4, v3
	v_cmp_lt_f32_e64 s[0:1], 0, v4
	s_nop 1
	v_cndmask_b32_e64 v4, v5, v6, s[0:1]
	v_mul_f32_e32 v5, 0x37800000, v4
	v_cndmask_b32_e32 v4, v4, v5, vcc
	v_cmp_class_f32_e32 vcc, v3, v193
	s_nop 1
	v_cndmask_b32_e32 v3, v4, v3, vcc
	v_cmp_ngt_f32_e32 vcc, s23, v0
	s_nop 1
	v_cndmask_b32_e32 v0, 1.0, v3, vcc
	v_mul_f32_e32 v0, v1, v0
	v_mul_f32_e32 v0, v43, v0
	ds_write_b32 v73, v2 offset:4992
	ds_write_b32 v73, v0 offset:41856
	v_add_f32_e32 v0, v28, v36
	v_mul_f32_e32 v0, 0xbfb8aa3b, v0
	v_exp_f32_e32 v0, v0
	v_add_f32_e32 v1, v12, v38
	v_mul_f32_e32 v1, 0xbfb8aa3b, v1
	v_exp_f32_e32 v1, v1
	v_add_f32_e32 v0, 1.0, v0
	v_rcp_f32_e32 v0, v0
	v_add_f32_e32 v1, 1.0, v1
	v_rcp_f32_e32 v1, v1
	v_mul_f32_e32 v0, v0, v32
	v_mul_f32_e32 v2, 0x3fb8aa3b, v0
	v_add_f32_e32 v0, v0, v0
	v_mul_f32_e32 v3, 0x3fb8aa3b, v0
	v_rndne_f32_e32 v3, v3
	v_fmamk_f32 v4, v3, 0xbf317218, v0
	v_fmac_f32_e32 v4, 0x3102e308, v3
	v_fmamk_f32 v5, v4, 0x395133b1, v192
	v_cmp_eq_f32_e32 vcc, s20, v3
	v_cvt_i32_f32_e32 v3, v3
	v_fmaak_f32 v5, v4, v5, 0x3c0887f9
	v_fmaak_f32 v5, v4, v5, 0x3d2aaa81
	v_fmaak_f32 v5, v4, v5, 0x3e2aaaab
	v_fma_f32 v5, v4, v5, 0.5
	v_ldexp_f32 v3, 1.0, v3
	v_mul_f32_e32 v5, v4, v5
	v_cndmask_b32_e32 v3, v3, v202, vcc
	v_fmac_f32_e32 v4, v4, v5
	v_add_f32_e32 v5, -1.0, v3
	v_fmac_f32_e32 v5, v3, v4
	v_add_f32_e32 v3, v5, v5
	v_cndmask_b32_e32 v3, v5, v3, vcc
	v_cmp_nlt_f32_e32 vcc, s21, v0
	v_exp_f32_e32 v2, v2
	s_nop 0
	v_cndmask_b32_e64 v3, v201, -v3, vcc
	v_cmp_gt_f32_e32 vcc, s22, v3
	v_mul_f32_e32 v4, 0x4f800000, v3
	s_nop 0
	v_cndmask_b32_e32 v3, v3, v4, vcc
	v_sqrt_f32_e32 v4, v3
	s_nop 0
	v_add_u32_e32 v5, -1, v4
	v_fma_f32 v6, -v5, v4, v3
	v_cmp_ge_f32_e64 s[0:1], 0, v6
	v_add_u32_e32 v6, 1, v4
	s_nop 0
	v_cndmask_b32_e64 v5, v4, v5, s[0:1]
	v_fma_f32 v4, -v6, v4, v3
	v_cmp_lt_f32_e64 s[0:1], 0, v4
	s_nop 1
	v_cndmask_b32_e64 v4, v5, v6, s[0:1]
	v_mul_f32_e32 v5, 0x37800000, v4
	v_cndmask_b32_e32 v4, v4, v5, vcc
	v_cmp_class_f32_e32 vcc, v3, v193
	s_nop 1
	v_cndmask_b32_e32 v3, v4, v3, vcc
	v_cmp_ngt_f32_e32 vcc, s23, v0
	s_nop 1
	v_cndmask_b32_e32 v0, 1.0, v3, vcc
	v_mul_f32_e32 v0, v1, v0
	v_mul_f32_e32 v0, v59, v0
	ds_write_b32 v73, v2 offset:6272
	ds_write_b32 v73, v0 offset:43136
	v_add_f32_e32 v0, v29, v36
	v_mul_f32_e32 v0, 0xbfb8aa3b, v0
	v_exp_f32_e32 v0, v0
	v_add_f32_e32 v1, v13, v38
	v_mul_f32_e32 v1, 0xbfb8aa3b, v1
	v_exp_f32_e32 v1, v1
	v_add_f32_e32 v0, 1.0, v0
	v_rcp_f32_e32 v0, v0
	v_add_f32_e32 v1, 1.0, v1
	v_rcp_f32_e32 v1, v1
	v_mul_f32_e32 v0, v0, v32
	v_mul_f32_e32 v2, 0x3fb8aa3b, v0
	v_add_f32_e32 v0, v0, v0
	v_mul_f32_e32 v3, 0x3fb8aa3b, v0
	v_rndne_f32_e32 v3, v3
	v_fmamk_f32 v4, v3, 0xbf317218, v0
	v_fmac_f32_e32 v4, 0x3102e308, v3
	v_fmamk_f32 v5, v4, 0x395133b1, v192
	v_cmp_eq_f32_e32 vcc, s20, v3
	v_cvt_i32_f32_e32 v3, v3
	v_fmaak_f32 v5, v4, v5, 0x3c0887f9
	v_fmaak_f32 v5, v4, v5, 0x3d2aaa81
	v_fmaak_f32 v5, v4, v5, 0x3e2aaaab
	v_fma_f32 v5, v4, v5, 0.5
	v_ldexp_f32 v3, 1.0, v3
	v_mul_f32_e32 v5, v4, v5
	v_cndmask_b32_e32 v3, v3, v202, vcc
	v_fmac_f32_e32 v4, v4, v5
	v_add_f32_e32 v5, -1.0, v3
	v_fmac_f32_e32 v5, v3, v4
	v_add_f32_e32 v3, v5, v5
	v_cndmask_b32_e32 v3, v5, v3, vcc
	v_cmp_nlt_f32_e32 vcc, s21, v0
	v_exp_f32_e32 v2, v2
	s_nop 0
	v_cndmask_b32_e64 v3, v201, -v3, vcc
	v_cmp_gt_f32_e32 vcc, s22, v3
	v_mul_f32_e32 v4, 0x4f800000, v3
	s_nop 0
	v_cndmask_b32_e32 v3, v3, v4, vcc
	v_sqrt_f32_e32 v4, v3
	s_nop 0
	v_add_u32_e32 v5, -1, v4
	v_fma_f32 v6, -v5, v4, v3
	v_cmp_ge_f32_e64 s[0:1], 0, v6
	v_add_u32_e32 v6, 1, v4
	s_nop 0
	v_cndmask_b32_e64 v5, v4, v5, s[0:1]
	v_fma_f32 v4, -v6, v4, v3
	v_cmp_lt_f32_e64 s[0:1], 0, v4
	s_nop 1
	v_cndmask_b32_e64 v4, v5, v6, s[0:1]
	v_mul_f32_e32 v5, 0x37800000, v4
	v_cndmask_b32_e32 v4, v4, v5, vcc
	v_cmp_class_f32_e32 vcc, v3, v193
	s_nop 1
	v_cndmask_b32_e32 v3, v4, v3, vcc
	v_cmp_ngt_f32_e32 vcc, s23, v0
	s_nop 1
	v_cndmask_b32_e32 v0, 1.0, v3, vcc
	v_mul_f32_e32 v0, v1, v0
	v_mul_f32_e32 v0, v45, v0
	ds_write_b32 v73, v2 offset:6528
	ds_write_b32 v73, v0 offset:43392
	v_add_f32_e32 v0, v30, v36
	v_mul_f32_e32 v0, 0xbfb8aa3b, v0
	v_exp_f32_e32 v0, v0
	v_add_f32_e32 v1, v14, v38
	v_mul_f32_e32 v1, 0xbfb8aa3b, v1
	v_exp_f32_e32 v1, v1
	v_add_f32_e32 v0, 1.0, v0
	v_rcp_f32_e32 v0, v0
	v_add_f32_e32 v1, 1.0, v1
	v_rcp_f32_e32 v1, v1
	v_mul_f32_e32 v0, v0, v32
	v_mul_f32_e32 v2, 0x3fb8aa3b, v0
	v_add_f32_e32 v0, v0, v0
	v_mul_f32_e32 v3, 0x3fb8aa3b, v0
	v_rndne_f32_e32 v3, v3
	v_fmamk_f32 v4, v3, 0xbf317218, v0
	v_fmac_f32_e32 v4, 0x3102e308, v3
	v_fmamk_f32 v5, v4, 0x395133b1, v192
	v_cmp_eq_f32_e32 vcc, s20, v3
	v_cvt_i32_f32_e32 v3, v3
	v_fmaak_f32 v5, v4, v5, 0x3c0887f9
	v_fmaak_f32 v5, v4, v5, 0x3d2aaa81
	v_fmaak_f32 v5, v4, v5, 0x3e2aaaab
	v_fma_f32 v5, v4, v5, 0.5
	v_ldexp_f32 v3, 1.0, v3
	v_mul_f32_e32 v5, v4, v5
	v_cndmask_b32_e32 v3, v3, v202, vcc
	v_fmac_f32_e32 v4, v4, v5
	v_add_f32_e32 v5, -1.0, v3
	v_fmac_f32_e32 v5, v3, v4
	v_add_f32_e32 v3, v5, v5
	v_cndmask_b32_e32 v3, v5, v3, vcc
	v_cmp_nlt_f32_e32 vcc, s21, v0
	v_exp_f32_e32 v2, v2
	s_nop 0
	v_cndmask_b32_e64 v3, v201, -v3, vcc
	v_cmp_gt_f32_e32 vcc, s22, v3
	v_mul_f32_e32 v4, 0x4f800000, v3
	s_nop 0
	v_cndmask_b32_e32 v3, v3, v4, vcc
	v_sqrt_f32_e32 v4, v3
	s_nop 0
	v_add_u32_e32 v5, -1, v4
	v_fma_f32 v6, -v5, v4, v3
	v_cmp_ge_f32_e64 s[0:1], 0, v6
	v_add_u32_e32 v6, 1, v4
	s_nop 0
	v_cndmask_b32_e64 v5, v4, v5, s[0:1]
	v_fma_f32 v4, -v6, v4, v3
	v_cmp_lt_f32_e64 s[0:1], 0, v4
	s_nop 1
	v_cndmask_b32_e64 v4, v5, v6, s[0:1]
	v_mul_f32_e32 v5, 0x37800000, v4
	v_cndmask_b32_e32 v4, v4, v5, vcc
	v_cmp_class_f32_e32 vcc, v3, v193
	s_nop 1
	v_cndmask_b32_e32 v3, v4, v3, vcc
	v_cmp_ngt_f32_e32 vcc, s23, v0
	s_nop 1
	v_cndmask_b32_e32 v0, 1.0, v3, vcc
	v_mul_f32_e32 v0, v1, v0
	v_mul_f32_e32 v0, v35, v0
	v_add_u32_e32 v1, 0x1800, v73
	ds_write2_b32 v1, v2, v34 offset0:160 offset1:192
	ds_write_b32 v73, v0 offset:43648
	v_add_f32_e32 v0, v31, v36
	v_mul_f32_e32 v0, 0xbfb8aa3b, v0
	v_exp_f32_e32 v0, v0
	v_add_f32_e32 v1, v15, v38
	v_mul_f32_e32 v1, 0xbfb8aa3b, v1
	v_exp_f32_e32 v1, v1
	v_add_f32_e32 v0, 1.0, v0
	v_rcp_f32_e32 v0, v0
	v_add_f32_e32 v1, 1.0, v1
	v_rcp_f32_e32 v1, v1
	v_mul_f32_e32 v0, v0, v32
	v_mul_f32_e32 v2, 0x3fb8aa3b, v0
	v_add_f32_e32 v0, v0, v0
	v_mul_f32_e32 v3, 0x3fb8aa3b, v0
	v_rndne_f32_e32 v3, v3
	v_fmamk_f32 v4, v3, 0xbf317218, v0
	v_fmac_f32_e32 v4, 0x3102e308, v3
	v_fmamk_f32 v5, v4, 0x395133b1, v192
	v_cmp_eq_f32_e32 vcc, s20, v3
	v_cvt_i32_f32_e32 v3, v3
	v_fmaak_f32 v5, v4, v5, 0x3c0887f9
	v_fmaak_f32 v5, v4, v5, 0x3d2aaa81
	v_fmaak_f32 v5, v4, v5, 0x3e2aaaab
	v_fma_f32 v5, v4, v5, 0.5
	v_ldexp_f32 v3, 1.0, v3
	v_mul_f32_e32 v5, v4, v5
	v_cndmask_b32_e32 v3, v3, v202, vcc
	v_fmac_f32_e32 v4, v4, v5
	v_add_f32_e32 v5, -1.0, v3
	v_fmac_f32_e32 v5, v3, v4
	v_add_f32_e32 v3, v5, v5
	v_cndmask_b32_e32 v3, v5, v3, vcc
	v_cmp_nlt_f32_e32 vcc, s21, v0
	v_exp_f32_e32 v2, v2
	s_nop 0
	v_cndmask_b32_e64 v3, v201, -v3, vcc
	v_cmp_gt_f32_e32 vcc, s22, v3
	v_mul_f32_e32 v4, 0x4f800000, v3
	s_nop 0
	v_cndmask_b32_e32 v3, v3, v4, vcc
	v_sqrt_f32_e32 v4, v3
	s_nop 0
	v_add_u32_e32 v5, -1, v4
	v_fma_f32 v6, -v5, v4, v3
	v_cmp_ge_f32_e64 s[0:1], 0, v6
	v_add_u32_e32 v6, 1, v4
	s_nop 0
	v_cndmask_b32_e64 v5, v4, v5, s[0:1]
	v_fma_f32 v4, -v6, v4, v3
	v_cmp_lt_f32_e64 s[0:1], 0, v4
	s_nop 1
	v_cndmask_b32_e64 v4, v5, v6, s[0:1]
	v_mul_f32_e32 v5, 0x37800000, v4
	v_cndmask_b32_e32 v4, v4, v5, vcc
	v_cmp_class_f32_e32 vcc, v3, v193
	s_nop 1
	v_cndmask_b32_e32 v3, v4, v3, vcc
	v_cmp_ngt_f32_e32 vcc, s23, v0
	s_nop 1
	v_cndmask_b32_e32 v0, 1.0, v3, vcc
	v_mul_f32_e32 v0, v1, v0
	v_mul_f32_e32 v0, v33, v0
	ds_write_b32 v73, v2 offset:7040
	ds_write_b32 v73, v0 offset:43904
	s_waitcnt lgkmcnt(0)
	s_barrier
	s_cbranch_scc1 .LBB0_866
	v_lshl_add_u64 v[0:1], v[64:65], 0, s[4:5]
	global_load_dwordx2 v[98:99], v[0:1], off
	s_cmp_eq_u32 s12, 1
	s_waitcnt vmcnt(0)
	v_fmac_f32_e32 v99, 0, v98
	s_cbranch_scc1 .LBB0_867
	v_add_co_u32_e32 v0, vcc, 0x1000, v0
	s_cmp_eq_u32 s12, 2
	s_nop 0
	v_addc_co_u32_e32 v1, vcc, 0, v1, vcc
	global_load_dwordx2 v[0:1], v[0:1], off
	s_waitcnt vmcnt(0)
	v_fmac_f32_e32 v1, v99, v0
	s_cbranch_scc1 .LBB0_865
	v_readlane_b32 s0, v248, 32
	s_mul_i32 s46, s11, 36
	s_add_i32 s0, s0, s75
	s_mov_b32 s47, s5
	s_sub_i32 s0, s0, s70
	s_lshl_b64 s[44:45], s[46:47], 12
	v_readlane_b32 s1, v249, 45
	s_add_u32 s44, s1, s44
	v_readlane_b32 s1, v249, 46
	v_add_lshl_u32 v96, s13, v141, 3
	s_addc_u32 s45, s1, s45
	v_lshl_add_u64 v[2:3], s[44:45], 0, v[96:97]
	s_mov_b64 s[8:9], 0x1000

.LBB0_908:
	v_add_u32_e32 v137, v135, v134
	ds_read_b128 v[146:149], v135 offset:18432
	ds_read_b128 v[150:153], v137
	s_add_i32 s0, s0, 32
	s_cmp_lt_u32 s0, 48
	s_waitcnt lgkmcnt(0)
	v_mfma_f32_32x32x16_bf16 v[48:63], v[150:153], v[146:149], v[48:63]
	ds_read_b128 v[146:149], v135 offset:23040
	s_waitcnt lgkmcnt(0)
	v_mfma_f32_32x32x16_bf16 v[16:31], v[150:153], v[146:149], v[16:31]
	ds_read_b128 v[146:149], v135 offset:27648
	s_waitcnt lgkmcnt(0)
	v_mfma_f32_32x32x16_bf16 v[32:47], v[150:153], v[146:149], v[32:47]
	ds_read_b128 v[146:149], v135 offset:32256
	ds_read_b128 v[154:157], v135 offset:18464
	s_waitcnt lgkmcnt(1)
	v_mfma_f32_32x32x16_bf16 v[0:15], v[150:153], v[146:149], v[0:15]
	ds_read_b128 v[146:149], v137 offset:32
	ds_read_b128 v[150:153], v135 offset:23072
	s_waitcnt lgkmcnt(0)
	v_mfma_f32_32x32x16_bf16 v[16:31], v[146:149], v[150:153], v[16:31]
	ds_read_b128 v[150:153], v135 offset:27680
	s_waitcnt lgkmcnt(0)
	v_mfma_f32_32x32x16_bf16 v[32:47], v[146:149], v[150:153], v[32:47]
	ds_read_b128 v[150:153], v135 offset:32288
	v_add_u32_e32 v135, 64, v135
	v_mfma_f32_32x32x16_bf16 v[48:63], v[146:149], v[154:157], v[48:63]
	s_waitcnt lgkmcnt(0)
	v_mfma_f32_32x32x16_bf16 v[0:15], v[146:149], v[150:153], v[0:15]
	s_cbranch_scc1 .LBB0_908
	s_cmp_gt_u32 s12, 1
	v_readlane_b32 s0, v248, 27
	s_cselect_b32 s2, 19, 1
	s_or_b32 s3, s13, s0
	v_lshlrev_b32_e32 v137, 11, v96
	v_or_b32_e32 v96, s3, v145
	v_readlane_b32 s16, v251, 20
	v_lshlrev_b64 v[134:135], 2, v[96:97]
	v_readlane_b32 s18, v251, 22
	v_readlane_b32 s19, v251, 23
	s_barrier
	s_nop 0
	v_lshl_add_u64 v[138:139], s[18:19], 0, v[134:135]
	v_readlane_b32 s100, v251, 16
	v_readlane_b32 s101, v251, 17
	s_nop 1
	v_lshl_add_u64 v[220:221], s[100:101], 0, v[134:135]
	v_readlane_b32 s100, v251, 20
	v_readlane_b32 s101, v251, 21
	s_nop 1
	v_lshl_add_u64 v[222:223], s[100:101], 0, v[134:135]
	global_load_dword v224, v[220:221], off
	global_load_dword v225, v[222:223], off
	global_load_dword v226, v[138:139], off offset:128
	global_load_dword v227, v[222:223], off offset:128
	global_load_dword v228, v[220:221], off offset:128
	global_load_dword v96, v[138:139], off
	s_mov_b32 s8, 0x3f2aaaab
	s_mov_b32 s9, 0x3f317218
	s_mov_b32 s10, 0x7f800000
	v_readlane_b32 s20, v251, 24
	s_mov_b32 s20, 0x33800000
	v_readlane_b32 s40, v251, 4
	v_readlane_b32 s52, v251, 16
	v_readlane_b32 s53, v251, 17
	v_readlane_b32 s17, v251, 21
	v_readlane_b32 s21, v251, 25
	s_mov_b32 s21, 0x43000000
	v_readlane_b32 s22, v251, 26
	s_mov_b32 s22, 0x42b17217
	v_readlane_b32 s23, v251, 27
	s_mov_b32 s23, 0xf800000
	v_readlane_b32 s24, v251, 28
	s_mov_b32 s24, 0xc1880000
	v_readlane_b32 s30, v251, 34
	v_readlane_b32 s31, v251, 35
	v_readlane_b32 s25, v251, 29
	v_readlane_b32 s27, v251, 31
	v_readlane_b32 s28, v251, 32
	v_readlane_b32 s29, v251, 33
	v_readlane_b32 s30, v248, 2
	s_cmp_eq_u32 s2, s12
	v_readlane_b32 s31, v248, 3
	s_mov_b32 s28, 0x4800000
	s_movk_i32 s29, 0x47ff
	s_mov_b32 s25, 0x85000
	v_readlane_b32 s27, v248, 10
	v_readlane_b32 s26, v251, 30
	v_readlane_b32 s41, v251, 5
	v_readlane_b32 s42, v251, 6
	v_readlane_b32 s43, v251, 7
	v_readlane_b32 s44, v251, 8
	v_readlane_b32 s45, v251, 9
	v_readlane_b32 s46, v251, 10
	v_readlane_b32 s47, v251, 11
	v_readlane_b32 s48, v251, 12
	v_readlane_b32 s49, v251, 13
	v_readlane_b32 s50, v251, 14
	v_readlane_b32 s51, v251, 15
	v_readlane_b32 s54, v251, 18
	v_readlane_b32 s55, v251, 19
	s_waitcnt vmcnt(0)
	v_mul_f32_e32 v96, 0xbfb8aa3b, v96
	v_exp_f32_e32 v96, v96
	s_nop 0
	v_add_f32_e32 v144, 1.0, v96
	v_add_f32_e32 v138, -1.0, v144
	v_sub_f32_e32 v139, v138, v144
	v_add_f32_e32 v139, 1.0, v139
	v_sub_f32_e32 v138, v96, v138
	v_add_f32_e32 v146, v138, v139
	v_frexp_mant_f32_e32 v138, v144
	v_cmp_gt_f32_e32 vcc, s8, v138
	v_cvt_f64_f32_e32 v[138:139], v144
	v_frexp_exp_i32_f64_e32 v138, v[138:139]
	v_subbrev_co_u32_e32 v152, vcc, 0, v138, vcc
	v_sub_u32_e32 v138, 0, v152
	v_ldexp_f32 v139, v144, v138
	v_add_f32_e32 v144, -1.0, v139
	v_add_f32_e32 v147, 1.0, v139
	v_ldexp_f32 v138, v146, v138
	v_add_f32_e32 v146, 1.0, v144
	v_add_f32_e32 v148, -1.0, v147
	v_sub_f32_e32 v146, v139, v146
	v_sub_f32_e32 v139, v139, v148
	v_add_f32_e32 v146, v138, v146
	v_add_f32_e32 v138, v138, v139
	v_add_f32_e32 v153, v147, v138
	v_rcp_f32_e32 v155, v153
	v_sub_f32_e32 v139, v153, v147
	v_sub_f32_e32 v154, v138, v139
	v_add_f32_e32 v139, v144, v146
	v_sub_f32_e32 v138, v139, v144
	v_mul_f32_e32 v156, v139, v155
	v_sub_f32_e32 v144, v146, v138
	v_mul_f32_e32 v146, v153, v156
	v_fma_f32 v148, v156, v153, -v146
	v_fmac_f32_e32 v148, v156, v154
	v_add_f32_e32 v138, v146, v148
	v_sub_f32_e32 v147, v139, v138
	v_pk_add_f32 v[150:151], v[138:139], v[146:147] neg_lo:[0,1] neg_hi:[0,1]
	v_mov_b32_e32 v149, v138
	v_pk_add_f32 v[138:139], v[150:151], v[148:149] neg_lo:[0,1] neg_hi:[0,1]
	v_cmp_neq_f32_e32 vcc, s10, v96
	v_add_f32_e32 v139, v144, v139
	v_add_f32_e32 v138, v138, v139
	v_add_f32_e32 v139, v147, v138
	v_mul_f32_e32 v144, v155, v139
	v_mul_f32_e32 v146, v153, v144
	v_fma_f32 v148, v144, v153, -v146
	v_fmac_f32_e32 v148, v144, v154
	v_sub_f32_e32 v147, v147, v139
	v_add_f32_e32 v153, v138, v147
	v_add_f32_e32 v138, v146, v148
	v_sub_f32_e32 v147, v139, v138
	v_pk_add_f32 v[150:151], v[138:139], v[146:147] neg_lo:[0,1] neg_hi:[0,1]
	v_mov_b32_e32 v149, v138
	v_pk_add_f32 v[138:139], v[150:151], v[148:149] neg_lo:[0,1] neg_hi:[0,1]
	v_add_f32_e32 v139, v153, v139
	v_add_f32_e32 v138, v138, v139
	v_add_f32_e32 v139, v156, v144
	v_add_f32_e32 v138, v147, v138
	v_sub_f32_e32 v146, v139, v156
	v_mul_f32_e32 v138, v155, v138
	v_sub_f32_e32 v144, v144, v146
	v_add_f32_e32 v144, v144, v138
	v_add_f32_e32 v146, v139, v144
	v_mul_f32_e32 v148, v146, v146
	v_fmamk_f32 v138, v148, 0x3e9b6dac, v191
	v_fmaak_f32 v169, v148, v138, 0x3f2aaada
	v_cvt_f32_i32_e32 v138, v152
	v_sub_f32_e32 v139, v146, v139
	v_sub_f32_e32 v139, v144, v139
	v_ldexp_f32 v144, v139, 1
	v_mul_f32_e32 v139, v146, v148
	v_pk_mul_f32 v[148:149], v[138:139], v[168:169]
	v_ldexp_f32 v147, v146, 1
	v_fma_f32 v146, v138, s9, -v148
	v_fmac_f32_e32 v146, 0xb102e308, v138
	v_pk_add_f32 v[138:139], v[148:149], v[146:147]
	v_mov_b32_e32 v150, v148
	v_sub_f32_e32 v147, v139, v147
	v_sub_f32_e32 v147, v149, v147
	v_add_f32_e32 v151, v144, v147
	v_pk_add_f32 v[148:149], v[138:139], v[148:149] neg_lo:[0,1] neg_hi:[0,1]
	v_pk_add_f32 v[152:153], v[138:139], v[150:151]
	v_mov_b32_e32 v147, v138
	v_mov_b32_e32 v149, v153
	v_pk_add_f32 v[154:155], v[146:147], v[148:149] neg_lo:[0,1] neg_hi:[0,1]
	v_pk_add_f32 v[146:147], v[146:147], v[148:149]
	v_mov_b32_e32 v150, v151
	v_pk_add_f32 v[148:149], v[146:147], v[138:139] op_sel:[1,0] op_sel_hi:[0,1] neg_lo:[0,1] neg_hi:[0,1]
	v_pk_add_f32 v[156:157], v[152:153], v[148:149] op_sel_hi:[1,0] neg_lo:[0,1] neg_hi:[0,1]
	v_mov_b32_e32 v152, v153
	v_mov_b32_e32 v153, v147
	v_pk_mov_b32 v[148:149], v[138:139], v[148:149] op_sel:[1,0]
	v_mov_b32_e32 v151, v138
	v_pk_add_f32 v[148:149], v[152:153], v[148:149] neg_lo:[0,1] neg_hi:[0,1]
	v_mov_b32_e32 v156, v154
	v_pk_add_f32 v[138:139], v[150:151], v[148:149] neg_lo:[0,1] neg_hi:[0,1]
	v_mov_b32_e32 v155, v147
	v_pk_add_f32 v[148:149], v[156:157], v[138:139]
	v_pk_add_f32 v[150:151], v[148:149], v[148:149] op_sel:[0,1] op_sel_hi:[1,0]
	v_pk_add_f32 v[146:147], v[146:147], v[150:151] op_sel:[1,0] op_sel_hi:[0,1]
	v_mov_b32_e32 v149, v146
	v_pk_add_f32 v[152:153], v[148:149], v[154:155] neg_lo:[0,1] neg_hi:[0,1]
	v_mov_b32_e32 v139, v150
	v_sub_f32_e32 v144, v148, v152
	v_pk_add_f32 v[138:139], v[138:139], v[152:153] neg_lo:[0,1] neg_hi:[0,1]
	v_sub_f32_e32 v144, v154, v144
	v_add_f32_e32 v138, v138, v144
	v_add_f32_e32 v138, v138, v139
	v_add_f32_e32 v138, v146, v138
	v_cndmask_b32_e32 v138, v199, v138, vcc
	v_cmp_ngt_f32_e32 vcc, -1.0, v96
	s_nop 1
	v_cndmask_b32_e32 v138, v200, v138, vcc
	v_cmp_neq_f32_e32 vcc, -1.0, v96
	s_nop 1
	v_cndmask_b32_e32 v138, v201, v138, vcc
	v_cmp_lt_f32_e64 vcc, |v96|, s20
	s_nop 1
	v_cndmask_b32_e32 v96, v138, v96, vcc
	v_lshl_add_u64 v[138:139], s[52:53], 0, v[134:135]
	v_mov_b32_e32 v147, v224
	v_lshl_add_u64 v[134:135], s[16:17], 0, v[134:135]
	v_mov_b32_e32 v146, v225
	v_mul_f32_e32 v96, 0xc1000000, v96
	v_add_f32_e32 v48, v48, v147
	v_mul_f32_e32 v48, 0xbfb8aa3b, v48
	v_exp_f32_e32 v48, v48
	v_add_f32_e32 v32, v32, v146
	v_mul_f32_e32 v32, 0xbfb8aa3b, v32
	v_exp_f32_e32 v32, v32
	v_add_f32_e32 v48, 1.0, v48
	v_rcp_f32_e32 v48, v48
	v_add_f32_e32 v33, v33, v146
	v_add_f32_e32 v32, 1.0, v32
	v_rcp_f32_e32 v32, v32
	v_mul_f32_e32 v48, v48, v96
	v_mul_f32_e32 v134, 0x3fb8aa3b, v48
	v_add_f32_e32 v48, v48, v48
	v_exp_f32_e32 v138, v134
	v_mul_f32_e32 v134, 0x3fb8aa3b, v48
	v_rndne_f32_e32 v134, v134
	v_fmamk_f32 v135, v134, 0xbf317218, v48
	v_fmac_f32_e32 v135, 0x3102e308, v134
	v_fmamk_f32 v139, v135, 0x395133b1, v192
	v_cmp_eq_f32_e32 vcc, s21, v134
	v_cvt_i32_f32_e32 v134, v134
	v_fmaak_f32 v139, v135, v139, 0x3c0887f9
	v_fmaak_f32 v139, v135, v139, 0x3d2aaa81
	v_fmaak_f32 v139, v135, v139, 0x3e2aaaab
	v_fma_f32 v139, v135, v139, 0.5
	v_ldexp_f32 v134, 1.0, v134
	v_mul_f32_e32 v139, v135, v139
	v_cndmask_b32_e32 v134, v134, v202, vcc
	v_fmac_f32_e32 v135, v135, v139
	v_add_f32_e32 v139, -1.0, v134
	v_fmac_f32_e32 v139, v134, v135
	v_add_f32_e32 v134, v139, v139
	v_cndmask_b32_e32 v134, v139, v134, vcc
	v_cmp_nlt_f32_e32 vcc, s22, v48
	v_mul_f32_e32 v33, 0xbfb8aa3b, v33
	v_exp_f32_e32 v33, v33
	v_cndmask_b32_e64 v134, v201, -v134, vcc
	v_cmp_gt_f32_e32 vcc, s23, v134
	v_mul_f32_e32 v135, 0x4f800000, v134
	v_add_f32_e32 v33, 1.0, v33
	v_cndmask_b32_e32 v134, v134, v135, vcc
	v_sqrt_f32_e32 v135, v134
	v_rcp_f32_e32 v33, v33
	v_add_f32_e32 v34, v34, v146
	v_mul_f32_e32 v34, 0xbfb8aa3b, v34
	v_add_u32_e32 v139, -1, v135
	v_fma_f32 v144, -v139, v135, v134
	v_cmp_ge_f32_e64 s[0:1], 0, v144
	v_add_u32_e32 v144, 1, v135
	v_exp_f32_e32 v34, v34
	v_cndmask_b32_e64 v139, v135, v139, s[0:1]
	v_fma_f32 v135, -v144, v135, v134
	v_cmp_lt_f32_e64 s[0:1], 0, v135
	v_add_f32_e32 v34, 1.0, v34
	v_rcp_f32_e32 v34, v34
	v_cndmask_b32_e64 v135, v139, v144, s[0:1]
	v_mul_f32_e32 v139, 0x37800000, v135
	v_cndmask_b32_e32 v135, v135, v139, vcc
	v_cmp_class_f32_e32 vcc, v134, v193
	s_nop 1
	v_cndmask_b32_e32 v134, v135, v134, vcc
	v_cmp_ngt_f32_e32 vcc, s24, v48
	s_nop 1
	v_cndmask_b32_e32 v48, 1.0, v134, vcc
	v_mul_f32_e32 v48, v32, v48
	v_and_b32_e32 v32, 0x100, v136
	v_or3_b32 v32, v137, v145, v32
	v_lshl_add_u32 v144, v32, 2, 0
	v_add_u32_e32 v32, 0x9000, v144
	ds_read2_b32 v[134:135], v32 offset1:32
	s_waitcnt lgkmcnt(0)
	v_mul_f32_e32 v48, v134, v48
	ds_write_b32 v144, v138
	ds_write_b32 v144, v48 offset:36864
	v_add_f32_e32 v48, v49, v147
	v_mul_f32_e32 v48, 0xbfb8aa3b, v48
	v_exp_f32_e32 v48, v48
	s_nop 0
	v_add_f32_e32 v48, 1.0, v48
	v_rcp_f32_e32 v48, v48
	s_nop 0
	v_mul_f32_e32 v48, v48, v96
	v_mul_f32_e32 v49, 0x3fb8aa3b, v48
	v_add_f32_e32 v48, v48, v48
	v_exp_f32_e32 v134, v49
	v_mul_f32_e32 v49, 0x3fb8aa3b, v48
	v_rndne_f32_e32 v49, v49
	v_fmamk_f32 v136, v49, 0xbf317218, v48
	v_fmac_f32_e32 v136, 0x3102e308, v49
	v_fmamk_f32 v137, v136, 0x395133b1, v192
	v_cmp_eq_f32_e32 vcc, s21, v49
	v_cvt_i32_f32_e32 v49, v49
	v_fmaak_f32 v137, v136, v137, 0x3c0887f9
	v_fmaak_f32 v137, v136, v137, 0x3d2aaa81
	v_fmaak_f32 v137, v136, v137, 0x3e2aaaab
	v_fma_f32 v137, v136, v137, 0.5
	v_ldexp_f32 v49, 1.0, v49
	v_mul_f32_e32 v137, v136, v137
	v_cndmask_b32_e32 v49, v49, v202, vcc
	v_fmac_f32_e32 v136, v136, v137
	v_add_f32_e32 v137, -1.0, v49
	v_fmac_f32_e32 v137, v49, v136
	v_add_f32_e32 v49, v137, v137
	v_cndmask_b32_e32 v49, v137, v49, vcc
	v_cmp_nlt_f32_e32 vcc, s22, v48
	s_nop 1
	v_cndmask_b32_e64 v49, v201, -v49, vcc
	v_cmp_gt_f32_e32 vcc, s23, v49
	v_mul_f32_e32 v136, 0x4f800000, v49
	s_nop 0
	v_cndmask_b32_e32 v49, v49, v136, vcc
	v_sqrt_f32_e32 v136, v49
	s_nop 0
	v_add_u32_e32 v137, -1, v136
	v_fma_f32 v138, -v137, v136, v49
	v_cmp_ge_f32_e64 s[0:1], 0, v138
	v_add_u32_e32 v138, 1, v136
	s_nop 0
	v_cndmask_b32_e64 v137, v136, v137, s[0:1]
	v_fma_f32 v136, -v138, v136, v49
	v_cmp_lt_f32_e64 s[0:1], 0, v136
	s_nop 1
	v_cndmask_b32_e64 v136, v137, v138, s[0:1]
	v_mul_f32_e32 v137, 0x37800000, v136
	v_cndmask_b32_e32 v136, v136, v137, vcc
	v_cmp_class_f32_e32 vcc, v49, v193
	s_nop 1
	v_cndmask_b32_e32 v49, v136, v49, vcc
	v_cmp_ngt_f32_e32 vcc, s24, v48
	s_nop 1
	v_cndmask_b32_e32 v48, 1.0, v49, vcc
	v_mul_f32_e32 v33, v33, v48
	ds_read2_b32 v[48:49], v32 offset0:64 offset1:96
	s_waitcnt lgkmcnt(0)
	v_mul_f32_e32 v33, v48, v33
	ds_write_b32 v144, v134 offset:256
	ds_write_b32 v144, v33 offset:37120
	v_add_f32_e32 v33, v50, v147
	v_mul_f32_e32 v33, 0xbfb8aa3b, v33
	v_exp_f32_e32 v33, v33
	s_nop 0
	v_add_f32_e32 v33, 1.0, v33
	v_rcp_f32_e32 v33, v33
	s_nop 0
	v_mul_f32_e32 v33, v33, v96
	v_mul_f32_e32 v48, 0x3fb8aa3b, v33
	v_add_f32_e32 v33, v33, v33
	v_mul_f32_e32 v50, 0x3fb8aa3b, v33
	v_rndne_f32_e32 v50, v50
	v_fmamk_f32 v134, v50, 0xbf317218, v33
	v_fmac_f32_e32 v134, 0x3102e308, v50
	v_fmamk_f32 v136, v134, 0x395133b1, v192
	v_cmp_eq_f32_e32 vcc, s21, v50
	v_cvt_i32_f32_e32 v50, v50
	v_fmaak_f32 v136, v134, v136, 0x3c0887f9
	v_fmaak_f32 v136, v134, v136, 0x3d2aaa81
	v_fmaak_f32 v136, v134, v136, 0x3e2aaaab
	v_fma_f32 v136, v134, v136, 0.5
	v_ldexp_f32 v50, 1.0, v50
	v_mul_f32_e32 v136, v134, v136
	v_cndmask_b32_e32 v50, v50, v202, vcc
	v_fmac_f32_e32 v134, v134, v136
	v_add_f32_e32 v136, -1.0, v50
	v_fmac_f32_e32 v136, v50, v134
	v_add_f32_e32 v50, v136, v136
	v_cndmask_b32_e32 v50, v136, v50, vcc
	v_cmp_nlt_f32_e32 vcc, s22, v33
	v_exp_f32_e32 v48, v48
	s_nop 0
	v_cndmask_b32_e64 v50, v201, -v50, vcc
	v_cmp_gt_f32_e32 vcc, s23, v50
	v_mul_f32_e32 v134, 0x4f800000, v50
	s_nop 0
	v_cndmask_b32_e32 v50, v50, v134, vcc
	v_sqrt_f32_e32 v134, v50
	s_nop 0
	v_add_u32_e32 v136, -1, v134
	v_fma_f32 v137, -v136, v134, v50
	v_cmp_ge_f32_e64 s[0:1], 0, v137
	v_add_u32_e32 v137, 1, v134
	s_nop 0
	v_cndmask_b32_e64 v136, v134, v136, s[0:1]
	v_fma_f32 v134, -v137, v134, v50
	v_cmp_lt_f32_e64 s[0:1], 0, v134
	s_nop 1
	v_cndmask_b32_e64 v134, v136, v137, s[0:1]
	v_mul_f32_e32 v136, 0x37800000, v134
	v_cndmask_b32_e32 v134, v134, v136, vcc
	ds_read2_b32 v[136:137], v32 offset0:128 offset1:160
	v_cmp_class_f32_e32 vcc, v50, v193
	s_nop 1
	v_cndmask_b32_e32 v50, v134, v50, vcc
	v_cmp_ngt_f32_e32 vcc, s24, v33
	s_nop 1
	v_cndmask_b32_e32 v33, 1.0, v50, vcc
	v_mul_f32_e32 v33, v34, v33
	s_waitcnt lgkmcnt(0)
	v_mul_f32_e32 v33, v136, v33
	ds_write_b32 v144, v48 offset:512
	ds_write_b32 v144, v33 offset:37376
	v_add_f32_e32 v33, v51, v147
	v_mul_f32_e32 v33, 0xbfb8aa3b, v33
	v_exp_f32_e32 v33, v33
	v_add_f32_e32 v34, v35, v146
	v_mul_f32_e32 v34, 0xbfb8aa3b, v34
	v_exp_f32_e32 v34, v34
	v_add_f32_e32 v33, 1.0, v33
	v_rcp_f32_e32 v33, v33
	v_add_f32_e32 v34, 1.0, v34
	v_rcp_f32_e32 v34, v34
	v_mul_f32_e32 v33, v33, v96
	v_mul_f32_e32 v35, 0x3fb8aa3b, v33
	v_add_f32_e32 v33, v33, v33
	v_mul_f32_e32 v48, 0x3fb8aa3b, v33
	v_rndne_f32_e32 v48, v48
	v_fmamk_f32 v50, v48, 0xbf317218, v33
	v_fmac_f32_e32 v50, 0x3102e308, v48
	v_fmamk_f32 v51, v50, 0x395133b1, v192
	v_cmp_eq_f32_e32 vcc, s21, v48
	v_cvt_i32_f32_e32 v48, v48
	v_fmaak_f32 v51, v50, v51, 0x3c0887f9
	v_fmaak_f32 v51, v50, v51, 0x3d2aaa81
	v_fmaak_f32 v51, v50, v51, 0x3e2aaaab
	v_fma_f32 v51, v50, v51, 0.5
	v_ldexp_f32 v48, 1.0, v48
	v_mul_f32_e32 v51, v50, v51
	v_cndmask_b32_e32 v48, v48, v202, vcc
	v_fmac_f32_e32 v50, v50, v51
	v_add_f32_e32 v51, -1.0, v48
	v_fmac_f32_e32 v51, v48, v50
	v_add_f32_e32 v48, v51, v51
	v_cndmask_b32_e32 v48, v51, v48, vcc
	v_cmp_nlt_f32_e32 vcc, s22, v33
	v_exp_f32_e32 v35, v35
	s_nop 0
	v_cndmask_b32_e64 v48, v201, -v48, vcc
	v_cmp_gt_f32_e32 vcc, s23, v48
	v_mul_f32_e32 v50, 0x4f800000, v48
	s_nop 0
	v_cndmask_b32_e32 v48, v48, v50, vcc
	v_sqrt_f32_e32 v50, v48
	s_nop 0
	v_add_u32_e32 v51, -1, v50
	v_fma_f32 v134, -v51, v50, v48
	v_cmp_ge_f32_e64 s[0:1], 0, v134
	v_add_u32_e32 v134, 1, v50
	s_nop 0
	v_cndmask_b32_e64 v51, v50, v51, s[0:1]
	v_fma_f32 v50, -v134, v50, v48
	v_cmp_lt_f32_e64 s[0:1], 0, v50
	s_nop 1
	v_cndmask_b32_e64 v50, v51, v134, s[0:1]
	v_mul_f32_e32 v51, 0x37800000, v50
	v_cndmask_b32_e32 v50, v50, v51, vcc
	v_cmp_class_f32_e32 vcc, v48, v193
	s_nop 1
	v_cndmask_b32_e32 v48, v50, v48, vcc
	ds_read2_b32 v[50:51], v32 offset0:192 offset1:224
	v_cmp_ngt_f32_e32 vcc, s24, v33
	s_nop 1
	v_cndmask_b32_e32 v33, 1.0, v48, vcc
	v_mul_f32_e32 v33, v34, v33
	s_waitcnt lgkmcnt(0)
	v_mul_f32_e32 v32, v50, v33
	ds_write_b32 v144, v35 offset:768
	ds_write_b32 v144, v32 offset:37632
	v_add_f32_e32 v32, v52, v147
	v_mul_f32_e32 v32, 0xbfb8aa3b, v32
	v_exp_f32_e32 v32, v32
	v_add_f32_e32 v33, v36, v146
	v_mul_f32_e32 v33, 0xbfb8aa3b, v33
	v_exp_f32_e32 v33, v33
	v_add_f32_e32 v32, 1.0, v32
	v_rcp_f32_e32 v32, v32
	v_add_f32_e32 v33, 1.0, v33
	v_rcp_f32_e32 v33, v33
	v_mul_f32_e32 v32, v32, v96
	v_mul_f32_e32 v34, 0x3fb8aa3b, v32
	v_add_f32_e32 v32, v32, v32
	v_mul_f32_e32 v35, 0x3fb8aa3b, v32
	v_rndne_f32_e32 v35, v35
	v_fmamk_f32 v36, v35, 0xbf317218, v32
	v_fmac_f32_e32 v36, 0x3102e308, v35
	v_fmamk_f32 v48, v36, 0x395133b1, v192
	v_cmp_eq_f32_e32 vcc, s21, v35
	v_cvt_i32_f32_e32 v35, v35
	v_fmaak_f32 v48, v36, v48, 0x3c0887f9
	v_fmaak_f32 v48, v36, v48, 0x3d2aaa81
	v_fmaak_f32 v48, v36, v48, 0x3e2aaaab
	v_fma_f32 v48, v36, v48, 0.5
	v_ldexp_f32 v35, 1.0, v35
	v_mul_f32_e32 v48, v36, v48
	v_cndmask_b32_e32 v35, v35, v202, vcc
	v_fmac_f32_e32 v36, v36, v48
	v_add_f32_e32 v48, -1.0, v35
	v_fmac_f32_e32 v48, v35, v36
	v_add_f32_e32 v35, v48, v48
	v_cndmask_b32_e32 v35, v48, v35, vcc
	v_cmp_nlt_f32_e32 vcc, s22, v32
	v_exp_f32_e32 v34, v34
	s_nop 0
	v_cndmask_b32_e64 v35, v201, -v35, vcc
	v_cmp_gt_f32_e32 vcc, s23, v35
	v_mul_f32_e32 v36, 0x4f800000, v35
	s_nop 0
	v_cndmask_b32_e32 v35, v35, v36, vcc
	v_sqrt_f32_e32 v36, v35
	s_nop 0
	v_add_u32_e32 v48, -1, v36
	v_fma_f32 v50, -v48, v36, v35
	v_cmp_ge_f32_e64 s[0:1], 0, v50
	v_add_u32_e32 v50, 1, v36
	s_nop 0
	v_cndmask_b32_e64 v48, v36, v48, s[0:1]
	v_fma_f32 v36, -v50, v36, v35
	v_cmp_lt_f32_e64 s[0:1], 0, v36
	s_nop 1
	v_cndmask_b32_e64 v36, v48, v50, s[0:1]
	v_mul_f32_e32 v48, 0x37800000, v36
	v_cndmask_b32_e32 v36, v36, v48, vcc
	v_cmp_class_f32_e32 vcc, v35, v193
	s_nop 1
	v_cndmask_b32_e32 v35, v36, v35, vcc
	v_cmp_ngt_f32_e32 vcc, s24, v32
	s_nop 1
	v_cndmask_b32_e32 v32, 1.0, v35, vcc
	v_mul_f32_e32 v33, v33, v32
	v_add_u32_e32 v32, 0x9800, v144
	ds_read2_b32 v[138:139], v32 offset1:32
	s_waitcnt lgkmcnt(0)
	v_mul_f32_e32 v33, v138, v33
	ds_write_b32 v144, v34 offset:2048
	ds_write_b32 v144, v33 offset:38912
	v_add_f32_e32 v33, v53, v147
	v_mul_f32_e32 v33, 0xbfb8aa3b, v33
	v_exp_f32_e32 v33, v33
	v_add_f32_e32 v34, v37, v146
	v_mul_f32_e32 v34, 0xbfb8aa3b, v34
	v_exp_f32_e32 v34, v34
	v_add_f32_e32 v33, 1.0, v33
	v_rcp_f32_e32 v33, v33
	v_add_f32_e32 v34, 1.0, v34
	v_rcp_f32_e32 v34, v34
	v_mul_f32_e32 v33, v33, v96
	v_mul_f32_e32 v35, 0x3fb8aa3b, v33
	v_add_f32_e32 v33, v33, v33
	v_mul_f32_e32 v36, 0x3fb8aa3b, v33
	v_rndne_f32_e32 v36, v36
	v_fmamk_f32 v37, v36, 0xbf317218, v33
	v_fmac_f32_e32 v37, 0x3102e308, v36
	v_fmamk_f32 v48, v37, 0x395133b1, v192
	v_cmp_eq_f32_e32 vcc, s21, v36
	v_cvt_i32_f32_e32 v36, v36
	v_fmaak_f32 v48, v37, v48, 0x3c0887f9
	v_fmaak_f32 v48, v37, v48, 0x3d2aaa81
	v_fmaak_f32 v48, v37, v48, 0x3e2aaaab
	v_fma_f32 v48, v37, v48, 0.5
	v_ldexp_f32 v36, 1.0, v36
	v_mul_f32_e32 v48, v37, v48
	v_cndmask_b32_e32 v36, v36, v202, vcc
	v_fmac_f32_e32 v37, v37, v48
	v_add_f32_e32 v48, -1.0, v36
	v_fmac_f32_e32 v48, v36, v37
	v_add_f32_e32 v36, v48, v48
	v_cndmask_b32_e32 v36, v48, v36, vcc
	v_cmp_nlt_f32_e32 vcc, s22, v33
	v_exp_f32_e32 v35, v35
	s_nop 0
	v_cndmask_b32_e64 v36, v201, -v36, vcc
	v_cmp_gt_f32_e32 vcc, s23, v36
	v_mul_f32_e32 v37, 0x4f800000, v36
	s_nop 0
	v_cndmask_b32_e32 v36, v36, v37, vcc
	v_sqrt_f32_e32 v37, v36
	s_nop 0
	v_add_u32_e32 v48, -1, v37
	v_fma_f32 v50, -v48, v37, v36
	v_cmp_ge_f32_e64 s[0:1], 0, v50
	v_add_u32_e32 v50, 1, v37
	s_nop 0
	v_cndmask_b32_e64 v48, v37, v48, s[0:1]
	v_fma_f32 v37, -v50, v37, v36
	v_cmp_lt_f32_e64 s[0:1], 0, v37
	s_nop 1
	v_cndmask_b32_e64 v37, v48, v50, s[0:1]
	v_mul_f32_e32 v48, 0x37800000, v37
	v_cndmask_b32_e32 v37, v37, v48, vcc
	v_cmp_class_f32_e32 vcc, v36, v193
	s_nop 1
	v_cndmask_b32_e32 v36, v37, v36, vcc
	v_cmp_ngt_f32_e32 vcc, s24, v33
	s_nop 1
	v_cndmask_b32_e32 v33, 1.0, v36, vcc
	ds_read2_b32 v[36:37], v32 offset0:64 offset1:96
	v_mul_f32_e32 v33, v34, v33
	v_add_f32_e32 v34, v38, v146
	v_mul_f32_e32 v34, 0xbfb8aa3b, v34
	v_exp_f32_e32 v34, v34
	s_waitcnt lgkmcnt(0)
	v_mul_f32_e32 v33, v36, v33
	ds_write_b32 v144, v35 offset:2304
	ds_write_b32 v144, v33 offset:39168
	v_add_f32_e32 v33, v54, v147
	v_mul_f32_e32 v33, 0xbfb8aa3b, v33
	v_exp_f32_e32 v33, v33
	v_add_f32_e32 v34, 1.0, v34
	v_rcp_f32_e32 v34, v34
	ds_read2_b32 v[52:53], v32 offset0:128 offset1:160
	v_add_f32_e32 v33, 1.0, v33
	v_rcp_f32_e32 v33, v33
	s_nop 0
	v_mul_f32_e32 v33, v33, v96
	v_mul_f32_e32 v35, 0x3fb8aa3b, v33
	v_add_f32_e32 v33, v33, v33
	v_mul_f32_e32 v36, 0x3fb8aa3b, v33
	v_rndne_f32_e32 v36, v36
	v_fmamk_f32 v38, v36, 0xbf317218, v33
	v_fmac_f32_e32 v38, 0x3102e308, v36
	v_fmamk_f32 v48, v38, 0x395133b1, v192
	v_cmp_eq_f32_e32 vcc, s21, v36
	v_cvt_i32_f32_e32 v36, v36
	v_fmaak_f32 v48, v38, v48, 0x3c0887f9
	v_fmaak_f32 v48, v38, v48, 0x3d2aaa81
	v_fmaak_f32 v48, v38, v48, 0x3e2aaaab
	v_fma_f32 v48, v38, v48, 0.5
	v_ldexp_f32 v36, 1.0, v36
	v_mul_f32_e32 v48, v38, v48
	v_cndmask_b32_e32 v36, v36, v202, vcc
	v_fmac_f32_e32 v38, v38, v48
	v_add_f32_e32 v48, -1.0, v36
	v_fmac_f32_e32 v48, v36, v38
	v_add_f32_e32 v36, v48, v48
	v_cndmask_b32_e32 v36, v48, v36, vcc
	v_cmp_nlt_f32_e32 vcc, s22, v33
	v_exp_f32_e32 v35, v35
	s_nop 0
	v_cndmask_b32_e64 v36, v201, -v36, vcc
	v_cmp_gt_f32_e32 vcc, s23, v36
	v_mul_f32_e32 v38, 0x4f800000, v36
	s_nop 0
	v_cndmask_b32_e32 v36, v36, v38, vcc
	v_sqrt_f32_e32 v38, v36
	s_nop 0
	v_add_u32_e32 v48, -1, v38
	v_fma_f32 v50, -v48, v38, v36
	v_cmp_ge_f32_e64 s[0:1], 0, v50
	v_add_u32_e32 v50, 1, v38
	s_nop 0
	v_cndmask_b32_e64 v48, v38, v48, s[0:1]
	v_fma_f32 v38, -v50, v38, v36
	v_cmp_lt_f32_e64 s[0:1], 0, v38
	s_nop 1
	v_cndmask_b32_e64 v38, v48, v50, s[0:1]
	v_mul_f32_e32 v48, 0x37800000, v38
	v_cndmask_b32_e32 v38, v38, v48, vcc
	v_cmp_class_f32_e32 vcc, v36, v193
	s_nop 1
	v_cndmask_b32_e32 v36, v38, v36, vcc
	v_cmp_ngt_f32_e32 vcc, s24, v33
	s_nop 1
	v_cndmask_b32_e32 v33, 1.0, v36, vcc
	v_mul_f32_e32 v33, v34, v33
	s_waitcnt lgkmcnt(0)
	v_mul_f32_e32 v33, v52, v33
	ds_write_b32 v144, v35 offset:2560
	ds_write_b32 v144, v33 offset:39424
	v_add_f32_e32 v33, v55, v147
	v_mul_f32_e32 v33, 0xbfb8aa3b, v33
	v_exp_f32_e32 v33, v33
	v_add_f32_e32 v34, v39, v146
	v_mul_f32_e32 v34, 0xbfb8aa3b, v34
	v_exp_f32_e32 v34, v34
	v_add_f32_e32 v33, 1.0, v33
	v_rcp_f32_e32 v33, v33
	v_add_f32_e32 v34, 1.0, v34
	v_rcp_f32_e32 v34, v34
	v_mul_f32_e32 v33, v33, v96
	v_mul_f32_e32 v35, 0x3fb8aa3b, v33
	v_add_f32_e32 v33, v33, v33
	v_mul_f32_e32 v36, 0x3fb8aa3b, v33
	v_rndne_f32_e32 v36, v36
	v_fmamk_f32 v38, v36, 0xbf317218, v33
	v_fmac_f32_e32 v38, 0x3102e308, v36
	v_fmamk_f32 v39, v38, 0x395133b1, v192
	v_cmp_eq_f32_e32 vcc, s21, v36
	v_cvt_i32_f32_e32 v36, v36
	v_fmaak_f32 v39, v38, v39, 0x3c0887f9
	v_fmaak_f32 v39, v38, v39, 0x3d2aaa81
	v_fmaak_f32 v39, v38, v39, 0x3e2aaaab
	v_fma_f32 v39, v38, v39, 0.5
	v_ldexp_f32 v36, 1.0, v36
	v_mul_f32_e32 v39, v38, v39
	v_cndmask_b32_e32 v36, v36, v202, vcc
	v_fmac_f32_e32 v38, v38, v39
	v_add_f32_e32 v39, -1.0, v36
	v_fmac_f32_e32 v39, v36, v38
	v_add_f32_e32 v36, v39, v39
	v_cndmask_b32_e32 v36, v39, v36, vcc
	v_cmp_nlt_f32_e32 vcc, s22, v33
	v_exp_f32_e32 v35, v35
	s_nop 0
	v_cndmask_b32_e64 v36, v201, -v36, vcc
	v_cmp_gt_f32_e32 vcc, s23, v36
	v_mul_f32_e32 v38, 0x4f800000, v36
	s_nop 0
	v_cndmask_b32_e32 v36, v36, v38, vcc
	v_sqrt_f32_e32 v38, v36
	s_nop 0
	v_add_u32_e32 v39, -1, v38
	v_fma_f32 v48, -v39, v38, v36
	v_cmp_ge_f32_e64 s[0:1], 0, v48
	v_add_u32_e32 v48, 1, v38
	s_nop 0
	v_cndmask_b32_e64 v39, v38, v39, s[0:1]
	v_fma_f32 v38, -v48, v38, v36
	v_cmp_lt_f32_e64 s[0:1], 0, v38
	s_nop 1
	v_cndmask_b32_e64 v38, v39, v48, s[0:1]
	v_mul_f32_e32 v39, 0x37800000, v38
	v_cndmask_b32_e32 v38, v38, v39, vcc
	v_cmp_class_f32_e32 vcc, v36, v193
	s_nop 1
	v_cndmask_b32_e32 v36, v38, v36, vcc
	ds_read2_b32 v[38:39], v32 offset0:192 offset1:224
	v_cmp_ngt_f32_e32 vcc, s24, v33
	s_nop 1
	v_cndmask_b32_e32 v33, 1.0, v36, vcc
	v_mul_f32_e32 v33, v34, v33
	s_waitcnt lgkmcnt(0)
	v_mul_f32_e32 v32, v38, v33
	ds_write_b32 v144, v35 offset:2816
	ds_write_b32 v144, v32 offset:39680
	v_add_f32_e32 v32, v56, v147
	v_mul_f32_e32 v32, 0xbfb8aa3b, v32
	v_exp_f32_e32 v32, v32
	v_add_f32_e32 v33, v40, v146
	v_mul_f32_e32 v33, 0xbfb8aa3b, v33
	v_exp_f32_e32 v33, v33
	v_add_f32_e32 v32, 1.0, v32
	v_rcp_f32_e32 v32, v32
	v_add_f32_e32 v33, 1.0, v33
	v_rcp_f32_e32 v33, v33
	v_mul_f32_e32 v32, v32, v96
	v_mul_f32_e32 v34, 0x3fb8aa3b, v32
	v_add_f32_e32 v32, v32, v32
	v_mul_f32_e32 v35, 0x3fb8aa3b, v32
	v_rndne_f32_e32 v35, v35
	v_fmamk_f32 v36, v35, 0xbf317218, v32
	v_fmac_f32_e32 v36, 0x3102e308, v35
	v_fmamk_f32 v38, v36, 0x395133b1, v192
	v_cmp_eq_f32_e32 vcc, s21, v35
	v_cvt_i32_f32_e32 v35, v35
	v_fmaak_f32 v38, v36, v38, 0x3c0887f9
	v_fmaak_f32 v38, v36, v38, 0x3d2aaa81
	v_fmaak_f32 v38, v36, v38, 0x3e2aaaab
	v_fma_f32 v38, v36, v38, 0.5
	v_ldexp_f32 v35, 1.0, v35
	v_mul_f32_e32 v38, v36, v38
	v_cndmask_b32_e32 v35, v35, v202, vcc
	v_fmac_f32_e32 v36, v36, v38
	v_add_f32_e32 v38, -1.0, v35
	v_fmac_f32_e32 v38, v35, v36
	v_add_f32_e32 v35, v38, v38
	v_cndmask_b32_e32 v35, v38, v35, vcc
	v_cmp_nlt_f32_e32 vcc, s22, v32
	v_exp_f32_e32 v34, v34
	s_nop 0
	v_cndmask_b32_e64 v35, v201, -v35, vcc
	v_cmp_gt_f32_e32 vcc, s23, v35
	v_mul_f32_e32 v36, 0x4f800000, v35
	s_nop 0
	v_cndmask_b32_e32 v35, v35, v36, vcc
	v_sqrt_f32_e32 v36, v35
	s_nop 0
	v_add_u32_e32 v38, -1, v36
	v_fma_f32 v40, -v38, v36, v35
	v_cmp_ge_f32_e64 s[0:1], 0, v40
	v_add_u32_e32 v40, 1, v36
	s_nop 0
	v_cndmask_b32_e64 v38, v36, v38, s[0:1]
	v_fma_f32 v36, -v40, v36, v35
	v_cmp_lt_f32_e64 s[0:1], 0, v36
	s_nop 1
	v_cndmask_b32_e64 v36, v38, v40, s[0:1]
	v_mul_f32_e32 v38, 0x37800000, v36
	v_cndmask_b32_e32 v36, v36, v38, vcc
	v_cmp_class_f32_e32 vcc, v35, v193
	s_nop 1
	v_cndmask_b32_e32 v35, v36, v35, vcc
	v_cmp_ngt_f32_e32 vcc, s24, v32
	s_nop 1
	v_cndmask_b32_e32 v32, 1.0, v35, vcc
	v_mul_f32_e32 v33, v33, v32
	v_add_u32_e32 v32, 0xa000, v144
	ds_read2_b32 v[54:55], v32 offset1:32
	s_waitcnt lgkmcnt(0)
	v_mul_f32_e32 v33, v54, v33
	ds_write_b32 v144, v34 offset:4096
	ds_write_b32 v144, v33 offset:40960
	v_add_f32_e32 v33, v57, v147
	v_mul_f32_e32 v33, 0xbfb8aa3b, v33
	v_exp_f32_e32 v33, v33
	v_add_f32_e32 v34, v41, v146
	v_mul_f32_e32 v34, 0xbfb8aa3b, v34
	v_exp_f32_e32 v34, v34
	v_add_f32_e32 v33, 1.0, v33
	v_rcp_f32_e32 v33, v33
	v_add_f32_e32 v34, 1.0, v34
	v_rcp_f32_e32 v34, v34
	v_mul_f32_e32 v33, v33, v96
	v_mul_f32_e32 v35, 0x3fb8aa3b, v33
	v_add_f32_e32 v33, v33, v33
	v_mul_f32_e32 v36, 0x3fb8aa3b, v33
	v_rndne_f32_e32 v36, v36
	v_fmamk_f32 v38, v36, 0xbf317218, v33
	v_fmac_f32_e32 v38, 0x3102e308, v36
	v_fmamk_f32 v40, v38, 0x395133b1, v192
	v_cmp_eq_f32_e32 vcc, s21, v36
	v_cvt_i32_f32_e32 v36, v36
	v_fmaak_f32 v40, v38, v40, 0x3c0887f9
	v_fmaak_f32 v40, v38, v40, 0x3d2aaa81
	v_fmaak_f32 v40, v38, v40, 0x3e2aaaab
	v_fma_f32 v40, v38, v40, 0.5
	v_ldexp_f32 v36, 1.0, v36
	v_mul_f32_e32 v40, v38, v40
	v_cndmask_b32_e32 v36, v36, v202, vcc
	v_fmac_f32_e32 v38, v38, v40
	v_add_f32_e32 v40, -1.0, v36
	v_fmac_f32_e32 v40, v36, v38
	v_add_f32_e32 v36, v40, v40
	v_cndmask_b32_e32 v36, v40, v36, vcc
	v_cmp_nlt_f32_e32 vcc, s22, v33
	v_exp_f32_e32 v35, v35
	s_nop 0
	v_cndmask_b32_e64 v36, v201, -v36, vcc
	v_cmp_gt_f32_e32 vcc, s23, v36
	v_mul_f32_e32 v38, 0x4f800000, v36
	s_nop 0
	v_cndmask_b32_e32 v36, v36, v38, vcc
	v_sqrt_f32_e32 v38, v36
	s_nop 0
	v_add_u32_e32 v40, -1, v38
	v_fma_f32 v41, -v40, v38, v36
	v_cmp_ge_f32_e64 s[0:1], 0, v41
	v_add_u32_e32 v41, 1, v38
	s_nop 0
	v_cndmask_b32_e64 v40, v38, v40, s[0:1]
	v_fma_f32 v38, -v41, v38, v36
	v_cmp_lt_f32_e64 s[0:1], 0, v38
	s_nop 1
	v_cndmask_b32_e64 v38, v40, v41, s[0:1]
	v_mul_f32_e32 v40, 0x37800000, v38
	v_cndmask_b32_e32 v38, v38, v40, vcc
	ds_read2_b32 v[40:41], v32 offset0:64 offset1:96
	v_cmp_class_f32_e32 vcc, v36, v193
	s_nop 1
	v_cndmask_b32_e32 v36, v38, v36, vcc
	v_cmp_ngt_f32_e32 vcc, s24, v33
	s_nop 1
	v_cndmask_b32_e32 v33, 1.0, v36, vcc
	v_mul_f32_e32 v33, v34, v33
	s_waitcnt lgkmcnt(0)
	v_mul_f32_e32 v33, v40, v33
	ds_write_b32 v144, v35 offset:4352
	ds_write_b32 v144, v33 offset:41216
	v_add_f32_e32 v33, v58, v147
	v_mul_f32_e32 v33, 0xbfb8aa3b, v33
	v_exp_f32_e32 v33, v33
	v_add_f32_e32 v34, v42, v146
	v_mul_f32_e32 v34, 0xbfb8aa3b, v34
	v_exp_f32_e32 v34, v34
	v_add_f32_e32 v33, 1.0, v33
	v_rcp_f32_e32 v33, v33
	ds_read2_b32 v[56:57], v32 offset0:128 offset1:160
	v_add_f32_e32 v34, 1.0, v34
	v_rcp_f32_e32 v34, v34
	v_mul_f32_e32 v33, v33, v96
	v_mul_f32_e32 v35, 0x3fb8aa3b, v33
	v_add_f32_e32 v33, v33, v33
	v_mul_f32_e32 v36, 0x3fb8aa3b, v33
	v_rndne_f32_e32 v36, v36
	v_fmamk_f32 v38, v36, 0xbf317218, v33
	v_fmac_f32_e32 v38, 0x3102e308, v36
	v_fmamk_f32 v40, v38, 0x395133b1, v192
	v_cmp_eq_f32_e32 vcc, s21, v36
	v_cvt_i32_f32_e32 v36, v36
	v_fmaak_f32 v40, v38, v40, 0x3c0887f9
	v_fmaak_f32 v40, v38, v40, 0x3d2aaa81
	v_fmaak_f32 v40, v38, v40, 0x3e2aaaab
	v_fma_f32 v40, v38, v40, 0.5
	v_ldexp_f32 v36, 1.0, v36
	v_mul_f32_e32 v40, v38, v40
	v_cndmask_b32_e32 v36, v36, v202, vcc
	v_fmac_f32_e32 v38, v38, v40
	v_add_f32_e32 v40, -1.0, v36
	v_fmac_f32_e32 v40, v36, v38
	v_add_f32_e32 v36, v40, v40
	v_cndmask_b32_e32 v36, v40, v36, vcc
	v_cmp_nlt_f32_e32 vcc, s22, v33
	v_exp_f32_e32 v35, v35
	s_nop 0
	v_cndmask_b32_e64 v36, v201, -v36, vcc
	v_cmp_gt_f32_e32 vcc, s23, v36
	v_mul_f32_e32 v38, 0x4f800000, v36
	s_nop 0
	v_cndmask_b32_e32 v36, v36, v38, vcc
	v_sqrt_f32_e32 v38, v36
	s_nop 0
	v_add_u32_e32 v40, -1, v38
	v_fma_f32 v42, -v40, v38, v36
	v_cmp_ge_f32_e64 s[0:1], 0, v42
	v_add_u32_e32 v42, 1, v38
	s_nop 0
	v_cndmask_b32_e64 v40, v38, v40, s[0:1]
	v_fma_f32 v38, -v42, v38, v36
	v_cmp_lt_f32_e64 s[0:1], 0, v38
	s_nop 1
	v_cndmask_b32_e64 v38, v40, v42, s[0:1]
	v_mul_f32_e32 v40, 0x37800000, v38
	v_cndmask_b32_e32 v38, v38, v40, vcc
	v_cmp_class_f32_e32 vcc, v36, v193
	s_nop 1
	v_cndmask_b32_e32 v36, v38, v36, vcc
	v_cmp_ngt_f32_e32 vcc, s24, v33
	s_nop 1
	v_cndmask_b32_e32 v33, 1.0, v36, vcc
	v_mul_f32_e32 v33, v34, v33
	s_waitcnt lgkmcnt(0)
	v_mul_f32_e32 v33, v56, v33
	ds_write_b32 v144, v35 offset:4608
	ds_write_b32 v144, v33 offset:41472
	v_add_f32_e32 v33, v59, v147
	v_mul_f32_e32 v33, 0xbfb8aa3b, v33
	v_exp_f32_e32 v33, v33
	v_add_f32_e32 v34, v43, v146
	v_mul_f32_e32 v34, 0xbfb8aa3b, v34
	v_exp_f32_e32 v34, v34
	v_add_f32_e32 v33, 1.0, v33
	v_rcp_f32_e32 v33, v33
	v_add_f32_e32 v34, 1.0, v34
	v_rcp_f32_e32 v34, v34
	v_mul_f32_e32 v33, v33, v96
	v_mul_f32_e32 v35, 0x3fb8aa3b, v33
	v_add_f32_e32 v33, v33, v33
	v_mul_f32_e32 v36, 0x3fb8aa3b, v33
	v_rndne_f32_e32 v36, v36
	v_fmamk_f32 v38, v36, 0xbf317218, v33
	v_fmac_f32_e32 v38, 0x3102e308, v36
	v_fmamk_f32 v40, v38, 0x395133b1, v192
	v_cmp_eq_f32_e32 vcc, s21, v36
	v_cvt_i32_f32_e32 v36, v36
	v_fmaak_f32 v40, v38, v40, 0x3c0887f9
	v_fmaak_f32 v40, v38, v40, 0x3d2aaa81
	v_fmaak_f32 v40, v38, v40, 0x3e2aaaab
	v_fma_f32 v40, v38, v40, 0.5
	v_ldexp_f32 v36, 1.0, v36
	v_mul_f32_e32 v40, v38, v40
	v_cndmask_b32_e32 v36, v36, v202, vcc
	v_fmac_f32_e32 v38, v38, v40
	v_add_f32_e32 v40, -1.0, v36
	v_fmac_f32_e32 v40, v36, v38
	v_add_f32_e32 v36, v40, v40
	v_cndmask_b32_e32 v36, v40, v36, vcc
	v_cmp_nlt_f32_e32 vcc, s22, v33
	v_exp_f32_e32 v35, v35
	s_nop 0
	v_cndmask_b32_e64 v36, v201, -v36, vcc
	v_cmp_gt_f32_e32 vcc, s23, v36
	v_mul_f32_e32 v38, 0x4f800000, v36
	s_nop 0
	v_cndmask_b32_e32 v36, v36, v38, vcc
	v_sqrt_f32_e32 v38, v36
	s_nop 0
	v_add_u32_e32 v40, -1, v38
	v_fma_f32 v42, -v40, v38, v36
	v_cmp_ge_f32_e64 s[0:1], 0, v42
	v_add_u32_e32 v42, 1, v38
	s_nop 0
	v_cndmask_b32_e64 v40, v38, v40, s[0:1]
	v_fma_f32 v38, -v42, v38, v36
	v_cmp_lt_f32_e64 s[0:1], 0, v38
	s_nop 1
	v_cndmask_b32_e64 v38, v40, v42, s[0:1]
	v_mul_f32_e32 v40, 0x37800000, v38
	ds_read2_b32 v[42:43], v32 offset0:192 offset1:224
	v_cndmask_b32_e32 v38, v38, v40, vcc
	v_cmp_class_f32_e32 vcc, v36, v193
	s_nop 1
	v_cndmask_b32_e32 v36, v38, v36, vcc
	v_cmp_ngt_f32_e32 vcc, s24, v33
	s_nop 1
	v_cndmask_b32_e32 v33, 1.0, v36, vcc
	v_mul_f32_e32 v33, v34, v33
	s_waitcnt lgkmcnt(0)
	v_mul_f32_e32 v32, v42, v33
	ds_write_b32 v144, v35 offset:4864
	ds_write_b32 v144, v32 offset:41728
	v_add_f32_e32 v32, v60, v147
	v_mul_f32_e32 v32, 0xbfb8aa3b, v32
	v_exp_f32_e32 v32, v32
	v_add_f32_e32 v33, v44, v146
	v_mul_f32_e32 v33, 0xbfb8aa3b, v33
	v_exp_f32_e32 v33, v33
	v_add_f32_e32 v32, 1.0, v32
	v_rcp_f32_e32 v32, v32
	v_add_f32_e32 v33, 1.0, v33
	v_rcp_f32_e32 v33, v33
	v_mul_f32_e32 v32, v32, v96
	v_mul_f32_e32 v34, 0x3fb8aa3b, v32
	v_add_f32_e32 v32, v32, v32
	v_mul_f32_e32 v35, 0x3fb8aa3b, v32
	v_rndne_f32_e32 v35, v35
	v_fmamk_f32 v36, v35, 0xbf317218, v32
	v_fmac_f32_e32 v36, 0x3102e308, v35
	v_fmamk_f32 v38, v36, 0x395133b1, v192
	v_cmp_eq_f32_e32 vcc, s21, v35
	v_cvt_i32_f32_e32 v35, v35
	v_fmaak_f32 v38, v36, v38, 0x3c0887f9
	v_fmaak_f32 v38, v36, v38, 0x3d2aaa81
	v_fmaak_f32 v38, v36, v38, 0x3e2aaaab
	v_fma_f32 v38, v36, v38, 0.5
	v_ldexp_f32 v35, 1.0, v35
	v_mul_f32_e32 v38, v36, v38
	v_cndmask_b32_e32 v35, v35, v202, vcc
	v_fmac_f32_e32 v36, v36, v38
	v_add_f32_e32 v38, -1.0, v35
	v_fmac_f32_e32 v38, v35, v36
	v_add_f32_e32 v35, v38, v38
	v_cndmask_b32_e32 v35, v38, v35, vcc
	v_cmp_nlt_f32_e32 vcc, s22, v32
	v_exp_f32_e32 v34, v34
	s_nop 0
	v_cndmask_b32_e64 v35, v201, -v35, vcc
	v_cmp_gt_f32_e32 vcc, s23, v35
	v_mul_f32_e32 v36, 0x4f800000, v35
	s_nop 0
	v_cndmask_b32_e32 v35, v35, v36, vcc
	v_sqrt_f32_e32 v36, v35
	s_nop 0
	v_add_u32_e32 v38, -1, v36
	v_fma_f32 v40, -v38, v36, v35
	v_cmp_ge_f32_e64 s[0:1], 0, v40
	v_add_u32_e32 v40, 1, v36
	s_nop 0
	v_cndmask_b32_e64 v38, v36, v38, s[0:1]
	v_fma_f32 v36, -v40, v36, v35
	v_cmp_lt_f32_e64 s[0:1], 0, v36
	s_nop 1
	v_cndmask_b32_e64 v36, v38, v40, s[0:1]
	v_mul_f32_e32 v38, 0x37800000, v36
	v_cndmask_b32_e32 v36, v36, v38, vcc
	v_cmp_class_f32_e32 vcc, v35, v193
	s_nop 1
	v_cndmask_b32_e32 v35, v36, v35, vcc
	v_cmp_ngt_f32_e32 vcc, s24, v32
	s_nop 1
	v_cndmask_b32_e32 v32, 1.0, v35, vcc
	v_mul_f32_e32 v32, v33, v32
	v_add_u32_e32 v33, 0xa800, v144
	ds_read2_b32 v[58:59], v33 offset1:32
	s_waitcnt lgkmcnt(0)
	v_mul_f32_e32 v32, v58, v32
	ds_write_b32 v144, v34 offset:6144
	ds_write_b32 v144, v32 offset:43008
	v_add_f32_e32 v32, v61, v147
	v_mul_f32_e32 v32, 0xbfb8aa3b, v32
	v_exp_f32_e32 v32, v32
	v_add_f32_e32 v34, v45, v146
	v_mul_f32_e32 v34, 0xbfb8aa3b, v34
	v_exp_f32_e32 v34, v34
	v_add_f32_e32 v32, 1.0, v32
	v_rcp_f32_e32 v32, v32
	ds_read2_b32 v[44:45], v33 offset0:64 offset1:96
	v_add_f32_e32 v34, 1.0, v34
	v_rcp_f32_e32 v34, v34
	v_mul_f32_e32 v32, v32, v96
	v_mul_f32_e32 v35, 0x3fb8aa3b, v32
	v_add_f32_e32 v32, v32, v32
	v_mul_f32_e32 v36, 0x3fb8aa3b, v32
	v_rndne_f32_e32 v36, v36
	v_fmamk_f32 v38, v36, 0xbf317218, v32
	v_fmac_f32_e32 v38, 0x3102e308, v36
	v_fmamk_f32 v40, v38, 0x395133b1, v192
	v_cmp_eq_f32_e32 vcc, s21, v36
	v_cvt_i32_f32_e32 v36, v36
	v_fmaak_f32 v40, v38, v40, 0x3c0887f9
	v_fmaak_f32 v40, v38, v40, 0x3d2aaa81
	v_fmaak_f32 v40, v38, v40, 0x3e2aaaab
	v_fma_f32 v40, v38, v40, 0.5
	v_ldexp_f32 v36, 1.0, v36
	v_mul_f32_e32 v40, v38, v40
	v_cndmask_b32_e32 v36, v36, v202, vcc
	v_fmac_f32_e32 v38, v38, v40
	v_add_f32_e32 v40, -1.0, v36
	v_fmac_f32_e32 v40, v36, v38
	v_add_f32_e32 v36, v40, v40
	v_cndmask_b32_e32 v36, v40, v36, vcc
	v_cmp_nlt_f32_e32 vcc, s22, v32
	v_exp_f32_e32 v35, v35
	s_nop 0
	v_cndmask_b32_e64 v36, v201, -v36, vcc
	v_cmp_gt_f32_e32 vcc, s23, v36
	v_mul_f32_e32 v38, 0x4f800000, v36
	s_nop 0
	v_cndmask_b32_e32 v36, v36, v38, vcc
	v_sqrt_f32_e32 v38, v36
	s_nop 0
	v_add_u32_e32 v40, -1, v38
	v_fma_f32 v42, -v40, v38, v36
	v_cmp_ge_f32_e64 s[0:1], 0, v42
	v_add_u32_e32 v42, 1, v38
	s_nop 0
	v_cndmask_b32_e64 v40, v38, v40, s[0:1]
	v_fma_f32 v38, -v42, v38, v36
	v_cmp_lt_f32_e64 s[0:1], 0, v38
	s_nop 1
	v_cndmask_b32_e64 v38, v40, v42, s[0:1]
	v_mul_f32_e32 v40, 0x37800000, v38
	v_cndmask_b32_e32 v38, v38, v40, vcc
	v_cmp_class_f32_e32 vcc, v36, v193
	s_nop 1
	v_cndmask_b32_e32 v36, v38, v36, vcc
	v_cmp_ngt_f32_e32 vcc, s24, v32
	s_nop 1
	v_cndmask_b32_e32 v32, 1.0, v36, vcc
	v_mul_f32_e32 v32, v34, v32
	s_waitcnt lgkmcnt(0)
	v_mul_f32_e32 v32, v44, v32
	ds_write_b32 v144, v35 offset:6400
	ds_write_b32 v144, v32 offset:43264
	v_add_f32_e32 v32, v62, v147
	v_mul_f32_e32 v32, 0xbfb8aa3b, v32
	v_exp_f32_e32 v32, v32
	v_add_f32_e32 v34, v46, v146
	v_mul_f32_e32 v34, 0xbfb8aa3b, v34
	v_exp_f32_e32 v34, v34
	v_add_f32_e32 v32, 1.0, v32
	v_rcp_f32_e32 v32, v32
	v_add_f32_e32 v34, 1.0, v34
	v_rcp_f32_e32 v34, v34
	v_mul_f32_e32 v32, v32, v96
	v_mul_f32_e32 v35, 0x3fb8aa3b, v32
	v_add_f32_e32 v32, v32, v32
	v_exp_f32_e32 v36, v35
	v_mul_f32_e32 v35, 0x3fb8aa3b, v32
	v_rndne_f32_e32 v35, v35
	v_fmamk_f32 v38, v35, 0xbf317218, v32
	v_fmac_f32_e32 v38, 0x3102e308, v35
	v_fmamk_f32 v40, v38, 0x395133b1, v192
	v_cmp_eq_f32_e32 vcc, s21, v35
	v_cvt_i32_f32_e32 v35, v35
	v_fmaak_f32 v40, v38, v40, 0x3c0887f9
	v_fmaak_f32 v40, v38, v40, 0x3d2aaa81
	v_fmaak_f32 v40, v38, v40, 0x3e2aaaab
	v_fma_f32 v40, v38, v40, 0.5
	v_ldexp_f32 v35, 1.0, v35
	v_mul_f32_e32 v40, v38, v40
	v_cndmask_b32_e32 v35, v35, v202, vcc
	v_fmac_f32_e32 v38, v38, v40
	v_add_f32_e32 v40, -1.0, v35
	v_fmac_f32_e32 v40, v35, v38
	v_add_f32_e32 v35, v40, v40
	v_cndmask_b32_e32 v35, v40, v35, vcc
	v_cmp_nlt_f32_e32 vcc, s22, v32
	s_nop 1
	v_cndmask_b32_e64 v35, v201, -v35, vcc
	v_cmp_gt_f32_e32 vcc, s23, v35
	v_mul_f32_e32 v38, 0x4f800000, v35
	s_nop 0
	v_cndmask_b32_e32 v35, v35, v38, vcc
	v_sqrt_f32_e32 v38, v35
	s_nop 0
	v_add_u32_e32 v40, -1, v38
	v_fma_f32 v42, -v40, v38, v35
	v_cmp_ge_f32_e64 s[0:1], 0, v42
	v_add_u32_e32 v42, 1, v38
	s_nop 0
	v_cndmask_b32_e64 v40, v38, v40, s[0:1]
	v_fma_f32 v38, -v42, v38, v35
	v_cmp_lt_f32_e64 s[0:1], 0, v38
	s_nop 1
	v_cndmask_b32_e64 v38, v40, v42, s[0:1]
	v_mul_f32_e32 v40, 0x37800000, v38
	v_cndmask_b32_e32 v38, v38, v40, vcc
	v_cmp_class_f32_e32 vcc, v35, v193
	s_nop 1
	v_cndmask_b32_e32 v35, v38, v35, vcc
	v_cmp_ngt_f32_e32 vcc, s24, v32
	s_nop 1
	v_cndmask_b32_e32 v32, 1.0, v35, vcc
	v_mul_f32_e32 v32, v34, v32
	ds_read2_b32 v[34:35], v33 offset0:128 offset1:160
	s_waitcnt lgkmcnt(0)
	v_mul_f32_e32 v32, v34, v32
	ds_write_b32 v144, v36 offset:6656
	ds_write_b32 v144, v32 offset:43520
	v_add_f32_e32 v32, v63, v147
	v_mul_f32_e32 v32, 0xbfb8aa3b, v32
	v_exp_f32_e32 v32, v32
	v_add_f32_e32 v34, v47, v146
	v_mul_f32_e32 v34, 0xbfb8aa3b, v34
	v_exp_f32_e32 v34, v34
	v_add_f32_e32 v32, 1.0, v32
	v_rcp_f32_e32 v32, v32
	v_add_f32_e32 v34, 1.0, v34
	v_rcp_f32_e32 v36, v34
	v_mul_f32_e32 v32, v32, v96
	v_mul_f32_e32 v34, 0x3fb8aa3b, v32
	v_add_f32_e32 v32, v32, v32
	v_mul_f32_e32 v38, 0x3fb8aa3b, v32
	v_rndne_f32_e32 v38, v38
	v_fmamk_f32 v40, v38, 0xbf317218, v32
	v_fmac_f32_e32 v40, 0x3102e308, v38
	v_fmamk_f32 v42, v40, 0x395133b1, v192
	v_cmp_eq_f32_e32 vcc, s21, v38
	v_cvt_i32_f32_e32 v38, v38
	v_fmaak_f32 v42, v40, v42, 0x3c0887f9
	v_fmaak_f32 v42, v40, v42, 0x3d2aaa81
	v_fmaak_f32 v42, v40, v42, 0x3e2aaaab
	v_fma_f32 v42, v40, v42, 0.5
	v_ldexp_f32 v38, 1.0, v38
	v_mul_f32_e32 v42, v40, v42
	v_cndmask_b32_e32 v38, v38, v202, vcc
	v_fmac_f32_e32 v40, v40, v42
	v_add_f32_e32 v42, -1.0, v38
	v_fmac_f32_e32 v42, v38, v40
	v_add_f32_e32 v38, v42, v42
	v_cndmask_b32_e32 v38, v42, v38, vcc
	v_cmp_nlt_f32_e32 vcc, s22, v32
	v_add_u32_e32 v96, s3, v145
	v_lshlrev_b64 v[46:47], 2, v[96:97]
	v_cndmask_b32_e64 v38, v201, -v38, vcc
	v_cmp_gt_f32_e32 vcc, s23, v38
	v_mul_f32_e32 v40, 0x4f800000, v38
	v_lshl_add_u64 v[60:61], s[18:19], 0, v[46:47]
	v_cndmask_b32_e32 v38, v38, v40, vcc
	v_sqrt_f32_e32 v40, v38
	v_exp_f32_e32 v34, v34
	s_movk_i32 s18, 0x1600
	s_mov_b32 s19, 0x2c000
	v_add_u32_e32 v42, -1, v40
	v_fma_f32 v44, -v42, v40, v38
	v_cmp_ge_f32_e64 s[0:1], 0, v44
	v_add_u32_e32 v44, 1, v40
	s_nop 0
	v_cndmask_b32_e64 v42, v40, v42, s[0:1]
	v_fma_f32 v40, -v44, v40, v38
	v_cmp_lt_f32_e64 s[0:1], 0, v40
	s_nop 1
	v_cndmask_b32_e64 v40, v42, v44, s[0:1]
	v_mul_f32_e32 v42, 0x37800000, v40
	v_cndmask_b32_e32 v40, v40, v42, vcc
	v_cmp_class_f32_e32 vcc, v38, v193
	s_nop 1
	v_cndmask_b32_e32 v38, v40, v38, vcc
	v_cmp_ngt_f32_e32 vcc, s24, v32
	s_nop 1
	v_cndmask_b32_e32 v32, 1.0, v38, vcc
	v_mul_f32_e32 v36, v36, v32
	ds_read2_b32 v[32:33], v33 offset0:192 offset1:224
	s_waitcnt lgkmcnt(0)
	v_mul_f32_e32 v32, v32, v36
	ds_write_b32 v144, v32 offset:43776
	v_mov_b32_e32 v32, v226
	v_mul_f32_e32 v32, 0xbfb8aa3b, v32
	v_exp_f32_e32 v32, v32
	s_nop 0
	v_add_f32_e32 v36, 1.0, v32
	v_add_f32_e32 v38, -1.0, v36
	v_sub_f32_e32 v40, v38, v36
	v_add_f32_e32 v40, 1.0, v40
	v_sub_f32_e32 v38, v32, v38
	v_add_f32_e32 v38, v38, v40
	v_frexp_mant_f32_e32 v40, v36
	v_cvt_f64_f32_e32 v[60:61], v36
	v_cmp_gt_f32_e32 vcc, s8, v40
	v_frexp_exp_i32_f64_e32 v40, v[60:61]
	s_nop 0
	v_subbrev_co_u32_e32 v40, vcc, 0, v40, vcc
	v_sub_u32_e32 v42, 0, v40
	v_ldexp_f32 v36, v36, v42
	v_ldexp_f32 v38, v38, v42
	v_add_f32_e32 v42, -1.0, v36
	v_add_f32_e32 v48, 1.0, v36
	v_add_f32_e32 v44, 1.0, v42
	v_add_f32_e32 v50, -1.0, v48
	v_sub_f32_e32 v44, v36, v44
	v_sub_f32_e32 v36, v36, v50
	v_add_f32_e32 v36, v38, v36
	v_add_f32_e32 v44, v38, v44
	v_add_f32_e32 v38, v48, v36
	v_sub_f32_e32 v48, v38, v48
	v_sub_f32_e32 v36, v36, v48
	v_rcp_f32_e32 v48, v38
	v_add_f32_e32 v61, v42, v44
	v_sub_f32_e32 v42, v61, v42
	v_sub_f32_e32 v42, v44, v42
	v_mul_f32_e32 v44, v61, v48
	v_mul_f32_e32 v62, v38, v44
	v_fma_f32 v146, v44, v38, -v62
	v_fmac_f32_e32 v146, v44, v36
	v_add_f32_e32 v60, v62, v146
	v_sub_f32_e32 v63, v61, v60
	v_pk_add_f32 v[148:149], v[60:61], v[62:63] neg_lo:[0,1] neg_hi:[0,1]
	v_mov_b32_e32 v147, v60
	v_pk_add_f32 v[60:61], v[148:149], v[146:147] neg_lo:[0,1] neg_hi:[0,1]
	v_cmp_neq_f32_e32 vcc, s10, v32
	v_add_f32_e32 v42, v42, v61
	v_add_f32_e32 v42, v60, v42
	v_add_f32_e32 v61, v63, v42
	v_mul_f32_e32 v50, v48, v61
	v_mul_f32_e32 v62, v38, v50
	v_fma_f32 v146, v50, v38, -v62
	v_fmac_f32_e32 v146, v50, v36
	v_add_f32_e32 v60, v62, v146
	v_sub_f32_e32 v36, v63, v61
	v_sub_f32_e32 v63, v61, v60
	v_pk_add_f32 v[148:149], v[60:61], v[62:63] neg_lo:[0,1] neg_hi:[0,1]
	v_mov_b32_e32 v147, v60
	v_add_f32_e32 v36, v42, v36
	v_pk_add_f32 v[60:61], v[148:149], v[146:147] neg_lo:[0,1] neg_hi:[0,1]
	v_add_f32_e32 v38, v44, v50
	v_add_f32_e32 v36, v36, v61
	v_add_f32_e32 v36, v60, v36
	v_add_f32_e32 v36, v63, v36
	v_sub_f32_e32 v42, v38, v44
	v_mul_f32_e32 v36, v48, v36
	v_sub_f32_e32 v42, v50, v42
	v_add_f32_e32 v36, v42, v36
	v_add_f32_e32 v42, v38, v36
	v_cvt_f32_i32_e32 v60, v40
	v_mul_f32_e32 v44, v42, v42
	v_fmamk_f32 v48, v44, 0x3e9b6dac, v191
	v_fmaak_f32 v169, v44, v48, 0x3f2aaada
	v_mul_f32_e32 v61, v42, v44
	v_pk_mul_f32 v[146:147], v[60:61], v[168:169]
	v_ldexp_f32 v63, v42, 1
	v_fma_f32 v62, v60, s9, -v146
	v_fmac_f32_e32 v62, 0xb102e308, v60
	v_sub_f32_e32 v38, v42, v38
	v_pk_add_f32 v[60:61], v[146:147], v[62:63]
	v_sub_f32_e32 v36, v36, v38
	v_sub_f32_e32 v38, v61, v63
	v_ldexp_f32 v36, v36, 1
	v_sub_f32_e32 v38, v147, v38
	v_add_f32_e32 v149, v36, v38
	v_mov_b32_e32 v148, v146
	v_pk_add_f32 v[146:147], v[60:61], v[146:147] neg_lo:[0,1] neg_hi:[0,1]
	v_pk_add_f32 v[150:151], v[60:61], v[148:149]
	v_mov_b32_e32 v63, v60
	v_mov_b32_e32 v147, v151
	v_pk_add_f32 v[152:153], v[62:63], v[146:147] neg_lo:[0,1] neg_hi:[0,1]
	v_pk_add_f32 v[62:63], v[62:63], v[146:147]
	v_mov_b32_e32 v148, v149
	v_pk_add_f32 v[146:147], v[62:63], v[60:61] op_sel:[1,0] op_sel_hi:[0,1] neg_lo:[0,1] neg_hi:[0,1]
	v_pk_add_f32 v[154:155], v[150:151], v[146:147] op_sel_hi:[1,0] neg_lo:[0,1] neg_hi:[0,1]
	v_mov_b32_e32 v150, v151
	v_mov_b32_e32 v151, v63
	v_pk_mov_b32 v[146:147], v[60:61], v[146:147] op_sel:[1,0]
	v_mov_b32_e32 v149, v60
	v_pk_add_f32 v[146:147], v[150:151], v[146:147] neg_lo:[0,1] neg_hi:[0,1]
	v_mov_b32_e32 v154, v152
	v_pk_add_f32 v[60:61], v[148:149], v[146:147] neg_lo:[0,1] neg_hi:[0,1]
	v_mov_b32_e32 v153, v63
	v_pk_add_f32 v[146:147], v[154:155], v[60:61]
	v_readlane_b32 s10, v248, 33
	v_pk_add_f32 v[148:149], v[146:147], v[146:147] op_sel:[0,1] op_sel_hi:[1,0]
	v_pk_add_f32 v[62:63], v[62:63], v[148:149] op_sel:[1,0] op_sel_hi:[0,1]
	v_mov_b32_e32 v147, v62
	v_pk_add_f32 v[150:151], v[146:147], v[152:153] neg_lo:[0,1] neg_hi:[0,1]
	v_mov_b32_e32 v61, v148
	v_sub_f32_e32 v36, v146, v150
	v_pk_add_f32 v[60:61], v[60:61], v[150:151] neg_lo:[0,1] neg_hi:[0,1]
	v_sub_f32_e32 v36, v152, v36
	v_add_f32_e32 v36, v60, v36
	v_add_f32_e32 v36, v36, v61
	v_add_f32_e32 v36, v62, v36
	v_cndmask_b32_e32 v36, v199, v36, vcc
	v_cmp_ngt_f32_e32 vcc, -1.0, v32
	v_lshl_add_u64 v[60:61], s[52:53], 0, v[46:47]
	v_lshl_add_u64 v[46:47], s[16:17], 0, v[46:47]
	v_cndmask_b32_e32 v36, v200, v36, vcc
	v_cmp_neq_f32_e32 vcc, -1.0, v32
	v_mov_b32_e32 v38, v227
	s_mov_b64 s[16:17], s[82:83]
	v_cndmask_b32_e32 v36, v201, v36, vcc
	v_cmp_lt_f32_e64 vcc, |v32|, s20
	s_mov_b32 s20, 0x58000
	v_add_f32_e32 v0, v0, v38
	v_cndmask_b32_e32 v32, v36, v32, vcc
	v_mov_b32_e32 v36, v228
	v_mul_f32_e32 v32, 0xc1000000, v32
	v_mul_f32_e32 v0, 0xbfb8aa3b, v0
	v_exp_f32_e32 v0, v0
	v_add_f32_e32 v1, v1, v38
	v_mul_f32_e32 v1, 0xbfb8aa3b, v1
	v_exp_f32_e32 v1, v1
	v_add_f32_e32 v0, 1.0, v0
	v_rcp_f32_e32 v0, v0
	v_add_f32_e32 v1, 1.0, v1
	v_rcp_f32_e32 v1, v1
	v_add_f32_e32 v16, v16, v36
	v_mul_f32_e32 v16, 0xbfb8aa3b, v16
	v_exp_f32_e32 v16, v16
	s_nop 0
	v_add_f32_e32 v16, 1.0, v16
	v_rcp_f32_e32 v16, v16
	s_nop 0
	v_mul_f32_e32 v16, v16, v32
	v_mul_f32_e32 v40, 0x3fb8aa3b, v16
	v_add_f32_e32 v16, v16, v16
	v_mul_f32_e32 v42, 0x3fb8aa3b, v16
	v_rndne_f32_e32 v42, v42
	v_fmamk_f32 v44, v42, 0xbf317218, v16
	v_fmac_f32_e32 v44, 0x3102e308, v42
	v_fmamk_f32 v46, v44, 0x395133b1, v192
	v_cmp_eq_f32_e32 vcc, s21, v42
	v_cvt_i32_f32_e32 v42, v42
	v_fmaak_f32 v46, v44, v46, 0x3c0887f9
	v_fmaak_f32 v46, v44, v46, 0x3d2aaa81
	v_fmaak_f32 v46, v44, v46, 0x3e2aaaab
	v_fma_f32 v46, v44, v46, 0.5
	v_ldexp_f32 v42, 1.0, v42
	v_mul_f32_e32 v46, v44, v46
	v_cndmask_b32_e32 v42, v42, v202, vcc
	v_fmac_f32_e32 v44, v44, v46
	v_add_f32_e32 v46, -1.0, v42
	v_fmac_f32_e32 v46, v42, v44
	v_add_f32_e32 v42, v46, v46
	v_cndmask_b32_e32 v42, v46, v42, vcc
	v_cmp_nlt_f32_e32 vcc, s22, v16
	v_exp_f32_e32 v40, v40
	s_nop 0
	v_cndmask_b32_e64 v42, v201, -v42, vcc
	v_cmp_gt_f32_e32 vcc, s23, v42
	v_mul_f32_e32 v44, 0x4f800000, v42
	s_nop 0
	v_cndmask_b32_e32 v42, v42, v44, vcc
	v_sqrt_f32_e32 v44, v42
	s_nop 0
	v_add_u32_e32 v46, -1, v44
	v_fma_f32 v47, -v46, v44, v42
	v_cmp_ge_f32_e64 s[0:1], 0, v47
	v_add_u32_e32 v47, 1, v44
	s_nop 0
	v_cndmask_b32_e64 v46, v44, v46, s[0:1]
	v_fma_f32 v44, -v47, v44, v42
	v_cmp_lt_f32_e64 s[0:1], 0, v44
	s_nop 1
	v_cndmask_b32_e64 v44, v46, v47, s[0:1]
	v_mul_f32_e32 v46, 0x37800000, v44
	v_cndmask_b32_e32 v44, v44, v46, vcc
	v_cmp_class_f32_e32 vcc, v42, v193
	s_nop 1
	v_cndmask_b32_e32 v42, v44, v42, vcc
	v_cmp_ngt_f32_e32 vcc, s24, v16
	s_nop 1
	v_cndmask_b32_e32 v16, 1.0, v42, vcc
	v_mul_f32_e32 v0, v0, v16
	v_mul_f32_e32 v0, v135, v0
	ds_write_b32 v144, v40 offset:128
	ds_write_b32 v144, v0 offset:36992
	v_add_f32_e32 v0, v17, v36
	v_mul_f32_e32 v0, 0xbfb8aa3b, v0
	v_exp_f32_e32 v0, v0
	s_nop 0
	v_add_f32_e32 v0, 1.0, v0
	v_rcp_f32_e32 v0, v0
	s_nop 0
	v_mul_f32_e32 v0, v0, v32
	v_mul_f32_e32 v16, 0x3fb8aa3b, v0
	v_add_f32_e32 v0, v0, v0
	v_mul_f32_e32 v17, 0x3fb8aa3b, v0
	v_rndne_f32_e32 v17, v17
	v_fmamk_f32 v40, v17, 0xbf317218, v0
	v_fmac_f32_e32 v40, 0x3102e308, v17
	v_fmamk_f32 v42, v40, 0x395133b1, v192
	v_cmp_eq_f32_e32 vcc, s21, v17
	v_cvt_i32_f32_e32 v17, v17
	v_fmaak_f32 v42, v40, v42, 0x3c0887f9
	v_fmaak_f32 v42, v40, v42, 0x3d2aaa81
	v_fmaak_f32 v42, v40, v42, 0x3e2aaaab
	v_fma_f32 v42, v40, v42, 0.5
	v_ldexp_f32 v17, 1.0, v17
	v_mul_f32_e32 v42, v40, v42
	v_cndmask_b32_e32 v17, v17, v202, vcc
	v_fmac_f32_e32 v40, v40, v42
	v_add_f32_e32 v42, -1.0, v17
	v_fmac_f32_e32 v42, v17, v40
	v_add_f32_e32 v17, v42, v42
	v_cndmask_b32_e32 v17, v42, v17, vcc
	v_cmp_nlt_f32_e32 vcc, s22, v0
	v_exp_f32_e32 v16, v16
	s_nop 0
	v_cndmask_b32_e64 v17, v201, -v17, vcc
	v_cmp_gt_f32_e32 vcc, s23, v17
	v_mul_f32_e32 v40, 0x4f800000, v17
	s_nop 0
	v_cndmask_b32_e32 v17, v17, v40, vcc
	v_sqrt_f32_e32 v40, v17
	s_nop 0
	v_add_u32_e32 v42, -1, v40
	v_fma_f32 v44, -v42, v40, v17
	v_cmp_ge_f32_e64 s[0:1], 0, v44
	v_add_u32_e32 v44, 1, v40
	s_nop 0
	v_cndmask_b32_e64 v42, v40, v42, s[0:1]
	v_fma_f32 v40, -v44, v40, v17
	v_cmp_lt_f32_e64 s[0:1], 0, v40
	s_nop 1
	v_cndmask_b32_e64 v40, v42, v44, s[0:1]
	v_mul_f32_e32 v42, 0x37800000, v40
	v_cndmask_b32_e32 v40, v40, v42, vcc
	v_cmp_class_f32_e32 vcc, v17, v193
	s_nop 1
	v_cndmask_b32_e32 v17, v40, v17, vcc
	v_cmp_ngt_f32_e32 vcc, s24, v0
	s_nop 1
	v_cndmask_b32_e32 v0, 1.0, v17, vcc
	v_mul_f32_e32 v0, v1, v0
	v_mul_f32_e32 v0, v49, v0
	ds_write_b32 v144, v16 offset:384
	ds_write_b32 v144, v0 offset:37248
	v_add_f32_e32 v0, v18, v36
	v_mul_f32_e32 v0, 0xbfb8aa3b, v0
	v_exp_f32_e32 v0, v0
	v_add_f32_e32 v1, v2, v38
	v_mul_f32_e32 v1, 0xbfb8aa3b, v1
	v_exp_f32_e32 v1, v1
	v_add_f32_e32 v0, 1.0, v0
	v_rcp_f32_e32 v0, v0
	v_add_f32_e32 v1, 1.0, v1
	v_rcp_f32_e32 v1, v1
	v_mul_f32_e32 v0, v0, v32
	v_mul_f32_e32 v2, 0x3fb8aa3b, v0
	v_add_f32_e32 v0, v0, v0
	v_mul_f32_e32 v16, 0x3fb8aa3b, v0
	v_rndne_f32_e32 v16, v16
	v_fmamk_f32 v17, v16, 0xbf317218, v0
	v_fmac_f32_e32 v17, 0x3102e308, v16
	v_fmamk_f32 v18, v17, 0x395133b1, v192
	v_cmp_eq_f32_e32 vcc, s21, v16
	v_cvt_i32_f32_e32 v16, v16
	v_fmaak_f32 v18, v17, v18, 0x3c0887f9
	v_fmaak_f32 v18, v17, v18, 0x3d2aaa81
	v_fmaak_f32 v18, v17, v18, 0x3e2aaaab
	v_fma_f32 v18, v17, v18, 0.5
	v_ldexp_f32 v16, 1.0, v16
	v_mul_f32_e32 v18, v17, v18
	v_cndmask_b32_e32 v16, v16, v202, vcc
	v_fmac_f32_e32 v17, v17, v18
	v_add_f32_e32 v18, -1.0, v16
	v_fmac_f32_e32 v18, v16, v17
	v_add_f32_e32 v16, v18, v18
	v_cndmask_b32_e32 v16, v18, v16, vcc
	v_cmp_nlt_f32_e32 vcc, s22, v0
	v_exp_f32_e32 v2, v2
	s_nop 0
	v_cndmask_b32_e64 v16, v201, -v16, vcc
	v_cmp_gt_f32_e32 vcc, s23, v16
	v_mul_f32_e32 v17, 0x4f800000, v16
	s_nop 0
	v_cndmask_b32_e32 v16, v16, v17, vcc
	v_sqrt_f32_e32 v17, v16
	s_nop 0
	v_add_u32_e32 v18, -1, v17
	v_fma_f32 v40, -v18, v17, v16
	v_cmp_ge_f32_e64 s[0:1], 0, v40
	v_add_u32_e32 v40, 1, v17
	s_nop 0
	v_cndmask_b32_e64 v18, v17, v18, s[0:1]
	v_fma_f32 v17, -v40, v17, v16
	v_cmp_lt_f32_e64 s[0:1], 0, v17
	s_nop 1
	v_cndmask_b32_e64 v17, v18, v40, s[0:1]
	v_mul_f32_e32 v18, 0x37800000, v17
	v_cndmask_b32_e32 v17, v17, v18, vcc
	v_cmp_class_f32_e32 vcc, v16, v193
	s_nop 1
	v_cndmask_b32_e32 v16, v17, v16, vcc
	v_cmp_ngt_f32_e32 vcc, s24, v0
	s_nop 1
	v_cndmask_b32_e32 v0, 1.0, v16, vcc
	v_mul_f32_e32 v0, v1, v0
	v_mul_f32_e32 v0, v137, v0
	ds_write_b32 v144, v2 offset:640
	ds_write_b32 v144, v0 offset:37504
	v_add_f32_e32 v0, v19, v36
	v_mul_f32_e32 v0, 0xbfb8aa3b, v0
	v_exp_f32_e32 v0, v0
	v_add_f32_e32 v1, v3, v38
	v_mul_f32_e32 v1, 0xbfb8aa3b, v1
	v_exp_f32_e32 v1, v1
	v_add_f32_e32 v0, 1.0, v0
	v_rcp_f32_e32 v0, v0
	v_add_f32_e32 v1, 1.0, v1
	v_rcp_f32_e32 v1, v1
	v_mul_f32_e32 v0, v0, v32
	v_mul_f32_e32 v2, 0x3fb8aa3b, v0
	v_add_f32_e32 v0, v0, v0
	v_mul_f32_e32 v3, 0x3fb8aa3b, v0
	v_rndne_f32_e32 v3, v3
	v_fmamk_f32 v16, v3, 0xbf317218, v0
	v_fmac_f32_e32 v16, 0x3102e308, v3
	v_fmamk_f32 v17, v16, 0x395133b1, v192
	v_cmp_eq_f32_e32 vcc, s21, v3
	v_cvt_i32_f32_e32 v3, v3
	v_fmaak_f32 v17, v16, v17, 0x3c0887f9
	v_fmaak_f32 v17, v16, v17, 0x3d2aaa81
	v_fmaak_f32 v17, v16, v17, 0x3e2aaaab
	v_fma_f32 v17, v16, v17, 0.5
	v_ldexp_f32 v3, 1.0, v3
	v_mul_f32_e32 v17, v16, v17
	v_cndmask_b32_e32 v3, v3, v202, vcc
	v_fmac_f32_e32 v16, v16, v17
	v_add_f32_e32 v17, -1.0, v3
	v_fmac_f32_e32 v17, v3, v16
	v_add_f32_e32 v3, v17, v17
	v_cndmask_b32_e32 v3, v17, v3, vcc
	v_cmp_nlt_f32_e32 vcc, s22, v0
	v_exp_f32_e32 v2, v2
	s_nop 0
	v_cndmask_b32_e64 v3, v201, -v3, vcc
	v_cmp_gt_f32_e32 vcc, s23, v3
	v_mul_f32_e32 v16, 0x4f800000, v3
	s_nop 0
	v_cndmask_b32_e32 v3, v3, v16, vcc
	v_sqrt_f32_e32 v16, v3
	s_nop 0
	v_add_u32_e32 v17, -1, v16
	v_fma_f32 v18, -v17, v16, v3
	v_cmp_ge_f32_e64 s[0:1], 0, v18
	v_add_u32_e32 v18, 1, v16
	s_nop 0
	v_cndmask_b32_e64 v17, v16, v17, s[0:1]
	v_fma_f32 v16, -v18, v16, v3
	v_cmp_lt_f32_e64 s[0:1], 0, v16
	s_nop 1
	v_cndmask_b32_e64 v16, v17, v18, s[0:1]
	v_mul_f32_e32 v17, 0x37800000, v16
	v_cndmask_b32_e32 v16, v16, v17, vcc
	v_cmp_class_f32_e32 vcc, v3, v193
	s_nop 1
	v_cndmask_b32_e32 v3, v16, v3, vcc
	v_cmp_ngt_f32_e32 vcc, s24, v0
	s_nop 1
	v_cndmask_b32_e32 v0, 1.0, v3, vcc
	v_mul_f32_e32 v0, v1, v0
	v_mul_f32_e32 v0, v51, v0
	ds_write_b32 v144, v2 offset:896
	ds_write_b32 v144, v0 offset:37760
	v_add_f32_e32 v0, v20, v36
	v_mul_f32_e32 v0, 0xbfb8aa3b, v0
	v_exp_f32_e32 v0, v0
	v_add_f32_e32 v1, v4, v38
	v_mul_f32_e32 v1, 0xbfb8aa3b, v1
	v_exp_f32_e32 v1, v1
	v_add_f32_e32 v0, 1.0, v0
	v_rcp_f32_e32 v0, v0
	v_add_f32_e32 v1, 1.0, v1
	v_rcp_f32_e32 v1, v1
	v_mul_f32_e32 v0, v0, v32
	v_mul_f32_e32 v2, 0x3fb8aa3b, v0
	v_add_f32_e32 v0, v0, v0
	v_mul_f32_e32 v3, 0x3fb8aa3b, v0
	v_rndne_f32_e32 v3, v3
	v_fmamk_f32 v4, v3, 0xbf317218, v0
	v_fmac_f32_e32 v4, 0x3102e308, v3
	v_fmamk_f32 v16, v4, 0x395133b1, v192
	v_cmp_eq_f32_e32 vcc, s21, v3
	v_cvt_i32_f32_e32 v3, v3
	v_fmaak_f32 v16, v4, v16, 0x3c0887f9
	v_fmaak_f32 v16, v4, v16, 0x3d2aaa81
	v_fmaak_f32 v16, v4, v16, 0x3e2aaaab
	v_fma_f32 v16, v4, v16, 0.5
	v_ldexp_f32 v3, 1.0, v3
	v_mul_f32_e32 v16, v4, v16
	v_cndmask_b32_e32 v3, v3, v202, vcc
	v_fmac_f32_e32 v4, v4, v16
	v_add_f32_e32 v16, -1.0, v3
	v_fmac_f32_e32 v16, v3, v4
	v_add_f32_e32 v3, v16, v16
	v_cndmask_b32_e32 v3, v16, v3, vcc
	v_cmp_nlt_f32_e32 vcc, s22, v0
	v_exp_f32_e32 v2, v2
	s_nop 0
	v_cndmask_b32_e64 v3, v201, -v3, vcc
	v_cmp_gt_f32_e32 vcc, s23, v3
	v_mul_f32_e32 v4, 0x4f800000, v3
	s_nop 0
	v_cndmask_b32_e32 v3, v3, v4, vcc
	v_sqrt_f32_e32 v4, v3
	s_nop 0
	v_add_u32_e32 v16, -1, v4
	v_fma_f32 v17, -v16, v4, v3
	v_cmp_ge_f32_e64 s[0:1], 0, v17
	v_add_u32_e32 v17, 1, v4
	s_nop 0
	v_cndmask_b32_e64 v16, v4, v16, s[0:1]
	v_fma_f32 v4, -v17, v4, v3
	v_cmp_lt_f32_e64 s[0:1], 0, v4
	s_nop 1
	v_cndmask_b32_e64 v4, v16, v17, s[0:1]
	v_mul_f32_e32 v16, 0x37800000, v4
	v_cndmask_b32_e32 v4, v4, v16, vcc
	v_cmp_class_f32_e32 vcc, v3, v193
	s_nop 1
	v_cndmask_b32_e32 v3, v4, v3, vcc
	v_cmp_ngt_f32_e32 vcc, s24, v0
	s_nop 1
	v_cndmask_b32_e32 v0, 1.0, v3, vcc
	v_mul_f32_e32 v0, v1, v0
	v_mul_f32_e32 v0, v139, v0
	ds_write_b32 v144, v2 offset:2176
	ds_write_b32 v144, v0 offset:39040
	v_add_f32_e32 v0, v21, v36
	v_mul_f32_e32 v0, 0xbfb8aa3b, v0
	v_exp_f32_e32 v0, v0
	v_add_f32_e32 v1, v5, v38
	v_mul_f32_e32 v1, 0xbfb8aa3b, v1
	v_exp_f32_e32 v1, v1
	v_add_f32_e32 v0, 1.0, v0
	v_rcp_f32_e32 v0, v0
	v_add_f32_e32 v1, 1.0, v1
	v_rcp_f32_e32 v1, v1
	v_mul_f32_e32 v0, v0, v32
	v_mul_f32_e32 v2, 0x3fb8aa3b, v0
	v_add_f32_e32 v0, v0, v0
	v_mul_f32_e32 v3, 0x3fb8aa3b, v0
	v_rndne_f32_e32 v3, v3
	v_fmamk_f32 v4, v3, 0xbf317218, v0
	v_fmac_f32_e32 v4, 0x3102e308, v3
	v_fmamk_f32 v5, v4, 0x395133b1, v192
	v_cmp_eq_f32_e32 vcc, s21, v3
	v_cvt_i32_f32_e32 v3, v3
	v_fmaak_f32 v5, v4, v5, 0x3c0887f9
	v_fmaak_f32 v5, v4, v5, 0x3d2aaa81
	v_fmaak_f32 v5, v4, v5, 0x3e2aaaab
	v_fma_f32 v5, v4, v5, 0.5
	v_ldexp_f32 v3, 1.0, v3
	v_mul_f32_e32 v5, v4, v5
	v_cndmask_b32_e32 v3, v3, v202, vcc
	v_fmac_f32_e32 v4, v4, v5
	v_add_f32_e32 v5, -1.0, v3
	v_fmac_f32_e32 v5, v3, v4
	v_add_f32_e32 v3, v5, v5
	v_cndmask_b32_e32 v3, v5, v3, vcc
	v_cmp_nlt_f32_e32 vcc, s22, v0
	v_exp_f32_e32 v2, v2
	s_nop 0
	v_cndmask_b32_e64 v3, v201, -v3, vcc
	v_cmp_gt_f32_e32 vcc, s23, v3
	v_mul_f32_e32 v4, 0x4f800000, v3
	s_nop 0
	v_cndmask_b32_e32 v3, v3, v4, vcc
	v_sqrt_f32_e32 v4, v3
	s_nop 0
	v_add_u32_e32 v5, -1, v4
	v_fma_f32 v16, -v5, v4, v3
	v_cmp_ge_f32_e64 s[0:1], 0, v16
	v_add_u32_e32 v16, 1, v4
	s_nop 0
	v_cndmask_b32_e64 v5, v4, v5, s[0:1]
	v_fma_f32 v4, -v16, v4, v3
	v_cmp_lt_f32_e64 s[0:1], 0, v4
	s_nop 1
	v_cndmask_b32_e64 v4, v5, v16, s[0:1]
	v_mul_f32_e32 v5, 0x37800000, v4
	v_cndmask_b32_e32 v4, v4, v5, vcc
	v_cmp_class_f32_e32 vcc, v3, v193
	s_nop 1
	v_cndmask_b32_e32 v3, v4, v3, vcc
	v_cmp_ngt_f32_e32 vcc, s24, v0
	s_nop 1
	v_cndmask_b32_e32 v0, 1.0, v3, vcc
	v_mul_f32_e32 v0, v1, v0
	v_mul_f32_e32 v0, v37, v0
	ds_write_b32 v144, v2 offset:2432
	ds_write_b32 v144, v0 offset:39296
	v_add_f32_e32 v0, v22, v36
	v_mul_f32_e32 v0, 0xbfb8aa3b, v0
	v_exp_f32_e32 v0, v0
	v_add_f32_e32 v1, v6, v38
	v_mul_f32_e32 v1, 0xbfb8aa3b, v1
	v_exp_f32_e32 v1, v1
	v_add_f32_e32 v0, 1.0, v0
	v_rcp_f32_e32 v0, v0
	v_add_f32_e32 v1, 1.0, v1
	v_rcp_f32_e32 v1, v1
	v_mul_f32_e32 v0, v0, v32
	v_mul_f32_e32 v2, 0x3fb8aa3b, v0
	v_add_f32_e32 v0, v0, v0
	v_mul_f32_e32 v3, 0x3fb8aa3b, v0
	v_rndne_f32_e32 v3, v3
	v_fmamk_f32 v4, v3, 0xbf317218, v0
	v_fmac_f32_e32 v4, 0x3102e308, v3
	v_fmamk_f32 v5, v4, 0x395133b1, v192
	v_cmp_eq_f32_e32 vcc, s21, v3
	v_cvt_i32_f32_e32 v3, v3
	v_fmaak_f32 v5, v4, v5, 0x3c0887f9
	v_fmaak_f32 v5, v4, v5, 0x3d2aaa81
	v_fmaak_f32 v5, v4, v5, 0x3e2aaaab
	v_fma_f32 v5, v4, v5, 0.5
	v_ldexp_f32 v3, 1.0, v3
	v_mul_f32_e32 v5, v4, v5
	v_cndmask_b32_e32 v3, v3, v202, vcc
	v_fmac_f32_e32 v4, v4, v5
	v_add_f32_e32 v5, -1.0, v3
	v_fmac_f32_e32 v5, v3, v4
	v_add_f32_e32 v3, v5, v5
	v_cndmask_b32_e32 v3, v5, v3, vcc
	v_cmp_nlt_f32_e32 vcc, s22, v0
	v_exp_f32_e32 v2, v2
	s_nop 0
	v_cndmask_b32_e64 v3, v201, -v3, vcc
	v_cmp_gt_f32_e32 vcc, s23, v3
	v_mul_f32_e32 v4, 0x4f800000, v3
	s_nop 0
	v_cndmask_b32_e32 v3, v3, v4, vcc
	v_sqrt_f32_e32 v4, v3
	s_nop 0
	v_add_u32_e32 v5, -1, v4
	v_fma_f32 v6, -v5, v4, v3
	v_cmp_ge_f32_e64 s[0:1], 0, v6
	v_add_u32_e32 v6, 1, v4
	s_nop 0
	v_cndmask_b32_e64 v5, v4, v5, s[0:1]
	v_fma_f32 v4, -v6, v4, v3
	v_cmp_lt_f32_e64 s[0:1], 0, v4
	s_nop 1
	v_cndmask_b32_e64 v4, v5, v6, s[0:1]
	v_mul_f32_e32 v5, 0x37800000, v4
	v_cndmask_b32_e32 v4, v4, v5, vcc
	v_cmp_class_f32_e32 vcc, v3, v193
	s_nop 1
	v_cndmask_b32_e32 v3, v4, v3, vcc
	v_cmp_ngt_f32_e32 vcc, s24, v0
	s_nop 1
	v_cndmask_b32_e32 v0, 1.0, v3, vcc
	v_mul_f32_e32 v0, v1, v0
	v_mul_f32_e32 v0, v53, v0
	ds_write_b32 v144, v2 offset:2688
	ds_write_b32 v144, v0 offset:39552
	v_add_f32_e32 v0, v23, v36
	v_mul_f32_e32 v0, 0xbfb8aa3b, v0
	v_exp_f32_e32 v0, v0
	v_add_f32_e32 v1, v7, v38
	v_mul_f32_e32 v1, 0xbfb8aa3b, v1
	v_exp_f32_e32 v1, v1
	v_add_f32_e32 v0, 1.0, v0
	v_rcp_f32_e32 v0, v0
	v_add_f32_e32 v1, 1.0, v1
	v_rcp_f32_e32 v1, v1
	v_mul_f32_e32 v0, v0, v32
	v_mul_f32_e32 v2, 0x3fb8aa3b, v0
	v_add_f32_e32 v0, v0, v0
	v_mul_f32_e32 v3, 0x3fb8aa3b, v0
	v_rndne_f32_e32 v3, v3
	v_fmamk_f32 v4, v3, 0xbf317218, v0
	v_fmac_f32_e32 v4, 0x3102e308, v3
	v_fmamk_f32 v5, v4, 0x395133b1, v192
	v_cmp_eq_f32_e32 vcc, s21, v3
	v_cvt_i32_f32_e32 v3, v3
	v_fmaak_f32 v5, v4, v5, 0x3c0887f9
	v_fmaak_f32 v5, v4, v5, 0x3d2aaa81
	v_fmaak_f32 v5, v4, v5, 0x3e2aaaab
	v_fma_f32 v5, v4, v5, 0.5
	v_ldexp_f32 v3, 1.0, v3
	v_mul_f32_e32 v5, v4, v5
	v_cndmask_b32_e32 v3, v3, v202, vcc
	v_fmac_f32_e32 v4, v4, v5
	v_add_f32_e32 v5, -1.0, v3
	v_fmac_f32_e32 v5, v3, v4
	v_add_f32_e32 v3, v5, v5
	v_cndmask_b32_e32 v3, v5, v3, vcc
	v_cmp_nlt_f32_e32 vcc, s22, v0
	v_exp_f32_e32 v2, v2
	s_nop 0
	v_cndmask_b32_e64 v3, v201, -v3, vcc
	v_cmp_gt_f32_e32 vcc, s23, v3
	v_mul_f32_e32 v4, 0x4f800000, v3
	s_nop 0
	v_cndmask_b32_e32 v3, v3, v4, vcc
	v_sqrt_f32_e32 v4, v3
	s_nop 0
	v_add_u32_e32 v5, -1, v4
	v_fma_f32 v6, -v5, v4, v3
	v_cmp_ge_f32_e64 s[0:1], 0, v6
	v_add_u32_e32 v6, 1, v4
	s_nop 0
	v_cndmask_b32_e64 v5, v4, v5, s[0:1]
	v_fma_f32 v4, -v6, v4, v3
	v_cmp_lt_f32_e64 s[0:1], 0, v4
	s_nop 1
	v_cndmask_b32_e64 v4, v5, v6, s[0:1]
	v_mul_f32_e32 v5, 0x37800000, v4
	v_cndmask_b32_e32 v4, v4, v5, vcc
	v_cmp_class_f32_e32 vcc, v3, v193
	s_nop 1
	v_cndmask_b32_e32 v3, v4, v3, vcc
	v_cmp_ngt_f32_e32 vcc, s24, v0
	s_nop 1
	v_cndmask_b32_e32 v0, 1.0, v3, vcc
	v_mul_f32_e32 v0, v1, v0
	v_mul_f32_e32 v0, v39, v0
	ds_write_b32 v144, v2 offset:2944
	ds_write_b32 v144, v0 offset:39808
	v_add_f32_e32 v0, v24, v36
	v_mul_f32_e32 v0, 0xbfb8aa3b, v0
	v_exp_f32_e32 v0, v0
	v_add_f32_e32 v1, v8, v38
	v_mul_f32_e32 v1, 0xbfb8aa3b, v1
	v_exp_f32_e32 v1, v1
	v_add_f32_e32 v0, 1.0, v0
	v_rcp_f32_e32 v0, v0
	v_add_f32_e32 v1, 1.0, v1
	v_rcp_f32_e32 v1, v1
	v_mul_f32_e32 v0, v0, v32
	v_mul_f32_e32 v2, 0x3fb8aa3b, v0
	v_add_f32_e32 v0, v0, v0
	v_mul_f32_e32 v3, 0x3fb8aa3b, v0
	v_rndne_f32_e32 v3, v3
	v_fmamk_f32 v4, v3, 0xbf317218, v0
	v_fmac_f32_e32 v4, 0x3102e308, v3
	v_fmamk_f32 v5, v4, 0x395133b1, v192
	v_cmp_eq_f32_e32 vcc, s21, v3
	v_cvt_i32_f32_e32 v3, v3
	v_fmaak_f32 v5, v4, v5, 0x3c0887f9
	v_fmaak_f32 v5, v4, v5, 0x3d2aaa81
	v_fmaak_f32 v5, v4, v5, 0x3e2aaaab
	v_fma_f32 v5, v4, v5, 0.5
	v_ldexp_f32 v3, 1.0, v3
	v_mul_f32_e32 v5, v4, v5
	v_cndmask_b32_e32 v3, v3, v202, vcc
	v_fmac_f32_e32 v4, v4, v5
	v_add_f32_e32 v5, -1.0, v3
	v_fmac_f32_e32 v5, v3, v4
	v_add_f32_e32 v3, v5, v5
	v_cndmask_b32_e32 v3, v5, v3, vcc
	v_cmp_nlt_f32_e32 vcc, s22, v0
	v_exp_f32_e32 v2, v2
	s_nop 0
	v_cndmask_b32_e64 v3, v201, -v3, vcc
	v_cmp_gt_f32_e32 vcc, s23, v3
	v_mul_f32_e32 v4, 0x4f800000, v3
	s_nop 0
	v_cndmask_b32_e32 v3, v3, v4, vcc
	v_sqrt_f32_e32 v4, v3
	s_nop 0
	v_add_u32_e32 v5, -1, v4
	v_fma_f32 v6, -v5, v4, v3
	v_cmp_ge_f32_e64 s[0:1], 0, v6
	v_add_u32_e32 v6, 1, v4
	s_nop 0
	v_cndmask_b32_e64 v5, v4, v5, s[0:1]
	v_fma_f32 v4, -v6, v4, v3
	v_cmp_lt_f32_e64 s[0:1], 0, v4
	s_nop 1
	v_cndmask_b32_e64 v4, v5, v6, s[0:1]
	v_mul_f32_e32 v5, 0x37800000, v4
	v_cndmask_b32_e32 v4, v4, v5, vcc
	v_cmp_class_f32_e32 vcc, v3, v193
	s_nop 1
	v_cndmask_b32_e32 v3, v4, v3, vcc
	v_cmp_ngt_f32_e32 vcc, s24, v0
	s_nop 1
	v_cndmask_b32_e32 v0, 1.0, v3, vcc
	v_mul_f32_e32 v0, v1, v0
	v_mul_f32_e32 v0, v55, v0
	ds_write_b32 v144, v2 offset:4224
	ds_write_b32 v144, v0 offset:41088
	v_add_f32_e32 v0, v25, v36
	v_mul_f32_e32 v0, 0xbfb8aa3b, v0
	v_exp_f32_e32 v0, v0
	v_add_f32_e32 v1, v9, v38
	v_mul_f32_e32 v1, 0xbfb8aa3b, v1
	v_exp_f32_e32 v1, v1
	v_add_f32_e32 v0, 1.0, v0
	v_rcp_f32_e32 v0, v0
	v_add_f32_e32 v1, 1.0, v1
	v_rcp_f32_e32 v1, v1
	v_mul_f32_e32 v0, v0, v32
	v_mul_f32_e32 v2, 0x3fb8aa3b, v0
	v_add_f32_e32 v0, v0, v0
	v_mul_f32_e32 v3, 0x3fb8aa3b, v0
	v_rndne_f32_e32 v3, v3
	v_fmamk_f32 v4, v3, 0xbf317218, v0
	v_fmac_f32_e32 v4, 0x3102e308, v3
	v_fmamk_f32 v5, v4, 0x395133b1, v192
	v_cmp_eq_f32_e32 vcc, s21, v3
	v_cvt_i32_f32_e32 v3, v3
	v_fmaak_f32 v5, v4, v5, 0x3c0887f9
	v_fmaak_f32 v5, v4, v5, 0x3d2aaa81
	v_fmaak_f32 v5, v4, v5, 0x3e2aaaab
	v_fma_f32 v5, v4, v5, 0.5
	v_ldexp_f32 v3, 1.0, v3
	v_mul_f32_e32 v5, v4, v5
	v_cndmask_b32_e32 v3, v3, v202, vcc
	v_fmac_f32_e32 v4, v4, v5
	v_add_f32_e32 v5, -1.0, v3
	v_fmac_f32_e32 v5, v3, v4
	v_add_f32_e32 v3, v5, v5
	v_cndmask_b32_e32 v3, v5, v3, vcc
	v_cmp_nlt_f32_e32 vcc, s22, v0
	v_exp_f32_e32 v2, v2
	s_nop 0
	v_cndmask_b32_e64 v3, v201, -v3, vcc
	v_cmp_gt_f32_e32 vcc, s23, v3
	v_mul_f32_e32 v4, 0x4f800000, v3
	s_nop 0
	v_cndmask_b32_e32 v3, v3, v4, vcc
	v_sqrt_f32_e32 v4, v3
	s_nop 0
	v_add_u32_e32 v5, -1, v4
	v_fma_f32 v6, -v5, v4, v3
	v_cmp_ge_f32_e64 s[0:1], 0, v6
	v_add_u32_e32 v6, 1, v4
	s_nop 0
	v_cndmask_b32_e64 v5, v4, v5, s[0:1]
	v_fma_f32 v4, -v6, v4, v3
	v_cmp_lt_f32_e64 s[0:1], 0, v4
	s_nop 1
	v_cndmask_b32_e64 v4, v5, v6, s[0:1]
	v_mul_f32_e32 v5, 0x37800000, v4
	v_cndmask_b32_e32 v4, v4, v5, vcc
	v_cmp_class_f32_e32 vcc, v3, v193
	s_nop 1
	v_cndmask_b32_e32 v3, v4, v3, vcc
	v_cmp_ngt_f32_e32 vcc, s24, v0
	s_nop 1
	v_cndmask_b32_e32 v0, 1.0, v3, vcc
	v_mul_f32_e32 v0, v1, v0
	v_mul_f32_e32 v0, v41, v0
	ds_write_b32 v144, v2 offset:4480
	ds_write_b32 v144, v0 offset:41344
	v_add_f32_e32 v0, v26, v36
	v_mul_f32_e32 v0, 0xbfb8aa3b, v0
	v_exp_f32_e32 v0, v0
	v_add_f32_e32 v1, v10, v38
	v_mul_f32_e32 v1, 0xbfb8aa3b, v1
	v_exp_f32_e32 v1, v1
	v_add_f32_e32 v0, 1.0, v0
	v_rcp_f32_e32 v0, v0
	v_add_f32_e32 v1, 1.0, v1
	v_rcp_f32_e32 v1, v1
	v_mul_f32_e32 v0, v0, v32
	v_mul_f32_e32 v2, 0x3fb8aa3b, v0
	v_add_f32_e32 v0, v0, v0
	v_mul_f32_e32 v3, 0x3fb8aa3b, v0
	v_rndne_f32_e32 v3, v3
	v_fmamk_f32 v4, v3, 0xbf317218, v0
	v_fmac_f32_e32 v4, 0x3102e308, v3
	v_fmamk_f32 v5, v4, 0x395133b1, v192
	v_cmp_eq_f32_e32 vcc, s21, v3
	v_cvt_i32_f32_e32 v3, v3
	v_fmaak_f32 v5, v4, v5, 0x3c0887f9
	v_fmaak_f32 v5, v4, v5, 0x3d2aaa81
	v_fmaak_f32 v5, v4, v5, 0x3e2aaaab
	v_fma_f32 v5, v4, v5, 0.5
	v_ldexp_f32 v3, 1.0, v3
	v_mul_f32_e32 v5, v4, v5
	v_cndmask_b32_e32 v3, v3, v202, vcc
	v_fmac_f32_e32 v4, v4, v5
	v_add_f32_e32 v5, -1.0, v3
	v_fmac_f32_e32 v5, v3, v4
	v_add_f32_e32 v3, v5, v5
	v_cndmask_b32_e32 v3, v5, v3, vcc
	v_cmp_nlt_f32_e32 vcc, s22, v0
	v_exp_f32_e32 v2, v2
	s_nop 0
	v_cndmask_b32_e64 v3, v201, -v3, vcc
	v_cmp_gt_f32_e32 vcc, s23, v3
	v_mul_f32_e32 v4, 0x4f800000, v3
	s_nop 0
	v_cndmask_b32_e32 v3, v3, v4, vcc
	v_sqrt_f32_e32 v4, v3
	s_nop 0
	v_add_u32_e32 v5, -1, v4
	v_fma_f32 v6, -v5, v4, v3
	v_cmp_ge_f32_e64 s[0:1], 0, v6
	v_add_u32_e32 v6, 1, v4
	s_nop 0
	v_cndmask_b32_e64 v5, v4, v5, s[0:1]
	v_fma_f32 v4, -v6, v4, v3
	v_cmp_lt_f32_e64 s[0:1], 0, v4
	s_nop 1
	v_cndmask_b32_e64 v4, v5, v6, s[0:1]
	v_mul_f32_e32 v5, 0x37800000, v4
	v_cndmask_b32_e32 v4, v4, v5, vcc
	v_cmp_class_f32_e32 vcc, v3, v193
	s_nop 1
	v_cndmask_b32_e32 v3, v4, v3, vcc
	v_cmp_ngt_f32_e32 vcc, s24, v0
	s_nop 1
	v_cndmask_b32_e32 v0, 1.0, v3, vcc
	v_mul_f32_e32 v0, v1, v0
	v_mul_f32_e32 v0, v57, v0
	ds_write_b32 v144, v2 offset:4736
	ds_write_b32 v144, v0 offset:41600
	v_add_f32_e32 v0, v27, v36
	v_mul_f32_e32 v0, 0xbfb8aa3b, v0
	v_exp_f32_e32 v0, v0
	v_add_f32_e32 v1, v11, v38
	v_mul_f32_e32 v1, 0xbfb8aa3b, v1
	v_exp_f32_e32 v1, v1
	v_add_f32_e32 v0, 1.0, v0
	v_rcp_f32_e32 v0, v0
	v_add_f32_e32 v1, 1.0, v1
	v_rcp_f32_e32 v1, v1
	v_mul_f32_e32 v0, v0, v32
	v_mul_f32_e32 v2, 0x3fb8aa3b, v0
	v_add_f32_e32 v0, v0, v0
	v_mul_f32_e32 v3, 0x3fb8aa3b, v0
	v_rndne_f32_e32 v3, v3
	v_fmamk_f32 v4, v3, 0xbf317218, v0
	v_fmac_f32_e32 v4, 0x3102e308, v3
	v_fmamk_f32 v5, v4, 0x395133b1, v192
	v_cmp_eq_f32_e32 vcc, s21, v3
	v_cvt_i32_f32_e32 v3, v3
	v_fmaak_f32 v5, v4, v5, 0x3c0887f9
	v_fmaak_f32 v5, v4, v5, 0x3d2aaa81
	v_fmaak_f32 v5, v4, v5, 0x3e2aaaab
	v_fma_f32 v5, v4, v5, 0.5
	v_ldexp_f32 v3, 1.0, v3
	v_mul_f32_e32 v5, v4, v5
	v_cndmask_b32_e32 v3, v3, v202, vcc
	v_fmac_f32_e32 v4, v4, v5
	v_add_f32_e32 v5, -1.0, v3
	v_fmac_f32_e32 v5, v3, v4
	v_add_f32_e32 v3, v5, v5
	v_cndmask_b32_e32 v3, v5, v3, vcc
	v_cmp_nlt_f32_e32 vcc, s22, v0
	v_exp_f32_e32 v2, v2
	s_nop 0
	v_cndmask_b32_e64 v3, v201, -v3, vcc
	v_cmp_gt_f32_e32 vcc, s23, v3
	v_mul_f32_e32 v4, 0x4f800000, v3
	s_nop 0
	v_cndmask_b32_e32 v3, v3, v4, vcc
	v_sqrt_f32_e32 v4, v3
	s_nop 0
	v_add_u32_e32 v5, -1, v4
	v_fma_f32 v6, -v5, v4, v3
	v_cmp_ge_f32_e64 s[0:1], 0, v6
	v_add_u32_e32 v6, 1, v4
	s_nop 0
	v_cndmask_b32_e64 v5, v4, v5, s[0:1]
	v_fma_f32 v4, -v6, v4, v3
	v_cmp_lt_f32_e64 s[0:1], 0, v4
	s_nop 1
	v_cndmask_b32_e64 v4, v5, v6, s[0:1]
	v_mul_f32_e32 v5, 0x37800000, v4
	v_cndmask_b32_e32 v4, v4, v5, vcc
	v_cmp_class_f32_e32 vcc, v3, v193
	s_nop 1
	v_cndmask_b32_e32 v3, v4, v3, vcc
	v_cmp_ngt_f32_e32 vcc, s24, v0
	s_nop 1
	v_cndmask_b32_e32 v0, 1.0, v3, vcc
	v_mul_f32_e32 v0, v1, v0
	v_mul_f32_e32 v0, v43, v0
	ds_write_b32 v144, v2 offset:4992
	ds_write_b32 v144, v0 offset:41856
	v_add_f32_e32 v0, v28, v36
	v_mul_f32_e32 v0, 0xbfb8aa3b, v0
	v_exp_f32_e32 v0, v0
	v_add_f32_e32 v1, v12, v38
	v_mul_f32_e32 v1, 0xbfb8aa3b, v1
	v_exp_f32_e32 v1, v1
	v_add_f32_e32 v0, 1.0, v0
	v_rcp_f32_e32 v0, v0
	v_add_f32_e32 v1, 1.0, v1
	v_rcp_f32_e32 v1, v1
	v_mul_f32_e32 v0, v0, v32
	v_mul_f32_e32 v2, 0x3fb8aa3b, v0
	v_add_f32_e32 v0, v0, v0
	v_mul_f32_e32 v3, 0x3fb8aa3b, v0
	v_rndne_f32_e32 v3, v3
	v_fmamk_f32 v4, v3, 0xbf317218, v0
	v_fmac_f32_e32 v4, 0x3102e308, v3
	v_fmamk_f32 v5, v4, 0x395133b1, v192
	v_cmp_eq_f32_e32 vcc, s21, v3
	v_cvt_i32_f32_e32 v3, v3
	v_fmaak_f32 v5, v4, v5, 0x3c0887f9
	v_fmaak_f32 v5, v4, v5, 0x3d2aaa81
	v_fmaak_f32 v5, v4, v5, 0x3e2aaaab
	v_fma_f32 v5, v4, v5, 0.5
	v_ldexp_f32 v3, 1.0, v3
	v_mul_f32_e32 v5, v4, v5
	v_cndmask_b32_e32 v3, v3, v202, vcc
	v_fmac_f32_e32 v4, v4, v5
	v_add_f32_e32 v5, -1.0, v3
	v_fmac_f32_e32 v5, v3, v4
	v_add_f32_e32 v3, v5, v5
	v_cndmask_b32_e32 v3, v5, v3, vcc
	v_cmp_nlt_f32_e32 vcc, s22, v0
	v_exp_f32_e32 v2, v2
	s_nop 0
	v_cndmask_b32_e64 v3, v201, -v3, vcc
	v_cmp_gt_f32_e32 vcc, s23, v3
	v_mul_f32_e32 v4, 0x4f800000, v3
	s_nop 0
	v_cndmask_b32_e32 v3, v3, v4, vcc
	v_sqrt_f32_e32 v4, v3
	s_nop 0
	v_add_u32_e32 v5, -1, v4
	v_fma_f32 v6, -v5, v4, v3
	v_cmp_ge_f32_e64 s[0:1], 0, v6
	v_add_u32_e32 v6, 1, v4
	s_nop 0
	v_cndmask_b32_e64 v5, v4, v5, s[0:1]
	v_fma_f32 v4, -v6, v4, v3
	v_cmp_lt_f32_e64 s[0:1], 0, v4
	s_nop 1
	v_cndmask_b32_e64 v4, v5, v6, s[0:1]
	v_mul_f32_e32 v5, 0x37800000, v4
	v_cndmask_b32_e32 v4, v4, v5, vcc
	v_cmp_class_f32_e32 vcc, v3, v193
	s_nop 1
	v_cndmask_b32_e32 v3, v4, v3, vcc
	v_cmp_ngt_f32_e32 vcc, s24, v0
	s_nop 1
	v_cndmask_b32_e32 v0, 1.0, v3, vcc
	v_mul_f32_e32 v0, v1, v0
	v_mul_f32_e32 v0, v59, v0
	ds_write_b32 v144, v2 offset:6272
	ds_write_b32 v144, v0 offset:43136
	v_add_f32_e32 v0, v29, v36
	v_mul_f32_e32 v0, 0xbfb8aa3b, v0
	v_exp_f32_e32 v0, v0
	v_add_f32_e32 v1, v13, v38
	v_mul_f32_e32 v1, 0xbfb8aa3b, v1
	v_exp_f32_e32 v1, v1
	v_add_f32_e32 v0, 1.0, v0
	v_rcp_f32_e32 v0, v0
	v_add_f32_e32 v1, 1.0, v1
	v_rcp_f32_e32 v1, v1
	v_mul_f32_e32 v0, v0, v32
	v_mul_f32_e32 v2, 0x3fb8aa3b, v0
	v_add_f32_e32 v0, v0, v0
	v_mul_f32_e32 v3, 0x3fb8aa3b, v0
	v_rndne_f32_e32 v3, v3
	v_fmamk_f32 v4, v3, 0xbf317218, v0
	v_fmac_f32_e32 v4, 0x3102e308, v3
	v_fmamk_f32 v5, v4, 0x395133b1, v192
	v_cmp_eq_f32_e32 vcc, s21, v3
	v_cvt_i32_f32_e32 v3, v3
	v_fmaak_f32 v5, v4, v5, 0x3c0887f9
	v_fmaak_f32 v5, v4, v5, 0x3d2aaa81
	v_fmaak_f32 v5, v4, v5, 0x3e2aaaab
	v_fma_f32 v5, v4, v5, 0.5
	v_ldexp_f32 v3, 1.0, v3
	v_mul_f32_e32 v5, v4, v5
	v_cndmask_b32_e32 v3, v3, v202, vcc
	v_fmac_f32_e32 v4, v4, v5
	v_add_f32_e32 v5, -1.0, v3
	v_fmac_f32_e32 v5, v3, v4
	v_add_f32_e32 v3, v5, v5
	v_cndmask_b32_e32 v3, v5, v3, vcc
	v_cmp_nlt_f32_e32 vcc, s22, v0
	v_exp_f32_e32 v2, v2
	s_nop 0
	v_cndmask_b32_e64 v3, v201, -v3, vcc
	v_cmp_gt_f32_e32 vcc, s23, v3
	v_mul_f32_e32 v4, 0x4f800000, v3
	s_nop 0
	v_cndmask_b32_e32 v3, v3, v4, vcc
	v_sqrt_f32_e32 v4, v3
	s_nop 0
	v_add_u32_e32 v5, -1, v4
	v_fma_f32 v6, -v5, v4, v3
	v_cmp_ge_f32_e64 s[0:1], 0, v6
	v_add_u32_e32 v6, 1, v4
	s_nop 0
	v_cndmask_b32_e64 v5, v4, v5, s[0:1]
	v_fma_f32 v4, -v6, v4, v3
	v_cmp_lt_f32_e64 s[0:1], 0, v4
	s_nop 1
	v_cndmask_b32_e64 v4, v5, v6, s[0:1]
	v_mul_f32_e32 v5, 0x37800000, v4
	v_cndmask_b32_e32 v4, v4, v5, vcc
	v_cmp_class_f32_e32 vcc, v3, v193
	s_nop 1
	v_cndmask_b32_e32 v3, v4, v3, vcc
	v_cmp_ngt_f32_e32 vcc, s24, v0
	s_nop 1
	v_cndmask_b32_e32 v0, 1.0, v3, vcc
	v_mul_f32_e32 v0, v1, v0
	v_mul_f32_e32 v0, v45, v0
	ds_write_b32 v144, v2 offset:6528
	ds_write_b32 v144, v0 offset:43392
	v_add_f32_e32 v0, v30, v36
	v_mul_f32_e32 v0, 0xbfb8aa3b, v0
	v_exp_f32_e32 v0, v0
	v_add_f32_e32 v1, v14, v38
	v_mul_f32_e32 v1, 0xbfb8aa3b, v1
	v_exp_f32_e32 v1, v1
	v_add_f32_e32 v0, 1.0, v0
	v_rcp_f32_e32 v0, v0
	v_add_f32_e32 v1, 1.0, v1
	v_rcp_f32_e32 v1, v1
	v_mul_f32_e32 v0, v0, v32
	v_mul_f32_e32 v2, 0x3fb8aa3b, v0
	v_add_f32_e32 v0, v0, v0
	v_mul_f32_e32 v3, 0x3fb8aa3b, v0
	v_rndne_f32_e32 v3, v3
	v_fmamk_f32 v4, v3, 0xbf317218, v0
	v_fmac_f32_e32 v4, 0x3102e308, v3
	v_fmamk_f32 v5, v4, 0x395133b1, v192
	v_cmp_eq_f32_e32 vcc, s21, v3
	v_cvt_i32_f32_e32 v3, v3
	v_fmaak_f32 v5, v4, v5, 0x3c0887f9
	v_fmaak_f32 v5, v4, v5, 0x3d2aaa81
	v_fmaak_f32 v5, v4, v5, 0x3e2aaaab
	v_fma_f32 v5, v4, v5, 0.5
	v_ldexp_f32 v3, 1.0, v3
	v_mul_f32_e32 v5, v4, v5
	v_cndmask_b32_e32 v3, v3, v202, vcc
	v_fmac_f32_e32 v4, v4, v5
	v_add_f32_e32 v5, -1.0, v3
	v_fmac_f32_e32 v5, v3, v4
	v_add_f32_e32 v3, v5, v5
	v_cndmask_b32_e32 v3, v5, v3, vcc
	v_cmp_nlt_f32_e32 vcc, s22, v0
	v_exp_f32_e32 v2, v2
	s_nop 0
	v_cndmask_b32_e64 v3, v201, -v3, vcc
	v_cmp_gt_f32_e32 vcc, s23, v3
	v_mul_f32_e32 v4, 0x4f800000, v3
	s_nop 0
	v_cndmask_b32_e32 v3, v3, v4, vcc
	v_sqrt_f32_e32 v4, v3
	s_nop 0
	v_add_u32_e32 v5, -1, v4
	v_fma_f32 v6, -v5, v4, v3
	v_cmp_ge_f32_e64 s[0:1], 0, v6
	v_add_u32_e32 v6, 1, v4
	s_nop 0
	v_cndmask_b32_e64 v5, v4, v5, s[0:1]
	v_fma_f32 v4, -v6, v4, v3
	v_cmp_lt_f32_e64 s[0:1], 0, v4
	s_nop 1
	v_cndmask_b32_e64 v4, v5, v6, s[0:1]
	v_mul_f32_e32 v5, 0x37800000, v4
	v_cndmask_b32_e32 v4, v4, v5, vcc
	v_cmp_class_f32_e32 vcc, v3, v193
	s_nop 1
	v_cndmask_b32_e32 v3, v4, v3, vcc
	v_cmp_ngt_f32_e32 vcc, s24, v0
	s_nop 1
	v_cndmask_b32_e32 v0, 1.0, v3, vcc
	v_mul_f32_e32 v0, v1, v0
	v_mul_f32_e32 v0, v35, v0
	v_add_u32_e32 v1, 0x1800, v144
	ds_write2_b32 v1, v2, v34 offset0:160 offset1:192
	ds_write_b32 v144, v0 offset:43648
	v_add_f32_e32 v0, v31, v36
	v_mul_f32_e32 v0, 0xbfb8aa3b, v0
	v_exp_f32_e32 v0, v0
	v_add_f32_e32 v1, v15, v38
	v_mul_f32_e32 v1, 0xbfb8aa3b, v1
	v_exp_f32_e32 v1, v1
	v_add_f32_e32 v0, 1.0, v0
	v_rcp_f32_e32 v0, v0
	v_add_f32_e32 v1, 1.0, v1
	v_rcp_f32_e32 v1, v1
	v_mul_f32_e32 v0, v0, v32
	v_mul_f32_e32 v2, 0x3fb8aa3b, v0
	v_add_f32_e32 v0, v0, v0
	v_mul_f32_e32 v3, 0x3fb8aa3b, v0
	v_rndne_f32_e32 v3, v3
	v_fmamk_f32 v4, v3, 0xbf317218, v0
	v_fmac_f32_e32 v4, 0x3102e308, v3
	v_fmamk_f32 v5, v4, 0x395133b1, v192
	v_cmp_eq_f32_e32 vcc, s21, v3
	v_cvt_i32_f32_e32 v3, v3
	v_fmaak_f32 v5, v4, v5, 0x3c0887f9
	v_fmaak_f32 v5, v4, v5, 0x3d2aaa81
	v_fmaak_f32 v5, v4, v5, 0x3e2aaaab
	v_fma_f32 v5, v4, v5, 0.5
	v_ldexp_f32 v3, 1.0, v3
	v_mul_f32_e32 v5, v4, v5
	v_cndmask_b32_e32 v3, v3, v202, vcc
	v_fmac_f32_e32 v4, v4, v5
	v_add_f32_e32 v5, -1.0, v3
	v_fmac_f32_e32 v5, v3, v4
	v_add_f32_e32 v3, v5, v5
	v_cndmask_b32_e32 v3, v5, v3, vcc
	v_cmp_nlt_f32_e32 vcc, s22, v0
	v_exp_f32_e32 v2, v2
	s_mov_b32 s21, 0x84000
	v_cndmask_b32_e64 v3, v201, -v3, vcc
	v_cmp_gt_f32_e32 vcc, s23, v3
	v_mul_f32_e32 v4, 0x4f800000, v3
	s_mov_b32 s22, 0x2d000
	v_cndmask_b32_e32 v3, v3, v4, vcc
	v_sqrt_f32_e32 v4, v3
	s_mov_b32 s23, 0x59000
	v_add_u32_e32 v5, -1, v4
	v_fma_f32 v6, -v5, v4, v3
	v_cmp_ge_f32_e64 s[0:1], 0, v6
	v_add_u32_e32 v6, 1, v4
	s_nop 0
	v_cndmask_b32_e64 v5, v4, v5, s[0:1]
	v_fma_f32 v4, -v6, v4, v3
	v_cmp_lt_f32_e64 s[0:1], 0, v4
	s_nop 1
	v_cndmask_b32_e64 v4, v5, v6, s[0:1]
	v_mul_f32_e32 v5, 0x37800000, v4
	v_cndmask_b32_e32 v4, v4, v5, vcc
	v_cmp_class_f32_e32 vcc, v3, v193
	v_mov_b32_e32 v5, 0
	s_nop 0
	v_cndmask_b32_e32 v3, v4, v3, vcc
	v_cmp_ngt_f32_e32 vcc, s24, v0
	v_readlane_b32 s24, v248, 7
	s_nop 0
	v_cndmask_b32_e32 v0, 1.0, v3, vcc
	v_mul_f32_e32 v0, v1, v0
	v_mul_f32_e32 v0, v33, v0
	ds_write_b32 v144, v2 offset:7040
	ds_write_b32 v144, v0 offset:43904
	v_mov_b32_e32 v0, 0
	s_waitcnt lgkmcnt(0)
	s_barrier
	s_cbranch_scc1 .LBB0_915
	v_lshl_add_u64 v[2:3], v[64:65], 0, s[4:5]
	v_add_co_u32_e32 v4, vcc, 0x13000, v2
	s_sub_i32 s0, s2, s12
	s_nop 0
	v_addc_co_u32_e32 v5, vcc, 0, v3, vcc
	global_load_dwordx2 v[4:5], v[4:5], off
	s_cmp_eq_u32 s0, 1
	s_waitcnt vmcnt(0)
	v_fmac_f32_e32 v5, 0, v4
	s_cbranch_scc1 .LBB0_915
	v_add_co_u32_e32 v2, vcc, 0x12000, v2
	s_cmp_eq_u32 s0, 2
	s_nop 0
	v_addc_co_u32_e32 v3, vcc, 0, v3, vcc
	global_load_dwordx2 v[2:3], v[2:3], off
	s_waitcnt vmcnt(0)
	v_fmac_f32_e32 v3, v5, v2
	s_cbranch_scc1 .LBB0_914
	s_mul_i32 s1, s11, 36
	s_add_i32 s2, s1, 36
	s_ashr_i32 s3, s2, 31
	s_lshl_b64 s[2:3], s[2:3], 12
	v_readlane_b32 s1, v249, 47
	s_add_u32 s2, s1, s2
	v_readlane_b32 s1, v249, 48
	v_add_lshl_u32 v96, s13, v141, 3
	s_addc_u32 s3, s1, s3
	v_lshl_add_u64 v[4:5], s[2:3], 0, v[96:97]
	s_add_i32 s0, s0, -2

.LBB0_947:
	s_or_b64 exec, exec, s[0:1]
	v_add_f32_e32 v0, 0, v110
	v_add_f32_e32 v0, v0, v111
	v_add_f32_e32 v0, v0, v109
	v_cvt_pk_bf16_f32 v110, v110, v111
	v_cvt_pk_bf16_f32 v111, v109, v112
	v_xor_b32_e32 v109, 16, v105
	v_cmp_lt_i32_e64 s[0:1], v109, v106
	v_add_f32_e32 v118, v0, v112
	v_lshl_add_u32 v113, v99, 3, 0
	v_cndmask_b32_e64 v109, v105, v109, s[0:1]
	v_lshlrev_b32_e32 v229, 2, v109
	v_mul_lo_u32 v0, v100, s87
	v_mov_b32_e32 v109, v118
	v_mov_b32_e32 v255, v118
	s_nop 1
	v_permlane16_swap_b32_e32 v109, v255
	v_add_u32_e32 v0, v113, v0
	ds_write_b64 v0, v[110:111] offset:34816
	v_xor_b32_e32 v110, 8, v105
	v_cmp_lt_i32_e64 s[0:1], v110, v106
	s_waitcnt lgkmcnt(1)
	v_add_f32_e32 v109, v109, v255
	v_cmp_eq_u32_e32 vcc, 0, v99
	v_cndmask_b32_e64 v110, v105, v110, s[0:1]
	v_lshlrev_b32_e32 v230, 2, v110
	s_waitcnt lgkmcnt(0)
	v_add_f32_dpp v109, v109, v109 row_ror:8 row_mask:0xf bank_mask:0xf
	v_xor_b32_e32 v110, 4, v105
	v_cmp_lt_i32_e64 s[0:1], v110, v106
	s_nop 1
	v_cndmask_b32_e64 v110, v105, v110, s[0:1]
	v_lshlrev_b32_e32 v231, 2, v110
	v_mov_b32_dpp v110, v109 row_shl:4 row_mask:0xf bank_mask:0x5
	v_mov_b32_dpp v110, v109 row_shr:4 row_mask:0xf bank_mask:0xa
	v_add_f32_e32 v109, v109, v110
	v_xor_b32_e32 v110, 2, v105
	v_cmp_lt_i32_e64 s[0:1], v110, v106
	s_nop 1
	v_cndmask_b32_e64 v110, v105, v110, s[0:1]
	v_lshlrev_b32_e32 v232, 2, v110
	v_add_f32_dpp v109, v109, v109 quad_perm:[2,3,0,1] row_mask:0xf bank_mask:0xf
	v_xor_b32_e32 v110, 1, v105
	v_cmp_lt_i32_e64 s[0:1], v110, v106
	s_nop 1
	v_cndmask_b32_e64 v105, v105, v110, s[0:1]
	v_lshlrev_b32_e32 v233, 2, v105
	v_mov_b32_dpp v105, v109 quad_perm:[1,0,3,2] row_mask:0xf bank_mask:0xf
	s_and_saveexec_b64 s[0:1], vcc
	s_cbranch_execz .LBB0_949
	v_add_f32_e32 v105, v109, v105
	s_waitcnt vmcnt(0)
	v_sub_f32_e32 v106, v96, v108
	v_add_u32_e32 v109, 0x11c00, v107
	v_mul_f32_e32 v106, 0x3fb8aa3b, v106
	ds_read_b32 v109, v109
	v_exp_f32_e32 v106, v106
	s_waitcnt lgkmcnt(0)
	v_fmac_f32_e32 v105, v106, v109
	v_add_u32_e32 v109, 0x11e00, v107
	ds_write_b32 v109, v105
	v_add_u32_e32 v105, 0x12000, v107
	ds_write_b32 v105, v106
	v_add_u32_e32 v105, 0x11800, v107
	ds_read_b32 v105, v105
	v_add_u32_e32 v106, 0x12200, v107
	s_waitcnt lgkmcnt(0)
	v_add_f32_e32 v105, v108, v105
	v_mul_f32_e32 v105, 0xbfb8aa3b, v105
	v_exp_f32_e32 v105, v105
	ds_write_b32 v106, v105

.LBB0_957:
	s_or_b64 exec, exec, s[68:69]
	v_add_f32_e32 v1, 0, v108
	v_add_f32_e32 v1, v1, v107
	v_add_f32_e32 v1, v1, v49
	v_add_f32_e32 v1, v1, v33
	v_mov_b32_e32 v17, v1
	v_mov_b32_e32 v255, v1
	s_nop 1
	v_permlane16_swap_b32_e32 v17, v255
	s_nop 1
	v_mov_b32_dpp v17, v255 quad_perm:[0,1,2,3] row_mask:0x5 bank_mask:0xf
	v_cvt_pk_bf16_f32 v108, v108, v107
	v_cvt_pk_bf16_f32 v109, v49, v33
	ds_write_b64 v0, v[108:109] offset:35088
	s_waitcnt lgkmcnt(1)
	v_add_f32_e32 v1, v1, v17
	s_nop 1
	v_mov_b32_dpp v17, v1 row_ror:8 row_mask:0xf bank_mask:0xf
	s_waitcnt lgkmcnt(0)
	v_add_f32_e32 v1, v1, v17
	s_nop 1
	v_mov_b32_dpp v17, v1 row_shl:4 row_mask:0xf bank_mask:0x5
	v_mov_b32_dpp v17, v1 row_shr:4 row_mask:0xf bank_mask:0xa
	s_nop 0
	v_add_f32_e32 v1, v1, v17
	s_nop 1
	v_mov_b32_dpp v17, v1 quad_perm:[2,3,0,1] row_mask:0xf bank_mask:0xf
	s_nop 0
	v_add_f32_e32 v1, v1, v17
	s_nop 1
	v_mov_b32_dpp v17, v1 quad_perm:[1,0,3,2] row_mask:0xf bank_mask:0xf
	s_and_saveexec_b64 s[0:1], vcc
	s_cbranch_execz .LBB0_959
	v_add_f32_e32 v1, v1, v17
	s_waitcnt vmcnt(0)
	v_sub_f32_e32 v17, v96, v106
	v_add_u32_e32 v33, 0x11c00, v105
	v_mul_f32_e32 v17, 0x3fb8aa3b, v17
	ds_read_b32 v33, v33
	v_exp_f32_e32 v17, v17
	s_waitcnt lgkmcnt(0)
	v_fmac_f32_e32 v1, v17, v33
	v_add_u32_e32 v33, 0x11e00, v105
	ds_write_b32 v33, v1
	v_add_u32_e32 v1, 0x12000, v105
	ds_write_b32 v1, v17
	v_add_u32_e32 v1, 0x11800, v105
	ds_read_b32 v1, v1
	v_add_u32_e32 v17, 0x12200, v105
	s_waitcnt lgkmcnt(0)
	v_add_f32_e32 v1, v106, v1
	v_mul_f32_e32 v1, 0xbfb8aa3b, v1
	v_exp_f32_e32 v1, v1
	ds_write_b32 v17, v1

.LBB0_967:
	s_or_b64 exec, exec, s[68:69]
	v_add_f32_e32 v2, 0, v49
	v_add_f32_e32 v2, v2, v33
	v_add_f32_e32 v2, v2, v50
	v_add_f32_e32 v2, v2, v34
	v_mov_b32_e32 v18, v2
	v_mov_b32_e32 v255, v2
	s_nop 1
	v_permlane16_swap_b32_e32 v18, v255
	s_nop 1
	v_mov_b32_dpp v18, v255 quad_perm:[0,1,2,3] row_mask:0x5 bank_mask:0xf
	v_cvt_pk_bf16_f32 v106, v49, v33
	v_cvt_pk_bf16_f32 v107, v50, v34
	ds_write_b64 v0, v[106:107] offset:35360
	s_waitcnt lgkmcnt(1)
	v_add_f32_e32 v2, v2, v18
	s_nop 1
	v_mov_b32_dpp v18, v2 row_ror:8 row_mask:0xf bank_mask:0xf
	s_waitcnt lgkmcnt(0)
	v_add_f32_e32 v2, v2, v18
	s_nop 1
	v_mov_b32_dpp v18, v2 row_shl:4 row_mask:0xf bank_mask:0x5
	v_mov_b32_dpp v18, v2 row_shr:4 row_mask:0xf bank_mask:0xa
	s_nop 0
	v_add_f32_e32 v2, v2, v18
	s_nop 1
	v_mov_b32_dpp v18, v2 quad_perm:[2,3,0,1] row_mask:0xf bank_mask:0xf
	s_nop 0
	v_add_f32_e32 v2, v2, v18
	s_nop 1
	v_mov_b32_dpp v18, v2 quad_perm:[1,0,3,2] row_mask:0xf bank_mask:0xf
	s_and_saveexec_b64 s[0:1], vcc
	s_cbranch_execz .LBB0_969
	v_add_f32_e32 v2, v2, v18
	s_waitcnt vmcnt(0)
	v_sub_f32_e32 v18, v96, v17
	v_add_u32_e32 v33, 0x11c00, v1
	v_mul_f32_e32 v18, 0x3fb8aa3b, v18
	ds_read_b32 v33, v33
	v_exp_f32_e32 v18, v18
	s_waitcnt lgkmcnt(0)
	v_fmac_f32_e32 v2, v18, v33
	v_add_u32_e32 v33, 0x11e00, v1
	ds_write_b32 v33, v2
	v_add_u32_e32 v2, 0x12000, v1
	ds_write_b32 v2, v18
	v_add_u32_e32 v2, 0x11800, v1
	ds_read_b32 v2, v2
	v_add_u32_e32 v1, 0x12200, v1
	s_waitcnt lgkmcnt(0)
	v_add_f32_e32 v2, v17, v2
	v_mul_f32_e32 v2, 0xbfb8aa3b, v2
	v_exp_f32_e32 v2, v2
	ds_write_b32 v1, v2

.LBB0_977:
	s_or_b64 exec, exec, s[68:69]
	v_add_f32_e32 v3, 0, v18
	v_add_f32_e32 v3, v3, v17
	v_add_f32_e32 v3, v3, v35
	v_add_f32_e32 v3, v3, v34
	v_cvt_pk_bf16_f32 v18, v18, v17
	v_mov_b32_e32 v17, v3
	v_mov_b32_e32 v255, v3
	s_nop 1
	v_permlane16_swap_b32_e32 v17, v255
	s_nop 1
	v_mov_b32_dpp v17, v255 quad_perm:[0,1,2,3] row_mask:0x5 bank_mask:0xf
	v_cvt_pk_bf16_f32 v19, v35, v34
	ds_write_b64 v0, v[18:19] offset:35632
	s_waitcnt lgkmcnt(1)
	v_add_f32_e32 v3, v3, v17
	s_nop 1
	v_mov_b32_dpp v17, v3 row_ror:8 row_mask:0xf bank_mask:0xf
	s_waitcnt lgkmcnt(0)
	v_add_f32_e32 v3, v3, v17
	s_nop 1
	v_mov_b32_dpp v17, v3 row_shl:4 row_mask:0xf bank_mask:0x5
	v_mov_b32_dpp v17, v3 row_shr:4 row_mask:0xf bank_mask:0xa
	s_nop 0
	v_add_f32_e32 v3, v3, v17
	s_nop 1
	v_mov_b32_dpp v17, v3 quad_perm:[2,3,0,1] row_mask:0xf bank_mask:0xf
	s_nop 0
	v_add_f32_e32 v3, v3, v17
	s_nop 1
	v_mov_b32_dpp v17, v3 quad_perm:[1,0,3,2] row_mask:0xf bank_mask:0xf
	s_and_saveexec_b64 s[0:1], vcc
	s_cbranch_execz .LBB0_979
	v_add_f32_e32 v3, v3, v17
	s_waitcnt vmcnt(0)
	v_sub_f32_e32 v17, v96, v2
	v_add_u32_e32 v18, 0x11c00, v1
	v_mul_f32_e32 v17, 0x3fb8aa3b, v17
	ds_read_b32 v18, v18
	v_exp_f32_e32 v17, v17
	s_waitcnt lgkmcnt(0)
	v_fmac_f32_e32 v3, v17, v18
	v_add_u32_e32 v18, 0x11e00, v1
	ds_write_b32 v18, v3
	v_add_u32_e32 v3, 0x12000, v1
	ds_write_b32 v3, v17
	v_add_u32_e32 v3, 0x11800, v1
	ds_read_b32 v3, v3
	v_add_u32_e32 v1, 0x12200, v1
	s_waitcnt lgkmcnt(0)
	v_add_f32_e32 v2, v2, v3
	v_mul_f32_e32 v2, 0xbfb8aa3b, v2
	v_exp_f32_e32 v2, v2
	ds_write_b32 v1, v2

.LBB0_987:
	s_or_b64 exec, exec, s[68:69]
	v_add_f32_e32 v4, 0, v17
	v_add_f32_e32 v4, v4, v3
	v_add_f32_e32 v4, v4, v19
	v_add_f32_e32 v4, v4, v18
	v_cvt_pk_bf16_f32 v34, v17, v3
	v_mov_b32_e32 v3, v4
	v_mov_b32_e32 v255, v4
	s_nop 1
	v_permlane16_swap_b32_e32 v3, v255
	v_cvt_pk_bf16_f32 v35, v19, v18
	ds_write_b64 v0, v[34:35] offset:36992
	s_waitcnt lgkmcnt(1)
	v_add_f32_e32 v3, v3, v255
	s_nop 1
	v_mov_b32_dpp v4, v3 row_ror:8 row_mask:0xf bank_mask:0xf
	s_waitcnt lgkmcnt(0)
	v_add_f32_e32 v3, v3, v4
	s_nop 1
	v_mov_b32_dpp v4, v3 row_shl:4 row_mask:0xf bank_mask:0x5
	v_mov_b32_dpp v4, v3 row_shr:4 row_mask:0xf bank_mask:0xa
	s_nop 0
	v_add_f32_e32 v3, v3, v4
	s_nop 1
	v_mov_b32_dpp v4, v3 quad_perm:[2,3,0,1] row_mask:0xf bank_mask:0xf
	s_nop 0
	v_add_f32_e32 v3, v3, v4
	s_nop 1
	v_mov_b32_dpp v4, v3 quad_perm:[1,0,3,2] row_mask:0xf bank_mask:0xf
	s_and_saveexec_b64 s[0:1], vcc
	s_cbranch_execz .LBB0_989
	v_lshl_add_u32 v2, v2, 2, 0
	v_add_f32_e32 v3, v3, v4
	s_waitcnt vmcnt(0)
	v_sub_f32_e32 v4, v96, v1
	v_add_u32_e32 v17, 0x11c00, v2
	v_mul_f32_e32 v4, 0x3fb8aa3b, v4
	ds_read_b32 v17, v17
	v_exp_f32_e32 v4, v4
	s_waitcnt lgkmcnt(0)
	v_fmac_f32_e32 v3, v4, v17
	v_add_u32_e32 v17, 0x11e00, v2
	ds_write_b32 v17, v3
	v_add_u32_e32 v3, 0x12000, v2
	ds_write_b32 v3, v4
	v_add_u32_e32 v3, 0x11800, v2
	ds_read_b32 v3, v3
	v_add_u32_e32 v2, 0x12200, v2
	s_waitcnt lgkmcnt(0)
	v_add_f32_e32 v1, v1, v3
	v_mul_f32_e32 v1, 0xbfb8aa3b, v1
	v_exp_f32_e32 v1, v1
	ds_write_b32 v2, v1

.LBB0_997:
	s_or_b64 exec, exec, s[68:69]
	v_add_f32_e32 v5, 0, v4
	v_add_f32_e32 v5, v5, v3
	v_add_f32_e32 v5, v5, v18
	v_add_f32_e32 v19, v5, v17
	v_cvt_pk_bf16_f32 v4, v4, v3
	v_mov_b32_e32 v3, v19
	v_mov_b32_e32 v255, v19
	s_nop 1
	v_permlane16_swap_b32_e32 v3, v255
	v_cvt_pk_bf16_f32 v5, v18, v17
	ds_write_b64 v0, v[4:5] offset:37264
	s_waitcnt lgkmcnt(1)
	v_add_f32_e32 v3, v3, v255
	s_nop 1
	v_mov_b32_dpp v4, v3 row_ror:8 row_mask:0xf bank_mask:0xf
	s_waitcnt lgkmcnt(0)
	v_add_f32_e32 v3, v3, v4
	s_nop 1
	v_mov_b32_dpp v4, v3 row_shl:4 row_mask:0xf bank_mask:0x5
	v_mov_b32_dpp v4, v3 row_shr:4 row_mask:0xf bank_mask:0xa
	s_nop 0
	v_add_f32_e32 v3, v3, v4
	s_nop 1
	v_mov_b32_dpp v4, v3 quad_perm:[2,3,0,1] row_mask:0xf bank_mask:0xf
	s_nop 0
	v_add_f32_e32 v3, v3, v4
	s_nop 1
	v_mov_b32_dpp v4, v3 quad_perm:[1,0,3,2] row_mask:0xf bank_mask:0xf
	s_and_saveexec_b64 s[0:1], vcc
	s_cbranch_execz .LBB0_999
	v_lshl_add_u32 v2, v2, 2, 0
	v_add_f32_e32 v3, v3, v4
	s_waitcnt vmcnt(0)
	v_sub_f32_e32 v4, v96, v1
	v_add_u32_e32 v5, 0x11c00, v2
	v_mul_f32_e32 v4, 0x3fb8aa3b, v4
	ds_read_b32 v5, v5
	v_exp_f32_e32 v4, v4
	s_waitcnt lgkmcnt(0)
	v_fmac_f32_e32 v3, v4, v5
	v_add_u32_e32 v5, 0x11e00, v2
	ds_write_b32 v5, v3
	v_add_u32_e32 v3, 0x12000, v2
	ds_write_b32 v3, v4
	v_add_u32_e32 v3, 0x11800, v2
	ds_read_b32 v3, v3
	v_add_u32_e32 v2, 0x12200, v2
	s_waitcnt lgkmcnt(0)
	v_add_f32_e32 v1, v1, v3
	v_mul_f32_e32 v1, 0xbfb8aa3b, v1
	v_exp_f32_e32 v1, v1
	ds_write_b32 v2, v1

.LBB0_1007:
	s_or_b64 exec, exec, s[68:69]
	v_add_f32_e32 v6, 0, v4
	v_add_f32_e32 v6, v6, v3
	v_add_f32_e32 v6, v6, v17
	v_add_f32_e32 v6, v6, v5
	v_cvt_pk_bf16_f32 v4, v4, v3
	v_mov_b32_e32 v3, v6
	v_mov_b32_e32 v255, v6
	s_nop 1
	v_permlane16_swap_b32_e32 v3, v255
	v_cvt_pk_bf16_f32 v5, v17, v5
	ds_write_b64 v0, v[4:5] offset:37536
	s_waitcnt lgkmcnt(1)
	v_add_f32_e32 v3, v3, v255
	s_nop 1
	v_mov_b32_dpp v4, v3 row_ror:8 row_mask:0xf bank_mask:0xf
	s_waitcnt lgkmcnt(0)
	v_add_f32_e32 v3, v3, v4
	s_nop 1
	v_mov_b32_dpp v4, v3 row_shl:4 row_mask:0xf bank_mask:0x5
	v_mov_b32_dpp v4, v3 row_shr:4 row_mask:0xf bank_mask:0xa
	s_nop 0
	v_add_f32_e32 v3, v3, v4
	s_nop 1
	v_mov_b32_dpp v4, v3 quad_perm:[2,3,0,1] row_mask:0xf bank_mask:0xf
	s_nop 0
	v_add_f32_e32 v3, v3, v4
	s_nop 1
	v_mov_b32_dpp v4, v3 quad_perm:[1,0,3,2] row_mask:0xf bank_mask:0xf
	s_and_saveexec_b64 s[0:1], vcc
	s_cbranch_execz .LBB0_1009
	v_lshl_add_u32 v2, v2, 2, 0
	v_add_f32_e32 v3, v3, v4
	s_waitcnt vmcnt(0)
	v_sub_f32_e32 v4, v96, v1
	v_add_u32_e32 v5, 0x11c00, v2
	v_mul_f32_e32 v4, 0x3fb8aa3b, v4
	ds_read_b32 v5, v5
	v_exp_f32_e32 v4, v4
	s_waitcnt lgkmcnt(0)
	v_fmac_f32_e32 v3, v4, v5
	v_add_u32_e32 v5, 0x11e00, v2
	ds_write_b32 v5, v3
	v_add_u32_e32 v3, 0x12000, v2
	ds_write_b32 v3, v4
	v_add_u32_e32 v3, 0x11800, v2
	ds_read_b32 v3, v3
	v_add_u32_e32 v2, 0x12200, v2
	s_waitcnt lgkmcnt(0)
	v_add_f32_e32 v1, v1, v3
	v_mul_f32_e32 v1, 0xbfb8aa3b, v1
	v_exp_f32_e32 v1, v1
	ds_write_b32 v2, v1

.LBB0_1017:
	s_or_b64 exec, exec, s[68:69]
	v_add_f32_e32 v7, 0, v4
	v_add_f32_e32 v7, v7, v3
	v_add_f32_e32 v7, v7, v6
	v_add_f32_e32 v7, v7, v5
	v_cvt_pk_bf16_f32 v4, v4, v3
	v_mov_b32_e32 v3, v7
	v_mov_b32_e32 v255, v7
	s_nop 1
	v_permlane16_swap_b32_e32 v3, v255
	v_cvt_pk_bf16_f32 v5, v6, v5
	ds_write_b64 v0, v[4:5] offset:37808
	s_waitcnt lgkmcnt(1)
	v_add_f32_e32 v3, v3, v255
	s_nop 1
	v_mov_b32_dpp v4, v3 row_ror:8 row_mask:0xf bank_mask:0xf
	s_waitcnt lgkmcnt(0)
	v_add_f32_e32 v3, v3, v4
	s_nop 1
	v_mov_b32_dpp v4, v3 row_shl:4 row_mask:0xf bank_mask:0x5
	v_mov_b32_dpp v4, v3 row_shr:4 row_mask:0xf bank_mask:0xa
	s_nop 0
	v_add_f32_e32 v3, v3, v4
	s_nop 1
	v_mov_b32_dpp v4, v3 quad_perm:[2,3,0,1] row_mask:0xf bank_mask:0xf
	s_nop 0
	v_add_f32_e32 v3, v3, v4
	s_nop 1
	v_mov_b32_dpp v4, v3 quad_perm:[1,0,3,2] row_mask:0xf bank_mask:0xf
	s_and_saveexec_b64 s[0:1], vcc
	s_cbranch_execz .LBB0_1019
	v_lshl_add_u32 v2, v2, 2, 0
	v_add_f32_e32 v3, v3, v4
	s_waitcnt vmcnt(0)
	v_sub_f32_e32 v4, v96, v1
	v_add_u32_e32 v5, 0x11c00, v2
	v_mul_f32_e32 v4, 0x3fb8aa3b, v4
	ds_read_b32 v5, v5
	v_exp_f32_e32 v4, v4
	s_waitcnt lgkmcnt(0)
	v_fmac_f32_e32 v3, v4, v5
	v_add_u32_e32 v5, 0x11e00, v2
	ds_write_b32 v5, v3
	v_add_u32_e32 v3, 0x12000, v2
	ds_write_b32 v3, v4
	v_add_u32_e32 v3, 0x11800, v2
	ds_read_b32 v3, v3
	v_add_u32_e32 v2, 0x12200, v2
	s_waitcnt lgkmcnt(0)
	v_add_f32_e32 v1, v1, v3
	v_mul_f32_e32 v1, 0xbfb8aa3b, v1
	v_exp_f32_e32 v1, v1
	ds_write_b32 v2, v1

.LBB0_1027:
	s_or_b64 exec, exec, s[68:69]
	v_add_f32_e32 v7, 0, v4
	v_add_f32_e32 v7, v7, v3
	v_add_f32_e32 v7, v7, v6
	v_add_f32_e32 v7, v7, v5
	v_cvt_pk_bf16_f32 v4, v4, v3
	v_mov_b32_e32 v3, v7
	v_mov_b32_e32 v255, v7
	s_nop 1
	v_permlane16_swap_b32_e32 v3, v255
	v_cvt_pk_bf16_f32 v5, v6, v5
	ds_write_b64 v0, v[4:5] offset:39168
	s_waitcnt lgkmcnt(1)
	v_add_f32_e32 v3, v3, v255
	s_nop 1
	v_mov_b32_dpp v4, v3 row_ror:8 row_mask:0xf bank_mask:0xf
	s_waitcnt lgkmcnt(0)
	v_add_f32_e32 v3, v3, v4
	s_nop 1
	v_mov_b32_dpp v4, v3 row_shl:4 row_mask:0xf bank_mask:0x5
	v_mov_b32_dpp v4, v3 row_shr:4 row_mask:0xf bank_mask:0xa
	s_nop 0
	v_add_f32_e32 v3, v3, v4
	s_nop 1
	v_mov_b32_dpp v4, v3 quad_perm:[2,3,0,1] row_mask:0xf bank_mask:0xf
	s_nop 0
	v_add_f32_e32 v3, v3, v4
	s_nop 1
	v_mov_b32_dpp v4, v3 quad_perm:[1,0,3,2] row_mask:0xf bank_mask:0xf
	s_and_saveexec_b64 s[0:1], vcc
	s_cbranch_execz .LBB0_1029
	v_lshl_add_u32 v2, v2, 2, 0
	v_add_f32_e32 v3, v3, v4
	s_waitcnt vmcnt(0)
	v_sub_f32_e32 v4, v96, v1
	v_add_u32_e32 v5, 0x11c00, v2
	v_mul_f32_e32 v4, 0x3fb8aa3b, v4
	ds_read_b32 v5, v5
	v_exp_f32_e32 v4, v4
	s_waitcnt lgkmcnt(0)
	v_fmac_f32_e32 v3, v4, v5
	v_add_u32_e32 v5, 0x11e00, v2
	ds_write_b32 v5, v3
	v_add_u32_e32 v3, 0x12000, v2
	ds_write_b32 v3, v4
	v_add_u32_e32 v3, 0x11800, v2
	ds_read_b32 v3, v3
	v_add_u32_e32 v2, 0x12200, v2
	s_waitcnt lgkmcnt(0)
	v_add_f32_e32 v1, v1, v3
	v_mul_f32_e32 v1, 0xbfb8aa3b, v1
	v_exp_f32_e32 v1, v1
	ds_write_b32 v2, v1

.LBB0_1037:
	s_or_b64 exec, exec, s[68:69]
	v_add_f32_e32 v7, 0, v4
	v_add_f32_e32 v7, v7, v3
	v_add_f32_e32 v7, v7, v6
	v_add_f32_e32 v7, v7, v5
	v_cvt_pk_bf16_f32 v4, v4, v3
	v_mov_b32_e32 v3, v7
	v_mov_b32_e32 v255, v7
	s_nop 1
	v_permlane16_swap_b32_e32 v3, v255
	v_cvt_pk_bf16_f32 v5, v6, v5
	ds_write_b64 v0, v[4:5] offset:39440
	s_waitcnt lgkmcnt(1)
	v_add_f32_e32 v3, v3, v255
	s_nop 1
	v_mov_b32_dpp v4, v3 row_ror:8 row_mask:0xf bank_mask:0xf
	s_waitcnt lgkmcnt(0)
	v_add_f32_e32 v3, v3, v4
	s_nop 1
	v_mov_b32_dpp v4, v3 row_shl:4 row_mask:0xf bank_mask:0x5
	v_mov_b32_dpp v4, v3 row_shr:4 row_mask:0xf bank_mask:0xa
	s_nop 0
	v_add_f32_e32 v3, v3, v4
	s_nop 1
	v_mov_b32_dpp v4, v3 quad_perm:[2,3,0,1] row_mask:0xf bank_mask:0xf
	s_nop 0
	v_add_f32_e32 v3, v3, v4
	s_nop 1
	v_mov_b32_dpp v4, v3 quad_perm:[1,0,3,2] row_mask:0xf bank_mask:0xf
	s_and_saveexec_b64 s[0:1], vcc
	s_cbranch_execz .LBB0_1039
	v_lshl_add_u32 v2, v2, 2, 0
	v_add_f32_e32 v3, v3, v4
	s_waitcnt vmcnt(0)
	v_sub_f32_e32 v4, v96, v1
	v_add_u32_e32 v5, 0x11c00, v2
	v_mul_f32_e32 v4, 0x3fb8aa3b, v4
	ds_read_b32 v5, v5
	v_exp_f32_e32 v4, v4
	s_waitcnt lgkmcnt(0)
	v_fmac_f32_e32 v3, v4, v5
	v_add_u32_e32 v5, 0x11e00, v2
	ds_write_b32 v5, v3
	v_add_u32_e32 v3, 0x12000, v2
	ds_write_b32 v3, v4
	v_add_u32_e32 v3, 0x11800, v2
	ds_read_b32 v3, v3
	v_add_u32_e32 v2, 0x12200, v2
	s_waitcnt lgkmcnt(0)
	v_add_f32_e32 v1, v1, v3
	v_mul_f32_e32 v1, 0xbfb8aa3b, v1
	v_exp_f32_e32 v1, v1
	ds_write_b32 v2, v1

.LBB0_1047:
	s_or_b64 exec, exec, s[68:69]
	v_add_f32_e32 v7, 0, v4
	v_add_f32_e32 v7, v7, v3
	v_add_f32_e32 v7, v7, v6
	v_add_f32_e32 v7, v7, v5
	v_cvt_pk_bf16_f32 v4, v4, v3
	v_mov_b32_e32 v3, v7
	v_mov_b32_e32 v255, v7
	s_nop 1
	v_permlane16_swap_b32_e32 v3, v255
	v_cvt_pk_bf16_f32 v5, v6, v5
	ds_write_b64 v0, v[4:5] offset:39712
	s_waitcnt lgkmcnt(1)
	v_add_f32_e32 v3, v3, v255
	s_nop 1
	v_mov_b32_dpp v4, v3 row_ror:8 row_mask:0xf bank_mask:0xf
	s_waitcnt lgkmcnt(0)
	v_add_f32_e32 v3, v3, v4
	s_nop 1
	v_mov_b32_dpp v4, v3 row_shl:4 row_mask:0xf bank_mask:0x5
	v_mov_b32_dpp v4, v3 row_shr:4 row_mask:0xf bank_mask:0xa
	s_nop 0
	v_add_f32_e32 v3, v3, v4
	s_nop 1
	v_mov_b32_dpp v4, v3 quad_perm:[2,3,0,1] row_mask:0xf bank_mask:0xf
	s_nop 0
	v_add_f32_e32 v3, v3, v4
	s_nop 1
	v_mov_b32_dpp v4, v3 quad_perm:[1,0,3,2] row_mask:0xf bank_mask:0xf
	s_and_saveexec_b64 s[0:1], vcc
	s_cbranch_execz .LBB0_1049
	v_lshl_add_u32 v2, v2, 2, 0
	v_add_f32_e32 v3, v3, v4
	s_waitcnt vmcnt(0)
	v_sub_f32_e32 v4, v96, v1
	v_add_u32_e32 v5, 0x11c00, v2
	v_mul_f32_e32 v4, 0x3fb8aa3b, v4
	ds_read_b32 v5, v5
	v_exp_f32_e32 v4, v4
	s_waitcnt lgkmcnt(0)
	v_fmac_f32_e32 v3, v4, v5
	v_add_u32_e32 v5, 0x11e00, v2
	ds_write_b32 v5, v3
	v_add_u32_e32 v3, 0x12000, v2
	ds_write_b32 v3, v4
	v_add_u32_e32 v3, 0x11800, v2
	ds_read_b32 v3, v3
	v_add_u32_e32 v2, 0x12200, v2
	s_waitcnt lgkmcnt(0)
	v_add_f32_e32 v1, v1, v3
	v_mul_f32_e32 v1, 0xbfb8aa3b, v1
	v_exp_f32_e32 v1, v1
	ds_write_b32 v2, v1

.LBB0_1057:
	s_or_b64 exec, exec, s[68:69]
	v_add_f32_e32 v7, 0, v4
	v_add_f32_e32 v7, v7, v3
	v_add_f32_e32 v7, v7, v6
	v_add_f32_e32 v7, v7, v5
	v_cvt_pk_bf16_f32 v4, v4, v3
	v_mov_b32_e32 v3, v7
	v_mov_b32_e32 v255, v7
	s_nop 1
	v_permlane16_swap_b32_e32 v3, v255
	v_cvt_pk_bf16_f32 v5, v6, v5
	ds_write_b64 v0, v[4:5] offset:39984
	s_waitcnt lgkmcnt(1)
	v_add_f32_e32 v3, v3, v255
	s_nop 1
	v_mov_b32_dpp v4, v3 row_ror:8 row_mask:0xf bank_mask:0xf
	s_waitcnt lgkmcnt(0)
	v_add_f32_e32 v3, v3, v4
	s_nop 1
	v_mov_b32_dpp v4, v3 row_shl:4 row_mask:0xf bank_mask:0x5
	v_mov_b32_dpp v4, v3 row_shr:4 row_mask:0xf bank_mask:0xa
	s_nop 0
	v_add_f32_e32 v3, v3, v4
	s_nop 1
	v_mov_b32_dpp v4, v3 quad_perm:[2,3,0,1] row_mask:0xf bank_mask:0xf
	s_nop 0
	v_add_f32_e32 v3, v3, v4
	s_nop 1
	v_mov_b32_dpp v4, v3 quad_perm:[1,0,3,2] row_mask:0xf bank_mask:0xf
	s_and_saveexec_b64 s[0:1], vcc
	s_cbranch_execz .LBB0_1059
	v_lshl_add_u32 v2, v2, 2, 0
	v_add_f32_e32 v3, v3, v4
	s_waitcnt vmcnt(0)
	v_sub_f32_e32 v4, v96, v1
	v_add_u32_e32 v5, 0x11c00, v2
	v_mul_f32_e32 v4, 0x3fb8aa3b, v4
	ds_read_b32 v5, v5
	v_exp_f32_e32 v4, v4
	s_waitcnt lgkmcnt(0)
	v_fmac_f32_e32 v3, v4, v5
	v_add_u32_e32 v5, 0x11e00, v2
	ds_write_b32 v5, v3
	v_add_u32_e32 v3, 0x12000, v2
	ds_write_b32 v3, v4
	v_add_u32_e32 v3, 0x11800, v2
	ds_read_b32 v3, v3
	v_add_u32_e32 v2, 0x12200, v2
	s_waitcnt lgkmcnt(0)
	v_add_f32_e32 v1, v1, v3
	v_mul_f32_e32 v1, 0xbfb8aa3b, v1
	v_exp_f32_e32 v1, v1
	ds_write_b32 v2, v1

.LBB0_1067:
	s_or_b64 exec, exec, s[68:69]
	v_add_f32_e32 v7, 0, v4
	v_add_f32_e32 v7, v7, v3
	v_add_f32_e32 v7, v7, v6
	v_add_f32_e32 v7, v7, v5
	v_cvt_pk_bf16_f32 v4, v4, v3
	v_mov_b32_e32 v3, v7
	v_mov_b32_e32 v255, v7
	s_nop 1
	v_permlane16_swap_b32_e32 v3, v255
	v_cvt_pk_bf16_f32 v5, v6, v5
	ds_write_b64 v0, v[4:5] offset:41344
	s_waitcnt lgkmcnt(1)
	v_add_f32_e32 v3, v3, v255
	s_nop 1
	v_mov_b32_dpp v4, v3 row_ror:8 row_mask:0xf bank_mask:0xf
	s_waitcnt lgkmcnt(0)
	v_add_f32_e32 v3, v3, v4
	s_nop 1
	v_mov_b32_dpp v4, v3 row_shl:4 row_mask:0xf bank_mask:0x5
	v_mov_b32_dpp v4, v3 row_shr:4 row_mask:0xf bank_mask:0xa
	s_nop 0
	v_add_f32_e32 v3, v3, v4
	s_nop 1
	v_mov_b32_dpp v4, v3 quad_perm:[2,3,0,1] row_mask:0xf bank_mask:0xf
	s_nop 0
	v_add_f32_e32 v3, v3, v4
	s_nop 1
	v_mov_b32_dpp v4, v3 quad_perm:[1,0,3,2] row_mask:0xf bank_mask:0xf
	s_and_saveexec_b64 s[0:1], vcc
	s_cbranch_execz .LBB0_1069
	v_lshl_add_u32 v2, v2, 2, 0
	v_add_f32_e32 v3, v3, v4
	s_waitcnt vmcnt(0)
	v_sub_f32_e32 v4, v96, v1
	v_add_u32_e32 v5, 0x11c00, v2
	v_mul_f32_e32 v4, 0x3fb8aa3b, v4
	ds_read_b32 v5, v5
	v_exp_f32_e32 v4, v4
	s_waitcnt lgkmcnt(0)
	v_fmac_f32_e32 v3, v4, v5
	v_add_u32_e32 v5, 0x11e00, v2
	ds_write_b32 v5, v3
	v_add_u32_e32 v3, 0x12000, v2
	ds_write_b32 v3, v4
	v_add_u32_e32 v3, 0x11800, v2
	ds_read_b32 v3, v3
	v_add_u32_e32 v2, 0x12200, v2
	s_waitcnt lgkmcnt(0)
	v_add_f32_e32 v1, v1, v3
	v_mul_f32_e32 v1, 0xbfb8aa3b, v1
	v_exp_f32_e32 v1, v1
	ds_write_b32 v2, v1

.LBB0_1077:
	s_or_b64 exec, exec, s[68:69]
	v_add_f32_e32 v7, 0, v4
	v_add_f32_e32 v7, v7, v3
	v_add_f32_e32 v7, v7, v6
	v_add_f32_e32 v7, v7, v5
	v_cvt_pk_bf16_f32 v4, v4, v3
	v_mov_b32_e32 v3, v7
	v_mov_b32_e32 v255, v7
	s_nop 1
	v_permlane16_swap_b32_e32 v3, v255
	v_cvt_pk_bf16_f32 v5, v6, v5
	ds_write_b64 v0, v[4:5] offset:41616
	s_waitcnt lgkmcnt(1)
	v_add_f32_e32 v3, v3, v255
	s_nop 1
	v_mov_b32_dpp v4, v3 row_ror:8 row_mask:0xf bank_mask:0xf
	s_waitcnt lgkmcnt(0)
	v_add_f32_e32 v3, v3, v4
	s_nop 1
	v_mov_b32_dpp v4, v3 row_shl:4 row_mask:0xf bank_mask:0x5
	v_mov_b32_dpp v4, v3 row_shr:4 row_mask:0xf bank_mask:0xa
	s_nop 0
	v_add_f32_e32 v3, v3, v4
	s_nop 1
	v_mov_b32_dpp v4, v3 quad_perm:[2,3,0,1] row_mask:0xf bank_mask:0xf
	s_nop 0
	v_add_f32_e32 v3, v3, v4
	s_nop 1
	v_mov_b32_dpp v4, v3 quad_perm:[1,0,3,2] row_mask:0xf bank_mask:0xf
	s_and_saveexec_b64 s[0:1], vcc
	s_cbranch_execz .LBB0_1079
	v_lshl_add_u32 v2, v2, 2, 0
	v_add_f32_e32 v3, v3, v4
	s_waitcnt vmcnt(0)
	v_sub_f32_e32 v4, v96, v1
	v_add_u32_e32 v5, 0x11c00, v2
	v_mul_f32_e32 v4, 0x3fb8aa3b, v4
	ds_read_b32 v5, v5
	v_exp_f32_e32 v4, v4
	s_waitcnt lgkmcnt(0)
	v_fmac_f32_e32 v3, v4, v5
	v_add_u32_e32 v5, 0x11e00, v2
	ds_write_b32 v5, v3
	v_add_u32_e32 v3, 0x12000, v2
	ds_write_b32 v3, v4
	v_add_u32_e32 v3, 0x11800, v2
	ds_read_b32 v3, v3
	v_add_u32_e32 v2, 0x12200, v2
	s_waitcnt lgkmcnt(0)
	v_add_f32_e32 v1, v1, v3
	v_mul_f32_e32 v1, 0xbfb8aa3b, v1
	v_exp_f32_e32 v1, v1
	ds_write_b32 v2, v1

.LBB0_1087:
	s_or_b64 exec, exec, s[68:69]
	v_add_f32_e32 v7, 0, v4
	v_add_f32_e32 v7, v7, v3
	v_add_f32_e32 v7, v7, v6
	v_add_f32_e32 v7, v7, v5
	v_cvt_pk_bf16_f32 v4, v4, v3
	v_mov_b32_e32 v3, v7
	v_mov_b32_e32 v255, v7
	s_nop 1
	v_permlane16_swap_b32_e32 v3, v255
	v_cvt_pk_bf16_f32 v5, v6, v5
	ds_write_b64 v0, v[4:5] offset:41888
	s_waitcnt lgkmcnt(1)
	v_add_f32_e32 v3, v3, v255
	s_nop 1
	v_mov_b32_dpp v4, v3 row_ror:8 row_mask:0xf bank_mask:0xf
	s_waitcnt lgkmcnt(0)
	v_add_f32_e32 v3, v3, v4
	s_nop 1
	v_mov_b32_dpp v4, v3 row_shl:4 row_mask:0xf bank_mask:0x5
	v_mov_b32_dpp v4, v3 row_shr:4 row_mask:0xf bank_mask:0xa
	s_nop 0
	v_add_f32_e32 v3, v3, v4
	s_nop 1
	v_mov_b32_dpp v4, v3 quad_perm:[2,3,0,1] row_mask:0xf bank_mask:0xf
	s_nop 0
	v_add_f32_e32 v3, v3, v4
	s_nop 1
	v_mov_b32_dpp v4, v3 quad_perm:[1,0,3,2] row_mask:0xf bank_mask:0xf
	s_and_saveexec_b64 s[0:1], vcc
	s_cbranch_execz .LBB0_1089
	v_lshl_add_u32 v2, v2, 2, 0
	v_add_f32_e32 v3, v3, v4
	s_waitcnt vmcnt(0)
	v_sub_f32_e32 v4, v96, v1
	v_add_u32_e32 v5, 0x11c00, v2
	v_mul_f32_e32 v4, 0x3fb8aa3b, v4
	ds_read_b32 v5, v5
	v_exp_f32_e32 v4, v4
	s_waitcnt lgkmcnt(0)
	v_fmac_f32_e32 v3, v4, v5
	v_add_u32_e32 v5, 0x11e00, v2
	ds_write_b32 v5, v3
	v_add_u32_e32 v3, 0x12000, v2
	ds_write_b32 v3, v4
	v_add_u32_e32 v3, 0x11800, v2
	ds_read_b32 v3, v3
	v_add_u32_e32 v2, 0x12200, v2
	s_waitcnt lgkmcnt(0)
	v_add_f32_e32 v1, v1, v3
	v_mul_f32_e32 v1, 0xbfb8aa3b, v1
	v_exp_f32_e32 v1, v1
	ds_write_b32 v2, v1

.LBB0_1097:
	s_or_b64 exec, exec, s[6:7]
	v_add_f32_e32 v7, 0, v4
	v_add_f32_e32 v7, v7, v3
	v_add_f32_e32 v7, v7, v6
	v_add_f32_e32 v7, v7, v5
	v_cvt_pk_bf16_f32 v4, v4, v3
	v_cvt_pk_bf16_f32 v5, v6, v5
	ds_write_b64 v0, v[4:5] offset:42160
	v_mov_b32_e32 v0, v7
	v_mov_b32_e32 v255, v7
	s_nop 1
	v_permlane16_swap_b32_e32 v0, v255
	s_waitcnt lgkmcnt(0)
	v_add_f32_e32 v0, v0, v255
	s_nop 1
	v_mov_b32_dpp v3, v0 row_ror:8 row_mask:0xf bank_mask:0xf
	s_nop 0
	v_add_f32_e32 v0, v0, v3
	s_nop 1
	v_mov_b32_dpp v3, v0 row_shl:4 row_mask:0xf bank_mask:0x5
	v_mov_b32_dpp v3, v0 row_shr:4 row_mask:0xf bank_mask:0xa
	s_nop 0
	v_add_f32_e32 v0, v0, v3
	s_nop 1
	v_mov_b32_dpp v3, v0 quad_perm:[2,3,0,1] row_mask:0xf bank_mask:0xf
	s_nop 0
	v_add_f32_e32 v0, v0, v3
	s_nop 1
	v_mov_b32_dpp v3, v0 quad_perm:[1,0,3,2] row_mask:0xf bank_mask:0xf
	s_and_saveexec_b64 s[0:1], vcc
	s_cbranch_execz .LBB0_1099
	v_lshl_add_u32 v2, v2, 2, 0
	v_add_f32_e32 v0, v0, v3
	s_waitcnt vmcnt(0)
	v_sub_f32_e32 v3, v96, v1
	v_add_u32_e32 v4, 0x11c00, v2
	v_mul_f32_e32 v3, 0x3fb8aa3b, v3
	ds_read_b32 v4, v4
	v_exp_f32_e32 v3, v3
	s_waitcnt lgkmcnt(0)
	v_fmac_f32_e32 v0, v3, v4
	v_add_u32_e32 v4, 0x11e00, v2
	ds_write_b32 v4, v0
	v_add_u32_e32 v0, 0x12000, v2
	ds_write_b32 v0, v3
	v_add_u32_e32 v0, 0x11800, v2
	ds_read_b32 v0, v0
	s_waitcnt lgkmcnt(0)
	v_add_f32_e32 v0, v1, v0
	v_mul_f32_e32 v0, 0xbfb8aa3b, v0
	v_exp_f32_e32 v0, v0
	v_add_u32_e32 v1, 0x12200, v2
	ds_write_b32 v1, v0

.LBB0_1101:
	s_waitcnt lgkmcnt(0)
	v_ashrrev_i32_e32 v3, 31, v0
	v_lshrrev_b32_e32 v3, 28, v3
	v_add_u32_e32 v3, v0, v3
	v_ashrrev_i32_e32 v4, 4, v3
	v_ashrrev_i32_e32 v5, 31, v4
	v_lshlrev_b32_e32 v6, 7, v4
	v_lshlrev_b64 v[4:5], 8, v[4:5]
	v_sub_u32_e32 v6, v2, v6
	v_lshl_add_u64 v[4:5], s[6:7], 0, v[4:5]
	v_ashrrev_i32_e32 v7, 31, v6
	v_lshl_add_u64 v[4:5], v[6:7], 1, v[4:5]
	global_load_dwordx4 v[16:19], v[4:5], off
	v_add_u32_e32 v8, 0x100, v0
	v_cmp_lt_i32_e32 vcc, s77, v0
	v_and_b32_e32 v3, -16, v3
	s_or_b64 s[12:13], vcc, s[12:13]
	v_mov_b32_e32 v0, v8
	v_add_u32_e32 v3, v1, v3
	v_add_u32_e32 v1, 0x1000, v1
	v_add_u32_e32 v2, 0x800, v2
	v_mov_b32_e32 v44, v3
	v_ashrrev_i32_e32 v3, 31, v0
	v_lshrrev_b32_e32 v3, 28, v3
	v_add_u32_e32 v3, v0, v3
	v_ashrrev_i32_e32 v4, 4, v3
	v_ashrrev_i32_e32 v5, 31, v4
	v_lshlrev_b32_e32 v6, 7, v4
	v_lshlrev_b64 v[4:5], 8, v[4:5]
	v_sub_u32_e32 v6, v2, v6
	v_lshl_add_u64 v[4:5], s[6:7], 0, v[4:5]
	v_ashrrev_i32_e32 v7, 31, v6
	v_lshl_add_u64 v[4:5], v[6:7], 1, v[4:5]
	global_load_dwordx4 v[20:23], v[4:5], off
	v_add_u32_e32 v8, 0x100, v0
	v_cmp_lt_i32_e32 vcc, s77, v0
	v_and_b32_e32 v3, -16, v3
	s_or_b64 s[12:13], vcc, s[12:13]
	v_mov_b32_e32 v0, v8
	v_add_u32_e32 v3, v1, v3
	v_add_u32_e32 v1, 0x1000, v1
	v_add_u32_e32 v2, 0x800, v2
	v_mov_b32_e32 v45, v3
	v_ashrrev_i32_e32 v3, 31, v0
	v_lshrrev_b32_e32 v3, 28, v3
	v_add_u32_e32 v3, v0, v3
	v_ashrrev_i32_e32 v4, 4, v3
	v_ashrrev_i32_e32 v5, 31, v4
	v_lshlrev_b32_e32 v6, 7, v4
	v_lshlrev_b64 v[4:5], 8, v[4:5]
	v_sub_u32_e32 v6, v2, v6
	v_lshl_add_u64 v[4:5], s[6:7], 0, v[4:5]
	v_ashrrev_i32_e32 v7, 31, v6
	v_lshl_add_u64 v[4:5], v[6:7], 1, v[4:5]
	global_load_dwordx4 v[24:27], v[4:5], off
	v_add_u32_e32 v8, 0x100, v0
	v_cmp_lt_i32_e32 vcc, s77, v0
	v_and_b32_e32 v3, -16, v3
	s_or_b64 s[12:13], vcc, s[12:13]
	v_mov_b32_e32 v0, v8
	v_add_u32_e32 v3, v1, v3
	v_add_u32_e32 v1, 0x1000, v1
	v_add_u32_e32 v2, 0x800, v2
	v_mov_b32_e32 v46, v3
	v_ashrrev_i32_e32 v3, 31, v0
	v_lshrrev_b32_e32 v3, 28, v3
	v_add_u32_e32 v3, v0, v3
	v_ashrrev_i32_e32 v4, 4, v3
	v_ashrrev_i32_e32 v5, 31, v4
	v_lshlrev_b32_e32 v6, 7, v4
	v_lshlrev_b64 v[4:5], 8, v[4:5]
	v_sub_u32_e32 v6, v2, v6
	v_lshl_add_u64 v[4:5], s[6:7], 0, v[4:5]
	v_ashrrev_i32_e32 v7, 31, v6
	v_lshl_add_u64 v[4:5], v[6:7], 1, v[4:5]
	global_load_dwordx4 v[28:31], v[4:5], off
	v_add_u32_e32 v8, 0x100, v0
	v_cmp_lt_i32_e32 vcc, s77, v0
	v_and_b32_e32 v3, -16, v3
	s_or_b64 s[12:13], vcc, s[12:13]
	v_mov_b32_e32 v0, v8
	v_add_u32_e32 v3, v1, v3
	v_add_u32_e32 v1, 0x1000, v1
	v_add_u32_e32 v2, 0x800, v2
	v_mov_b32_e32 v47, v3
	v_ashrrev_i32_e32 v3, 31, v0
	v_lshrrev_b32_e32 v3, 28, v3
	v_add_u32_e32 v3, v0, v3
	v_ashrrev_i32_e32 v4, 4, v3
	v_ashrrev_i32_e32 v5, 31, v4
	v_lshlrev_b32_e32 v6, 7, v4
	v_lshlrev_b64 v[4:5], 8, v[4:5]
	v_sub_u32_e32 v6, v2, v6
	v_lshl_add_u64 v[4:5], s[6:7], 0, v[4:5]
	v_ashrrev_i32_e32 v7, 31, v6
	v_lshl_add_u64 v[4:5], v[6:7], 1, v[4:5]
	global_load_dwordx4 v[32:35], v[4:5], off
	v_add_u32_e32 v8, 0x100, v0
	v_cmp_lt_i32_e32 vcc, s77, v0
	v_and_b32_e32 v3, -16, v3
	s_or_b64 s[12:13], vcc, s[12:13]
	v_mov_b32_e32 v0, v8
	v_add_u32_e32 v3, v1, v3
	v_add_u32_e32 v1, 0x1000, v1
	v_add_u32_e32 v2, 0x800, v2
	v_mov_b32_e32 v48, v3
	v_ashrrev_i32_e32 v3, 31, v0
	v_lshrrev_b32_e32 v3, 28, v3
	v_add_u32_e32 v3, v0, v3
	v_ashrrev_i32_e32 v4, 4, v3
	v_ashrrev_i32_e32 v5, 31, v4
	v_lshlrev_b32_e32 v6, 7, v4
	v_lshlrev_b64 v[4:5], 8, v[4:5]
	v_sub_u32_e32 v6, v2, v6
	v_lshl_add_u64 v[4:5], s[6:7], 0, v[4:5]
	v_ashrrev_i32_e32 v7, 31, v6
	v_lshl_add_u64 v[4:5], v[6:7], 1, v[4:5]
	global_load_dwordx4 v[36:39], v[4:5], off
	v_add_u32_e32 v8, 0x100, v0
	v_cmp_lt_i32_e32 vcc, s77, v0
	v_and_b32_e32 v3, -16, v3
	s_or_b64 s[12:13], vcc, s[12:13]
	v_mov_b32_e32 v0, v8
	v_add_u32_e32 v3, v1, v3
	v_add_u32_e32 v1, 0x1000, v1
	v_add_u32_e32 v2, 0x800, v2
	v_mov_b32_e32 v49, v3
	v_ashrrev_i32_e32 v3, 31, v0
	v_lshrrev_b32_e32 v3, 28, v3
	v_add_u32_e32 v3, v0, v3
	v_ashrrev_i32_e32 v4, 4, v3
	v_ashrrev_i32_e32 v5, 31, v4
	v_lshlrev_b32_e32 v6, 7, v4
	v_lshlrev_b64 v[4:5], 8, v[4:5]
	v_sub_u32_e32 v6, v2, v6
	v_lshl_add_u64 v[4:5], s[6:7], 0, v[4:5]
	v_ashrrev_i32_e32 v7, 31, v6
	v_lshl_add_u64 v[4:5], v[6:7], 1, v[4:5]
	global_load_dwordx4 v[40:43], v[4:5], off
	v_add_u32_e32 v8, 0x100, v0
	v_cmp_lt_i32_e32 vcc, s77, v0
	v_and_b32_e32 v3, -16, v3
	s_or_b64 s[12:13], vcc, s[12:13]
	v_mov_b32_e32 v0, v8
	v_add_u32_e32 v3, v1, v3
	v_add_u32_e32 v1, 0x1000, v1
	v_add_u32_e32 v2, 0x800, v2
	v_mov_b32_e32 v50, v3
	v_ashrrev_i32_e32 v3, 31, v0
	v_lshrrev_b32_e32 v3, 28, v3
	v_add_u32_e32 v3, v0, v3
	v_ashrrev_i32_e32 v4, 4, v3
	v_ashrrev_i32_e32 v5, 31, v4
	v_lshlrev_b32_e32 v6, 7, v4
	v_lshlrev_b64 v[4:5], 8, v[4:5]
	v_sub_u32_e32 v6, v2, v6
	v_lshl_add_u64 v[4:5], s[6:7], 0, v[4:5]
	v_ashrrev_i32_e32 v7, 31, v6
	v_lshl_add_u64 v[4:5], v[6:7], 1, v[4:5]
	global_load_dwordx4 v[4:7], v[4:5], off
	v_add_u32_e32 v8, 0x100, v0
	v_cmp_lt_i32_e32 vcc, s77, v0
	v_and_b32_e32 v3, -16, v3
	s_or_b64 s[12:13], vcc, s[12:13]
	v_mov_b32_e32 v0, v8
	v_add_u32_e32 v3, v1, v3
	v_add_u32_e32 v1, 0x1000, v1
	v_add_u32_e32 v2, 0x800, v2
	s_waitcnt vmcnt(7)
	ds_write_b128 v44, v[16:19]
	s_waitcnt vmcnt(6)
	ds_write_b128 v45, v[20:23]
	s_waitcnt vmcnt(5)
	ds_write_b128 v46, v[24:27]
	s_waitcnt vmcnt(4)
	ds_write_b128 v47, v[28:31]
	s_waitcnt vmcnt(3)
	ds_write_b128 v48, v[32:35]
	s_waitcnt vmcnt(2)
	ds_write_b128 v49, v[36:39]
	s_waitcnt vmcnt(1)
	ds_write_b128 v50, v[40:43]
	s_waitcnt vmcnt(0)
	ds_write_b128 v3, v[4:7]
	s_or_b64 exec, exec, s[12:13]

.LBB0_1116:
	s_waitcnt vmcnt(0)
	s_barrier
	s_mov_b64 s[0:1], exec
	v_readlane_b32 s2, v251, 0
	v_readlane_b32 s3, v251, 1
	s_and_b64 s[2:3], s[0:1], s[2:3]
	v_readlane_b32 s34, v248, 6
	s_mov_b64 exec, s[2:3]
	s_cbranch_execz .LBB0_1164
	v_readlane_b32 s2, v249, 49
	s_waitcnt expcnt(0) lgkmcnt(0)
	s_nop 0
	v_mov_b32_e32 v0, s2
	ds_read_b32 v2, v0
	v_readlane_b32 s2, v249, 50
	s_waitcnt lgkmcnt(0)
	v_cmp_ne_u32_e32 vcc, 0, v2
	v_mov_b32_e32 v0, s2
	ds_read_b32 v0, v0
	s_cbranch_vccnz .LBB0_1132
	s_mov_b32 s4, 1
	s_branch .LBB0_1120

.LBB0_1246:
	s_waitcnt vmcnt(0)
	s_barrier
	s_mov_b64 s[2:3], exec
	v_readlane_b32 s6, v251, 0
	v_readlane_b32 s7, v251, 1
	s_and_b64 s[6:7], s[2:3], s[6:7]
	s_mov_b64 exec, s[6:7]
	s_cbranch_execz .LBB0_1294
	v_readlane_b32 s6, v249, 49
	s_waitcnt expcnt(0) lgkmcnt(0)
	s_nop 0
	v_mov_b32_e32 v0, s6
	ds_read_b32 v2, v0
	v_readlane_b32 s6, v249, 50
	s_waitcnt lgkmcnt(0)
	v_cmp_ne_u32_e32 vcc, 0, v2
	v_mov_b32_e32 v0, s6
	ds_read_b32 v0, v0
	s_cbranch_vccnz .LBB0_1262
	s_mov_b32 s40, 1
	s_branch .LBB0_1250

.LBB0_1297:
	s_or_b64 exec, exec, s[2:3]
	s_waitcnt vmcnt(0)
	s_barrier
	s_mov_b64 s[2:3], exec
	v_readlane_b32 s6, v251, 0
	v_readlane_b32 s7, v251, 1
	s_and_b64 s[6:7], s[2:3], s[6:7]
	s_xor_b64 s[2:3], s[6:7], s[2:3]
	s_mov_b64 s[16:17], s[82:83]
	s_mov_b64 exec, s[6:7]
	s_cbranch_execz .LBB0_1346
	v_readlane_b32 s6, v249, 49
	s_waitcnt expcnt(0) lgkmcnt(0)
	s_nop 0
	v_mov_b32_e32 v0, s6
	ds_read_b32 v2, v0
	v_readlane_b32 s6, v249, 50
	s_waitcnt lgkmcnt(0)
	v_cmp_ne_u32_e32 vcc, 0, v2
	v_mov_b32_e32 v0, s6
	ds_read_b32 v0, v0
	s_cbranch_vccnz .LBB0_1313
	s_mov_b32 s40, 1
	s_branch .LBB0_1301

.LBB0_1353:
	v_readlane_b32 s42, v248, 8
	v_readlane_b32 s43, v248, 9
	s_add_u32 s7, s42, s40
	s_addc_u32 s13, s43, s41
	s_and_b64 s[40:41], s[44:45], exec
	s_cselect_b32 s40, s7, 0
	v_readlane_b32 s7, v249, 33
	s_cselect_b32 s41, s13, 0
	s_add_u32 s7, s7, s46
	v_readlane_b32 s8, v249, 34
	s_addc_u32 s13, s8, s47
	s_and_b64 s[46:47], s[44:45], exec
	s_cselect_b32 s47, s13, 0
	s_cselect_b32 s46, s7, 0
	v_lshl_add_u64 v[4:5], s[40:41], 0, v[0:1]
	v_lshl_add_u64 v[0:1], s[46:47], 0, v[0:1]
	v_lshl_add_u64 v[146:147], v[0:1], 0, v[96:97]
	v_lshrrev_b32_e32 v0, 1, v2
	v_and_b32_e32 v1, 31, v2
	v_and_or_b32 v1, v0, s81, v1
	v_lshrrev_b32_e32 v0, 2, v2
	v_and_b32_e32 v0, 8, v0
	v_lshl_add_u64 v[148:149], v[4:5], 0, v[96:97]
	v_mad_u64_u32 v[4:5], s[40:41], v1, s84, v[0:1]
	v_and_b32_e32 v1, 0x5f, v2
	v_mad_u32_u24 v0, v1, s84, v0
	v_lshl_add_u32 v176, v4, 1, 0
	v_lshl_add_u32 v96, v0, 1, 0
	v_add_u32_e32 v177, 0xd800, v175
	s_setprio 1
	ds_read_b128 v[212:215], v96 offset:36864
	ds_read_b128 v[216:219], v176
	ds_read_b128 v[220:223], v176 offset:4608
	ds_read_b128 v[224:227], v96 offset:36896
	ds_read_b128 v[228:231], v176 offset:32
	ds_read_b128 v[244:247], v176 offset:4640
	ds_read_b128 v[252:255], v96 offset:41472
	s_waitcnt lgkmcnt(5)
	v_mfma_f32_32x32x16_bf16 v[32:47], v[212:215], v[216:219], 0
	s_waitcnt lgkmcnt(4)
	v_mfma_f32_32x32x16_bf16 v[0:15], v[212:215], v[220:223], 0
	ds_read_b128 v[212:215], v96 offset:41504
	s_waitcnt lgkmcnt(3)
	v_mfma_f32_32x32x16_bf16 v[32:47], v[224:227], v[228:231], v[32:47]
	s_waitcnt lgkmcnt(2)
	v_mfma_f32_32x32x16_bf16 v[0:15], v[224:227], v[244:247], v[0:15]
	ds_read_b128 v[224:227], v96 offset:36928
	s_waitcnt lgkmcnt(2)
	v_mfma_f32_32x32x16_bf16 v[48:63], v[252:255], v[216:219], 0
	ds_read_b128 v[216:219], v176 offset:64
	v_mfma_f32_32x32x16_bf16 v[16:31], v[252:255], v[220:223], 0
	ds_read_b128 v[252:255], v176 offset:4672
	ds_read_b128 v[220:223], v96 offset:41536
	s_waitcnt lgkmcnt(4)
	v_mfma_f32_32x32x16_bf16 v[48:63], v[212:215], v[228:231], v[48:63]
	ds_read_b128 v[228:231], v96 offset:36960
	v_mfma_f32_32x32x16_bf16 v[16:31], v[212:215], v[244:247], v[16:31]
	ds_read_b128 v[212:215], v176 offset:96
	ds_read_b128 v[244:247], v176 offset:4704
	s_waitcnt lgkmcnt(5)
	v_mfma_f32_32x32x16_bf16 v[32:47], v[224:227], v[216:219], v[32:47]
	v_add_co_u32_e32 v154, vcc, s9, v152
	s_waitcnt vmcnt(11)
	ds_write_b128 v175, v[100:103] offset:18432
	s_waitcnt vmcnt(10)
	ds_write_b128 v175, v[104:107] offset:23040
	s_waitcnt lgkmcnt(6)
	v_mfma_f32_32x32x16_bf16 v[0:15], v[224:227], v[252:255], v[0:15]
	ds_read_b128 v[224:227], v96 offset:41568
	s_waitcnt vmcnt(9)
	ds_write_b128 v175, v[108:111] offset:27648
	s_waitcnt vmcnt(8)
	ds_write_b128 v175, v[112:115] offset:32256
	s_waitcnt vmcnt(7)
	s_waitcnt lgkmcnt(8)
	v_mfma_f32_32x32x16_bf16 v[48:63], v[220:223], v[216:219], v[48:63]
	ds_write_b128 v175, v[116:119] offset:55296
	s_waitcnt vmcnt(6)
	ds_write_b128 v175, v[124:127] offset:59904
	s_waitcnt vmcnt(5)
	ds_write_b128 v175, v[120:123] offset:64512
	v_mfma_f32_32x32x16_bf16 v[16:31], v[220:223], v[252:255], v[16:31]
	s_waitcnt vmcnt(4)
	ds_write_b128 v177, v[128:131] offset:13824
	v_addc_co_u32_e32 v155, vcc, 0, v153, vcc
	v_add_co_u32_e32 v156, vcc, s16, v152
	s_waitcnt lgkmcnt(10)
	v_mfma_f32_32x32x16_bf16 v[32:47], v[228:231], v[212:215], v[32:47]
	global_load_dwordx4 v[98:101], v[152:153], off offset:384
	global_load_dwordx4 v[102:105], v[154:155], off offset:384
	v_addc_co_u32_e32 v157, vcc, 0, v153, vcc
	v_add_co_u32_e32 v158, vcc, s17, v152
	global_load_dwordx4 v[106:109], v[156:157], off offset:384
	s_waitcnt lgkmcnt(9)
	v_mfma_f32_32x32x16_bf16 v[0:15], v[228:231], v[244:247], v[0:15]
	s_nop 0
	v_addc_co_u32_e32 v159, vcc, 0, v153, vcc
	v_add_co_u32_e32 v160, vcc, s9, v150
	global_load_dwordx4 v[110:113], v[158:159], off offset:384
	global_load_dwordx4 v[114:117], v[150:151], off offset:384
	s_waitcnt lgkmcnt(6)
	v_mfma_f32_32x32x16_bf16 v[48:63], v[224:227], v[212:215], v[48:63]
	v_addc_co_u32_e32 v161, vcc, 0, v151, vcc
	v_add_co_u32_e32 v170, vcc, s16, v150
	global_load_dwordx4 v[118:121], v[160:161], off offset:384
	s_nop 0
	v_addc_co_u32_e32 v171, vcc, 0, v151, vcc
	v_mfma_f32_32x32x16_bf16 v[16:31], v[224:227], v[244:247], v[16:31]
	v_add_co_u32_e32 v172, vcc, s17, v150
	global_load_dwordx4 v[122:125], v[170:171], off offset:384
	s_nop 0
	v_addc_co_u32_e32 v173, vcc, 0, v151, vcc
	global_load_dwordx4 v[130:133], v[172:173], off offset:384
	s_setprio 0
	s_waitcnt lgkmcnt(0)
	s_barrier
	s_setprio 1
	ds_read_b128 v[212:215], v96 offset:55296
	ds_read_b128 v[216:219], v176 offset:18432
	ds_read_b128 v[220:223], v176 offset:23040
	ds_read_b128 v[224:227], v96 offset:59904
	ds_read_b128 v[228:231], v96 offset:55328
	ds_read_b128 v[244:247], v176 offset:18464
	ds_read_b128 v[252:255], v176 offset:23072
	s_waitcnt lgkmcnt(5)
	v_mfma_f32_32x32x16_bf16 v[32:47], v[212:215], v[216:219], v[32:47]
	s_waitcnt lgkmcnt(4)
	v_mfma_f32_32x32x16_bf16 v[0:15], v[212:215], v[220:223], v[0:15]
	ds_read_b128 v[212:215], v96 offset:59936
	s_waitcnt lgkmcnt(4)
	v_mfma_f32_32x32x16_bf16 v[48:63], v[224:227], v[216:219], v[48:63]
	ds_read_b128 v[216:219], v96 offset:55360
	v_mfma_f32_32x32x16_bf16 v[16:31], v[224:227], v[220:223], v[16:31]
	ds_read_b128 v[224:227], v176 offset:18496
	ds_read_b128 v[220:223], v176 offset:23104
	s_waitcnt lgkmcnt(5)
	v_mfma_f32_32x32x16_bf16 v[32:47], v[228:231], v[244:247], v[32:47]
	s_waitcnt lgkmcnt(4)
	v_mfma_f32_32x32x16_bf16 v[0:15], v[228:231], v[252:255], v[0:15]
	ds_read_b128 v[228:231], v96 offset:59968
	s_waitcnt lgkmcnt(4)
	v_mfma_f32_32x32x16_bf16 v[48:63], v[212:215], v[244:247], v[48:63]
	ds_read_b128 v[244:247], v96 offset:55392
	v_mfma_f32_32x32x16_bf16 v[16:31], v[212:215], v[252:255], v[16:31]
	ds_read_b128 v[212:215], v176 offset:18528
	ds_read_b128 v[252:255], v176 offset:23136
	s_waitcnt lgkmcnt(5)
	v_mfma_f32_32x32x16_bf16 v[32:47], v[216:219], v[224:227], v[32:47]
	ds_write_b128 v175, v[64:67]
	global_load_dwordx4 v[64:67], v[152:153], off offset:512
	s_waitcnt lgkmcnt(5)
	v_mfma_f32_32x32x16_bf16 v[0:15], v[216:219], v[220:223], v[0:15]
	ds_read_b128 v[216:219], v96 offset:60000
	ds_write_b128 v175, v[68:71] offset:4608
	ds_write_b128 v175, v[72:75] offset:9216
	s_waitcnt lgkmcnt(7)
	v_mfma_f32_32x32x16_bf16 v[48:63], v[228:231], v[224:227], v[48:63]
	global_load_dwordx4 v[72:75], v[154:155], off offset:512
	ds_write_b128 v175, v[76:79] offset:13824
	v_mfma_f32_32x32x16_bf16 v[16:31], v[228:231], v[220:223], v[16:31]
	global_load_dwordx4 v[76:79], v[156:157], off offset:512
	s_waitcnt vmcnt(14)
	ds_write_b128 v175, v[80:83] offset:36864
	s_waitcnt lgkmcnt(7)
	v_mfma_f32_32x32x16_bf16 v[32:47], v[244:247], v[212:215], v[32:47]
	global_load_dwordx4 v[80:83], v[158:159], off offset:512
	global_load_dwordx4 v[126:129], v[150:151], off offset:512
	s_waitcnt lgkmcnt(6)
	v_mfma_f32_32x32x16_bf16 v[0:15], v[244:247], v[252:255], v[0:15]
	s_waitcnt vmcnt(15)
	ds_write_b128 v175, v[84:87] offset:41472
	global_load_dwordx4 v[134:137], v[160:161], off offset:512
	s_waitcnt lgkmcnt(5)
	v_mfma_f32_32x32x16_bf16 v[48:63], v[216:219], v[212:215], v[48:63]
	s_waitcnt vmcnt(15)
	ds_write_b128 v175, v[88:91] offset:46080
	global_load_dwordx4 v[138:141], v[170:171], off offset:512
	v_mfma_f32_32x32x16_bf16 v[16:31], v[216:219], v[252:255], v[16:31]
	s_waitcnt vmcnt(15)
	ds_write_b128 v175, v[92:95] offset:50688
	global_load_dwordx4 v[142:145], v[172:173], off offset:512
	s_setprio 0
	s_waitcnt lgkmcnt(0)
	s_barrier
	s_setprio 1
	ds_read_b128 v[212:215], v96 offset:36864
	ds_read_b128 v[216:219], v176
	ds_read_b128 v[220:223], v176 offset:4608
	ds_read_b128 v[224:227], v96 offset:41472
	ds_read_b128 v[228:231], v96 offset:36896
	ds_read_b128 v[244:247], v176 offset:32
	ds_read_b128 v[252:255], v176 offset:4640
	s_waitcnt lgkmcnt(5)
	v_mfma_f32_32x32x16_bf16 v[32:47], v[212:215], v[216:219], v[32:47]
	s_waitcnt lgkmcnt(4)
	v_mfma_f32_32x32x16_bf16 v[0:15], v[212:215], v[220:223], v[0:15]
	ds_read_b128 v[212:215], v96 offset:41504
	s_waitcnt lgkmcnt(4)
	v_mfma_f32_32x32x16_bf16 v[48:63], v[224:227], v[216:219], v[48:63]
	ds_read_b128 v[216:219], v96 offset:36928
	v_mfma_f32_32x32x16_bf16 v[16:31], v[224:227], v[220:223], v[16:31]
	ds_read_b128 v[224:227], v176 offset:64
	ds_read_b128 v[220:223], v176 offset:4672
	s_waitcnt lgkmcnt(5)
	v_mfma_f32_32x32x16_bf16 v[32:47], v[228:231], v[244:247], v[32:47]
	s_waitcnt lgkmcnt(4)
	v_mfma_f32_32x32x16_bf16 v[0:15], v[228:231], v[252:255], v[0:15]
	ds_read_b128 v[228:231], v96 offset:41536
	s_waitcnt lgkmcnt(4)
	v_mfma_f32_32x32x16_bf16 v[48:63], v[212:215], v[244:247], v[48:63]
	ds_read_b128 v[244:247], v96 offset:36960
	v_mfma_f32_32x32x16_bf16 v[16:31], v[212:215], v[252:255], v[16:31]
	ds_read_b128 v[212:215], v176 offset:96
	ds_read_b128 v[252:255], v176 offset:4704
	s_waitcnt lgkmcnt(5)
	v_mfma_f32_32x32x16_bf16 v[32:47], v[216:219], v[224:227], v[32:47]
	s_waitcnt vmcnt(15)
	ds_write_b128 v175, v[98:101] offset:18432
	global_load_dwordx4 v[68:71], v[152:153], off offset:640
	s_waitcnt lgkmcnt(5)
	v_mfma_f32_32x32x16_bf16 v[0:15], v[216:219], v[220:223], v[0:15]
	ds_read_b128 v[216:219], v96 offset:41568
	s_waitcnt vmcnt(15)
	ds_write_b128 v175, v[102:105] offset:23040
	global_load_dwordx4 v[84:87], v[154:155], off offset:640
	s_waitcnt lgkmcnt(6)
	v_mfma_f32_32x32x16_bf16 v[48:63], v[228:231], v[224:227], v[48:63]
	s_waitcnt vmcnt(15)
	ds_write_b128 v175, v[106:109] offset:27648
	global_load_dwordx4 v[88:91], v[156:157], off offset:640
	v_mfma_f32_32x32x16_bf16 v[16:31], v[228:231], v[220:223], v[16:31]
	s_waitcnt vmcnt(15)
	ds_write_b128 v175, v[110:113] offset:32256
	global_load_dwordx4 v[92:95], v[158:159], off offset:640
	s_waitcnt lgkmcnt(6)
	v_mfma_f32_32x32x16_bf16 v[32:47], v[244:247], v[212:215], v[32:47]
	s_waitcnt vmcnt(15)
	ds_write_b128 v175, v[114:117] offset:55296
	global_load_dwordx4 v[98:101], v[150:151], off offset:640
	s_waitcnt lgkmcnt(6)
	v_mfma_f32_32x32x16_bf16 v[0:15], v[244:247], v[252:255], v[0:15]
	s_waitcnt vmcnt(15)
	ds_write_b128 v175, v[118:121] offset:59904
	global_load_dwordx4 v[106:109], v[160:161], off offset:640
	s_waitcnt lgkmcnt(5)
	v_mfma_f32_32x32x16_bf16 v[48:63], v[216:219], v[212:215], v[48:63]
	s_waitcnt vmcnt(15)
	ds_write_b128 v175, v[122:125] offset:64512
	global_load_dwordx4 v[110:113], v[170:171], off offset:640
	v_mfma_f32_32x32x16_bf16 v[16:31], v[216:219], v[252:255], v[16:31]
	s_waitcnt vmcnt(15)
	ds_write_b128 v177, v[130:133] offset:13824
	global_load_dwordx4 v[114:117], v[172:173], off offset:640
	s_setprio 0
	s_waitcnt lgkmcnt(0)
	s_barrier
	s_setprio 1
	ds_read_b128 v[212:215], v96 offset:55296
	ds_read_b128 v[216:219], v176 offset:18432
	ds_read_b128 v[220:223], v176 offset:23040
	ds_read_b128 v[224:227], v96 offset:59904
	ds_read_b128 v[228:231], v96 offset:55328
	ds_read_b128 v[244:247], v176 offset:18464
	ds_read_b128 v[252:255], v176 offset:23072
	s_waitcnt lgkmcnt(5)
	v_mfma_f32_32x32x16_bf16 v[32:47], v[212:215], v[216:219], v[32:47]
	s_waitcnt lgkmcnt(4)
	v_mfma_f32_32x32x16_bf16 v[0:15], v[212:215], v[220:223], v[0:15]
	ds_read_b128 v[212:215], v96 offset:59936
	s_waitcnt lgkmcnt(4)
	v_mfma_f32_32x32x16_bf16 v[48:63], v[224:227], v[216:219], v[48:63]
	ds_read_b128 v[216:219], v96 offset:55360
	v_mfma_f32_32x32x16_bf16 v[16:31], v[224:227], v[220:223], v[16:31]
	ds_read_b128 v[224:227], v176 offset:18496
	ds_read_b128 v[220:223], v176 offset:23104
	s_waitcnt lgkmcnt(5)
	v_mfma_f32_32x32x16_bf16 v[32:47], v[228:231], v[244:247], v[32:47]
	s_waitcnt lgkmcnt(4)
	v_mfma_f32_32x32x16_bf16 v[0:15], v[228:231], v[252:255], v[0:15]
	ds_read_b128 v[228:231], v96 offset:59968
	s_waitcnt lgkmcnt(4)
	v_mfma_f32_32x32x16_bf16 v[48:63], v[212:215], v[244:247], v[48:63]
	ds_read_b128 v[244:247], v96 offset:55392
	v_mfma_f32_32x32x16_bf16 v[16:31], v[212:215], v[252:255], v[16:31]
	ds_read_b128 v[212:215], v176 offset:18528
	ds_read_b128 v[252:255], v176 offset:23136
	s_waitcnt lgkmcnt(5)
	v_mfma_f32_32x32x16_bf16 v[32:47], v[216:219], v[224:227], v[32:47]
	s_waitcnt vmcnt(15)
	ds_write_b128 v175, v[64:67]
	global_load_dwordx4 v[64:67], v[152:153], off offset:768
	s_waitcnt lgkmcnt(5)
	v_mfma_f32_32x32x16_bf16 v[0:15], v[216:219], v[220:223], v[0:15]
	ds_read_b128 v[216:219], v96 offset:60000
	s_waitcnt vmcnt(15)
	ds_write_b128 v175, v[72:75] offset:4608
	global_load_dwordx4 v[72:75], v[154:155], off offset:768
	s_waitcnt lgkmcnt(6)
	v_mfma_f32_32x32x16_bf16 v[48:63], v[228:231], v[224:227], v[48:63]
	s_waitcnt vmcnt(15)
	ds_write_b128 v175, v[76:79] offset:9216
	global_load_dwordx4 v[76:79], v[156:157], off offset:768
	v_mfma_f32_32x32x16_bf16 v[16:31], v[228:231], v[220:223], v[16:31]
	s_waitcnt vmcnt(15)
	ds_write_b128 v175, v[80:83] offset:13824
	global_load_dwordx4 v[80:83], v[158:159], off offset:768
	s_waitcnt lgkmcnt(6)
	v_mfma_f32_32x32x16_bf16 v[32:47], v[244:247], v[212:215], v[32:47]
	s_waitcnt vmcnt(15)
	ds_write_b128 v175, v[126:129] offset:36864
	global_load_dwordx4 v[102:105], v[150:151], off offset:768
	s_waitcnt lgkmcnt(6)
	v_mfma_f32_32x32x16_bf16 v[0:15], v[244:247], v[252:255], v[0:15]
	s_waitcnt vmcnt(15)
	ds_write_b128 v175, v[134:137] offset:41472
	global_load_dwordx4 v[118:121], v[160:161], off offset:768
	s_waitcnt lgkmcnt(5)
	v_mfma_f32_32x32x16_bf16 v[48:63], v[216:219], v[212:215], v[48:63]
	s_waitcnt vmcnt(15)
	ds_write_b128 v175, v[138:141] offset:46080
	global_load_dwordx4 v[122:125], v[170:171], off offset:768
	v_mfma_f32_32x32x16_bf16 v[16:31], v[216:219], v[252:255], v[16:31]
	s_waitcnt vmcnt(15)
	ds_write_b128 v175, v[142:145] offset:50688
	global_load_dwordx4 v[126:129], v[172:173], off offset:768
	s_setprio 0
	s_waitcnt lgkmcnt(0)
	s_barrier
	s_setprio 1
	ds_read_b128 v[212:215], v96 offset:36864
	ds_read_b128 v[216:219], v176
	ds_read_b128 v[220:223], v176 offset:4608
	ds_read_b128 v[224:227], v96 offset:41472
	ds_read_b128 v[228:231], v96 offset:36896
	ds_read_b128 v[244:247], v176 offset:32
	ds_read_b128 v[252:255], v176 offset:4640
	s_waitcnt lgkmcnt(5)
	v_mfma_f32_32x32x16_bf16 v[32:47], v[212:215], v[216:219], v[32:47]
	s_waitcnt lgkmcnt(4)
	v_mfma_f32_32x32x16_bf16 v[0:15], v[212:215], v[220:223], v[0:15]
	ds_read_b128 v[212:215], v96 offset:41504
	s_waitcnt lgkmcnt(4)
	v_mfma_f32_32x32x16_bf16 v[48:63], v[224:227], v[216:219], v[48:63]
	ds_read_b128 v[216:219], v96 offset:36928
	v_mfma_f32_32x32x16_bf16 v[16:31], v[224:227], v[220:223], v[16:31]
	ds_read_b128 v[224:227], v176 offset:64
	ds_read_b128 v[220:223], v176 offset:4672
	s_waitcnt lgkmcnt(5)
	v_mfma_f32_32x32x16_bf16 v[32:47], v[228:231], v[244:247], v[32:47]
	s_waitcnt lgkmcnt(4)
	v_mfma_f32_32x32x16_bf16 v[0:15], v[228:231], v[252:255], v[0:15]
	ds_read_b128 v[228:231], v96 offset:41536
	s_waitcnt lgkmcnt(4)
	v_mfma_f32_32x32x16_bf16 v[48:63], v[212:215], v[244:247], v[48:63]
	ds_read_b128 v[244:247], v96 offset:36960
	v_mfma_f32_32x32x16_bf16 v[16:31], v[212:215], v[252:255], v[16:31]
	ds_read_b128 v[212:215], v176 offset:96
	ds_read_b128 v[252:255], v176 offset:4704
	s_waitcnt lgkmcnt(5)
	v_mfma_f32_32x32x16_bf16 v[32:47], v[216:219], v[224:227], v[32:47]
	s_waitcnt vmcnt(15)
	ds_write_b128 v175, v[68:71] offset:18432
	global_load_dwordx4 v[68:71], v[152:153], off offset:896
	s_waitcnt lgkmcnt(5)
	v_mfma_f32_32x32x16_bf16 v[0:15], v[216:219], v[220:223], v[0:15]
	ds_read_b128 v[216:219], v96 offset:41568
	s_waitcnt vmcnt(15)
	ds_write_b128 v175, v[84:87] offset:23040
	global_load_dwordx4 v[84:87], v[154:155], off offset:896
	s_waitcnt lgkmcnt(6)
	v_mfma_f32_32x32x16_bf16 v[48:63], v[228:231], v[224:227], v[48:63]
	s_waitcnt vmcnt(15)
	ds_write_b128 v175, v[88:91] offset:27648
	global_load_dwordx4 v[88:91], v[156:157], off offset:896
	v_mfma_f32_32x32x16_bf16 v[16:31], v[228:231], v[220:223], v[16:31]
	s_waitcnt vmcnt(15)
	ds_write_b128 v175, v[92:95] offset:32256
	global_load_dwordx4 v[92:95], v[158:159], off offset:896
	s_waitcnt lgkmcnt(6)
	v_mfma_f32_32x32x16_bf16 v[32:47], v[244:247], v[212:215], v[32:47]
	s_waitcnt vmcnt(15)
	ds_write_b128 v175, v[98:101] offset:55296
	global_load_dwordx4 v[98:101], v[150:151], off offset:896
	s_waitcnt lgkmcnt(6)
	v_mfma_f32_32x32x16_bf16 v[0:15], v[244:247], v[252:255], v[0:15]
	s_waitcnt vmcnt(15)
	ds_write_b128 v175, v[106:109] offset:59904
	global_load_dwordx4 v[106:109], v[160:161], off offset:896
	s_waitcnt lgkmcnt(5)
	v_mfma_f32_32x32x16_bf16 v[48:63], v[216:219], v[212:215], v[48:63]
	s_waitcnt vmcnt(15)
	ds_write_b128 v175, v[110:113] offset:64512
	global_load_dwordx4 v[110:113], v[170:171], off offset:896
	v_mfma_f32_32x32x16_bf16 v[16:31], v[216:219], v[252:255], v[16:31]
	s_waitcnt vmcnt(15)
	ds_write_b128 v177, v[114:117] offset:13824
	global_load_dwordx4 v[114:117], v[172:173], off offset:896
	s_setprio 0
	s_waitcnt lgkmcnt(0)
	s_barrier
	s_setprio 1
	ds_read_b128 v[212:215], v96 offset:55296
	ds_read_b128 v[216:219], v176 offset:18432
	ds_read_b128 v[220:223], v176 offset:23040
	ds_read_b128 v[224:227], v96 offset:59904
	ds_read_b128 v[228:231], v96 offset:55328
	ds_read_b128 v[244:247], v176 offset:18464
	ds_read_b128 v[252:255], v176 offset:23072
	s_waitcnt lgkmcnt(5)
	v_mfma_f32_32x32x16_bf16 v[32:47], v[212:215], v[216:219], v[32:47]
	s_waitcnt lgkmcnt(4)
	v_mfma_f32_32x32x16_bf16 v[0:15], v[212:215], v[220:223], v[0:15]
	ds_read_b128 v[212:215], v96 offset:59936
	s_waitcnt lgkmcnt(4)
	v_mfma_f32_32x32x16_bf16 v[48:63], v[224:227], v[216:219], v[48:63]
	ds_read_b128 v[216:219], v96 offset:55360
	v_mfma_f32_32x32x16_bf16 v[16:31], v[224:227], v[220:223], v[16:31]
	ds_read_b128 v[224:227], v176 offset:18496
	ds_read_b128 v[220:223], v176 offset:23104
	s_waitcnt lgkmcnt(5)
	v_mfma_f32_32x32x16_bf16 v[32:47], v[228:231], v[244:247], v[32:47]
	s_waitcnt lgkmcnt(4)
	v_mfma_f32_32x32x16_bf16 v[0:15], v[228:231], v[252:255], v[0:15]
	ds_read_b128 v[228:231], v96 offset:59968
	s_waitcnt lgkmcnt(4)
	v_mfma_f32_32x32x16_bf16 v[48:63], v[212:215], v[244:247], v[48:63]
	ds_read_b128 v[244:247], v96 offset:55392
	v_mfma_f32_32x32x16_bf16 v[16:31], v[212:215], v[252:255], v[16:31]
	ds_read_b128 v[212:215], v176 offset:18528
	ds_read_b128 v[252:255], v176 offset:23136
	s_waitcnt lgkmcnt(5)
	v_mfma_f32_32x32x16_bf16 v[32:47], v[216:219], v[224:227], v[32:47]
	s_waitcnt vmcnt(15)
	ds_write_b128 v175, v[64:67]
	global_load_dwordx4 v[64:67], v[152:153], off offset:1024
	s_waitcnt lgkmcnt(5)
	v_mfma_f32_32x32x16_bf16 v[0:15], v[216:219], v[220:223], v[0:15]
	ds_read_b128 v[216:219], v96 offset:60000
	s_waitcnt vmcnt(15)
	ds_write_b128 v175, v[72:75] offset:4608
	global_load_dwordx4 v[72:75], v[154:155], off offset:1024
	s_waitcnt lgkmcnt(6)
	v_mfma_f32_32x32x16_bf16 v[48:63], v[228:231], v[224:227], v[48:63]
	s_waitcnt vmcnt(15)
	ds_write_b128 v175, v[76:79] offset:9216
	global_load_dwordx4 v[76:79], v[156:157], off offset:1024
	v_mfma_f32_32x32x16_bf16 v[16:31], v[228:231], v[220:223], v[16:31]
	s_waitcnt vmcnt(15)
	ds_write_b128 v175, v[80:83] offset:13824
	global_load_dwordx4 v[80:83], v[158:159], off offset:1024
	s_waitcnt lgkmcnt(6)
	v_mfma_f32_32x32x16_bf16 v[32:47], v[244:247], v[212:215], v[32:47]
	s_waitcnt vmcnt(15)
	ds_write_b128 v175, v[102:105] offset:36864
	global_load_dwordx4 v[102:105], v[150:151], off offset:1024
	s_waitcnt lgkmcnt(6)
	v_mfma_f32_32x32x16_bf16 v[0:15], v[244:247], v[252:255], v[0:15]
	s_waitcnt vmcnt(15)
	ds_write_b128 v175, v[118:121] offset:41472
	global_load_dwordx4 v[118:121], v[160:161], off offset:1024
	s_waitcnt lgkmcnt(5)
	v_mfma_f32_32x32x16_bf16 v[48:63], v[216:219], v[212:215], v[48:63]
	s_waitcnt vmcnt(15)
	ds_write_b128 v175, v[122:125] offset:46080
	global_load_dwordx4 v[122:125], v[170:171], off offset:1024
	v_mfma_f32_32x32x16_bf16 v[16:31], v[216:219], v[252:255], v[16:31]
	s_waitcnt vmcnt(15)
	ds_write_b128 v175, v[126:129] offset:50688
	global_load_dwordx4 v[126:129], v[172:173], off offset:1024
	s_setprio 0
	s_waitcnt lgkmcnt(0)
	s_barrier
	s_setprio 1
	ds_read_b128 v[212:215], v96 offset:36864
	ds_read_b128 v[216:219], v176
	ds_read_b128 v[220:223], v176 offset:4608
	ds_read_b128 v[224:227], v96 offset:41472
	ds_read_b128 v[228:231], v96 offset:36896
	ds_read_b128 v[244:247], v176 offset:32
	ds_read_b128 v[252:255], v176 offset:4640
	s_waitcnt lgkmcnt(5)
	v_mfma_f32_32x32x16_bf16 v[32:47], v[212:215], v[216:219], v[32:47]
	s_waitcnt lgkmcnt(4)
	v_mfma_f32_32x32x16_bf16 v[0:15], v[212:215], v[220:223], v[0:15]
	ds_read_b128 v[212:215], v96 offset:41504
	s_waitcnt lgkmcnt(4)
	v_mfma_f32_32x32x16_bf16 v[48:63], v[224:227], v[216:219], v[48:63]
	ds_read_b128 v[216:219], v96 offset:36928
	v_mfma_f32_32x32x16_bf16 v[16:31], v[224:227], v[220:223], v[16:31]
	ds_read_b128 v[224:227], v176 offset:64
	ds_read_b128 v[220:223], v176 offset:4672
	s_waitcnt lgkmcnt(5)
	v_mfma_f32_32x32x16_bf16 v[32:47], v[228:231], v[244:247], v[32:47]
	s_waitcnt lgkmcnt(4)
	v_mfma_f32_32x32x16_bf16 v[0:15], v[228:231], v[252:255], v[0:15]
	ds_read_b128 v[228:231], v96 offset:41536
	s_waitcnt lgkmcnt(4)
	v_mfma_f32_32x32x16_bf16 v[48:63], v[212:215], v[244:247], v[48:63]
	ds_read_b128 v[244:247], v96 offset:36960
	v_mfma_f32_32x32x16_bf16 v[16:31], v[212:215], v[252:255], v[16:31]
	ds_read_b128 v[212:215], v176 offset:96
	ds_read_b128 v[252:255], v176 offset:4704
	s_waitcnt lgkmcnt(5)
	v_mfma_f32_32x32x16_bf16 v[32:47], v[216:219], v[224:227], v[32:47]
	s_waitcnt vmcnt(15)
	ds_write_b128 v175, v[68:71] offset:18432
	global_load_dwordx4 v[68:71], v[152:153], off offset:1152
	s_waitcnt lgkmcnt(5)
	v_mfma_f32_32x32x16_bf16 v[0:15], v[216:219], v[220:223], v[0:15]
	ds_read_b128 v[216:219], v96 offset:41568
	s_waitcnt vmcnt(15)
	ds_write_b128 v175, v[84:87] offset:23040
	global_load_dwordx4 v[84:87], v[154:155], off offset:1152
	s_waitcnt lgkmcnt(6)
	v_mfma_f32_32x32x16_bf16 v[48:63], v[228:231], v[224:227], v[48:63]
	s_waitcnt vmcnt(15)
	ds_write_b128 v175, v[88:91] offset:27648
	global_load_dwordx4 v[88:91], v[156:157], off offset:1152
	v_mfma_f32_32x32x16_bf16 v[16:31], v[228:231], v[220:223], v[16:31]
	s_waitcnt vmcnt(15)
	ds_write_b128 v175, v[92:95] offset:32256
	global_load_dwordx4 v[92:95], v[158:159], off offset:1152
	s_waitcnt lgkmcnt(6)
	v_mfma_f32_32x32x16_bf16 v[32:47], v[244:247], v[212:215], v[32:47]
	s_waitcnt vmcnt(15)
	ds_write_b128 v175, v[98:101] offset:55296
	global_load_dwordx4 v[98:101], v[150:151], off offset:1152
	s_waitcnt lgkmcnt(6)
	v_mfma_f32_32x32x16_bf16 v[0:15], v[244:247], v[252:255], v[0:15]
	s_waitcnt vmcnt(15)
	ds_write_b128 v175, v[106:109] offset:59904
	global_load_dwordx4 v[106:109], v[160:161], off offset:1152
	s_waitcnt lgkmcnt(5)
	v_mfma_f32_32x32x16_bf16 v[48:63], v[216:219], v[212:215], v[48:63]
	s_waitcnt vmcnt(15)
	ds_write_b128 v175, v[110:113] offset:64512
	global_load_dwordx4 v[110:113], v[170:171], off offset:1152
	v_mfma_f32_32x32x16_bf16 v[16:31], v[216:219], v[252:255], v[16:31]
	s_waitcnt vmcnt(15)
	ds_write_b128 v177, v[114:117] offset:13824
	global_load_dwordx4 v[114:117], v[172:173], off offset:1152
	s_setprio 0
	s_waitcnt lgkmcnt(0)
	s_barrier
	s_setprio 1
	ds_read_b128 v[212:215], v96 offset:55296
	ds_read_b128 v[216:219], v176 offset:18432
	ds_read_b128 v[220:223], v176 offset:23040
	ds_read_b128 v[224:227], v96 offset:59904
	ds_read_b128 v[228:231], v96 offset:55328
	ds_read_b128 v[244:247], v176 offset:18464
	ds_read_b128 v[252:255], v176 offset:23072
	s_waitcnt lgkmcnt(5)
	v_mfma_f32_32x32x16_bf16 v[32:47], v[212:215], v[216:219], v[32:47]
	s_waitcnt lgkmcnt(4)
	v_mfma_f32_32x32x16_bf16 v[0:15], v[212:215], v[220:223], v[0:15]
	ds_read_b128 v[212:215], v96 offset:59936
	s_waitcnt lgkmcnt(4)
	v_mfma_f32_32x32x16_bf16 v[48:63], v[224:227], v[216:219], v[48:63]
	ds_read_b128 v[216:219], v96 offset:55360
	v_mfma_f32_32x32x16_bf16 v[16:31], v[224:227], v[220:223], v[16:31]
	ds_read_b128 v[224:227], v176 offset:18496
	ds_read_b128 v[220:223], v176 offset:23104
	s_waitcnt lgkmcnt(5)
	v_mfma_f32_32x32x16_bf16 v[32:47], v[228:231], v[244:247], v[32:47]
	s_waitcnt lgkmcnt(4)
	v_mfma_f32_32x32x16_bf16 v[0:15], v[228:231], v[252:255], v[0:15]
	ds_read_b128 v[228:231], v96 offset:59968
	s_waitcnt lgkmcnt(4)
	v_mfma_f32_32x32x16_bf16 v[48:63], v[212:215], v[244:247], v[48:63]
	ds_read_b128 v[244:247], v96 offset:55392
	v_mfma_f32_32x32x16_bf16 v[16:31], v[212:215], v[252:255], v[16:31]
	ds_read_b128 v[212:215], v176 offset:18528
	ds_read_b128 v[252:255], v176 offset:23136
	s_waitcnt lgkmcnt(5)
	v_mfma_f32_32x32x16_bf16 v[32:47], v[216:219], v[224:227], v[32:47]
	s_waitcnt vmcnt(15)
	ds_write_b128 v175, v[64:67]
	global_load_dwordx4 v[64:67], v[152:153], off offset:1280
	s_waitcnt lgkmcnt(5)
	v_mfma_f32_32x32x16_bf16 v[0:15], v[216:219], v[220:223], v[0:15]
	ds_read_b128 v[216:219], v96 offset:60000
	s_waitcnt vmcnt(15)
	ds_write_b128 v175, v[72:75] offset:4608
	global_load_dwordx4 v[72:75], v[154:155], off offset:1280
	s_waitcnt lgkmcnt(6)
	v_mfma_f32_32x32x16_bf16 v[48:63], v[228:231], v[224:227], v[48:63]
	s_waitcnt vmcnt(15)
	ds_write_b128 v175, v[76:79] offset:9216
	global_load_dwordx4 v[76:79], v[156:157], off offset:1280
	v_mfma_f32_32x32x16_bf16 v[16:31], v[228:231], v[220:223], v[16:31]
	s_waitcnt vmcnt(15)
	ds_write_b128 v175, v[80:83] offset:13824
	global_load_dwordx4 v[80:83], v[158:159], off offset:1280
	s_waitcnt lgkmcnt(6)
	v_mfma_f32_32x32x16_bf16 v[32:47], v[244:247], v[212:215], v[32:47]
	s_waitcnt vmcnt(15)
	ds_write_b128 v175, v[102:105] offset:36864
	global_load_dwordx4 v[102:105], v[150:151], off offset:1280
	s_waitcnt lgkmcnt(6)
	v_mfma_f32_32x32x16_bf16 v[0:15], v[244:247], v[252:255], v[0:15]
	s_waitcnt vmcnt(15)
	ds_write_b128 v175, v[118:121] offset:41472
	global_load_dwordx4 v[118:121], v[160:161], off offset:1280
	s_waitcnt lgkmcnt(5)
	v_mfma_f32_32x32x16_bf16 v[48:63], v[216:219], v[212:215], v[48:63]
	s_waitcnt vmcnt(15)
	ds_write_b128 v175, v[122:125] offset:46080
	global_load_dwordx4 v[122:125], v[170:171], off offset:1280
	v_mfma_f32_32x32x16_bf16 v[16:31], v[216:219], v[252:255], v[16:31]
	s_waitcnt vmcnt(15)
	ds_write_b128 v175, v[126:129] offset:50688
	global_load_dwordx4 v[126:129], v[172:173], off offset:1280
	s_setprio 0
	s_waitcnt lgkmcnt(0)
	s_barrier
	s_setprio 1
	ds_read_b128 v[212:215], v96 offset:36864
	ds_read_b128 v[216:219], v176
	ds_read_b128 v[220:223], v176 offset:4608
	ds_read_b128 v[224:227], v96 offset:41472
	ds_read_b128 v[228:231], v96 offset:36896
	ds_read_b128 v[244:247], v176 offset:32
	ds_read_b128 v[252:255], v176 offset:4640
	s_waitcnt lgkmcnt(5)
	v_mfma_f32_32x32x16_bf16 v[32:47], v[212:215], v[216:219], v[32:47]
	s_waitcnt lgkmcnt(4)
	v_mfma_f32_32x32x16_bf16 v[0:15], v[212:215], v[220:223], v[0:15]
	ds_read_b128 v[212:215], v96 offset:41504
	s_waitcnt lgkmcnt(4)
	v_mfma_f32_32x32x16_bf16 v[48:63], v[224:227], v[216:219], v[48:63]
	ds_read_b128 v[216:219], v96 offset:36928
	v_mfma_f32_32x32x16_bf16 v[16:31], v[224:227], v[220:223], v[16:31]
	ds_read_b128 v[224:227], v176 offset:64
	ds_read_b128 v[220:223], v176 offset:4672
	s_waitcnt lgkmcnt(5)
	v_mfma_f32_32x32x16_bf16 v[32:47], v[228:231], v[244:247], v[32:47]
	s_waitcnt lgkmcnt(4)
	v_mfma_f32_32x32x16_bf16 v[0:15], v[228:231], v[252:255], v[0:15]
	ds_read_b128 v[228:231], v96 offset:41536
	s_waitcnt lgkmcnt(4)
	v_mfma_f32_32x32x16_bf16 v[48:63], v[212:215], v[244:247], v[48:63]
	ds_read_b128 v[244:247], v96 offset:36960
	v_mfma_f32_32x32x16_bf16 v[16:31], v[212:215], v[252:255], v[16:31]
	ds_read_b128 v[212:215], v176 offset:96
	ds_read_b128 v[252:255], v176 offset:4704
	s_waitcnt lgkmcnt(5)
	v_mfma_f32_32x32x16_bf16 v[32:47], v[216:219], v[224:227], v[32:47]
	s_waitcnt vmcnt(15)
	ds_write_b128 v175, v[68:71] offset:18432
	global_load_dwordx4 v[68:71], v[152:153], off offset:1408
	s_waitcnt lgkmcnt(5)
	v_mfma_f32_32x32x16_bf16 v[0:15], v[216:219], v[220:223], v[0:15]
	ds_read_b128 v[216:219], v96 offset:41568
	s_waitcnt vmcnt(15)
	ds_write_b128 v175, v[84:87] offset:23040
	global_load_dwordx4 v[84:87], v[154:155], off offset:1408
	s_waitcnt lgkmcnt(6)
	v_mfma_f32_32x32x16_bf16 v[48:63], v[228:231], v[224:227], v[48:63]
	s_waitcnt vmcnt(15)
	ds_write_b128 v175, v[88:91] offset:27648
	global_load_dwordx4 v[88:91], v[156:157], off offset:1408
	v_mfma_f32_32x32x16_bf16 v[16:31], v[228:231], v[220:223], v[16:31]
	s_waitcnt vmcnt(15)
	ds_write_b128 v175, v[92:95] offset:32256
	global_load_dwordx4 v[92:95], v[158:159], off offset:1408
	s_waitcnt lgkmcnt(6)
	v_mfma_f32_32x32x16_bf16 v[32:47], v[244:247], v[212:215], v[32:47]
	s_waitcnt vmcnt(15)
	ds_write_b128 v175, v[98:101] offset:55296
	global_load_dwordx4 v[98:101], v[150:151], off offset:1408
	s_waitcnt lgkmcnt(6)
	v_mfma_f32_32x32x16_bf16 v[0:15], v[244:247], v[252:255], v[0:15]
	s_waitcnt vmcnt(15)
	ds_write_b128 v175, v[106:109] offset:59904
	global_load_dwordx4 v[106:109], v[160:161], off offset:1408
	s_waitcnt lgkmcnt(5)
	v_mfma_f32_32x32x16_bf16 v[48:63], v[216:219], v[212:215], v[48:63]
	s_waitcnt vmcnt(15)
	ds_write_b128 v175, v[110:113] offset:64512
	global_load_dwordx4 v[110:113], v[170:171], off offset:1408
	v_mfma_f32_32x32x16_bf16 v[16:31], v[216:219], v[252:255], v[16:31]
	s_waitcnt vmcnt(15)
	ds_write_b128 v177, v[114:117] offset:13824
	global_load_dwordx4 v[130:133], v[172:173], off offset:1408
	s_setprio 0
	s_waitcnt lgkmcnt(0)
	s_barrier
	s_setprio 1
	ds_read_b128 v[212:215], v96 offset:55296
	ds_read_b128 v[216:219], v176 offset:18432
	ds_read_b128 v[220:223], v176 offset:23040
	ds_read_b128 v[224:227], v96 offset:59904
	ds_read_b128 v[228:231], v96 offset:55328
	ds_read_b128 v[244:247], v176 offset:18464
	ds_read_b128 v[252:255], v176 offset:23072
	s_waitcnt lgkmcnt(5)
	v_mfma_f32_32x32x16_bf16 v[32:47], v[212:215], v[216:219], v[32:47]
	s_waitcnt lgkmcnt(4)
	v_mfma_f32_32x32x16_bf16 v[0:15], v[212:215], v[220:223], v[0:15]
	ds_read_b128 v[212:215], v96 offset:59936
	s_waitcnt lgkmcnt(4)
	v_mfma_f32_32x32x16_bf16 v[48:63], v[224:227], v[216:219], v[48:63]
	ds_read_b128 v[216:219], v96 offset:55360
	v_mfma_f32_32x32x16_bf16 v[16:31], v[224:227], v[220:223], v[16:31]
	ds_read_b128 v[224:227], v176 offset:18496
	ds_read_b128 v[220:223], v176 offset:23104
	s_waitcnt lgkmcnt(5)
	v_mfma_f32_32x32x16_bf16 v[32:47], v[228:231], v[244:247], v[32:47]
	s_waitcnt lgkmcnt(4)
	v_mfma_f32_32x32x16_bf16 v[0:15], v[228:231], v[252:255], v[0:15]
	ds_read_b128 v[228:231], v96 offset:59968
	s_waitcnt lgkmcnt(4)
	v_mfma_f32_32x32x16_bf16 v[48:63], v[212:215], v[244:247], v[48:63]
	ds_read_b128 v[244:247], v96 offset:55392
	v_mfma_f32_32x32x16_bf16 v[16:31], v[212:215], v[252:255], v[16:31]
	ds_read_b128 v[212:215], v176 offset:18528
	ds_read_b128 v[252:255], v176 offset:23136
	s_waitcnt lgkmcnt(5)
	v_mfma_f32_32x32x16_bf16 v[32:47], v[216:219], v[224:227], v[32:47]
	s_waitcnt vmcnt(15)
	ds_write_b128 v175, v[64:67]
	global_load_dwordx4 v[64:67], v[152:153], off offset:1536
	s_waitcnt lgkmcnt(5)
	v_mfma_f32_32x32x16_bf16 v[0:15], v[216:219], v[220:223], v[0:15]
	ds_read_b128 v[216:219], v96 offset:60000
	s_waitcnt vmcnt(15)
	ds_write_b128 v175, v[72:75] offset:4608
	global_load_dwordx4 v[72:75], v[154:155], off offset:1536
	s_waitcnt lgkmcnt(6)
	v_mfma_f32_32x32x16_bf16 v[48:63], v[228:231], v[224:227], v[48:63]
	s_waitcnt vmcnt(15)
	ds_write_b128 v175, v[76:79] offset:9216
	global_load_dwordx4 v[76:79], v[156:157], off offset:1536
	v_mfma_f32_32x32x16_bf16 v[16:31], v[228:231], v[220:223], v[16:31]
	s_waitcnt vmcnt(15)
	ds_write_b128 v175, v[80:83] offset:13824
	global_load_dwordx4 v[80:83], v[158:159], off offset:1536
	s_waitcnt lgkmcnt(6)
	v_mfma_f32_32x32x16_bf16 v[32:47], v[244:247], v[212:215], v[32:47]
	s_waitcnt vmcnt(15)
	ds_write_b128 v175, v[102:105] offset:36864
	global_load_dwordx4 v[114:117], v[150:151], off offset:1536
	s_waitcnt lgkmcnt(6)
	v_mfma_f32_32x32x16_bf16 v[0:15], v[244:247], v[252:255], v[0:15]
	s_waitcnt vmcnt(15)
	ds_write_b128 v175, v[118:121] offset:41472
	s_waitcnt vmcnt(14)
	ds_write_b128 v175, v[122:125] offset:46080
	s_waitcnt lgkmcnt(6)
	v_mfma_f32_32x32x16_bf16 v[48:63], v[216:219], v[212:215], v[48:63]
	global_load_dwordx4 v[122:125], v[160:161], off offset:1536
	s_waitcnt vmcnt(14)
	ds_write_b128 v175, v[126:129] offset:50688
	v_mfma_f32_32x32x16_bf16 v[16:31], v[216:219], v[252:255], v[16:31]
	global_load_dwordx4 v[126:129], v[170:171], off offset:1536
	global_load_dwordx4 v[134:137], v[172:173], off offset:1536
	s_setprio 0
	s_waitcnt lgkmcnt(0)
	s_barrier
	s_setprio 1
	ds_read_b128 v[212:215], v96 offset:36864
	ds_read_b128 v[216:219], v176
	ds_read_b128 v[220:223], v176 offset:4608
	ds_read_b128 v[224:227], v96 offset:41472
	ds_read_b128 v[228:231], v96 offset:36896
	ds_read_b128 v[244:247], v176 offset:32
	ds_read_b128 v[252:255], v176 offset:4640
	s_waitcnt lgkmcnt(5)
	v_mfma_f32_32x32x16_bf16 v[32:47], v[212:215], v[216:219], v[32:47]
	s_waitcnt lgkmcnt(4)
	v_mfma_f32_32x32x16_bf16 v[0:15], v[212:215], v[220:223], v[0:15]
	ds_read_b128 v[212:215], v96 offset:41504
	s_waitcnt lgkmcnt(4)
	v_mfma_f32_32x32x16_bf16 v[48:63], v[224:227], v[216:219], v[48:63]
	ds_read_b128 v[216:219], v96 offset:36928
	v_mfma_f32_32x32x16_bf16 v[16:31], v[224:227], v[220:223], v[16:31]
	ds_read_b128 v[224:227], v176 offset:64
	ds_read_b128 v[220:223], v176 offset:4672
	s_waitcnt lgkmcnt(5)
	v_mfma_f32_32x32x16_bf16 v[32:47], v[228:231], v[244:247], v[32:47]
	s_waitcnt lgkmcnt(4)
	v_mfma_f32_32x32x16_bf16 v[0:15], v[228:231], v[252:255], v[0:15]
	ds_read_b128 v[228:231], v96 offset:41536
	s_waitcnt lgkmcnt(4)
	v_mfma_f32_32x32x16_bf16 v[48:63], v[212:215], v[244:247], v[48:63]
	ds_read_b128 v[244:247], v96 offset:36960
	v_mfma_f32_32x32x16_bf16 v[16:31], v[212:215], v[252:255], v[16:31]
	ds_read_b128 v[212:215], v176 offset:96
	ds_read_b128 v[252:255], v176 offset:4704
	s_waitcnt lgkmcnt(5)
	v_mfma_f32_32x32x16_bf16 v[32:47], v[216:219], v[224:227], v[32:47]
	s_waitcnt vmcnt(15)
	ds_write_b128 v175, v[68:71] offset:18432
	s_waitcnt vmcnt(14)
	ds_write_b128 v175, v[84:87] offset:23040
	s_waitcnt lgkmcnt(6)
	v_mfma_f32_32x32x16_bf16 v[0:15], v[216:219], v[220:223], v[0:15]
	ds_read_b128 v[216:219], v96 offset:41568
	s_waitcnt vmcnt(13)
	ds_write_b128 v175, v[88:91] offset:27648
	s_waitcnt vmcnt(12)
	ds_write_b128 v175, v[92:95] offset:32256
	s_waitcnt lgkmcnt(8)
	v_mfma_f32_32x32x16_bf16 v[48:63], v[228:231], v[224:227], v[48:63]
	s_waitcnt vmcnt(11)
	ds_write_b128 v175, v[98:101] offset:55296
	v_mfma_f32_32x32x16_bf16 v[16:31], v[228:231], v[220:223], v[16:31]
	global_load_dwordx4 v[98:101], v[152:153], off offset:1664
	global_load_dwordx4 v[102:105], v[154:155], off offset:1664
	s_waitcnt vmcnt(12)
	ds_write_b128 v175, v[106:109] offset:59904
	s_waitcnt lgkmcnt(8)
	v_mfma_f32_32x32x16_bf16 v[32:47], v[244:247], v[212:215], v[32:47]
	global_load_dwordx4 v[106:109], v[156:157], off offset:1664
	s_waitcnt vmcnt(12)
	ds_write_b128 v175, v[110:113] offset:64512
	s_waitcnt lgkmcnt(8)
	v_mfma_f32_32x32x16_bf16 v[0:15], v[244:247], v[252:255], v[0:15]
	global_load_dwordx4 v[110:113], v[158:159], off offset:1664
	global_load_dwordx4 v[118:121], v[150:151], off offset:1664
	s_waitcnt lgkmcnt(5)
	v_mfma_f32_32x32x16_bf16 v[48:63], v[216:219], v[212:215], v[48:63]
	s_waitcnt vmcnt(13)
	ds_write_b128 v177, v[130:133] offset:13824
	global_load_dwordx4 v[130:133], v[160:161], off offset:1664
	v_mfma_f32_32x32x16_bf16 v[16:31], v[216:219], v[252:255], v[16:31]
	global_load_dwordx4 v[138:141], v[170:171], off offset:1664
	global_load_dwordx4 v[142:145], v[172:173], off offset:1664
	s_setprio 0
	s_waitcnt lgkmcnt(0)
	s_barrier
	s_setprio 1
	ds_read_b128 v[212:215], v96 offset:55296
	ds_read_b128 v[216:219], v176 offset:18432
	ds_read_b128 v[220:223], v176 offset:23040
	ds_read_b128 v[224:227], v96 offset:59904
	ds_read_b128 v[228:231], v96 offset:55328
	ds_read_b128 v[244:247], v176 offset:18464
	ds_read_b128 v[252:255], v176 offset:23072
	s_waitcnt lgkmcnt(5)
	v_mfma_f32_32x32x16_bf16 v[32:47], v[212:215], v[216:219], v[32:47]
	s_waitcnt lgkmcnt(4)
	v_mfma_f32_32x32x16_bf16 v[0:15], v[212:215], v[220:223], v[0:15]
	ds_read_b128 v[212:215], v96 offset:59936
	s_waitcnt lgkmcnt(4)
	v_mfma_f32_32x32x16_bf16 v[48:63], v[224:227], v[216:219], v[48:63]
	ds_read_b128 v[216:219], v96 offset:55360
	v_mfma_f32_32x32x16_bf16 v[16:31], v[224:227], v[220:223], v[16:31]
	ds_read_b128 v[224:227], v176 offset:18496
	ds_read_b128 v[220:223], v176 offset:23104
	s_waitcnt lgkmcnt(5)
	v_mfma_f32_32x32x16_bf16 v[32:47], v[228:231], v[244:247], v[32:47]
	s_waitcnt lgkmcnt(4)
	v_mfma_f32_32x32x16_bf16 v[0:15], v[228:231], v[252:255], v[0:15]
	ds_read_b128 v[228:231], v96 offset:59968
	s_waitcnt lgkmcnt(4)
	v_mfma_f32_32x32x16_bf16 v[48:63], v[212:215], v[244:247], v[48:63]
	ds_read_b128 v[244:247], v96 offset:55392
	v_mfma_f32_32x32x16_bf16 v[16:31], v[212:215], v[252:255], v[16:31]
	ds_read_b128 v[212:215], v176 offset:18528
	ds_read_b128 v[252:255], v176 offset:23136
	s_waitcnt lgkmcnt(5)
	v_mfma_f32_32x32x16_bf16 v[32:47], v[216:219], v[224:227], v[32:47]
	s_waitcnt vmcnt(15)
	ds_write_b128 v175, v[64:67]
	global_load_dwordx4 v[64:67], v[152:153], off offset:1792
	s_waitcnt lgkmcnt(5)
	v_mfma_f32_32x32x16_bf16 v[0:15], v[216:219], v[220:223], v[0:15]
	ds_read_b128 v[216:219], v96 offset:60000
	s_waitcnt vmcnt(15)
	ds_write_b128 v175, v[72:75] offset:4608
	global_load_dwordx4 v[68:71], v[154:155], off offset:1792
	s_waitcnt lgkmcnt(6)
	v_mfma_f32_32x32x16_bf16 v[48:63], v[228:231], v[224:227], v[48:63]
	s_waitcnt vmcnt(15)
	ds_write_b128 v175, v[76:79] offset:9216
	global_load_dwordx4 v[72:75], v[156:157], off offset:1792
	v_mfma_f32_32x32x16_bf16 v[16:31], v[228:231], v[220:223], v[16:31]
	s_waitcnt vmcnt(15)
	ds_write_b128 v175, v[80:83] offset:13824
	global_load_dwordx4 v[76:79], v[158:159], off offset:1792
	s_waitcnt lgkmcnt(6)
	v_mfma_f32_32x32x16_bf16 v[32:47], v[244:247], v[212:215], v[32:47]
	s_waitcnt vmcnt(15)
	ds_write_b128 v175, v[114:117] offset:36864
	global_load_dwordx4 v[80:83], v[150:151], off offset:1792
	s_waitcnt lgkmcnt(6)
	v_mfma_f32_32x32x16_bf16 v[0:15], v[244:247], v[252:255], v[0:15]
	s_waitcnt vmcnt(15)
	ds_write_b128 v175, v[122:125] offset:41472
	global_load_dwordx4 v[84:87], v[160:161], off offset:1792
	s_waitcnt lgkmcnt(5)
	v_mfma_f32_32x32x16_bf16 v[48:63], v[216:219], v[212:215], v[48:63]
	s_waitcnt vmcnt(15)
	ds_write_b128 v175, v[126:129] offset:46080
	global_load_dwordx4 v[88:91], v[170:171], off offset:1792
	v_mfma_f32_32x32x16_bf16 v[16:31], v[216:219], v[252:255], v[16:31]
	s_waitcnt vmcnt(15)
	ds_write_b128 v175, v[134:137] offset:50688
	global_load_dwordx4 v[92:95], v[172:173], off offset:1792
	s_setprio 0
	s_waitcnt lgkmcnt(0)
	s_barrier
	s_setprio 1
	ds_read_b128 v[212:215], v96 offset:36864
	ds_read_b128 v[216:219], v176
	ds_read_b128 v[220:223], v176 offset:4608
	ds_read_b128 v[224:227], v96 offset:41472
	ds_read_b128 v[228:231], v96 offset:36896
	ds_read_b128 v[244:247], v176 offset:32
	ds_read_b128 v[252:255], v176 offset:4640
	s_waitcnt lgkmcnt(5)
	v_mfma_f32_32x32x16_bf16 v[32:47], v[212:215], v[216:219], v[32:47]
	s_waitcnt lgkmcnt(4)
	v_mfma_f32_32x32x16_bf16 v[0:15], v[212:215], v[220:223], v[0:15]
	ds_read_b128 v[212:215], v96 offset:41504
	s_waitcnt lgkmcnt(4)
	v_mfma_f32_32x32x16_bf16 v[48:63], v[224:227], v[216:219], v[48:63]
	ds_read_b128 v[216:219], v96 offset:36928
	v_mfma_f32_32x32x16_bf16 v[16:31], v[224:227], v[220:223], v[16:31]
	ds_read_b128 v[224:227], v176 offset:64
	ds_read_b128 v[220:223], v176 offset:4672
	s_waitcnt lgkmcnt(5)
	v_mfma_f32_32x32x16_bf16 v[32:47], v[228:231], v[244:247], v[32:47]
	s_waitcnt lgkmcnt(4)
	v_mfma_f32_32x32x16_bf16 v[0:15], v[228:231], v[252:255], v[0:15]
	ds_read_b128 v[228:231], v96 offset:41536
	s_waitcnt lgkmcnt(4)
	v_mfma_f32_32x32x16_bf16 v[48:63], v[212:215], v[244:247], v[48:63]
	ds_read_b128 v[244:247], v96 offset:36960
	v_mfma_f32_32x32x16_bf16 v[16:31], v[212:215], v[252:255], v[16:31]
	ds_read_b128 v[212:215], v176 offset:96
	ds_read_b128 v[252:255], v176 offset:4704
	s_waitcnt lgkmcnt(5)
	v_mfma_f32_32x32x16_bf16 v[32:47], v[216:219], v[224:227], v[32:47]
	s_waitcnt vmcnt(15)
	ds_write_b128 v175, v[98:101] offset:18432
	s_waitcnt vmcnt(14)
	ds_write_b128 v175, v[102:105] offset:23040
	s_waitcnt lgkmcnt(6)
	v_mfma_f32_32x32x16_bf16 v[0:15], v[216:219], v[220:223], v[0:15]
	ds_read_b128 v[216:219], v96 offset:41568
	global_load_dwordx4 v[100:103], v[152:153], off offset:1920
	s_waitcnt vmcnt(14)
	ds_write_b128 v175, v[106:109] offset:27648
	s_waitcnt lgkmcnt(7)
	v_mfma_f32_32x32x16_bf16 v[48:63], v[228:231], v[224:227], v[48:63]
	global_load_dwordx4 v[104:107], v[154:155], off offset:1920
	s_waitcnt vmcnt(14)
	ds_write_b128 v175, v[110:113] offset:32256
	v_mfma_f32_32x32x16_bf16 v[16:31], v[228:231], v[220:223], v[16:31]
	global_load_dwordx4 v[108:111], v[156:157], off offset:1920
	global_load_dwordx4 v[112:115], v[158:159], off offset:1920
	s_waitcnt lgkmcnt(6)
	v_mfma_f32_32x32x16_bf16 v[32:47], v[244:247], v[212:215], v[32:47]
	s_waitcnt vmcnt(15)
	ds_write_b128 v175, v[118:121] offset:55296
	global_load_dwordx4 v[116:119], v[150:151], off offset:1920
	s_waitcnt lgkmcnt(6)
	v_mfma_f32_32x32x16_bf16 v[0:15], v[244:247], v[252:255], v[0:15]
	s_waitcnt vmcnt(15)
	ds_write_b128 v175, v[130:133] offset:59904
	global_load_dwordx4 v[124:127], v[160:161], off offset:1920
	s_waitcnt lgkmcnt(4)
	v_mfma_f32_32x32x16_bf16 v[48:63], v[216:219], v[212:215], v[48:63]
	s_waitcnt vmcnt(15)
	ds_write_b128 v175, v[138:141] offset:64512
	global_load_dwordx4 v[120:123], v[170:171], off offset:1920
	v_mfma_f32_32x32x16_bf16 v[16:31], v[216:219], v[252:255], v[16:31]
	s_waitcnt vmcnt(15)
	ds_write_b128 v177, v[142:145] offset:13824
	global_load_dwordx4 v[128:131], v[172:173], off offset:1920
	s_setprio 0
	s_waitcnt lgkmcnt(0)
	s_barrier
	s_setprio 1
	ds_read_b128 v[212:215], v96 offset:55296
	ds_read_b128 v[216:219], v176 offset:18432
	ds_read_b128 v[220:223], v176 offset:23040
	ds_read_b128 v[224:227], v96 offset:59904
	ds_read_b128 v[228:231], v96 offset:55328
	ds_read_b128 v[244:247], v176 offset:18464
	ds_read_b128 v[252:255], v176 offset:23072
	s_waitcnt lgkmcnt(5)
	v_mfma_f32_32x32x16_bf16 v[32:47], v[212:215], v[216:219], v[32:47]
	s_waitcnt lgkmcnt(4)
	v_mfma_f32_32x32x16_bf16 v[0:15], v[212:215], v[220:223], v[0:15]
	ds_read_b128 v[212:215], v96 offset:59936
	s_waitcnt lgkmcnt(4)
	v_mfma_f32_32x32x16_bf16 v[48:63], v[224:227], v[216:219], v[48:63]
	ds_read_b128 v[216:219], v96 offset:55360
	v_mfma_f32_32x32x16_bf16 v[16:31], v[224:227], v[220:223], v[16:31]
	ds_read_b128 v[224:227], v176 offset:18496
	ds_read_b128 v[220:223], v176 offset:23104
	s_waitcnt lgkmcnt(5)
	v_mfma_f32_32x32x16_bf16 v[32:47], v[228:231], v[244:247], v[32:47]
	s_waitcnt lgkmcnt(4)
	v_mfma_f32_32x32x16_bf16 v[0:15], v[228:231], v[252:255], v[0:15]
	ds_read_b128 v[228:231], v96 offset:59968
	s_waitcnt lgkmcnt(4)
	v_mfma_f32_32x32x16_bf16 v[48:63], v[212:215], v[244:247], v[48:63]
	ds_read_b128 v[244:247], v96 offset:55392
	v_mfma_f32_32x32x16_bf16 v[16:31], v[212:215], v[252:255], v[16:31]
	ds_read_b128 v[212:215], v176 offset:18528
	ds_read_b128 v[252:255], v176 offset:23136
	s_waitcnt lgkmcnt(5)
	v_mfma_f32_32x32x16_bf16 v[32:47], v[216:219], v[224:227], v[32:47]
	s_waitcnt lgkmcnt(4)
	v_mfma_f32_32x32x16_bf16 v[0:15], v[216:219], v[220:223], v[0:15]
	ds_read_b128 v[216:219], v96 offset:60000
	s_waitcnt lgkmcnt(4)
	v_mfma_f32_32x32x16_bf16 v[48:63], v[228:231], v[224:227], v[48:63]
	v_mfma_f32_32x32x16_bf16 v[16:31], v[228:231], v[220:223], v[16:31]
	s_waitcnt lgkmcnt(2)
	v_mfma_f32_32x32x16_bf16 v[32:47], v[244:247], v[212:215], v[32:47]
	s_waitcnt lgkmcnt(1)
	v_mfma_f32_32x32x16_bf16 v[0:15], v[244:247], v[252:255], v[0:15]
	s_waitcnt lgkmcnt(0)
	v_mfma_f32_32x32x16_bf16 v[48:63], v[216:219], v[212:215], v[48:63]
	v_mfma_f32_32x32x16_bf16 v[16:31], v[216:219], v[252:255], v[16:31]
	s_setprio 0
	v_cndmask_b32_e64 v98, 0, 1, s[44:45]
	v_cmp_ne_u32_e64 s[40:41], 1, v98
	s_andn2_b64 vcc, exec, s[44:45]
	s_waitcnt vmcnt(15)
	ds_write_b128 v175, v[64:67]
	s_waitcnt vmcnt(14)
	ds_write_b128 v175, v[68:71] offset:4608
	s_waitcnt vmcnt(13)
	ds_write_b128 v175, v[72:75] offset:9216
	s_waitcnt vmcnt(12)
	ds_write_b128 v175, v[76:79] offset:13824
	s_waitcnt vmcnt(11)
	ds_write_b128 v175, v[80:83] offset:36864
	s_waitcnt vmcnt(10)
	ds_write_b128 v175, v[84:87] offset:41472
	s_waitcnt vmcnt(9)
	ds_write_b128 v175, v[88:91] offset:46080
	s_waitcnt vmcnt(8)
	ds_write_b128 v175, v[92:95] offset:50688
	s_cbranch_vccnz .LBB0_1355
	v_add_co_u32_e32 v68, vcc, 0x10000, v148
	global_load_dwordx4 v[64:67], v[148:149], off
	s_nop 0
	v_addc_co_u32_e32 v69, vcc, 0, v149, vcc
	v_add_co_u32_e32 v72, vcc, 0x20000, v148
	s_nop 1
	v_addc_co_u32_e32 v73, vcc, 0, v149, vcc
	v_add_co_u32_e32 v76, vcc, 0x30000, v148
	global_load_dwordx4 v[68:71], v[68:69], off
	global_load_dwordx4 v[72:75], v[72:73], off
	v_addc_co_u32_e32 v77, vcc, 0, v149, vcc
	v_add_co_u32_e32 v84, vcc, 0x10000, v146
	global_load_dwordx4 v[76:79], v[76:77], off
	s_nop 0
	global_load_dwordx4 v[80:83], v[146:147], off
	v_addc_co_u32_e32 v85, vcc, 0, v147, vcc
	v_add_co_u32_e32 v88, vcc, 0x20000, v146
	s_nop 1
	v_addc_co_u32_e32 v89, vcc, 0, v147, vcc
	v_add_co_u32_e32 v92, vcc, 0x30000, v146
	global_load_dwordx4 v[84:87], v[84:85], off
	s_nop 0
	global_load_dwordx4 v[88:91], v[88:89], off
	v_addc_co_u32_e32 v93, vcc, 0, v147, vcc
	global_load_dwordx4 v[92:95], v[92:93], off

.LBB0_1359:
	s_waitcnt vmcnt(0)
	s_barrier
	s_mov_b64 s[2:3], exec
	v_readlane_b32 s6, v251, 0
	v_readlane_b32 s7, v251, 1
	s_and_b64 s[6:7], s[2:3], s[6:7]
	v_readlane_b32 s82, v248, 8
	s_xor_b64 s[2:3], s[6:7], s[2:3]
	v_readlane_b32 s83, v248, 9
	s_mov_b64 exec, s[6:7]
	s_cbranch_execz .LBB0_1408
	v_readlane_b32 s6, v249, 49
	s_waitcnt expcnt(0) lgkmcnt(0)
	s_nop 0
	v_mov_b32_e32 v0, s6
	ds_read_b32 v2, v0
	v_readlane_b32 s6, v249, 50
	s_waitcnt lgkmcnt(0)
	v_cmp_ne_u32_e32 vcc, 0, v2
	v_mov_b32_e32 v0, s6
	ds_read_b32 v0, v0
	s_cbranch_vccnz .LBB0_1375
	s_mov_b32 s40, 1
	s_branch .LBB0_1363
